# mLSTM phase C hand-scheduled (pipelined QK chains, DPP reductions); pool_diff rewritten with batched double-buffered loads; flat->global
# speedup vs baseline: 1.0173x; 1.0080x over previous
; __device__ NOINL void prep_mod(const float* c, const float* wada, const float* bada, float* mod, LAS unsigned char* lds, int wv) {
;     ...
;             for (int kk = 0; kk < 256; ++kk) { const float w = wp[(size_t)kk * 12288];
; #pragma unroll
;                 for (int b = 0; b < 16; ++b) acc[b] += cs[b * 1024 + kq * 256 + kk] * w; }
.Lpm_body:
	global_load_dword v122, v186, s[8:9]
	s_add_u32 s8, s8, 0xc000
	s_addc_u32 s9, s9, 0
	global_load_dword v123, v186, s[8:9]
	s_add_u32 s8, s8, 0xc000
	s_addc_u32 s9, s9, 0
	global_load_dword v124, v186, s[8:9]
	s_add_u32 s8, s8, 0xc000
	s_addc_u32 s9, s9, 0
	global_load_dword v125, v186, s[8:9]
	s_add_u32 s8, s8, 0xc000
	s_addc_u32 s9, s9, 0
	ds_read_b128 v[2:5], v93 offset:0
	ds_read_b128 v[6:9], v93 offset:4096
	ds_read_b128 v[10:13], v93 offset:8192
	ds_read_b128 v[14:17], v93 offset:12288
	ds_read_b128 v[18:21], v93 offset:16384
	ds_read_b128 v[22:25], v93 offset:20480
	ds_read_b128 v[26:29], v93 offset:24576
	ds_read_b128 v[30:33], v93 offset:28672
	ds_read_b128 v[34:37], v93 offset:32768
	ds_read_b128 v[38:41], v93 offset:36864
	ds_read_b128 v[42:45], v93 offset:40960
	ds_read_b128 v[126:129], v93 offset:45056
	ds_read_b128 v[130:133], v93 offset:49152
	ds_read_b128 v[134:137], v93 offset:53248
	ds_read_b128 v[138:141], v93 offset:57344
	ds_read_b128 v[142:145], v93 offset:61440
	s_waitcnt vmcnt(28)
	s_waitcnt lgkmcnt(8)
	v_pk_fma_f32 v[146:147], v[2:3], v[94:95], v[146:147]
	v_pk_fma_f32 v[148:149], v[6:7], v[94:95], v[148:149]
	v_pk_fma_f32 v[150:151], v[10:11], v[94:95], v[150:151]
	v_pk_fma_f32 v[152:153], v[14:15], v[94:95], v[152:153]
	v_pk_fma_f32 v[154:155], v[18:19], v[94:95], v[154:155]
	v_pk_fma_f32 v[156:157], v[22:23], v[94:95], v[156:157]
	v_pk_fma_f32 v[158:159], v[26:27], v[94:95], v[158:159]
	v_pk_fma_f32 v[168:169], v[30:31], v[94:95], v[168:169]
	v_pk_fma_f32 v[146:147], v[4:5], v[96:97], v[146:147]
	v_pk_fma_f32 v[148:149], v[8:9], v[96:97], v[148:149]
	v_pk_fma_f32 v[150:151], v[12:13], v[96:97], v[150:151]
	v_pk_fma_f32 v[152:153], v[16:17], v[96:97], v[152:153]
	v_pk_fma_f32 v[154:155], v[20:21], v[96:97], v[154:155]
	v_pk_fma_f32 v[156:157], v[24:25], v[96:97], v[156:157]
	v_pk_fma_f32 v[158:159], v[28:29], v[96:97], v[158:159]
	v_pk_fma_f32 v[168:169], v[32:33], v[96:97], v[168:169]
	s_waitcnt lgkmcnt(0)
	v_pk_fma_f32 v[170:171], v[34:35], v[94:95], v[170:171]
	v_pk_fma_f32 v[172:173], v[38:39], v[94:95], v[172:173]
	v_pk_fma_f32 v[174:175], v[42:43], v[94:95], v[174:175]
	v_pk_fma_f32 v[176:177], v[126:127], v[94:95], v[176:177]
	v_pk_fma_f32 v[178:179], v[130:131], v[94:95], v[178:179]
	v_pk_fma_f32 v[180:181], v[134:135], v[94:95], v[180:181]
	v_pk_fma_f32 v[182:183], v[138:139], v[94:95], v[182:183]
	v_pk_fma_f32 v[184:185], v[142:143], v[94:95], v[184:185]
	v_pk_fma_f32 v[170:171], v[36:37], v[96:97], v[170:171]
	v_pk_fma_f32 v[172:173], v[40:41], v[96:97], v[172:173]
	v_pk_fma_f32 v[174:175], v[44:45], v[96:97], v[174:175]
	v_pk_fma_f32 v[176:177], v[128:129], v[96:97], v[176:177]
	v_pk_fma_f32 v[178:179], v[132:133], v[96:97], v[178:179]
	v_pk_fma_f32 v[180:181], v[136:137], v[96:97], v[180:181]
	v_pk_fma_f32 v[182:183], v[140:141], v[96:97], v[182:183]
	v_pk_fma_f32 v[184:185], v[144:145], v[96:97], v[184:185]
	s_cmp_eq_u32 s24, 15
	s_cselect_b32 s8, s29, s8
	s_cselect_b32 s9, s30, s9
	global_load_dword v94, v186, s[8:9]
	s_add_u32 s8, s8, 0xc000
	s_addc_u32 s9, s9, 0
	global_load_dword v95, v186, s[8:9]
	s_add_u32 s8, s8, 0xc000
	s_addc_u32 s9, s9, 0
	global_load_dword v96, v186, s[8:9]
	s_add_u32 s8, s8, 0xc000
	s_addc_u32 s9, s9, 0
	global_load_dword v97, v186, s[8:9]
	s_add_u32 s8, s8, 0xc000
	s_addc_u32 s9, s9, 0
	ds_read_b128 v[2:5], v93 offset:16
	ds_read_b128 v[6:9], v93 offset:4112
	ds_read_b128 v[10:13], v93 offset:8208
	ds_read_b128 v[14:17], v93 offset:12304
	ds_read_b128 v[18:21], v93 offset:16400
	ds_read_b128 v[22:25], v93 offset:20496
	ds_read_b128 v[26:29], v93 offset:24592
	ds_read_b128 v[30:33], v93 offset:28688
	ds_read_b128 v[34:37], v93 offset:32784
	ds_read_b128 v[38:41], v93 offset:36880
	ds_read_b128 v[42:45], v93 offset:40976
	ds_read_b128 v[126:129], v93 offset:45072
	ds_read_b128 v[130:133], v93 offset:49168
	ds_read_b128 v[134:137], v93 offset:53264
	ds_read_b128 v[138:141], v93 offset:57360
	ds_read_b128 v[142:145], v93 offset:61456
	s_waitcnt vmcnt(28)
	s_waitcnt lgkmcnt(8)
	v_pk_fma_f32 v[146:147], v[2:3], v[98:99], v[146:147]
	v_pk_fma_f32 v[148:149], v[6:7], v[98:99], v[148:149]
	v_pk_fma_f32 v[150:151], v[10:11], v[98:99], v[150:151]
	v_pk_fma_f32 v[152:153], v[14:15], v[98:99], v[152:153]
	v_pk_fma_f32 v[154:155], v[18:19], v[98:99], v[154:155]
	v_pk_fma_f32 v[156:157], v[22:23], v[98:99], v[156:157]
	v_pk_fma_f32 v[158:159], v[26:27], v[98:99], v[158:159]
	v_pk_fma_f32 v[168:169], v[30:31], v[98:99], v[168:169]
	v_pk_fma_f32 v[146:147], v[4:5], v[100:101], v[146:147]
	v_pk_fma_f32 v[148:149], v[8:9], v[100:101], v[148:149]
	v_pk_fma_f32 v[150:151], v[12:13], v[100:101], v[150:151]
	v_pk_fma_f32 v[152:153], v[16:17], v[100:101], v[152:153]
	v_pk_fma_f32 v[154:155], v[20:21], v[100:101], v[154:155]
	v_pk_fma_f32 v[156:157], v[24:25], v[100:101], v[156:157]
	v_pk_fma_f32 v[158:159], v[28:29], v[100:101], v[158:159]
	v_pk_fma_f32 v[168:169], v[32:33], v[100:101], v[168:169]
	s_waitcnt lgkmcnt(0)
; __device__ NOINL void prep_mod(const float* c, const float* wada, const float* bada, float* mod, LAS unsigned char* lds, int wv) {
;     ...
;             for (int kk = 0; kk < 256; ++kk) { const float w = wp[(size_t)kk * 12288];
; #pragma unroll
;                 for (int b = 0; b < 16; ++b) acc[b] += cs[b * 1024 + kq * 256 + kk] * w; }
	v_pk_fma_f32 v[170:171], v[34:35], v[98:99], v[170:171]
	v_pk_fma_f32 v[172:173], v[38:39], v[98:99], v[172:173]
	v_pk_fma_f32 v[174:175], v[42:43], v[98:99], v[174:175]
	v_pk_fma_f32 v[176:177], v[126:127], v[98:99], v[176:177]
	v_pk_fma_f32 v[178:179], v[130:131], v[98:99], v[178:179]
	v_pk_fma_f32 v[180:181], v[134:135], v[98:99], v[180:181]
	v_pk_fma_f32 v[182:183], v[138:139], v[98:99], v[182:183]
	v_pk_fma_f32 v[184:185], v[142:143], v[98:99], v[184:185]
	v_pk_fma_f32 v[170:171], v[36:37], v[100:101], v[170:171]
	v_pk_fma_f32 v[172:173], v[40:41], v[100:101], v[172:173]
	v_pk_fma_f32 v[174:175], v[44:45], v[100:101], v[174:175]
	v_pk_fma_f32 v[176:177], v[128:129], v[100:101], v[176:177]
	v_pk_fma_f32 v[178:179], v[132:133], v[100:101], v[178:179]
	v_pk_fma_f32 v[180:181], v[136:137], v[100:101], v[180:181]
	v_pk_fma_f32 v[182:183], v[140:141], v[100:101], v[182:183]
	v_pk_fma_f32 v[184:185], v[144:145], v[100:101], v[184:185]
	global_load_dword v98, v186, s[8:9]
	s_add_u32 s8, s8, 0xc000
	s_addc_u32 s9, s9, 0
	global_load_dword v99, v186, s[8:9]
	s_add_u32 s8, s8, 0xc000
	s_addc_u32 s9, s9, 0
	global_load_dword v100, v186, s[8:9]
	s_add_u32 s8, s8, 0xc000
	s_addc_u32 s9, s9, 0
	global_load_dword v101, v186, s[8:9]
	s_add_u32 s8, s8, 0xc000
	s_addc_u32 s9, s9, 0
	ds_read_b128 v[2:5], v93 offset:32
	ds_read_b128 v[6:9], v93 offset:4128
	ds_read_b128 v[10:13], v93 offset:8224
	ds_read_b128 v[14:17], v93 offset:12320
	ds_read_b128 v[18:21], v93 offset:16416
	ds_read_b128 v[22:25], v93 offset:20512
	ds_read_b128 v[26:29], v93 offset:24608
	ds_read_b128 v[30:33], v93 offset:28704
	ds_read_b128 v[34:37], v93 offset:32800
	ds_read_b128 v[38:41], v93 offset:36896
	ds_read_b128 v[42:45], v93 offset:40992
	ds_read_b128 v[126:129], v93 offset:45088
	ds_read_b128 v[130:133], v93 offset:49184
	ds_read_b128 v[134:137], v93 offset:53280
	ds_read_b128 v[138:141], v93 offset:57376
	ds_read_b128 v[142:145], v93 offset:61472
	s_waitcnt vmcnt(28)
	s_waitcnt lgkmcnt(8)
	v_pk_fma_f32 v[146:147], v[2:3], v[102:103], v[146:147]
	v_pk_fma_f32 v[148:149], v[6:7], v[102:103], v[148:149]
	v_pk_fma_f32 v[150:151], v[10:11], v[102:103], v[150:151]
	v_pk_fma_f32 v[152:153], v[14:15], v[102:103], v[152:153]
	v_pk_fma_f32 v[154:155], v[18:19], v[102:103], v[154:155]
	v_pk_fma_f32 v[156:157], v[22:23], v[102:103], v[156:157]
	v_pk_fma_f32 v[158:159], v[26:27], v[102:103], v[158:159]
	v_pk_fma_f32 v[168:169], v[30:31], v[102:103], v[168:169]
	v_pk_fma_f32 v[146:147], v[4:5], v[104:105], v[146:147]
	v_pk_fma_f32 v[148:149], v[8:9], v[104:105], v[148:149]
	v_pk_fma_f32 v[150:151], v[12:13], v[104:105], v[150:151]
	v_pk_fma_f32 v[152:153], v[16:17], v[104:105], v[152:153]
	v_pk_fma_f32 v[154:155], v[20:21], v[104:105], v[154:155]
	v_pk_fma_f32 v[156:157], v[24:25], v[104:105], v[156:157]
	v_pk_fma_f32 v[158:159], v[28:29], v[104:105], v[158:159]
	v_pk_fma_f32 v[168:169], v[32:33], v[104:105], v[168:169]
	s_waitcnt lgkmcnt(0)
	v_pk_fma_f32 v[170:171], v[34:35], v[102:103], v[170:171]
	v_pk_fma_f32 v[172:173], v[38:39], v[102:103], v[172:173]
	v_pk_fma_f32 v[174:175], v[42:43], v[102:103], v[174:175]
	v_pk_fma_f32 v[176:177], v[126:127], v[102:103], v[176:177]
	v_pk_fma_f32 v[178:179], v[130:131], v[102:103], v[178:179]
	v_pk_fma_f32 v[180:181], v[134:135], v[102:103], v[180:181]
	v_pk_fma_f32 v[182:183], v[138:139], v[102:103], v[182:183]
	v_pk_fma_f32 v[184:185], v[142:143], v[102:103], v[184:185]
	v_pk_fma_f32 v[170:171], v[36:37], v[104:105], v[170:171]
	v_pk_fma_f32 v[172:173], v[40:41], v[104:105], v[172:173]
	v_pk_fma_f32 v[174:175], v[44:45], v[104:105], v[174:175]
	v_pk_fma_f32 v[176:177], v[128:129], v[104:105], v[176:177]
	v_pk_fma_f32 v[178:179], v[132:133], v[104:105], v[178:179]
	v_pk_fma_f32 v[180:181], v[136:137], v[104:105], v[180:181]
	v_pk_fma_f32 v[182:183], v[140:141], v[104:105], v[182:183]
	v_pk_fma_f32 v[184:185], v[144:145], v[104:105], v[184:185]
	global_load_dword v102, v186, s[8:9]
	s_add_u32 s8, s8, 0xc000
	s_addc_u32 s9, s9, 0
	global_load_dword v103, v186, s[8:9]
	s_add_u32 s8, s8, 0xc000
	s_addc_u32 s9, s9, 0
	global_load_dword v104, v186, s[8:9]
	s_add_u32 s8, s8, 0xc000
	s_addc_u32 s9, s9, 0
	global_load_dword v105, v186, s[8:9]
	s_add_u32 s8, s8, 0xc000
	s_addc_u32 s9, s9, 0
	ds_read_b128 v[2:5], v93 offset:48
	ds_read_b128 v[6:9], v93 offset:4144
	ds_read_b128 v[10:13], v93 offset:8240
	ds_read_b128 v[14:17], v93 offset:12336
	ds_read_b128 v[18:21], v93 offset:16432
	ds_read_b128 v[22:25], v93 offset:20528
	ds_read_b128 v[26:29], v93 offset:24624
	ds_read_b128 v[30:33], v93 offset:28720
	ds_read_b128 v[34:37], v93 offset:32816
	ds_read_b128 v[38:41], v93 offset:36912
	ds_read_b128 v[42:45], v93 offset:41008
	ds_read_b128 v[126:129], v93 offset:45104
	ds_read_b128 v[130:133], v93 offset:49200
	ds_read_b128 v[134:137], v93 offset:53296
	ds_read_b128 v[138:141], v93 offset:57392
	ds_read_b128 v[142:145], v93 offset:61488
	s_waitcnt vmcnt(28)
	s_waitcnt lgkmcnt(8)
	v_pk_fma_f32 v[146:147], v[2:3], v[106:107], v[146:147]
	v_pk_fma_f32 v[148:149], v[6:7], v[106:107], v[148:149]
	v_pk_fma_f32 v[150:151], v[10:11], v[106:107], v[150:151]
	v_pk_fma_f32 v[152:153], v[14:15], v[106:107], v[152:153]
	v_pk_fma_f32 v[154:155], v[18:19], v[106:107], v[154:155]
	v_pk_fma_f32 v[156:157], v[22:23], v[106:107], v[156:157]
	v_pk_fma_f32 v[158:159], v[26:27], v[106:107], v[158:159]
	v_pk_fma_f32 v[168:169], v[30:31], v[106:107], v[168:169]
	v_pk_fma_f32 v[146:147], v[4:5], v[108:109], v[146:147]
	v_pk_fma_f32 v[148:149], v[8:9], v[108:109], v[148:149]
	v_pk_fma_f32 v[150:151], v[12:13], v[108:109], v[150:151]
	v_pk_fma_f32 v[152:153], v[16:17], v[108:109], v[152:153]
	v_pk_fma_f32 v[154:155], v[20:21], v[108:109], v[154:155]
	v_pk_fma_f32 v[156:157], v[24:25], v[108:109], v[156:157]
	v_pk_fma_f32 v[158:159], v[28:29], v[108:109], v[158:159]
	v_pk_fma_f32 v[168:169], v[32:33], v[108:109], v[168:169]
	s_waitcnt lgkmcnt(0)
; __device__ NOINL void prep_mod(const float* c, const float* wada, const float* bada, float* mod, LAS unsigned char* lds, int wv) {
;     ...
;             for (int kk = 0; kk < 256; ++kk) { const float w = wp[(size_t)kk * 12288];
; #pragma unroll
;                 for (int b = 0; b < 16; ++b) acc[b] += cs[b * 1024 + kq * 256 + kk] * w; }
	v_pk_fma_f32 v[170:171], v[34:35], v[106:107], v[170:171]
	v_pk_fma_f32 v[172:173], v[38:39], v[106:107], v[172:173]
	v_pk_fma_f32 v[174:175], v[42:43], v[106:107], v[174:175]
	v_pk_fma_f32 v[176:177], v[126:127], v[106:107], v[176:177]
	v_pk_fma_f32 v[178:179], v[130:131], v[106:107], v[178:179]
	v_pk_fma_f32 v[180:181], v[134:135], v[106:107], v[180:181]
	v_pk_fma_f32 v[182:183], v[138:139], v[106:107], v[182:183]
	v_pk_fma_f32 v[184:185], v[142:143], v[106:107], v[184:185]
	v_pk_fma_f32 v[170:171], v[36:37], v[108:109], v[170:171]
	v_pk_fma_f32 v[172:173], v[40:41], v[108:109], v[172:173]
	v_pk_fma_f32 v[174:175], v[44:45], v[108:109], v[174:175]
	v_pk_fma_f32 v[176:177], v[128:129], v[108:109], v[176:177]
	v_pk_fma_f32 v[178:179], v[132:133], v[108:109], v[178:179]
	v_pk_fma_f32 v[180:181], v[136:137], v[108:109], v[180:181]
	v_pk_fma_f32 v[182:183], v[140:141], v[108:109], v[182:183]
	v_pk_fma_f32 v[184:185], v[144:145], v[108:109], v[184:185]
	global_load_dword v106, v186, s[8:9]
	s_add_u32 s8, s8, 0xc000
	s_addc_u32 s9, s9, 0
	global_load_dword v107, v186, s[8:9]
	s_add_u32 s8, s8, 0xc000
	s_addc_u32 s9, s9, 0
	global_load_dword v108, v186, s[8:9]
	s_add_u32 s8, s8, 0xc000
	s_addc_u32 s9, s9, 0
	global_load_dword v109, v186, s[8:9]
	s_add_u32 s8, s8, 0xc000
	s_addc_u32 s9, s9, 0
	ds_read_b128 v[2:5], v93 offset:64
	ds_read_b128 v[6:9], v93 offset:4160
	ds_read_b128 v[10:13], v93 offset:8256
	ds_read_b128 v[14:17], v93 offset:12352
	ds_read_b128 v[18:21], v93 offset:16448
	ds_read_b128 v[22:25], v93 offset:20544
	ds_read_b128 v[26:29], v93 offset:24640
	ds_read_b128 v[30:33], v93 offset:28736
	ds_read_b128 v[34:37], v93 offset:32832
	ds_read_b128 v[38:41], v93 offset:36928
	ds_read_b128 v[42:45], v93 offset:41024
	ds_read_b128 v[126:129], v93 offset:45120
	ds_read_b128 v[130:133], v93 offset:49216
	ds_read_b128 v[134:137], v93 offset:53312
	ds_read_b128 v[138:141], v93 offset:57408
	ds_read_b128 v[142:145], v93 offset:61504
	s_waitcnt vmcnt(28)
	s_waitcnt lgkmcnt(8)
	v_pk_fma_f32 v[146:147], v[2:3], v[110:111], v[146:147]
	v_pk_fma_f32 v[148:149], v[6:7], v[110:111], v[148:149]
	v_pk_fma_f32 v[150:151], v[10:11], v[110:111], v[150:151]
	v_pk_fma_f32 v[152:153], v[14:15], v[110:111], v[152:153]
	v_pk_fma_f32 v[154:155], v[18:19], v[110:111], v[154:155]
	v_pk_fma_f32 v[156:157], v[22:23], v[110:111], v[156:157]
	v_pk_fma_f32 v[158:159], v[26:27], v[110:111], v[158:159]
	v_pk_fma_f32 v[168:169], v[30:31], v[110:111], v[168:169]
	v_pk_fma_f32 v[146:147], v[4:5], v[112:113], v[146:147]
	v_pk_fma_f32 v[148:149], v[8:9], v[112:113], v[148:149]
	v_pk_fma_f32 v[150:151], v[12:13], v[112:113], v[150:151]
	v_pk_fma_f32 v[152:153], v[16:17], v[112:113], v[152:153]
	v_pk_fma_f32 v[154:155], v[20:21], v[112:113], v[154:155]
	v_pk_fma_f32 v[156:157], v[24:25], v[112:113], v[156:157]
	v_pk_fma_f32 v[158:159], v[28:29], v[112:113], v[158:159]
	v_pk_fma_f32 v[168:169], v[32:33], v[112:113], v[168:169]
	s_waitcnt lgkmcnt(0)
	v_pk_fma_f32 v[170:171], v[34:35], v[110:111], v[170:171]
	v_pk_fma_f32 v[172:173], v[38:39], v[110:111], v[172:173]
	v_pk_fma_f32 v[174:175], v[42:43], v[110:111], v[174:175]
	v_pk_fma_f32 v[176:177], v[126:127], v[110:111], v[176:177]
	v_pk_fma_f32 v[178:179], v[130:131], v[110:111], v[178:179]
	v_pk_fma_f32 v[180:181], v[134:135], v[110:111], v[180:181]
	v_pk_fma_f32 v[182:183], v[138:139], v[110:111], v[182:183]
	v_pk_fma_f32 v[184:185], v[142:143], v[110:111], v[184:185]
	v_pk_fma_f32 v[170:171], v[36:37], v[112:113], v[170:171]
	v_pk_fma_f32 v[172:173], v[40:41], v[112:113], v[172:173]
	v_pk_fma_f32 v[174:175], v[44:45], v[112:113], v[174:175]
	v_pk_fma_f32 v[176:177], v[128:129], v[112:113], v[176:177]
	v_pk_fma_f32 v[178:179], v[132:133], v[112:113], v[178:179]
	v_pk_fma_f32 v[180:181], v[136:137], v[112:113], v[180:181]
	v_pk_fma_f32 v[182:183], v[140:141], v[112:113], v[182:183]
	v_pk_fma_f32 v[184:185], v[144:145], v[112:113], v[184:185]
	global_load_dword v110, v186, s[8:9]
	s_add_u32 s8, s8, 0xc000
	s_addc_u32 s9, s9, 0
	global_load_dword v111, v186, s[8:9]
	s_add_u32 s8, s8, 0xc000
	s_addc_u32 s9, s9, 0
	global_load_dword v112, v186, s[8:9]
	s_add_u32 s8, s8, 0xc000
	s_addc_u32 s9, s9, 0
	global_load_dword v113, v186, s[8:9]
	s_add_u32 s8, s8, 0xc000
	s_addc_u32 s9, s9, 0
	ds_read_b128 v[2:5], v93 offset:80
	ds_read_b128 v[6:9], v93 offset:4176
	ds_read_b128 v[10:13], v93 offset:8272
	ds_read_b128 v[14:17], v93 offset:12368
	ds_read_b128 v[18:21], v93 offset:16464
	ds_read_b128 v[22:25], v93 offset:20560
	ds_read_b128 v[26:29], v93 offset:24656
	ds_read_b128 v[30:33], v93 offset:28752
	ds_read_b128 v[34:37], v93 offset:32848
	ds_read_b128 v[38:41], v93 offset:36944
	ds_read_b128 v[42:45], v93 offset:41040
	ds_read_b128 v[126:129], v93 offset:45136
	ds_read_b128 v[130:133], v93 offset:49232
	ds_read_b128 v[134:137], v93 offset:53328
	ds_read_b128 v[138:141], v93 offset:57424
	ds_read_b128 v[142:145], v93 offset:61520
	s_waitcnt vmcnt(28)
	s_waitcnt lgkmcnt(8)
	v_pk_fma_f32 v[146:147], v[2:3], v[114:115], v[146:147]
	v_pk_fma_f32 v[148:149], v[6:7], v[114:115], v[148:149]
	v_pk_fma_f32 v[150:151], v[10:11], v[114:115], v[150:151]
	v_pk_fma_f32 v[152:153], v[14:15], v[114:115], v[152:153]
	v_pk_fma_f32 v[154:155], v[18:19], v[114:115], v[154:155]
	v_pk_fma_f32 v[156:157], v[22:23], v[114:115], v[156:157]
	v_pk_fma_f32 v[158:159], v[26:27], v[114:115], v[158:159]
	v_pk_fma_f32 v[168:169], v[30:31], v[114:115], v[168:169]
	v_pk_fma_f32 v[146:147], v[4:5], v[116:117], v[146:147]
	v_pk_fma_f32 v[148:149], v[8:9], v[116:117], v[148:149]
	v_pk_fma_f32 v[150:151], v[12:13], v[116:117], v[150:151]
	v_pk_fma_f32 v[152:153], v[16:17], v[116:117], v[152:153]
	v_pk_fma_f32 v[154:155], v[20:21], v[116:117], v[154:155]
	v_pk_fma_f32 v[156:157], v[24:25], v[116:117], v[156:157]
	v_pk_fma_f32 v[158:159], v[28:29], v[116:117], v[158:159]
	v_pk_fma_f32 v[168:169], v[32:33], v[116:117], v[168:169]
	s_waitcnt lgkmcnt(0)
; __device__ NOINL void prep_mod(const float* c, const float* wada, const float* bada, float* mod, LAS unsigned char* lds, int wv) {
;     ...
;             for (int kk = 0; kk < 256; ++kk) { const float w = wp[(size_t)kk * 12288];
; #pragma unroll
;                 for (int b = 0; b < 16; ++b) acc[b] += cs[b * 1024 + kq * 256 + kk] * w; }
	v_pk_fma_f32 v[170:171], v[34:35], v[114:115], v[170:171]
	v_pk_fma_f32 v[172:173], v[38:39], v[114:115], v[172:173]
	v_pk_fma_f32 v[174:175], v[42:43], v[114:115], v[174:175]
	v_pk_fma_f32 v[176:177], v[126:127], v[114:115], v[176:177]
	v_pk_fma_f32 v[178:179], v[130:131], v[114:115], v[178:179]
	v_pk_fma_f32 v[180:181], v[134:135], v[114:115], v[180:181]
	v_pk_fma_f32 v[182:183], v[138:139], v[114:115], v[182:183]
	v_pk_fma_f32 v[184:185], v[142:143], v[114:115], v[184:185]
	v_pk_fma_f32 v[170:171], v[36:37], v[116:117], v[170:171]
	v_pk_fma_f32 v[172:173], v[40:41], v[116:117], v[172:173]
	v_pk_fma_f32 v[174:175], v[44:45], v[116:117], v[174:175]
	v_pk_fma_f32 v[176:177], v[128:129], v[116:117], v[176:177]
	v_pk_fma_f32 v[178:179], v[132:133], v[116:117], v[178:179]
	v_pk_fma_f32 v[180:181], v[136:137], v[116:117], v[180:181]
	v_pk_fma_f32 v[182:183], v[140:141], v[116:117], v[182:183]
	v_pk_fma_f32 v[184:185], v[144:145], v[116:117], v[184:185]
	global_load_dword v114, v186, s[8:9]
	s_add_u32 s8, s8, 0xc000
	s_addc_u32 s9, s9, 0
	global_load_dword v115, v186, s[8:9]
	s_add_u32 s8, s8, 0xc000
	s_addc_u32 s9, s9, 0
	global_load_dword v116, v186, s[8:9]
	s_add_u32 s8, s8, 0xc000
	s_addc_u32 s9, s9, 0
	global_load_dword v117, v186, s[8:9]
	s_add_u32 s8, s8, 0xc000
	s_addc_u32 s9, s9, 0
	ds_read_b128 v[2:5], v93 offset:96
	ds_read_b128 v[6:9], v93 offset:4192
	ds_read_b128 v[10:13], v93 offset:8288
	ds_read_b128 v[14:17], v93 offset:12384
	ds_read_b128 v[18:21], v93 offset:16480
	ds_read_b128 v[22:25], v93 offset:20576
	ds_read_b128 v[26:29], v93 offset:24672
	ds_read_b128 v[30:33], v93 offset:28768
	ds_read_b128 v[34:37], v93 offset:32864
	ds_read_b128 v[38:41], v93 offset:36960
	ds_read_b128 v[42:45], v93 offset:41056
	ds_read_b128 v[126:129], v93 offset:45152
	ds_read_b128 v[130:133], v93 offset:49248
	ds_read_b128 v[134:137], v93 offset:53344
	ds_read_b128 v[138:141], v93 offset:57440
	ds_read_b128 v[142:145], v93 offset:61536
	s_waitcnt vmcnt(28)
	s_waitcnt lgkmcnt(8)
	v_pk_fma_f32 v[146:147], v[2:3], v[118:119], v[146:147]
	v_pk_fma_f32 v[148:149], v[6:7], v[118:119], v[148:149]
	v_pk_fma_f32 v[150:151], v[10:11], v[118:119], v[150:151]
	v_pk_fma_f32 v[152:153], v[14:15], v[118:119], v[152:153]
	v_pk_fma_f32 v[154:155], v[18:19], v[118:119], v[154:155]
	v_pk_fma_f32 v[156:157], v[22:23], v[118:119], v[156:157]
	v_pk_fma_f32 v[158:159], v[26:27], v[118:119], v[158:159]
	v_pk_fma_f32 v[168:169], v[30:31], v[118:119], v[168:169]
	v_pk_fma_f32 v[146:147], v[4:5], v[120:121], v[146:147]
	v_pk_fma_f32 v[148:149], v[8:9], v[120:121], v[148:149]
	v_pk_fma_f32 v[150:151], v[12:13], v[120:121], v[150:151]
	v_pk_fma_f32 v[152:153], v[16:17], v[120:121], v[152:153]
	v_pk_fma_f32 v[154:155], v[20:21], v[120:121], v[154:155]
	v_pk_fma_f32 v[156:157], v[24:25], v[120:121], v[156:157]
	v_pk_fma_f32 v[158:159], v[28:29], v[120:121], v[158:159]
	v_pk_fma_f32 v[168:169], v[32:33], v[120:121], v[168:169]
	s_waitcnt lgkmcnt(0)
	v_pk_fma_f32 v[170:171], v[34:35], v[118:119], v[170:171]
	v_pk_fma_f32 v[172:173], v[38:39], v[118:119], v[172:173]
	v_pk_fma_f32 v[174:175], v[42:43], v[118:119], v[174:175]
	v_pk_fma_f32 v[176:177], v[126:127], v[118:119], v[176:177]
	v_pk_fma_f32 v[178:179], v[130:131], v[118:119], v[178:179]
	v_pk_fma_f32 v[180:181], v[134:135], v[118:119], v[180:181]
	v_pk_fma_f32 v[182:183], v[138:139], v[118:119], v[182:183]
	v_pk_fma_f32 v[184:185], v[142:143], v[118:119], v[184:185]
	v_pk_fma_f32 v[170:171], v[36:37], v[120:121], v[170:171]
	v_pk_fma_f32 v[172:173], v[40:41], v[120:121], v[172:173]
	v_pk_fma_f32 v[174:175], v[44:45], v[120:121], v[174:175]
	v_pk_fma_f32 v[176:177], v[128:129], v[120:121], v[176:177]
	v_pk_fma_f32 v[178:179], v[132:133], v[120:121], v[178:179]
	v_pk_fma_f32 v[180:181], v[136:137], v[120:121], v[180:181]
	v_pk_fma_f32 v[182:183], v[140:141], v[120:121], v[182:183]
	v_pk_fma_f32 v[184:185], v[144:145], v[120:121], v[184:185]
	global_load_dword v118, v186, s[8:9]
	s_add_u32 s8, s8, 0xc000
	s_addc_u32 s9, s9, 0
	global_load_dword v119, v186, s[8:9]
	s_add_u32 s8, s8, 0xc000
	s_addc_u32 s9, s9, 0
	global_load_dword v120, v186, s[8:9]
	s_add_u32 s8, s8, 0xc000
	s_addc_u32 s9, s9, 0
	global_load_dword v121, v186, s[8:9]
	s_add_u32 s8, s8, 0xc000
	s_addc_u32 s9, s9, 0
	ds_read_b128 v[2:5], v93 offset:112
	ds_read_b128 v[6:9], v93 offset:4208
	ds_read_b128 v[10:13], v93 offset:8304
	ds_read_b128 v[14:17], v93 offset:12400
	ds_read_b128 v[18:21], v93 offset:16496
	ds_read_b128 v[22:25], v93 offset:20592
	ds_read_b128 v[26:29], v93 offset:24688
	ds_read_b128 v[30:33], v93 offset:28784
	ds_read_b128 v[34:37], v93 offset:32880
	ds_read_b128 v[38:41], v93 offset:36976
	ds_read_b128 v[42:45], v93 offset:41072
	ds_read_b128 v[126:129], v93 offset:45168
	ds_read_b128 v[130:133], v93 offset:49264
	ds_read_b128 v[134:137], v93 offset:53360
	ds_read_b128 v[138:141], v93 offset:57456
	ds_read_b128 v[142:145], v93 offset:61552
	s_waitcnt vmcnt(28)
	s_waitcnt lgkmcnt(8)
	v_pk_fma_f32 v[146:147], v[2:3], v[122:123], v[146:147]
	v_pk_fma_f32 v[148:149], v[6:7], v[122:123], v[148:149]
	v_pk_fma_f32 v[150:151], v[10:11], v[122:123], v[150:151]
	v_pk_fma_f32 v[152:153], v[14:15], v[122:123], v[152:153]
	v_pk_fma_f32 v[154:155], v[18:19], v[122:123], v[154:155]
	v_pk_fma_f32 v[156:157], v[22:23], v[122:123], v[156:157]
	v_pk_fma_f32 v[158:159], v[26:27], v[122:123], v[158:159]
	v_pk_fma_f32 v[168:169], v[30:31], v[122:123], v[168:169]
	v_pk_fma_f32 v[146:147], v[4:5], v[124:125], v[146:147]
	v_pk_fma_f32 v[148:149], v[8:9], v[124:125], v[148:149]
	v_pk_fma_f32 v[150:151], v[12:13], v[124:125], v[150:151]
	v_pk_fma_f32 v[152:153], v[16:17], v[124:125], v[152:153]
	v_pk_fma_f32 v[154:155], v[20:21], v[124:125], v[154:155]
	v_pk_fma_f32 v[156:157], v[24:25], v[124:125], v[156:157]
	v_pk_fma_f32 v[158:159], v[28:29], v[124:125], v[158:159]
	v_pk_fma_f32 v[168:169], v[32:33], v[124:125], v[168:169]
	s_waitcnt lgkmcnt(0)
	v_pk_fma_f32 v[170:171], v[34:35], v[122:123], v[170:171]
	v_pk_fma_f32 v[172:173], v[38:39], v[122:123], v[172:173]
	v_pk_fma_f32 v[174:175], v[42:43], v[122:123], v[174:175]
	v_pk_fma_f32 v[176:177], v[126:127], v[122:123], v[176:177]
	v_pk_fma_f32 v[178:179], v[130:131], v[122:123], v[178:179]
	v_pk_fma_f32 v[180:181], v[134:135], v[122:123], v[180:181]
	v_pk_fma_f32 v[182:183], v[138:139], v[122:123], v[182:183]
	v_pk_fma_f32 v[184:185], v[142:143], v[122:123], v[184:185]
	v_pk_fma_f32 v[170:171], v[36:37], v[124:125], v[170:171]
	v_pk_fma_f32 v[172:173], v[40:41], v[124:125], v[172:173]
	v_pk_fma_f32 v[174:175], v[44:45], v[124:125], v[174:175]
	v_pk_fma_f32 v[176:177], v[128:129], v[124:125], v[176:177]
	v_pk_fma_f32 v[178:179], v[132:133], v[124:125], v[178:179]
	v_pk_fma_f32 v[180:181], v[136:137], v[124:125], v[180:181]
	v_pk_fma_f32 v[182:183], v[140:141], v[124:125], v[182:183]
	v_pk_fma_f32 v[184:185], v[144:145], v[124:125], v[184:185]
	v_add_u32_e32 v93, 0x80, v93
	s_add_i32 s24, s24, 1
	s_cmp_eq_u32 s24, 16
	s_cbranch_scc0 .Lpm_loop
; __device__ NOINL void prep_mod(const float* c, const float* wada, const float* bada, float* mod, LAS unsigned char* lds, int wv) {
;     ...
;         }
;         __syncthreads();
; #pragma unroll
;         for (int b = 0; b < 16; ++b) red[(kq * 16 + b) * 128 + j] = acc[b];
;         __syncthreads();
;         for (int i = 0; i < 4; ++i) { const int o = i * 512 + tid, b = o >> 7, jj = o & 127;
;             const float s = red[(0 * 16 + b) * 128 + jj] + red[(1 * 16 + b) * 128 + jj] + red[(2 * 16 + b) * 128 + jj] + red[(3 * 16 + b) * 128 + jj] + bada[l * 12288 + j0 + jj];
;             mod[((size_t)l * 16 + b) * 12288 + j0 + jj] = s; }
	s_waitcnt vmcnt(0)
	v_add_f32_e32 v70, v146, v147
	v_add_f32_e32 v71, v148, v149
	v_add_f32_e32 v76, v150, v151
	v_add_f32_e32 v77, v152, v153
	v_add_f32_e32 v74, v154, v155
	v_add_f32_e32 v75, v156, v157
	v_add_f32_e32 v72, v158, v159
	v_add_f32_e32 v73, v168, v169
	v_add_f32_e32 v68, v170, v171
	v_add_f32_e32 v69, v172, v173
	v_add_f32_e32 v66, v174, v175
	v_add_f32_e32 v67, v176, v177
	v_add_f32_e32 v64, v178, v179
	v_add_f32_e32 v65, v180, v181
	v_add_f32_e32 v62, v182, v183
	v_add_f32_e32 v63, v184, v185
	s_mul_i32 s8, s2, 0x3000
	s_add_i32 s8, s8, s6
	v_or_b32_e32 v2, s8, v78
	v_ashrrev_i32_e32 v3, 31, v2
	v_lshl_add_u64 v[2:3], v[2:3], 2, s[58:59]
	s_barrier
	ds_write2st64_b32 v92, v70, v71 offset1:2
	ds_write2st64_b32 v92, v76, v77 offset0:4 offset1:6
	ds_write2st64_b32 v92, v74, v75 offset0:8 offset1:10
	ds_write2st64_b32 v92, v72, v73 offset0:12 offset1:14
	ds_write2st64_b32 v92, v68, v69 offset0:16 offset1:18
	ds_write2st64_b32 v92, v66, v67 offset0:20 offset1:22
	ds_write2st64_b32 v92, v64, v65 offset0:24 offset1:26
	ds_write2st64_b32 v92, v62, v63 offset0:28 offset1:30
	s_waitcnt lgkmcnt(0)
	s_barrier
	global_load_dword v12, v[2:3], off
	ds_read2st64_b32 v[6:7], v82 offset0:32 offset1:64
	ds_read_b32 v13, v81
	ds_read_b32 v14, v82 offset:24576
	s_lshl_b64 s[2:3], s[2:3], 4
	v_lshl_add_u64 v[4:5], s[6:7], 2, v[52:53]
	v_lshl_add_u64 v[8:9], s[2:3], 0, v[46:47]
	s_waitcnt lgkmcnt(0)
	v_add_f32_e32 v6, v13, v6
	v_add_f32_e32 v6, v6, v7
	v_mad_u64_u32 v[10:11], s[6:7], v8, s15, v[4:5]
	v_add_f32_e32 v6, v6, v14
	v_mad_i32_i24 v11, v9, s15, v11
	s_waitcnt vmcnt(0)
	v_add_f32_e32 v6, v6, v12
	global_store_dword v[10:11], v6, off
	global_load_dword v12, v[2:3], off
	ds_read2st64_b32 v[8:9], v84 offset0:32 offset1:64
	ds_read_b32 v13, v83
	ds_read_b32 v14, v84 offset:24576
	v_lshl_add_u64 v[6:7], s[2:3], 0, v[54:55]
	v_mad_u64_u32 v[10:11], s[6:7], v6, s15, v[4:5]
	s_waitcnt lgkmcnt(0)
	v_add_f32_e32 v6, v13, v8
	v_add_f32_e32 v6, v6, v9
	v_add_f32_e32 v6, v6, v14
	v_mad_i32_i24 v11, v7, s15, v11
	s_waitcnt vmcnt(0)
	v_add_f32_e32 v6, v6, v12
	global_store_dword v[10:11], v6, off
	global_load_dword v12, v[2:3], off
	ds_read2st64_b32 v[8:9], v86 offset0:32 offset1:64
	ds_read_b32 v13, v85
	ds_read_b32 v14, v86 offset:24576
	v_lshl_add_u64 v[6:7], s[2:3], 0, v[56:57]
	v_mad_u64_u32 v[10:11], s[6:7], v6, s15, v[4:5]
	s_waitcnt lgkmcnt(0)
	v_add_f32_e32 v6, v13, v8
	v_add_f32_e32 v6, v6, v9
	v_add_f32_e32 v6, v6, v14
	v_mad_i32_i24 v11, v7, s15, v11
	s_waitcnt vmcnt(0)
	v_add_f32_e32 v6, v6, v12
	global_store_dword v[10:11], v6, off
	global_load_dword v8, v[2:3], off
	s_load_dword s6, s[0:1], 0xa0
	ds_read2st64_b32 v[6:7], v88 offset0:32 offset1:64
	ds_read_b32 v9, v87
	ds_read_b32 v10, v88 offset:24576
	v_lshl_add_u64 v[2:3], s[2:3], 0, v[58:59]
	v_mad_u64_u32 v[4:5], s[2:3], v2, s15, v[4:5]
	s_waitcnt lgkmcnt(0)
	v_add_f32_e32 v2, v9, v6
	v_add_f32_e32 v2, v2, v7
	v_add_f32_e32 v2, v2, v10
	v_mad_i32_i24 v5, v3, s15, v5
	s_waitcnt vmcnt(0)
	v_add_f32_e32 v2, v2, v8
	global_store_dword v[4:5], v2, off
	s_add_i32 s10, s6, s10
	s_cmpk_gt_i32 s10, 0xbf
	s_cbranch_scc0 .LBB0_2

; __device__ __forceinline__ unsigned cvt_pk_bf16(float lo, float hi) { f32x2_t f = {lo, hi}; bf16x2_t v = __builtin_convertvector(f, bf16x2_t); return __builtin_bit_cast(unsigned, v); }
; __device__ __forceinline__ void conv_tile(LAS float* tl, const float* src, int ldsrc, int k0, int n0, int N, bf16_t* dst, int lddst, int mode, int wv) {
;     ...
;     for (int i = 0; i < 8; ++i) { const int e = i * 512 + tid, kk = e >> 6, n = n0 + (e & 63) * 4;
;         v[i] = (f32x4){0.f, 0.f, 0.f, 0.f};
;         if (n + 3 < N) v[i] = *(const f32x4*)(src + (size_t)(k0 + kk) * ldsrc + n);
;         else { for (int j = 0; j < 4; ++j) if (n + j < N) v[i][j] = src[(size_t)(k0 + kk) * ldsrc + n + j]; } }
;     __syncthreads();
; #pragma unroll
;     for (int i = 0; i < 8; ++i) { const int e = i * 512 + tid, kk = e >> 6, n4 = (e & 63) * 4;
; #pragma unroll
;         for (int j = 0; j < 4; ++j) tl[kk * S + n4 + j] = v[i][j]; }
;     __syncthreads();
; #pragma unroll
;     for (int i = 0; i < 4; ++i) { const int item = i * 512 + tid, nl = item >> 3, k8 = (item & 7) * 8, n = n0 + nl;
;         int row = n;
;         if (mode == 0) row = n < 8192 ? n : (n < 8200 ? -1 : n - 8);
;         else if (mode == 2) { const int c = n % DFF, gt = n / DFF; row = (c >> 7) * 256 + gt * 128 + (c & 127); }
;         if (n < N && row >= 0) {
;             float x[8];
; #pragma unroll
;             for (int j = 0; j < 8; ++j) x[j] = tl[(k8 + j) * S + nl];
;             u32x4 w; w.x = cvt_pk_bf16(x[0], x[1]); w.y = cvt_pk_bf16(x[2], x[3]); w.z = cvt_pk_bf16(x[4], x[5]); w.w = cvt_pk_bf16(x[6], x[7]);
;             *(u32x4*)(dst + (size_t)row * lddst + k0 + k8) = w;
; __device__ NOINL void convert_weights(const float* win, const float* wbr, const float* wout, const float* wup, const float* wdown, unsigned char* ws, LAS unsigned char* lds, int wv) {
;     ...
;         else { const int q = t - T3, tk = q / 8, tn = q % 8;
;             conv_tile(tl, wdown, 2048, tk * 64, tn * 256, 2048, (bf16_t*)(ws + WS_WDOWN), DFF, 1, wv); }
.LBB0_15:
	s_cmpk_gt_i32 s26, 0x71f
	s_mov_b64 s[2:3], -1
	s_cbranch_scc0 .LBB0_60
	s_cmpk_gt_u32 s26, 0x81f
	s_cbranch_scc0 .LBB0_49
	s_cmpk_gt_u32 s26, 0x91f
	s_cbranch_scc0 .LBB0_38
	s_cmpk_gt_u32 s26, 0xe9f
	s_cbranch_scc0 .LBB0_28
	s_lshl_b32 s2, s26, 3
	s_and_b32 s2, s2, 0x7fffffc0
	v_mov_b32_e32 v9, v236
	s_add_i32 s18, s2, 0xffff8b00
	s_lshl_b32 s2, s26, 8
	s_and_b32 s20, s2, 0x700
	v_lshlrev_b32_e32 v2, 2, v9
	v_add_u32_e32 v8, 0x200, v9
	v_and_b32_e32 v42, 0xfc, v2
	v_ashrrev_i32_e32 v43, 6, v9
	v_ashrrev_i32_e32 v44, 6, v8
	v_or_b32_e32 v2, s20, v42
	v_add_u32_e32 v6, s18, v43
	v_add_u32_e32 v10, s18, v44
	v_lshlrev_b32_e32 v2, 2, v2
	v_ashrrev_i32_e32 v7, 31, v6
	v_ashrrev_i32_e32 v11, 31, v10
	v_lshl_add_u64 v[4:5], s[14:15], 0, v[2:3]
	v_lshlrev_b64 v[6:7], 13, v[6:7]
	v_lshlrev_b64 v[10:11], 13, v[10:11]
	v_lshl_add_u64 v[6:7], v[4:5], 0, v[6:7]
	v_lshl_add_u64 v[14:15], v[4:5], 0, v[10:11]
	global_load_dwordx4 v[10:13], v[6:7], off
	s_nop 0
	global_load_dwordx4 v[14:17], v[14:15], off
	v_add_u32_e32 v7, 0x400, v9
	v_add_u32_e32 v6, 0x600, v9
	v_add_u32_e32 v2, 0x800, v9
	v_ashrrev_i32_e32 v45, 6, v7
	v_ashrrev_i32_e32 v46, 6, v6
	v_ashrrev_i32_e32 v48, 6, v2
	v_add_u32_e32 v2, 0xa00, v9
	v_add_u32_e32 v18, s18, v45
	v_add_u32_e32 v20, s18, v46
	v_ashrrev_i32_e32 v50, 6, v2
	v_add_u32_e32 v2, 0xc00, v9
	v_ashrrev_i32_e32 v19, 31, v18
	v_ashrrev_i32_e32 v21, 31, v20
	v_add_u32_e32 v26, s18, v48
	v_add_u32_e32 v28, s18, v50
	v_ashrrev_i32_e32 v51, 6, v2
	v_lshlrev_b64 v[18:19], 13, v[18:19]
	v_lshlrev_b64 v[20:21], 13, v[20:21]
	v_ashrrev_i32_e32 v27, 31, v26
	v_ashrrev_i32_e32 v29, 31, v28
	v_add_u32_e32 v34, s18, v51
	v_lshl_add_u64 v[18:19], v[4:5], 0, v[18:19]
	v_lshl_add_u64 v[22:23], v[4:5], 0, v[20:21]
	v_lshlrev_b64 v[26:27], 13, v[26:27]
	v_lshlrev_b64 v[28:29], 13, v[28:29]
	v_ashrrev_i32_e32 v35, 31, v34
	global_load_dwordx4 v[18:21], v[18:19], off
	s_nop 0
	global_load_dwordx4 v[22:25], v[22:23], off
	v_lshl_add_u64 v[26:27], v[4:5], 0, v[26:27]
	v_lshl_add_u64 v[30:31], v[4:5], 0, v[28:29]
	v_lshlrev_b64 v[34:35], 13, v[34:35]
	v_add_u32_e32 v2, 0xe00, v9
	global_load_dwordx4 v[26:29], v[26:27], off
	s_nop 0
	global_load_dwordx4 v[30:33], v[30:31], off
	v_lshl_add_u64 v[34:35], v[4:5], 0, v[34:35]
	v_ashrrev_i32_e32 v52, 6, v2
	global_load_dwordx4 v[34:37], v[34:35], off
	v_add_u32_e32 v38, s18, v52
	v_ashrrev_i32_e32 v39, 31, v38
	v_lshlrev_b64 v[38:39], 13, v[38:39]
	v_lshl_add_u64 v[4:5], v[4:5], 0, v[38:39]
	global_load_dwordx4 v[38:41], v[4:5], off
	v_lshl_add_u32 v2, v42, 2, 0
	v_mad_u64_u32 v[4:5], s[2:3], v43, s37, v[2:3]
	v_mad_u64_u32 v[42:43], s[2:3], v44, s37, v[2:3]
	v_mad_u64_u32 v[44:45], s[2:3], v45, s37, v[2:3]
	v_mad_u64_u32 v[46:47], s[2:3], v46, s37, v[2:3]
	v_mad_u64_u32 v[48:49], s[2:3], v48, s37, v[2:3]
	s_waitcnt lgkmcnt(0)
	s_barrier
	s_waitcnt vmcnt(0)
	ds_write2_b32 v4, v10, v11 offset1:1
	ds_write2_b32 v4, v12, v13 offset0:2 offset1:3
	ds_write2_b32 v42, v14, v15 offset1:1
	ds_write2_b32 v42, v16, v17 offset0:2 offset1:3
	ds_write2_b32 v44, v18, v19 offset1:1
	ds_write2_b32 v44, v20, v21 offset0:2 offset1:3
	ds_write2_b32 v46, v22, v23 offset1:1
	ds_write2_b32 v46, v24, v25 offset0:2 offset1:3
	ds_write2_b32 v48, v26, v27 offset1:1
	ds_write2_b32 v48, v28, v29 offset0:2 offset1:3
	v_mad_u64_u32 v[4:5], s[2:3], v50, s37, v[2:3]
	ds_write2_b32 v4, v30, v31 offset1:1
	ds_write2_b32 v4, v32, v33 offset0:2 offset1:3
	v_mad_u64_u32 v[4:5], s[2:3], v51, s37, v[2:3]
	ds_write2_b32 v4, v34, v35 offset1:1
	ds_write2_b32 v4, v36, v37 offset0:2 offset1:3
	v_mad_u64_u32 v[4:5], s[2:3], v52, s37, v[2:3]
	v_lshlrev_b32_e32 v2, 3, v9
	s_lshl_b64 s[2:3], s[18:19], 1
	v_and_b32_e32 v11, 56, v2
	s_add_u32 s2, s27, s2
	s_addc_u32 s3, s28, s3
	v_lshlrev_b32_e32 v2, 1, v11
	v_ashrrev_i32_e32 v10, 3, v9
	ds_write2_b32 v4, v38, v39 offset1:1
	ds_write2_b32 v4, v40, v41 offset0:2 offset1:3
	v_lshl_add_u64 v[4:5], s[2:3], 0, v[2:3]
	v_add_u32_e32 v2, s20, v10
	v_cmp_gt_u32_e32 vcc, s36, v2
	v_mul_u32_u24_e32 v9, 0x414, v11
	s_waitcnt lgkmcnt(0)
	s_barrier
	s_and_saveexec_b64 s[2:3], vcc
	s_cbranch_execz .LBB0_21
	v_lshlrev_b32_e32 v10, 2, v10
	v_add3_u32 v10, 0, v10, v9
	ds_read_b32 v11, v10
	ds_read_b32 v12, v10 offset:1044
	ds_read_b32 v13, v10 offset:2088
	ds_read_b32 v14, v10 offset:3132
	ds_read_b32 v15, v10 offset:4176
	ds_read_b32 v16, v10 offset:5220
	ds_read_b32 v17, v10 offset:6264
	ds_read_b32 v18, v10 offset:7308
	v_mul_lo_u32 v2, v2, s38
	s_waitcnt lgkmcnt(6)
	v_cvt_pk_bf16_f32 v10, v11, v12
	s_waitcnt lgkmcnt(4)
	v_cvt_pk_bf16_f32 v11, v13, v14
	s_waitcnt lgkmcnt(2)
	v_cvt_pk_bf16_f32 v12, v15, v16
	s_waitcnt lgkmcnt(0)
	v_cvt_pk_bf16_f32 v13, v17, v18
	v_lshl_add_u64 v[14:15], v[2:3], 1, v[4:5]
	global_store_dwordx4 v[14:15], v[10:13], off
.LBB0_21:
	s_or_b64 exec, exec, s[2:3]
	v_ashrrev_i32_e32 v8, 3, v8
	v_add_u32_e32 v2, s20, v8
	v_cmp_gt_u32_e32 vcc, s36, v2
	s_and_saveexec_b64 s[2:3], vcc
	s_cbranch_execz .LBB0_23
	v_lshlrev_b32_e32 v8, 2, v8
	v_add3_u32 v8, 0, v8, v9
	ds_read_b32 v10, v8
	ds_read_b32 v11, v8 offset:1044
	ds_read_b32 v12, v8 offset:2088
	ds_read_b32 v13, v8 offset:3132
	ds_read_b32 v14, v8 offset:4176
	ds_read_b32 v15, v8 offset:5220
	ds_read_b32 v16, v8 offset:6264
	ds_read_b32 v8, v8 offset:7308
	v_mul_lo_u32 v2, v2, s38
	s_waitcnt lgkmcnt(0)
	v_cvt_pk_bf16_f32 v10, v10, v11
	v_cvt_pk_bf16_f32 v11, v12, v13
	v_cvt_pk_bf16_f32 v12, v14, v15
	v_cvt_pk_bf16_f32 v13, v16, v8
	v_lshl_add_u64 v[14:15], v[2:3], 1, v[4:5]
	global_store_dwordx4 v[14:15], v[10:13], off
.LBB0_23:
	s_or_b64 exec, exec, s[2:3]
	v_ashrrev_i32_e32 v7, 3, v7
	v_add_u32_e32 v2, s20, v7
	v_cmp_gt_u32_e32 vcc, s36, v2
	s_and_saveexec_b64 s[2:3], vcc
	s_cbranch_execz .LBB0_25
	v_lshlrev_b32_e32 v7, 2, v7
	v_add3_u32 v7, 0, v7, v9
	ds_read_b32 v8, v7
	ds_read_b32 v10, v7 offset:1044
	ds_read_b32 v11, v7 offset:2088
	ds_read_b32 v12, v7 offset:3132
	ds_read_b32 v13, v7 offset:4176
	ds_read_b32 v14, v7 offset:5220
	ds_read_b32 v15, v7 offset:6264
	ds_read_b32 v7, v7 offset:7308
	v_mul_lo_u32 v2, v2, s38
	s_waitcnt lgkmcnt(0)
	v_cvt_pk_bf16_f32 v10, v8, v10
	v_cvt_pk_bf16_f32 v11, v11, v12
	v_cvt_pk_bf16_f32 v12, v13, v14
	v_cvt_pk_bf16_f32 v13, v15, v7
	v_lshl_add_u64 v[14:15], v[2:3], 1, v[4:5]
	global_store_dwordx4 v[14:15], v[10:13], off
.LBB0_25:
	s_or_b64 exec, exec, s[2:3]
	v_ashrrev_i32_e32 v6, 3, v6
	v_add_u32_e32 v2, s20, v6
	v_cmp_gt_u32_e32 vcc, s36, v2
	s_and_saveexec_b64 s[2:3], vcc
	s_cbranch_execz .LBB0_27
	v_lshlrev_b32_e32 v6, 2, v6
	v_add3_u32 v6, 0, v6, v9
	ds_read_b32 v7, v6
	ds_read_b32 v8, v6 offset:1044
	ds_read_b32 v9, v6 offset:2088
	ds_read_b32 v10, v6 offset:3132
	ds_read_b32 v11, v6 offset:4176
	ds_read_b32 v12, v6 offset:5220
	ds_read_b32 v13, v6 offset:6264
	ds_read_b32 v14, v6 offset:7308
	v_mul_lo_u32 v2, v2, s38
	s_waitcnt lgkmcnt(0)
	v_cvt_pk_bf16_f32 v6, v7, v8
	v_cvt_pk_bf16_f32 v7, v9, v10
	v_cvt_pk_bf16_f32 v8, v11, v12
	v_cvt_pk_bf16_f32 v9, v13, v14
	v_lshl_add_u64 v[4:5], v[2:3], 1, v[4:5]
	global_store_dwordx4 v[4:5], v[6:9], off

; __device__ __forceinline__ unsigned cvt_pk_bf16(float lo, float hi) { f32x2_t f = {lo, hi}; bf16x2_t v = __builtin_convertvector(f, bf16x2_t); return __builtin_bit_cast(unsigned, v); }
; __device__ __forceinline__ void conv_tile(LAS float* tl, const float* src, int ldsrc, int k0, int n0, int N, bf16_t* dst, int lddst, int mode, int wv) {
;     ...
;     for (int i = 0; i < 8; ++i) { const int e = i * 512 + tid, kk = e >> 6, n = n0 + (e & 63) * 4;
;         v[i] = (f32x4){0.f, 0.f, 0.f, 0.f};
;         if (n + 3 < N) v[i] = *(const f32x4*)(src + (size_t)(k0 + kk) * ldsrc + n);
;         else { for (int j = 0; j < 4; ++j) if (n + j < N) v[i][j] = src[(size_t)(k0 + kk) * ldsrc + n + j]; } }
;     __syncthreads();
; #pragma unroll
;     for (int i = 0; i < 8; ++i) { const int e = i * 512 + tid, kk = e >> 6, n4 = (e & 63) * 4;
; #pragma unroll
;         for (int j = 0; j < 4; ++j) tl[kk * S + n4 + j] = v[i][j]; }
;     __syncthreads();
; #pragma unroll
;     for (int i = 0; i < 4; ++i) { const int item = i * 512 + tid, nl = item >> 3, k8 = (item & 7) * 8, n = n0 + nl;
;         int row = n;
;         if (mode == 0) row = n < 8192 ? n : (n < 8200 ? -1 : n - 8);
;         else if (mode == 2) { const int c = n % DFF, gt = n / DFF; row = (c >> 7) * 256 + gt * 128 + (c & 127); }
;         if (n < N && row >= 0) {
;             float x[8];
; #pragma unroll
;             for (int j = 0; j < 8; ++j) x[j] = tl[(k8 + j) * S + nl];
;             u32x4 w; w.x = cvt_pk_bf16(x[0], x[1]); w.y = cvt_pk_bf16(x[2], x[3]); w.z = cvt_pk_bf16(x[4], x[5]); w.w = cvt_pk_bf16(x[6], x[7]);
;             *(u32x4*)(dst + (size_t)row * lddst + k0 + k8) = w;
; __device__ NOINL void convert_weights(const float* win, const float* wbr, const float* wout, const float* wup, const float* wdown, unsigned char* ws, LAS unsigned char* lds, int wv) {
;     ...
;         else if (t < T3) { const int q = t - T2, tk = q / 44, tn = q % 44;
;             conv_tile(tl, wup, NUP, tk * 64, tn * 256, NUP, (bf16_t*)(ws + WS_WUP), 2048, 2, wv); }
.LBB0_28:
	s_and_b64 vcc, exec, s[2:3]
	s_cbranch_vccz .LBB0_149
	s_add_i32 s2, s26, 0xf6e0
	s_and_b32 s3, s2, 0xffff
	s_mul_i32 s3, s3, 0xba2f
	s_lshr_b32 s20, s3, 21
	s_mul_i32 s3, s20, 44
	s_sub_i32 s2, s2, s3
	v_mov_b32_e32 v8, v236
	s_lshl_b32 s2, s2, 8
	s_and_b32 s18, s2, 0xff00
	v_lshlrev_b32_e32 v2, 2, v8
	v_and_b32_e32 v42, 0xfc, v2
	v_or_b32_e32 v2, s18, v42
	s_lshl_b32 s21, s20, 6
	v_lshlrev_b32_e32 v2, 2, v2
	v_ashrrev_i32_e32 v43, 6, v8
	v_add_u32_e32 v9, 0x200, v8
	v_lshl_add_u64 v[4:5], s[12:13], 0, v[2:3]
	v_add_u32_e32 v2, s21, v43
	v_ashrrev_i32_e32 v44, 6, v9
	v_mad_i64_i32 v[6:7], s[2:3], v2, s39, v[4:5]
	v_add_u32_e32 v2, s21, v44
	v_mad_i64_i32 v[14:15], s[2:3], v2, s39, v[4:5]
	global_load_dwordx4 v[10:13], v[6:7], off
	s_nop 0
	global_load_dwordx4 v[14:17], v[14:15], off
	v_add_u32_e32 v7, 0x400, v8
	v_ashrrev_i32_e32 v45, 6, v7
	v_add_u32_e32 v6, 0x600, v8
	v_add_u32_e32 v2, s21, v45
	v_ashrrev_i32_e32 v46, 6, v6
	v_mad_i64_i32 v[18:19], s[2:3], v2, s39, v[4:5]
	v_add_u32_e32 v2, s21, v46
	v_mad_i64_i32 v[22:23], s[2:3], v2, s39, v[4:5]
	v_add_u32_e32 v2, 0x800, v8
	v_ashrrev_i32_e32 v48, 6, v2
	v_add_u32_e32 v2, s21, v48
	v_mad_i64_i32 v[26:27], s[2:3], v2, s39, v[4:5]
	v_add_u32_e32 v2, 0xa00, v8
	v_ashrrev_i32_e32 v50, 6, v2
	v_add_u32_e32 v2, s21, v50
	v_mad_i64_i32 v[30:31], s[2:3], v2, s39, v[4:5]
	v_add_u32_e32 v2, 0xc00, v8
	v_ashrrev_i32_e32 v52, 6, v2
	v_add_u32_e32 v2, s21, v52
	global_load_dwordx4 v[18:21], v[18:19], off
	s_nop 0
	global_load_dwordx4 v[22:25], v[22:23], off
	s_nop 0
	global_load_dwordx4 v[26:29], v[26:27], off
	s_nop 0
	global_load_dwordx4 v[30:33], v[30:31], off
	v_mad_i64_i32 v[34:35], s[2:3], v2, s39, v[4:5]
	v_add_u32_e32 v2, 0xe00, v8
	v_ashrrev_i32_e32 v54, 6, v2
	v_add_u32_e32 v2, s21, v54
	v_mad_i64_i32 v[4:5], s[2:3], v2, s39, v[4:5]
	global_load_dwordx4 v[34:37], v[34:35], off
	v_lshl_add_u32 v2, v42, 2, 0
	global_load_dwordx4 v[38:41], v[4:5], off
	v_mad_u64_u32 v[4:5], s[2:3], v43, s37, v[2:3]
	v_mad_u64_u32 v[42:43], s[2:3], v44, s37, v[2:3]
	v_mad_u64_u32 v[44:45], s[2:3], v45, s37, v[2:3]
	v_mad_u64_u32 v[46:47], s[2:3], v46, s37, v[2:3]
	v_mad_u64_u32 v[48:49], s[2:3], v48, s37, v[2:3]
	v_mad_u64_u32 v[50:51], s[2:3], v50, s37, v[2:3]
	v_mad_u64_u32 v[52:53], s[2:3], v52, s37, v[2:3]
	s_waitcnt lgkmcnt(0)
	s_barrier
	s_waitcnt vmcnt(0)
	ds_write2_b32 v4, v10, v11 offset1:1
	ds_write2_b32 v4, v12, v13 offset0:2 offset1:3
	ds_write2_b32 v42, v14, v15 offset1:1
	ds_write2_b32 v42, v16, v17 offset0:2 offset1:3
	ds_write2_b32 v44, v18, v19 offset1:1
	ds_write2_b32 v44, v20, v21 offset0:2 offset1:3
	ds_write2_b32 v46, v22, v23 offset1:1
	ds_write2_b32 v46, v24, v25 offset0:2 offset1:3
	ds_write2_b32 v48, v26, v27 offset1:1
	ds_write2_b32 v48, v28, v29 offset0:2 offset1:3
	ds_write2_b32 v50, v30, v31 offset1:1
	ds_write2_b32 v50, v32, v33 offset0:2 offset1:3
	ds_write2_b32 v52, v34, v35 offset1:1
	ds_write2_b32 v52, v36, v37 offset0:2 offset1:3
	v_mad_u64_u32 v[4:5], s[2:3], v54, s37, v[2:3]
	v_lshlrev_b32_e32 v2, 3, v8
	s_lshl_b32 s2, s20, 7
	v_and_b32_e32 v12, 56, v2
	s_add_u32 s2, s29, s2
	v_ashrrev_i32_e32 v10, 3, v8
	s_addc_u32 s3, s30, 0
	v_lshlrev_b32_e32 v2, 1, v12
	v_add_u32_e32 v8, s18, v10
	ds_write2_b32 v4, v38, v39 offset1:1
	ds_write2_b32 v4, v40, v41 offset0:2 offset1:3
	v_lshl_add_u64 v[4:5], s[2:3], 0, v[2:3]
	v_mul_hi_i32 v2, v8, s40
	v_lshrrev_b32_e32 v11, 31, v2
	v_ashrrev_i32_e32 v2, 10, v2
	v_add_u32_e32 v11, v2, v11
	v_mul_i32_i24_e32 v2, 0x1600, v11
	v_sub_u32_e32 v2, v8, v2
	v_lshlrev_b32_e32 v13, 1, v2
	v_and_b32_e32 v13, 0xffffff00, v13
	v_lshl_add_u32 v11, v11, 7, v13
	v_cmp_gt_i32_e32 vcc, s41, v8
	v_cmp_lt_i32_e64 s[2:3], -1, v11
	s_and_b64 s[20:21], vcc, s[2:3]
	v_mul_u32_u24_e32 v8, 0x414, v12
	s_waitcnt lgkmcnt(0)
	s_barrier
	s_and_saveexec_b64 s[2:3], s[20:21]
	s_cbranch_execz .LBB0_31
	v_lshlrev_b32_e32 v10, 2, v10
	v_add3_u32 v10, 0, v10, v8
	ds_read_b32 v12, v10
	ds_read_b32 v13, v10 offset:1044
	ds_read_b32 v14, v10 offset:2088
	ds_read_b32 v15, v10 offset:3132
	ds_read_b32 v16, v10 offset:4176
	ds_read_b32 v17, v10 offset:5220
	ds_read_b32 v18, v10 offset:6264
	ds_read_b32 v19, v10 offset:7308
	v_and_or_b32 v2, v2, s42, v11
	s_waitcnt lgkmcnt(4)
	v_cvt_pk_bf16_f32 v11, v14, v15
	v_lshlrev_b64 v[14:15], 12, v[2:3]
	v_cvt_pk_bf16_f32 v10, v12, v13
	s_waitcnt lgkmcnt(2)
	v_cvt_pk_bf16_f32 v12, v16, v17
	s_waitcnt lgkmcnt(0)
	v_cvt_pk_bf16_f32 v13, v18, v19
	v_lshl_add_u64 v[14:15], v[4:5], 0, v[14:15]
	global_store_dwordx4 v[14:15], v[10:13], off
; __device__ __forceinline__ unsigned cvt_pk_bf16(float lo, float hi) { f32x2_t f = {lo, hi}; bf16x2_t v = __builtin_convertvector(f, bf16x2_t); return __builtin_bit_cast(unsigned, v); }
; __device__ __forceinline__ void conv_tile(LAS float* tl, const float* src, int ldsrc, int k0, int n0, int N, bf16_t* dst, int lddst, int mode, int wv) {
;     ...
;     for (int i = 0; i < 4; ++i) { const int item = i * 512 + tid, nl = item >> 3, k8 = (item & 7) * 8, n = n0 + nl;
;         int row = n;
;         if (mode == 0) row = n < 8192 ? n : (n < 8200 ? -1 : n - 8);
;         else if (mode == 2) { const int c = n % DFF, gt = n / DFF; row = (c >> 7) * 256 + gt * 128 + (c & 127); }
;         if (n < N && row >= 0) {
;             float x[8];
; #pragma unroll
;             for (int j = 0; j < 8; ++j) x[j] = tl[(k8 + j) * S + nl];
;             u32x4 w; w.x = cvt_pk_bf16(x[0], x[1]); w.y = cvt_pk_bf16(x[2], x[3]); w.z = cvt_pk_bf16(x[4], x[5]); w.w = cvt_pk_bf16(x[6], x[7]);
;             *(u32x4*)(dst + (size_t)row * lddst + k0 + k8) = w;
.LBB0_31:
	s_or_b64 exec, exec, s[2:3]
	v_ashrrev_i32_e32 v9, 3, v9
	v_add_u32_e32 v11, s18, v9
	v_mul_hi_i32 v2, v11, s40
	v_lshrrev_b32_e32 v10, 31, v2
	v_ashrrev_i32_e32 v2, 10, v2
	v_add_u32_e32 v10, v2, v10
	v_mul_i32_i24_e32 v2, 0x1600, v10
	v_sub_u32_e32 v2, v11, v2
	v_lshlrev_b32_e32 v12, 1, v2
	v_and_b32_e32 v12, 0xffffff00, v12
	v_lshl_add_u32 v10, v10, 7, v12
	v_cmp_gt_i32_e32 vcc, s41, v11
	v_cmp_lt_i32_e64 s[2:3], -1, v10
	s_and_b64 s[20:21], vcc, s[2:3]
	s_and_saveexec_b64 s[2:3], s[20:21]
	s_cbranch_execz .LBB0_33
	v_lshlrev_b32_e32 v9, 2, v9
	v_add3_u32 v9, 0, v9, v8
	ds_read_b32 v11, v9
	ds_read_b32 v12, v9 offset:1044
	ds_read_b32 v13, v9 offset:2088
	ds_read_b32 v14, v9 offset:3132
	ds_read_b32 v15, v9 offset:4176
	ds_read_b32 v16, v9 offset:5220
	ds_read_b32 v17, v9 offset:6264
	ds_read_b32 v9, v9 offset:7308
	v_and_or_b32 v2, v2, s42, v10
	s_waitcnt lgkmcnt(0)
	v_cvt_pk_bf16_f32 v10, v11, v12
	v_cvt_pk_bf16_f32 v11, v13, v14
	v_cvt_pk_bf16_f32 v12, v15, v16
	v_lshlrev_b64 v[14:15], 12, v[2:3]
	v_cvt_pk_bf16_f32 v13, v17, v9
	v_lshl_add_u64 v[14:15], v[4:5], 0, v[14:15]
	global_store_dwordx4 v[14:15], v[10:13], off
.LBB0_33:
	s_or_b64 exec, exec, s[2:3]
	v_ashrrev_i32_e32 v7, 3, v7
	v_add_u32_e32 v10, s18, v7
	v_mul_hi_i32 v2, v10, s40
	v_lshrrev_b32_e32 v9, 31, v2
	v_ashrrev_i32_e32 v2, 10, v2
	v_add_u32_e32 v9, v2, v9
	v_mul_i32_i24_e32 v2, 0x1600, v9
	v_sub_u32_e32 v2, v10, v2
	v_lshlrev_b32_e32 v11, 1, v2
	v_and_b32_e32 v11, 0xffffff00, v11
	v_lshl_add_u32 v9, v9, 7, v11
	v_cmp_gt_i32_e32 vcc, s41, v10
	v_cmp_lt_i32_e64 s[2:3], -1, v9
	s_and_b64 s[20:21], vcc, s[2:3]
	s_and_saveexec_b64 s[2:3], s[20:21]
	s_cbranch_execz .LBB0_35
	v_lshlrev_b32_e32 v7, 2, v7
	v_add3_u32 v7, 0, v7, v8
	ds_read_b32 v10, v7
	ds_read_b32 v11, v7 offset:1044
	ds_read_b32 v12, v7 offset:2088
	ds_read_b32 v13, v7 offset:3132
	ds_read_b32 v14, v7 offset:4176
	ds_read_b32 v15, v7 offset:5220
	ds_read_b32 v16, v7 offset:6264
	ds_read_b32 v7, v7 offset:7308
	v_and_or_b32 v2, v2, s42, v9
	s_waitcnt lgkmcnt(0)
	v_cvt_pk_bf16_f32 v10, v10, v11
	v_cvt_pk_bf16_f32 v11, v12, v13
	v_cvt_pk_bf16_f32 v12, v14, v15
	v_lshlrev_b64 v[14:15], 12, v[2:3]
	v_cvt_pk_bf16_f32 v13, v16, v7
	v_lshl_add_u64 v[14:15], v[4:5], 0, v[14:15]
	global_store_dwordx4 v[14:15], v[10:13], off
.LBB0_35:
	s_or_b64 exec, exec, s[2:3]
	v_ashrrev_i32_e32 v6, 3, v6
	v_add_u32_e32 v9, s18, v6
	v_mul_hi_i32 v2, v9, s40
	v_lshrrev_b32_e32 v7, 31, v2
	v_ashrrev_i32_e32 v2, 10, v2
	v_add_u32_e32 v7, v2, v7
	v_mul_i32_i24_e32 v2, 0x1600, v7
	v_sub_u32_e32 v2, v9, v2
	v_lshlrev_b32_e32 v10, 1, v2
	v_and_b32_e32 v10, 0xffffff00, v10
	v_lshl_add_u32 v7, v7, 7, v10
	v_cmp_gt_i32_e32 vcc, s41, v9
	v_cmp_lt_i32_e64 s[2:3], -1, v7
	s_and_b64 s[20:21], vcc, s[2:3]
	s_and_saveexec_b64 s[2:3], s[20:21]
	s_cbranch_execz .LBB0_37
	v_lshlrev_b32_e32 v6, 2, v6
	v_add3_u32 v6, 0, v6, v8
	ds_read_b32 v8, v6
	ds_read_b32 v9, v6 offset:1044
	ds_read_b32 v10, v6 offset:2088
	ds_read_b32 v11, v6 offset:3132
	ds_read_b32 v12, v6 offset:4176
	ds_read_b32 v13, v6 offset:5220
	ds_read_b32 v14, v6 offset:6264
	ds_read_b32 v15, v6 offset:7308
	v_and_or_b32 v2, v2, s42, v7
	s_waitcnt lgkmcnt(0)
	v_cvt_pk_bf16_f32 v7, v10, v11
	v_lshlrev_b64 v[10:11], 12, v[2:3]
	v_cvt_pk_bf16_f32 v6, v8, v9
	v_cvt_pk_bf16_f32 v8, v12, v13
	v_cvt_pk_bf16_f32 v9, v14, v15
	v_lshl_add_u64 v[4:5], v[4:5], 0, v[10:11]
	global_store_dwordx4 v[4:5], v[6:9], off

; __device__ __forceinline__ unsigned cvt_pk_bf16(float lo, float hi) { f32x2_t f = {lo, hi}; bf16x2_t v = __builtin_convertvector(f, bf16x2_t); return __builtin_bit_cast(unsigned, v); }
; __device__ __forceinline__ void conv_tile(LAS float* tl, const float* src, int ldsrc, int k0, int n0, int N, bf16_t* dst, int lddst, int mode, int wv) {
;     ...
;     for (int i = 0; i < 8; ++i) { const int e = i * 512 + tid, kk = e >> 6, n = n0 + (e & 63) * 4;
;         v[i] = (f32x4){0.f, 0.f, 0.f, 0.f};
;         if (n + 3 < N) v[i] = *(const f32x4*)(src + (size_t)(k0 + kk) * ldsrc + n);
;         else { for (int j = 0; j < 4; ++j) if (n + j < N) v[i][j] = src[(size_t)(k0 + kk) * ldsrc + n + j]; } }
;     __syncthreads();
; #pragma unroll
;     for (int i = 0; i < 8; ++i) { const int e = i * 512 + tid, kk = e >> 6, n4 = (e & 63) * 4;
; #pragma unroll
;         for (int j = 0; j < 4; ++j) tl[kk * S + n4 + j] = v[i][j]; }
;     __syncthreads();
; #pragma unroll
;     for (int i = 0; i < 4; ++i) { const int item = i * 512 + tid, nl = item >> 3, k8 = (item & 7) * 8, n = n0 + nl;
;         int row = n;
;         if (mode == 0) row = n < 8192 ? n : (n < 8200 ? -1 : n - 8);
;         else if (mode == 2) { const int c = n % DFF, gt = n / DFF; row = (c >> 7) * 256 + gt * 128 + (c & 127); }
;         if (n < N && row >= 0) {
;             float x[8];
; #pragma unroll
;             for (int j = 0; j < 8; ++j) x[j] = tl[(k8 + j) * S + nl];
;             u32x4 w; w.x = cvt_pk_bf16(x[0], x[1]); w.y = cvt_pk_bf16(x[2], x[3]); w.z = cvt_pk_bf16(x[4], x[5]); w.w = cvt_pk_bf16(x[6], x[7]);
;             *(u32x4*)(dst + (size_t)row * lddst + k0 + k8) = w;
; __device__ NOINL void convert_weights(const float* win, const float* wbr, const float* wout, const float* wup, const float* wdown, unsigned char* ws, LAS unsigned char* lds, int wv) {
;     ...
;         else if (t < T2) { const int q = t - T1, tk = q / 8, tn = q % 8;
;             conv_tile(tl, wout, 2048, tk * 64, tn * 256, 2048, (bf16_t*)(ws + WS_WOUT), 2048, 1, wv); }
.LBB0_39:
	s_lshl_b32 s2, s26, 3
	s_and_b32 s2, s2, 0x7fc0
	v_mov_b32_e32 v9, v236
	s_add_i32 s18, s2, 0xffffbf00
	s_lshl_b32 s2, s26, 8
	s_and_b32 s20, s2, 0x700
	v_lshlrev_b32_e32 v2, 2, v9
	v_add_u32_e32 v8, 0x200, v9
	v_and_b32_e32 v42, 0xfc, v2
	v_ashrrev_i32_e32 v43, 6, v9
	v_ashrrev_i32_e32 v44, 6, v8
	v_or_b32_e32 v2, s20, v42
	v_add_u32_e32 v6, s18, v43
	v_add_u32_e32 v10, s18, v44
	v_lshlrev_b32_e32 v2, 2, v2
	v_ashrrev_i32_e32 v7, 31, v6
	v_ashrrev_i32_e32 v11, 31, v10
	v_lshl_add_u64 v[4:5], s[10:11], 0, v[2:3]
	v_lshlrev_b64 v[6:7], 13, v[6:7]
	v_lshlrev_b64 v[10:11], 13, v[10:11]
	v_lshl_add_u64 v[6:7], v[4:5], 0, v[6:7]
	v_lshl_add_u64 v[14:15], v[4:5], 0, v[10:11]
	global_load_dwordx4 v[10:13], v[6:7], off
	s_nop 0
	global_load_dwordx4 v[14:17], v[14:15], off
	v_add_u32_e32 v7, 0x400, v9
	v_add_u32_e32 v6, 0x600, v9
	v_add_u32_e32 v2, 0x800, v9
	v_ashrrev_i32_e32 v45, 6, v7
	v_ashrrev_i32_e32 v46, 6, v6
	v_ashrrev_i32_e32 v48, 6, v2
	v_add_u32_e32 v2, 0xa00, v9
	v_add_u32_e32 v18, s18, v45
	v_add_u32_e32 v20, s18, v46
	v_ashrrev_i32_e32 v50, 6, v2
	v_add_u32_e32 v2, 0xc00, v9
	v_ashrrev_i32_e32 v19, 31, v18
	v_ashrrev_i32_e32 v21, 31, v20
	v_add_u32_e32 v26, s18, v48
	v_add_u32_e32 v28, s18, v50
	v_ashrrev_i32_e32 v51, 6, v2
	v_lshlrev_b64 v[18:19], 13, v[18:19]
	v_lshlrev_b64 v[20:21], 13, v[20:21]
	v_ashrrev_i32_e32 v27, 31, v26
	v_ashrrev_i32_e32 v29, 31, v28
	v_add_u32_e32 v34, s18, v51
	v_lshl_add_u64 v[18:19], v[4:5], 0, v[18:19]
	v_lshl_add_u64 v[22:23], v[4:5], 0, v[20:21]
	v_lshlrev_b64 v[26:27], 13, v[26:27]
	v_lshlrev_b64 v[28:29], 13, v[28:29]
	v_ashrrev_i32_e32 v35, 31, v34
	global_load_dwordx4 v[18:21], v[18:19], off
	s_nop 0
	global_load_dwordx4 v[22:25], v[22:23], off
	v_lshl_add_u64 v[26:27], v[4:5], 0, v[26:27]
	v_lshl_add_u64 v[30:31], v[4:5], 0, v[28:29]
	v_lshlrev_b64 v[34:35], 13, v[34:35]
	v_add_u32_e32 v2, 0xe00, v9
	global_load_dwordx4 v[26:29], v[26:27], off
	s_nop 0
	global_load_dwordx4 v[30:33], v[30:31], off
	v_lshl_add_u64 v[34:35], v[4:5], 0, v[34:35]
	v_ashrrev_i32_e32 v52, 6, v2
	global_load_dwordx4 v[34:37], v[34:35], off
	v_add_u32_e32 v38, s18, v52
	v_ashrrev_i32_e32 v39, 31, v38
	v_lshlrev_b64 v[38:39], 13, v[38:39]
	v_lshl_add_u64 v[4:5], v[4:5], 0, v[38:39]
	global_load_dwordx4 v[38:41], v[4:5], off
	v_lshl_add_u32 v2, v42, 2, 0
	v_mad_u64_u32 v[4:5], s[2:3], v43, s37, v[2:3]
	v_mad_u64_u32 v[42:43], s[2:3], v44, s37, v[2:3]
	v_mad_u64_u32 v[44:45], s[2:3], v45, s37, v[2:3]
	v_mad_u64_u32 v[46:47], s[2:3], v46, s37, v[2:3]
	v_mad_u64_u32 v[48:49], s[2:3], v48, s37, v[2:3]
	s_waitcnt lgkmcnt(0)
	s_barrier
	s_waitcnt vmcnt(0)
	ds_write2_b32 v4, v10, v11 offset1:1
	ds_write2_b32 v4, v12, v13 offset0:2 offset1:3
	ds_write2_b32 v42, v14, v15 offset1:1
	ds_write2_b32 v42, v16, v17 offset0:2 offset1:3
	ds_write2_b32 v44, v18, v19 offset1:1
	ds_write2_b32 v44, v20, v21 offset0:2 offset1:3
	ds_write2_b32 v46, v22, v23 offset1:1
	ds_write2_b32 v46, v24, v25 offset0:2 offset1:3
	ds_write2_b32 v48, v26, v27 offset1:1
	ds_write2_b32 v48, v28, v29 offset0:2 offset1:3
	v_mad_u64_u32 v[4:5], s[2:3], v50, s37, v[2:3]
	ds_write2_b32 v4, v30, v31 offset1:1
	ds_write2_b32 v4, v32, v33 offset0:2 offset1:3
	v_mad_u64_u32 v[4:5], s[2:3], v51, s37, v[2:3]
	ds_write2_b32 v4, v34, v35 offset1:1
	ds_write2_b32 v4, v36, v37 offset0:2 offset1:3
	v_mad_u64_u32 v[4:5], s[2:3], v52, s37, v[2:3]
	v_lshlrev_b32_e32 v2, 3, v9
	s_lshl_b64 s[2:3], s[18:19], 1
	v_and_b32_e32 v11, 56, v2
	s_add_u32 s2, s31, s2
	s_addc_u32 s3, s33, s3
	v_lshlrev_b32_e32 v2, 1, v11
	v_ashrrev_i32_e32 v10, 3, v9
	ds_write2_b32 v4, v38, v39 offset1:1
	ds_write2_b32 v4, v40, v41 offset0:2 offset1:3
	v_lshl_add_u64 v[4:5], s[2:3], 0, v[2:3]
	v_add_u32_e32 v2, s20, v10
	v_cmp_gt_u32_e32 vcc, s36, v2
	v_mul_u32_u24_e32 v9, 0x414, v11
	s_waitcnt lgkmcnt(0)
	s_barrier
	s_and_saveexec_b64 s[2:3], vcc
	s_cbranch_execz .LBB0_41
	v_lshlrev_b32_e32 v10, 2, v10
	v_add3_u32 v10, 0, v10, v9
	ds_read_b32 v11, v10
	ds_read_b32 v12, v10 offset:1044
	ds_read_b32 v13, v10 offset:2088
	ds_read_b32 v14, v10 offset:3132
	ds_read_b32 v15, v10 offset:4176
	ds_read_b32 v16, v10 offset:5220
	ds_read_b32 v17, v10 offset:6264
	ds_read_b32 v18, v10 offset:7308
	v_lshlrev_b32_e32 v2, 12, v2
	s_waitcnt lgkmcnt(6)
	v_cvt_pk_bf16_f32 v10, v11, v12
	s_waitcnt lgkmcnt(4)
	v_cvt_pk_bf16_f32 v11, v13, v14
	s_waitcnt lgkmcnt(2)
	v_cvt_pk_bf16_f32 v12, v15, v16
	s_waitcnt lgkmcnt(0)
	v_cvt_pk_bf16_f32 v13, v17, v18
	v_lshl_add_u64 v[14:15], v[4:5], 0, v[2:3]
	global_store_dwordx4 v[14:15], v[10:13], off
.LBB0_41:
	s_or_b64 exec, exec, s[2:3]
	v_ashrrev_i32_e32 v8, 3, v8
	v_add_u32_e32 v2, s20, v8
	v_cmp_gt_u32_e32 vcc, s36, v2
	s_and_saveexec_b64 s[2:3], vcc
	s_cbranch_execz .LBB0_43
	v_lshlrev_b32_e32 v8, 2, v8
	v_add3_u32 v8, 0, v8, v9
	ds_read_b32 v10, v8
	ds_read_b32 v11, v8 offset:1044
	ds_read_b32 v12, v8 offset:2088
	ds_read_b32 v13, v8 offset:3132
	ds_read_b32 v14, v8 offset:4176
	ds_read_b32 v15, v8 offset:5220
	ds_read_b32 v16, v8 offset:6264
	ds_read_b32 v8, v8 offset:7308
	v_lshlrev_b32_e32 v2, 12, v2
	s_waitcnt lgkmcnt(0)
	v_cvt_pk_bf16_f32 v10, v10, v11
	v_cvt_pk_bf16_f32 v11, v12, v13
	v_cvt_pk_bf16_f32 v12, v14, v15
	v_cvt_pk_bf16_f32 v13, v16, v8
	v_lshl_add_u64 v[14:15], v[4:5], 0, v[2:3]
	global_store_dwordx4 v[14:15], v[10:13], off
.LBB0_43:
	s_or_b64 exec, exec, s[2:3]
	v_ashrrev_i32_e32 v7, 3, v7
	v_add_u32_e32 v2, s20, v7
	v_cmp_gt_u32_e32 vcc, s36, v2
	s_and_saveexec_b64 s[2:3], vcc
	s_cbranch_execz .LBB0_45
	v_lshlrev_b32_e32 v7, 2, v7
	v_add3_u32 v7, 0, v7, v9
	ds_read_b32 v8, v7
	ds_read_b32 v10, v7 offset:1044
	ds_read_b32 v11, v7 offset:2088
	ds_read_b32 v12, v7 offset:3132
	ds_read_b32 v13, v7 offset:4176
	ds_read_b32 v14, v7 offset:5220
	ds_read_b32 v15, v7 offset:6264
	ds_read_b32 v7, v7 offset:7308
	v_lshlrev_b32_e32 v2, 12, v2
	s_waitcnt lgkmcnt(0)
	v_cvt_pk_bf16_f32 v10, v8, v10
	v_cvt_pk_bf16_f32 v11, v11, v12
	v_cvt_pk_bf16_f32 v12, v13, v14
	v_cvt_pk_bf16_f32 v13, v15, v7
	v_lshl_add_u64 v[14:15], v[4:5], 0, v[2:3]
	global_store_dwordx4 v[14:15], v[10:13], off
.LBB0_45:
	s_or_b64 exec, exec, s[2:3]
	v_ashrrev_i32_e32 v6, 3, v6
	v_add_u32_e32 v2, s20, v6
	v_cmp_gt_u32_e32 vcc, s36, v2
	s_and_saveexec_b64 s[2:3], vcc
	s_cbranch_execz .LBB0_47
	v_lshlrev_b32_e32 v6, 2, v6
	v_add3_u32 v6, 0, v6, v9
	ds_read_b32 v7, v6
	ds_read_b32 v8, v6 offset:1044
	ds_read_b32 v9, v6 offset:2088
	ds_read_b32 v10, v6 offset:3132
	ds_read_b32 v11, v6 offset:4176
	ds_read_b32 v12, v6 offset:5220
	ds_read_b32 v13, v6 offset:6264
	ds_read_b32 v14, v6 offset:7308
	v_lshlrev_b32_e32 v2, 12, v2
	s_waitcnt lgkmcnt(0)
	v_cvt_pk_bf16_f32 v6, v7, v8
	v_cvt_pk_bf16_f32 v7, v9, v10
	v_cvt_pk_bf16_f32 v8, v11, v12
	v_cvt_pk_bf16_f32 v9, v13, v14
	v_lshl_add_u64 v[4:5], v[4:5], 0, v[2:3]
	global_store_dwordx4 v[4:5], v[6:9], off

; __device__ __forceinline__ unsigned cvt_pk_bf16(float lo, float hi) { f32x2_t f = {lo, hi}; bf16x2_t v = __builtin_convertvector(f, bf16x2_t); return __builtin_bit_cast(unsigned, v); }
; __device__ __forceinline__ void conv_tile(LAS float* tl, const float* src, int ldsrc, int k0, int n0, int N, bf16_t* dst, int lddst, int mode, int wv) {
;     ...
;     for (int i = 0; i < 8; ++i) { const int e = i * 512 + tid, kk = e >> 6, n = n0 + (e & 63) * 4;
;         v[i] = (f32x4){0.f, 0.f, 0.f, 0.f};
;         if (n + 3 < N) v[i] = *(const f32x4*)(src + (size_t)(k0 + kk) * ldsrc + n);
;         else { for (int j = 0; j < 4; ++j) if (n + j < N) v[i][j] = src[(size_t)(k0 + kk) * ldsrc + n + j]; } }
;     __syncthreads();
; #pragma unroll
;     for (int i = 0; i < 8; ++i) { const int e = i * 512 + tid, kk = e >> 6, n4 = (e & 63) * 4;
; #pragma unroll
;         for (int j = 0; j < 4; ++j) tl[kk * S + n4 + j] = v[i][j]; }
;     __syncthreads();
; #pragma unroll
;     for (int i = 0; i < 4; ++i) { const int item = i * 512 + tid, nl = item >> 3, k8 = (item & 7) * 8, n = n0 + nl;
;         int row = n;
;         if (mode == 0) row = n < 8192 ? n : (n < 8200 ? -1 : n - 8);
;         else if (mode == 2) { const int c = n % DFF, gt = n / DFF; row = (c >> 7) * 256 + gt * 128 + (c & 127); }
;         if (n < N && row >= 0) {
;             float x[8];
; #pragma unroll
;             for (int j = 0; j < 8; ++j) x[j] = tl[(k8 + j) * S + nl];
;             u32x4 w; w.x = cvt_pk_bf16(x[0], x[1]); w.y = cvt_pk_bf16(x[2], x[3]); w.z = cvt_pk_bf16(x[4], x[5]); w.w = cvt_pk_bf16(x[6], x[7]);
;             *(u32x4*)(dst + (size_t)row * lddst + k0 + k8) = w;
; __device__ NOINL void convert_weights(const float* win, const float* wbr, const float* wout, const float* wup, const float* wdown, unsigned char* ws, LAS unsigned char* lds, int wv) {
;     ...
;         else if (t < T1) { const int r = t - T0, br = 1 + r / 128, q = r % 128, tk = q / 8, tn = q % 8;
;             conv_tile(tl, wbr + (size_t)br * 1024 * 2048, 2048, tk * 64, tn * 256, 2048, (bf16_t*)(ws + WS_WBR) + (size_t)br * 2048 * 1024, 1024, 1, wv); }
.LBB0_49:
	s_andn2_b64 vcc, exec, s[2:3]
	s_cbranch_vccnz .LBB0_59
	s_add_i32 s20, s26, 0xfffff8e0
	s_lshr_b32 s2, s20, 7
	s_add_i32 s18, s2, 1
	s_lshl_b64 s[2:3], s[18:19], 23
	s_add_u32 s2, s8, s2
	s_addc_u32 s3, s9, s3
	s_lshl_b32 s20, s20, 3
	v_mov_b32_e32 v9, v236
	s_and_b32 s21, s20, 0x3c0
	s_lshl_b32 s20, s26, 8
	s_and_b32 s20, s20, 0x700
	v_lshlrev_b32_e32 v2, 2, v9
	v_add_u32_e32 v8, 0x200, v9
	v_and_b32_e32 v42, 0xfc, v2
	v_ashrrev_i32_e32 v43, 6, v9
	v_ashrrev_i32_e32 v44, 6, v8
	v_or_b32_e32 v2, s20, v42
	v_add_u32_e32 v6, s21, v43
	v_add_u32_e32 v10, s21, v44
	v_lshlrev_b32_e32 v2, 2, v2
	v_ashrrev_i32_e32 v7, 31, v6
	v_ashrrev_i32_e32 v11, 31, v10
	v_lshl_add_u64 v[4:5], s[2:3], 0, v[2:3]
	v_lshlrev_b64 v[6:7], 13, v[6:7]
	v_lshlrev_b64 v[10:11], 13, v[10:11]
	v_lshl_add_u64 v[6:7], v[4:5], 0, v[6:7]
	v_lshl_add_u64 v[14:15], v[4:5], 0, v[10:11]
	global_load_dwordx4 v[10:13], v[6:7], off
	s_nop 0
	global_load_dwordx4 v[14:17], v[14:15], off
	v_add_u32_e32 v7, 0x400, v9
	v_add_u32_e32 v6, 0x600, v9
	v_ashrrev_i32_e32 v45, 6, v7
	v_ashrrev_i32_e32 v46, 6, v6
	v_add_u32_e32 v2, 0x800, v9
	v_add_u32_e32 v18, s21, v45
	v_add_u32_e32 v20, s21, v46
	v_ashrrev_i32_e32 v47, 6, v2
	v_add_u32_e32 v2, 0xa00, v9
	v_ashrrev_i32_e32 v19, 31, v18
	v_ashrrev_i32_e32 v21, 31, v20
	v_ashrrev_i32_e32 v48, 6, v2
	v_add_u32_e32 v2, 0xc00, v9
	v_lshlrev_b64 v[18:19], 13, v[18:19]
	v_lshlrev_b64 v[20:21], 13, v[20:21]
	v_add_u32_e32 v26, s21, v47
	v_add_u32_e32 v28, s21, v48
	v_ashrrev_i32_e32 v49, 6, v2
	v_lshl_add_u64 v[18:19], v[4:5], 0, v[18:19]
	v_lshl_add_u64 v[22:23], v[4:5], 0, v[20:21]
	v_ashrrev_i32_e32 v27, 31, v26
	v_ashrrev_i32_e32 v29, 31, v28
	v_add_u32_e32 v34, s21, v49
	global_load_dwordx4 v[18:21], v[18:19], off
	s_nop 0
	global_load_dwordx4 v[22:25], v[22:23], off
	v_lshlrev_b64 v[26:27], 13, v[26:27]
	v_lshlrev_b64 v[28:29], 13, v[28:29]
	v_ashrrev_i32_e32 v35, 31, v34
	v_lshl_add_u64 v[26:27], v[4:5], 0, v[26:27]
	v_lshl_add_u64 v[30:31], v[4:5], 0, v[28:29]
	v_lshlrev_b64 v[34:35], 13, v[34:35]
	v_add_u32_e32 v2, 0xe00, v9
	global_load_dwordx4 v[26:29], v[26:27], off
	s_nop 0
	global_load_dwordx4 v[30:33], v[30:31], off
	v_lshl_add_u64 v[34:35], v[4:5], 0, v[34:35]
	v_ashrrev_i32_e32 v50, 6, v2
	global_load_dwordx4 v[34:37], v[34:35], off
	v_add_u32_e32 v38, s21, v50
	v_ashrrev_i32_e32 v39, 31, v38
	v_lshlrev_b64 v[38:39], 13, v[38:39]
	v_lshl_add_u64 v[4:5], v[4:5], 0, v[38:39]
	global_load_dwordx4 v[38:41], v[4:5], off
	v_lshl_add_u32 v2, v42, 2, 0
	s_lshl_b64 s[2:3], s[18:19], 22
	v_mad_u64_u32 v[4:5], s[22:23], v43, s37, v[2:3]
	v_mad_u64_u32 v[42:43], s[22:23], v44, s37, v[2:3]
	v_mad_u64_u32 v[44:45], s[22:23], v45, s37, v[2:3]
	s_add_u32 s18, s34, s2
	s_addc_u32 s22, s35, s3
	s_waitcnt lgkmcnt(0)
	s_barrier
	s_waitcnt vmcnt(0)
	ds_write2_b32 v4, v10, v11 offset1:1
	ds_write2_b32 v4, v12, v13 offset0:2 offset1:3
	ds_write2_b32 v42, v14, v15 offset1:1
	ds_write2_b32 v42, v16, v17 offset0:2 offset1:3
	ds_write2_b32 v44, v18, v19 offset1:1
	ds_write2_b32 v44, v20, v21 offset0:2 offset1:3
	v_mad_u64_u32 v[4:5], s[2:3], v46, s37, v[2:3]
	ds_write2_b32 v4, v22, v23 offset1:1
	ds_write2_b32 v4, v24, v25 offset0:2 offset1:3
	v_mad_u64_u32 v[4:5], s[2:3], v47, s37, v[2:3]
	ds_write2_b32 v4, v26, v27 offset1:1
	ds_write2_b32 v4, v28, v29 offset0:2 offset1:3
	v_mad_u64_u32 v[4:5], s[2:3], v48, s37, v[2:3]
	ds_write2_b32 v4, v30, v31 offset1:1
	ds_write2_b32 v4, v32, v33 offset0:2 offset1:3
	v_mad_u64_u32 v[4:5], s[2:3], v49, s37, v[2:3]
	ds_write2_b32 v4, v34, v35 offset1:1
	ds_write2_b32 v4, v36, v37 offset0:2 offset1:3
	v_mad_u64_u32 v[4:5], s[2:3], v50, s37, v[2:3]
	v_lshlrev_b32_e32 v2, 3, v9
	s_lshl_b32 s2, s21, 1
	v_and_b32_e32 v11, 56, v2
	s_add_u32 s2, s18, s2
	s_addc_u32 s3, s22, 0
	v_lshlrev_b32_e32 v2, 1, v11
	v_ashrrev_i32_e32 v10, 3, v9
	ds_write2_b32 v4, v38, v39 offset1:1
	ds_write2_b32 v4, v40, v41 offset0:2 offset1:3
	v_lshl_add_u64 v[4:5], s[2:3], 0, v[2:3]
	v_add_u32_e32 v2, s20, v10
	v_cmp_gt_u32_e32 vcc, s36, v2
	v_mul_u32_u24_e32 v9, 0x414, v11
	s_waitcnt lgkmcnt(0)
	s_barrier
	s_and_saveexec_b64 s[2:3], vcc
	s_cbranch_execz .LBB0_52
	v_lshlrev_b32_e32 v10, 2, v10
	v_add3_u32 v10, 0, v10, v9
	ds_read_b32 v11, v10
	ds_read_b32 v12, v10 offset:1044
	ds_read_b32 v13, v10 offset:2088
	ds_read_b32 v14, v10 offset:3132
	ds_read_b32 v15, v10 offset:4176
	ds_read_b32 v16, v10 offset:5220
	ds_read_b32 v17, v10 offset:6264
	ds_read_b32 v18, v10 offset:7308
	v_lshlrev_b32_e32 v2, 11, v2
	s_waitcnt lgkmcnt(6)
	v_cvt_pk_bf16_f32 v10, v11, v12
	s_waitcnt lgkmcnt(4)
	v_cvt_pk_bf16_f32 v11, v13, v14
	s_waitcnt lgkmcnt(2)
	v_cvt_pk_bf16_f32 v12, v15, v16
	s_waitcnt lgkmcnt(0)
	v_cvt_pk_bf16_f32 v13, v17, v18
	v_lshl_add_u64 v[14:15], v[4:5], 0, v[2:3]
	global_store_dwordx4 v[14:15], v[10:13], off
; __device__ __forceinline__ unsigned cvt_pk_bf16(float lo, float hi) { f32x2_t f = {lo, hi}; bf16x2_t v = __builtin_convertvector(f, bf16x2_t); return __builtin_bit_cast(unsigned, v); }
; __device__ __forceinline__ void conv_tile(LAS float* tl, const float* src, int ldsrc, int k0, int n0, int N, bf16_t* dst, int lddst, int mode, int wv) {
;     ...
;     for (int i = 0; i < 4; ++i) { const int item = i * 512 + tid, nl = item >> 3, k8 = (item & 7) * 8, n = n0 + nl;
;         int row = n;
;         if (mode == 0) row = n < 8192 ? n : (n < 8200 ? -1 : n - 8);
;         else if (mode == 2) { const int c = n % DFF, gt = n / DFF; row = (c >> 7) * 256 + gt * 128 + (c & 127); }
;         if (n < N && row >= 0) {
;             float x[8];
; #pragma unroll
;             for (int j = 0; j < 8; ++j) x[j] = tl[(k8 + j) * S + nl];
;             u32x4 w; w.x = cvt_pk_bf16(x[0], x[1]); w.y = cvt_pk_bf16(x[2], x[3]); w.z = cvt_pk_bf16(x[4], x[5]); w.w = cvt_pk_bf16(x[6], x[7]);
;             *(u32x4*)(dst + (size_t)row * lddst + k0 + k8) = w;
;         } }
.LBB0_52:
	s_or_b64 exec, exec, s[2:3]
	v_ashrrev_i32_e32 v8, 3, v8
	v_add_u32_e32 v2, s20, v8
	v_cmp_gt_u32_e32 vcc, s36, v2
	s_and_saveexec_b64 s[2:3], vcc
	s_cbranch_execz .LBB0_54
	v_lshlrev_b32_e32 v8, 2, v8
	v_add3_u32 v8, 0, v8, v9
	ds_read_b32 v10, v8
	ds_read_b32 v11, v8 offset:1044
	ds_read_b32 v12, v8 offset:2088
	ds_read_b32 v13, v8 offset:3132
	ds_read_b32 v14, v8 offset:4176
	ds_read_b32 v15, v8 offset:5220
	ds_read_b32 v16, v8 offset:6264
	ds_read_b32 v8, v8 offset:7308
	v_lshlrev_b32_e32 v2, 11, v2
	s_waitcnt lgkmcnt(0)
	v_cvt_pk_bf16_f32 v10, v10, v11
	v_cvt_pk_bf16_f32 v11, v12, v13
	v_cvt_pk_bf16_f32 v12, v14, v15
	v_cvt_pk_bf16_f32 v13, v16, v8
	v_lshl_add_u64 v[14:15], v[4:5], 0, v[2:3]
	global_store_dwordx4 v[14:15], v[10:13], off
.LBB0_54:
	s_or_b64 exec, exec, s[2:3]
	v_ashrrev_i32_e32 v7, 3, v7
	v_add_u32_e32 v2, s20, v7
	v_cmp_gt_u32_e32 vcc, s36, v2
	s_and_saveexec_b64 s[2:3], vcc
	s_cbranch_execz .LBB0_56
	v_lshlrev_b32_e32 v7, 2, v7
	v_add3_u32 v7, 0, v7, v9
	ds_read_b32 v8, v7
	ds_read_b32 v10, v7 offset:1044
	ds_read_b32 v11, v7 offset:2088
	ds_read_b32 v12, v7 offset:3132
	ds_read_b32 v13, v7 offset:4176
	ds_read_b32 v14, v7 offset:5220
	ds_read_b32 v15, v7 offset:6264
	ds_read_b32 v7, v7 offset:7308
	v_lshlrev_b32_e32 v2, 11, v2
	s_waitcnt lgkmcnt(0)
	v_cvt_pk_bf16_f32 v10, v8, v10
	v_cvt_pk_bf16_f32 v11, v11, v12
	v_cvt_pk_bf16_f32 v12, v13, v14
	v_cvt_pk_bf16_f32 v13, v15, v7
	v_lshl_add_u64 v[14:15], v[4:5], 0, v[2:3]
	global_store_dwordx4 v[14:15], v[10:13], off
.LBB0_56:
	s_or_b64 exec, exec, s[2:3]
	v_ashrrev_i32_e32 v6, 3, v6
	v_add_u32_e32 v2, s20, v6
	v_cmp_gt_u32_e32 vcc, s36, v2
	s_and_saveexec_b64 s[2:3], vcc
	s_cbranch_execz .LBB0_58
	v_lshlrev_b32_e32 v6, 2, v6
	v_add3_u32 v6, 0, v6, v9
	ds_read_b32 v7, v6
	ds_read_b32 v8, v6 offset:1044
	ds_read_b32 v9, v6 offset:2088
	ds_read_b32 v10, v6 offset:3132
	ds_read_b32 v11, v6 offset:4176
	ds_read_b32 v12, v6 offset:5220
	ds_read_b32 v13, v6 offset:6264
	ds_read_b32 v14, v6 offset:7308
	v_lshlrev_b32_e32 v2, 11, v2
	s_waitcnt lgkmcnt(0)
	v_cvt_pk_bf16_f32 v6, v7, v8
	v_cvt_pk_bf16_f32 v7, v9, v10
	v_cvt_pk_bf16_f32 v8, v11, v12
	v_cvt_pk_bf16_f32 v9, v13, v14
	v_lshl_add_u64 v[4:5], v[4:5], 0, v[2:3]
	global_store_dwordx4 v[4:5], v[6:9], off

; __device__ __forceinline__ void conv_tile(LAS float* tl, const float* src, int ldsrc, int k0, int n0, int N, bf16_t* dst, int lddst, int mode, int wv) {
;     ...
;     for (int i = 0; i < 8; ++i) { const int e = i * 512 + tid, kk = e >> 6, n = n0 + (e & 63) * 4;
;         v[i] = (f32x4){0.f, 0.f, 0.f, 0.f};
;         if (n + 3 < N) v[i] = *(const f32x4*)(src + (size_t)(k0 + kk) * ldsrc + n);
;         else { for (int j = 0; j < 4; ++j) if (n + j < N) v[i][j] = src[(size_t)(k0 + kk) * ldsrc + n + j]; } }
; __device__ NOINL void convert_weights(const float* win, const float* wbr, const float* wout, const float* wup, const float* wdown, unsigned char* ws, LAS unsigned char* lds, int wv) {
;     ...
;         if (t < T0) { const int tk = t / 57, tn = t % 57;
;             conv_tile(tl, win, DIN, tk * 64, tn * 256, DIN, (bf16_t*)(ws + WS_WIN), 2048, 0, wv); }
.LBB0_60:
	s_andn2_b64 vcc, exec, s[2:3]
	s_cbranch_vccnz .LBB0_14
	s_mul_hi_i32 s2, s26, 0x8fb823ef
	s_add_i32 s2, s2, s26
	s_lshr_b32 s3, s2, 31
	s_ashr_i32 s2, s2, 5
	s_add_i32 s2, s2, s3
	s_mul_i32 s3, s2, 57
	v_mov_b32_e32 v42, v236
	s_sub_i32 s3, s26, s3
	s_lshl_b32 s18, s3, 8
	v_lshlrev_b32_e32 v2, 2, v42
	v_and_b32_e32 v43, 0xfc, v2
	v_or_b32_e32 v38, s18, v43
	s_lshl_b32 s20, s2, 6
	v_or_b32_e32 v2, 3, v38
	v_ashrrev_i32_e32 v39, 31, v38
	v_ashrrev_i32_e32 v44, 6, v42
	v_cmp_lt_i32_e32 vcc, s43, v2
	v_lshl_add_u64 v[34:35], v[38:39], 2, s[6:7]
	v_add_u32_e32 v2, s20, v44
	v_mad_i64_i32 v[10:11], s[2:3], v2, s44, v[34:35]
	s_and_saveexec_b64 s[2:3], vcc
	s_xor_b64 s[22:23], exec, s[2:3]
	s_cbranch_execz .LBB0_67
	v_mov_b32_e32 v4, v3
	v_mov_b32_e32 v5, v3
	v_mov_b32_e32 v2, v3
	v_mov_b64_e32 v[8:9], v[4:5]
	v_cmp_gt_u32_e64 s[2:3], s45, v38
	v_mov_b64_e32 v[6:7], v[2:3]
	s_and_saveexec_b64 s[24:25], s[2:3]
	s_cbranch_execz .LBB0_133
	global_load_dword v2, v[10:11], off
	v_mov_b32_e32 v4, v3
	v_mov_b32_e32 v5, v3
	s_waitcnt vmcnt(0) lgkmcnt(0)
	v_mov_b64_e32 v[8:9], v[4:5]
	v_mov_b64_e32 v[6:7], v[2:3]
	s_or_b64 exec, exec, s[24:25]
	s_and_saveexec_b64 s[24:25], s[2:3]
	s_cbranch_execnz .LBB0_134

; __device__ __forceinline__ void conv_tile(LAS float* tl, const float* src, int ldsrc, int k0, int n0, int N, bf16_t* dst, int lddst, int mode, int wv) {
;     ...
;         else { for (int j = 0; j < 4; ++j) if (n + j < N) v[i][j] = src[(size_t)(k0 + kk) * ldsrc + n + j]; } }
.LBB0_65:
	global_load_dword v8, v[10:11], off offset:8

; __device__ __forceinline__ void conv_tile(LAS float* tl, const float* src, int ldsrc, int k0, int n0, int N, bf16_t* dst, int lddst, int mode, int wv) {
;     ...
;     for (int i = 0; i < 8; ++i) { const int e = i * 512 + tid, kk = e >> 6, n = n0 + (e & 63) * 4;
;         v[i] = (f32x4){0.f, 0.f, 0.f, 0.f};
;         if (n + 3 < N) v[i] = *(const f32x4*)(src + (size_t)(k0 + kk) * ldsrc + n);
;         else { for (int j = 0; j < 4; ++j) if (n + j < N) v[i][j] = src[(size_t)(k0 + kk) * ldsrc + n + j]; } }
.LBB0_67:
	s_andn2_saveexec_b64 s[2:3], s[22:23]
	s_cbranch_execz .LBB0_69
	s_waitcnt vmcnt(0) lgkmcnt(0)
	global_load_dwordx4 v[6:9], v[10:11], off
.LBB0_69:
	s_or_b64 exec, exec, s[2:3]
	v_add_u32_e32 v39, 0x200, v42
	v_ashrrev_i32_e32 v46, 6, v39
	v_add_u32_e32 v2, s20, v46
	v_mad_i64_i32 v[14:15], s[2:3], v2, s44, v[34:35]
	s_and_saveexec_b64 s[2:3], vcc
	s_xor_b64 s[22:23], exec, s[2:3]
	s_cbranch_execz .LBB0_75
	v_mov_b32_e32 v4, v3
	v_mov_b32_e32 v5, v3
	v_mov_b32_e32 v2, v3
	v_mov_b64_e32 v[12:13], v[4:5]
	v_cmp_gt_u32_e64 s[2:3], s45, v38
	v_mov_b64_e32 v[10:11], v[2:3]
	s_and_saveexec_b64 s[24:25], s[2:3]
	s_cbranch_execz .LBB0_135
	global_load_dword v2, v[14:15], off
	v_mov_b32_e32 v4, v3
	v_mov_b32_e32 v5, v3
	s_waitcnt vmcnt(0) lgkmcnt(0)
	v_mov_b64_e32 v[12:13], v[4:5]
	v_mov_b64_e32 v[10:11], v[2:3]
	s_or_b64 exec, exec, s[24:25]
	s_and_saveexec_b64 s[24:25], s[2:3]
	s_cbranch_execnz .LBB0_136

; __device__ __forceinline__ void conv_tile(LAS float* tl, const float* src, int ldsrc, int k0, int n0, int N, bf16_t* dst, int lddst, int mode, int wv) {
;     ...
;         else { for (int j = 0; j < 4; ++j) if (n + j < N) v[i][j] = src[(size_t)(k0 + kk) * ldsrc + n + j]; } }
.LBB0_73:
	global_load_dword v12, v[14:15], off offset:8

; __device__ __forceinline__ void conv_tile(LAS float* tl, const float* src, int ldsrc, int k0, int n0, int N, bf16_t* dst, int lddst, int mode, int wv) {
;     ...
;     for (int i = 0; i < 8; ++i) { const int e = i * 512 + tid, kk = e >> 6, n = n0 + (e & 63) * 4;
;         v[i] = (f32x4){0.f, 0.f, 0.f, 0.f};
;         if (n + 3 < N) v[i] = *(const f32x4*)(src + (size_t)(k0 + kk) * ldsrc + n);
;         else { for (int j = 0; j < 4; ++j) if (n + j < N) v[i][j] = src[(size_t)(k0 + kk) * ldsrc + n + j]; } }
.LBB0_75:
	s_andn2_saveexec_b64 s[2:3], s[22:23]
	s_cbranch_execz .LBB0_77
	s_waitcnt vmcnt(0) lgkmcnt(0)
	global_load_dwordx4 v[10:13], v[14:15], off
.LBB0_77:
	s_or_b64 exec, exec, s[2:3]
	v_add_u32_e32 v45, 0x400, v42
	v_ashrrev_i32_e32 v48, 6, v45
	v_add_u32_e32 v2, s20, v48
	v_mad_i64_i32 v[18:19], s[2:3], v2, s44, v[34:35]
	s_and_saveexec_b64 s[2:3], vcc
	s_xor_b64 s[22:23], exec, s[2:3]
	s_cbranch_execz .LBB0_83
	v_mov_b32_e32 v4, v3
	v_mov_b32_e32 v5, v3
	v_mov_b32_e32 v2, v3
	v_mov_b64_e32 v[16:17], v[4:5]
	v_cmp_gt_u32_e64 s[2:3], s45, v38
	v_mov_b64_e32 v[14:15], v[2:3]
	s_and_saveexec_b64 s[24:25], s[2:3]
	s_cbranch_execz .LBB0_137
	global_load_dword v2, v[18:19], off
	v_mov_b32_e32 v4, v3
	v_mov_b32_e32 v5, v3
	s_waitcnt vmcnt(0) lgkmcnt(0)
	v_mov_b64_e32 v[16:17], v[4:5]
	v_mov_b64_e32 v[14:15], v[2:3]
	s_or_b64 exec, exec, s[24:25]
	s_and_saveexec_b64 s[24:25], s[2:3]
	s_cbranch_execnz .LBB0_138

; __device__ __forceinline__ void conv_tile(LAS float* tl, const float* src, int ldsrc, int k0, int n0, int N, bf16_t* dst, int lddst, int mode, int wv) {
;     ...
;         else { for (int j = 0; j < 4; ++j) if (n + j < N) v[i][j] = src[(size_t)(k0 + kk) * ldsrc + n + j]; } }
.LBB0_81:
	global_load_dword v16, v[18:19], off offset:8

; __device__ __forceinline__ void conv_tile(LAS float* tl, const float* src, int ldsrc, int k0, int n0, int N, bf16_t* dst, int lddst, int mode, int wv) {
;     ...
;     for (int i = 0; i < 8; ++i) { const int e = i * 512 + tid, kk = e >> 6, n = n0 + (e & 63) * 4;
;         v[i] = (f32x4){0.f, 0.f, 0.f, 0.f};
;         if (n + 3 < N) v[i] = *(const f32x4*)(src + (size_t)(k0 + kk) * ldsrc + n);
;         else { for (int j = 0; j < 4; ++j) if (n + j < N) v[i][j] = src[(size_t)(k0 + kk) * ldsrc + n + j]; } }
.LBB0_83:
	s_andn2_saveexec_b64 s[2:3], s[22:23]
	s_cbranch_execz .LBB0_85
	s_waitcnt vmcnt(0) lgkmcnt(0)
	global_load_dwordx4 v[14:17], v[18:19], off
.LBB0_85:
	s_or_b64 exec, exec, s[2:3]
	v_add_u32_e32 v47, 0x600, v42
	v_ashrrev_i32_e32 v49, 6, v47
	v_add_u32_e32 v2, s20, v49
	v_mad_i64_i32 v[22:23], s[2:3], v2, s44, v[34:35]
	s_and_saveexec_b64 s[2:3], vcc
	s_xor_b64 s[22:23], exec, s[2:3]
	s_cbranch_execz .LBB0_91
	v_mov_b32_e32 v4, v3
	v_mov_b32_e32 v5, v3
	v_mov_b32_e32 v2, v3
	v_mov_b64_e32 v[20:21], v[4:5]
	v_cmp_gt_u32_e64 s[2:3], s45, v38
	v_mov_b64_e32 v[18:19], v[2:3]
	s_and_saveexec_b64 s[24:25], s[2:3]
	s_cbranch_execz .LBB0_139
	global_load_dword v2, v[22:23], off
	v_mov_b32_e32 v4, v3
	v_mov_b32_e32 v5, v3
	s_waitcnt vmcnt(0) lgkmcnt(0)
	v_mov_b64_e32 v[20:21], v[4:5]
	v_mov_b64_e32 v[18:19], v[2:3]
	s_or_b64 exec, exec, s[24:25]
	s_and_saveexec_b64 s[24:25], s[2:3]
	s_cbranch_execnz .LBB0_140

; __device__ __forceinline__ void conv_tile(LAS float* tl, const float* src, int ldsrc, int k0, int n0, int N, bf16_t* dst, int lddst, int mode, int wv) {
;     ...
;         else { for (int j = 0; j < 4; ++j) if (n + j < N) v[i][j] = src[(size_t)(k0 + kk) * ldsrc + n + j]; } }
.LBB0_89:
	global_load_dword v20, v[22:23], off offset:8

; __device__ __forceinline__ void conv_tile(LAS float* tl, const float* src, int ldsrc, int k0, int n0, int N, bf16_t* dst, int lddst, int mode, int wv) {
;     ...
;     for (int i = 0; i < 8; ++i) { const int e = i * 512 + tid, kk = e >> 6, n = n0 + (e & 63) * 4;
;         v[i] = (f32x4){0.f, 0.f, 0.f, 0.f};
;         if (n + 3 < N) v[i] = *(const f32x4*)(src + (size_t)(k0 + kk) * ldsrc + n);
;         else { for (int j = 0; j < 4; ++j) if (n + j < N) v[i][j] = src[(size_t)(k0 + kk) * ldsrc + n + j]; } }
.LBB0_91:
	s_andn2_saveexec_b64 s[2:3], s[22:23]
	s_cbranch_execz .LBB0_93
	s_waitcnt vmcnt(0) lgkmcnt(0)
	global_load_dwordx4 v[18:21], v[22:23], off
.LBB0_93:
	s_or_b64 exec, exec, s[2:3]
	v_add_u32_e32 v2, 0x800, v42
	v_ashrrev_i32_e32 v50, 6, v2
	v_add_u32_e32 v2, s20, v50
	v_mad_i64_i32 v[26:27], s[2:3], v2, s44, v[34:35]
	s_and_saveexec_b64 s[2:3], vcc
	s_xor_b64 s[22:23], exec, s[2:3]
	s_cbranch_execz .LBB0_99
	v_mov_b32_e32 v4, v3
	v_mov_b32_e32 v5, v3
	v_mov_b32_e32 v2, v3
	v_mov_b64_e32 v[24:25], v[4:5]
	v_cmp_gt_u32_e64 s[2:3], s45, v38
	v_mov_b64_e32 v[22:23], v[2:3]
	s_and_saveexec_b64 s[24:25], s[2:3]
	s_cbranch_execz .LBB0_141
	global_load_dword v2, v[26:27], off
	v_mov_b32_e32 v4, v3
	v_mov_b32_e32 v5, v3
	s_waitcnt vmcnt(0) lgkmcnt(0)
	v_mov_b64_e32 v[24:25], v[4:5]
	v_mov_b64_e32 v[22:23], v[2:3]
	s_or_b64 exec, exec, s[24:25]
	s_and_saveexec_b64 s[24:25], s[2:3]
	s_cbranch_execnz .LBB0_142

; __device__ __forceinline__ void conv_tile(LAS float* tl, const float* src, int ldsrc, int k0, int n0, int N, bf16_t* dst, int lddst, int mode, int wv) {
;     ...
;         else { for (int j = 0; j < 4; ++j) if (n + j < N) v[i][j] = src[(size_t)(k0 + kk) * ldsrc + n + j]; } }
.LBB0_97:
	global_load_dword v24, v[26:27], off offset:8

; __device__ __forceinline__ void conv_tile(LAS float* tl, const float* src, int ldsrc, int k0, int n0, int N, bf16_t* dst, int lddst, int mode, int wv) {
;     ...
;     for (int i = 0; i < 8; ++i) { const int e = i * 512 + tid, kk = e >> 6, n = n0 + (e & 63) * 4;
;         v[i] = (f32x4){0.f, 0.f, 0.f, 0.f};
;         if (n + 3 < N) v[i] = *(const f32x4*)(src + (size_t)(k0 + kk) * ldsrc + n);
;         else { for (int j = 0; j < 4; ++j) if (n + j < N) v[i][j] = src[(size_t)(k0 + kk) * ldsrc + n + j]; } }
.LBB0_99:
	s_andn2_saveexec_b64 s[2:3], s[22:23]
	s_cbranch_execz .LBB0_101
	s_waitcnt vmcnt(0) lgkmcnt(0)
	global_load_dwordx4 v[22:25], v[26:27], off
.LBB0_101:
	s_or_b64 exec, exec, s[2:3]
	v_add_u32_e32 v2, 0xa00, v42
	v_ashrrev_i32_e32 v51, 6, v2
	v_add_u32_e32 v2, s20, v51
	v_mad_i64_i32 v[30:31], s[2:3], v2, s44, v[34:35]
	s_and_saveexec_b64 s[2:3], vcc
	s_xor_b64 s[22:23], exec, s[2:3]
	s_cbranch_execz .LBB0_107
	v_mov_b32_e32 v4, v3
	v_mov_b32_e32 v5, v3
	v_mov_b32_e32 v2, v3
	v_mov_b64_e32 v[28:29], v[4:5]
	v_cmp_gt_u32_e64 s[2:3], s45, v38
	v_mov_b64_e32 v[26:27], v[2:3]
	s_and_saveexec_b64 s[24:25], s[2:3]
	s_cbranch_execz .LBB0_143
	global_load_dword v2, v[30:31], off
	v_mov_b32_e32 v4, v3
	v_mov_b32_e32 v5, v3
	s_waitcnt vmcnt(0) lgkmcnt(0)
	v_mov_b64_e32 v[28:29], v[4:5]
	v_mov_b64_e32 v[26:27], v[2:3]
	s_or_b64 exec, exec, s[24:25]
	s_and_saveexec_b64 s[24:25], s[2:3]
	s_cbranch_execnz .LBB0_144

; __device__ __forceinline__ void conv_tile(LAS float* tl, const float* src, int ldsrc, int k0, int n0, int N, bf16_t* dst, int lddst, int mode, int wv) {
;     ...
;         else { for (int j = 0; j < 4; ++j) if (n + j < N) v[i][j] = src[(size_t)(k0 + kk) * ldsrc + n + j]; } }
.LBB0_105:
	global_load_dword v28, v[30:31], off offset:8

; __device__ __forceinline__ void conv_tile(LAS float* tl, const float* src, int ldsrc, int k0, int n0, int N, bf16_t* dst, int lddst, int mode, int wv) {
;     ...
;     for (int i = 0; i < 8; ++i) { const int e = i * 512 + tid, kk = e >> 6, n = n0 + (e & 63) * 4;
;         v[i] = (f32x4){0.f, 0.f, 0.f, 0.f};
;         if (n + 3 < N) v[i] = *(const f32x4*)(src + (size_t)(k0 + kk) * ldsrc + n);
;         else { for (int j = 0; j < 4; ++j) if (n + j < N) v[i][j] = src[(size_t)(k0 + kk) * ldsrc + n + j]; } }
.LBB0_107:
	s_andn2_saveexec_b64 s[2:3], s[22:23]
	s_cbranch_execz .LBB0_109
	s_waitcnt vmcnt(0) lgkmcnt(0)
	global_load_dwordx4 v[26:29], v[30:31], off
.LBB0_109:
	s_or_b64 exec, exec, s[2:3]
	v_add_u32_e32 v2, 0xc00, v42
	v_ashrrev_i32_e32 v52, 6, v2
	v_add_u32_e32 v2, s20, v52
	v_mad_i64_i32 v[36:37], s[2:3], v2, s44, v[34:35]
	s_and_saveexec_b64 s[2:3], vcc
	s_xor_b64 s[22:23], exec, s[2:3]
	s_cbranch_execz .LBB0_115
	v_mov_b32_e32 v4, v3
	v_mov_b32_e32 v5, v3
	v_mov_b32_e32 v2, v3
	v_mov_b64_e32 v[32:33], v[4:5]
	v_cmp_gt_u32_e64 s[2:3], s45, v38
	v_mov_b64_e32 v[30:31], v[2:3]
	s_and_saveexec_b64 s[24:25], s[2:3]
	s_cbranch_execz .LBB0_145
	global_load_dword v2, v[36:37], off
	v_mov_b32_e32 v4, v3
	v_mov_b32_e32 v5, v3
	s_waitcnt vmcnt(0) lgkmcnt(0)
	v_mov_b64_e32 v[32:33], v[4:5]
	v_mov_b64_e32 v[30:31], v[2:3]
	s_or_b64 exec, exec, s[24:25]
	s_and_saveexec_b64 s[24:25], s[2:3]
	s_cbranch_execnz .LBB0_146

; __device__ __forceinline__ void conv_tile(LAS float* tl, const float* src, int ldsrc, int k0, int n0, int N, bf16_t* dst, int lddst, int mode, int wv) {
;     ...
;         else { for (int j = 0; j < 4; ++j) if (n + j < N) v[i][j] = src[(size_t)(k0 + kk) * ldsrc + n + j]; } }
.LBB0_113:
	global_load_dword v32, v[36:37], off offset:8

; __device__ __forceinline__ void conv_tile(LAS float* tl, const float* src, int ldsrc, int k0, int n0, int N, bf16_t* dst, int lddst, int mode, int wv) {
;     ...
;     for (int i = 0; i < 8; ++i) { const int e = i * 512 + tid, kk = e >> 6, n = n0 + (e & 63) * 4;
;         v[i] = (f32x4){0.f, 0.f, 0.f, 0.f};
;         if (n + 3 < N) v[i] = *(const f32x4*)(src + (size_t)(k0 + kk) * ldsrc + n);
;         else { for (int j = 0; j < 4; ++j) if (n + j < N) v[i][j] = src[(size_t)(k0 + kk) * ldsrc + n + j]; } }
.LBB0_115:
	s_andn2_saveexec_b64 s[2:3], s[22:23]
	s_cbranch_execz .LBB0_117
	s_waitcnt vmcnt(0) lgkmcnt(0)
	global_load_dwordx4 v[30:33], v[36:37], off
.LBB0_117:
	s_or_b64 exec, exec, s[2:3]
	v_add_u32_e32 v2, 0xe00, v42
	v_ashrrev_i32_e32 v53, 6, v2
	v_add_u32_e32 v2, s20, v53
	v_mad_i64_i32 v[40:41], s[2:3], v2, s44, v[34:35]
	s_and_saveexec_b64 s[2:3], vcc
	s_xor_b64 s[2:3], exec, s[2:3]
	s_cbranch_execz .LBB0_123
	v_mov_b32_e32 v4, v3
	v_mov_b32_e32 v5, v3
	v_mov_b32_e32 v2, v3
	v_mov_b64_e32 v[36:37], v[4:5]
	v_cmp_gt_u32_e32 vcc, s45, v38
	v_mov_b64_e32 v[34:35], v[2:3]
	s_and_saveexec_b64 s[22:23], vcc
	s_cbranch_execz .LBB0_147
	global_load_dword v2, v[40:41], off
	v_mov_b32_e32 v4, v3
	v_mov_b32_e32 v5, v3
	s_waitcnt vmcnt(0) lgkmcnt(0)
	v_mov_b64_e32 v[36:37], v[4:5]
	v_mov_b64_e32 v[34:35], v[2:3]
	s_or_b64 exec, exec, s[22:23]
	s_and_saveexec_b64 s[22:23], vcc
	s_cbranch_execnz .LBB0_148

; __device__ __forceinline__ void conv_tile(LAS float* tl, const float* src, int ldsrc, int k0, int n0, int N, bf16_t* dst, int lddst, int mode, int wv) {
;     ...
;         else { for (int j = 0; j < 4; ++j) if (n + j < N) v[i][j] = src[(size_t)(k0 + kk) * ldsrc + n + j]; } }
.LBB0_121:
	global_load_dword v36, v[40:41], off offset:8

; __device__ __forceinline__ unsigned cvt_pk_bf16(float lo, float hi) { f32x2_t f = {lo, hi}; bf16x2_t v = __builtin_convertvector(f, bf16x2_t); return __builtin_bit_cast(unsigned, v); }
; __device__ __forceinline__ void conv_tile(LAS float* tl, const float* src, int ldsrc, int k0, int n0, int N, bf16_t* dst, int lddst, int mode, int wv) {
;     ...
;     __syncthreads();
; #pragma unroll
;     for (int i = 0; i < 8; ++i) { const int e = i * 512 + tid, kk = e >> 6, n4 = (e & 63) * 4;
; #pragma unroll
;         for (int j = 0; j < 4; ++j) tl[kk * S + n4 + j] = v[i][j]; }
;     __syncthreads();
; #pragma unroll
;     for (int i = 0; i < 4; ++i) { const int item = i * 512 + tid, nl = item >> 3, k8 = (item & 7) * 8, n = n0 + nl;
;         int row = n;
;         if (mode == 0) row = n < 8192 ? n : (n < 8200 ? -1 : n - 8);
;         else if (mode == 2) { const int c = n % DFF, gt = n / DFF; row = (c >> 7) * 256 + gt * 128 + (c & 127); }
;         if (n < N && row >= 0) {
;             float x[8];
; #pragma unroll
;             for (int j = 0; j < 8; ++j) x[j] = tl[(k8 + j) * S + nl];
;             u32x4 w; w.x = cvt_pk_bf16(x[0], x[1]); w.y = cvt_pk_bf16(x[2], x[3]); w.z = cvt_pk_bf16(x[4], x[5]); w.w = cvt_pk_bf16(x[6], x[7]);
;             *(u32x4*)(dst + (size_t)row * lddst + k0 + k8) = w;
;         } }
.LBB0_123:
	s_andn2_saveexec_b64 s[2:3], s[2:3]
	s_cbranch_execz .LBB0_125
	s_waitcnt vmcnt(0) lgkmcnt(0)
	global_load_dwordx4 v[34:37], v[40:41], off
.LBB0_125:
	s_or_b64 exec, exec, s[2:3]
	v_lshl_add_u32 v2, v43, 2, 0
	v_mad_u64_u32 v[4:5], s[2:3], v44, s37, v[2:3]
	s_waitcnt lgkmcnt(0)
	s_barrier
	s_waitcnt vmcnt(0)
	ds_write2_b32 v4, v6, v7 offset1:1
	ds_write2_b32 v4, v8, v9 offset0:2 offset1:3
	v_mad_u64_u32 v[4:5], s[2:3], v46, s37, v[2:3]
	ds_write2_b32 v4, v10, v11 offset1:1
	ds_write2_b32 v4, v12, v13 offset0:2 offset1:3
	v_mad_u64_u32 v[4:5], s[2:3], v48, s37, v[2:3]
	ds_write2_b32 v4, v14, v15 offset1:1
	ds_write2_b32 v4, v16, v17 offset0:2 offset1:3
	v_mad_u64_u32 v[4:5], s[2:3], v49, s37, v[2:3]
	ds_write2_b32 v4, v18, v19 offset1:1
	ds_write2_b32 v4, v20, v21 offset0:2 offset1:3
	v_mad_u64_u32 v[4:5], s[2:3], v50, s37, v[2:3]
	ds_write2_b32 v4, v22, v23 offset1:1
	ds_write2_b32 v4, v24, v25 offset0:2 offset1:3
	v_mad_u64_u32 v[4:5], s[2:3], v51, s37, v[2:3]
	ds_write2_b32 v4, v26, v27 offset1:1
	ds_write2_b32 v4, v28, v29 offset0:2 offset1:3
	v_mad_u64_u32 v[4:5], s[2:3], v52, s37, v[2:3]
	ds_write2_b32 v4, v30, v31 offset1:1
	ds_write2_b32 v4, v32, v33 offset0:2 offset1:3
	v_mad_u64_u32 v[4:5], s[2:3], v53, s37, v[2:3]
	s_ashr_i32 s21, s20, 31
	v_lshlrev_b32_e32 v2, 3, v42
	s_lshl_b64 s[2:3], s[20:21], 1
	v_and_b32_e32 v6, 56, v2
	s_add_u32 s2, s16, s2
	v_ashrrev_i32_e32 v7, 3, v42
	s_addc_u32 s3, s17, s3
	v_lshlrev_b32_e32 v2, 1, v6
	v_add_u32_e32 v8, s18, v7
	ds_write2_b32 v4, v34, v35 offset1:1
	ds_write2_b32 v4, v36, v37 offset0:2 offset1:3
	v_lshl_add_u64 v[4:5], s[2:3], 0, v[2:3]
	v_add_u32_e32 v2, -8, v8
	v_cmp_lt_u32_e32 vcc, s47, v8
	v_mul_u32_u24_e32 v6, 0x414, v6
	s_waitcnt lgkmcnt(0)
	v_cndmask_b32_e32 v2, -1, v2, vcc
	v_cmp_gt_i32_e32 vcc, s46, v8
	s_barrier
	s_nop 0
	v_cndmask_b32_e32 v2, v2, v8, vcc
	v_cmp_gt_i32_e32 vcc, s45, v8
	v_cmp_lt_i32_e64 s[2:3], -1, v2
	s_and_b64 s[20:21], vcc, s[2:3]
	s_and_saveexec_b64 s[2:3], s[20:21]
	s_cbranch_execz .LBB0_127
	v_lshlrev_b32_e32 v7, 2, v7
	v_add3_u32 v7, 0, v7, v6
	ds_read_b32 v8, v7
	ds_read_b32 v9, v7 offset:1044
	ds_read_b32 v10, v7 offset:2088
	ds_read_b32 v11, v7 offset:3132
	ds_read_b32 v12, v7 offset:4176
	ds_read_b32 v13, v7 offset:5220
	ds_read_b32 v14, v7 offset:6264
	ds_read_b32 v7, v7 offset:7308
	s_waitcnt lgkmcnt(6)
	v_cvt_pk_bf16_f32 v8, v8, v9
	s_waitcnt lgkmcnt(4)
	v_cvt_pk_bf16_f32 v9, v10, v11
	s_waitcnt lgkmcnt(2)
	v_cvt_pk_bf16_f32 v10, v12, v13
	v_lshlrev_b64 v[12:13], 12, v[2:3]
	s_waitcnt lgkmcnt(0)
	v_cvt_pk_bf16_f32 v11, v14, v7
	v_lshl_add_u64 v[12:13], v[4:5], 0, v[12:13]
	global_store_dwordx4 v[12:13], v[8:11], off
.LBB0_127:
	s_or_b64 exec, exec, s[2:3]
	v_ashrrev_i32_e32 v7, 3, v39
	v_add_u32_e32 v8, s18, v7
	v_add_u32_e32 v2, -8, v8
	v_cmp_lt_u32_e32 vcc, s47, v8
	s_nop 1
	v_cndmask_b32_e32 v2, -1, v2, vcc
	v_cmp_gt_i32_e32 vcc, s46, v8
	s_nop 1
	v_cndmask_b32_e32 v2, v2, v8, vcc
	v_cmp_gt_i32_e32 vcc, s45, v8
	v_cmp_lt_i32_e64 s[2:3], -1, v2
	s_and_b64 s[20:21], vcc, s[2:3]
	s_and_saveexec_b64 s[2:3], s[20:21]
	s_cbranch_execz .LBB0_129
	v_lshlrev_b32_e32 v7, 2, v7
	v_add3_u32 v7, 0, v7, v6
	ds_read_b32 v8, v7
	ds_read_b32 v9, v7 offset:1044
	ds_read_b32 v10, v7 offset:2088
	ds_read_b32 v11, v7 offset:3132
	ds_read_b32 v12, v7 offset:4176
	ds_read_b32 v13, v7 offset:5220
	ds_read_b32 v14, v7 offset:6264
	ds_read_b32 v7, v7 offset:7308
	s_waitcnt lgkmcnt(0)
	v_cvt_pk_bf16_f32 v8, v8, v9
	v_cvt_pk_bf16_f32 v9, v10, v11
	v_cvt_pk_bf16_f32 v10, v12, v13
	v_lshlrev_b64 v[12:13], 12, v[2:3]
	v_cvt_pk_bf16_f32 v11, v14, v7
	v_lshl_add_u64 v[12:13], v[4:5], 0, v[12:13]
	global_store_dwordx4 v[12:13], v[8:11], off
.LBB0_129:
	s_or_b64 exec, exec, s[2:3]
	v_ashrrev_i32_e32 v7, 3, v45
	v_add_u32_e32 v8, s18, v7
	v_add_u32_e32 v2, -8, v8
	v_cmp_lt_u32_e32 vcc, s47, v8
	s_nop 1
	v_cndmask_b32_e32 v2, -1, v2, vcc
	v_cmp_gt_i32_e32 vcc, s46, v8
	s_nop 1
	v_cndmask_b32_e32 v2, v2, v8, vcc
	v_cmp_gt_i32_e32 vcc, s45, v8
	v_cmp_lt_i32_e64 s[2:3], -1, v2
	s_and_b64 s[20:21], vcc, s[2:3]
	s_and_saveexec_b64 s[2:3], s[20:21]
	s_cbranch_execz .LBB0_131
	v_lshlrev_b32_e32 v7, 2, v7
	v_add3_u32 v7, 0, v7, v6
	ds_read_b32 v8, v7
	ds_read_b32 v9, v7 offset:1044
	ds_read_b32 v10, v7 offset:2088
	ds_read_b32 v11, v7 offset:3132
	ds_read_b32 v12, v7 offset:4176
	ds_read_b32 v13, v7 offset:5220
	ds_read_b32 v14, v7 offset:6264
	ds_read_b32 v7, v7 offset:7308
	s_waitcnt lgkmcnt(0)
	v_cvt_pk_bf16_f32 v8, v8, v9
	v_cvt_pk_bf16_f32 v9, v10, v11
	v_cvt_pk_bf16_f32 v10, v12, v13
	v_lshlrev_b64 v[12:13], 12, v[2:3]
	v_cvt_pk_bf16_f32 v11, v14, v7
	v_lshl_add_u64 v[12:13], v[4:5], 0, v[12:13]
	global_store_dwordx4 v[12:13], v[8:11], off
.LBB0_131:
	s_or_b64 exec, exec, s[2:3]
	v_ashrrev_i32_e32 v7, 3, v47
	v_add_u32_e32 v8, s18, v7
	v_add_u32_e32 v2, -8, v8
	v_cmp_lt_u32_e32 vcc, s47, v8
	s_nop 1
	v_cndmask_b32_e32 v2, -1, v2, vcc
	v_cmp_gt_i32_e32 vcc, s46, v8
	s_nop 1
	v_cndmask_b32_e32 v2, v2, v8, vcc
	v_cmp_gt_i32_e32 vcc, s45, v8
	v_cmp_lt_i32_e64 s[2:3], -1, v2
	s_and_b64 s[20:21], vcc, s[2:3]
	s_and_saveexec_b64 s[2:3], s[20:21]
	s_cbranch_execz .LBB0_13
	v_lshlrev_b32_e32 v7, 2, v7
	v_add3_u32 v6, 0, v7, v6
	ds_read_b32 v7, v6
	ds_read_b32 v8, v6 offset:1044
	ds_read_b32 v9, v6 offset:2088
	ds_read_b32 v10, v6 offset:3132
	ds_read_b32 v11, v6 offset:4176
	ds_read_b32 v12, v6 offset:5220
	ds_read_b32 v13, v6 offset:6264
	ds_read_b32 v14, v6 offset:7308
	s_waitcnt lgkmcnt(0)
	v_cvt_pk_bf16_f32 v6, v7, v8
	v_cvt_pk_bf16_f32 v7, v9, v10
	v_cvt_pk_bf16_f32 v8, v11, v12
	v_lshlrev_b64 v[10:11], 12, v[2:3]
	v_cvt_pk_bf16_f32 v9, v13, v14
	v_lshl_add_u64 v[4:5], v[4:5], 0, v[10:11]
	global_store_dwordx4 v[4:5], v[6:9], off
	s_branch .LBB0_13

; __device__ __forceinline__ void conv_tile(LAS float* tl, const float* src, int ldsrc, int k0, int n0, int N, bf16_t* dst, int lddst, int mode, int wv) {
;     ...
;         else { for (int j = 0; j < 4; ++j) if (n + j < N) v[i][j] = src[(size_t)(k0 + kk) * ldsrc + n + j]; } }
.LBB0_134:
	global_load_dword v7, v[10:11], off offset:4
	s_or_b64 exec, exec, s[24:25]
	s_and_saveexec_b64 s[24:25], s[2:3]
	s_cbranch_execnz .LBB0_65
	s_branch .LBB0_66

; __device__ __forceinline__ void conv_tile(LAS float* tl, const float* src, int ldsrc, int k0, int n0, int N, bf16_t* dst, int lddst, int mode, int wv) {
;     ...
;         else { for (int j = 0; j < 4; ++j) if (n + j < N) v[i][j] = src[(size_t)(k0 + kk) * ldsrc + n + j]; } }
.LBB0_136:
	global_load_dword v11, v[14:15], off offset:4
	s_or_b64 exec, exec, s[24:25]
	s_and_saveexec_b64 s[24:25], s[2:3]
	s_cbranch_execnz .LBB0_73
	s_branch .LBB0_74

; __device__ __forceinline__ void conv_tile(LAS float* tl, const float* src, int ldsrc, int k0, int n0, int N, bf16_t* dst, int lddst, int mode, int wv) {
;     ...
;         else { for (int j = 0; j < 4; ++j) if (n + j < N) v[i][j] = src[(size_t)(k0 + kk) * ldsrc + n + j]; } }
.LBB0_138:
	global_load_dword v15, v[18:19], off offset:4
	s_or_b64 exec, exec, s[24:25]
	s_and_saveexec_b64 s[24:25], s[2:3]
	s_cbranch_execnz .LBB0_81
	s_branch .LBB0_82

; __device__ __forceinline__ void conv_tile(LAS float* tl, const float* src, int ldsrc, int k0, int n0, int N, bf16_t* dst, int lddst, int mode, int wv) {
;     ...
;         else { for (int j = 0; j < 4; ++j) if (n + j < N) v[i][j] = src[(size_t)(k0 + kk) * ldsrc + n + j]; } }
.LBB0_140:
	global_load_dword v19, v[22:23], off offset:4
	s_or_b64 exec, exec, s[24:25]
	s_and_saveexec_b64 s[24:25], s[2:3]
	s_cbranch_execnz .LBB0_89
	s_branch .LBB0_90

; __device__ __forceinline__ void conv_tile(LAS float* tl, const float* src, int ldsrc, int k0, int n0, int N, bf16_t* dst, int lddst, int mode, int wv) {
;     ...
;         else { for (int j = 0; j < 4; ++j) if (n + j < N) v[i][j] = src[(size_t)(k0 + kk) * ldsrc + n + j]; } }
.LBB0_142:
	global_load_dword v23, v[26:27], off offset:4
	s_or_b64 exec, exec, s[24:25]
	s_and_saveexec_b64 s[24:25], s[2:3]
	s_cbranch_execnz .LBB0_97
	s_branch .LBB0_98

; __device__ __forceinline__ void conv_tile(LAS float* tl, const float* src, int ldsrc, int k0, int n0, int N, bf16_t* dst, int lddst, int mode, int wv) {
;     ...
;         else { for (int j = 0; j < 4; ++j) if (n + j < N) v[i][j] = src[(size_t)(k0 + kk) * ldsrc + n + j]; } }
.LBB0_144:
	global_load_dword v27, v[30:31], off offset:4
	s_or_b64 exec, exec, s[24:25]
	s_and_saveexec_b64 s[24:25], s[2:3]
	s_cbranch_execnz .LBB0_105
	s_branch .LBB0_106

; __device__ __forceinline__ void conv_tile(LAS float* tl, const float* src, int ldsrc, int k0, int n0, int N, bf16_t* dst, int lddst, int mode, int wv) {
;     ...
;         else { for (int j = 0; j < 4; ++j) if (n + j < N) v[i][j] = src[(size_t)(k0 + kk) * ldsrc + n + j]; } }
.LBB0_146:
	global_load_dword v31, v[36:37], off offset:4
	s_or_b64 exec, exec, s[24:25]
	s_and_saveexec_b64 s[24:25], s[2:3]
	s_cbranch_execnz .LBB0_113
	s_branch .LBB0_114

; __device__ __forceinline__ void conv_tile(LAS float* tl, const float* src, int ldsrc, int k0, int n0, int N, bf16_t* dst, int lddst, int mode, int wv) {
;     ...
;         else { for (int j = 0; j < 4; ++j) if (n + j < N) v[i][j] = src[(size_t)(k0 + kk) * ldsrc + n + j]; } }
.LBB0_148:
	global_load_dword v35, v[40:41], off offset:4
	s_or_b64 exec, exec, s[22:23]
	s_and_saveexec_b64 s[22:23], vcc
	s_cbranch_execnz .LBB0_121
	s_branch .LBB0_122

; __device__ NOINL void prep_weff(const float* pw, const float* ps, const float* wb, bf16_t* dst, LAS unsigned char* lds, int wv) {
;     ...
;         const float* wp = wb + (size_t)(g * 256) * 2048 + n;
; #pragma unroll 4
;         for (int d = 0; d < 256; ++d) { const float w = wp[(size_t)d * 2048];
; #pragma unroll
;             for (int cc = 0; cc < 8; ++cc) acc[cc] += wl[cc * 256 + d] * w; }
.Lweff1_loop:
	global_load_dword v124, v184, s[20:21]
	s_add_u32 s20, s20, 0x2000
	s_addc_u32 s21, s21, 0
	global_load_dword v125, v184, s[20:21]
	s_add_u32 s20, s20, 0x2000
	s_addc_u32 s21, s21, 0
	global_load_dword v126, v184, s[20:21]
	s_add_u32 s20, s20, 0x2000
	s_addc_u32 s21, s21, 0
	global_load_dword v127, v184, s[20:21]
	s_add_u32 s20, s20, 0x2000
	s_addc_u32 s21, s21, 0
	global_load_dword v128, v184, s[20:21]
	s_add_u32 s20, s20, 0x2000
	s_addc_u32 s21, s21, 0
	global_load_dword v129, v184, s[20:21]
	s_add_u32 s20, s20, 0x2000
	s_addc_u32 s21, s21, 0
	global_load_dword v130, v184, s[20:21]
	s_add_u32 s20, s20, 0x2000
	s_addc_u32 s21, s21, 0
	global_load_dword v131, v184, s[20:21]
	s_add_u32 s20, s20, 0x2000
	s_addc_u32 s21, s21, 0
	ds_read_b128 v[64:67], v185 offset:0
	ds_read_b128 v[72:75], v185 offset:1024
	ds_read_b128 v[80:83], v185 offset:2048
	ds_read_b128 v[88:91], v185 offset:3072
	ds_read_b128 v[96:99], v185 offset:4096
	ds_read_b128 v[136:139], v185 offset:5120
	ds_read_b128 v[144:147], v185 offset:6144
	ds_read_b128 v[152:155], v185 offset:7168
	ds_read_b128 v[68:71], v185 offset:16
	ds_read_b128 v[76:79], v185 offset:1040
	ds_read_b128 v[84:87], v185 offset:2064
	ds_read_b128 v[92:95], v185 offset:3088
	ds_read_b128 v[132:135], v185 offset:4112
	ds_read_b128 v[140:143], v185 offset:5136
	ds_read_b128 v[148:151], v185 offset:6160
	ds_read_b128 v[156:159], v185 offset:7184
	s_waitcnt vmcnt(24)
	s_waitcnt lgkmcnt(8)
	v_pk_fma_f32 v[168:169], v[64:65], v[100:101], v[168:169]
	v_pk_fma_f32 v[170:171], v[72:73], v[100:101], v[170:171]
	v_pk_fma_f32 v[172:173], v[80:81], v[100:101], v[172:173]
	v_pk_fma_f32 v[174:175], v[88:89], v[100:101], v[174:175]
	v_pk_fma_f32 v[176:177], v[96:97], v[100:101], v[176:177]
	v_pk_fma_f32 v[178:179], v[136:137], v[100:101], v[178:179]
	v_pk_fma_f32 v[180:181], v[144:145], v[100:101], v[180:181]
	v_pk_fma_f32 v[182:183], v[152:153], v[100:101], v[182:183]
	v_pk_fma_f32 v[168:169], v[66:67], v[102:103], v[168:169]
	v_pk_fma_f32 v[170:171], v[74:75], v[102:103], v[170:171]
	v_pk_fma_f32 v[172:173], v[82:83], v[102:103], v[172:173]
	v_pk_fma_f32 v[174:175], v[90:91], v[102:103], v[174:175]
	v_pk_fma_f32 v[176:177], v[98:99], v[102:103], v[176:177]
	v_pk_fma_f32 v[178:179], v[138:139], v[102:103], v[178:179]
	v_pk_fma_f32 v[180:181], v[146:147], v[102:103], v[180:181]
	v_pk_fma_f32 v[182:183], v[154:155], v[102:103], v[182:183]
	s_waitcnt lgkmcnt(0)
	v_pk_fma_f32 v[168:169], v[68:69], v[104:105], v[168:169]
	v_pk_fma_f32 v[170:171], v[76:77], v[104:105], v[170:171]
	v_pk_fma_f32 v[172:173], v[84:85], v[104:105], v[172:173]
	v_pk_fma_f32 v[174:175], v[92:93], v[104:105], v[174:175]
	v_pk_fma_f32 v[176:177], v[132:133], v[104:105], v[176:177]
	v_pk_fma_f32 v[178:179], v[140:141], v[104:105], v[178:179]
	v_pk_fma_f32 v[180:181], v[148:149], v[104:105], v[180:181]
	v_pk_fma_f32 v[182:183], v[156:157], v[104:105], v[182:183]
	v_pk_fma_f32 v[168:169], v[70:71], v[106:107], v[168:169]
	v_pk_fma_f32 v[170:171], v[78:79], v[106:107], v[170:171]
	v_pk_fma_f32 v[172:173], v[86:87], v[106:107], v[172:173]
	v_pk_fma_f32 v[174:175], v[94:95], v[106:107], v[174:175]
	v_pk_fma_f32 v[176:177], v[134:135], v[106:107], v[176:177]
	v_pk_fma_f32 v[178:179], v[142:143], v[106:107], v[178:179]
	v_pk_fma_f32 v[180:181], v[150:151], v[106:107], v[180:181]
	v_pk_fma_f32 v[182:183], v[158:159], v[106:107], v[182:183]
	global_load_dword v100, v184, s[20:21]
	s_add_u32 s20, s20, 0x2000
	s_addc_u32 s21, s21, 0
	global_load_dword v101, v184, s[20:21]
	s_add_u32 s20, s20, 0x2000
	s_addc_u32 s21, s21, 0
	global_load_dword v102, v184, s[20:21]
	s_add_u32 s20, s20, 0x2000
	s_addc_u32 s21, s21, 0
	global_load_dword v103, v184, s[20:21]
	s_add_u32 s20, s20, 0x2000
	s_addc_u32 s21, s21, 0
	global_load_dword v104, v184, s[20:21]
	s_add_u32 s20, s20, 0x2000
	s_addc_u32 s21, s21, 0
	global_load_dword v105, v184, s[20:21]
	s_add_u32 s20, s20, 0x2000
	s_addc_u32 s21, s21, 0
	global_load_dword v106, v184, s[20:21]
	s_add_u32 s20, s20, 0x2000
	s_addc_u32 s21, s21, 0
	global_load_dword v107, v184, s[20:21]
	s_add_u32 s20, s20, 0x2000
	s_addc_u32 s21, s21, 0
	ds_read_b128 v[64:67], v185 offset:32
	ds_read_b128 v[72:75], v185 offset:1056
	ds_read_b128 v[80:83], v185 offset:2080
	ds_read_b128 v[88:91], v185 offset:3104
	ds_read_b128 v[96:99], v185 offset:4128
	ds_read_b128 v[136:139], v185 offset:5152
	ds_read_b128 v[144:147], v185 offset:6176
	ds_read_b128 v[152:155], v185 offset:7200
	ds_read_b128 v[68:71], v185 offset:48
	ds_read_b128 v[76:79], v185 offset:1072
	ds_read_b128 v[84:87], v185 offset:2096
	ds_read_b128 v[92:95], v185 offset:3120
	ds_read_b128 v[132:135], v185 offset:4144
	ds_read_b128 v[140:143], v185 offset:5168
	ds_read_b128 v[148:151], v185 offset:6192
	ds_read_b128 v[156:159], v185 offset:7216
	s_waitcnt vmcnt(24)
	s_waitcnt lgkmcnt(8)
	v_pk_fma_f32 v[168:169], v[64:65], v[108:109], v[168:169]
	v_pk_fma_f32 v[170:171], v[72:73], v[108:109], v[170:171]
	v_pk_fma_f32 v[172:173], v[80:81], v[108:109], v[172:173]
	v_pk_fma_f32 v[174:175], v[88:89], v[108:109], v[174:175]
	v_pk_fma_f32 v[176:177], v[96:97], v[108:109], v[176:177]
	v_pk_fma_f32 v[178:179], v[136:137], v[108:109], v[178:179]
	v_pk_fma_f32 v[180:181], v[144:145], v[108:109], v[180:181]
	v_pk_fma_f32 v[182:183], v[152:153], v[108:109], v[182:183]
	v_pk_fma_f32 v[168:169], v[66:67], v[110:111], v[168:169]
	v_pk_fma_f32 v[170:171], v[74:75], v[110:111], v[170:171]
	v_pk_fma_f32 v[172:173], v[82:83], v[110:111], v[172:173]
	v_pk_fma_f32 v[174:175], v[90:91], v[110:111], v[174:175]
	v_pk_fma_f32 v[176:177], v[98:99], v[110:111], v[176:177]
	v_pk_fma_f32 v[178:179], v[138:139], v[110:111], v[178:179]
	v_pk_fma_f32 v[180:181], v[146:147], v[110:111], v[180:181]
	v_pk_fma_f32 v[182:183], v[154:155], v[110:111], v[182:183]
	s_waitcnt lgkmcnt(0)
; __device__ NOINL void prep_weff(const float* pw, const float* ps, const float* wb, bf16_t* dst, LAS unsigned char* lds, int wv) {
;     ...
;         for (int d = 0; d < 256; ++d) { const float w = wp[(size_t)d * 2048];
; #pragma unroll
;             for (int cc = 0; cc < 8; ++cc) acc[cc] += wl[cc * 256 + d] * w; }
	v_pk_fma_f32 v[168:169], v[68:69], v[112:113], v[168:169]
	v_pk_fma_f32 v[170:171], v[76:77], v[112:113], v[170:171]
	v_pk_fma_f32 v[172:173], v[84:85], v[112:113], v[172:173]
	v_pk_fma_f32 v[174:175], v[92:93], v[112:113], v[174:175]
	v_pk_fma_f32 v[176:177], v[132:133], v[112:113], v[176:177]
	v_pk_fma_f32 v[178:179], v[140:141], v[112:113], v[178:179]
	v_pk_fma_f32 v[180:181], v[148:149], v[112:113], v[180:181]
	v_pk_fma_f32 v[182:183], v[156:157], v[112:113], v[182:183]
	v_pk_fma_f32 v[168:169], v[70:71], v[114:115], v[168:169]
	v_pk_fma_f32 v[170:171], v[78:79], v[114:115], v[170:171]
	v_pk_fma_f32 v[172:173], v[86:87], v[114:115], v[172:173]
	v_pk_fma_f32 v[174:175], v[94:95], v[114:115], v[174:175]
	v_pk_fma_f32 v[176:177], v[134:135], v[114:115], v[176:177]
	v_pk_fma_f32 v[178:179], v[142:143], v[114:115], v[178:179]
	v_pk_fma_f32 v[180:181], v[150:151], v[114:115], v[180:181]
	v_pk_fma_f32 v[182:183], v[158:159], v[114:115], v[182:183]
	global_load_dword v108, v184, s[20:21]
	s_add_u32 s20, s20, 0x2000
	s_addc_u32 s21, s21, 0
	global_load_dword v109, v184, s[20:21]
	s_add_u32 s20, s20, 0x2000
	s_addc_u32 s21, s21, 0
	global_load_dword v110, v184, s[20:21]
	s_add_u32 s20, s20, 0x2000
	s_addc_u32 s21, s21, 0
	global_load_dword v111, v184, s[20:21]
	s_add_u32 s20, s20, 0x2000
	s_addc_u32 s21, s21, 0
	global_load_dword v112, v184, s[20:21]
	s_add_u32 s20, s20, 0x2000
	s_addc_u32 s21, s21, 0
	global_load_dword v113, v184, s[20:21]
	s_add_u32 s20, s20, 0x2000
	s_addc_u32 s21, s21, 0
	global_load_dword v114, v184, s[20:21]
	s_add_u32 s20, s20, 0x2000
	s_addc_u32 s21, s21, 0
	global_load_dword v115, v184, s[20:21]
	s_add_u32 s20, s20, 0x2000
	s_addc_u32 s21, s21, 0
	ds_read_b128 v[64:67], v185 offset:64
	ds_read_b128 v[72:75], v185 offset:1088
	ds_read_b128 v[80:83], v185 offset:2112
	ds_read_b128 v[88:91], v185 offset:3136
	ds_read_b128 v[96:99], v185 offset:4160
	ds_read_b128 v[136:139], v185 offset:5184
	ds_read_b128 v[144:147], v185 offset:6208
	ds_read_b128 v[152:155], v185 offset:7232
	ds_read_b128 v[68:71], v185 offset:80
	ds_read_b128 v[76:79], v185 offset:1104
	ds_read_b128 v[84:87], v185 offset:2128
	ds_read_b128 v[92:95], v185 offset:3152
	ds_read_b128 v[132:135], v185 offset:4176
	ds_read_b128 v[140:143], v185 offset:5200
	ds_read_b128 v[148:151], v185 offset:6224
	ds_read_b128 v[156:159], v185 offset:7248
	s_waitcnt vmcnt(24)
	s_waitcnt lgkmcnt(8)
	v_pk_fma_f32 v[168:169], v[64:65], v[116:117], v[168:169]
	v_pk_fma_f32 v[170:171], v[72:73], v[116:117], v[170:171]
	v_pk_fma_f32 v[172:173], v[80:81], v[116:117], v[172:173]
	v_pk_fma_f32 v[174:175], v[88:89], v[116:117], v[174:175]
	v_pk_fma_f32 v[176:177], v[96:97], v[116:117], v[176:177]
	v_pk_fma_f32 v[178:179], v[136:137], v[116:117], v[178:179]
	v_pk_fma_f32 v[180:181], v[144:145], v[116:117], v[180:181]
	v_pk_fma_f32 v[182:183], v[152:153], v[116:117], v[182:183]
	v_pk_fma_f32 v[168:169], v[66:67], v[118:119], v[168:169]
	v_pk_fma_f32 v[170:171], v[74:75], v[118:119], v[170:171]
	v_pk_fma_f32 v[172:173], v[82:83], v[118:119], v[172:173]
	v_pk_fma_f32 v[174:175], v[90:91], v[118:119], v[174:175]
	v_pk_fma_f32 v[176:177], v[98:99], v[118:119], v[176:177]
	v_pk_fma_f32 v[178:179], v[138:139], v[118:119], v[178:179]
	v_pk_fma_f32 v[180:181], v[146:147], v[118:119], v[180:181]
	v_pk_fma_f32 v[182:183], v[154:155], v[118:119], v[182:183]
	s_waitcnt lgkmcnt(0)
; __device__ __forceinline__ unsigned cvt_pk_bf16(float lo, float hi) { f32x2_t f = {lo, hi}; bf16x2_t v = __builtin_convertvector(f, bf16x2_t); return __builtin_bit_cast(unsigned, v); }
; __device__ NOINL void prep_weff(const float* pw, const float* ps, const float* wb, bf16_t* dst, LAS unsigned char* lds, int wv) {
;     ...
;         for (int d = 0; d < 256; ++d) { const float w = wp[(size_t)d * 2048];
; #pragma unroll
;             for (int cc = 0; cc < 8; ++cc) acc[cc] += wl[cc * 256 + d] * w; }
;         u32x4 w; w.x = cvt_pk_bf16(acc[0], acc[1]); w.y = cvt_pk_bf16(acc[2], acc[3]); w.z = cvt_pk_bf16(acc[4], acc[5]); w.w = cvt_pk_bf16(acc[6], acc[7]);
;         *(u32x4*)(dst + (size_t)n * 1024 + g * 256 + c8 * 8) = w;
	v_pk_fma_f32 v[168:169], v[68:69], v[120:121], v[168:169]
	v_pk_fma_f32 v[170:171], v[76:77], v[120:121], v[170:171]
	v_pk_fma_f32 v[172:173], v[84:85], v[120:121], v[172:173]
	v_pk_fma_f32 v[174:175], v[92:93], v[120:121], v[174:175]
	v_pk_fma_f32 v[176:177], v[132:133], v[120:121], v[176:177]
	v_pk_fma_f32 v[178:179], v[140:141], v[120:121], v[178:179]
	v_pk_fma_f32 v[180:181], v[148:149], v[120:121], v[180:181]
	v_pk_fma_f32 v[182:183], v[156:157], v[120:121], v[182:183]
	v_pk_fma_f32 v[168:169], v[70:71], v[122:123], v[168:169]
	v_pk_fma_f32 v[170:171], v[78:79], v[122:123], v[170:171]
	v_pk_fma_f32 v[172:173], v[86:87], v[122:123], v[172:173]
	v_pk_fma_f32 v[174:175], v[94:95], v[122:123], v[174:175]
	v_pk_fma_f32 v[176:177], v[134:135], v[122:123], v[176:177]
	v_pk_fma_f32 v[178:179], v[142:143], v[122:123], v[178:179]
	v_pk_fma_f32 v[180:181], v[150:151], v[122:123], v[180:181]
	v_pk_fma_f32 v[182:183], v[158:159], v[122:123], v[182:183]
	global_load_dword v116, v184, s[20:21]
	s_add_u32 s20, s20, 0x2000
	s_addc_u32 s21, s21, 0
	global_load_dword v117, v184, s[20:21]
	s_add_u32 s20, s20, 0x2000
	s_addc_u32 s21, s21, 0
	global_load_dword v118, v184, s[20:21]
	s_add_u32 s20, s20, 0x2000
	s_addc_u32 s21, s21, 0
	global_load_dword v119, v184, s[20:21]
	s_add_u32 s20, s20, 0x2000
	s_addc_u32 s21, s21, 0
	global_load_dword v120, v184, s[20:21]
	s_add_u32 s20, s20, 0x2000
	s_addc_u32 s21, s21, 0
	global_load_dword v121, v184, s[20:21]
	s_add_u32 s20, s20, 0x2000
	s_addc_u32 s21, s21, 0
	global_load_dword v122, v184, s[20:21]
	s_add_u32 s20, s20, 0x2000
	s_addc_u32 s21, s21, 0
	global_load_dword v123, v184, s[20:21]
	s_add_u32 s20, s20, 0x2000
	s_addc_u32 s21, s21, 0
	ds_read_b128 v[64:67], v185 offset:96
	ds_read_b128 v[72:75], v185 offset:1120
	ds_read_b128 v[80:83], v185 offset:2144
	ds_read_b128 v[88:91], v185 offset:3168
	ds_read_b128 v[96:99], v185 offset:4192
	ds_read_b128 v[136:139], v185 offset:5216
	ds_read_b128 v[144:147], v185 offset:6240
	ds_read_b128 v[152:155], v185 offset:7264
	ds_read_b128 v[68:71], v185 offset:112
	ds_read_b128 v[76:79], v185 offset:1136
	ds_read_b128 v[84:87], v185 offset:2160
	ds_read_b128 v[92:95], v185 offset:3184
	ds_read_b128 v[132:135], v185 offset:4208
	ds_read_b128 v[140:143], v185 offset:5232
	ds_read_b128 v[148:151], v185 offset:6256
	ds_read_b128 v[156:159], v185 offset:7280
	s_waitcnt vmcnt(24)
	s_waitcnt lgkmcnt(8)
	v_pk_fma_f32 v[168:169], v[64:65], v[124:125], v[168:169]
	v_pk_fma_f32 v[170:171], v[72:73], v[124:125], v[170:171]
	v_pk_fma_f32 v[172:173], v[80:81], v[124:125], v[172:173]
	v_pk_fma_f32 v[174:175], v[88:89], v[124:125], v[174:175]
	v_pk_fma_f32 v[176:177], v[96:97], v[124:125], v[176:177]
	v_pk_fma_f32 v[178:179], v[136:137], v[124:125], v[178:179]
	v_pk_fma_f32 v[180:181], v[144:145], v[124:125], v[180:181]
	v_pk_fma_f32 v[182:183], v[152:153], v[124:125], v[182:183]
	v_pk_fma_f32 v[168:169], v[66:67], v[126:127], v[168:169]
	v_pk_fma_f32 v[170:171], v[74:75], v[126:127], v[170:171]
	v_pk_fma_f32 v[172:173], v[82:83], v[126:127], v[172:173]
	v_pk_fma_f32 v[174:175], v[90:91], v[126:127], v[174:175]
	v_pk_fma_f32 v[176:177], v[98:99], v[126:127], v[176:177]
	v_pk_fma_f32 v[178:179], v[138:139], v[126:127], v[178:179]
	v_pk_fma_f32 v[180:181], v[146:147], v[126:127], v[180:181]
	v_pk_fma_f32 v[182:183], v[154:155], v[126:127], v[182:183]
	s_waitcnt lgkmcnt(0)
	v_pk_fma_f32 v[168:169], v[68:69], v[128:129], v[168:169]
	v_pk_fma_f32 v[170:171], v[76:77], v[128:129], v[170:171]
	v_pk_fma_f32 v[172:173], v[84:85], v[128:129], v[172:173]
	v_pk_fma_f32 v[174:175], v[92:93], v[128:129], v[174:175]
	v_pk_fma_f32 v[176:177], v[132:133], v[128:129], v[176:177]
	v_pk_fma_f32 v[178:179], v[140:141], v[128:129], v[178:179]
	v_pk_fma_f32 v[180:181], v[148:149], v[128:129], v[180:181]
	v_pk_fma_f32 v[182:183], v[156:157], v[128:129], v[182:183]
	v_pk_fma_f32 v[168:169], v[70:71], v[130:131], v[168:169]
	v_pk_fma_f32 v[170:171], v[78:79], v[130:131], v[170:171]
	v_pk_fma_f32 v[172:173], v[86:87], v[130:131], v[172:173]
	v_pk_fma_f32 v[174:175], v[94:95], v[130:131], v[174:175]
	v_pk_fma_f32 v[176:177], v[134:135], v[130:131], v[176:177]
	v_pk_fma_f32 v[178:179], v[142:143], v[130:131], v[178:179]
	v_pk_fma_f32 v[180:181], v[150:151], v[130:131], v[180:181]
	v_pk_fma_f32 v[182:183], v[158:159], v[130:131], v[182:183]
	v_add_u32_e32 v185, 0x80, v185
	s_add_i32 s18, s18, 1
	s_cmp_eq_u32 s18, 8
	s_cbranch_scc0 .Lweff1_loop
	s_waitcnt vmcnt(0)
	v_add_f32_e32 v18, v168, v169
	v_add_f32_e32 v19, v170, v171
	v_add_f32_e32 v20, v172, v173
	v_add_f32_e32 v21, v174, v175
	v_add_f32_e32 v24, v176, v177
	v_add_f32_e32 v25, v178, v179
	v_add_f32_e32 v16, v180, v181
	v_add_f32_e32 v17, v182, v183
	v_lshlrev_b64 v[14:15], 11, v[14:15]
	v_lshl_add_u64 v[14:15], s[6:7], 0, v[14:15]
	v_lshl_add_u64 v[14:15], s[10:11], 1, v[14:15]
	s_lshl_b32 s8, s8, 1
	v_cvt_pk_bf16_f32 v18, v18, v19
	v_cvt_pk_bf16_f32 v19, v20, v21
	v_cvt_pk_bf16_f32 v20, v24, v25
	v_cvt_pk_bf16_f32 v21, v16, v17
	v_lshl_add_u64 v[14:15], v[14:15], 0, s[8:9]
	s_mov_b32 s8, s58
	global_store_dwordx4 v[14:15], v[18:21], off
	s_add_i32 s14, s8, s14
	s_cmpk_gt_i32 s14, 0x1ff
	s_cbranch_scc0 .LBB0_153

; template <bool DO_LN, bool DO_H, bool DO_GATES, bool WRITE_X> ...
;     ...
;         const float* mb = modl + (size_t)(row0 >> 11) * 12288 + lane * 4;
;         f32x4 PA[8], PB[8];
; #pragma unroll
;         for (int i = 0; i < 8; ++i) {
;             f32x4 g4 = {1.f, 1.f, 1.f, 1.f}, b4 = {0.f, 0.f, 0.f, 0.f};
;             if (DO_LN) { g4 = *(const f32x4*)(lng + lane * 4 + i * 256); b4 = *(const f32x4*)(lnb + lane * 4 + i * 256); }
;             if (DO_H) { const f32x4 sc = *(const f32x4*)(mb + sc_idx * 2048 + i * 256) + 1.0f, sh = *(const f32x4*)(mb + sh_idx * 2048 + i * 256);
;                 PA[i] = g4 * sc; PB[i] = b4 * sc + sh; }
;             else { PA[i] = g4; PB[i] = b4; }
;         }
;         f32x4 nv[8];
; #pragma unroll
;         for (int i = 0; i < 8; ++i) nv[i] = __builtin_nontemporal_load((const f32x4*)(src + (size_t)row0 * DM + lane * 4 + i * 256));
.LBB0_171:
	v_ashrrev_i32_e32 v0, 7, v69
	v_mad_i64_i32 v[32:33], s[2:3], v0, s16, v[64:65]
	v_add_co_u32_e32 v28, vcc, 0x2000, v32
	v_add_co_u32_e64 v12, s[2:3], s17, v32
	s_nop 0
	v_addc_co_u32_e32 v29, vcc, 0, v33, vcc
	v_add_co_u32_e32 v34, vcc, s18, v32
	v_lshlrev_b32_e32 v72, 4, v69
	v_addc_co_u32_e64 v13, s[2:3], 0, v33, s[2:3]
	v_addc_co_u32_e32 v35, vcc, 0, v33, vcc
	v_ashrrev_i32_e32 v73, 31, v72
	global_load_dwordx4 v[0:3], v[12:13], off
	global_load_dwordx4 v[4:7], v[12:13], off offset:1024
	global_load_dwordx4 v[8:11], v[12:13], off offset:2048
	s_nop 0
	global_load_dwordx4 v[12:15], v[12:13], off offset:3072
	s_nop 0
	global_load_dwordx4 v[16:19], v[28:29], off
	global_load_dwordx4 v[20:23], v[28:29], off offset:1024
	global_load_dwordx4 v[24:27], v[28:29], off offset:2048
	s_nop 0
	global_load_dwordx4 v[28:31], v[28:29], off offset:3072
	s_nop 0
	global_load_dwordx4 v[108:111], v[34:35], off
	global_load_dwordx4 v[124:127], v[32:33], off
	global_load_dwordx4 v[128:131], v[32:33], off offset:1024
	global_load_dwordx4 v[112:115], v[34:35], off offset:1024
	global_load_dwordx4 v[116:119], v[34:35], off offset:2048
	global_load_dwordx4 v[132:135], v[32:33], off offset:2048
	global_load_dwordx4 v[146:149], v[32:33], off offset:3072
	global_load_dwordx4 v[120:123], v[34:35], off offset:3072
	v_lshlrev_b64 v[32:33], 13, v[72:73]
	v_lshl_add_u64 v[32:33], v[66:67], 0, v[32:33]
	global_load_dwordx4 v[60:63], v[32:33], off nt
	global_load_dwordx4 v[56:59], v[32:33], off offset:1024 nt
	global_load_dwordx4 v[52:55], v[32:33], off offset:2048 nt
	global_load_dwordx4 v[48:51], v[32:33], off offset:3072 nt
	v_add_co_u32_e32 v32, vcc, s18, v32
	v_or_b32_e32 v145, 1, v72
	s_nop 0
	v_addc_co_u32_e32 v33, vcc, 0, v33, vcc
	global_load_dwordx4 v[44:47], v[32:33], off nt
	global_load_dwordx4 v[40:43], v[32:33], off offset:1024 nt
	global_load_dwordx4 v[36:39], v[32:33], off offset:2048 nt
	s_nop 0
	global_load_dwordx4 v[32:35], v[32:33], off offset:3072 nt
	v_lshlrev_b64 v[70:71], 5, v[72:73]
	v_lshlrev_b64 v[72:73], 12, v[72:73]
	s_mov_b32 s21, 0
	v_or_b32_e32 v72, v68, v72
	s_waitcnt vmcnt(0) lgkmcnt(0)
	v_pk_add_f32 v[86:87], v[14:15], 1.0 op_sel_hi:[1,0]
	v_pk_add_f32 v[74:75], v[2:3], 1.0 op_sel_hi:[1,0]
	v_pk_add_f32 v[76:77], v[0:1], 1.0 op_sel_hi:[1,0]
	v_pk_add_f32 v[78:79], v[6:7], 1.0 op_sel_hi:[1,0]
	v_pk_add_f32 v[80:81], v[4:5], 1.0 op_sel_hi:[1,0]
	v_pk_add_f32 v[82:83], v[10:11], 1.0 op_sel_hi:[1,0]
	v_pk_add_f32 v[84:85], v[8:9], 1.0 op_sel_hi:[1,0]
	v_pk_add_f32 v[88:89], v[12:13], 1.0 op_sel_hi:[1,0]
	v_pk_add_f32 v[90:91], v[18:19], 1.0 op_sel_hi:[1,0]
	v_pk_add_f32 v[92:93], v[16:17], 1.0 op_sel_hi:[1,0]
	v_pk_add_f32 v[94:95], v[22:23], 1.0 op_sel_hi:[1,0]
	v_pk_add_f32 v[96:97], v[20:21], 1.0 op_sel_hi:[1,0]
	v_pk_add_f32 v[98:99], v[26:27], 1.0 op_sel_hi:[1,0]
	v_pk_add_f32 v[100:101], v[24:25], 1.0 op_sel_hi:[1,0]
	v_pk_add_f32 v[102:103], v[30:31], 1.0 op_sel_hi:[1,0]
	v_pk_add_f32 v[104:105], v[28:29], 1.0 op_sel_hi:[1,0]
	v_mov_b64_e32 v[0:1], v[60:61]
	v_mov_b64_e32 v[4:5], v[56:57]
	v_mov_b64_e32 v[8:9], v[52:53]
	v_mov_b64_e32 v[12:13], v[48:49]
	v_mov_b64_e32 v[16:17], v[44:45]
	v_mov_b64_e32 v[20:21], v[40:41]
	v_mov_b64_e32 v[24:25], v[36:37]
	v_mov_b64_e32 v[28:29], v[32:33]
	v_pk_fma_f32 v[106:107], v[74:75], 0, v[110:111] op_sel_hi:[1,0,1]
	v_pk_fma_f32 v[108:109], v[76:77], 0, v[108:109] op_sel_hi:[1,0,1]
	v_pk_fma_f32 v[110:111], v[78:79], 0, v[114:115] op_sel_hi:[1,0,1]
	v_pk_fma_f32 v[112:113], v[80:81], 0, v[112:113] op_sel_hi:[1,0,1]
	v_pk_fma_f32 v[114:115], v[82:83], 0, v[118:119] op_sel_hi:[1,0,1]
	v_pk_fma_f32 v[116:117], v[84:85], 0, v[116:117] op_sel_hi:[1,0,1]
	v_pk_fma_f32 v[118:119], v[86:87], 0, v[122:123] op_sel_hi:[1,0,1]
	v_pk_fma_f32 v[120:121], v[88:89], 0, v[120:121] op_sel_hi:[1,0,1]
	v_pk_fma_f32 v[122:123], v[90:91], 0, v[126:127] op_sel_hi:[1,0,1]
	v_pk_fma_f32 v[124:125], v[92:93], 0, v[124:125] op_sel_hi:[1,0,1]
	v_pk_fma_f32 v[126:127], v[94:95], 0, v[130:131] op_sel_hi:[1,0,1]
	v_pk_fma_f32 v[128:129], v[96:97], 0, v[128:129] op_sel_hi:[1,0,1]
	v_pk_fma_f32 v[130:131], v[98:99], 0, v[134:135] op_sel_hi:[1,0,1]
	v_pk_fma_f32 v[132:133], v[100:101], 0, v[132:133] op_sel_hi:[1,0,1]
	v_pk_fma_f32 v[134:135], v[102:103], 0, v[148:149] op_sel_hi:[1,0,1]
	v_pk_fma_f32 v[136:137], v[104:105], 0, v[146:147] op_sel_hi:[1,0,1]
	v_mov_b64_e32 v[2:3], v[62:63]
	v_mov_b64_e32 v[6:7], v[58:59]
	v_mov_b64_e32 v[10:11], v[54:55]
	v_mov_b64_e32 v[14:15], v[50:51]
	v_mov_b64_e32 v[18:19], v[46:47]
	v_mov_b64_e32 v[22:23], v[42:43]
	v_mov_b64_e32 v[26:27], v[38:39]
	v_mov_b64_e32 v[30:31], v[34:35]
	s_branch .LBB0_173

; #define LAS __attribute__((address_space(3)))
; __device__ __forceinline__ unsigned cvt_pk_bf16(float lo, float hi) { f32x2_t f = {lo, hi}; bf16x2_t v = __builtin_convertvector(f, bf16x2_t); return __builtin_bit_cast(unsigned, v); }
; template <bool DO_LN, bool DO_H, bool DO_GATES, bool WRITE_X> ...
;     ...
;         for (int rr = 0; rr < 16; ++rr) {
;             const int row = row0 + rr;
;             f32x4 v[8];
; #pragma unroll
;             for (int i = 0; i < 8; ++i) v[i] = nv[i];
;             if (rr + 1 < 16) {
; #pragma unroll
;                 for (int i = 0; i < 8; ++i) nv[i] = __builtin_nontemporal_load((const f32x4*)(src + (size_t)(row + 1) * DM + lane * 4 + i * 256)); }
;             if (DO_LN) {
;                 float s = 0.f;
; #pragma unroll
;                 for (int i = 0; i < 8; ++i) s += (v[i][0] + v[i][1]) + (v[i][2] + v[i][3]);
;                 const float mu = wave_sum(s, lane) * (1.0f / DM);
;                 float q = 0.f;
; #pragma unroll
;                 for (int i = 0; i < 8; ++i) { const f32x4 d = v[i] - mu; q += (d[0] * d[0] + d[1] * d[1]) + (d[2] * d[2] + d[3] * d[3]); }
;                 const float rstd = 1.0f / sqrtf(wave_sum(q, lane) * (1.0f / DM) + LN_EPS);
; #pragma unroll
;                 for (int i = 0; i < 8; ++i) v[i] = (v[i] - mu) * rstd;
;                 if (!WRITE_X && lane == 0) { float* st = (float*)(ws + WS_STATS) + (size_t)row * 2; st[0] = mu; st[1] = rstd; }
;             }
;             if (WRITE_X && !DO_H) {
; #pragma unroll
;                 for (int i = 0; i < 8; ++i) __builtin_nontemporal_store(v[i] * PA[i] + PB[i], (f32x4*)(xout + (size_t)row * DM + lane * 4 + i * 256));
;             }
;             if (DO_H) {
;                 float ga[8];
; #pragma unroll
;                 for (int gg = 0; gg < 8; ++gg) ga[gg] = 0.f;
; #pragma unroll
;                 for (int i = 0; i < 8; ++i) { const f32x4 h = v[i] * PA[i] + PB[i];
;                     u32x2 w; w.x = cvt_pk_bf16(h[0], h[1]); w.y = cvt_pk_bf16(h[2], h[3]);
;                     *(u32x2*)(H + (size_t)row * DM + lane * 4 + i * 256) = w;
;                     if (DO_GATES) {
; #pragma unroll
;                         for (int gg = 0; gg < 8; ++gg) { const f32x4 w4 = *(const LAS f32x4*)(wif + gg * 2048 + lane * 4 + i * 256); ga[gg] += (h[0] * w4[0] + h[1] * w4[1]) + (h[2] * w4[2] + h[3] * w4[3]); }
.LBB0_173:
	s_cmp_eq_u32 s21, 15
	s_cbranch_scc1 .LBB0_175
	v_add_u32_e32 v0, s21, v145
	v_ashrrev_i32_e32 v1, 31, v0
	v_lshlrev_b64 v[0:1], 13, v[0:1]
	v_lshl_add_u64 v[16:17], v[66:67], 0, v[0:1]
	v_add_co_u32_e32 v28, vcc, 0x1000, v16
	global_load_dwordx4 v[0:3], v[16:17], off nt
	global_load_dwordx4 v[4:7], v[16:17], off offset:1024 nt
	global_load_dwordx4 v[8:11], v[16:17], off offset:2048 nt
	global_load_dwordx4 v[12:15], v[16:17], off offset:3072 nt
	v_addc_co_u32_e32 v29, vcc, 0, v17, vcc
	global_load_dwordx4 v[16:19], v[28:29], off nt
	global_load_dwordx4 v[20:23], v[28:29], off offset:1024 nt
	global_load_dwordx4 v[24:27], v[28:29], off offset:2048 nt
	s_nop 0
	global_load_dwordx4 v[28:31], v[28:29], off offset:3072 nt
.LBB0_175:
	v_lshl_add_u64 v[146:147], s[4:5], 0, v[72:73]
	v_pk_fma_f32 v[62:63], v[90:91], v[62:63], v[122:123]
	v_pk_fma_f32 v[154:155], v[92:93], v[60:61], v[124:125]
	v_add_co_u32_e32 v60, vcc, s19, v146
	v_cvt_pk_bf16_f32 v148, v154, v155
	v_cvt_pk_bf16_f32 v149, v62, v63
	v_addc_co_u32_e32 v61, vcc, 0, v147, vcc
	global_store_dwordx2 v[60:61], v[148:149], off
	ds_read_b128 v[146:149], v138
	ds_read_b128 v[150:153], v138 offset:8192
	s_waitcnt lgkmcnt(0)
	v_mul_f32_e32 v147, v155, v147
	v_fmac_f32_e32 v147, v154, v146
	v_mul_f32_e32 v146, v63, v149
	v_fmac_f32_e32 v146, v62, v148
	v_add_f32_e32 v146, v147, v146
	v_add_f32_e32 v156, 0, v146
	v_mul_f32_e32 v151, v155, v151
	ds_read_b128 v[146:149], v138 offset:16384
	v_fmac_f32_e32 v151, v154, v150
	v_mul_f32_e32 v150, v63, v153
	v_fmac_f32_e32 v150, v62, v152
	v_add_f32_e32 v150, v151, v150
	v_add_f32_e32 v157, 0, v150
	ds_read_b128 v[150:153], v138 offset:24576
	s_waitcnt lgkmcnt(0)
	v_mul_f32_e32 v147, v155, v147
	v_fmac_f32_e32 v147, v154, v146
	v_mul_f32_e32 v146, v63, v149
	v_fmac_f32_e32 v146, v62, v148
	v_add_f32_e32 v146, v147, v146
	v_add_f32_e32 v158, 0, v146
	v_mul_f32_e32 v151, v155, v151
	ds_read_b128 v[146:149], v138 offset:32768
	v_fmac_f32_e32 v151, v154, v150
	v_mul_f32_e32 v150, v63, v153
	v_fmac_f32_e32 v150, v62, v152
	v_add_f32_e32 v150, v151, v150
	v_add_f32_e32 v159, 0, v150
	ds_read_b128 v[150:153], v138 offset:40960
	s_waitcnt lgkmcnt(0)
	v_mul_f32_e32 v147, v155, v147
	v_fmac_f32_e32 v147, v154, v146
	v_mul_f32_e32 v146, v63, v149
	v_fmac_f32_e32 v146, v62, v148
	v_add_f32_e32 v146, v147, v146
	v_add_f32_e32 v160, 0, v146
	v_mul_f32_e32 v151, v155, v151
	ds_read_b128 v[146:149], v138 offset:49152
	v_fmac_f32_e32 v151, v154, v150
	v_mul_f32_e32 v150, v63, v153
	v_fmac_f32_e32 v150, v62, v152
	v_add_f32_e32 v150, v151, v150
	v_add_f32_e32 v161, 0, v150
	ds_read_b128 v[150:153], v138 offset:57344
	s_waitcnt lgkmcnt(0)
	v_mul_f32_e32 v147, v155, v147
	v_fmac_f32_e32 v147, v154, v146
	v_mul_f32_e32 v146, v63, v149
	v_fmac_f32_e32 v146, v62, v148
	v_add_f32_e32 v146, v147, v146
	v_add_f32_e32 v162, 0, v146
	v_mul_f32_e32 v146, v155, v151
	v_fmac_f32_e32 v146, v154, v150
	v_pk_fma_f32 v[150:151], v[94:95], v[58:59], v[126:127]
	v_pk_fma_f32 v[154:155], v[96:97], v[56:57], v[128:129]
	v_cvt_pk_bf16_f32 v57, v150, v151
	v_cvt_pk_bf16_f32 v56, v154, v155
	global_store_dwordx2 v[60:61], v[56:57], off offset:512
	ds_read_b128 v[56:59], v138 offset:1024
	v_mul_f32_e32 v63, v63, v153
	v_fmac_f32_e32 v63, v62, v152
	v_add_f32_e32 v62, v146, v63
	ds_read_b128 v[146:149], v138 offset:9216
	s_waitcnt lgkmcnt(0)
	v_mul_f32_e32 v57, v155, v57
	v_fmac_f32_e32 v57, v154, v56
	v_mul_f32_e32 v56, v151, v59
	v_fmac_f32_e32 v56, v150, v58
	v_add_f32_e32 v56, v57, v56
	v_add_f32_e32 v153, v156, v56
	ds_read_b128 v[56:59], v138 offset:17408
	v_add_f32_e32 v152, 0, v62
	v_mul_f32_e32 v62, v155, v147
	v_mul_f32_e32 v63, v151, v149
	v_fmac_f32_e32 v62, v154, v146
	v_fmac_f32_e32 v63, v150, v148
	ds_read_b128 v[146:149], v138 offset:25600
	s_waitcnt lgkmcnt(0)
	v_mul_f32_e32 v57, v155, v57
	v_fmac_f32_e32 v57, v154, v56
	v_mul_f32_e32 v56, v151, v59
	v_fmac_f32_e32 v56, v150, v58
	v_add_f32_e32 v62, v62, v63
	v_add_f32_e32 v56, v57, v56
	v_add_f32_e32 v156, v157, v62
	v_add_f32_e32 v157, v158, v56
	ds_read_b128 v[56:59], v138 offset:33792
	v_mul_f32_e32 v62, v155, v147
	v_mul_f32_e32 v63, v151, v149
	v_fmac_f32_e32 v62, v154, v146
	v_fmac_f32_e32 v63, v150, v148
	ds_read_b128 v[146:149], v138 offset:41984
	s_waitcnt lgkmcnt(0)
	v_mul_f32_e32 v57, v155, v57
	v_fmac_f32_e32 v57, v154, v56
	v_mul_f32_e32 v56, v151, v59
	v_fmac_f32_e32 v56, v150, v58
	v_add_f32_e32 v62, v62, v63
	v_add_f32_e32 v56, v57, v56
	v_add_f32_e32 v158, v159, v62
	v_add_f32_e32 v159, v160, v56
	ds_read_b128 v[56:59], v138 offset:50176
	v_mul_f32_e32 v62, v155, v147
	v_mul_f32_e32 v63, v151, v149
	v_fmac_f32_e32 v62, v154, v146
	v_fmac_f32_e32 v63, v150, v148
	ds_read_b128 v[146:149], v138 offset:58368
	s_waitcnt lgkmcnt(0)
	v_mul_f32_e32 v57, v155, v57
	v_fmac_f32_e32 v57, v154, v56
	v_mul_f32_e32 v56, v151, v59
	v_fmac_f32_e32 v56, v150, v58
	v_add_f32_e32 v62, v62, v63
	v_add_f32_e32 v56, v57, v56
	v_add_f32_e32 v160, v161, v62
	v_add_f32_e32 v161, v162, v56
	v_mul_f32_e32 v56, v155, v147
	v_fmac_f32_e32 v56, v154, v146
	v_pk_fma_f32 v[62:63], v[98:99], v[54:55], v[130:131]
	v_pk_fma_f32 v[146:147], v[100:101], v[52:53], v[132:133]
	v_cvt_pk_bf16_f32 v53, v62, v63
	v_cvt_pk_bf16_f32 v52, v146, v147
	global_store_dwordx2 v[60:61], v[52:53], off offset:1024
	ds_read_b128 v[52:55], v138 offset:2048
	v_mul_f32_e32 v57, v151, v149
	v_fmac_f32_e32 v57, v150, v148
	v_add_f32_e32 v56, v56, v57
	v_add_f32_e32 v148, v152, v56
	ds_read_b128 v[56:59], v138 offset:10240
	s_waitcnt lgkmcnt(0)
; #define LAS __attribute__((address_space(3)))
; __device__ __forceinline__ unsigned cvt_pk_bf16(float lo, float hi) { f32x2_t f = {lo, hi}; bf16x2_t v = __builtin_convertvector(f, bf16x2_t); return __builtin_bit_cast(unsigned, v); }
; template <bool DO_LN, bool DO_H, bool DO_GATES, bool WRITE_X> ...
;     ...
;                 for (int i = 0; i < 8; ++i) { const f32x4 h = v[i] * PA[i] + PB[i];
;                     u32x2 w; w.x = cvt_pk_bf16(h[0], h[1]); w.y = cvt_pk_bf16(h[2], h[3]);
;                     *(u32x2*)(H + (size_t)row * DM + lane * 4 + i * 256) = w;
;                     if (DO_GATES) {
; #pragma unroll
;                         for (int gg = 0; gg < 8; ++gg) { const f32x4 w4 = *(const LAS f32x4*)(wif + gg * 2048 + lane * 4 + i * 256); ga[gg] += (h[0] * w4[0] + h[1] * w4[1]) + (h[2] * w4[2] + h[3] * w4[3]); }
	v_mul_f32_e32 v53, v147, v53
	v_fmac_f32_e32 v53, v146, v52
	v_mul_f32_e32 v52, v63, v55
	v_fmac_f32_e32 v52, v62, v54
	v_add_f32_e32 v52, v53, v52
	v_add_f32_e32 v149, v153, v52
	v_mul_f32_e32 v57, v147, v57
	ds_read_b128 v[52:55], v138 offset:18432
	v_fmac_f32_e32 v57, v146, v56
	v_mul_f32_e32 v56, v63, v59
	v_fmac_f32_e32 v56, v62, v58
	v_add_f32_e32 v56, v57, v56
	v_add_f32_e32 v150, v156, v56
	ds_read_b128 v[56:59], v138 offset:26624
	s_waitcnt lgkmcnt(0)
	v_mul_f32_e32 v53, v147, v53
	v_fmac_f32_e32 v53, v146, v52
	v_mul_f32_e32 v52, v63, v55
	v_fmac_f32_e32 v52, v62, v54
	v_add_f32_e32 v52, v53, v52
	v_add_f32_e32 v151, v157, v52
	v_mul_f32_e32 v57, v147, v57
	ds_read_b128 v[52:55], v138 offset:34816
	v_fmac_f32_e32 v57, v146, v56
	v_mul_f32_e32 v56, v63, v59
	v_fmac_f32_e32 v56, v62, v58
	v_add_f32_e32 v56, v57, v56
	v_add_f32_e32 v152, v158, v56
	ds_read_b128 v[56:59], v138 offset:43008
	s_waitcnt lgkmcnt(0)
	v_mul_f32_e32 v53, v147, v53
	v_fmac_f32_e32 v53, v146, v52
	v_mul_f32_e32 v52, v63, v55
	v_fmac_f32_e32 v52, v62, v54
	v_add_f32_e32 v52, v53, v52
	v_add_f32_e32 v153, v159, v52
	v_mul_f32_e32 v57, v147, v57
	ds_read_b128 v[52:55], v138 offset:51200
	v_fmac_f32_e32 v57, v146, v56
	v_mul_f32_e32 v56, v63, v59
	v_fmac_f32_e32 v56, v62, v58
	v_add_f32_e32 v56, v57, v56
	v_add_f32_e32 v154, v160, v56
	ds_read_b128 v[56:59], v138 offset:59392
	s_waitcnt lgkmcnt(0)
	v_mul_f32_e32 v53, v147, v53
	v_fmac_f32_e32 v53, v146, v52
	v_mul_f32_e32 v52, v63, v55
	v_fmac_f32_e32 v52, v62, v54
	v_add_f32_e32 v52, v53, v52
	v_add_f32_e32 v155, v161, v52
	v_mul_f32_e32 v52, v147, v57
	v_fmac_f32_e32 v52, v146, v56
	v_pk_fma_f32 v[56:57], v[102:103], v[50:51], v[134:135]
	v_pk_fma_f32 v[146:147], v[104:105], v[48:49], v[136:137]
	v_cvt_pk_bf16_f32 v49, v56, v57
	v_cvt_pk_bf16_f32 v48, v146, v147
	global_store_dwordx2 v[60:61], v[48:49], off offset:1536
	ds_read_b128 v[48:51], v138 offset:3072
	v_mul_f32_e32 v53, v63, v59
	v_fmac_f32_e32 v53, v62, v58
	v_add_f32_e32 v52, v52, v53
	v_add_f32_e32 v62, v148, v52
	ds_read_b128 v[52:55], v138 offset:11264
	s_waitcnt lgkmcnt(0)
	v_mul_f32_e32 v49, v147, v49
	v_fmac_f32_e32 v49, v146, v48
	v_mul_f32_e32 v48, v57, v51
	v_fmac_f32_e32 v48, v56, v50
	v_add_f32_e32 v48, v49, v48
	v_add_f32_e32 v63, v149, v48
	v_mul_f32_e32 v53, v147, v53
	ds_read_b128 v[48:51], v138 offset:19456
	v_fmac_f32_e32 v53, v146, v52
	v_mul_f32_e32 v52, v57, v55
	v_fmac_f32_e32 v52, v56, v54
	v_add_f32_e32 v52, v53, v52
	v_add_f32_e32 v148, v150, v52
	ds_read_b128 v[52:55], v138 offset:27648
	s_waitcnt lgkmcnt(0)
	v_mul_f32_e32 v49, v147, v49
	v_fmac_f32_e32 v49, v146, v48
	v_mul_f32_e32 v48, v57, v51
	v_fmac_f32_e32 v48, v56, v50
	v_add_f32_e32 v48, v49, v48
	v_add_f32_e32 v149, v151, v48
	v_mul_f32_e32 v53, v147, v53
	ds_read_b128 v[48:51], v138 offset:35840
	v_fmac_f32_e32 v53, v146, v52
	v_mul_f32_e32 v52, v57, v55
	v_fmac_f32_e32 v52, v56, v54
	v_add_f32_e32 v52, v53, v52
	v_add_f32_e32 v150, v152, v52
	ds_read_b128 v[52:55], v138 offset:44032
	s_waitcnt lgkmcnt(0)
	v_mul_f32_e32 v49, v147, v49
	v_fmac_f32_e32 v49, v146, v48
	v_mul_f32_e32 v48, v57, v51
	v_fmac_f32_e32 v48, v56, v50
	v_add_f32_e32 v48, v49, v48
	v_add_f32_e32 v151, v153, v48
	v_mul_f32_e32 v53, v147, v53
	ds_read_b128 v[48:51], v138 offset:52224
	v_fmac_f32_e32 v53, v146, v52
	v_mul_f32_e32 v52, v57, v55
	v_fmac_f32_e32 v52, v56, v54
	v_add_f32_e32 v52, v53, v52
	v_add_f32_e32 v152, v154, v52
	ds_read_b128 v[52:55], v138 offset:60416
	s_waitcnt lgkmcnt(0)
	v_mul_f32_e32 v49, v147, v49
	v_fmac_f32_e32 v49, v146, v48
	v_mul_f32_e32 v48, v57, v51
	v_fmac_f32_e32 v48, v56, v50
	v_add_f32_e32 v48, v49, v48
	v_add_f32_e32 v153, v155, v48
	v_mul_f32_e32 v48, v147, v53
	v_fmac_f32_e32 v48, v146, v52
	v_pk_fma_f32 v[52:53], v[74:75], v[46:47], v[106:107]
	v_pk_fma_f32 v[58:59], v[76:77], v[44:45], v[108:109]
	v_cvt_pk_bf16_f32 v45, v52, v53
	v_cvt_pk_bf16_f32 v44, v58, v59
	global_store_dwordx2 v[60:61], v[44:45], off offset:2048
	ds_read_b128 v[44:47], v138 offset:4096
	v_mul_f32_e32 v49, v57, v55
	v_fmac_f32_e32 v49, v56, v54
	v_add_f32_e32 v48, v48, v49
	v_add_f32_e32 v56, v62, v48
	ds_read_b128 v[48:51], v138 offset:12288
	s_waitcnt lgkmcnt(0)
	v_mul_f32_e32 v45, v59, v45
	v_fmac_f32_e32 v45, v58, v44
	v_mul_f32_e32 v44, v53, v47
	v_fmac_f32_e32 v44, v52, v46
	v_add_f32_e32 v44, v45, v44
	v_add_f32_e32 v57, v63, v44
	v_mul_f32_e32 v49, v59, v49
	ds_read_b128 v[44:47], v138 offset:20480
	v_fmac_f32_e32 v49, v58, v48
	v_mul_f32_e32 v48, v53, v51
	v_fmac_f32_e32 v48, v52, v50
	v_add_f32_e32 v48, v49, v48
	v_add_f32_e32 v62, v148, v48
	ds_read_b128 v[48:51], v138 offset:28672
	s_waitcnt lgkmcnt(0)
	v_mul_f32_e32 v45, v59, v45
	v_fmac_f32_e32 v45, v58, v44
	v_mul_f32_e32 v44, v53, v47
	v_fmac_f32_e32 v44, v52, v46
	v_add_f32_e32 v44, v45, v44
	v_add_f32_e32 v63, v149, v44
	v_mul_f32_e32 v49, v59, v49
	ds_read_b128 v[44:47], v138 offset:36864
	v_fmac_f32_e32 v49, v58, v48
	v_mul_f32_e32 v48, v53, v51
	v_fmac_f32_e32 v48, v52, v50
	v_add_f32_e32 v48, v49, v48
	v_add_f32_e32 v146, v150, v48
	ds_read_b128 v[48:51], v138 offset:45056
	s_waitcnt lgkmcnt(0)
	v_mul_f32_e32 v45, v59, v45
	v_fmac_f32_e32 v45, v58, v44
	v_mul_f32_e32 v44, v53, v47
	v_fmac_f32_e32 v44, v52, v46
	v_add_f32_e32 v44, v45, v44
	v_add_f32_e32 v147, v151, v44
	v_mul_f32_e32 v49, v59, v49
	ds_read_b128 v[44:47], v138 offset:53248
	v_fmac_f32_e32 v49, v58, v48
	v_mul_f32_e32 v48, v53, v51
	v_fmac_f32_e32 v48, v52, v50
	v_add_f32_e32 v48, v49, v48
	v_add_f32_e32 v148, v152, v48
	ds_read_b128 v[48:51], v138 offset:61440
	s_waitcnt lgkmcnt(0)
; #define LAS __attribute__((address_space(3)))
; __device__ __forceinline__ unsigned cvt_pk_bf16(float lo, float hi) { f32x2_t f = {lo, hi}; bf16x2_t v = __builtin_convertvector(f, bf16x2_t); return __builtin_bit_cast(unsigned, v); }
; template <bool DO_LN, bool DO_H, bool DO_GATES, bool WRITE_X> ...
;     ...
;                 for (int i = 0; i < 8; ++i) { const f32x4 h = v[i] * PA[i] + PB[i];
;                     u32x2 w; w.x = cvt_pk_bf16(h[0], h[1]); w.y = cvt_pk_bf16(h[2], h[3]);
;                     *(u32x2*)(H + (size_t)row * DM + lane * 4 + i * 256) = w;
;                     if (DO_GATES) {
; #pragma unroll
;                         for (int gg = 0; gg < 8; ++gg) { const f32x4 w4 = *(const LAS f32x4*)(wif + gg * 2048 + lane * 4 + i * 256); ga[gg] += (h[0] * w4[0] + h[1] * w4[1]) + (h[2] * w4[2] + h[3] * w4[3]); }
	v_mul_f32_e32 v45, v59, v45
	v_fmac_f32_e32 v45, v58, v44
	v_mul_f32_e32 v44, v53, v47
	v_fmac_f32_e32 v44, v52, v46
	v_add_f32_e32 v44, v45, v44
	v_add_f32_e32 v149, v153, v44
	v_mul_f32_e32 v44, v59, v49
	v_fmac_f32_e32 v44, v58, v48
	v_pk_fma_f32 v[48:49], v[78:79], v[42:43], v[110:111]
	v_pk_fma_f32 v[54:55], v[80:81], v[40:41], v[112:113]
	v_cvt_pk_bf16_f32 v41, v48, v49
	v_cvt_pk_bf16_f32 v40, v54, v55
	global_store_dwordx2 v[60:61], v[40:41], off offset:2560
	ds_read_b128 v[40:43], v138 offset:5120
	v_mul_f32_e32 v45, v53, v51
	v_fmac_f32_e32 v45, v52, v50
	v_add_f32_e32 v44, v44, v45
	v_add_f32_e32 v52, v56, v44
	ds_read_b128 v[44:47], v138 offset:13312
	s_waitcnt lgkmcnt(0)
	v_mul_f32_e32 v41, v55, v41
	v_fmac_f32_e32 v41, v54, v40
	v_mul_f32_e32 v40, v49, v43
	v_fmac_f32_e32 v40, v48, v42
	v_add_f32_e32 v40, v41, v40
	v_add_f32_e32 v53, v57, v40
	v_mul_f32_e32 v45, v55, v45
	ds_read_b128 v[40:43], v138 offset:21504
	v_fmac_f32_e32 v45, v54, v44
	v_mul_f32_e32 v44, v49, v47
	v_fmac_f32_e32 v44, v48, v46
	v_add_f32_e32 v44, v45, v44
	v_add_f32_e32 v56, v62, v44
	ds_read_b128 v[44:47], v138 offset:29696
	s_waitcnt lgkmcnt(0)
	v_mul_f32_e32 v41, v55, v41
	v_fmac_f32_e32 v41, v54, v40
	v_mul_f32_e32 v40, v49, v43
	v_fmac_f32_e32 v40, v48, v42
	v_add_f32_e32 v40, v41, v40
	v_add_f32_e32 v57, v63, v40
	v_mul_f32_e32 v45, v55, v45
	ds_read_b128 v[40:43], v138 offset:37888
	v_fmac_f32_e32 v45, v54, v44
	v_mul_f32_e32 v44, v49, v47
	v_fmac_f32_e32 v44, v48, v46
	v_add_f32_e32 v44, v45, v44
	v_add_f32_e32 v58, v146, v44
	ds_read_b128 v[44:47], v138 offset:46080
	s_waitcnt lgkmcnt(0)
	v_mul_f32_e32 v41, v55, v41
	v_fmac_f32_e32 v41, v54, v40
	v_mul_f32_e32 v40, v49, v43
	v_fmac_f32_e32 v40, v48, v42
	v_add_f32_e32 v40, v41, v40
	v_add_f32_e32 v59, v147, v40
	v_mul_f32_e32 v45, v55, v45
	ds_read_b128 v[40:43], v138 offset:54272
	v_fmac_f32_e32 v45, v54, v44
	v_mul_f32_e32 v44, v49, v47
	v_fmac_f32_e32 v44, v48, v46
	v_add_f32_e32 v44, v45, v44
	v_add_f32_e32 v62, v148, v44
	ds_read_b128 v[44:47], v138 offset:62464
	s_waitcnt lgkmcnt(0)
	v_mul_f32_e32 v41, v55, v41
	v_fmac_f32_e32 v41, v54, v40
	v_mul_f32_e32 v40, v49, v43
	v_fmac_f32_e32 v40, v48, v42
	v_add_f32_e32 v40, v41, v40
	v_add_f32_e32 v63, v149, v40
	v_mul_f32_e32 v40, v55, v45
	v_fmac_f32_e32 v40, v54, v44
	v_pk_fma_f32 v[44:45], v[82:83], v[38:39], v[114:115]
	v_pk_fma_f32 v[50:51], v[84:85], v[36:37], v[116:117]
	v_cvt_pk_bf16_f32 v37, v44, v45
	v_cvt_pk_bf16_f32 v36, v50, v51
	global_store_dwordx2 v[60:61], v[36:37], off offset:3072
	ds_read_b128 v[36:39], v138 offset:6144
	v_mul_f32_e32 v41, v49, v47
	v_fmac_f32_e32 v41, v48, v46
	v_add_f32_e32 v40, v40, v41
	v_add_f32_e32 v48, v52, v40
	ds_read_b128 v[40:43], v138 offset:14336
	s_waitcnt lgkmcnt(0)
	v_mul_f32_e32 v37, v51, v37
	v_fmac_f32_e32 v37, v50, v36
	v_mul_f32_e32 v36, v45, v39
	v_fmac_f32_e32 v36, v44, v38
	v_add_f32_e32 v36, v37, v36
	v_add_f32_e32 v49, v53, v36
	v_mul_f32_e32 v41, v51, v41
	ds_read_b128 v[36:39], v138 offset:22528
	v_fmac_f32_e32 v41, v50, v40
	v_mul_f32_e32 v40, v45, v43
	v_fmac_f32_e32 v40, v44, v42
	v_add_f32_e32 v40, v41, v40
	v_add_f32_e32 v52, v56, v40
	ds_read_b128 v[40:43], v138 offset:30720
	s_waitcnt lgkmcnt(0)
	v_mul_f32_e32 v37, v51, v37
	v_fmac_f32_e32 v37, v50, v36
	v_mul_f32_e32 v36, v45, v39
	v_fmac_f32_e32 v36, v44, v38
	v_add_f32_e32 v36, v37, v36
	v_add_f32_e32 v53, v57, v36
	v_mul_f32_e32 v41, v51, v41
	ds_read_b128 v[36:39], v138 offset:38912
	v_fmac_f32_e32 v41, v50, v40
	v_mul_f32_e32 v40, v45, v43
	v_fmac_f32_e32 v40, v44, v42
	v_add_f32_e32 v40, v41, v40
	v_add_f32_e32 v54, v58, v40
	ds_read_b128 v[40:43], v138 offset:47104
	s_waitcnt lgkmcnt(0)
	v_mul_f32_e32 v37, v51, v37
	v_fmac_f32_e32 v37, v50, v36
	v_mul_f32_e32 v36, v45, v39
	v_fmac_f32_e32 v36, v44, v38
	v_add_f32_e32 v36, v37, v36
	v_add_f32_e32 v55, v59, v36
	v_mul_f32_e32 v41, v51, v41
	ds_read_b128 v[36:39], v138 offset:55296
	v_fmac_f32_e32 v41, v50, v40
	v_mul_f32_e32 v40, v45, v43
	v_fmac_f32_e32 v40, v44, v42
	v_add_f32_e32 v40, v41, v40
	v_add_f32_e32 v56, v62, v40
	ds_read_b128 v[40:43], v138 offset:63488
	s_waitcnt lgkmcnt(0)
	v_mul_f32_e32 v37, v51, v37
	v_fmac_f32_e32 v37, v50, v36
	v_mul_f32_e32 v36, v45, v39
	v_fmac_f32_e32 v36, v44, v38
	v_add_f32_e32 v36, v37, v36
	v_add_f32_e32 v57, v63, v36
	v_mul_f32_e32 v36, v51, v41
	v_fmac_f32_e32 v36, v50, v40
	v_pk_fma_f32 v[40:41], v[86:87], v[34:35], v[118:119]
	v_pk_fma_f32 v[46:47], v[88:89], v[32:33], v[120:121]
	v_cvt_pk_bf16_f32 v33, v40, v41
	v_cvt_pk_bf16_f32 v32, v46, v47
	global_store_dwordx2 v[60:61], v[32:33], off offset:3584
	ds_read_b128 v[32:35], v138 offset:7168
	v_mul_f32_e32 v37, v45, v43
	v_fmac_f32_e32 v37, v44, v42
	v_add_f32_e32 v36, v36, v37
	v_add_f32_e32 v42, v48, v36
	ds_read_b128 v[36:39], v138 offset:15360
	s_waitcnt lgkmcnt(0)
	v_mul_f32_e32 v33, v47, v33
	v_fmac_f32_e32 v33, v46, v32
	v_mul_f32_e32 v32, v41, v35
	v_fmac_f32_e32 v32, v40, v34
	v_add_f32_e32 v32, v33, v32
	v_add_f32_e32 v43, v49, v32
	ds_read_b128 v[32:35], v138 offset:23552
	v_mul_f32_e32 v37, v47, v37
	v_fmac_f32_e32 v37, v46, v36
	v_mul_f32_e32 v36, v41, v39
	v_fmac_f32_e32 v36, v40, v38
	v_add_f32_e32 v36, v37, v36
	v_add_f32_e32 v44, v52, v36
	ds_read_b128 v[36:39], v138 offset:31744
	s_waitcnt lgkmcnt(0)
	v_mul_f32_e32 v33, v47, v33
	v_fmac_f32_e32 v33, v46, v32
	v_mul_f32_e32 v32, v41, v35
	v_fmac_f32_e32 v32, v40, v34
	v_add_f32_e32 v32, v33, v32
	v_add_f32_e32 v45, v53, v32
	ds_read_b128 v[32:35], v138 offset:39936
	v_mul_f32_e32 v37, v47, v37
	v_fmac_f32_e32 v37, v46, v36
	v_mul_f32_e32 v36, v41, v39
	v_fmac_f32_e32 v36, v40, v38
	v_add_f32_e32 v36, v37, v36
	v_add_f32_e32 v48, v54, v36
	ds_read_b128 v[36:39], v138 offset:48128
	s_waitcnt lgkmcnt(0)
; #define LAS __attribute__((address_space(3)))
; #define SHX(lane, v, m) shfl_idx(lane, (v), (lane) ^ (m))
; __device__ __forceinline__ float wave_sum(float v, int lane) {
; #pragma unroll
;     for (int o = 32; o >= 1; o >>= 1) v += SHX(lane, v, o);
;     return v;
; template <bool DO_LN, bool DO_H, bool DO_GATES, bool WRITE_X> ...
;     ...
;                         for (int gg = 0; gg < 8; ++gg) { const f32x4 w4 = *(const LAS f32x4*)(wif + gg * 2048 + lane * 4 + i * 256); ga[gg] += (h[0] * w4[0] + h[1] * w4[1]) + (h[2] * w4[2] + h[3] * w4[3]); }
;                     } }
;                 if (DO_GATES) {
; #pragma unroll
;                     for (int gg = 0; gg < 8; ++gg) ga[gg] = wave_sum(ga[gg], lane);
;                     if (lane == 0) {
; #pragma unroll
;                         for (int gg = 0; gg < 8; ++gg) GIF[(size_t)row * 8 + gg] = ga[gg] + (gg < 4 ? igb[gg] : fgb[gg - 4]); }
	v_mul_f32_e32 v33, v47, v33
	v_fmac_f32_e32 v33, v46, v32
	v_mul_f32_e32 v32, v41, v35
	v_fmac_f32_e32 v32, v40, v34
	v_add_f32_e32 v32, v33, v32
	v_add_f32_e32 v49, v55, v32
	ds_read_b128 v[32:35], v138 offset:56320
	v_mul_f32_e32 v37, v47, v37
	v_fmac_f32_e32 v37, v46, v36
	v_mul_f32_e32 v36, v41, v39
	v_fmac_f32_e32 v36, v40, v38
	v_add_f32_e32 v36, v37, v36
	v_add_f32_e32 v50, v56, v36
	ds_read_b128 v[36:39], v138 offset:64512
	s_waitcnt lgkmcnt(0)
	v_mul_f32_e32 v33, v47, v33
	v_mul_f32_e32 v35, v41, v35
	v_fmac_f32_e32 v33, v46, v32
	v_fmac_f32_e32 v35, v40, v34
	v_add_f32_e32 v33, v33, v35
	ds_bpermute_b32 v35, v139, v44
	v_mul_f32_e32 v34, v47, v37
	v_fmac_f32_e32 v34, v46, v36
	v_mul_f32_e32 v36, v41, v39
	v_fmac_f32_e32 v36, v40, v38
	s_waitcnt lgkmcnt(0)
	v_add_f32_e32 v35, v44, v35
	ds_bpermute_b32 v37, v140, v35
	v_add_f32_e32 v34, v34, v36
	v_add_f32_e32 v42, v42, v34
	ds_bpermute_b32 v34, v139, v45
	ds_bpermute_b32 v38, v139, v49
	s_waitcnt lgkmcnt(0)
	v_add_f32_e32 v35, v35, v37
	ds_bpermute_b32 v36, v141, v35
	ds_bpermute_b32 v32, v139, v43
	v_add_f32_e32 v34, v45, v34
	ds_bpermute_b32 v37, v140, v34
	v_add_f32_e32 v38, v49, v38
	s_waitcnt lgkmcnt(0)
	v_add_f32_e32 v35, v35, v36
	ds_bpermute_b32 v36, v142, v35
	ds_bpermute_b32 v41, v140, v38
	v_add_f32_e32 v34, v34, v37
	ds_bpermute_b32 v37, v141, v34
	v_add_f32_e32 v32, v43, v32
	s_waitcnt lgkmcnt(0)
	v_add_f32_e32 v35, v35, v36
	ds_bpermute_b32 v36, v139, v48
	ds_bpermute_b32 v39, v143, v35
	v_add_f32_e32 v37, v34, v37
	ds_bpermute_b32 v43, v142, v37
	v_add_f32_e32 v51, v57, v33
	s_waitcnt lgkmcnt(0)
	v_add_f32_e32 v36, v48, v36
	ds_bpermute_b32 v40, v140, v36
	v_add_f32_e32 v34, v35, v39
	v_add_f32_e32 v35, v38, v41
	ds_bpermute_b32 v38, v141, v35
	v_add_f32_e32 v37, v37, v43
	s_waitcnt lgkmcnt(0)
	v_add_f32_e32 v36, v36, v40
	ds_bpermute_b32 v40, v141, v36
	ds_bpermute_b32 v44, v139, v51
	v_add_f32_e32 v41, v35, v38
	ds_bpermute_b32 v43, v142, v41
	ds_bpermute_b32 v45, v139, v42
	s_waitcnt lgkmcnt(0)
	v_add_f32_e32 v36, v36, v40
	ds_bpermute_b32 v40, v143, v37
	v_add_f32_e32 v44, v51, v44
	ds_bpermute_b32 v33, v140, v32
	v_add_f32_e32 v42, v42, v45
	ds_bpermute_b32 v47, v140, v44
	s_waitcnt lgkmcnt(0)
	v_add_f32_e32 v35, v37, v40
	v_add_f32_e32 v37, v41, v43
	ds_bpermute_b32 v43, v139, v50
	ds_bpermute_b32 v45, v140, v42
	v_add_f32_e32 v32, v32, v33
	v_add_f32_e32 v44, v44, v47
	ds_bpermute_b32 v33, v141, v32
	s_waitcnt lgkmcnt(0)
	v_add_f32_e32 v43, v50, v43
	ds_bpermute_b32 v46, v140, v43
	v_add_f32_e32 v42, v42, v45
	ds_bpermute_b32 v47, v141, v44
	ds_bpermute_b32 v45, v141, v42
	v_add_f32_e32 v32, v32, v33
	s_waitcnt lgkmcnt(0)
	v_add_f32_e32 v43, v43, v46
	ds_bpermute_b32 v46, v141, v43
	v_add_f32_e32 v44, v44, v47
	v_add_f32_e32 v42, v42, v45
	ds_bpermute_b32 v33, v142, v32
	ds_bpermute_b32 v39, v142, v36
	s_waitcnt lgkmcnt(0)
	v_add_f32_e32 v43, v43, v46
	ds_bpermute_b32 v46, v142, v43
	ds_bpermute_b32 v47, v142, v44
	ds_bpermute_b32 v45, v142, v42
	v_add_f32_e32 v32, v32, v33
	v_add_f32_e32 v36, v36, v39
	s_waitcnt lgkmcnt(0)
	v_add_f32_e32 v43, v43, v46
	v_add_f32_e32 v44, v44, v47
	v_add_f32_e32 v42, v42, v45
	ds_bpermute_b32 v33, v143, v32
	ds_bpermute_b32 v39, v143, v36
	ds_bpermute_b32 v41, v143, v37
	ds_bpermute_b32 v46, v143, v43
	ds_bpermute_b32 v48, v143, v44
	ds_bpermute_b32 v49, v143, v42
	s_waitcnt lgkmcnt(0)
	v_add_f32_e32 v32, v32, v33
	v_add_f32_e32 v36, v36, v39
	v_add_f32_e32 v37, v37, v41
	v_add_f32_e32 v46, v43, v46
	v_add_f32_e32 v44, v44, v48
	v_add_f32_e32 v42, v42, v49
	ds_bpermute_b32 v33, v144, v32
	ds_bpermute_b32 v38, v144, v34
	ds_bpermute_b32 v40, v144, v35
	ds_bpermute_b32 v39, v144, v36
	ds_bpermute_b32 v41, v144, v37
	ds_bpermute_b32 v47, v144, v46
	ds_bpermute_b32 v45, v144, v44
	ds_bpermute_b32 v43, v144, v42
	s_and_saveexec_b64 s[2:3], s[0:1]
	s_cbranch_execz .LBB0_172
	v_mov_b64_e32 v[48:49], s[6:7]
	global_load_dword v50, v[48:49], off
	s_waitcnt lgkmcnt(0)
	v_add_f32_e32 v51, v32, v33
	v_lshl_add_u64 v[32:33], s[4:5], 0, v[70:71]
	v_add_co_u32_e32 v32, vcc, 0x3d000000, v32
	v_add_f32_e32 v34, v34, v38
	s_nop 0
	v_addc_co_u32_e32 v33, vcc, 0, v33, vcc
	v_add_f32_e32 v35, v35, v40
	v_add_f32_e32 v37, v37, v41
	s_waitcnt vmcnt(0)
	v_add_f32_e32 v50, v51, v50
	global_store_dword v[32:33], v50, off
	global_load_dword v50, v[48:49], off offset:4
	s_waitcnt vmcnt(0) lgkmcnt(0)
	v_add_f32_e32 v34, v34, v50
	global_store_dword v[32:33], v34, off offset:4
	global_load_dword v34, v[48:49], off offset:8
	s_waitcnt vmcnt(0) lgkmcnt(0)
	v_add_f32_e32 v34, v35, v34
	global_store_dword v[32:33], v34, off offset:8
	global_load_dword v34, v[48:49], off offset:12
	v_add_f32_e32 v35, v36, v39
	s_waitcnt vmcnt(0) lgkmcnt(0)
	v_add_f32_e32 v34, v35, v34
	global_store_dword v[32:33], v34, off offset:12
	v_mov_b64_e32 v[34:35], s[8:9]
	global_load_dword v36, v[34:35], off
	s_waitcnt vmcnt(0) lgkmcnt(0)
	v_add_f32_e32 v36, v37, v36
	global_store_dword v[32:33], v36, off offset:16
	global_load_dword v36, v[34:35], off offset:4
	v_add_f32_e32 v37, v46, v47
	s_waitcnt vmcnt(0) lgkmcnt(0)
	v_add_f32_e32 v36, v37, v36
	global_store_dword v[32:33], v36, off offset:20
	global_load_dword v36, v[34:35], off offset:8
	v_add_f32_e32 v37, v44, v45
	s_waitcnt vmcnt(0) lgkmcnt(0)
	v_add_f32_e32 v36, v37, v36
	global_store_dword v[32:33], v36, off offset:24
	global_load_dword v34, v[34:35], off offset:12
	v_add_f32_e32 v35, v42, v43
	s_waitcnt vmcnt(0) lgkmcnt(0)
	v_add_f32_e32 v34, v35, v34
	global_store_dword v[32:33], v34, off offset:28
	s_branch .LBB0_172

; #define PG8_STAGE(bufoff, gbase, voff) do { _Pragma("unroll") for (int _i = 0; _i < 2; ++_i) \
;         __builtin_amdgcn_global_load_lds((const unsigned*)((const char*)(gbase) + (voff)[_i]), (LAS unsigned*)(lds + (bufoff) + ldsw + _i * 8192), 16, 0, 0); } while (0)
; #define PG8_LDA(dst, b, h) do { _Pragma("unroll") for (int m = 0; m < 4; ++m) _Pragma("unroll") for (int k = 0; k < 2; ++k) dst[m][k] = *(const LAS bf16x8*)(lds + PG8_SA(b, h) + aoff + m * 2048 + k * 1024); } while (0)
; #define PG8_WAIT_V(n) asm volatile("s_waitcnt vmcnt(" #n ")" ::: "memory")
; #define PG8_BAR __builtin_amdgcn_s_barrier()
; template <class Epi, class Sched, bool AREMAP>
; __device__ __forceinline__ void gemm_phase(LAS unsigned char* lds, const Gemm g, const Sched& S, const Epi& E, int wv) {
;     ...
;         for (int t = 0; t < nt; t += 2) {
;             const bool last = (t == nt - 2);
;             const char* a1 = cA + (size_t)(t + 1) * kstep;
;             const char* a2 = last ? nA : cA + (size_t)(t + 2) * kstep; const char* b2 = last ? nB : cB + (size_t)(t + 2) * kstep;
;             const char* a3 = a2 + kstep; const char* b3 = b2 + kstep;
;             PG8_LDB(B0, 0, 0); PG8_SCHED; PG8_LDA(At, 0, 0); PG8_STAGE(PG8_SA(1, 1), a1 + hstepA, voffA);
;             PG8_WAIT_L(8); PG8_BAR; PG8_WAIT_L(0); PG8_MMA(0, 0, At, B0); PG8_BAR; PG8_SCHED;
;             PG8_LDB(B1, 0, 1); PG8_STAGE(PG8_SB(0, 0), b2, voffB);
;             PG8_BAR; PG8_WAIT_L(0); PG8_MMA(0, 1, At, B1); PG8_BAR;
;             PG8_LDA(At, 0, 1); PG8_STAGE(PG8_SA(0, 0), a2, voffA);
;             PG8_BAR; PG8_WAIT_L(0); PG8_MMA(1, 0, At, B0); PG8_BAR; PG8_SCHED;
;             PG8_STAGE(PG8_SB(0, 1), b2 + hstepB, voffB);
;             PG8_WAIT_V(6); PG8_BAR; PG8_MMA(1, 1, At, B1); PG8_BAR;
;             PG8_LDB(B0, 1, 0); PG8_SCHED; PG8_LDA(At, 1, 0); PG8_STAGE(PG8_SA(0, 1), a2 + hstepA, voffA);
;             PG8_WAIT_L(8); PG8_BAR; PG8_WAIT_L(0); PG8_MMA(0, 0, At, B0); PG8_BAR; PG8_SCHED;
;             PG8_LDB(B1, 1, 1); PG8_STAGE(PG8_SB(1, 0), b3, voffB);
;             PG8_BAR; PG8_WAIT_L(0); PG8_MMA(0, 1, At, B1); PG8_BAR;
;             PG8_LDA(At, 1, 1); PG8_STAGE(PG8_SA(1, 0), a3, voffA);
;             PG8_BAR; PG8_WAIT_L(0); PG8_MMA(1, 0, At, B0); PG8_BAR; PG8_SCHED;
;             PG8_STAGE(PG8_SB(1, 1), b3 + hstepB, voffB);
;             PG8_WAIT_V(6); PG8_BAR; PG8_MMA(1, 1, At, B1); PG8_BAR;
;         }
.LBB0_202:
	s_add_u32 s18, s16, 0xfff80080
	s_addc_u32 s19, s17, -1
	s_add_i32 s38, 0, 0x10000
	v_add_u32_e32 v145, s38, v142
	ds_read_b128 v[146:149], v145
	ds_read_b128 v[150:153], v145 offset:1024
	ds_read_b128 v[154:157], v145 offset:2048
	ds_read_b128 v[158:161], v145 offset:3072
	s_cmp_eq_u32 s56, 28
	s_cselect_b32 s21, s11, s19
	s_cselect_b32 s20, s47, s18
	s_cselect_b32 s19, s9, s55
	s_cselect_b32 s18, s52, s53
	v_lshl_add_u64 v[186:187], s[16:17], 0, v[140:141]
	s_add_i32 m0, s7, 0xc000
	ds_read_b128 v[162:165], v144
	ds_read_b128 v[166:169], v144 offset:1024
	ds_read_b128 v[170:173], v144 offset:2048
	ds_read_b128 v[174:177], v144 offset:3072
	ds_read_b128 v[178:181], v144 offset:4096
	ds_read_b128 v[182:185], v144 offset:5120
	ds_read_b128 v[196:199], v144 offset:6144
	ds_read_b128 v[200:203], v144 offset:7168
	global_load_lds_dwordx4 v[186:187], off
	v_lshl_add_u64 v[186:187], s[16:17], 0, v[138:139]
	s_add_i32 m0, s7, 0xe000
	s_nop 0
	global_load_lds_dwordx4 v[186:187], off
	s_waitcnt lgkmcnt(8)
	s_barrier
	s_waitcnt lgkmcnt(0)
	s_setprio 1
	s_waitcnt lgkmcnt(0)
	v_mfma_f32_16x16x32_bf16 v[126:129], v[146:149], v[162:165], v[126:129]
	v_mfma_f32_16x16x32_bf16 v[122:125], v[154:157], v[162:165], v[122:125]
	v_mfma_f32_16x16x32_bf16 v[118:121], v[146:149], v[170:173], v[118:121]
	v_mfma_f32_16x16x32_bf16 v[114:117], v[154:157], v[170:173], v[114:117]
	v_mfma_f32_16x16x32_bf16 v[102:105], v[146:149], v[178:181], v[102:105]
	v_mfma_f32_16x16x32_bf16 v[98:101], v[154:157], v[178:181], v[98:101]
	v_mfma_f32_16x16x32_bf16 v[86:89], v[146:149], v[196:199], v[86:89]
	v_mfma_f32_16x16x32_bf16 v[82:85], v[154:157], v[196:199], v[82:85]
	v_mfma_f32_16x16x32_bf16 v[126:129], v[150:153], v[166:169], v[126:129]
	v_mfma_f32_16x16x32_bf16 v[122:125], v[158:161], v[166:169], v[122:125]
	v_mfma_f32_16x16x32_bf16 v[118:121], v[150:153], v[174:177], v[118:121]
	v_mfma_f32_16x16x32_bf16 v[114:117], v[158:161], v[174:177], v[114:117]
	v_mfma_f32_16x16x32_bf16 v[102:105], v[150:153], v[182:185], v[102:105]
	v_mfma_f32_16x16x32_bf16 v[98:101], v[158:161], v[182:185], v[98:101]
	v_mfma_f32_16x16x32_bf16 v[86:89], v[150:153], v[200:203], v[86:89]
	v_mfma_f32_16x16x32_bf16 v[82:85], v[158:161], v[200:203], v[82:85]
	s_setprio 0
	s_barrier
	s_add_i32 s39, 0, 0x14000
	s_add_i32 s38, s38, s29
	v_add_u32_e32 v145, s39, v142
	v_lshl_add_u64 v[186:187], s[18:19], 0, v[132:133]
	s_mov_b32 m0, s38
	ds_read_b128 v[204:207], v145
	ds_read_b128 v[208:211], v145 offset:1024
	ds_read_b128 v[212:215], v145 offset:2048
	ds_read_b128 v[216:219], v145 offset:3072
	global_load_lds_dwordx4 v[186:187], off
	v_lshl_add_u64 v[192:193], s[18:19], 0, v[136:137]
	s_add_i32 m0, s38, 0x2000
	s_nop 0
	global_load_lds_dwordx4 v[192:193], off
	s_barrier
	s_waitcnt lgkmcnt(0)
	s_setprio 1
	s_waitcnt lgkmcnt(0)
	v_mfma_f32_16x16x32_bf16 v[110:113], v[204:207], v[162:165], v[110:113]
	v_mfma_f32_16x16x32_bf16 v[106:109], v[212:215], v[162:165], v[106:109]
	v_mfma_f32_16x16x32_bf16 v[94:97], v[204:207], v[170:173], v[94:97]
	v_mfma_f32_16x16x32_bf16 v[90:93], v[212:215], v[170:173], v[90:93]
	v_mfma_f32_16x16x32_bf16 v[78:81], v[204:207], v[178:181], v[78:81]
	v_mfma_f32_16x16x32_bf16 v[74:77], v[212:215], v[178:181], v[74:77]
	v_mfma_f32_16x16x32_bf16 v[70:73], v[204:207], v[196:199], v[70:73]
	v_mfma_f32_16x16x32_bf16 v[66:69], v[212:215], v[196:199], v[66:69]
	v_mfma_f32_16x16x32_bf16 v[110:113], v[208:211], v[166:169], v[110:113]
	v_mfma_f32_16x16x32_bf16 v[106:109], v[216:219], v[166:169], v[106:109]
	v_mfma_f32_16x16x32_bf16 v[94:97], v[208:211], v[174:177], v[94:97]
	v_mfma_f32_16x16x32_bf16 v[90:93], v[216:219], v[174:177], v[90:93]
	v_mfma_f32_16x16x32_bf16 v[78:81], v[208:211], v[182:185], v[78:81]
	v_mfma_f32_16x16x32_bf16 v[74:77], v[216:219], v[182:185], v[74:77]
	v_mfma_f32_16x16x32_bf16 v[70:73], v[208:211], v[200:203], v[70:73]
	v_mfma_f32_16x16x32_bf16 v[66:69], v[216:219], v[200:203], v[66:69]
	s_setprio 0
	s_mov_b32 m0, s7
	v_lshl_add_u64 v[194:195], s[20:21], 0, v[130:131]
	s_barrier
	ds_read_b128 v[162:165], v144 offset:16384
	ds_read_b128 v[166:169], v144 offset:17408
	ds_read_b128 v[170:173], v144 offset:18432
	ds_read_b128 v[174:177], v144 offset:19456
	ds_read_b128 v[178:181], v144 offset:20480
	ds_read_b128 v[182:185], v144 offset:21504
	ds_read_b128 v[196:199], v144 offset:22528
	ds_read_b128 v[200:203], v144 offset:23552
	global_load_lds_dwordx4 v[194:195], off
	v_lshl_add_u64 v[220:221], s[20:21], 0, v[134:135]
	s_mov_b32 m0, s30
	s_nop 0
	global_load_lds_dwordx4 v[220:221], off
	s_barrier
	s_waitcnt lgkmcnt(0)
	s_setprio 1
	s_waitcnt lgkmcnt(0)
	v_mfma_f32_16x16x32_bf16 v[62:65], v[146:149], v[162:165], v[62:65]
	v_mfma_f32_16x16x32_bf16 v[58:61], v[154:157], v[162:165], v[58:61]
	v_mfma_f32_16x16x32_bf16 v[54:57], v[146:149], v[170:173], v[54:57]
	v_mfma_f32_16x16x32_bf16 v[50:53], v[154:157], v[170:173], v[50:53]
	v_mfma_f32_16x16x32_bf16 v[38:41], v[146:149], v[178:181], v[38:41]
	v_mfma_f32_16x16x32_bf16 v[34:37], v[154:157], v[178:181], v[34:37]
	v_mfma_f32_16x16x32_bf16 v[22:25], v[146:149], v[196:199], v[22:25]
	v_mfma_f32_16x16x32_bf16 v[18:21], v[154:157], v[196:199], v[18:21]
	v_mfma_f32_16x16x32_bf16 v[62:65], v[150:153], v[166:169], v[62:65]
	v_mfma_f32_16x16x32_bf16 v[58:61], v[158:161], v[166:169], v[58:61]
	v_mfma_f32_16x16x32_bf16 v[54:57], v[150:153], v[174:177], v[54:57]
	v_mfma_f32_16x16x32_bf16 v[50:53], v[158:161], v[174:177], v[50:53]
	v_mfma_f32_16x16x32_bf16 v[38:41], v[150:153], v[182:185], v[38:41]
	v_mfma_f32_16x16x32_bf16 v[34:37], v[158:161], v[182:185], v[34:37]
	v_mfma_f32_16x16x32_bf16 v[22:25], v[150:153], v[200:203], v[22:25]
	v_mfma_f32_16x16x32_bf16 v[18:21], v[158:161], v[200:203], v[18:21]
	s_setprio 0
	s_barrier
; #define PG8_STAGE(bufoff, gbase, voff) do { _Pragma("unroll") for (int _i = 0; _i < 2; ++_i) \
;         __builtin_amdgcn_global_load_lds((const unsigned*)((const char*)(gbase) + (voff)[_i]), (LAS unsigned*)(lds + (bufoff) + ldsw + _i * 8192), 16, 0, 0); } while (0)
; #define PG8_LDA(dst, b, h) do { _Pragma("unroll") for (int m = 0; m < 4; ++m) _Pragma("unroll") for (int k = 0; k < 2; ++k) dst[m][k] = *(const LAS bf16x8*)(lds + PG8_SA(b, h) + aoff + m * 2048 + k * 1024); } while (0)
; #define PG8_WAIT_V(n) asm volatile("s_waitcnt vmcnt(" #n ")" ::: "memory")
; #define PG8_BAR __builtin_amdgcn_s_barrier()
; template <class Epi, class Sched, bool AREMAP>
; __device__ __forceinline__ void gemm_phase(LAS unsigned char* lds, const Gemm g, const Sched& S, const Epi& E, int wv) {
;     ...
;         for (int t = 0; t < nt; t += 2) {
;             const bool last = (t == nt - 2);
;             const char* a1 = cA + (size_t)(t + 1) * kstep;
;             const char* a2 = last ? nA : cA + (size_t)(t + 2) * kstep; const char* b2 = last ? nB : cB + (size_t)(t + 2) * kstep;
;             const char* a3 = a2 + kstep; const char* b3 = b2 + kstep;
;             PG8_LDB(B0, 0, 0); PG8_SCHED; PG8_LDA(At, 0, 0); PG8_STAGE(PG8_SA(1, 1), a1 + hstepA, voffA);
;             PG8_WAIT_L(8); PG8_BAR; PG8_WAIT_L(0); PG8_MMA(0, 0, At, B0); PG8_BAR; PG8_SCHED;
;             PG8_LDB(B1, 0, 1); PG8_STAGE(PG8_SB(0, 0), b2, voffB);
;             PG8_BAR; PG8_WAIT_L(0); PG8_MMA(0, 1, At, B1); PG8_BAR;
;             PG8_LDA(At, 0, 1); PG8_STAGE(PG8_SA(0, 0), a2, voffA);
;             PG8_BAR; PG8_WAIT_L(0); PG8_MMA(1, 0, At, B0); PG8_BAR; PG8_SCHED;
;             PG8_STAGE(PG8_SB(0, 1), b2 + hstepB, voffB);
;             PG8_WAIT_V(6); PG8_BAR; PG8_MMA(1, 1, At, B1); PG8_BAR;
;             PG8_LDB(B0, 1, 0); PG8_SCHED; PG8_LDA(At, 1, 0); PG8_STAGE(PG8_SA(0, 1), a2 + hstepA, voffA);
;             PG8_WAIT_L(8); PG8_BAR; PG8_WAIT_L(0); PG8_MMA(0, 0, At, B0); PG8_BAR; PG8_SCHED;
;             PG8_LDB(B1, 1, 1); PG8_STAGE(PG8_SB(1, 0), b3, voffB);
;             PG8_BAR; PG8_WAIT_L(0); PG8_MMA(0, 1, At, B1); PG8_BAR;
;             PG8_LDA(At, 1, 1); PG8_STAGE(PG8_SA(1, 0), a3, voffA);
;             PG8_BAR; PG8_WAIT_L(0); PG8_MMA(1, 0, At, B0); PG8_BAR; PG8_SCHED;
;             PG8_STAGE(PG8_SB(1, 1), b3 + hstepB, voffB);
;             PG8_WAIT_V(6); PG8_BAR; PG8_MMA(1, 1, At, B1); PG8_BAR;
;         }
	s_add_u32 s62, s18, 0x80000
	s_addc_u32 s63, s19, 0
	s_add_i32 s38, s39, s29
	v_lshl_add_u64 v[146:147], s[62:63], 0, v[132:133]
	s_mov_b32 m0, s38
	s_nop 0
	global_load_lds_dwordx4 v[146:147], off
	v_lshl_add_u64 v[146:147], s[62:63], 0, v[136:137]
	s_add_i32 m0, s38, 0x2000
	s_nop 0
	global_load_lds_dwordx4 v[146:147], off
	s_waitcnt vmcnt(6)
	s_barrier
	s_setprio 1
	v_mfma_f32_16x16x32_bf16 v[46:49], v[204:207], v[162:165], v[46:49]
	v_mfma_f32_16x16x32_bf16 v[42:45], v[212:215], v[162:165], v[42:45]
	v_mfma_f32_16x16x32_bf16 v[30:33], v[204:207], v[170:173], v[30:33]
	v_mfma_f32_16x16x32_bf16 v[26:29], v[212:215], v[170:173], v[26:29]
	v_mfma_f32_16x16x32_bf16 v[14:17], v[204:207], v[178:181], v[14:17]
	v_mfma_f32_16x16x32_bf16 v[10:13], v[212:215], v[178:181], v[10:13]
	v_mfma_f32_16x16x32_bf16 v[6:9], v[204:207], v[196:199], v[6:9]
	v_mfma_f32_16x16x32_bf16 v[2:5], v[212:215], v[196:199], v[2:5]
	v_mfma_f32_16x16x32_bf16 v[46:49], v[208:211], v[166:169], v[46:49]
	v_mfma_f32_16x16x32_bf16 v[42:45], v[216:219], v[166:169], v[42:45]
	v_mfma_f32_16x16x32_bf16 v[30:33], v[208:211], v[174:177], v[30:33]
	v_mfma_f32_16x16x32_bf16 v[26:29], v[216:219], v[174:177], v[26:29]
	v_mfma_f32_16x16x32_bf16 v[14:17], v[208:211], v[182:185], v[14:17]
	v_mfma_f32_16x16x32_bf16 v[10:13], v[216:219], v[182:185], v[10:13]
	v_mfma_f32_16x16x32_bf16 v[6:9], v[208:211], v[200:203], v[6:9]
	v_mfma_f32_16x16x32_bf16 v[2:5], v[216:219], v[200:203], v[2:5]
	s_setprio 0
	s_add_i32 s38, 0, 0x18000
	v_add_u32_e32 v145, s38, v142
	s_barrier
	ds_read_b128 v[146:149], v145
	ds_read_b128 v[150:153], v145 offset:1024
	ds_read_b128 v[154:157], v145 offset:2048
	ds_read_b128 v[158:161], v145 offset:3072
	s_add_u32 s20, s20, 0x80000
	s_addc_u32 s21, s21, 0
	s_mov_b32 m0, s31
	v_lshl_add_u64 v[204:205], s[20:21], 0, v[130:131]
	ds_read_b128 v[162:165], v144 offset:32768
	ds_read_b128 v[166:169], v144 offset:33792
	ds_read_b128 v[170:173], v144 offset:34816
	ds_read_b128 v[174:177], v144 offset:35840
	ds_read_b128 v[178:181], v144 offset:36864
	ds_read_b128 v[182:185], v144 offset:37888
	ds_read_b128 v[196:199], v144 offset:38912
	ds_read_b128 v[200:203], v144 offset:39936
	global_load_lds_dwordx4 v[204:205], off
	v_lshl_add_u64 v[204:205], s[20:21], 0, v[134:135]
	s_mov_b32 m0, s34
	s_nop 0
	global_load_lds_dwordx4 v[204:205], off
	s_waitcnt lgkmcnt(8)
	s_barrier
	s_waitcnt lgkmcnt(0)
	s_setprio 1
	s_waitcnt lgkmcnt(0)
	v_mfma_f32_16x16x32_bf16 v[126:129], v[146:149], v[162:165], v[126:129]
	v_mfma_f32_16x16x32_bf16 v[122:125], v[154:157], v[162:165], v[122:125]
	v_mfma_f32_16x16x32_bf16 v[118:121], v[146:149], v[170:173], v[118:121]
	v_mfma_f32_16x16x32_bf16 v[114:117], v[154:157], v[170:173], v[114:117]
	v_mfma_f32_16x16x32_bf16 v[102:105], v[146:149], v[178:181], v[102:105]
	v_mfma_f32_16x16x32_bf16 v[98:101], v[154:157], v[178:181], v[98:101]
	v_mfma_f32_16x16x32_bf16 v[86:89], v[146:149], v[196:199], v[86:89]
	v_mfma_f32_16x16x32_bf16 v[82:85], v[154:157], v[196:199], v[82:85]
	v_mfma_f32_16x16x32_bf16 v[126:129], v[150:153], v[166:169], v[126:129]
	v_mfma_f32_16x16x32_bf16 v[122:125], v[158:161], v[166:169], v[122:125]
	v_mfma_f32_16x16x32_bf16 v[118:121], v[150:153], v[174:177], v[118:121]
	v_mfma_f32_16x16x32_bf16 v[114:117], v[158:161], v[174:177], v[114:117]
	v_mfma_f32_16x16x32_bf16 v[102:105], v[150:153], v[182:185], v[102:105]
	v_mfma_f32_16x16x32_bf16 v[98:101], v[158:161], v[182:185], v[98:101]
	v_mfma_f32_16x16x32_bf16 v[86:89], v[150:153], v[200:203], v[86:89]
	v_mfma_f32_16x16x32_bf16 v[82:85], v[158:161], v[200:203], v[82:85]
	s_setprio 0
	s_barrier
	s_add_i32 s20, 0, 0x1c000
	s_add_i32 s21, s38, s29
	v_add_u32_e32 v145, s20, v142
	v_lshl_add_u64 v[186:187], v[186:187], 0, s[86:87]
	s_mov_b32 m0, s21
	ds_read_b128 v[204:207], v145
	ds_read_b128 v[208:211], v145 offset:1024
	ds_read_b128 v[212:215], v145 offset:2048
	ds_read_b128 v[216:219], v145 offset:3072
	global_load_lds_dwordx4 v[186:187], off
	v_lshl_add_u64 v[186:187], v[192:193], 0, s[86:87]
	s_add_i32 m0, s21, 0x2000
	s_nop 0
	global_load_lds_dwordx4 v[186:187], off
	s_barrier
	s_waitcnt lgkmcnt(0)
	s_setprio 1
	s_waitcnt lgkmcnt(0)
	v_mfma_f32_16x16x32_bf16 v[110:113], v[204:207], v[162:165], v[110:113]
	v_mfma_f32_16x16x32_bf16 v[106:109], v[212:215], v[162:165], v[106:109]
	v_mfma_f32_16x16x32_bf16 v[94:97], v[204:207], v[170:173], v[94:97]
	v_mfma_f32_16x16x32_bf16 v[90:93], v[212:215], v[170:173], v[90:93]
	v_mfma_f32_16x16x32_bf16 v[78:81], v[204:207], v[178:181], v[78:81]
	v_mfma_f32_16x16x32_bf16 v[74:77], v[212:215], v[178:181], v[74:77]
	v_mfma_f32_16x16x32_bf16 v[70:73], v[204:207], v[196:199], v[70:73]
	v_mfma_f32_16x16x32_bf16 v[66:69], v[212:215], v[196:199], v[66:69]
	v_mfma_f32_16x16x32_bf16 v[110:113], v[208:211], v[166:169], v[110:113]
	v_mfma_f32_16x16x32_bf16 v[106:109], v[216:219], v[166:169], v[106:109]
	v_mfma_f32_16x16x32_bf16 v[94:97], v[208:211], v[174:177], v[94:97]
	v_mfma_f32_16x16x32_bf16 v[90:93], v[216:219], v[174:177], v[90:93]
	v_mfma_f32_16x16x32_bf16 v[78:81], v[208:211], v[182:185], v[78:81]
	v_mfma_f32_16x16x32_bf16 v[74:77], v[216:219], v[182:185], v[74:77]
	v_mfma_f32_16x16x32_bf16 v[70:73], v[208:211], v[200:203], v[70:73]
	v_mfma_f32_16x16x32_bf16 v[66:69], v[216:219], v[200:203], v[66:69]
	s_setprio 0
	s_mov_b32 m0, s35
	v_lshl_add_u64 v[186:187], v[194:195], 0, s[86:87]
	s_barrier
	ds_read_b128 v[162:165], v144 offset:49152
	ds_read_b128 v[166:169], v144 offset:50176
	ds_read_b128 v[170:173], v144 offset:51200
	ds_read_b128 v[174:177], v144 offset:52224
	ds_read_b128 v[178:181], v144 offset:53248
	ds_read_b128 v[182:185], v144 offset:54272
	ds_read_b128 v[196:199], v144 offset:55296
	ds_read_b128 v[200:203], v144 offset:56320
	global_load_lds_dwordx4 v[186:187], off
	v_lshl_add_u64 v[186:187], v[220:221], 0, s[86:87]
	s_mov_b32 m0, s36
	s_nop 0
	global_load_lds_dwordx4 v[186:187], off
	s_barrier
; #define PG8_STAGE(bufoff, gbase, voff) do { _Pragma("unroll") for (int _i = 0; _i < 2; ++_i) \
;         __builtin_amdgcn_global_load_lds((const unsigned*)((const char*)(gbase) + (voff)[_i]), (LAS unsigned*)(lds + (bufoff) + ldsw + _i * 8192), 16, 0, 0); } while (0)
; #define PG8_LDA(dst, b, h) do { _Pragma("unroll") for (int m = 0; m < 4; ++m) _Pragma("unroll") for (int k = 0; k < 2; ++k) dst[m][k] = *(const LAS bf16x8*)(lds + PG8_SA(b, h) + aoff + m * 2048 + k * 1024); } while (0)
; #define PG8_WAIT_V(n) asm volatile("s_waitcnt vmcnt(" #n ")" ::: "memory")
; #define PG8_BAR __builtin_amdgcn_s_barrier()
; template <class Epi, class Sched, bool AREMAP>
; __device__ __forceinline__ void gemm_phase(LAS unsigned char* lds, const Gemm g, const Sched& S, const Epi& E, int wv) {
;     ...
;         for (int t = 0; t < nt; t += 2) {
;             const bool last = (t == nt - 2);
;             const char* a1 = cA + (size_t)(t + 1) * kstep;
;             const char* a2 = last ? nA : cA + (size_t)(t + 2) * kstep; const char* b2 = last ? nB : cB + (size_t)(t + 2) * kstep;
;             const char* a3 = a2 + kstep; const char* b3 = b2 + kstep;
;             PG8_LDB(B0, 0, 0); PG8_SCHED; PG8_LDA(At, 0, 0); PG8_STAGE(PG8_SA(1, 1), a1 + hstepA, voffA);
;             PG8_WAIT_L(8); PG8_BAR; PG8_WAIT_L(0); PG8_MMA(0, 0, At, B0); PG8_BAR; PG8_SCHED;
;             PG8_LDB(B1, 0, 1); PG8_STAGE(PG8_SB(0, 0), b2, voffB);
;             PG8_BAR; PG8_WAIT_L(0); PG8_MMA(0, 1, At, B1); PG8_BAR;
;             PG8_LDA(At, 0, 1); PG8_STAGE(PG8_SA(0, 0), a2, voffA);
;             PG8_BAR; PG8_WAIT_L(0); PG8_MMA(1, 0, At, B0); PG8_BAR; PG8_SCHED;
;             PG8_STAGE(PG8_SB(0, 1), b2 + hstepB, voffB);
;             PG8_WAIT_V(6); PG8_BAR; PG8_MMA(1, 1, At, B1); PG8_BAR;
;             PG8_LDB(B0, 1, 0); PG8_SCHED; PG8_LDA(At, 1, 0); PG8_STAGE(PG8_SA(0, 1), a2 + hstepA, voffA);
;             PG8_WAIT_L(8); PG8_BAR; PG8_WAIT_L(0); PG8_MMA(0, 0, At, B0); PG8_BAR; PG8_SCHED;
;             PG8_LDB(B1, 1, 1); PG8_STAGE(PG8_SB(1, 0), b3, voffB);
;             PG8_BAR; PG8_WAIT_L(0); PG8_MMA(0, 1, At, B1); PG8_BAR;
;             PG8_LDA(At, 1, 1); PG8_STAGE(PG8_SA(1, 0), a3, voffA);
;             PG8_BAR; PG8_WAIT_L(0); PG8_MMA(1, 0, At, B0); PG8_BAR; PG8_SCHED;
;             PG8_STAGE(PG8_SB(1, 1), b3 + hstepB, voffB);
;             PG8_WAIT_V(6); PG8_BAR; PG8_MMA(1, 1, At, B1); PG8_BAR;
;         }
	s_waitcnt lgkmcnt(0)
	s_setprio 1
	s_waitcnt lgkmcnt(0)
	v_mfma_f32_16x16x32_bf16 v[62:65], v[146:149], v[162:165], v[62:65]
	v_mfma_f32_16x16x32_bf16 v[58:61], v[154:157], v[162:165], v[58:61]
	v_mfma_f32_16x16x32_bf16 v[54:57], v[146:149], v[170:173], v[54:57]
	v_mfma_f32_16x16x32_bf16 v[50:53], v[154:157], v[170:173], v[50:53]
	v_mfma_f32_16x16x32_bf16 v[38:41], v[146:149], v[178:181], v[38:41]
	v_mfma_f32_16x16x32_bf16 v[34:37], v[154:157], v[178:181], v[34:37]
	v_mfma_f32_16x16x32_bf16 v[22:25], v[146:149], v[196:199], v[22:25]
	v_mfma_f32_16x16x32_bf16 v[18:21], v[154:157], v[196:199], v[18:21]
	v_mfma_f32_16x16x32_bf16 v[62:65], v[150:153], v[166:169], v[62:65]
	v_mfma_f32_16x16x32_bf16 v[58:61], v[158:161], v[166:169], v[58:61]
	v_mfma_f32_16x16x32_bf16 v[54:57], v[150:153], v[174:177], v[54:57]
	v_mfma_f32_16x16x32_bf16 v[50:53], v[158:161], v[174:177], v[50:53]
	v_mfma_f32_16x16x32_bf16 v[38:41], v[150:153], v[182:185], v[38:41]
	v_mfma_f32_16x16x32_bf16 v[34:37], v[158:161], v[182:185], v[34:37]
	v_mfma_f32_16x16x32_bf16 v[22:25], v[150:153], v[200:203], v[22:25]
	v_mfma_f32_16x16x32_bf16 v[18:21], v[158:161], v[200:203], v[18:21]
	s_setprio 0
	s_barrier
	s_add_u32 s18, s18, 0x80080
	s_addc_u32 s19, s19, 0
	s_add_i32 s20, s20, s29
	v_lshl_add_u64 v[146:147], s[18:19], 0, v[132:133]
	s_mov_b32 m0, s20
	s_nop 0
	global_load_lds_dwordx4 v[146:147], off
	v_lshl_add_u64 v[146:147], s[18:19], 0, v[136:137]
	s_add_i32 m0, s20, 0x2000
	s_nop 0
	global_load_lds_dwordx4 v[146:147], off
	s_waitcnt vmcnt(6)
	s_barrier
	s_setprio 1
	v_mfma_f32_16x16x32_bf16 v[46:49], v[204:207], v[162:165], v[46:49]
	v_mfma_f32_16x16x32_bf16 v[42:45], v[212:215], v[162:165], v[42:45]
	v_mfma_f32_16x16x32_bf16 v[30:33], v[204:207], v[170:173], v[30:33]
	v_mfma_f32_16x16x32_bf16 v[26:29], v[212:215], v[170:173], v[26:29]
	v_mfma_f32_16x16x32_bf16 v[14:17], v[204:207], v[178:181], v[14:17]
	v_mfma_f32_16x16x32_bf16 v[10:13], v[212:215], v[178:181], v[10:13]
	v_mfma_f32_16x16x32_bf16 v[6:9], v[204:207], v[196:199], v[6:9]
	v_mfma_f32_16x16x32_bf16 v[2:5], v[212:215], v[196:199], v[2:5]
	v_mfma_f32_16x16x32_bf16 v[46:49], v[208:211], v[166:169], v[46:49]
	v_mfma_f32_16x16x32_bf16 v[42:45], v[216:219], v[166:169], v[42:45]
	v_mfma_f32_16x16x32_bf16 v[30:33], v[208:211], v[174:177], v[30:33]
	v_mfma_f32_16x16x32_bf16 v[26:29], v[216:219], v[174:177], v[26:29]
	v_mfma_f32_16x16x32_bf16 v[14:17], v[208:211], v[182:185], v[14:17]
	v_mfma_f32_16x16x32_bf16 v[10:13], v[216:219], v[182:185], v[10:13]
	v_mfma_f32_16x16x32_bf16 v[6:9], v[208:211], v[200:203], v[6:9]
	v_mfma_f32_16x16x32_bf16 v[2:5], v[216:219], v[200:203], v[2:5]
	s_setprio 0
	s_add_i32 s56, s56, 2
	s_add_u32 s53, s53, 0x100
	s_addc_u32 s55, s55, 0
	s_add_u32 s16, s16, 0x100
	s_addc_u32 s17, s17, 0
	s_cmp_gt_u32 s56, 29
	s_barrier
	s_cbranch_scc0 .LBB0_202
; __device__ __forceinline__ unsigned cvt_pk_bf16(float lo, float hi) { f32x2_t f = {lo, hi}; bf16x2_t v = __builtin_convertvector(f, bf16x2_t); return __builtin_bit_cast(unsigned, v); }
; #define PG8_WAIT_V(n) asm volatile("s_waitcnt vmcnt(" #n ")" ::: "memory")
; #define PG8_BAR __builtin_amdgcn_s_barrier()
; template <class Epi, class Sched, bool AREMAP>
; __device__ __forceinline__ void gemm_phase(LAS unsigned char* lds, const Gemm g, const Sched& S, const Epi& E, int wv) {
;     ...
;         E(acc, cur, wr, wc, fr, fq);
;         if (!has_next) break;
; #pragma unroll
;         for (int a = 0; a < 2; ++a)
; #pragma unroll
;             for (int b = 0; b < 2; ++b)
; #pragma unroll
;                 for (int m = 0; m < 4; ++m)
; #pragma unroll
;                     for (int n = 0; n < 2; ++n) acc[a][b][m][n] = (f32x4){0.f, 0.f, 0.f, 0.f};
;         cur = nxt; cA = nA; cB = nB; ++ui;
;     }
;     PG8_WAIT_V(0);
;     if (wr == 0) PG8_BAR;
;     __device__ __forceinline__ void operator()(const f32x4 (&acc)[2][2][4][2], const Unit& u, int wr, int wc, int fr, int fq) const {
;         const int row0 = u.pm * BM + wr * 64 + fr; int colt = u.pn * BM; bf16_t* base = O;
;         if (split_cols) { const int t = colt / split_cols; base += (size_t)t * split_stride; colt -= t * split_cols; }
;         const int col0 = colt + wc * 32 + 8 * fq;
; #pragma unroll
;         for (int ai = 0; ai < 2; ++ai)
; #pragma unroll
;             for (int m = 0; m < 4; ++m) { bf16_t* rowp = base + (size_t)(row0 + ai * HALF + m * 16) * ldc + col0;
; #pragma unroll
;                 for (int bj = 0; bj < 2; ++bj) { const f32x4 v0 = acc[ai][bj][m][0], v1 = acc[ai][bj][m][1];
;                     u32x4 w; w.x = cvt_pk_bf16(v0[0], v0[1]); w.y = cvt_pk_bf16(v0[2], v0[3]); w.z = cvt_pk_bf16(v1[0], v1[1]); w.w = cvt_pk_bf16(v1[2], v1[3]);
;                     *(u32x4*)(rowp + bj * HALF) = w; } }
	v_lshl_add_u32 v146, s6, 8, v1
	v_lshl_or_b32 v148, s46, 8, v143
	v_ashrrev_i32_e32 v149, 31, v148
	v_ashrrev_i32_e32 v147, 31, v146
	v_lshl_add_u64 v[148:149], v[148:149], 1, s[4:5]
	v_lshlrev_b64 v[150:151], 14, v[146:147]
	v_lshl_add_u64 v[150:151], v[148:149], 0, v[150:151]
	s_mov_b32 s6, 0x200000
	s_mov_b64 s[16:17], 0x200000
	v_cvt_pk_bf16_f32 v62, v62, v63
	v_cvt_pk_bf16_f32 v63, v64, v65
	v_cvt_pk_bf16_f32 v64, v58, v59
	v_add_co_u32_e32 v58, vcc, s6, v150
	v_cvt_pk_bf16_f32 v70, v70, v71
	v_cvt_pk_bf16_f32 v71, v72, v73
	v_cvt_pk_bf16_f32 v72, v66, v67
	v_lshl_add_u64 v[66:67], v[150:151], 0, s[16:17]
	v_addc_co_u32_e32 v59, vcc, 0, v151, vcc
	v_cvt_pk_bf16_f32 v46, v46, v47
	v_cvt_pk_bf16_f32 v47, v48, v49
	v_cvt_pk_bf16_f32 v48, v42, v43
	v_cvt_pk_bf16_f32 v49, v44, v45
	s_mov_b32 s6, 0x240000
	global_store_dwordx4 v[66:67], v[46:49], off offset:256
	s_mov_b64 s[16:17], 0x240000
	v_cvt_pk_bf16_f32 v110, v110, v111
	v_add_co_u32_e32 v48, vcc, s6, v150
	v_cvt_pk_bf16_f32 v111, v112, v113
	v_cvt_pk_bf16_f32 v112, v106, v107
	v_or_b32_e32 v106, 16, v146
	v_lshl_add_u64 v[46:47], v[150:151], 0, s[16:17]
	v_addc_co_u32_e32 v49, vcc, 0, v151, vcc
	v_cvt_pk_bf16_f32 v30, v30, v31
	v_cvt_pk_bf16_f32 v31, v32, v33
	v_cvt_pk_bf16_f32 v32, v26, v27
	v_cvt_pk_bf16_f32 v33, v28, v29
	s_mov_b32 s6, 0x280000
	v_ashrrev_i32_e32 v107, 31, v106
	v_cvt_pk_bf16_f32 v94, v94, v95
	v_cvt_pk_bf16_f32 v95, v96, v97
	v_cvt_pk_bf16_f32 v96, v90, v91
	v_or_b32_e32 v90, 32, v146
	global_store_dwordx4 v[46:47], v[30:33], off offset:256
	s_mov_b64 s[16:17], 0x280000
	v_cvt_pk_bf16_f32 v113, v108, v109
	v_add_co_u32_e32 v32, vcc, s6, v150
	v_lshlrev_b64 v[106:107], 14, v[106:107]
	v_ashrrev_i32_e32 v91, 31, v90
	v_cvt_pk_bf16_f32 v78, v78, v79
	v_cvt_pk_bf16_f32 v79, v80, v81
	v_cvt_pk_bf16_f32 v80, v74, v75
	v_or_b32_e32 v74, 48, v146
	v_lshl_add_u64 v[30:31], v[150:151], 0, s[16:17]
	v_addc_co_u32_e32 v33, vcc, 0, v151, vcc
	v_cvt_pk_bf16_f32 v14, v14, v15
	v_cvt_pk_bf16_f32 v15, v16, v17
	v_cvt_pk_bf16_f32 v16, v10, v11
	v_cvt_pk_bf16_f32 v17, v12, v13
	global_store_dwordx4 v[150:151], v[110:113], off offset:256
	v_cvt_pk_bf16_f32 v97, v92, v93
	v_lshlrev_b64 v[90:91], 14, v[90:91]
	v_lshl_add_u64 v[110:111], v[148:149], 0, v[106:107]
	v_ashrrev_i32_e32 v75, 31, v74
	global_store_dwordx4 v[30:31], v[14:17], off offset:256
	global_store_dwordx4 v[110:111], v[94:97], off offset:256
	v_cvt_pk_bf16_f32 v81, v76, v77
	v_add_co_u32_e32 v16, vcc, s33, v150
	v_lshl_add_u64 v[94:95], v[148:149], 0, v[90:91]
	v_lshlrev_b64 v[74:75], 14, v[74:75]
	s_mov_b64 s[16:17], 0x2c0000
	v_addc_co_u32_e32 v17, vcc, 0, v151, vcc
	v_cvt_pk_bf16_f32 v126, v126, v127
	v_cvt_pk_bf16_f32 v127, v128, v129
	v_cvt_pk_bf16_f32 v128, v122, v123
	v_cvt_pk_bf16_f32 v129, v124, v125
	v_cvt_pk_bf16_f32 v106, v118, v119
	v_cvt_pk_bf16_f32 v107, v120, v121
	v_cvt_pk_bf16_f32 v108, v114, v115
	v_cvt_pk_bf16_f32 v109, v116, v117
	v_cvt_pk_bf16_f32 v90, v102, v103
	v_cvt_pk_bf16_f32 v91, v104, v105
	v_cvt_pk_bf16_f32 v92, v98, v99
	v_cvt_pk_bf16_f32 v93, v100, v101
	global_store_dwordx4 v[94:95], v[78:81], off offset:256
	v_cvt_pk_bf16_f32 v76, v82, v83
	v_cvt_pk_bf16_f32 v77, v84, v85
	v_lshl_add_u64 v[78:79], v[148:149], 0, v[74:75]
	v_cvt_pk_bf16_f32 v74, v86, v87
	v_cvt_pk_bf16_f32 v75, v88, v89
	v_cvt_pk_bf16_f32 v73, v68, v69
	v_cvt_pk_bf16_f32 v65, v60, v61
	v_cvt_pk_bf16_f32 v42, v54, v55
	v_cvt_pk_bf16_f32 v43, v56, v57
	v_cvt_pk_bf16_f32 v44, v50, v51
	v_cvt_pk_bf16_f32 v45, v52, v53
	v_cvt_pk_bf16_f32 v26, v38, v39
	v_cvt_pk_bf16_f32 v27, v40, v41
	v_cvt_pk_bf16_f32 v28, v34, v35
	v_cvt_pk_bf16_f32 v29, v36, v37
	v_lshl_add_u64 v[14:15], v[150:151], 0, s[16:17]
	v_cvt_pk_bf16_f32 v10, v22, v23
	v_cvt_pk_bf16_f32 v11, v24, v25
	v_cvt_pk_bf16_f32 v12, v18, v19
	v_cvt_pk_bf16_f32 v13, v20, v21
	v_cvt_pk_bf16_f32 v6, v6, v7
	v_cvt_pk_bf16_f32 v7, v8, v9
	v_cvt_pk_bf16_f32 v8, v2, v3
	v_cvt_pk_bf16_f32 v9, v4, v5
	s_and_b64 vcc, exec, s[0:1]
	s_mov_b32 s46, s8
	s_mov_b32 s6, s10
	s_mov_b64 s[16:17], s[14:15]
	s_mov_b64 s[18:19], s[12:13]
	s_mov_b32 s39, 0xb2a5705f
	s_mov_b32 s38, 0x42ce8ed0
	s_mov_b64 s[52:53], 0x41000
	global_store_dwordx4 v[150:151], v[126:129], off
	global_store_dwordx4 v[110:111], v[106:109], off
	global_store_dwordx4 v[94:95], v[90:93], off
	global_store_dwordx4 v[78:79], v[74:77], off
	global_store_dwordx4 v[78:79], v[70:73], off offset:256
	global_store_dwordx4 v[58:59], v[62:65], off
	global_store_dwordx4 v[48:49], v[42:45], off
	global_store_dwordx4 v[32:33], v[26:29], off
	global_store_dwordx4 v[16:17], v[10:13], off
	global_store_dwordx4 v[14:15], v[6:9], off offset:256
	s_cbranch_vccz .LBB0_195
	s_waitcnt vmcnt(0)
	s_cmpk_gt_u32 s25, 0xff
	s_cbranch_scc1 .LBB0_206
	s_barrier

; #define LAS __attribute__((address_space(3)))
; __device__ NOINL void mlstm_unit(unsigned char* ws, const float* cwq, LAS unsigned char* lds, int unit, int wv) {
;     ...
;     const int isk = tid >> 8, run = (tid >> 5) & 7, d8 = tid & 31;
;     const int colA = (isk ? C_MLK : C_MLQ) + hd * 256 + d8 * 8, cch = (isk ? 1024 : 0) + hd * 256 + d8 * 8;
;     f32x4 cw[4][2];
; #pragma unroll
;     for (int kk = 0; kk < 4; ++kk) { cw[kk][0] = *(const f32x4*)(cwq + kk * 2048 + cch); cw[kk][1] = *(const f32x4*)(cwq + kk * 2048 + cch + 4); }
;     const int vrow = tid >> 3, v8 = tid & 7;
;     u32x4 xr[11], vpre, opre; float ipre = 0.f, fpre = 0.f;
;     ...
;     __syncthreads();
;     for (int i = tid; i < 64 * 132; i += NTHR) ((LAS unsigned*)Cb)[i] = 0u;
.LBB0_216:
	s_lshl_b32 s0, s57, 5
	s_and_b32 s0, s0, 0xe0
	s_ashr_i32 s1, s57, 3
	s_add_i32 s2, s0, s1
	v_readlane_b32 s0, v254, 32
	v_readlane_b32 s1, v254, 33
	s_and_b64 s[0:1], s[0:1], exec
	v_readlane_b32 s68, v254, 18
	s_cselect_b32 s10, s2, s57
	v_readlane_b32 s69, v254, 19
	s_mov_b64 s[0:1], s[80:81]
	v_mov_b32_e32 v92, v236
	s_movk_i32 s2, 0x100
	s_bfe_u32 s37, s10, 0x20002
	v_and_b32_e32 v95, 31, v92
	v_cmp_gt_u32_e64 s[2:3], s2, v92
	v_mov_b32_e32 v1, 0x400
	s_lshl_b32 s36, s37, 8
	v_lshlrev_b32_e32 v93, 3, v95
	v_cndmask_b32_e64 v1, v1, 0, s[2:3]
	v_or3_b32 v1, s36, v1, v93
	v_lshlrev_b32_e32 v2, 2, v1
	v_mov_b32_e32 v3, v0
	v_lshl_add_u64 v[2:3], s[0:1], 0, v[2:3]
	v_add_co_u32_e32 v16, vcc, s40, v2
	global_load_dwordx4 v[4:7], v[2:3], off
	global_load_dwordx4 v[8:11], v[2:3], off offset:16
	v_addc_co_u32_e32 v17, vcc, 0, v3, vcc
	v_add_co_u32_e32 v24, vcc, 0x4000, v2
	global_load_dwordx4 v[12:15], v[16:17], off
	s_nop 0
	global_load_dwordx4 v[16:19], v[16:17], off offset:16
	v_addc_co_u32_e32 v25, vcc, 0, v3, vcc
	v_add_co_u32_e32 v2, vcc, 0x6000, v2
	global_load_dwordx4 v[20:23], v[24:25], off
	s_nop 0
	global_load_dwordx4 v[24:27], v[24:25], off offset:16
	v_addc_co_u32_e32 v3, vcc, 0, v3, vcc
	global_load_dwordx4 v[28:31], v[2:3], off
	global_load_dwordx4 v[32:35], v[2:3], off offset:16
	s_movk_i32 s0, 0xff
	s_movk_i32 s4, 0x2100
	v_readfirstlane_b32 s18, v92
	v_cmp_lt_u32_e64 s[0:1], s0, v92
	v_cmp_gt_i32_e32 vcc, s4, v92
	s_waitcnt lgkmcnt(0)
	s_barrier
	s_and_saveexec_b64 s[4:5], vcc
	s_cbranch_execz .LBB0_219
	v_readlane_b32 s6, v255, 17
	v_add_u32_e32 v1, 0xfffffe00, v92
	s_nop 0
	v_lshl_add_u32 v2, v92, 2, s6
	s_mov_b64 s[6:7], 0

; __device__ NOINL void mlstm_unit(unsigned char* ws, const float* cwq, LAS unsigned char* lds, int unit, int wv) {
;     ...
;     if (tid < 256) nvec[tid] = 0.f;
;     f32x4 cacc[8];
; #pragma unroll
;     for (int e = 0; e < 8; ++e) cacc[e] = (f32x4){0.f, 0.f, 0.f, 0.f};
;     ML_ISSUE(0);
;     if (wave == 0) ML_GATES(0);
.LBB0_219:
	s_or_b64 exec, exec, s[4:5]
	s_movk_i32 s4, 0x100
	v_cmp_gt_i32_e32 vcc, s4, v92
	s_and_saveexec_b64 s[4:5], vcc
	v_lshl_add_u32 v1, v92, 2, 0
	v_add_u32_e32 v1, 0x1d400, v1
	ds_write_b32 v1, v0
	s_or_b64 exec, exec, s[4:5]
	s_ashr_i32 s78, s10, 4
	v_mov_b32_e32 v1, 0x1400
	v_mov_b32_e32 v2, 0x1000
	s_ashr_i32 s79, s78, 31
	v_cndmask_b32_e64 v94, v1, v2, s[2:3]
	s_add_u32 s6, s68, 0x10e00000
	v_or3_b32 v1, s36, v94, v93
	v_lshrrev_b32_e32 v2, 2, v92
	s_addc_u32 s7, s69, 0
	v_and_b32_e32 v157, 56, v2
	v_lshlrev_b32_e32 v2, 1, v1
	v_mov_b32_e32 v3, v0
	s_waitcnt vmcnt(0)
	v_lshl_add_u64 v[72:73], s[6:7], 0, v[2:3]
	v_mov_b32_e32 v2, v0
	v_mov_b32_e32 v1, v0
	v_mov_b64_e32 v[38:39], v[2:3]
	s_lshl_b64 s[4:5], s[78:79], 11
	v_cmp_ne_u32_e32 vcc, 0, v157
	v_mov_b64_e32 v[36:37], v[0:1]
	s_and_saveexec_b64 s[8:9], vcc
	s_cbranch_execz .LBB0_223
	v_add_u32_e32 v36, -3, v157
	v_mov_b32_e32 v37, v0
	v_lshl_add_u64 v[36:37], s[4:5], 0, v[36:37]
	v_lshlrev_b64 v[36:37], 14, v[36:37]
	v_lshl_add_u64 v[36:37], v[72:73], 0, v[36:37]
	global_load_dwordx4 v[36:39], v[36:37], off
.LBB0_223:
	s_or_b64 exec, exec, s[8:9]
	v_mov_b64_e32 v[42:43], v[2:3]
	v_mov_b64_e32 v[40:41], v[0:1]
	s_and_saveexec_b64 s[8:9], vcc
	s_cbranch_execz .LBB0_225
	v_add_u32_e32 v2, -2, v157
	v_mov_b32_e32 v3, v0
	v_lshl_add_u64 v[2:3], s[4:5], 0, v[2:3]
	v_lshlrev_b64 v[2:3], 14, v[2:3]
	v_lshl_add_u64 v[2:3], v[72:73], 0, v[2:3]
	global_load_dwordx4 v[40:43], v[2:3], off
.LBB0_225:
	s_or_b64 exec, exec, s[8:9]
	v_mov_b32_e32 v2, v0
	v_mov_b32_e32 v3, v0
	v_mov_b32_e32 v1, v0
	v_mov_b64_e32 v[46:47], v[2:3]
	v_mov_b64_e32 v[44:45], v[0:1]
	s_and_saveexec_b64 s[8:9], vcc
	s_cbranch_execz .LBB0_227
	v_add_u32_e32 v2, -1, v157
	v_mov_b32_e32 v3, v0
	v_lshl_add_u64 v[2:3], s[4:5], 0, v[2:3]
	v_lshlrev_b64 v[2:3], 14, v[2:3]
	v_lshl_add_u64 v[2:3], v[72:73], 0, v[2:3]
	global_load_dwordx4 v[44:47], v[2:3], off
.LBB0_227:
	s_or_b64 exec, exec, s[8:9]
	v_ashrrev_i32_e32 v88, 3, v92
	v_ashrrev_i32_e32 v89, 31, v88
	v_lshl_add_u64 v[80:81], s[4:5], 0, v[88:89]
	v_lshlrev_b64 v[80:81], 14, v[80:81]
	v_lshl_add_u64 v[80:81], s[6:7], 0, v[80:81]
	s_lshl_b32 s70, s36, 1
	s_lshl_b32 s6, s10, 7
	v_and_b32_e32 v2, 7, v92
	s_and_b32 s96, s6, 0x180
	s_mov_b32 s97, s71
	v_lshl_add_u64 v[80:81], v[80:81], 0, s[70:71]
	v_or_b32_e32 v74, s4, v157
	v_mov_b32_e32 v75, s5
	v_lshlrev_b32_e32 v90, 4, v2
	v_mov_b32_e32 v91, v0
	v_lshl_add_u64 v[80:81], v[80:81], 0, s[96:97]
	v_lshlrev_b64 v[48:49], 14, v[74:75]
	v_or_b32_e32 v50, 1, v74
	v_mov_b32_e32 v51, s5
	v_or_b32_e32 v56, 2, v74
	v_mov_b32_e32 v57, s5
	v_or_b32_e32 v58, 3, v74
	v_mov_b32_e32 v59, s5
	v_or_b32_e32 v64, 4, v74
	v_mov_b32_e32 v65, s5
	v_or_b32_e32 v66, 5, v74
	v_mov_b32_e32 v67, s5
	v_or_b32_e32 v76, 6, v74
	v_mov_b32_e32 v77, s5
	v_or_b32_e32 v74, 7, v74
	v_lshl_add_u64 v[80:81], v[80:81], 0, v[90:91]
	v_lshlrev_b64 v[50:51], 14, v[50:51]
	v_lshlrev_b64 v[56:57], 14, v[56:57]
	v_lshlrev_b64 v[58:59], 14, v[58:59]
	v_lshlrev_b64 v[64:65], 14, v[64:65]
	v_lshlrev_b64 v[66:67], 14, v[66:67]
	v_lshlrev_b64 v[76:77], 14, v[76:77]
	v_lshlrev_b64 v[74:75], 14, v[74:75]
	v_add_co_u32_e32 v84, vcc, 0x3000, v80
	v_lshl_add_u64 v[48:49], v[72:73], 0, v[48:49]
	v_lshl_add_u64 v[52:53], v[72:73], 0, v[50:51]
	v_lshl_add_u64 v[56:57], v[72:73], 0, v[56:57]
	v_lshl_add_u64 v[60:61], v[72:73], 0, v[58:59]
	v_lshl_add_u64 v[64:65], v[72:73], 0, v[64:65]
	v_lshl_add_u64 v[68:69], v[72:73], 0, v[66:67]
	v_lshl_add_u64 v[76:77], v[72:73], 0, v[76:77]
	v_lshl_add_u64 v[78:79], v[72:73], 0, v[74:75]
	v_addc_co_u32_e32 v85, vcc, 0, v81, vcc
	global_load_dwordx4 v[48:51], v[48:49], off
	s_nop 0
	global_load_dwordx4 v[52:55], v[52:53], off
	s_nop 0
	global_load_dwordx4 v[56:59], v[56:57], off
	s_nop 0
	global_load_dwordx4 v[60:63], v[60:61], off
	s_nop 0
	global_load_dwordx4 v[64:67], v[64:65], off
	s_nop 0
	global_load_dwordx4 v[68:71], v[68:69], off
	s_nop 0
	global_load_dwordx4 v[72:75], v[76:77], off
	s_nop 0
	global_load_dwordx4 v[76:79], v[78:79], off
	s_nop 0
	global_load_dwordx4 v[80:83], v[84:85], off
	s_nop 0
	global_load_dwordx4 v[84:87], v[84:85], off offset:2048
	s_cmp_gt_u32 s18, 63
	s_cselect_b64 s[62:63], -1, 0
	s_cmp_lt_u32 s18, 64
	v_and_b32_e32 v1, 63, v92
	s_cselect_b64 s[66:67], -1, 0
	v_mov_b32_e32 v159, 0
	s_and_b64 vcc, exec, s[62:63]
	v_mov_b32_e32 v160, 0
	s_cbranch_vccnz .LBB0_229
	v_or_b32_e32 v96, s4, v1
	v_mov_b32_e32 v97, s5
	v_lshlrev_b64 v[96:97], 5, v[96:97]
	v_lshl_add_u64 v[96:97], s[68:69], 0, v[96:97]
	s_lshl_b32 s70, s37, 2
	v_lshl_add_u64 v[96:97], v[96:97], 0, s[70:71]
	s_mov_b64 s[4:5], 0x3d000000
	v_lshl_add_u64 v[98:99], v[96:97], 0, s[4:5]
	v_add_co_u32_e32 v96, vcc, 0x3d000000, v96
	s_nop 1
	v_addc_co_u32_e32 v97, vcc, 0, v97, vcc
	global_load_dword v160, v[96:97], off
	global_load_dword v159, v[98:99], off offset:16

; #define LAS __attribute__((address_space(3)))
; __device__ __forceinline__ unsigned cvt_pk_bf16(float lo, float hi) { f32x2_t f = {lo, hi}; bf16x2_t v = __builtin_convertvector(f, bf16x2_t); return __builtin_bit_cast(unsigned, v); }
; __device__ __forceinline__ float bflo(unsigned w) { return __uint_as_float(w << 16); }
; __device__ __forceinline__ float bfhi(unsigned w) { return __uint_as_float(w & 0xffff0000u); }
; __device__ __forceinline__ float sigmoidf_(float x) { return __builtin_amdgcn_rcpf(1.0f + __expf(-x)); }
; __device__ NOINL void mlstm_unit(unsigned char* ws, const float* cwq, LAS unsigned char* lds, int unit, int wv) {
;     ...
;             for (int kk = 0; kk < 4; ++kk) { const u32x4 a = xr[j + kk];
;                 o[0] += cw[kk][0][0] * bflo(a.x); o[1] += cw[kk][0][1] * bfhi(a.x); o[2] += cw[kk][0][2] * bflo(a.y); o[3] += cw[kk][0][3] * bfhi(a.y);
;                 o[4] += cw[kk][1][0] * bflo(a.z); o[5] += cw[kk][1][1] * bfhi(a.z); o[6] += cw[kk][1][2] * bflo(a.w); o[7] += cw[kk][1][3] * bfhi(a.w); }
;             const float sc = isk ? 0.0625f * wsv[tt] : 1.0f;
; #pragma unroll
;             for (int e = 0; e < 8; ++e) o[e] = o[e] * sigmoidf_(o[e]) * sc;
;             u32x4 w; w.x = cvt_pk_bf16(o[0], o[1]); w.y = cvt_pk_bf16(o[2], o[3]); w.z = cvt_pk_bf16(o[4], o[5]); w.w = cvt_pk_bf16(o[6], o[7]);
;             *(LAS u32x4*)((isk ? Kw : Qs) + tt * 528 + d8 * 16) = w;
;         }
;         *(LAS u32x4*)(Vs + vrow * 144 + v8 * 16) = vpre;
;         *(LAS u32x4*)(Os + vrow * 144 + v8 * 16) = opre;
;         __syncthreads();
;         if (ch + 1 < SEQ / 64) ML_ISSUE(ch + 1);
.LBB0_254:
	s_or_b64 exec, exec, s[78:79]
	v_pk_fma_f32 v[122:123], v[4:5], v[154:155], 0 op_sel_hi:[1,1,0]
	v_pk_fma_f32 v[126:127], v[8:9], v[126:127], 0 op_sel_hi:[1,1,0]
	v_pk_fma_f32 v[122:123], v[12:13], v[152:153], v[122:123]
	v_pk_fma_f32 v[126:127], v[16:17], v[148:149], v[126:127]
	v_pk_fma_f32 v[122:123], v[20:21], v[144:145], v[122:123]
	v_lshlrev_b32_e32 v144, 16, v76
	v_and_b32_e32 v145, 0xffff0000, v76
	v_pk_fma_f32 v[122:123], v[28:29], v[144:145], v[122:123]
	v_pk_fma_f32 v[126:127], v[24:25], v[128:129], v[126:127]
	v_lshlrev_b32_e32 v128, 16, v78
	v_and_b32_e32 v129, 0xffff0000, v78
	v_pk_fma_f32 v[126:127], v[32:33], v[128:129], v[126:127]
	v_mul_f32_e32 v128, 0xbfb8aa3b, v122
	v_mul_f32_e32 v129, 0xbfb8aa3b, v123
	v_exp_f32_e32 v128, v128
	v_exp_f32_e32 v129, v129
	v_pk_fma_f32 v[124:125], v[10:11], v[124:125], 0 op_sel_hi:[1,1,0]
	v_pk_fma_f32 v[142:143], v[6:7], v[142:143], 0 op_sel_hi:[1,1,0]
	v_pk_fma_f32 v[124:125], v[18:19], v[134:135], v[124:125]
	v_pk_fma_f32 v[142:143], v[14:15], v[150:151], v[142:143]
	v_pk_fma_f32 v[120:121], v[26:27], v[120:121], v[124:125]
	v_add_f32_e32 v124, 1.0, v128
	v_add_f32_e32 v125, 1.0, v129
	v_rcp_f32_e32 v124, v124
	v_rcp_f32_e32 v125, v125
	v_pk_fma_f32 v[130:131], v[22:23], v[130:131], v[142:143]
	v_lshlrev_b32_e32 v142, 16, v77
	v_and_b32_e32 v143, 0xffff0000, v77
	v_pk_fma_f32 v[130:131], v[30:31], v[142:143], v[130:131]
	v_pk_mul_f32 v[122:123], v[122:123], v[124:125]
	v_mul_f32_e32 v124, 0xbfb8aa3b, v130
	v_mul_f32_e32 v125, 0xbfb8aa3b, v131
	v_exp_f32_e32 v124, v124
	v_exp_f32_e32 v125, v125
	v_lshlrev_b32_e32 v128, 16, v79
	v_and_b32_e32 v129, 0xffff0000, v79
	v_add_f32_e32 v124, 1.0, v124
	v_add_f32_e32 v125, 1.0, v125
	v_rcp_f32_e32 v124, v124
	v_rcp_f32_e32 v125, v125
	v_pk_fma_f32 v[120:121], v[34:35], v[128:129], v[120:121]
	v_mul_f32_e32 v128, 0xbfb8aa3b, v126
	v_mul_f32_e32 v129, 0xbfb8aa3b, v127
	v_pk_mul_f32 v[124:125], v[130:131], v[124:125]
	v_mul_f32_e32 v130, 0xbfb8aa3b, v120
	v_mul_f32_e32 v131, 0xbfb8aa3b, v121
	v_exp_f32_e32 v128, v128
	v_exp_f32_e32 v129, v129
	v_exp_f32_e32 v130, v130
	v_exp_f32_e32 v131, v131
	v_add_f32_e32 v128, 1.0, v128
	v_add_f32_e32 v129, 1.0, v129
	v_add_f32_e32 v130, 1.0, v130
	v_add_f32_e32 v131, 1.0, v131
	v_rcp_f32_e32 v128, v128
	v_rcp_f32_e32 v129, v129
	v_rcp_f32_e32 v130, v130
	v_rcp_f32_e32 v131, v131
	s_cmp_eq_u32 s70, 31
	v_pk_mul_f32 v[126:127], v[126:127], v[128:129]
	v_pk_mul_f32 v[122:123], v[122:123], v[132:133] op_sel_hi:[1,0]
	v_pk_mul_f32 v[120:121], v[120:121], v[130:131]
	v_pk_mul_f32 v[124:125], v[124:125], v[132:133] op_sel_hi:[1,0]
	v_pk_mul_f32 v[126:127], v[126:127], v[132:133] op_sel_hi:[1,0]
	v_pk_mul_f32 v[128:129], v[120:121], v[132:133] op_sel_hi:[1,0]
	s_cselect_b64 s[78:79], -1, 0
	v_cvt_pk_bf16_f32 v120, v122, v123
	v_cvt_pk_bf16_f32 v121, v124, v125
	v_cvt_pk_bf16_f32 v122, v126, v127
	v_cvt_pk_bf16_f32 v123, v128, v129
	s_and_b64 vcc, exec, s[78:79]
	ds_write_b128 v231, v[120:123] offset:3696
	ds_write_b128 v181, v[80:83]
	ds_write_b128 v182, v[84:87]
	s_waitcnt lgkmcnt(0)
	s_barrier
	s_cbranch_vccnz .LBB0_257
	v_lshl_add_u64 v[76:77], s[68:69], 0, v[138:139]
	v_add_co_u32_e32 v36, vcc, 0x10ef4000, v76
	v_lshl_add_u64 v[78:79], s[68:69], 0, v[136:137]
	s_nop 0
	v_addc_co_u32_e32 v37, vcc, 0, v77, vcc
	v_add_co_u32_e32 v40, vcc, 0x10ef8000, v76
	s_nop 1
	v_addc_co_u32_e32 v41, vcc, 0, v77, vcc
	v_add_co_u32_e32 v44, vcc, 0x10efc000, v76
	global_load_dwordx4 v[36:39], v[36:37], off
	s_nop 0
	global_load_dwordx4 v[40:43], v[40:41], off
	v_addc_co_u32_e32 v45, vcc, 0, v77, vcc
	v_add_co_u32_e32 v48, vcc, 0x10f00000, v76
	s_nop 1
	v_addc_co_u32_e32 v49, vcc, 0, v77, vcc
	v_add_co_u32_e32 v52, vcc, 0x10f04000, v76
	global_load_dwordx4 v[44:47], v[44:45], off
	s_nop 0
	global_load_dwordx4 v[48:51], v[48:49], off
	v_addc_co_u32_e32 v53, vcc, 0, v77, vcc
	v_add_co_u32_e32 v56, vcc, 0x10f08000, v76
	s_nop 1
	v_addc_co_u32_e32 v57, vcc, 0, v77, vcc
	v_add_co_u32_e32 v60, vcc, 0x10f0c000, v76
	global_load_dwordx4 v[52:55], v[52:53], off
	s_nop 0
	global_load_dwordx4 v[56:59], v[56:57], off
	v_addc_co_u32_e32 v61, vcc, 0, v77, vcc
	v_add_co_u32_e32 v64, vcc, 0x10f10000, v76
	s_nop 1
	v_addc_co_u32_e32 v65, vcc, 0, v77, vcc
	v_add_co_u32_e32 v68, vcc, 0x10f14000, v76
	global_load_dwordx4 v[60:63], v[60:61], off
	s_nop 0
	global_load_dwordx4 v[64:67], v[64:65], off
	v_addc_co_u32_e32 v69, vcc, 0, v77, vcc
	v_add_co_u32_e32 v72, vcc, 0x10f18000, v76
	s_nop 1
	v_addc_co_u32_e32 v73, vcc, 0, v77, vcc
	v_add_co_u32_e32 v76, vcc, 0x10f1c000, v76
	global_load_dwordx4 v[68:71], v[68:69], off
	s_nop 0
	global_load_dwordx4 v[72:75], v[72:73], off
	v_addc_co_u32_e32 v77, vcc, 0, v77, vcc
	v_add_co_u32_e32 v84, vcc, 0x10f03000, v78
	s_nop 1
	v_addc_co_u32_e32 v85, vcc, 0, v79, vcc
	global_load_dwordx4 v[76:79], v[76:77], off
	s_nop 0
	global_load_dwordx4 v[80:83], v[84:85], off
	s_nop 0
	global_load_dwordx4 v[84:87], v[84:85], off offset:2048
	s_andn2_b64 vcc, exec, s[66:67]
	s_cbranch_vccnz .LBB0_257
	v_lshl_add_u64 v[120:121], s[68:69], 0, v[2:3]
	v_add_co_u32_e32 v120, vcc, 0x3d000000, v120
	s_nop 1
	v_addc_co_u32_e32 v121, vcc, 0, v121, vcc
	global_load_dword v160, v[120:121], off offset:2048
	global_load_dword v159, v[120:121], off offset:2064
; #define LAS __attribute__((address_space(3)))
; __device__ __forceinline__ bf16_t f2bf(float f) { return (bf16_t)(cvt_pk_bf16(f, 0.f) & 0xffffu); }
; __device__ __forceinline__ float bflo(unsigned w) { return __uint_as_float(w << 16); }
; __device__ __forceinline__ float bfhi(unsigned w) { return __uint_as_float(w & 0xffff0000u); }
; #define SHX(lane, v, m) shfl_idx(lane, (v), (lane) ^ (m))
; __device__ NOINL void mlstm_unit(unsigned char* ws, const float* cwq, LAS unsigned char* lds, int unit, int wv) {
;     ...
;             float dsum[4] = {0.f, 0.f, 0.f, 0.f};
;             const int ti = wave >> 1;
; #pragma unroll
;             for (int e = 0; e < 2; ++e) { const int si = (wave & 1) * 2 + e;
;                 f32x4 a = {0.f, 0.f, 0.f, 0.f};
; #pragma unroll
;                 for (int ks = 0; ks < 8; ++ks) { const bf16x8 qa = *(const LAS bf16x8*)(Qs + (ti * 16 + fr) * 528 + ks * 64 + fq * 16), kb = *(const LAS bf16x8*)(Kw + (si * 16 + fr) * 528 + ks * 64 + fq * 16);
;                     a = __builtin_amdgcn_mfma_f32_16x16x32_bf16(qa, kb, a, 0, 0, 0); }
;                 const int s = si * 16 + fr;
; #pragma unroll
;                 for (int j = 0; j < 4; ++j) { const int t = ti * 16 + 4 * fq + j; const float v = (s <= t) ? a[j] * erel[t] : 0.f; dsum[j] += v;
;                     *(LAS bf16_t*)(Ps + t * 144 + s * 2) = f2bf(v); } }
; #pragma unroll
;             for (int j = 0; j < 4; ++j) { float v = dsum[j]; v += SHX(lane, v, 1); v += SHX(lane, v, 2); v += SHX(lane, v, 4); v += SHX(lane, v, 8);
;                 if (fr == 0) denp[(ti * 16 + 4 * fq + j) * 2 + (wave & 1)] = v; }
;             const int t = tid >> 3, part = tid & 7;
;             float s = 0.f;
; #pragma unroll
;             for (int i = 0; i < 4; ++i) { const u32x4 qv = *(const LAS u32x4*)(Qs + t * 528 + part * 64 + i * 16); const LAS float* np = nvec + part * 32 + i * 8;
;                 s += bflo(qv.x) * np[0] + bfhi(qv.x) * np[1] + bflo(qv.y) * np[2] + bfhi(qv.y) * np[3] + bflo(qv.z) * np[4] + bfhi(qv.z) * np[5] + bflo(qv.w) * np[6] + bfhi(qv.w) * np[7]; }
.LBB0_257:
	v_add_u32_e32 v235, v167, v176
	ds_read_b128 v[124:127], v232
	ds_read_b128 v[128:131], v235 offset:33792
	ds_read_b128 v[132:135], v232 offset:64
	ds_read_b128 v[142:145], v235 offset:33856
	ds_read_b128 v[146:149], v232 offset:128
	ds_read_b128 v[150:153], v235 offset:33920
	ds_read_b128 v[192:195], v232 offset:192
	ds_read_b128 v[250:253], v235 offset:33984
	s_waitcnt lgkmcnt(6)
	v_mfma_f32_16x16x32_bf16 v[120:123], v[124:127], v[128:131], 0
	ds_read_b128 v[124:127], v232 offset:256
	ds_read_b128 v[128:131], v235 offset:34048
	s_waitcnt lgkmcnt(6)
	v_mfma_f32_16x16x32_bf16 v[120:123], v[132:135], v[142:145], v[120:123]
	ds_read_b128 v[132:135], v232 offset:320
	ds_read_b128 v[142:145], v235 offset:34112
	s_waitcnt lgkmcnt(6)
	v_mfma_f32_16x16x32_bf16 v[120:123], v[146:149], v[150:153], v[120:123]
	ds_read_b128 v[146:149], v232 offset:384
	ds_read_b128 v[150:153], v235 offset:34176
	s_waitcnt lgkmcnt(6)
	v_mfma_f32_16x16x32_bf16 v[120:123], v[192:195], v[250:253], v[120:123]
	ds_read_b128 v[192:195], v232 offset:448
	ds_read_b128 v[250:253], v235 offset:34240
	s_waitcnt lgkmcnt(6)
	v_mfma_f32_16x16x32_bf16 v[120:123], v[124:127], v[128:131], v[120:123]
	s_waitcnt lgkmcnt(4)
	v_mfma_f32_16x16x32_bf16 v[120:123], v[132:135], v[142:145], v[120:123]
	s_waitcnt lgkmcnt(2)
	v_mfma_f32_16x16x32_bf16 v[120:123], v[146:149], v[150:153], v[120:123]
	s_waitcnt lgkmcnt(0)
	v_mfma_f32_16x16x32_bf16 v[120:123], v[192:195], v[250:253], v[120:123]
	v_add_u32_e32 v235, v167, v177
	v_lshl_add_u32 v249, v168, 2, s36
	ds_read_b128 v[192:195], v249 offset:512
	ds_read_b128 v[124:127], v232
	ds_read_b128 v[128:131], v235 offset:33792
	ds_read_b128 v[132:135], v232 offset:64
	ds_read_b128 v[142:145], v235 offset:33856
	ds_read_b128 v[146:149], v232 offset:128
	ds_read_b128 v[150:153], v235 offset:33920
	s_waitcnt lgkmcnt(4)
	v_mfma_f32_16x16x32_bf16 v[250:253], v[124:127], v[128:131], 0
	ds_read_b128 v[124:127], v232 offset:192
	ds_read_b128 v[128:131], v235 offset:33984
	s_waitcnt lgkmcnt(4)
	v_mfma_f32_16x16x32_bf16 v[250:253], v[132:135], v[142:145], v[250:253]
	ds_read_b128 v[132:135], v232 offset:256
	ds_read_b128 v[142:145], v235 offset:34048
	s_waitcnt lgkmcnt(4)
	v_mfma_f32_16x16x32_bf16 v[250:253], v[146:149], v[150:153], v[250:253]
	ds_read_b128 v[146:149], v232 offset:320
	ds_read_b128 v[150:153], v235 offset:34112
	s_waitcnt lgkmcnt(4)
	v_mfma_f32_16x16x32_bf16 v[250:253], v[124:127], v[128:131], v[250:253]
	ds_read_b128 v[124:127], v232 offset:384
	ds_read_b128 v[128:131], v235 offset:34176
	s_waitcnt lgkmcnt(4)
	v_mfma_f32_16x16x32_bf16 v[250:253], v[132:135], v[142:145], v[250:253]
	ds_read_b128 v[132:135], v232 offset:448
	ds_read_b128 v[142:145], v235 offset:34240
	s_waitcnt lgkmcnt(4)
	v_mfma_f32_16x16x32_bf16 v[250:253], v[146:149], v[150:153], v[250:253]
	s_waitcnt lgkmcnt(2)
	v_mfma_f32_16x16x32_bf16 v[250:253], v[124:127], v[128:131], v[250:253]
	s_waitcnt lgkmcnt(0)
	v_mfma_f32_16x16x32_bf16 v[250:253], v[132:135], v[142:145], v[250:253]
	v_mul_f32_e32 v120, v120, v192
	v_mul_f32_e32 v121, v121, v193
	v_mul_f32_e32 v122, v122, v194
	v_mul_f32_e32 v123, v123, v195
	v_cndmask_b32_e64 v120, 0, v120, s[10:11]
	v_cndmask_b32_e64 v121, 0, v121, s[12:13]
	v_cndmask_b32_e64 v122, 0, v122, s[14:15]
	v_cndmask_b32_e64 v123, 0, v123, s[16:17]
	v_cvt_pk_bf16_f32 v154, v120, v120
	v_cvt_pk_bf16_f32 v155, v121, v121
	v_cvt_pk_bf16_f32 v156, v122, v122
	v_cvt_pk_bf16_f32 v158, v123, v123
	ds_write_b16 v233, v154
	ds_write_b16 v233, v155 offset:144
	ds_write_b16 v233, v156 offset:288
	ds_write_b16 v233, v158 offset:432
	v_mul_f32_e32 v250, v250, v192
	v_mul_f32_e32 v251, v251, v193
	v_mul_f32_e32 v252, v252, v194
	v_mul_f32_e32 v253, v253, v195
	v_cndmask_b32_e64 v250, 0, v250, s[18:19]
	v_cndmask_b32_e64 v251, 0, v251, s[20:21]
	v_cndmask_b32_e64 v252, 0, v252, s[22:23]
	v_cndmask_b32_e64 v253, 0, v253, s[24:25]
	v_cvt_pk_bf16_f32 v154, v250, v250
	v_cvt_pk_bf16_f32 v155, v251, v251
	v_cvt_pk_bf16_f32 v156, v252, v252
	v_cvt_pk_bf16_f32 v158, v253, v253
	ds_write_b16 v234, v154
	ds_write_b16 v234, v155 offset:144
	ds_write_b16 v234, v156 offset:288
	ds_write_b16 v234, v158 offset:432
	v_add_f32_e32 v120, v120, v250
	v_add_f32_e32 v121, v121, v251
	v_add_f32_e32 v122, v122, v252
	v_add_f32_e32 v123, v123, v253
	v_add_f32_dpp v120, v120, v120 quad_perm:[1,0,3,2] row_mask:0xf bank_mask:0xf
	v_add_f32_dpp v121, v121, v121 quad_perm:[1,0,3,2] row_mask:0xf bank_mask:0xf
	v_add_f32_dpp v122, v122, v122 quad_perm:[1,0,3,2] row_mask:0xf bank_mask:0xf
	v_add_f32_dpp v123, v123, v123 quad_perm:[1,0,3,2] row_mask:0xf bank_mask:0xf
	v_add_f32_dpp v120, v120, v120 quad_perm:[2,3,0,1] row_mask:0xf bank_mask:0xf
	v_add_f32_dpp v121, v121, v121 quad_perm:[2,3,0,1] row_mask:0xf bank_mask:0xf
	v_add_f32_dpp v122, v122, v122 quad_perm:[2,3,0,1] row_mask:0xf bank_mask:0xf
	v_add_f32_dpp v123, v123, v123 quad_perm:[2,3,0,1] row_mask:0xf bank_mask:0xf
	v_add_f32_dpp v120, v120, v120 row_half_mirror row_mask:0xf bank_mask:0xf
	v_add_f32_dpp v121, v121, v121 row_half_mirror row_mask:0xf bank_mask:0xf
	v_add_f32_dpp v122, v122, v122 row_half_mirror row_mask:0xf bank_mask:0xf
	v_add_f32_dpp v123, v123, v123 row_half_mirror row_mask:0xf bank_mask:0xf
	v_add_f32_dpp v120, v120, v120 row_mirror row_mask:0xf bank_mask:0xf
	v_add_f32_dpp v121, v121, v121 row_mirror row_mask:0xf bank_mask:0xf
	v_add_f32_dpp v122, v122, v122 row_mirror row_mask:0xf bank_mask:0xf
	v_add_f32_dpp v123, v123, v123 row_mirror row_mask:0xf bank_mask:0xf
	v_add_u32_e32 v154, s56, v178
	v_add_u32_e32 v155, s56, v179
	s_and_saveexec_b64 s[96:97], s[2:3]
	ds_write_b32 v154, v120
	ds_write_b32 v183, v121
	ds_write_b32 v155, v122
	ds_write_b32 v184, v123
	s_or_b64 exec, exec, s[96:97]
	ds_read_b128 v[120:123], v185
	ds_read_b128 v[124:127], v185 offset:16
	ds_read_b128 v[130:133], v185 offset:32
	ds_read_b128 v[142:145], v185 offset:48
	ds_read_b128 v[146:149], v186
	ds_read_b128 v[150:153], v186 offset:16
	ds_read_b128 v[250:253], v186 offset:32
	ds_read_b128 v[192:195], v186 offset:48
	s_waitcnt lgkmcnt(0)
; __device__ NOINL void mlstm_unit(unsigned char* ws, const float* cwq, LAS unsigned char* lds, int unit, int wv) {
;     ...
;             const int t = tid >> 3, part = tid & 7;
;             float s = 0.f;
; #pragma unroll
;             for (int i = 0; i < 4; ++i) { const u32x4 qv = *(const LAS u32x4*)(Qs + t * 528 + part * 64 + i * 16); const LAS float* np = nvec + part * 32 + i * 8;
;                 s += bflo(qv.x) * np[0] + bfhi(qv.x) * np[1] + bflo(qv.y) * np[2] + bfhi(qv.y) * np[3] + bflo(qv.z) * np[4] + bfhi(qv.z) * np[5] + bflo(qv.w) * np[6] + bfhi(qv.w) * np[7]; }
;             s += SHX(lane, s, 1); s += SHX(lane, s, 2); s += SHX(lane, s, 4);
;             if (part == 0) deni[t] = s;
;         }
;         __syncthreads();
;         {
;             const int ti = wave >> 1;
; #pragma unroll
;             for (int e = 0; e < 2; ++e) { const int vi = (wave & 1) * 2 + e;
;                 f32x4 ai = {0.f, 0.f, 0.f, 0.f}, ap = {0.f, 0.f, 0.f, 0.f};
; #pragma unroll
;                 for (int ks = 0; ks < 8; ++ks) { const bf16x8 qa = *(const LAS bf16x8*)(Qs + (ti * 16 + fr) * 528 + ks * 64 + fq * 16), cb = *(const LAS bf16x8*)(Cb + (vi * 16 + fr) * 528 + ks * 64 + fq * 16);
;                     ai = __builtin_amdgcn_mfma_f32_16x16x32_bf16(qa, cb, ai, 0, 0, 0); }
; #pragma unroll
;                 for (int ks = 0; ks < 2; ++ks) { const bf16x8 pa = *(const LAS bf16x8*)(Ps + (ti * 16 + fr) * 144 + ks * 64 + fq * 16);
;                     const s16x4 lo = tr_read16(Vs + (32 * ks + 8 * fq + q4) * 144 + vi * 32 + 8 * p4);
;                     const s16x4 hi = tr_read16(Vs + (32 * ks + 8 * fq + 4 + q4) * 144 + vi * 32 + 8 * p4);
;                     const bf16x8 vf = __builtin_shufflevector(lo, hi, 0, 1, 2, 3, 4, 5, 6, 7);
;                     ap = __builtin_amdgcn_mfma_f32_16x16x32_bf16(pa, vf, ap, 0, 0, 0); }
; #pragma unroll
;                 for (int j = 0; j < 4; ++j) { const int t = ti * 16 + 4 * fq + j, v = vi * 16 + fr;
;                     const float ei = eint[t], num = ei * ai[j] + ap[j], den = ei * deni[t] + denp[t * 2] + denp[t * 2 + 1];
;                     const float h = num * __builtin_amdgcn_rcpf(fmaxf(fabsf(den), 1.0f));
;                     const float og = bf2f(*(const LAS bf16_t*)(Os + t * 144 + v * 2));
;                     *(LAS bf16_t*)(Hs + t * 144 + v * 2) = f2bf(h * sigmoidf_(og)); } }
	v_lshlrev_b32_e32 v129, 16, v120
	v_and_b32_e32 v120, 0xffff0000, v120
	v_mul_f32_e32 v120, v147, v120
	v_fmac_f32_e32 v120, v146, v129
	v_lshlrev_b32_e32 v129, 16, v121
	v_fmac_f32_e32 v120, v148, v129
	v_and_b32_e32 v121, 0xffff0000, v121
	v_fmac_f32_e32 v120, v149, v121
	v_lshlrev_b32_e32 v121, 16, v122
	v_fmac_f32_e32 v120, v150, v121
	v_and_b32_e32 v121, 0xffff0000, v122
	v_fmac_f32_e32 v120, v151, v121
	v_lshlrev_b32_e32 v121, 16, v123
	v_fmac_f32_e32 v120, v152, v121
	v_and_b32_e32 v121, 0xffff0000, v123
	v_fmac_f32_e32 v120, v153, v121
	v_and_b32_e32 v121, 0xffff0000, v124
	v_add_f32_e32 v129, 0, v120
	v_lshlrev_b32_e32 v120, 16, v124
	v_mul_f32_e32 v124, v251, v121
	v_fmac_f32_e32 v124, v250, v120
	v_lshlrev_b32_e32 v120, 16, v125
	v_fmac_f32_e32 v124, v252, v120
	v_and_b32_e32 v120, 0xffff0000, v125
	v_fmac_f32_e32 v124, v253, v120
	v_lshlrev_b32_e32 v120, 16, v126
	v_fmac_f32_e32 v124, v192, v120
	v_and_b32_e32 v120, 0xffff0000, v126
	v_fmac_f32_e32 v124, v193, v120
	v_lshlrev_b32_e32 v120, 16, v127
	v_fmac_f32_e32 v124, v194, v120
	v_and_b32_e32 v120, 0xffff0000, v127
	v_fmac_f32_e32 v124, v195, v120
	ds_read_b128 v[120:123], v186 offset:64
	v_add_f32_e32 v129, v129, v124
	v_lshlrev_b32_e32 v134, 16, v130
	v_and_b32_e32 v130, 0xffff0000, v130
	ds_read_b128 v[124:127], v186 offset:80
	s_waitcnt lgkmcnt(0)
	v_mul_f32_e32 v130, v121, v130
	v_fmac_f32_e32 v130, v120, v134
	v_lshlrev_b32_e32 v120, 16, v131
	v_fmac_f32_e32 v130, v122, v120
	v_and_b32_e32 v120, 0xffff0000, v131
	v_fmac_f32_e32 v130, v123, v120
	v_lshlrev_b32_e32 v120, 16, v132
	v_fmac_f32_e32 v130, v124, v120
	v_and_b32_e32 v120, 0xffff0000, v132
	v_fmac_f32_e32 v130, v125, v120
	v_lshlrev_b32_e32 v120, 16, v133
	v_fmac_f32_e32 v130, v126, v120
	v_and_b32_e32 v120, 0xffff0000, v133
	v_fmac_f32_e32 v130, v127, v120
	ds_read_b128 v[120:123], v186 offset:96
	ds_read_b128 v[124:127], v186 offset:112
	v_and_b32_e32 v131, 0xffff0000, v142
	v_add_f32_e32 v129, v129, v130
	v_lshlrev_b32_e32 v130, 16, v142
	s_waitcnt lgkmcnt(0)
	v_mul_f32_e32 v121, v121, v131
	v_fmac_f32_e32 v121, v120, v130
	v_lshlrev_b32_e32 v120, 16, v143
	v_fmac_f32_e32 v121, v122, v120
	v_and_b32_e32 v120, 0xffff0000, v143
	v_fmac_f32_e32 v121, v123, v120
	v_lshlrev_b32_e32 v120, 16, v144
	v_fmac_f32_e32 v121, v124, v120
	v_and_b32_e32 v120, 0xffff0000, v144
	v_fmac_f32_e32 v121, v125, v120
	v_lshlrev_b32_e32 v120, 16, v145
	v_fmac_f32_e32 v121, v126, v120
	v_and_b32_e32 v120, 0xffff0000, v145
	v_fmac_f32_e32 v121, v127, v120
	v_add_f32_e32 v120, v129, v121
	s_nop 1
	v_add_f32_dpp v120, v120, v120 quad_perm:[1,0,3,2] row_mask:0xf bank_mask:0xf
	s_nop 1
	v_add_f32_dpp v120, v120, v120 quad_perm:[2,3,0,1] row_mask:0xf bank_mask:0xf
	s_nop 1
	v_add_f32_dpp v120, v120, v120 row_half_mirror row_mask:0xf bank_mask:0xf
	s_and_saveexec_b64 s[96:97], s[4:5]
	ds_write_b32 v175, v120
	s_or_b64 exec, exec, s[96:97]
	v_lshl_add_u32 v128, v168, 2, s36
	s_waitcnt lgkmcnt(0)
	s_barrier
	ds_read_b128 v[120:123], v187
	ds_read_b64_tr_b16 v[126:127], v196 offset:576
	ds_read_b64_tr_b16 v[124:125], v196
	ds_read_b128 v[130:133], v187 offset:64
	ds_read_b64_tr_b16 v[142:143], v197
	ds_read_b64_tr_b16 v[144:145], v197 offset:576
	ds_read_b128 v[146:149], v232
	v_add_u32_e32 v129, v173, v176
	ds_read_b128 v[150:153], v129
	s_waitcnt lgkmcnt(0)
	v_mfma_f32_16x16x32_bf16 v[120:123], v[120:123], v[124:127], 0
	s_add_i32 s37, 0, 0x1de80
	v_mfma_f32_16x16x32_bf16 v[120:123], v[130:133], v[142:145], v[120:123]
	ds_read_b128 v[142:145], v232 offset:64
	ds_read_b128 v[192:195], v232 offset:128
	ds_read_b128 v[132:135], v232 offset:448
	ds_read_b128 v[124:127], v180
	v_mfma_f32_16x16x32_bf16 v[146:149], v[146:149], v[150:153], 0
	ds_read_b128 v[150:153], v129 offset:64
	ds_read_b128 v[250:253], v129 offset:128
	s_waitcnt lgkmcnt(0)
	v_mfma_f32_16x16x32_bf16 v[142:145], v[142:145], v[150:153], v[146:149]
	s_nop 3
	ds_read_b128 v[146:149], v232 offset:192
	ds_read_b128 v[150:153], v232 offset:256
	v_mfma_f32_16x16x32_bf16 v[142:145], v[192:195], v[250:253], v[142:145]
	ds_read_b128 v[192:195], v129 offset:192
	ds_read_b128 v[250:253], v129 offset:256
	s_waitcnt lgkmcnt(0)
	v_mfma_f32_16x16x32_bf16 v[142:145], v[146:149], v[192:195], v[142:145]
	ds_read_b128 v[146:149], v232 offset:320
	ds_read_b128 v[192:195], v232 offset:384
	v_mfma_f32_16x16x32_bf16 v[142:145], v[150:153], v[250:253], v[142:145]
	ds_read_b128 v[150:153], v129 offset:320
	ds_read_b128 v[250:253], v129 offset:384
	s_waitcnt lgkmcnt(0)
	v_mfma_f32_16x16x32_bf16 v[142:145], v[146:149], v[150:153], v[142:145]
	ds_read_b128 v[146:149], v129 offset:448
	ds_read_b128 v[128:131], v128 offset:256
	v_add_u32_e32 v150, s37, v178
	ds_read_b128 v[150:153], v150
	ds_read_u16 v154, v198
	ds_read_u16 v155, v198 offset:144
	ds_read_u16 v156, v198 offset:288
	ds_read_u16 v158, v202 offset:432
	v_mfma_f32_16x16x32_bf16 v[142:145], v[192:195], v[250:253], v[142:145]
	v_add_u32_e32 v195, v173, v177
	s_waitcnt lgkmcnt(0)
	v_fma_f32 v124, v128, v124, v150
	v_lshlrev_b32_e32 v150, 16, v154
	v_mul_f32_e32 v150, 0xbfb8aa3b, v150
	v_exp_f32_e32 v150, v150
	v_add_f32_e32 v124, v124, v151
	v_max_f32_e64 v124, |v124|, 1.0
	v_mfma_f32_16x16x32_bf16 v[132:135], v[132:135], v[146:149], v[142:145]
	v_rcp_f32_e32 v154, v124
	v_add_f32_e32 v124, 1.0, v150
	v_rcp_f32_e32 v124, v124
	s_nop 4
	v_fma_f32 v120, v132, v128, v120
	v_mul_f32_e32 v120, v120, v154
	v_mul_f32_e32 v120, v120, v124
	v_fma_f32 v124, v129, v125, v152
	v_lshlrev_b32_e32 v125, 16, v155
	v_mul_f32_e32 v125, 0xbfb8aa3b, v125
	v_exp_f32_e32 v125, v125
	v_cvt_pk_bf16_f32 v120, v120, s0
	v_add_f32_e32 v124, v124, v153
	v_max_f32_e64 v124, |v124|, 1.0
	ds_write_b16 v199, v120
	v_fma_f32 v120, v133, v129, v121
	v_add_u32_e32 v121, s37, v179
	v_rcp_f32_e32 v155, v124
	v_add_f32_e32 v124, 1.0, v125
	ds_read_b128 v[142:145], v121
	ds_read_u16 v192, v202
	ds_read_u16 v193, v202 offset:144
	ds_read_u16 v121, v198 offset:432
	v_rcp_f32_e32 v124, v124
	v_lshlrev_b32_e32 v125, 16, v156
	v_mul_f32_e32 v125, 0xbfb8aa3b, v125
	v_mul_f32_e32 v120, v120, v155
	v_exp_f32_e32 v125, v125
	v_mul_f32_e32 v120, v120, v124
	s_waitcnt lgkmcnt(0)
; #define LAS __attribute__((address_space(3)))
; __device__ NOINL void mlstm_unit(unsigned char* ws, const float* cwq, LAS unsigned char* lds, int unit, int wv) {
;     ...
;                 for (int j = 0; j < 4; ++j) { const int t = ti * 16 + 4 * fq + j, v = vi * 16 + fr;
;                     const float ei = eint[t], num = ei * ai[j] + ap[j], den = ei * deni[t] + denp[t * 2] + denp[t * 2 + 1];
;                     const float h = num * __builtin_amdgcn_rcpf(fmaxf(fabsf(den), 1.0f));
;                     const float og = bf2f(*(const LAS bf16_t*)(Os + t * 144 + v * 2));
;                     *(LAS bf16_t*)(Hs + t * 144 + v * 2) = f2bf(h * sigmoidf_(og)); } }
;         }
;         __syncthreads();
;         {
;             const float dc = wsv[192];
;             const int vi = wave >> 1;
;             *(u32x4*)(YML + (tokbase + tc0 + vrow) * 1024 + hd * 256 + vs * 64 + v8 * 8) = *(const LAS u32x4*)(Hs + vrow * 144 + v8 * 16);
;             bf16x8 va[2];
; #pragma unroll
;             for (int ks = 0; ks < 2; ++ks) { const s16x4 lo = tr_read16(Vs + (32 * ks + 8 * fq + q4) * 144 + vi * 32 + 8 * p4), hi = tr_read16(Vs + (32 * ks + 8 * fq + 4 + q4) * 144 + vi * 32 + 8 * p4);
;                 va[ks] = __builtin_shufflevector(lo, hi, 0, 1, 2, 3, 4, 5, 6, 7); }
;             const short one_bf = (short)0x3F80;
;             const bf16x8 ones = {one_bf, one_bf, one_bf, one_bf, one_bf, one_bf, one_bf, one_bf};
; #pragma unroll
;             for (int e = 0; e < 8; ++e) { const int ki = (wave & 1) * 8 + e;
;                 cacc[e] *= dc;
;                 f32x4 na = {0.f, 0.f, 0.f, 0.f};
; #pragma unroll
;                 for (int ks = 0; ks < 2; ++ks) { const s16x4 lo = tr_read16(Kw + (32 * ks + 8 * fq + q4) * 528 + ki * 32 + 8 * p4), hi = tr_read16(Kw + (32 * ks + 8 * fq + 4 + q4) * 528 + ki * 32 + 8 * p4);
;                     const bf16x8 kb = __builtin_shufflevector(lo, hi, 0, 1, 2, 3, 4, 5, 6, 7);
;                     cacc[e] = __builtin_amdgcn_mfma_f32_16x16x32_bf16(va[ks], kb, cacc[e], 0, 0, 0);
;                     na = __builtin_amdgcn_mfma_f32_16x16x32_bf16(ones, kb, na, 0, 0, 0); }
; #pragma unroll
;                 for (int j = 0; j < 4; ++j) *(LAS bf16_t*)(Cb + (vi * 16 + 4 * fq + j) * 528 + (ki * 16 + fr) * 2) = f2bf(cacc[e][j]);
;                 if (vi == 0 && fq == 0) nvec[ki * 16 + fr] = dc * nvec[ki * 16 + fr] + na[0];
	v_fma_f32 v124, v130, v126, v142
	v_lshlrev_b32_e32 v121, 16, v121
	v_add_f32_e32 v124, v124, v143
	v_mul_f32_e32 v121, 0xbfb8aa3b, v121
	v_cvt_pk_bf16_f32 v120, v120, s0
	v_max_f32_e64 v124, |v124|, 1.0
	v_exp_f32_e32 v121, v121
	v_rcp_f32_e32 v156, v124
	v_add_f32_e32 v124, 1.0, v125
	ds_write_b16 v199, v120 offset:144
	v_fma_f32 v120, v134, v130, v122
	v_fma_f32 v122, v131, v127, v144
	v_rcp_f32_e32 v124, v124
	v_add_f32_e32 v122, v122, v145
	v_max_f32_e64 v122, |v122|, 1.0
	v_rcp_f32_e32 v194, v122
	v_add_f32_e32 v121, 1.0, v121
	v_mul_f32_e32 v120, v120, v156
	v_rcp_f32_e32 v121, v121
	v_mul_f32_e32 v120, v120, v124
	v_cvt_pk_bf16_f32 v120, v120, s0
	v_fmac_f32_e32 v123, v135, v131
	ds_write_b16 v199, v120 offset:288
	v_mul_f32_e32 v120, v123, v194
	v_mul_f32_e32 v120, v120, v121
	v_cvt_pk_bf16_f32 v120, v120, s0
	ds_write_b16 v199, v120 offset:432
	ds_read_b128 v[120:123], v187
	ds_read_b128 v[124:127], v187 offset:64
	ds_read_b64_tr_b16 v[132:133], v200
	ds_read_b64_tr_b16 v[134:135], v200 offset:576
	ds_read_b64_tr_b16 v[142:143], v201
	ds_read_b64_tr_b16 v[144:145], v201 offset:576
	s_waitcnt lgkmcnt(0)
	v_mfma_f32_16x16x32_bf16 v[120:123], v[120:123], v[132:135], 0
	ds_read_b128 v[132:135], v232
	ds_read_b128 v[146:149], v232 offset:64
	v_mfma_f32_16x16x32_bf16 v[120:123], v[124:127], v[142:145], v[120:123]
	ds_read_b128 v[124:127], v195
	ds_read_b128 v[142:145], v195 offset:64
	s_waitcnt lgkmcnt(0)
	v_mfma_f32_16x16x32_bf16 v[124:127], v[132:135], v[124:127], 0
	ds_read_b128 v[132:135], v232 offset:128
	ds_read_b128 v[150:153], v232 offset:192
	v_mfma_f32_16x16x32_bf16 v[124:127], v[146:149], v[142:145], v[124:127]
	ds_read_b128 v[142:145], v195 offset:128
	ds_read_b128 v[146:149], v195 offset:192
	s_waitcnt lgkmcnt(0)
	v_mfma_f32_16x16x32_bf16 v[124:127], v[132:135], v[142:145], v[124:127]
	ds_read_b128 v[132:135], v232 offset:256
	ds_read_b128 v[142:145], v232 offset:320
	v_mfma_f32_16x16x32_bf16 v[124:127], v[150:153], v[146:149], v[124:127]
	ds_read_b128 v[146:149], v195 offset:256
	ds_read_b128 v[150:153], v195 offset:320
	s_waitcnt lgkmcnt(0)
	v_mfma_f32_16x16x32_bf16 v[124:127], v[132:135], v[146:149], v[124:127]
	ds_read_b128 v[132:135], v232 offset:384
	ds_read_b128 v[146:149], v195 offset:384
	v_mfma_f32_16x16x32_bf16 v[124:127], v[142:145], v[150:153], v[124:127]
	ds_read_b128 v[142:145], v232 offset:448
	ds_read_u16 v235, v202 offset:288
	ds_read_b128 v[150:153], v195 offset:448
	s_waitcnt lgkmcnt(0)
	v_mfma_f32_16x16x32_bf16 v[124:127], v[132:135], v[146:149], v[124:127]
	v_lshlrev_b32_e32 v132, 16, v192
	v_mul_f32_e32 v132, 0xbfb8aa3b, v132
	v_exp_f32_e32 v132, v132
	v_mfma_f32_16x16x32_bf16 v[124:127], v[142:145], v[150:153], v[124:127]
	v_mov_b64_e32 v[148:149], s[50:51]
	v_mov_b64_e32 v[146:147], s[48:49]
	s_nop 5
	v_fma_f32 v120, v128, v124, v120
	v_lshlrev_b32_e32 v128, 16, v193
	v_add_f32_e32 v124, 1.0, v132
	v_mul_f32_e32 v128, 0xbfb8aa3b, v128
	v_rcp_f32_e32 v124, v124
	v_exp_f32_e32 v128, v128
	v_mul_f32_e32 v120, v154, v120
	v_fmac_f32_e32 v123, v131, v127
	v_mul_f32_e32 v120, v120, v124
	v_add_f32_e32 v124, 1.0, v128
	v_cvt_pk_bf16_f32 v120, v120, s0
	v_rcp_f32_e32 v124, v124
	ds_write_b16 v203, v120
	v_fma_f32 v120, v129, v125, v121
	v_lshlrev_b32_e32 v121, 16, v235
	v_mul_f32_e32 v121, 0xbfb8aa3b, v121
	v_mul_f32_e32 v120, v155, v120
	v_exp_f32_e32 v121, v121
	v_mul_f32_e32 v120, v120, v124
	v_cvt_pk_bf16_f32 v120, v120, s0
	ds_write_b16 v203, v120 offset:144
	v_fma_f32 v120, v130, v126, v122
	v_lshlrev_b32_e32 v122, 16, v158
	v_add_f32_e32 v121, 1.0, v121
	v_mul_f32_e32 v122, 0xbfb8aa3b, v122
	v_rcp_f32_e32 v121, v121
	v_exp_f32_e32 v122, v122
	v_mul_f32_e32 v120, v156, v120
	v_mov_b32_e32 v124, s36
	v_mul_f32_e32 v120, v120, v121
	v_add_f32_e32 v121, 1.0, v122
	v_rcp_f32_e32 v121, v121
	v_cvt_pk_bf16_f32 v120, v120, s0
	ds_write_b16 v203, v120 offset:288
	v_mul_f32_e32 v120, v194, v123
	v_mul_f32_e32 v120, v120, v121
	v_cvt_pk_bf16_f32 v120, v120, s0
	ds_write_b16 v203, v120 offset:432
	s_waitcnt lgkmcnt(0)
	s_barrier
	v_add_u32_e32 v151, s91, v174
	ds_read_b32 v192, v151
	v_add_u32_e32 v152, s75, v174
	ds_read_b32 v193, v152
	v_add_u32_e32 v153, s74, v174
	ds_read_b32 v194, v153
	v_add_u32_e32 v154, s55, v174
	ds_read_b32 v195, v154
	v_add_u32_e32 v155, s52, v174
	ds_read_b32 v250, v155
	v_add_u32_e32 v156, s53, v174
	ds_read_b32 v251, v156
	v_add_u32_e32 v158, s41, v174
	ds_read_b32 v252, v158
	v_add_u32_e32 v235, s65, v174
	ds_read_b32 v253, v235
	ds_read_b128 v[120:123], v204
	ds_read_b32 v132, v124 offset:768
	v_lshl_add_u64 v[124:125], s[68:69], 0, v[140:141]
	s_waitcnt lgkmcnt(0)
	global_store_dwordx4 v[124:125], v[120:123], off
	ds_read_b64_tr_b16 v[124:125], v205
	ds_read_b64_tr_b16 v[126:127], v205 offset:576
	ds_read_b64_tr_b16 v[120:121], v206
	ds_read_b64_tr_b16 v[122:123], v206 offset:576
	ds_read_b64_tr_b16 v[128:129], v207 offset:33792
	ds_read_b64_tr_b16 v[130:131], v207 offset:35904
	v_pk_mul_f32 v[98:99], v[98:99], v[132:133] op_sel_hi:[1,0]
	v_pk_mul_f32 v[96:97], v[96:97], v[132:133] op_sel_hi:[1,0]
	ds_read_b64_tr_b16 v[142:143], v208 offset:33792
	ds_read_b64_tr_b16 v[144:145], v208 offset:35904
	s_waitcnt lgkmcnt(0)
	v_mfma_f32_16x16x32_bf16 v[96:99], v[124:127], v[128:131], v[96:99]
	v_mfma_f32_16x16x32_bf16 v[96:99], v[120:123], v[142:145], v[96:99]
	v_mfma_f32_16x16x32_bf16 v[128:131], v[146:149], v[128:131], 0
	v_mfma_f32_16x16x32_bf16 v[128:131], v[146:149], v[142:145], v[128:131]
	s_nop 5
	v_cvt_pk_bf16_f32 v133, v96, s0
	ds_write_b16 v209, v133
	v_cvt_pk_bf16_f32 v133, v97, s0
	ds_write_b16 v209, v133 offset:528
	v_cvt_pk_bf16_f32 v133, v98, s0
	ds_write_b16 v209, v133 offset:1056
	v_cvt_pk_bf16_f32 v133, v99, s0
	ds_write_b16 v209, v133 offset:1584
	s_and_saveexec_b64 s[96:97], s[76:77]
	s_cbranch_execz .LBB0_285
	v_add_u32_e32 v129, s91, v174
	v_fmac_f32_e32 v128, v132, v192
	ds_write_b32 v129, v128
; #define LAS __attribute__((address_space(3)))
; __device__ __forceinline__ bf16_t f2bf(float f) { return (bf16_t)(cvt_pk_bf16(f, 0.f) & 0xffffu); }
; __device__ __forceinline__ s16x4 tr_read16(const LAS unsigned char* p) { return __builtin_amdgcn_ds_read_tr16_b64_v4i16((LAS s16x4*)p); }
; __device__ NOINL void mlstm_unit(unsigned char* ws, const float* cwq, LAS unsigned char* lds, int unit, int wv) {
;     ...
; #pragma unroll
;             for (int e = 0; e < 8; ++e) { const int ki = (wave & 1) * 8 + e;
;                 cacc[e] *= dc;
;                 f32x4 na = {0.f, 0.f, 0.f, 0.f};
; #pragma unroll
;                 for (int ks = 0; ks < 2; ++ks) { const s16x4 lo = tr_read16(Kw + (32 * ks + 8 * fq + q4) * 528 + ki * 32 + 8 * p4), hi = tr_read16(Kw + (32 * ks + 8 * fq + 4 + q4) * 528 + ki * 32 + 8 * p4);
;                     const bf16x8 kb = __builtin_shufflevector(lo, hi, 0, 1, 2, 3, 4, 5, 6, 7);
;                     cacc[e] = __builtin_amdgcn_mfma_f32_16x16x32_bf16(va[ks], kb, cacc[e], 0, 0, 0);
;                     na = __builtin_amdgcn_mfma_f32_16x16x32_bf16(ones, kb, na, 0, 0, 0); }
; #pragma unroll
;                 for (int j = 0; j < 4; ++j) *(LAS bf16_t*)(Cb + (vi * 16 + 4 * fq + j) * 528 + (ki * 16 + fr) * 2) = f2bf(cacc[e][j]);
;                 if (vi == 0 && fq == 0) nvec[ki * 16 + fr] = dc * nvec[ki * 16 + fr] + na[0];
;                 __builtin_amdgcn_sched_barrier(0); }
.LBB0_285:
	s_or_b64 exec, exec, s[96:97]
	v_mov_b32_e32 v133, v132
	ds_read_b64_tr_b16 v[128:129], v210 offset:33792
	ds_read_b64_tr_b16 v[130:131], v210 offset:35904
	v_mov_b32_e32 v134, v132
	v_mov_b32_e32 v135, v132
	v_pk_mul_f32 v[118:119], v[118:119], v[134:135]
	v_pk_mul_f32 v[116:117], v[116:117], v[132:133]
	ds_read_b64_tr_b16 v[142:143], v211 offset:33792
	ds_read_b64_tr_b16 v[144:145], v211 offset:35904
	s_waitcnt lgkmcnt(0)
	v_mfma_f32_16x16x32_bf16 v[116:119], v[124:127], v[128:131], v[116:119]
	v_mfma_f32_16x16x32_bf16 v[116:119], v[120:123], v[142:145], v[116:119]
	s_nop 7
	v_cvt_pk_bf16_f32 v146, v116, s0
	ds_write_b16 v212, v146
	v_cvt_pk_bf16_f32 v146, v117, s0
	ds_write_b16 v212, v146 offset:528
	v_cvt_pk_bf16_f32 v146, v118, s0
	ds_write_b16 v212, v146 offset:1056
	v_cvt_pk_bf16_f32 v146, v119, s0
	ds_write_b16 v212, v146 offset:1584
	v_mov_b64_e32 v[148:149], s[50:51]
	v_mov_b64_e32 v[146:147], s[48:49]
	s_nop 1
	v_mfma_f32_16x16x32_bf16 v[128:131], v[146:149], v[128:131], 0
	v_mfma_f32_16x16x32_bf16 v[128:131], v[146:149], v[142:145], v[128:131]
	s_and_saveexec_b64 s[96:97], s[76:77]
	s_cbranch_execz .LBB0_287
	s_nop 5
	v_add_u32_e32 v129, s75, v174
	v_fmac_f32_e32 v128, v132, v193
	ds_write_b32 v129, v128
.LBB0_287:
	s_or_b64 exec, exec, s[96:97]
	s_nop 4
	ds_read_b64_tr_b16 v[128:129], v213 offset:33792
	ds_read_b64_tr_b16 v[130:131], v213 offset:35904
	v_mov_b64_e32 v[148:149], s[50:51]
	v_mov_b64_e32 v[146:147], s[48:49]
	v_pk_mul_f32 v[110:111], v[110:111], v[134:135]
	v_pk_mul_f32 v[108:109], v[108:109], v[132:133]
	ds_read_b64_tr_b16 v[142:143], v214 offset:33792
	ds_read_b64_tr_b16 v[144:145], v214 offset:35904
	s_waitcnt lgkmcnt(0)
	v_mfma_f32_16x16x32_bf16 v[108:111], v[124:127], v[128:131], v[108:111]
	v_mfma_f32_16x16x32_bf16 v[128:131], v[146:149], v[128:131], 0
	v_mfma_f32_16x16x32_bf16 v[108:111], v[120:123], v[142:145], v[108:111]
	v_mfma_f32_16x16x32_bf16 v[128:131], v[146:149], v[142:145], v[128:131]
	s_nop 6
	v_cvt_pk_bf16_f32 v134, v108, s0
	v_cvt_pk_bf16_f32 v135, v109, s0
	v_cvt_pk_bf16_f32 v150, v110, s0
	ds_write_b16 v215, v134
	ds_write_b16 v215, v135 offset:528
	ds_write_b16 v215, v150 offset:1056
	v_cvt_pk_bf16_f32 v134, v111, s0
	ds_write_b16 v215, v134 offset:1584
	s_and_saveexec_b64 s[96:97], s[76:77]
	s_cbranch_execz .LBB0_289
	v_add_u32_e32 v129, s74, v174
	v_fmac_f32_e32 v128, v132, v194
	ds_write_b32 v129, v128
.LBB0_289:
	s_or_b64 exec, exec, s[96:97]
	ds_read_b64_tr_b16 v[128:129], v216 offset:33792
	ds_read_b64_tr_b16 v[130:131], v216 offset:35904
	v_mov_b32_e32 v134, v132
	v_mov_b32_e32 v135, v132
	v_pk_mul_f32 v[114:115], v[114:115], v[134:135]
	v_pk_mul_f32 v[112:113], v[112:113], v[132:133]
	ds_read_b64_tr_b16 v[142:143], v217 offset:33792
	ds_read_b64_tr_b16 v[144:145], v217 offset:35904
	s_waitcnt lgkmcnt(0)
	v_mfma_f32_16x16x32_bf16 v[112:115], v[124:127], v[128:131], v[112:115]
	v_mfma_f32_16x16x32_bf16 v[112:115], v[120:123], v[142:145], v[112:115]
	s_nop 7
	v_cvt_pk_bf16_f32 v146, v112, s0
	ds_write_b16 v218, v146
	v_cvt_pk_bf16_f32 v146, v113, s0
	ds_write_b16 v218, v146 offset:528
	v_cvt_pk_bf16_f32 v146, v114, s0
	ds_write_b16 v218, v146 offset:1056
	v_cvt_pk_bf16_f32 v146, v115, s0
	ds_write_b16 v218, v146 offset:1584
	v_mov_b64_e32 v[148:149], s[50:51]
	v_mov_b64_e32 v[146:147], s[48:49]
	s_nop 1
	v_mfma_f32_16x16x32_bf16 v[128:131], v[146:149], v[128:131], 0
	v_mfma_f32_16x16x32_bf16 v[128:131], v[146:149], v[142:145], v[128:131]
	s_and_saveexec_b64 s[96:97], s[76:77]
	s_cbranch_execz .LBB0_291
	s_nop 5
	v_add_u32_e32 v129, s55, v174
	v_fmac_f32_e32 v128, v132, v195
	ds_write_b32 v129, v128
.LBB0_291:
	s_or_b64 exec, exec, s[96:97]
	s_nop 4
	ds_read_b64_tr_b16 v[128:129], v219 offset:33792
	ds_read_b64_tr_b16 v[130:131], v219 offset:35904
	v_mov_b64_e32 v[148:149], s[50:51]
	v_mov_b64_e32 v[146:147], s[48:49]
	v_pk_mul_f32 v[102:103], v[102:103], v[134:135]
	v_pk_mul_f32 v[100:101], v[100:101], v[132:133]
	ds_read_b64_tr_b16 v[142:143], v220 offset:33792
	ds_read_b64_tr_b16 v[144:145], v220 offset:35904
	s_waitcnt lgkmcnt(0)
	v_mfma_f32_16x16x32_bf16 v[100:103], v[124:127], v[128:131], v[100:103]
	v_mfma_f32_16x16x32_bf16 v[128:131], v[146:149], v[128:131], 0
	v_mfma_f32_16x16x32_bf16 v[100:103], v[120:123], v[142:145], v[100:103]
	v_mfma_f32_16x16x32_bf16 v[128:131], v[146:149], v[142:145], v[128:131]
	s_nop 6
	v_cvt_pk_bf16_f32 v134, v100, s0
	v_cvt_pk_bf16_f32 v135, v101, s0
	v_cvt_pk_bf16_f32 v150, v102, s0
	ds_write_b16 v221, v134
	ds_write_b16 v221, v135 offset:528
	ds_write_b16 v221, v150 offset:1056
	v_cvt_pk_bf16_f32 v134, v103, s0
	ds_write_b16 v221, v134 offset:1584
	s_and_saveexec_b64 s[96:97], s[76:77]
	s_cbranch_execz .LBB0_293
	v_add_u32_e32 v129, s52, v174
	v_fmac_f32_e32 v128, v132, v250
	ds_write_b32 v129, v128
.LBB0_293:
	s_or_b64 exec, exec, s[96:97]
	ds_read_b64_tr_b16 v[128:129], v222 offset:33792
	ds_read_b64_tr_b16 v[130:131], v222 offset:35904
	v_mov_b32_e32 v134, v132
	v_mov_b32_e32 v135, v132
	v_pk_mul_f32 v[106:107], v[106:107], v[134:135]
	v_pk_mul_f32 v[104:105], v[104:105], v[132:133]
	ds_read_b64_tr_b16 v[142:143], v223 offset:33792
	ds_read_b64_tr_b16 v[144:145], v223 offset:35904
	s_waitcnt lgkmcnt(0)
	v_mfma_f32_16x16x32_bf16 v[104:107], v[124:127], v[128:131], v[104:107]
	v_mfma_f32_16x16x32_bf16 v[104:107], v[120:123], v[142:145], v[104:107]
	s_nop 7
	v_cvt_pk_bf16_f32 v146, v104, s0
	ds_write_b16 v224, v146
	v_cvt_pk_bf16_f32 v146, v105, s0
	ds_write_b16 v224, v146 offset:528
	v_cvt_pk_bf16_f32 v146, v106, s0
	ds_write_b16 v224, v146 offset:1056
	v_cvt_pk_bf16_f32 v146, v107, s0
	ds_write_b16 v224, v146 offset:1584
	v_mov_b64_e32 v[148:149], s[50:51]
	v_mov_b64_e32 v[146:147], s[48:49]
	s_nop 1
	v_mfma_f32_16x16x32_bf16 v[128:131], v[146:149], v[128:131], 0
	v_mfma_f32_16x16x32_bf16 v[128:131], v[146:149], v[142:145], v[128:131]
	s_and_saveexec_b64 s[96:97], s[76:77]
	s_cbranch_execz .LBB0_295
	s_nop 5
	v_add_u32_e32 v129, s53, v174
	v_fmac_f32_e32 v128, v132, v251
	ds_write_b32 v129, v128
; #define LAS __attribute__((address_space(3)))
; __device__ __forceinline__ bf16_t f2bf(float f) { return (bf16_t)(cvt_pk_bf16(f, 0.f) & 0xffffu); }
; __device__ __forceinline__ s16x4 tr_read16(const LAS unsigned char* p) { return __builtin_amdgcn_ds_read_tr16_b64_v4i16((LAS s16x4*)p); }
; __device__ NOINL void mlstm_unit(unsigned char* ws, const float* cwq, LAS unsigned char* lds, int unit, int wv) {
;     ...
; #pragma unroll
;             for (int e = 0; e < 8; ++e) { const int ki = (wave & 1) * 8 + e;
;                 cacc[e] *= dc;
;                 f32x4 na = {0.f, 0.f, 0.f, 0.f};
; #pragma unroll
;                 for (int ks = 0; ks < 2; ++ks) { const s16x4 lo = tr_read16(Kw + (32 * ks + 8 * fq + q4) * 528 + ki * 32 + 8 * p4), hi = tr_read16(Kw + (32 * ks + 8 * fq + 4 + q4) * 528 + ki * 32 + 8 * p4);
;                     const bf16x8 kb = __builtin_shufflevector(lo, hi, 0, 1, 2, 3, 4, 5, 6, 7);
;                     cacc[e] = __builtin_amdgcn_mfma_f32_16x16x32_bf16(va[ks], kb, cacc[e], 0, 0, 0);
;                     na = __builtin_amdgcn_mfma_f32_16x16x32_bf16(ones, kb, na, 0, 0, 0); }
; #pragma unroll
;                 for (int j = 0; j < 4; ++j) *(LAS bf16_t*)(Cb + (vi * 16 + 4 * fq + j) * 528 + (ki * 16 + fr) * 2) = f2bf(cacc[e][j]);
;                 if (vi == 0 && fq == 0) nvec[ki * 16 + fr] = dc * nvec[ki * 16 + fr] + na[0];
;                 __builtin_amdgcn_sched_barrier(0); }
.LBB0_295:
	s_or_b64 exec, exec, s[96:97]
	s_nop 4
	ds_read_b64_tr_b16 v[128:129], v225 offset:33792
	ds_read_b64_tr_b16 v[130:131], v225 offset:35904
	v_mov_b64_e32 v[148:149], s[50:51]
	v_mov_b64_e32 v[146:147], s[48:49]
	v_pk_mul_f32 v[94:95], v[94:95], v[134:135]
	v_pk_mul_f32 v[92:93], v[92:93], v[132:133]
	ds_read_b64_tr_b16 v[142:143], v226 offset:33792
	ds_read_b64_tr_b16 v[144:145], v226 offset:35904
	s_waitcnt lgkmcnt(0)
	v_mfma_f32_16x16x32_bf16 v[92:95], v[124:127], v[128:131], v[92:95]
	v_mfma_f32_16x16x32_bf16 v[128:131], v[146:149], v[128:131], 0
	v_mfma_f32_16x16x32_bf16 v[92:95], v[120:123], v[142:145], v[92:95]
	v_mfma_f32_16x16x32_bf16 v[128:131], v[146:149], v[142:145], v[128:131]
	s_nop 6
	v_cvt_pk_bf16_f32 v134, v92, s0
	v_cvt_pk_bf16_f32 v135, v93, s0
	v_cvt_pk_bf16_f32 v150, v94, s0
	ds_write_b16 v227, v134
	ds_write_b16 v227, v135 offset:528
	ds_write_b16 v227, v150 offset:1056
	v_cvt_pk_bf16_f32 v134, v95, s0
	ds_write_b16 v227, v134 offset:1584
	s_and_saveexec_b64 s[96:97], s[76:77]
	s_cbranch_execz .LBB0_297
	v_add_u32_e32 v129, s41, v174
	v_fmac_f32_e32 v128, v132, v252
	ds_write_b32 v129, v128
.LBB0_297:
	s_or_b64 exec, exec, s[96:97]
	v_mov_b32_e32 v128, v132
	v_mov_b32_e32 v129, v132
	v_pk_mul_f32 v[90:91], v[90:91], v[128:129]
	ds_read_b64_tr_b16 v[128:129], v228 offset:33792
	ds_read_b64_tr_b16 v[130:131], v228 offset:35904
	v_pk_mul_f32 v[88:89], v[88:89], v[132:133]
	s_waitcnt lgkmcnt(0)
	s_nop 0
	v_mfma_f32_16x16x32_bf16 v[88:91], v[124:127], v[128:131], v[88:91]
	ds_read_b64_tr_b16 v[124:125], v229 offset:33792
	ds_read_b64_tr_b16 v[126:127], v229 offset:35904
	s_waitcnt lgkmcnt(0)
	v_mfma_f32_16x16x32_bf16 v[88:91], v[120:123], v[124:127], v[88:91]
	s_nop 7
	v_cvt_pk_bf16_f32 v120, v88, s0
	ds_write_b16 v230, v120
	v_cvt_pk_bf16_f32 v120, v89, s0
	ds_write_b16 v230, v120 offset:528
	v_cvt_pk_bf16_f32 v120, v90, s0
	ds_write_b16 v230, v120 offset:1056
	v_cvt_pk_bf16_f32 v120, v91, s0
	ds_write_b16 v230, v120 offset:1584
	v_mov_b64_e32 v[122:123], s[50:51]
	v_mov_b64_e32 v[120:121], s[48:49]
	s_nop 1
	v_mfma_f32_16x16x32_bf16 v[128:131], v[120:123], v[128:131], 0
	v_mfma_f32_16x16x32_bf16 v[120:123], v[120:123], v[124:127], v[128:131]
	s_and_saveexec_b64 s[96:97], s[76:77]
	s_cbranch_execz .LBB0_299
	s_nop 5
	v_add_u32_e32 v121, s65, v174
	v_fmac_f32_e32 v120, v132, v253
	ds_write_b32 v121, v120
.LBB0_299:
	s_or_b64 exec, exec, s[96:97]
	s_or_b64 s[36:37], s[62:63], s[78:79]
	s_and_b64 vcc, exec, s[36:37]
	s_cbranch_vccnz .LBB0_237
	s_waitcnt vmcnt(0)
	s_nop 0
	v_mul_f32_e64 v120, |v159|, s83
	v_rndne_f32_e32 v121, v120
	v_sub_f32_e32 v122, v120, v121
	v_fma_f32 v120, |v159|, s83, -v120
	v_fma_f32 v120, |v159|, s39, v120
	v_add_f32_e32 v120, v122, v120
	v_exp_f32_e32 v120, v120
	v_cvt_i32_f32_e32 v121, v121
	v_cmp_ngt_f32_e64 vcc, |v159|, s38
	s_mov_b32 s33, 0xc2b17218
	v_max_f32_e32 v122, v159, v159
	v_ldexp_f32 v120, v120, v121
	v_cndmask_b32_e32 v120, 0, v120, vcc
	v_cmp_nlt_f32_e64 vcc, |v159|, s33
	s_mov_b32 s33, 0x3f2aaaab
	v_min_f32_e32 v122, 0, v122
	v_cndmask_b32_e32 v123, v241, v120, vcc
	v_add_f32_e32 v124, 1.0, v123
	v_add_f32_e32 v120, -1.0, v124
	v_sub_f32_e32 v121, v120, v124
	v_add_f32_e32 v121, 1.0, v121
	v_sub_f32_e32 v120, v123, v120
	v_add_f32_e32 v125, v120, v121
	v_frexp_mant_f32_e32 v126, v124
	v_cvt_f64_f32_e32 v[120:121], v124
	v_frexp_exp_i32_f64_e32 v120, v[120:121]
	v_cmp_gt_f32_e32 vcc, s33, v126
	s_mov_b32 s33, 0x3f317218
	s_xor_b32 s37, s72, 1
	v_subbrev_co_u32_e32 v120, vcc, 0, v120, vcc
	v_sub_u32_e32 v121, 0, v120
	v_ldexp_f32 v124, v124, v121
	v_ldexp_f32 v121, v125, v121
	v_add_f32_e32 v125, -1.0, v124
	v_add_f32_e32 v128, 1.0, v124
	v_add_f32_e32 v126, 1.0, v125
	v_add_f32_e32 v129, -1.0, v128
	v_sub_f32_e32 v126, v124, v126
	v_sub_f32_e32 v124, v124, v129
	v_add_f32_e32 v126, v121, v126
	v_add_f32_e32 v121, v121, v124
	v_add_f32_e32 v124, v128, v121
	v_rcp_f32_e32 v129, v124
	v_add_f32_e32 v127, v125, v126
	v_sub_f32_e32 v125, v125, v127
	v_add_f32_e32 v125, v126, v125
	v_sub_f32_e32 v126, v128, v124
	v_add_f32_e32 v121, v121, v126
	v_mul_f32_e32 v126, v127, v129
	v_mul_f32_e32 v128, v124, v126
	v_fma_f32 v130, v126, v124, -v128
	v_fmac_f32_e32 v130, v126, v121
	v_add_f32_e32 v131, v128, v130
	v_sub_f32_e32 v132, v127, v131
	v_sub_f32_e32 v127, v127, v132
	v_sub_f32_e32 v128, v131, v128
	v_sub_f32_e32 v127, v127, v131
	v_add_f32_e32 v125, v125, v127
	v_sub_f32_e32 v127, v128, v130
	v_add_f32_e32 v125, v127, v125
	v_add_f32_e32 v127, v132, v125
	v_mul_f32_e32 v128, v129, v127
	v_mul_f32_e32 v130, v124, v128
	v_fma_f32 v124, v128, v124, -v130
	v_fmac_f32_e32 v124, v128, v121
	v_sub_f32_e32 v121, v132, v127
	v_add_f32_e32 v121, v125, v121
	v_add_f32_e32 v125, v130, v124
	v_sub_f32_e32 v131, v127, v125
	v_sub_f32_e32 v127, v127, v131
	v_sub_f32_e32 v130, v125, v130
	v_sub_f32_e32 v125, v127, v125
	v_add_f32_e32 v121, v121, v125
	v_sub_f32_e32 v124, v130, v124
	v_cvt_f32_i32_e32 v120, v120
	v_add_f32_e32 v121, v124, v121
	v_add_f32_e32 v124, v126, v128
	v_add_f32_e32 v121, v131, v121
	v_sub_f32_e32 v125, v124, v126
	v_mul_f32_e32 v121, v129, v121
	v_sub_f32_e32 v125, v128, v125
	v_add_f32_e32 v121, v125, v121
	v_mul_f32_e32 v128, 0x3f317218, v120
	v_add_f32_e32 v125, v124, v121
	v_fma_f32 v129, v120, s33, -v128
	v_mul_f32_e32 v126, v125, v125
	v_fmac_f32_e32 v129, 0xb102e308, v120
	v_sub_f32_e32 v120, v125, v124
	v_fmamk_f32 v127, v126, 0x3e9b6dac, v237
	v_sub_f32_e32 v120, v121, v120
	v_add_f32_e32 v121, v128, v129
	v_fmaak_f32 v127, v126, v127, 0x3f2aaada
	v_sub_f32_e32 v124, v121, v128
	v_ldexp_f32 v128, v125, 1
	v_mul_f32_e32 v125, v125, v126
	v_mul_f32_e32 v125, v125, v127
	v_add_f32_e32 v126, v128, v125
	v_sub_f32_e32 v127, v126, v128
	v_ldexp_f32 v120, v120, 1
	v_sub_f32_e32 v125, v125, v127
	v_add_f32_e32 v120, v120, v125
	v_add_f32_e32 v125, v126, v120
	v_sub_f32_e32 v126, v125, v126
	v_sub_f32_e32 v120, v120, v126
	v_add_f32_e32 v126, v121, v125
	v_sub_f32_e32 v127, v126, v121
	v_sub_f32_e32 v128, v126, v127
	v_sub_f32_e32 v124, v129, v124
	v_sub_f32_e32 v121, v121, v128
	v_sub_f32_e32 v125, v125, v127
	v_add_f32_e32 v121, v125, v121
	v_add_f32_e32 v125, v124, v120
	v_sub_f32_e32 v127, v125, v124
	v_sub_f32_e32 v128, v125, v127
	v_sub_f32_e32 v124, v124, v128
	v_sub_f32_e32 v120, v120, v127
	v_add_f32_e32 v121, v125, v121
	v_add_f32_e32 v120, v120, v124
	v_add_f32_e32 v124, v126, v121
	v_sub_f32_e32 v125, v124, v126
	v_sub_f32_e32 v121, v121, v125
	v_add_f32_e32 v120, v120, v121
	v_add_f32_e32 v120, v124, v120
	v_cmp_neq_f32_e32 vcc, s54, v123
	s_mulk_i32 s37, 0x340
	s_add_i32 s37, s37, 0
	v_cndmask_b32_e32 v120, v241, v120, vcc
	v_cmp_lt_f32_e64 vcc, |v123|, s60
	s_add_i32 s37, s37, 0x1d800
	s_nop 0
	v_cndmask_b32_e32 v120, v120, v123, vcc
	v_sub_f32_e32 v120, v122, v120
	s_nop 1
	v_add_f32_dpp v120, v120, v120 row_shr:1 row_mask:0xf bank_mask:0xf
	s_nop 1
	v_add_f32_dpp v120, v120, v120 row_shr:2 row_mask:0xf bank_mask:0xf
	s_nop 1
	v_add_f32_dpp v120, v120, v120 row_shr:4 row_mask:0xf bank_mask:0xf
	s_nop 1
	v_add_f32_dpp v120, v120, v120 row_shr:8 row_mask:0xf bank_mask:0xf
	s_nop 1
	v_add_f32_dpp v120, v120, v120 row_bcast:15 row_mask:0xa bank_mask:0xf
	s_nop 1
	v_add_f32_dpp v120, v120, v120 row_bcast:31 row_mask:0xc bank_mask:0xf
	s_nop 0
	v_readlane_b32 s36, v120, 63
	s_nop 1
	v_sub_f32_e32 v121, s36, v120
	v_add_f32_e32 v121, v160, v121
	v_mul_f32_e32 v122, 0x3fb8aa3b, v121
	v_fma_f32 v123, v121, s61, -v122
	v_rndne_f32_e32 v124, v122
	v_fmac_f32_e32 v123, 0x32a5705f, v121
	v_sub_f32_e32 v122, v122, v124
	v_add_f32_e32 v122, v122, v123
	v_exp_f32_e32 v122, v122
	v_cvt_i32_f32_e32 v123, v124
	v_cmp_ngt_f32_e32 vcc, s88, v121
	v_ldexp_f32 v122, v122, v123
	v_mul_f32_e32 v123, 0x3fb8aa3b, v120
	v_fma_f32 v124, v120, s61, -v123
	v_rndne_f32_e32 v125, v123
	v_fmac_f32_e32 v124, 0x32a5705f, v120
	v_sub_f32_e32 v123, v123, v125
	v_add_f32_e32 v123, v123, v124
	v_exp_f32_e32 v123, v123
	v_cvt_i32_f32_e32 v124, v125
	v_cndmask_b32_e32 v122, 0, v122, vcc
	v_cmp_nlt_f32_e32 vcc, s89, v121
	v_ldexp_f32 v123, v123, v124
	v_subrev_f32_e32 v124, s36, v120
	v_mul_f32_e32 v125, 0x3fb8aa3b, v124
	v_fma_f32 v126, v124, s61, -v125
	v_rndne_f32_e32 v127, v125
	v_fmac_f32_e32 v126, 0x32a5705f, v124
	v_sub_f32_e32 v125, v125, v127
	v_add_f32_e32 v125, v125, v126
	v_exp_f32_e32 v125, v125
	v_cvt_i32_f32_e32 v126, v127
	v_cndmask_b32_e32 v121, v241, v122, vcc
	v_cmp_ngt_f32_e32 vcc, s88, v120
	v_lshl_add_u32 v122, v1, 2, s37
	s_nop 0
	v_cndmask_b32_e32 v123, 0, v123, vcc
	v_cmp_nlt_f32_e32 vcc, s89, v120
	s_nop 1
	v_cndmask_b32_e32 v120, v241, v123, vcc
	ds_write2st64_b32 v122, v121, v120 offset1:1
	v_ldexp_f32 v120, v125, v126
	v_cmp_ngt_f32_e32 vcc, s88, v124
	s_nop 1
	v_cndmask_b32_e32 v120, 0, v120, vcc
	v_cmp_nlt_f32_e32 vcc, s89, v124
	s_nop 1
	v_cndmask_b32_e32 v120, v241, v120, vcc
	ds_write_b32 v122, v120 offset:512
	s_and_saveexec_b64 s[78:79], s[8:9]
	s_cbranch_execz .LBB0_236
	v_mul_f32_e32 v120, s36, v242
	v_rndne_f32_e32 v121, v120
	v_sub_f32_e32 v122, v120, v121
	v_fma_f32 v120, s36, v242, -v120
	v_fmac_f32_e32 v120, s36, v243
	v_add_f32_e32 v120, v122, v120
	v_cvt_i32_f32_e32 v121, v121
	v_exp_f32_e32 v120, v120
	v_cmp_nlt_f32_e32 vcc, s36, v244
	v_ldexp_f32 v120, v120, v121
	s_nop 0
	v_cndmask_b32_e32 v120, 0, v120, vcc
	v_cmp_ngt_f32_e32 vcc, s36, v245
	v_mov_b32_e32 v121, s37
	s_nop 0
	v_cndmask_b32_e32 v120, v241, v120, vcc
	ds_write_b32 v121, v120 offset:768
	s_branch .LBB0_236

; __device__ __forceinline__ int obx() { int b = blockIdx.x; asm volatile("" : "+s"(b)); return b; }
; __device__ __forceinline__ int ogx() { int g = gridDim.x; asm volatile("" : "+s"(g)); return g; }
; __device__ NOINL void pool_diff(unsigned char* ws, int wv) {
;     ...
;     for (int it = obx() * NTHR + tid; it < total; it += ogx() * NTHR) {
;         const int c8 = it & 127, run = (it >> 7) & 63, b = it >> 13, g = c8 >> 5, w = 2 << g, t0 = run * 32;
;         const bf16_t* ap = PROJ + ((size_t)b * SEQ) * NPROJ + C_POOL + c8 * 8;
;         float s[8];
; #pragma unroll
;         for (int j = 0; j < 8; ++j) s[j] = 0.f;
; #pragma unroll
;         for (int i = 1; i <= 16; ++i) { const int ts = t0 - i; if (i <= w && ts >= 0) acc8(s, *(const u32x4*)(ap + (size_t)ts * NPROJ), 1.0f); }
; #pragma unroll 8
;         for (int j = 0; j < 32; ++j) { const int t = t0 + j;
;             const u32x4 cur = *(const u32x4*)(ap + (size_t)t * NPROJ);
;             acc8(s, cur, 1.0f);
;             if (t - w >= 0) acc8(s, *(const u32x4*)(ap + (size_t)(t - w) * NPROJ), -1.0f);
.LBB0_306:
	v_ashrrev_i32_e32 v12, 13, v1
	v_and_b32_e32 v20, 0x7f, v1
	v_lshrrev_b32_e32 v2, 2, v1
	v_and_b32_e32 v38, 0x7e0, v2
	v_lshlrev_b32_e32 v2, 4, v20
	v_lshl_add_u32 v40, v12, 25, v2
	v_lshrrev_b32_e32 v21, 5, v20
	v_lshlrev_b32_e64 v39, v21, 2
	v_lshl_add_u32 v41, v12, 11, v38
	v_lshl_add_u32 v41, v41, 11, v2
	s_add_u32 s16, s2, 0x30e00000
	s_addc_u32 s17, s3, 0
	v_mov_b32_e32 v6, 0
	v_mov_b32_e32 v7, 0
	v_mov_b32_e32 v8, 0
	v_mov_b32_e32 v9, 0
	v_mov_b32_e32 v10, 0
	v_mov_b32_e32 v11, 0
	v_mov_b32_e32 v16, 0
	v_mov_b32_e32 v17, 0
	v_subrev_u32_e32 v18, 1, v38
	v_max_i32_e32 v18, 0, v18
	v_lshl_add_u32 v3, v18, 14, v40
	global_load_dwordx4 v[108:111], v3, s[6:7]
	v_subrev_u32_e32 v18, 2, v38
	v_max_i32_e32 v18, 0, v18
	v_lshl_add_u32 v3, v18, 14, v40
	global_load_dwordx4 v[112:115], v3, s[6:7]
	v_subrev_u32_e32 v18, 3, v38
	v_max_i32_e32 v18, 0, v18
	v_lshl_add_u32 v3, v18, 14, v40
	global_load_dwordx4 v[116:119], v3, s[6:7]
	v_subrev_u32_e32 v18, 4, v38
	v_max_i32_e32 v18, 0, v18
	v_lshl_add_u32 v3, v18, 14, v40
	global_load_dwordx4 v[120:123], v3, s[6:7]
	v_subrev_u32_e32 v18, 5, v38
	v_max_i32_e32 v18, 0, v18
	v_lshl_add_u32 v3, v18, 14, v40
	global_load_dwordx4 v[124:127], v3, s[6:7]
	v_subrev_u32_e32 v18, 6, v38
	v_max_i32_e32 v18, 0, v18
	v_lshl_add_u32 v3, v18, 14, v40
	global_load_dwordx4 v[128:131], v3, s[6:7]
	v_subrev_u32_e32 v18, 7, v38
	v_max_i32_e32 v18, 0, v18
	v_lshl_add_u32 v3, v18, 14, v40
	global_load_dwordx4 v[132:135], v3, s[6:7]
	v_subrev_u32_e32 v18, 8, v38
	v_max_i32_e32 v18, 0, v18
	v_lshl_add_u32 v3, v18, 14, v40
	global_load_dwordx4 v[136:139], v3, s[6:7]
	v_subrev_u32_e32 v18, 9, v38
	v_max_i32_e32 v18, 0, v18
	v_lshl_add_u32 v3, v18, 14, v40
	global_load_dwordx4 v[140:143], v3, s[6:7]
	v_subrev_u32_e32 v18, 10, v38
	v_max_i32_e32 v18, 0, v18
	v_lshl_add_u32 v3, v18, 14, v40
	global_load_dwordx4 v[144:147], v3, s[6:7]
	v_subrev_u32_e32 v18, 11, v38
	v_max_i32_e32 v18, 0, v18
	v_lshl_add_u32 v3, v18, 14, v40
	global_load_dwordx4 v[148:151], v3, s[6:7]
	v_subrev_u32_e32 v18, 12, v38
	v_max_i32_e32 v18, 0, v18
	v_lshl_add_u32 v3, v18, 14, v40
	global_load_dwordx4 v[152:155], v3, s[6:7]
	v_subrev_u32_e32 v18, 13, v38
	v_max_i32_e32 v18, 0, v18
	v_lshl_add_u32 v3, v18, 14, v40
	global_load_dwordx4 v[156:159], v3, s[6:7]
	v_subrev_u32_e32 v18, 14, v38
	v_max_i32_e32 v18, 0, v18
	v_lshl_add_u32 v3, v18, 14, v40
	global_load_dwordx4 v[160:163], v3, s[6:7]
	v_subrev_u32_e32 v18, 15, v38
	v_max_i32_e32 v18, 0, v18
	v_lshl_add_u32 v3, v18, 14, v40
	global_load_dwordx4 v[164:167], v3, s[6:7]
	v_subrev_u32_e32 v18, 16, v38
	v_max_i32_e32 v18, 0, v18
	v_lshl_add_u32 v3, v18, 14, v40
	global_load_dwordx4 v[168:171], v3, s[6:7]
	v_add_u32_e32 v18, 0, v38
	v_lshl_add_u32 v3, v18, 14, v40
	global_load_dwordx4 v[44:47], v3, s[6:7]
	v_sub_u32_e32 v19, v18, v39
	v_max_i32_e32 v19, 0, v19
	v_lshl_add_u32 v3, v19, 14, v40
	global_load_dwordx4 v[76:79], v3, s[6:7]
	v_add_u32_e32 v18, 1, v38
	v_lshl_add_u32 v3, v18, 14, v40
	global_load_dwordx4 v[48:51], v3, s[6:7]
	v_sub_u32_e32 v19, v18, v39
	v_max_i32_e32 v19, 0, v19
	v_lshl_add_u32 v3, v19, 14, v40
	global_load_dwordx4 v[80:83], v3, s[6:7]
	v_add_u32_e32 v18, 2, v38
	v_lshl_add_u32 v3, v18, 14, v40
	global_load_dwordx4 v[52:55], v3, s[6:7]
	v_sub_u32_e32 v19, v18, v39
	v_max_i32_e32 v19, 0, v19
	v_lshl_add_u32 v3, v19, 14, v40
	global_load_dwordx4 v[84:87], v3, s[6:7]
	v_add_u32_e32 v18, 3, v38
	v_lshl_add_u32 v3, v18, 14, v40
	global_load_dwordx4 v[56:59], v3, s[6:7]
	v_sub_u32_e32 v19, v18, v39
	v_max_i32_e32 v19, 0, v19
	v_lshl_add_u32 v3, v19, 14, v40
	global_load_dwordx4 v[88:91], v3, s[6:7]
	v_add_u32_e32 v18, 4, v38
	v_lshl_add_u32 v3, v18, 14, v40
	global_load_dwordx4 v[60:63], v3, s[6:7]
	v_sub_u32_e32 v19, v18, v39
	v_max_i32_e32 v19, 0, v19
	v_lshl_add_u32 v3, v19, 14, v40
	global_load_dwordx4 v[92:95], v3, s[6:7]
	v_add_u32_e32 v18, 5, v38
	v_lshl_add_u32 v3, v18, 14, v40
	global_load_dwordx4 v[64:67], v3, s[6:7]
	v_sub_u32_e32 v19, v18, v39
	v_max_i32_e32 v19, 0, v19
	v_lshl_add_u32 v3, v19, 14, v40
	global_load_dwordx4 v[96:99], v3, s[6:7]
	v_add_u32_e32 v18, 6, v38
	v_lshl_add_u32 v3, v18, 14, v40
	global_load_dwordx4 v[68:71], v3, s[6:7]
	v_sub_u32_e32 v19, v18, v39
	v_max_i32_e32 v19, 0, v19
	v_lshl_add_u32 v3, v19, 14, v40
	global_load_dwordx4 v[100:103], v3, s[6:7]
	v_add_u32_e32 v18, 7, v38
	v_lshl_add_u32 v3, v18, 14, v40
	global_load_dwordx4 v[72:75], v3, s[6:7]
	v_sub_u32_e32 v19, v18, v39
	v_max_i32_e32 v19, 0, v19
	v_lshl_add_u32 v3, v19, 14, v40
	global_load_dwordx4 v[104:107], v3, s[6:7]
	s_waitcnt vmcnt(16)
; __device__ __forceinline__ float bflo(unsigned w) { return __uint_as_float(w << 16); }
; __device__ __forceinline__ float bfhi(unsigned w) { return __uint_as_float(w & 0xffff0000u); }
; __device__ __forceinline__ void acc8(float (&s)[8], const u32x4 a, float sg) {
;     s[0] += sg * bflo(a.x); s[1] += sg * bfhi(a.x); s[2] += sg * bflo(a.y); s[3] += sg * bfhi(a.y); s[4] += sg * bflo(a.z); s[5] += sg * bfhi(a.z); s[6] += sg * bflo(a.w); s[7] += sg * bfhi(a.w);
; }
; __device__ NOINL void pool_diff(unsigned char* ws, int wv) {
;     ...
;         for (int i = 1; i <= 16; ++i) { const int ts = t0 - i; if (i <= w && ts >= 0) acc8(s, *(const u32x4*)(ap + (size_t)ts * NPROJ), 1.0f); }
	v_cmp_le_u32_e32 vcc, 1, v38
	v_cmp_le_u32_e64 s[0:1], 1, v39
	s_and_b64 s[0:1], vcc, s[0:1]
	s_and_saveexec_b64 s[10:11], s[0:1]
	v_lshlrev_b32_e32 v22, 16, v108
	v_and_b32_e32 v23, 0xffff0000, v108
	v_pk_add_f32 v[6:7], v[6:7], v[22:23]
	v_lshlrev_b32_e32 v22, 16, v109
	v_and_b32_e32 v23, 0xffff0000, v109
	v_pk_add_f32 v[8:9], v[8:9], v[22:23]
	v_lshlrev_b32_e32 v22, 16, v110
	v_and_b32_e32 v23, 0xffff0000, v110
	v_pk_add_f32 v[10:11], v[10:11], v[22:23]
	v_lshlrev_b32_e32 v22, 16, v111
	v_and_b32_e32 v23, 0xffff0000, v111
	v_pk_add_f32 v[16:17], v[16:17], v[22:23]
	s_or_b64 exec, exec, s[10:11]
	v_cmp_le_u32_e32 vcc, 2, v38
	v_cmp_le_u32_e64 s[0:1], 2, v39
	s_and_b64 s[0:1], vcc, s[0:1]
	s_and_saveexec_b64 s[10:11], s[0:1]
	v_lshlrev_b32_e32 v22, 16, v112
	v_and_b32_e32 v23, 0xffff0000, v112
	v_pk_add_f32 v[6:7], v[6:7], v[22:23]
	v_lshlrev_b32_e32 v22, 16, v113
	v_and_b32_e32 v23, 0xffff0000, v113
	v_pk_add_f32 v[8:9], v[8:9], v[22:23]
	v_lshlrev_b32_e32 v22, 16, v114
	v_and_b32_e32 v23, 0xffff0000, v114
	v_pk_add_f32 v[10:11], v[10:11], v[22:23]
	v_lshlrev_b32_e32 v22, 16, v115
	v_and_b32_e32 v23, 0xffff0000, v115
	v_pk_add_f32 v[16:17], v[16:17], v[22:23]
	s_or_b64 exec, exec, s[10:11]
	v_cmp_le_u32_e32 vcc, 3, v38
	v_cmp_le_u32_e64 s[0:1], 3, v39
	s_and_b64 s[0:1], vcc, s[0:1]
	s_and_saveexec_b64 s[10:11], s[0:1]
	v_lshlrev_b32_e32 v22, 16, v116
	v_and_b32_e32 v23, 0xffff0000, v116
	v_pk_add_f32 v[6:7], v[6:7], v[22:23]
	v_lshlrev_b32_e32 v22, 16, v117
	v_and_b32_e32 v23, 0xffff0000, v117
	v_pk_add_f32 v[8:9], v[8:9], v[22:23]
	v_lshlrev_b32_e32 v22, 16, v118
	v_and_b32_e32 v23, 0xffff0000, v118
	v_pk_add_f32 v[10:11], v[10:11], v[22:23]
	v_lshlrev_b32_e32 v22, 16, v119
	v_and_b32_e32 v23, 0xffff0000, v119
	v_pk_add_f32 v[16:17], v[16:17], v[22:23]
	s_or_b64 exec, exec, s[10:11]
	v_cmp_le_u32_e32 vcc, 4, v38
	v_cmp_le_u32_e64 s[0:1], 4, v39
	s_and_b64 s[0:1], vcc, s[0:1]
	s_and_saveexec_b64 s[10:11], s[0:1]
	v_lshlrev_b32_e32 v22, 16, v120
	v_and_b32_e32 v23, 0xffff0000, v120
	v_pk_add_f32 v[6:7], v[6:7], v[22:23]
	v_lshlrev_b32_e32 v22, 16, v121
	v_and_b32_e32 v23, 0xffff0000, v121
	v_pk_add_f32 v[8:9], v[8:9], v[22:23]
	v_lshlrev_b32_e32 v22, 16, v122
	v_and_b32_e32 v23, 0xffff0000, v122
	v_pk_add_f32 v[10:11], v[10:11], v[22:23]
	v_lshlrev_b32_e32 v22, 16, v123
	v_and_b32_e32 v23, 0xffff0000, v123
	v_pk_add_f32 v[16:17], v[16:17], v[22:23]
	s_or_b64 exec, exec, s[10:11]
	v_cmp_le_u32_e32 vcc, 5, v38
	v_cmp_le_u32_e64 s[0:1], 5, v39
	s_and_b64 s[0:1], vcc, s[0:1]
	s_and_saveexec_b64 s[10:11], s[0:1]
	v_lshlrev_b32_e32 v22, 16, v124
	v_and_b32_e32 v23, 0xffff0000, v124
	v_pk_add_f32 v[6:7], v[6:7], v[22:23]
	v_lshlrev_b32_e32 v22, 16, v125
	v_and_b32_e32 v23, 0xffff0000, v125
	v_pk_add_f32 v[8:9], v[8:9], v[22:23]
	v_lshlrev_b32_e32 v22, 16, v126
	v_and_b32_e32 v23, 0xffff0000, v126
	v_pk_add_f32 v[10:11], v[10:11], v[22:23]
	v_lshlrev_b32_e32 v22, 16, v127
	v_and_b32_e32 v23, 0xffff0000, v127
	v_pk_add_f32 v[16:17], v[16:17], v[22:23]
	s_or_b64 exec, exec, s[10:11]
	v_cmp_le_u32_e32 vcc, 6, v38
	v_cmp_le_u32_e64 s[0:1], 6, v39
	s_and_b64 s[0:1], vcc, s[0:1]
	s_and_saveexec_b64 s[10:11], s[0:1]
	v_lshlrev_b32_e32 v22, 16, v128
	v_and_b32_e32 v23, 0xffff0000, v128
	v_pk_add_f32 v[6:7], v[6:7], v[22:23]
	v_lshlrev_b32_e32 v22, 16, v129
	v_and_b32_e32 v23, 0xffff0000, v129
	v_pk_add_f32 v[8:9], v[8:9], v[22:23]
	v_lshlrev_b32_e32 v22, 16, v130
	v_and_b32_e32 v23, 0xffff0000, v130
	v_pk_add_f32 v[10:11], v[10:11], v[22:23]
	v_lshlrev_b32_e32 v22, 16, v131
	v_and_b32_e32 v23, 0xffff0000, v131
	v_pk_add_f32 v[16:17], v[16:17], v[22:23]
	s_or_b64 exec, exec, s[10:11]
	v_cmp_le_u32_e32 vcc, 7, v38
	v_cmp_le_u32_e64 s[0:1], 7, v39
	s_and_b64 s[0:1], vcc, s[0:1]
	s_and_saveexec_b64 s[10:11], s[0:1]
	v_lshlrev_b32_e32 v22, 16, v132
	v_and_b32_e32 v23, 0xffff0000, v132
	v_pk_add_f32 v[6:7], v[6:7], v[22:23]
	v_lshlrev_b32_e32 v22, 16, v133
	v_and_b32_e32 v23, 0xffff0000, v133
	v_pk_add_f32 v[8:9], v[8:9], v[22:23]
	v_lshlrev_b32_e32 v22, 16, v134
	v_and_b32_e32 v23, 0xffff0000, v134
	v_pk_add_f32 v[10:11], v[10:11], v[22:23]
	v_lshlrev_b32_e32 v22, 16, v135
	v_and_b32_e32 v23, 0xffff0000, v135
	v_pk_add_f32 v[16:17], v[16:17], v[22:23]
	s_or_b64 exec, exec, s[10:11]
	v_cmp_le_u32_e32 vcc, 8, v38
	v_cmp_le_u32_e64 s[0:1], 8, v39
	s_and_b64 s[0:1], vcc, s[0:1]
	s_and_saveexec_b64 s[10:11], s[0:1]
	v_lshlrev_b32_e32 v22, 16, v136
	v_and_b32_e32 v23, 0xffff0000, v136
	v_pk_add_f32 v[6:7], v[6:7], v[22:23]
	v_lshlrev_b32_e32 v22, 16, v137
	v_and_b32_e32 v23, 0xffff0000, v137
	v_pk_add_f32 v[8:9], v[8:9], v[22:23]
	v_lshlrev_b32_e32 v22, 16, v138
	v_and_b32_e32 v23, 0xffff0000, v138
	v_pk_add_f32 v[10:11], v[10:11], v[22:23]
	v_lshlrev_b32_e32 v22, 16, v139
	v_and_b32_e32 v23, 0xffff0000, v139
	v_pk_add_f32 v[16:17], v[16:17], v[22:23]
	s_or_b64 exec, exec, s[10:11]
	v_cmp_le_u32_e32 vcc, 9, v38
	v_cmp_le_u32_e64 s[0:1], 9, v39
	s_and_b64 s[0:1], vcc, s[0:1]
	s_and_saveexec_b64 s[10:11], s[0:1]
	v_lshlrev_b32_e32 v22, 16, v140
	v_and_b32_e32 v23, 0xffff0000, v140
	v_pk_add_f32 v[6:7], v[6:7], v[22:23]
	v_lshlrev_b32_e32 v22, 16, v141
	v_and_b32_e32 v23, 0xffff0000, v141
	v_pk_add_f32 v[8:9], v[8:9], v[22:23]
	v_lshlrev_b32_e32 v22, 16, v142
	v_and_b32_e32 v23, 0xffff0000, v142
	v_pk_add_f32 v[10:11], v[10:11], v[22:23]
	v_lshlrev_b32_e32 v22, 16, v143
	v_and_b32_e32 v23, 0xffff0000, v143
	v_pk_add_f32 v[16:17], v[16:17], v[22:23]
	s_or_b64 exec, exec, s[10:11]
	v_cmp_le_u32_e32 vcc, 10, v38
	v_cmp_le_u32_e64 s[0:1], 10, v39
	s_and_b64 s[0:1], vcc, s[0:1]
	s_and_saveexec_b64 s[10:11], s[0:1]
	v_lshlrev_b32_e32 v22, 16, v144
	v_and_b32_e32 v23, 0xffff0000, v144
; __device__ NOINL void pool_diff(unsigned char* ws, int wv) {
;     ...
;         for (int i = 1; i <= 16; ++i) { const int ts = t0 - i; if (i <= w && ts >= 0) acc8(s, *(const u32x4*)(ap + (size_t)ts * NPROJ), 1.0f); }
;     ...
;         for (int j = 0; j < 32; ++j) { const int t = t0 + j;
;             const u32x4 cur = *(const u32x4*)(ap + (size_t)t * NPROJ);
;             acc8(s, cur, 1.0f);
;             if (t - w >= 0) acc8(s, *(const u32x4*)(ap + (size_t)(t - w) * NPROJ), -1.0f);
	v_pk_add_f32 v[6:7], v[6:7], v[22:23]
	v_lshlrev_b32_e32 v22, 16, v145
	v_and_b32_e32 v23, 0xffff0000, v145
	v_pk_add_f32 v[8:9], v[8:9], v[22:23]
	v_lshlrev_b32_e32 v22, 16, v146
	v_and_b32_e32 v23, 0xffff0000, v146
	v_pk_add_f32 v[10:11], v[10:11], v[22:23]
	v_lshlrev_b32_e32 v22, 16, v147
	v_and_b32_e32 v23, 0xffff0000, v147
	v_pk_add_f32 v[16:17], v[16:17], v[22:23]
	s_or_b64 exec, exec, s[10:11]
	v_cmp_le_u32_e32 vcc, 11, v38
	v_cmp_le_u32_e64 s[0:1], 11, v39
	s_and_b64 s[0:1], vcc, s[0:1]
	s_and_saveexec_b64 s[10:11], s[0:1]
	v_lshlrev_b32_e32 v22, 16, v148
	v_and_b32_e32 v23, 0xffff0000, v148
	v_pk_add_f32 v[6:7], v[6:7], v[22:23]
	v_lshlrev_b32_e32 v22, 16, v149
	v_and_b32_e32 v23, 0xffff0000, v149
	v_pk_add_f32 v[8:9], v[8:9], v[22:23]
	v_lshlrev_b32_e32 v22, 16, v150
	v_and_b32_e32 v23, 0xffff0000, v150
	v_pk_add_f32 v[10:11], v[10:11], v[22:23]
	v_lshlrev_b32_e32 v22, 16, v151
	v_and_b32_e32 v23, 0xffff0000, v151
	v_pk_add_f32 v[16:17], v[16:17], v[22:23]
	s_or_b64 exec, exec, s[10:11]
	v_cmp_le_u32_e32 vcc, 12, v38
	v_cmp_le_u32_e64 s[0:1], 12, v39
	s_and_b64 s[0:1], vcc, s[0:1]
	s_and_saveexec_b64 s[10:11], s[0:1]
	v_lshlrev_b32_e32 v22, 16, v152
	v_and_b32_e32 v23, 0xffff0000, v152
	v_pk_add_f32 v[6:7], v[6:7], v[22:23]
	v_lshlrev_b32_e32 v22, 16, v153
	v_and_b32_e32 v23, 0xffff0000, v153
	v_pk_add_f32 v[8:9], v[8:9], v[22:23]
	v_lshlrev_b32_e32 v22, 16, v154
	v_and_b32_e32 v23, 0xffff0000, v154
	v_pk_add_f32 v[10:11], v[10:11], v[22:23]
	v_lshlrev_b32_e32 v22, 16, v155
	v_and_b32_e32 v23, 0xffff0000, v155
	v_pk_add_f32 v[16:17], v[16:17], v[22:23]
	s_or_b64 exec, exec, s[10:11]
	v_cmp_le_u32_e32 vcc, 13, v38
	v_cmp_le_u32_e64 s[0:1], 13, v39
	s_and_b64 s[0:1], vcc, s[0:1]
	s_and_saveexec_b64 s[10:11], s[0:1]
	v_lshlrev_b32_e32 v22, 16, v156
	v_and_b32_e32 v23, 0xffff0000, v156
	v_pk_add_f32 v[6:7], v[6:7], v[22:23]
	v_lshlrev_b32_e32 v22, 16, v157
	v_and_b32_e32 v23, 0xffff0000, v157
	v_pk_add_f32 v[8:9], v[8:9], v[22:23]
	v_lshlrev_b32_e32 v22, 16, v158
	v_and_b32_e32 v23, 0xffff0000, v158
	v_pk_add_f32 v[10:11], v[10:11], v[22:23]
	v_lshlrev_b32_e32 v22, 16, v159
	v_and_b32_e32 v23, 0xffff0000, v159
	v_pk_add_f32 v[16:17], v[16:17], v[22:23]
	s_or_b64 exec, exec, s[10:11]
	v_cmp_le_u32_e32 vcc, 14, v38
	v_cmp_le_u32_e64 s[0:1], 14, v39
	s_and_b64 s[0:1], vcc, s[0:1]
	s_and_saveexec_b64 s[10:11], s[0:1]
	v_lshlrev_b32_e32 v22, 16, v160
	v_and_b32_e32 v23, 0xffff0000, v160
	v_pk_add_f32 v[6:7], v[6:7], v[22:23]
	v_lshlrev_b32_e32 v22, 16, v161
	v_and_b32_e32 v23, 0xffff0000, v161
	v_pk_add_f32 v[8:9], v[8:9], v[22:23]
	v_lshlrev_b32_e32 v22, 16, v162
	v_and_b32_e32 v23, 0xffff0000, v162
	v_pk_add_f32 v[10:11], v[10:11], v[22:23]
	v_lshlrev_b32_e32 v22, 16, v163
	v_and_b32_e32 v23, 0xffff0000, v163
	v_pk_add_f32 v[16:17], v[16:17], v[22:23]
	s_or_b64 exec, exec, s[10:11]
	v_cmp_le_u32_e32 vcc, 15, v38
	v_cmp_le_u32_e64 s[0:1], 15, v39
	s_and_b64 s[0:1], vcc, s[0:1]
	s_and_saveexec_b64 s[10:11], s[0:1]
	v_lshlrev_b32_e32 v22, 16, v164
	v_and_b32_e32 v23, 0xffff0000, v164
	v_pk_add_f32 v[6:7], v[6:7], v[22:23]
	v_lshlrev_b32_e32 v22, 16, v165
	v_and_b32_e32 v23, 0xffff0000, v165
	v_pk_add_f32 v[8:9], v[8:9], v[22:23]
	v_lshlrev_b32_e32 v22, 16, v166
	v_and_b32_e32 v23, 0xffff0000, v166
	v_pk_add_f32 v[10:11], v[10:11], v[22:23]
	v_lshlrev_b32_e32 v22, 16, v167
	v_and_b32_e32 v23, 0xffff0000, v167
	v_pk_add_f32 v[16:17], v[16:17], v[22:23]
	s_or_b64 exec, exec, s[10:11]
	v_cmp_le_u32_e32 vcc, 16, v38
	v_cmp_le_u32_e64 s[0:1], 16, v39
	s_and_b64 s[0:1], vcc, s[0:1]
	s_and_saveexec_b64 s[10:11], s[0:1]
	v_lshlrev_b32_e32 v22, 16, v168
	v_and_b32_e32 v23, 0xffff0000, v168
	v_pk_add_f32 v[6:7], v[6:7], v[22:23]
	v_lshlrev_b32_e32 v22, 16, v169
	v_and_b32_e32 v23, 0xffff0000, v169
	v_pk_add_f32 v[8:9], v[8:9], v[22:23]
	v_lshlrev_b32_e32 v22, 16, v170
	v_and_b32_e32 v23, 0xffff0000, v170
	v_pk_add_f32 v[10:11], v[10:11], v[22:23]
	v_lshlrev_b32_e32 v22, 16, v171
	v_and_b32_e32 v23, 0xffff0000, v171
	v_pk_add_f32 v[16:17], v[16:17], v[22:23]
	s_or_b64 exec, exec, s[10:11]
	v_add_u32_e32 v18, 8, v38
	v_lshl_add_u32 v3, v18, 14, v40
	global_load_dwordx4 v[108:111], v3, s[6:7]
	v_sub_u32_e32 v19, v18, v39
	v_max_i32_e32 v19, 0, v19
	v_lshl_add_u32 v3, v19, 14, v40
	global_load_dwordx4 v[140:143], v3, s[6:7]
	v_add_u32_e32 v18, 9, v38
	v_lshl_add_u32 v3, v18, 14, v40
	global_load_dwordx4 v[112:115], v3, s[6:7]
	v_sub_u32_e32 v19, v18, v39
	v_max_i32_e32 v19, 0, v19
	v_lshl_add_u32 v3, v19, 14, v40
	global_load_dwordx4 v[144:147], v3, s[6:7]
	v_add_u32_e32 v18, 10, v38
	v_lshl_add_u32 v3, v18, 14, v40
	global_load_dwordx4 v[116:119], v3, s[6:7]
	v_sub_u32_e32 v19, v18, v39
	v_max_i32_e32 v19, 0, v19
	v_lshl_add_u32 v3, v19, 14, v40
	global_load_dwordx4 v[148:151], v3, s[6:7]
	v_add_u32_e32 v18, 11, v38
	v_lshl_add_u32 v3, v18, 14, v40
	global_load_dwordx4 v[120:123], v3, s[6:7]
	v_sub_u32_e32 v19, v18, v39
	v_max_i32_e32 v19, 0, v19
	v_lshl_add_u32 v3, v19, 14, v40
	global_load_dwordx4 v[152:155], v3, s[6:7]
	v_add_u32_e32 v18, 12, v38
	v_lshl_add_u32 v3, v18, 14, v40
	global_load_dwordx4 v[124:127], v3, s[6:7]
	v_sub_u32_e32 v19, v18, v39
	v_max_i32_e32 v19, 0, v19
	v_lshl_add_u32 v3, v19, 14, v40
	global_load_dwordx4 v[156:159], v3, s[6:7]
	v_add_u32_e32 v18, 13, v38
	v_lshl_add_u32 v3, v18, 14, v40
	global_load_dwordx4 v[128:131], v3, s[6:7]
	v_sub_u32_e32 v19, v18, v39
	v_max_i32_e32 v19, 0, v19
	v_lshl_add_u32 v3, v19, 14, v40
	global_load_dwordx4 v[160:163], v3, s[6:7]
	v_add_u32_e32 v18, 14, v38
	v_lshl_add_u32 v3, v18, 14, v40
	global_load_dwordx4 v[132:135], v3, s[6:7]
	v_sub_u32_e32 v19, v18, v39
	v_max_i32_e32 v19, 0, v19
	v_lshl_add_u32 v3, v19, 14, v40
	global_load_dwordx4 v[164:167], v3, s[6:7]
	v_add_u32_e32 v18, 15, v38
	v_lshl_add_u32 v3, v18, 14, v40
	global_load_dwordx4 v[136:139], v3, s[6:7]
	v_sub_u32_e32 v19, v18, v39
	v_max_i32_e32 v19, 0, v19
	v_lshl_add_u32 v3, v19, 14, v40
	global_load_dwordx4 v[168:171], v3, s[6:7]
	s_waitcnt vmcnt(16)
; __device__ __forceinline__ unsigned cvt_pk_bf16(float lo, float hi) { f32x2_t f = {lo, hi}; bf16x2_t v = __builtin_convertvector(f, bf16x2_t); return __builtin_bit_cast(unsigned, v); }
; __device__ __forceinline__ float bflo(unsigned w) { return __uint_as_float(w << 16); }
; __device__ __forceinline__ float bfhi(unsigned w) { return __uint_as_float(w & 0xffff0000u); }
; __device__ __forceinline__ void acc8(float (&s)[8], const u32x4 a, float sg) {
;     s[0] += sg * bflo(a.x); s[1] += sg * bfhi(a.x); s[2] += sg * bflo(a.y); s[3] += sg * bfhi(a.y); s[4] += sg * bflo(a.z); s[5] += sg * bfhi(a.z); s[6] += sg * bflo(a.w); s[7] += sg * bfhi(a.w);
; }
; __device__ NOINL void pool_diff(unsigned char* ws, int wv) {
;     ...
;         for (int j = 0; j < 32; ++j) { const int t = t0 + j;
;             const u32x4 cur = *(const u32x4*)(ap + (size_t)t * NPROJ);
;             acc8(s, cur, 1.0f);
;             if (t - w >= 0) acc8(s, *(const u32x4*)(ap + (size_t)(t - w) * NPROJ), -1.0f);
;             const int cnt = (t + 1) < w ? (t + 1) : w; const float inv = 1.0f / (float)cnt;
;             u32x4 o;
;             o.x = cvt_pk_bf16(s[0] * inv - bflo(cur.x), s[1] * inv - bfhi(cur.x)); o.y = cvt_pk_bf16(s[2] * inv - bflo(cur.y), s[3] * inv - bfhi(cur.y));
;             o.z = cvt_pk_bf16(s[4] * inv - bflo(cur.z), s[5] * inv - bfhi(cur.z)); o.w = cvt_pk_bf16(s[6] * inv - bflo(cur.w), s[7] * inv - bfhi(cur.w));
;             *(u32x4*)(Y0 + ((size_t)b * SEQ + t) * 1024 + c8 * 8) = o; }
	v_add_u32_e32 v24, 1, v38
	v_min_u32_e32 v24, v24, v39
	v_cvt_f32_ubyte0_e32 v24, v24
	v_div_scale_f32 v25, s[0:1], v24, v24, 1.0
	v_rcp_f32_e32 v30, v25
	v_div_scale_f32 v31, vcc, 1.0, v24, 1.0
	v_fma_f32 v32, -v25, v30, 1.0
	v_fmac_f32_e32 v30, v32, v30
	v_mul_f32_e32 v32, v31, v30
	v_fma_f32 v33, -v25, v32, v31
	v_fmac_f32_e32 v32, v33, v30
	v_fma_f32 v25, -v25, v32, v31
	v_div_fmas_f32 v25, v25, v30, v32
	v_div_fixup_f32 v36, v25, v24, 1.0
	v_lshlrev_b32_e32 v26, 16, v44
	v_and_b32_e32 v27, 0xffff0000, v44
	v_pk_add_f32 v[6:7], v[6:7], v[26:27]
	v_lshlrev_b32_e32 v28, 16, v45
	v_and_b32_e32 v29, 0xffff0000, v45
	v_pk_add_f32 v[8:9], v[8:9], v[28:29]
	v_lshlrev_b32_e32 v34, 16, v46
	v_and_b32_e32 v35, 0xffff0000, v46
	v_pk_add_f32 v[10:11], v[10:11], v[34:35]
	v_lshlrev_b32_e32 v42, 16, v47
	v_and_b32_e32 v43, 0xffff0000, v47
	v_pk_add_f32 v[16:17], v[16:17], v[42:43]
	v_add_u32_e32 v18, 0, v38
	v_cmp_le_u32_e32 vcc, v39, v18
	s_and_saveexec_b64 s[10:11], vcc
	v_lshlrev_b32_e32 v22, 16, v76
	v_and_b32_e32 v23, 0xffff0000, v76
	v_pk_add_f32 v[6:7], v[6:7], v[22:23] neg_lo:[0,1] neg_hi:[0,1]
	v_lshlrev_b32_e32 v22, 16, v77
	v_and_b32_e32 v23, 0xffff0000, v77
	v_pk_add_f32 v[8:9], v[8:9], v[22:23] neg_lo:[0,1] neg_hi:[0,1]
	v_lshlrev_b32_e32 v22, 16, v78
	v_and_b32_e32 v23, 0xffff0000, v78
	v_pk_add_f32 v[10:11], v[10:11], v[22:23] neg_lo:[0,1] neg_hi:[0,1]
	v_lshlrev_b32_e32 v22, 16, v79
	v_and_b32_e32 v23, 0xffff0000, v79
	v_pk_add_f32 v[16:17], v[16:17], v[22:23] neg_lo:[0,1] neg_hi:[0,1]
	s_or_b64 exec, exec, s[10:11]
	v_pk_fma_f32 v[26:27], v[36:37], v[6:7], v[26:27] op_sel_hi:[0,1,1] neg_lo:[0,0,1] neg_hi:[0,0,1]
	v_pk_fma_f32 v[28:29], v[36:37], v[8:9], v[28:29] op_sel_hi:[0,1,1] neg_lo:[0,0,1] neg_hi:[0,0,1]
	v_pk_fma_f32 v[34:35], v[36:37], v[10:11], v[34:35] op_sel_hi:[0,1,1] neg_lo:[0,0,1] neg_hi:[0,0,1]
	v_pk_fma_f32 v[42:43], v[36:37], v[16:17], v[42:43] op_sel_hi:[0,1,1] neg_lo:[0,0,1] neg_hi:[0,0,1]
	v_cvt_pk_bf16_f32 v44, v26, v27
	v_cvt_pk_bf16_f32 v45, v28, v29
	v_cvt_pk_bf16_f32 v46, v34, v35
	v_cvt_pk_bf16_f32 v47, v42, v43
	global_store_dwordx4 v41, v[44:47], s[16:17]
	v_add_u32_e32 v24, 2, v38
	v_min_u32_e32 v24, v24, v39
	v_cvt_f32_ubyte0_e32 v24, v24
	v_div_scale_f32 v25, s[0:1], v24, v24, 1.0
	v_rcp_f32_e32 v30, v25
	v_div_scale_f32 v31, vcc, 1.0, v24, 1.0
	v_fma_f32 v32, -v25, v30, 1.0
	v_fmac_f32_e32 v30, v32, v30
	v_mul_f32_e32 v32, v31, v30
	v_fma_f32 v33, -v25, v32, v31
	v_fmac_f32_e32 v32, v33, v30
	v_fma_f32 v25, -v25, v32, v31
	v_div_fmas_f32 v25, v25, v30, v32
	v_div_fixup_f32 v36, v25, v24, 1.0
	v_lshlrev_b32_e32 v26, 16, v48
	v_and_b32_e32 v27, 0xffff0000, v48
	v_pk_add_f32 v[6:7], v[6:7], v[26:27]
	v_lshlrev_b32_e32 v28, 16, v49
	v_and_b32_e32 v29, 0xffff0000, v49
	v_pk_add_f32 v[8:9], v[8:9], v[28:29]
	v_lshlrev_b32_e32 v34, 16, v50
	v_and_b32_e32 v35, 0xffff0000, v50
	v_pk_add_f32 v[10:11], v[10:11], v[34:35]
	v_lshlrev_b32_e32 v42, 16, v51
	v_and_b32_e32 v43, 0xffff0000, v51
	v_pk_add_f32 v[16:17], v[16:17], v[42:43]
	v_add_u32_e32 v18, 1, v38
	v_cmp_le_u32_e32 vcc, v39, v18
	s_and_saveexec_b64 s[10:11], vcc
	v_lshlrev_b32_e32 v22, 16, v80
	v_and_b32_e32 v23, 0xffff0000, v80
	v_pk_add_f32 v[6:7], v[6:7], v[22:23] neg_lo:[0,1] neg_hi:[0,1]
	v_lshlrev_b32_e32 v22, 16, v81
	v_and_b32_e32 v23, 0xffff0000, v81
	v_pk_add_f32 v[8:9], v[8:9], v[22:23] neg_lo:[0,1] neg_hi:[0,1]
	v_lshlrev_b32_e32 v22, 16, v82
	v_and_b32_e32 v23, 0xffff0000, v82
	v_pk_add_f32 v[10:11], v[10:11], v[22:23] neg_lo:[0,1] neg_hi:[0,1]
	v_lshlrev_b32_e32 v22, 16, v83
	v_and_b32_e32 v23, 0xffff0000, v83
	v_pk_add_f32 v[16:17], v[16:17], v[22:23] neg_lo:[0,1] neg_hi:[0,1]
	s_or_b64 exec, exec, s[10:11]
	v_pk_fma_f32 v[26:27], v[36:37], v[6:7], v[26:27] op_sel_hi:[0,1,1] neg_lo:[0,0,1] neg_hi:[0,0,1]
	v_pk_fma_f32 v[28:29], v[36:37], v[8:9], v[28:29] op_sel_hi:[0,1,1] neg_lo:[0,0,1] neg_hi:[0,0,1]
	v_pk_fma_f32 v[34:35], v[36:37], v[10:11], v[34:35] op_sel_hi:[0,1,1] neg_lo:[0,0,1] neg_hi:[0,0,1]
	v_pk_fma_f32 v[42:43], v[36:37], v[16:17], v[42:43] op_sel_hi:[0,1,1] neg_lo:[0,0,1] neg_hi:[0,0,1]
	v_cvt_pk_bf16_f32 v48, v26, v27
	v_cvt_pk_bf16_f32 v49, v28, v29
	v_cvt_pk_bf16_f32 v50, v34, v35
	v_cvt_pk_bf16_f32 v51, v42, v43
	global_store_dwordx4 v41, v[48:51], s[16:17] offset:2048
	v_add_u32_e32 v24, 3, v38
	v_min_u32_e32 v24, v24, v39
	v_cvt_f32_ubyte0_e32 v24, v24
	v_div_scale_f32 v25, s[0:1], v24, v24, 1.0
	v_rcp_f32_e32 v30, v25
	v_div_scale_f32 v31, vcc, 1.0, v24, 1.0
	v_fma_f32 v32, -v25, v30, 1.0
	v_fmac_f32_e32 v30, v32, v30
	v_mul_f32_e32 v32, v31, v30
	v_fma_f32 v33, -v25, v32, v31
	v_fmac_f32_e32 v32, v33, v30
	v_fma_f32 v25, -v25, v32, v31
	v_div_fmas_f32 v25, v25, v30, v32
	v_div_fixup_f32 v36, v25, v24, 1.0
	v_lshlrev_b32_e32 v26, 16, v52
	v_and_b32_e32 v27, 0xffff0000, v52
	v_pk_add_f32 v[6:7], v[6:7], v[26:27]
	v_lshlrev_b32_e32 v28, 16, v53
	v_and_b32_e32 v29, 0xffff0000, v53
	v_pk_add_f32 v[8:9], v[8:9], v[28:29]
	v_lshlrev_b32_e32 v34, 16, v54
	v_and_b32_e32 v35, 0xffff0000, v54
	v_pk_add_f32 v[10:11], v[10:11], v[34:35]
	v_lshlrev_b32_e32 v42, 16, v55
	v_and_b32_e32 v43, 0xffff0000, v55
	v_pk_add_f32 v[16:17], v[16:17], v[42:43]
	v_add_u32_e32 v18, 2, v38
	v_cmp_le_u32_e32 vcc, v39, v18
	s_and_saveexec_b64 s[10:11], vcc
	v_lshlrev_b32_e32 v22, 16, v84
	v_and_b32_e32 v23, 0xffff0000, v84
	v_pk_add_f32 v[6:7], v[6:7], v[22:23] neg_lo:[0,1] neg_hi:[0,1]
	v_lshlrev_b32_e32 v22, 16, v85
	v_and_b32_e32 v23, 0xffff0000, v85
	v_pk_add_f32 v[8:9], v[8:9], v[22:23] neg_lo:[0,1] neg_hi:[0,1]
	v_lshlrev_b32_e32 v22, 16, v86
	v_and_b32_e32 v23, 0xffff0000, v86
	v_pk_add_f32 v[10:11], v[10:11], v[22:23] neg_lo:[0,1] neg_hi:[0,1]
; __device__ __forceinline__ unsigned cvt_pk_bf16(float lo, float hi) { f32x2_t f = {lo, hi}; bf16x2_t v = __builtin_convertvector(f, bf16x2_t); return __builtin_bit_cast(unsigned, v); }
; __device__ __forceinline__ float bflo(unsigned w) { return __uint_as_float(w << 16); }
; __device__ __forceinline__ float bfhi(unsigned w) { return __uint_as_float(w & 0xffff0000u); }
; __device__ __forceinline__ void acc8(float (&s)[8], const u32x4 a, float sg) {
;     s[0] += sg * bflo(a.x); s[1] += sg * bfhi(a.x); s[2] += sg * bflo(a.y); s[3] += sg * bfhi(a.y); s[4] += sg * bflo(a.z); s[5] += sg * bfhi(a.z); s[6] += sg * bflo(a.w); s[7] += sg * bfhi(a.w);
; }
; __device__ NOINL void pool_diff(unsigned char* ws, int wv) {
;     ...
;         for (int j = 0; j < 32; ++j) { const int t = t0 + j;
;             const u32x4 cur = *(const u32x4*)(ap + (size_t)t * NPROJ);
;             acc8(s, cur, 1.0f);
;             if (t - w >= 0) acc8(s, *(const u32x4*)(ap + (size_t)(t - w) * NPROJ), -1.0f);
;             const int cnt = (t + 1) < w ? (t + 1) : w; const float inv = 1.0f / (float)cnt;
;             u32x4 o;
;             o.x = cvt_pk_bf16(s[0] * inv - bflo(cur.x), s[1] * inv - bfhi(cur.x)); o.y = cvt_pk_bf16(s[2] * inv - bflo(cur.y), s[3] * inv - bfhi(cur.y));
;             o.z = cvt_pk_bf16(s[4] * inv - bflo(cur.z), s[5] * inv - bfhi(cur.z)); o.w = cvt_pk_bf16(s[6] * inv - bflo(cur.w), s[7] * inv - bfhi(cur.w));
;             *(u32x4*)(Y0 + ((size_t)b * SEQ + t) * 1024 + c8 * 8) = o; }
	v_lshlrev_b32_e32 v22, 16, v87
	v_and_b32_e32 v23, 0xffff0000, v87
	v_pk_add_f32 v[16:17], v[16:17], v[22:23] neg_lo:[0,1] neg_hi:[0,1]
	s_or_b64 exec, exec, s[10:11]
	v_pk_fma_f32 v[26:27], v[36:37], v[6:7], v[26:27] op_sel_hi:[0,1,1] neg_lo:[0,0,1] neg_hi:[0,0,1]
	v_pk_fma_f32 v[28:29], v[36:37], v[8:9], v[28:29] op_sel_hi:[0,1,1] neg_lo:[0,0,1] neg_hi:[0,0,1]
	v_pk_fma_f32 v[34:35], v[36:37], v[10:11], v[34:35] op_sel_hi:[0,1,1] neg_lo:[0,0,1] neg_hi:[0,0,1]
	v_pk_fma_f32 v[42:43], v[36:37], v[16:17], v[42:43] op_sel_hi:[0,1,1] neg_lo:[0,0,1] neg_hi:[0,0,1]
	v_cvt_pk_bf16_f32 v52, v26, v27
	v_cvt_pk_bf16_f32 v53, v28, v29
	v_cvt_pk_bf16_f32 v54, v34, v35
	v_cvt_pk_bf16_f32 v55, v42, v43
	v_add_u32_e32 v41, 0x1000, v41
	global_store_dwordx4 v41, v[52:55], s[16:17]
	v_add_u32_e32 v24, 4, v38
	v_min_u32_e32 v24, v24, v39
	v_cvt_f32_ubyte0_e32 v24, v24
	v_div_scale_f32 v25, s[0:1], v24, v24, 1.0
	v_rcp_f32_e32 v30, v25
	v_div_scale_f32 v31, vcc, 1.0, v24, 1.0
	v_fma_f32 v32, -v25, v30, 1.0
	v_fmac_f32_e32 v30, v32, v30
	v_mul_f32_e32 v32, v31, v30
	v_fma_f32 v33, -v25, v32, v31
	v_fmac_f32_e32 v32, v33, v30
	v_fma_f32 v25, -v25, v32, v31
	v_div_fmas_f32 v25, v25, v30, v32
	v_div_fixup_f32 v36, v25, v24, 1.0
	v_lshlrev_b32_e32 v26, 16, v56
	v_and_b32_e32 v27, 0xffff0000, v56
	v_pk_add_f32 v[6:7], v[6:7], v[26:27]
	v_lshlrev_b32_e32 v28, 16, v57
	v_and_b32_e32 v29, 0xffff0000, v57
	v_pk_add_f32 v[8:9], v[8:9], v[28:29]
	v_lshlrev_b32_e32 v34, 16, v58
	v_and_b32_e32 v35, 0xffff0000, v58
	v_pk_add_f32 v[10:11], v[10:11], v[34:35]
	v_lshlrev_b32_e32 v42, 16, v59
	v_and_b32_e32 v43, 0xffff0000, v59
	v_pk_add_f32 v[16:17], v[16:17], v[42:43]
	v_add_u32_e32 v18, 3, v38
	v_cmp_le_u32_e32 vcc, v39, v18
	s_and_saveexec_b64 s[10:11], vcc
	v_lshlrev_b32_e32 v22, 16, v88
	v_and_b32_e32 v23, 0xffff0000, v88
	v_pk_add_f32 v[6:7], v[6:7], v[22:23] neg_lo:[0,1] neg_hi:[0,1]
	v_lshlrev_b32_e32 v22, 16, v89
	v_and_b32_e32 v23, 0xffff0000, v89
	v_pk_add_f32 v[8:9], v[8:9], v[22:23] neg_lo:[0,1] neg_hi:[0,1]
	v_lshlrev_b32_e32 v22, 16, v90
	v_and_b32_e32 v23, 0xffff0000, v90
	v_pk_add_f32 v[10:11], v[10:11], v[22:23] neg_lo:[0,1] neg_hi:[0,1]
	v_lshlrev_b32_e32 v22, 16, v91
	v_and_b32_e32 v23, 0xffff0000, v91
	v_pk_add_f32 v[16:17], v[16:17], v[22:23] neg_lo:[0,1] neg_hi:[0,1]
	s_or_b64 exec, exec, s[10:11]
	v_pk_fma_f32 v[26:27], v[36:37], v[6:7], v[26:27] op_sel_hi:[0,1,1] neg_lo:[0,0,1] neg_hi:[0,0,1]
	v_pk_fma_f32 v[28:29], v[36:37], v[8:9], v[28:29] op_sel_hi:[0,1,1] neg_lo:[0,0,1] neg_hi:[0,0,1]
	v_pk_fma_f32 v[34:35], v[36:37], v[10:11], v[34:35] op_sel_hi:[0,1,1] neg_lo:[0,0,1] neg_hi:[0,0,1]
	v_pk_fma_f32 v[42:43], v[36:37], v[16:17], v[42:43] op_sel_hi:[0,1,1] neg_lo:[0,0,1] neg_hi:[0,0,1]
	v_cvt_pk_bf16_f32 v56, v26, v27
	v_cvt_pk_bf16_f32 v57, v28, v29
	v_cvt_pk_bf16_f32 v58, v34, v35
	v_cvt_pk_bf16_f32 v59, v42, v43
	global_store_dwordx4 v41, v[56:59], s[16:17] offset:2048
	v_add_u32_e32 v24, 5, v38
	v_min_u32_e32 v24, v24, v39
	v_cvt_f32_ubyte0_e32 v24, v24
	v_div_scale_f32 v25, s[0:1], v24, v24, 1.0
	v_rcp_f32_e32 v30, v25
	v_div_scale_f32 v31, vcc, 1.0, v24, 1.0
	v_fma_f32 v32, -v25, v30, 1.0
	v_fmac_f32_e32 v30, v32, v30
	v_mul_f32_e32 v32, v31, v30
	v_fma_f32 v33, -v25, v32, v31
	v_fmac_f32_e32 v32, v33, v30
	v_fma_f32 v25, -v25, v32, v31
	v_div_fmas_f32 v25, v25, v30, v32
	v_div_fixup_f32 v36, v25, v24, 1.0
	v_lshlrev_b32_e32 v26, 16, v60
	v_and_b32_e32 v27, 0xffff0000, v60
	v_pk_add_f32 v[6:7], v[6:7], v[26:27]
	v_lshlrev_b32_e32 v28, 16, v61
	v_and_b32_e32 v29, 0xffff0000, v61
	v_pk_add_f32 v[8:9], v[8:9], v[28:29]
	v_lshlrev_b32_e32 v34, 16, v62
	v_and_b32_e32 v35, 0xffff0000, v62
	v_pk_add_f32 v[10:11], v[10:11], v[34:35]
	v_lshlrev_b32_e32 v42, 16, v63
	v_and_b32_e32 v43, 0xffff0000, v63
	v_pk_add_f32 v[16:17], v[16:17], v[42:43]
	v_add_u32_e32 v18, 4, v38
	v_cmp_le_u32_e32 vcc, v39, v18
	s_and_saveexec_b64 s[10:11], vcc
	v_lshlrev_b32_e32 v22, 16, v92
	v_and_b32_e32 v23, 0xffff0000, v92
	v_pk_add_f32 v[6:7], v[6:7], v[22:23] neg_lo:[0,1] neg_hi:[0,1]
	v_lshlrev_b32_e32 v22, 16, v93
	v_and_b32_e32 v23, 0xffff0000, v93
	v_pk_add_f32 v[8:9], v[8:9], v[22:23] neg_lo:[0,1] neg_hi:[0,1]
	v_lshlrev_b32_e32 v22, 16, v94
	v_and_b32_e32 v23, 0xffff0000, v94
	v_pk_add_f32 v[10:11], v[10:11], v[22:23] neg_lo:[0,1] neg_hi:[0,1]
	v_lshlrev_b32_e32 v22, 16, v95
	v_and_b32_e32 v23, 0xffff0000, v95
	v_pk_add_f32 v[16:17], v[16:17], v[22:23] neg_lo:[0,1] neg_hi:[0,1]
	s_or_b64 exec, exec, s[10:11]
	v_pk_fma_f32 v[26:27], v[36:37], v[6:7], v[26:27] op_sel_hi:[0,1,1] neg_lo:[0,0,1] neg_hi:[0,0,1]
	v_pk_fma_f32 v[28:29], v[36:37], v[8:9], v[28:29] op_sel_hi:[0,1,1] neg_lo:[0,0,1] neg_hi:[0,0,1]
	v_pk_fma_f32 v[34:35], v[36:37], v[10:11], v[34:35] op_sel_hi:[0,1,1] neg_lo:[0,0,1] neg_hi:[0,0,1]
	v_pk_fma_f32 v[42:43], v[36:37], v[16:17], v[42:43] op_sel_hi:[0,1,1] neg_lo:[0,0,1] neg_hi:[0,0,1]
	v_cvt_pk_bf16_f32 v60, v26, v27
	v_cvt_pk_bf16_f32 v61, v28, v29
	v_cvt_pk_bf16_f32 v62, v34, v35
	v_cvt_pk_bf16_f32 v63, v42, v43
	v_add_u32_e32 v41, 0x1000, v41
	global_store_dwordx4 v41, v[60:63], s[16:17]
	v_add_u32_e32 v24, 6, v38
	v_min_u32_e32 v24, v24, v39
	v_cvt_f32_ubyte0_e32 v24, v24
	v_div_scale_f32 v25, s[0:1], v24, v24, 1.0
	v_rcp_f32_e32 v30, v25
	v_div_scale_f32 v31, vcc, 1.0, v24, 1.0
	v_fma_f32 v32, -v25, v30, 1.0
	v_fmac_f32_e32 v30, v32, v30
	v_mul_f32_e32 v32, v31, v30
	v_fma_f32 v33, -v25, v32, v31
	v_fmac_f32_e32 v32, v33, v30
	v_fma_f32 v25, -v25, v32, v31
	v_div_fmas_f32 v25, v25, v30, v32
	v_div_fixup_f32 v36, v25, v24, 1.0
	v_lshlrev_b32_e32 v26, 16, v64
	v_and_b32_e32 v27, 0xffff0000, v64
	v_pk_add_f32 v[6:7], v[6:7], v[26:27]
; __device__ __forceinline__ unsigned cvt_pk_bf16(float lo, float hi) { f32x2_t f = {lo, hi}; bf16x2_t v = __builtin_convertvector(f, bf16x2_t); return __builtin_bit_cast(unsigned, v); }
; __device__ __forceinline__ float bflo(unsigned w) { return __uint_as_float(w << 16); }
; __device__ __forceinline__ float bfhi(unsigned w) { return __uint_as_float(w & 0xffff0000u); }
; __device__ __forceinline__ void acc8(float (&s)[8], const u32x4 a, float sg) {
;     s[0] += sg * bflo(a.x); s[1] += sg * bfhi(a.x); s[2] += sg * bflo(a.y); s[3] += sg * bfhi(a.y); s[4] += sg * bflo(a.z); s[5] += sg * bfhi(a.z); s[6] += sg * bflo(a.w); s[7] += sg * bfhi(a.w);
; }
; __device__ NOINL void pool_diff(unsigned char* ws, int wv) {
;     ...
;         for (int j = 0; j < 32; ++j) { const int t = t0 + j;
;             const u32x4 cur = *(const u32x4*)(ap + (size_t)t * NPROJ);
;             acc8(s, cur, 1.0f);
;             if (t - w >= 0) acc8(s, *(const u32x4*)(ap + (size_t)(t - w) * NPROJ), -1.0f);
;             const int cnt = (t + 1) < w ? (t + 1) : w; const float inv = 1.0f / (float)cnt;
;             u32x4 o;
;             o.x = cvt_pk_bf16(s[0] * inv - bflo(cur.x), s[1] * inv - bfhi(cur.x)); o.y = cvt_pk_bf16(s[2] * inv - bflo(cur.y), s[3] * inv - bfhi(cur.y));
;             o.z = cvt_pk_bf16(s[4] * inv - bflo(cur.z), s[5] * inv - bfhi(cur.z)); o.w = cvt_pk_bf16(s[6] * inv - bflo(cur.w), s[7] * inv - bfhi(cur.w));
;             *(u32x4*)(Y0 + ((size_t)b * SEQ + t) * 1024 + c8 * 8) = o; }
	v_lshlrev_b32_e32 v28, 16, v65
	v_and_b32_e32 v29, 0xffff0000, v65
	v_pk_add_f32 v[8:9], v[8:9], v[28:29]
	v_lshlrev_b32_e32 v34, 16, v66
	v_and_b32_e32 v35, 0xffff0000, v66
	v_pk_add_f32 v[10:11], v[10:11], v[34:35]
	v_lshlrev_b32_e32 v42, 16, v67
	v_and_b32_e32 v43, 0xffff0000, v67
	v_pk_add_f32 v[16:17], v[16:17], v[42:43]
	v_add_u32_e32 v18, 5, v38
	v_cmp_le_u32_e32 vcc, v39, v18
	s_and_saveexec_b64 s[10:11], vcc
	v_lshlrev_b32_e32 v22, 16, v96
	v_and_b32_e32 v23, 0xffff0000, v96
	v_pk_add_f32 v[6:7], v[6:7], v[22:23] neg_lo:[0,1] neg_hi:[0,1]
	v_lshlrev_b32_e32 v22, 16, v97
	v_and_b32_e32 v23, 0xffff0000, v97
	v_pk_add_f32 v[8:9], v[8:9], v[22:23] neg_lo:[0,1] neg_hi:[0,1]
	v_lshlrev_b32_e32 v22, 16, v98
	v_and_b32_e32 v23, 0xffff0000, v98
	v_pk_add_f32 v[10:11], v[10:11], v[22:23] neg_lo:[0,1] neg_hi:[0,1]
	v_lshlrev_b32_e32 v22, 16, v99
	v_and_b32_e32 v23, 0xffff0000, v99
	v_pk_add_f32 v[16:17], v[16:17], v[22:23] neg_lo:[0,1] neg_hi:[0,1]
	s_or_b64 exec, exec, s[10:11]
	v_pk_fma_f32 v[26:27], v[36:37], v[6:7], v[26:27] op_sel_hi:[0,1,1] neg_lo:[0,0,1] neg_hi:[0,0,1]
	v_pk_fma_f32 v[28:29], v[36:37], v[8:9], v[28:29] op_sel_hi:[0,1,1] neg_lo:[0,0,1] neg_hi:[0,0,1]
	v_pk_fma_f32 v[34:35], v[36:37], v[10:11], v[34:35] op_sel_hi:[0,1,1] neg_lo:[0,0,1] neg_hi:[0,0,1]
	v_pk_fma_f32 v[42:43], v[36:37], v[16:17], v[42:43] op_sel_hi:[0,1,1] neg_lo:[0,0,1] neg_hi:[0,0,1]
	v_cvt_pk_bf16_f32 v64, v26, v27
	v_cvt_pk_bf16_f32 v65, v28, v29
	v_cvt_pk_bf16_f32 v66, v34, v35
	v_cvt_pk_bf16_f32 v67, v42, v43
	global_store_dwordx4 v41, v[64:67], s[16:17] offset:2048
	v_add_u32_e32 v24, 7, v38
	v_min_u32_e32 v24, v24, v39
	v_cvt_f32_ubyte0_e32 v24, v24
	v_div_scale_f32 v25, s[0:1], v24, v24, 1.0
	v_rcp_f32_e32 v30, v25
	v_div_scale_f32 v31, vcc, 1.0, v24, 1.0
	v_fma_f32 v32, -v25, v30, 1.0
	v_fmac_f32_e32 v30, v32, v30
	v_mul_f32_e32 v32, v31, v30
	v_fma_f32 v33, -v25, v32, v31
	v_fmac_f32_e32 v32, v33, v30
	v_fma_f32 v25, -v25, v32, v31
	v_div_fmas_f32 v25, v25, v30, v32
	v_div_fixup_f32 v36, v25, v24, 1.0
	v_lshlrev_b32_e32 v26, 16, v68
	v_and_b32_e32 v27, 0xffff0000, v68
	v_pk_add_f32 v[6:7], v[6:7], v[26:27]
	v_lshlrev_b32_e32 v28, 16, v69
	v_and_b32_e32 v29, 0xffff0000, v69
	v_pk_add_f32 v[8:9], v[8:9], v[28:29]
	v_lshlrev_b32_e32 v34, 16, v70
	v_and_b32_e32 v35, 0xffff0000, v70
	v_pk_add_f32 v[10:11], v[10:11], v[34:35]
	v_lshlrev_b32_e32 v42, 16, v71
	v_and_b32_e32 v43, 0xffff0000, v71
	v_pk_add_f32 v[16:17], v[16:17], v[42:43]
	v_add_u32_e32 v18, 6, v38
	v_cmp_le_u32_e32 vcc, v39, v18
	s_and_saveexec_b64 s[10:11], vcc
	v_lshlrev_b32_e32 v22, 16, v100
	v_and_b32_e32 v23, 0xffff0000, v100
	v_pk_add_f32 v[6:7], v[6:7], v[22:23] neg_lo:[0,1] neg_hi:[0,1]
	v_lshlrev_b32_e32 v22, 16, v101
	v_and_b32_e32 v23, 0xffff0000, v101
	v_pk_add_f32 v[8:9], v[8:9], v[22:23] neg_lo:[0,1] neg_hi:[0,1]
	v_lshlrev_b32_e32 v22, 16, v102
	v_and_b32_e32 v23, 0xffff0000, v102
	v_pk_add_f32 v[10:11], v[10:11], v[22:23] neg_lo:[0,1] neg_hi:[0,1]
	v_lshlrev_b32_e32 v22, 16, v103
	v_and_b32_e32 v23, 0xffff0000, v103
	v_pk_add_f32 v[16:17], v[16:17], v[22:23] neg_lo:[0,1] neg_hi:[0,1]
	s_or_b64 exec, exec, s[10:11]
	v_pk_fma_f32 v[26:27], v[36:37], v[6:7], v[26:27] op_sel_hi:[0,1,1] neg_lo:[0,0,1] neg_hi:[0,0,1]
	v_pk_fma_f32 v[28:29], v[36:37], v[8:9], v[28:29] op_sel_hi:[0,1,1] neg_lo:[0,0,1] neg_hi:[0,0,1]
	v_pk_fma_f32 v[34:35], v[36:37], v[10:11], v[34:35] op_sel_hi:[0,1,1] neg_lo:[0,0,1] neg_hi:[0,0,1]
	v_pk_fma_f32 v[42:43], v[36:37], v[16:17], v[42:43] op_sel_hi:[0,1,1] neg_lo:[0,0,1] neg_hi:[0,0,1]
	v_cvt_pk_bf16_f32 v68, v26, v27
	v_cvt_pk_bf16_f32 v69, v28, v29
	v_cvt_pk_bf16_f32 v70, v34, v35
	v_cvt_pk_bf16_f32 v71, v42, v43
	v_add_u32_e32 v41, 0x1000, v41
	global_store_dwordx4 v41, v[68:71], s[16:17]
	v_add_u32_e32 v24, 8, v38
	v_min_u32_e32 v24, v24, v39
	v_cvt_f32_ubyte0_e32 v24, v24
	v_div_scale_f32 v25, s[0:1], v24, v24, 1.0
	v_rcp_f32_e32 v30, v25
	v_div_scale_f32 v31, vcc, 1.0, v24, 1.0
	v_fma_f32 v32, -v25, v30, 1.0
	v_fmac_f32_e32 v30, v32, v30
	v_mul_f32_e32 v32, v31, v30
	v_fma_f32 v33, -v25, v32, v31
	v_fmac_f32_e32 v32, v33, v30
	v_fma_f32 v25, -v25, v32, v31
	v_div_fmas_f32 v25, v25, v30, v32
	v_div_fixup_f32 v36, v25, v24, 1.0
	v_lshlrev_b32_e32 v26, 16, v72
	v_and_b32_e32 v27, 0xffff0000, v72
	v_pk_add_f32 v[6:7], v[6:7], v[26:27]
	v_lshlrev_b32_e32 v28, 16, v73
	v_and_b32_e32 v29, 0xffff0000, v73
	v_pk_add_f32 v[8:9], v[8:9], v[28:29]
	v_lshlrev_b32_e32 v34, 16, v74
	v_and_b32_e32 v35, 0xffff0000, v74
	v_pk_add_f32 v[10:11], v[10:11], v[34:35]
	v_lshlrev_b32_e32 v42, 16, v75
	v_and_b32_e32 v43, 0xffff0000, v75
	v_pk_add_f32 v[16:17], v[16:17], v[42:43]
	v_add_u32_e32 v18, 7, v38
	v_cmp_le_u32_e32 vcc, v39, v18
	s_and_saveexec_b64 s[10:11], vcc
	v_lshlrev_b32_e32 v22, 16, v104
	v_and_b32_e32 v23, 0xffff0000, v104
	v_pk_add_f32 v[6:7], v[6:7], v[22:23] neg_lo:[0,1] neg_hi:[0,1]
	v_lshlrev_b32_e32 v22, 16, v105
	v_and_b32_e32 v23, 0xffff0000, v105
	v_pk_add_f32 v[8:9], v[8:9], v[22:23] neg_lo:[0,1] neg_hi:[0,1]
	v_lshlrev_b32_e32 v22, 16, v106
	v_and_b32_e32 v23, 0xffff0000, v106
	v_pk_add_f32 v[10:11], v[10:11], v[22:23] neg_lo:[0,1] neg_hi:[0,1]
	v_lshlrev_b32_e32 v22, 16, v107
	v_and_b32_e32 v23, 0xffff0000, v107
	v_pk_add_f32 v[16:17], v[16:17], v[22:23] neg_lo:[0,1] neg_hi:[0,1]
	s_or_b64 exec, exec, s[10:11]
	v_pk_fma_f32 v[26:27], v[36:37], v[6:7], v[26:27] op_sel_hi:[0,1,1] neg_lo:[0,0,1] neg_hi:[0,0,1]
	v_pk_fma_f32 v[28:29], v[36:37], v[8:9], v[28:29] op_sel_hi:[0,1,1] neg_lo:[0,0,1] neg_hi:[0,0,1]
	v_pk_fma_f32 v[34:35], v[36:37], v[10:11], v[34:35] op_sel_hi:[0,1,1] neg_lo:[0,0,1] neg_hi:[0,0,1]
; __device__ __forceinline__ unsigned cvt_pk_bf16(float lo, float hi) { f32x2_t f = {lo, hi}; bf16x2_t v = __builtin_convertvector(f, bf16x2_t); return __builtin_bit_cast(unsigned, v); }
; __device__ __forceinline__ float bflo(unsigned w) { return __uint_as_float(w << 16); }
; __device__ __forceinline__ float bfhi(unsigned w) { return __uint_as_float(w & 0xffff0000u); }
; __device__ __forceinline__ void acc8(float (&s)[8], const u32x4 a, float sg) {
;     s[0] += sg * bflo(a.x); s[1] += sg * bfhi(a.x); s[2] += sg * bflo(a.y); s[3] += sg * bfhi(a.y); s[4] += sg * bflo(a.z); s[5] += sg * bfhi(a.z); s[6] += sg * bflo(a.w); s[7] += sg * bfhi(a.w);
; }
; __device__ NOINL void pool_diff(unsigned char* ws, int wv) {
;     ...
;         for (int j = 0; j < 32; ++j) { const int t = t0 + j;
;             const u32x4 cur = *(const u32x4*)(ap + (size_t)t * NPROJ);
;             acc8(s, cur, 1.0f);
;             if (t - w >= 0) acc8(s, *(const u32x4*)(ap + (size_t)(t - w) * NPROJ), -1.0f);
;             const int cnt = (t + 1) < w ? (t + 1) : w; const float inv = 1.0f / (float)cnt;
;             u32x4 o;
;             o.x = cvt_pk_bf16(s[0] * inv - bflo(cur.x), s[1] * inv - bfhi(cur.x)); o.y = cvt_pk_bf16(s[2] * inv - bflo(cur.y), s[3] * inv - bfhi(cur.y));
;             o.z = cvt_pk_bf16(s[4] * inv - bflo(cur.z), s[5] * inv - bfhi(cur.z)); o.w = cvt_pk_bf16(s[6] * inv - bflo(cur.w), s[7] * inv - bfhi(cur.w));
;             *(u32x4*)(Y0 + ((size_t)b * SEQ + t) * 1024 + c8 * 8) = o; }
	v_pk_fma_f32 v[42:43], v[36:37], v[16:17], v[42:43] op_sel_hi:[0,1,1] neg_lo:[0,0,1] neg_hi:[0,0,1]
	v_cvt_pk_bf16_f32 v72, v26, v27
	v_cvt_pk_bf16_f32 v73, v28, v29
	v_cvt_pk_bf16_f32 v74, v34, v35
	v_cvt_pk_bf16_f32 v75, v42, v43
	global_store_dwordx4 v41, v[72:75], s[16:17] offset:2048
	s_nop 1
	v_add_u32_e32 v18, 16, v38
	v_lshl_add_u32 v3, v18, 14, v40
	global_load_dwordx4 v[44:47], v3, s[6:7]
	v_sub_u32_e32 v19, v18, v39
	v_max_i32_e32 v19, 0, v19
	v_lshl_add_u32 v3, v19, 14, v40
	global_load_dwordx4 v[76:79], v3, s[6:7]
	v_add_u32_e32 v18, 17, v38
	v_lshl_add_u32 v3, v18, 14, v40
	global_load_dwordx4 v[48:51], v3, s[6:7]
	v_sub_u32_e32 v19, v18, v39
	v_max_i32_e32 v19, 0, v19
	v_lshl_add_u32 v3, v19, 14, v40
	global_load_dwordx4 v[80:83], v3, s[6:7]
	v_add_u32_e32 v18, 18, v38
	v_lshl_add_u32 v3, v18, 14, v40
	global_load_dwordx4 v[52:55], v3, s[6:7]
	v_sub_u32_e32 v19, v18, v39
	v_max_i32_e32 v19, 0, v19
	v_lshl_add_u32 v3, v19, 14, v40
	global_load_dwordx4 v[84:87], v3, s[6:7]
	v_add_u32_e32 v18, 19, v38
	v_lshl_add_u32 v3, v18, 14, v40
	global_load_dwordx4 v[56:59], v3, s[6:7]
	v_sub_u32_e32 v19, v18, v39
	v_max_i32_e32 v19, 0, v19
	v_lshl_add_u32 v3, v19, 14, v40
	global_load_dwordx4 v[88:91], v3, s[6:7]
	v_add_u32_e32 v18, 20, v38
	v_lshl_add_u32 v3, v18, 14, v40
	global_load_dwordx4 v[60:63], v3, s[6:7]
	v_sub_u32_e32 v19, v18, v39
	v_max_i32_e32 v19, 0, v19
	v_lshl_add_u32 v3, v19, 14, v40
	global_load_dwordx4 v[92:95], v3, s[6:7]
	v_add_u32_e32 v18, 21, v38
	v_lshl_add_u32 v3, v18, 14, v40
	global_load_dwordx4 v[64:67], v3, s[6:7]
	v_sub_u32_e32 v19, v18, v39
	v_max_i32_e32 v19, 0, v19
	v_lshl_add_u32 v3, v19, 14, v40
	global_load_dwordx4 v[96:99], v3, s[6:7]
	v_add_u32_e32 v18, 22, v38
	v_lshl_add_u32 v3, v18, 14, v40
	global_load_dwordx4 v[68:71], v3, s[6:7]
	v_sub_u32_e32 v19, v18, v39
	v_max_i32_e32 v19, 0, v19
	v_lshl_add_u32 v3, v19, 14, v40
	global_load_dwordx4 v[100:103], v3, s[6:7]
	v_add_u32_e32 v18, 23, v38
	v_lshl_add_u32 v3, v18, 14, v40
	global_load_dwordx4 v[72:75], v3, s[6:7]
	v_sub_u32_e32 v19, v18, v39
	v_max_i32_e32 v19, 0, v19
	v_lshl_add_u32 v3, v19, 14, v40
	global_load_dwordx4 v[104:107], v3, s[6:7]
	s_waitcnt vmcnt(24)
	v_add_u32_e32 v24, 9, v38
	v_min_u32_e32 v24, v24, v39
	v_cvt_f32_ubyte0_e32 v24, v24
	v_div_scale_f32 v25, s[0:1], v24, v24, 1.0
	v_rcp_f32_e32 v30, v25
	v_div_scale_f32 v31, vcc, 1.0, v24, 1.0
	v_fma_f32 v32, -v25, v30, 1.0
	v_fmac_f32_e32 v30, v32, v30
	v_mul_f32_e32 v32, v31, v30
	v_fma_f32 v33, -v25, v32, v31
	v_fmac_f32_e32 v32, v33, v30
	v_fma_f32 v25, -v25, v32, v31
	v_div_fmas_f32 v25, v25, v30, v32
	v_div_fixup_f32 v36, v25, v24, 1.0
	v_lshlrev_b32_e32 v26, 16, v108
	v_and_b32_e32 v27, 0xffff0000, v108
	v_pk_add_f32 v[6:7], v[6:7], v[26:27]
	v_lshlrev_b32_e32 v28, 16, v109
	v_and_b32_e32 v29, 0xffff0000, v109
	v_pk_add_f32 v[8:9], v[8:9], v[28:29]
	v_lshlrev_b32_e32 v34, 16, v110
	v_and_b32_e32 v35, 0xffff0000, v110
	v_pk_add_f32 v[10:11], v[10:11], v[34:35]
	v_lshlrev_b32_e32 v42, 16, v111
	v_and_b32_e32 v43, 0xffff0000, v111
	v_pk_add_f32 v[16:17], v[16:17], v[42:43]
	v_add_u32_e32 v18, 8, v38
	v_cmp_le_u32_e32 vcc, v39, v18
	s_and_saveexec_b64 s[10:11], vcc
	v_lshlrev_b32_e32 v22, 16, v140
	v_and_b32_e32 v23, 0xffff0000, v140
	v_pk_add_f32 v[6:7], v[6:7], v[22:23] neg_lo:[0,1] neg_hi:[0,1]
	v_lshlrev_b32_e32 v22, 16, v141
	v_and_b32_e32 v23, 0xffff0000, v141
	v_pk_add_f32 v[8:9], v[8:9], v[22:23] neg_lo:[0,1] neg_hi:[0,1]
	v_lshlrev_b32_e32 v22, 16, v142
	v_and_b32_e32 v23, 0xffff0000, v142
	v_pk_add_f32 v[10:11], v[10:11], v[22:23] neg_lo:[0,1] neg_hi:[0,1]
	v_lshlrev_b32_e32 v22, 16, v143
	v_and_b32_e32 v23, 0xffff0000, v143
	v_pk_add_f32 v[16:17], v[16:17], v[22:23] neg_lo:[0,1] neg_hi:[0,1]
	s_or_b64 exec, exec, s[10:11]
	v_pk_fma_f32 v[26:27], v[36:37], v[6:7], v[26:27] op_sel_hi:[0,1,1] neg_lo:[0,0,1] neg_hi:[0,0,1]
	v_pk_fma_f32 v[28:29], v[36:37], v[8:9], v[28:29] op_sel_hi:[0,1,1] neg_lo:[0,0,1] neg_hi:[0,0,1]
	v_pk_fma_f32 v[34:35], v[36:37], v[10:11], v[34:35] op_sel_hi:[0,1,1] neg_lo:[0,0,1] neg_hi:[0,0,1]
	v_pk_fma_f32 v[42:43], v[36:37], v[16:17], v[42:43] op_sel_hi:[0,1,1] neg_lo:[0,0,1] neg_hi:[0,0,1]
	v_cvt_pk_bf16_f32 v108, v26, v27
	v_cvt_pk_bf16_f32 v109, v28, v29
	v_cvt_pk_bf16_f32 v110, v34, v35
	v_cvt_pk_bf16_f32 v111, v42, v43
	v_add_u32_e32 v41, 0x1000, v41
	global_store_dwordx4 v41, v[108:111], s[16:17]
	v_add_u32_e32 v24, 10, v38
	v_min_u32_e32 v24, v24, v39
	v_cvt_f32_ubyte0_e32 v24, v24
	v_div_scale_f32 v25, s[0:1], v24, v24, 1.0
	v_rcp_f32_e32 v30, v25
	v_div_scale_f32 v31, vcc, 1.0, v24, 1.0
	v_fma_f32 v32, -v25, v30, 1.0
	v_fmac_f32_e32 v30, v32, v30
	v_mul_f32_e32 v32, v31, v30
	v_fma_f32 v33, -v25, v32, v31
	v_fmac_f32_e32 v32, v33, v30
	v_fma_f32 v25, -v25, v32, v31
	v_div_fmas_f32 v25, v25, v30, v32
	v_div_fixup_f32 v36, v25, v24, 1.0
	v_lshlrev_b32_e32 v26, 16, v112
	v_and_b32_e32 v27, 0xffff0000, v112
	v_pk_add_f32 v[6:7], v[6:7], v[26:27]
	v_lshlrev_b32_e32 v28, 16, v113
	v_and_b32_e32 v29, 0xffff0000, v113
	v_pk_add_f32 v[8:9], v[8:9], v[28:29]
	v_lshlrev_b32_e32 v34, 16, v114
	v_and_b32_e32 v35, 0xffff0000, v114
	v_pk_add_f32 v[10:11], v[10:11], v[34:35]
	v_lshlrev_b32_e32 v42, 16, v115
	v_and_b32_e32 v43, 0xffff0000, v115
	v_pk_add_f32 v[16:17], v[16:17], v[42:43]
	v_add_u32_e32 v18, 9, v38
	v_cmp_le_u32_e32 vcc, v39, v18
	s_and_saveexec_b64 s[10:11], vcc
	v_lshlrev_b32_e32 v22, 16, v144
	v_and_b32_e32 v23, 0xffff0000, v144
	v_pk_add_f32 v[6:7], v[6:7], v[22:23] neg_lo:[0,1] neg_hi:[0,1]
	v_lshlrev_b32_e32 v22, 16, v145
	v_and_b32_e32 v23, 0xffff0000, v145
	v_pk_add_f32 v[8:9], v[8:9], v[22:23] neg_lo:[0,1] neg_hi:[0,1]
; __device__ __forceinline__ unsigned cvt_pk_bf16(float lo, float hi) { f32x2_t f = {lo, hi}; bf16x2_t v = __builtin_convertvector(f, bf16x2_t); return __builtin_bit_cast(unsigned, v); }
; __device__ __forceinline__ float bflo(unsigned w) { return __uint_as_float(w << 16); }
; __device__ __forceinline__ float bfhi(unsigned w) { return __uint_as_float(w & 0xffff0000u); }
; __device__ __forceinline__ void acc8(float (&s)[8], const u32x4 a, float sg) {
;     s[0] += sg * bflo(a.x); s[1] += sg * bfhi(a.x); s[2] += sg * bflo(a.y); s[3] += sg * bfhi(a.y); s[4] += sg * bflo(a.z); s[5] += sg * bfhi(a.z); s[6] += sg * bflo(a.w); s[7] += sg * bfhi(a.w);
; }
; __device__ NOINL void pool_diff(unsigned char* ws, int wv) {
;     ...
;         for (int j = 0; j < 32; ++j) { const int t = t0 + j;
;             const u32x4 cur = *(const u32x4*)(ap + (size_t)t * NPROJ);
;             acc8(s, cur, 1.0f);
;             if (t - w >= 0) acc8(s, *(const u32x4*)(ap + (size_t)(t - w) * NPROJ), -1.0f);
;             const int cnt = (t + 1) < w ? (t + 1) : w; const float inv = 1.0f / (float)cnt;
;             u32x4 o;
;             o.x = cvt_pk_bf16(s[0] * inv - bflo(cur.x), s[1] * inv - bfhi(cur.x)); o.y = cvt_pk_bf16(s[2] * inv - bflo(cur.y), s[3] * inv - bfhi(cur.y));
;             o.z = cvt_pk_bf16(s[4] * inv - bflo(cur.z), s[5] * inv - bfhi(cur.z)); o.w = cvt_pk_bf16(s[6] * inv - bflo(cur.w), s[7] * inv - bfhi(cur.w));
;             *(u32x4*)(Y0 + ((size_t)b * SEQ + t) * 1024 + c8 * 8) = o; }
	v_lshlrev_b32_e32 v22, 16, v146
	v_and_b32_e32 v23, 0xffff0000, v146
	v_pk_add_f32 v[10:11], v[10:11], v[22:23] neg_lo:[0,1] neg_hi:[0,1]
	v_lshlrev_b32_e32 v22, 16, v147
	v_and_b32_e32 v23, 0xffff0000, v147
	v_pk_add_f32 v[16:17], v[16:17], v[22:23] neg_lo:[0,1] neg_hi:[0,1]
	s_or_b64 exec, exec, s[10:11]
	v_pk_fma_f32 v[26:27], v[36:37], v[6:7], v[26:27] op_sel_hi:[0,1,1] neg_lo:[0,0,1] neg_hi:[0,0,1]
	v_pk_fma_f32 v[28:29], v[36:37], v[8:9], v[28:29] op_sel_hi:[0,1,1] neg_lo:[0,0,1] neg_hi:[0,0,1]
	v_pk_fma_f32 v[34:35], v[36:37], v[10:11], v[34:35] op_sel_hi:[0,1,1] neg_lo:[0,0,1] neg_hi:[0,0,1]
	v_pk_fma_f32 v[42:43], v[36:37], v[16:17], v[42:43] op_sel_hi:[0,1,1] neg_lo:[0,0,1] neg_hi:[0,0,1]
	v_cvt_pk_bf16_f32 v112, v26, v27
	v_cvt_pk_bf16_f32 v113, v28, v29
	v_cvt_pk_bf16_f32 v114, v34, v35
	v_cvt_pk_bf16_f32 v115, v42, v43
	global_store_dwordx4 v41, v[112:115], s[16:17] offset:2048
	v_add_u32_e32 v24, 11, v38
	v_min_u32_e32 v24, v24, v39
	v_cvt_f32_ubyte0_e32 v24, v24
	v_div_scale_f32 v25, s[0:1], v24, v24, 1.0
	v_rcp_f32_e32 v30, v25
	v_div_scale_f32 v31, vcc, 1.0, v24, 1.0
	v_fma_f32 v32, -v25, v30, 1.0
	v_fmac_f32_e32 v30, v32, v30
	v_mul_f32_e32 v32, v31, v30
	v_fma_f32 v33, -v25, v32, v31
	v_fmac_f32_e32 v32, v33, v30
	v_fma_f32 v25, -v25, v32, v31
	v_div_fmas_f32 v25, v25, v30, v32
	v_div_fixup_f32 v36, v25, v24, 1.0
	v_lshlrev_b32_e32 v26, 16, v116
	v_and_b32_e32 v27, 0xffff0000, v116
	v_pk_add_f32 v[6:7], v[6:7], v[26:27]
	v_lshlrev_b32_e32 v28, 16, v117
	v_and_b32_e32 v29, 0xffff0000, v117
	v_pk_add_f32 v[8:9], v[8:9], v[28:29]
	v_lshlrev_b32_e32 v34, 16, v118
	v_and_b32_e32 v35, 0xffff0000, v118
	v_pk_add_f32 v[10:11], v[10:11], v[34:35]
	v_lshlrev_b32_e32 v42, 16, v119
	v_and_b32_e32 v43, 0xffff0000, v119
	v_pk_add_f32 v[16:17], v[16:17], v[42:43]
	v_add_u32_e32 v18, 10, v38
	v_cmp_le_u32_e32 vcc, v39, v18
	s_and_saveexec_b64 s[10:11], vcc
	v_lshlrev_b32_e32 v22, 16, v148
	v_and_b32_e32 v23, 0xffff0000, v148
	v_pk_add_f32 v[6:7], v[6:7], v[22:23] neg_lo:[0,1] neg_hi:[0,1]
	v_lshlrev_b32_e32 v22, 16, v149
	v_and_b32_e32 v23, 0xffff0000, v149
	v_pk_add_f32 v[8:9], v[8:9], v[22:23] neg_lo:[0,1] neg_hi:[0,1]
	v_lshlrev_b32_e32 v22, 16, v150
	v_and_b32_e32 v23, 0xffff0000, v150
	v_pk_add_f32 v[10:11], v[10:11], v[22:23] neg_lo:[0,1] neg_hi:[0,1]
	v_lshlrev_b32_e32 v22, 16, v151
	v_and_b32_e32 v23, 0xffff0000, v151
	v_pk_add_f32 v[16:17], v[16:17], v[22:23] neg_lo:[0,1] neg_hi:[0,1]
	s_or_b64 exec, exec, s[10:11]
	v_pk_fma_f32 v[26:27], v[36:37], v[6:7], v[26:27] op_sel_hi:[0,1,1] neg_lo:[0,0,1] neg_hi:[0,0,1]
	v_pk_fma_f32 v[28:29], v[36:37], v[8:9], v[28:29] op_sel_hi:[0,1,1] neg_lo:[0,0,1] neg_hi:[0,0,1]
	v_pk_fma_f32 v[34:35], v[36:37], v[10:11], v[34:35] op_sel_hi:[0,1,1] neg_lo:[0,0,1] neg_hi:[0,0,1]
	v_pk_fma_f32 v[42:43], v[36:37], v[16:17], v[42:43] op_sel_hi:[0,1,1] neg_lo:[0,0,1] neg_hi:[0,0,1]
	v_cvt_pk_bf16_f32 v116, v26, v27
	v_cvt_pk_bf16_f32 v117, v28, v29
	v_cvt_pk_bf16_f32 v118, v34, v35
	v_cvt_pk_bf16_f32 v119, v42, v43
	v_add_u32_e32 v41, 0x1000, v41
	global_store_dwordx4 v41, v[116:119], s[16:17]
	v_add_u32_e32 v24, 12, v38
	v_min_u32_e32 v24, v24, v39
	v_cvt_f32_ubyte0_e32 v24, v24
	v_div_scale_f32 v25, s[0:1], v24, v24, 1.0
	v_rcp_f32_e32 v30, v25
	v_div_scale_f32 v31, vcc, 1.0, v24, 1.0
	v_fma_f32 v32, -v25, v30, 1.0
	v_fmac_f32_e32 v30, v32, v30
	v_mul_f32_e32 v32, v31, v30
	v_fma_f32 v33, -v25, v32, v31
	v_fmac_f32_e32 v32, v33, v30
	v_fma_f32 v25, -v25, v32, v31
	v_div_fmas_f32 v25, v25, v30, v32
	v_div_fixup_f32 v36, v25, v24, 1.0
	v_lshlrev_b32_e32 v26, 16, v120
	v_and_b32_e32 v27, 0xffff0000, v120
	v_pk_add_f32 v[6:7], v[6:7], v[26:27]
	v_lshlrev_b32_e32 v28, 16, v121
	v_and_b32_e32 v29, 0xffff0000, v121
	v_pk_add_f32 v[8:9], v[8:9], v[28:29]
	v_lshlrev_b32_e32 v34, 16, v122
	v_and_b32_e32 v35, 0xffff0000, v122
	v_pk_add_f32 v[10:11], v[10:11], v[34:35]
	v_lshlrev_b32_e32 v42, 16, v123
	v_and_b32_e32 v43, 0xffff0000, v123
	v_pk_add_f32 v[16:17], v[16:17], v[42:43]
	v_add_u32_e32 v18, 11, v38
	v_cmp_le_u32_e32 vcc, v39, v18
	s_and_saveexec_b64 s[10:11], vcc
	v_lshlrev_b32_e32 v22, 16, v152
	v_and_b32_e32 v23, 0xffff0000, v152
	v_pk_add_f32 v[6:7], v[6:7], v[22:23] neg_lo:[0,1] neg_hi:[0,1]
	v_lshlrev_b32_e32 v22, 16, v153
	v_and_b32_e32 v23, 0xffff0000, v153
	v_pk_add_f32 v[8:9], v[8:9], v[22:23] neg_lo:[0,1] neg_hi:[0,1]
	v_lshlrev_b32_e32 v22, 16, v154
	v_and_b32_e32 v23, 0xffff0000, v154
	v_pk_add_f32 v[10:11], v[10:11], v[22:23] neg_lo:[0,1] neg_hi:[0,1]
	v_lshlrev_b32_e32 v22, 16, v155
	v_and_b32_e32 v23, 0xffff0000, v155
	v_pk_add_f32 v[16:17], v[16:17], v[22:23] neg_lo:[0,1] neg_hi:[0,1]
	s_or_b64 exec, exec, s[10:11]
	v_pk_fma_f32 v[26:27], v[36:37], v[6:7], v[26:27] op_sel_hi:[0,1,1] neg_lo:[0,0,1] neg_hi:[0,0,1]
	v_pk_fma_f32 v[28:29], v[36:37], v[8:9], v[28:29] op_sel_hi:[0,1,1] neg_lo:[0,0,1] neg_hi:[0,0,1]
	v_pk_fma_f32 v[34:35], v[36:37], v[10:11], v[34:35] op_sel_hi:[0,1,1] neg_lo:[0,0,1] neg_hi:[0,0,1]
	v_pk_fma_f32 v[42:43], v[36:37], v[16:17], v[42:43] op_sel_hi:[0,1,1] neg_lo:[0,0,1] neg_hi:[0,0,1]
	v_cvt_pk_bf16_f32 v120, v26, v27
	v_cvt_pk_bf16_f32 v121, v28, v29
	v_cvt_pk_bf16_f32 v122, v34, v35
	v_cvt_pk_bf16_f32 v123, v42, v43
	global_store_dwordx4 v41, v[120:123], s[16:17] offset:2048
	v_add_u32_e32 v24, 13, v38
	v_min_u32_e32 v24, v24, v39
	v_cvt_f32_ubyte0_e32 v24, v24
	v_div_scale_f32 v25, s[0:1], v24, v24, 1.0
	v_rcp_f32_e32 v30, v25
	v_div_scale_f32 v31, vcc, 1.0, v24, 1.0
	v_fma_f32 v32, -v25, v30, 1.0
	v_fmac_f32_e32 v30, v32, v30
	v_mul_f32_e32 v32, v31, v30
	v_fma_f32 v33, -v25, v32, v31
	v_fmac_f32_e32 v32, v33, v30
	v_fma_f32 v25, -v25, v32, v31
; __device__ __forceinline__ unsigned cvt_pk_bf16(float lo, float hi) { f32x2_t f = {lo, hi}; bf16x2_t v = __builtin_convertvector(f, bf16x2_t); return __builtin_bit_cast(unsigned, v); }
; __device__ __forceinline__ float bflo(unsigned w) { return __uint_as_float(w << 16); }
; __device__ __forceinline__ float bfhi(unsigned w) { return __uint_as_float(w & 0xffff0000u); }
; __device__ __forceinline__ void acc8(float (&s)[8], const u32x4 a, float sg) {
;     s[0] += sg * bflo(a.x); s[1] += sg * bfhi(a.x); s[2] += sg * bflo(a.y); s[3] += sg * bfhi(a.y); s[4] += sg * bflo(a.z); s[5] += sg * bfhi(a.z); s[6] += sg * bflo(a.w); s[7] += sg * bfhi(a.w);
; }
; __device__ NOINL void pool_diff(unsigned char* ws, int wv) {
;     ...
;         for (int j = 0; j < 32; ++j) { const int t = t0 + j;
;             const u32x4 cur = *(const u32x4*)(ap + (size_t)t * NPROJ);
;             acc8(s, cur, 1.0f);
;             if (t - w >= 0) acc8(s, *(const u32x4*)(ap + (size_t)(t - w) * NPROJ), -1.0f);
;             const int cnt = (t + 1) < w ? (t + 1) : w; const float inv = 1.0f / (float)cnt;
;             u32x4 o;
;             o.x = cvt_pk_bf16(s[0] * inv - bflo(cur.x), s[1] * inv - bfhi(cur.x)); o.y = cvt_pk_bf16(s[2] * inv - bflo(cur.y), s[3] * inv - bfhi(cur.y));
;             o.z = cvt_pk_bf16(s[4] * inv - bflo(cur.z), s[5] * inv - bfhi(cur.z)); o.w = cvt_pk_bf16(s[6] * inv - bflo(cur.w), s[7] * inv - bfhi(cur.w));
;             *(u32x4*)(Y0 + ((size_t)b * SEQ + t) * 1024 + c8 * 8) = o; }
	v_div_fmas_f32 v25, v25, v30, v32
	v_div_fixup_f32 v36, v25, v24, 1.0
	v_lshlrev_b32_e32 v26, 16, v124
	v_and_b32_e32 v27, 0xffff0000, v124
	v_pk_add_f32 v[6:7], v[6:7], v[26:27]
	v_lshlrev_b32_e32 v28, 16, v125
	v_and_b32_e32 v29, 0xffff0000, v125
	v_pk_add_f32 v[8:9], v[8:9], v[28:29]
	v_lshlrev_b32_e32 v34, 16, v126
	v_and_b32_e32 v35, 0xffff0000, v126
	v_pk_add_f32 v[10:11], v[10:11], v[34:35]
	v_lshlrev_b32_e32 v42, 16, v127
	v_and_b32_e32 v43, 0xffff0000, v127
	v_pk_add_f32 v[16:17], v[16:17], v[42:43]
	v_add_u32_e32 v18, 12, v38
	v_cmp_le_u32_e32 vcc, v39, v18
	s_and_saveexec_b64 s[10:11], vcc
	v_lshlrev_b32_e32 v22, 16, v156
	v_and_b32_e32 v23, 0xffff0000, v156
	v_pk_add_f32 v[6:7], v[6:7], v[22:23] neg_lo:[0,1] neg_hi:[0,1]
	v_lshlrev_b32_e32 v22, 16, v157
	v_and_b32_e32 v23, 0xffff0000, v157
	v_pk_add_f32 v[8:9], v[8:9], v[22:23] neg_lo:[0,1] neg_hi:[0,1]
	v_lshlrev_b32_e32 v22, 16, v158
	v_and_b32_e32 v23, 0xffff0000, v158
	v_pk_add_f32 v[10:11], v[10:11], v[22:23] neg_lo:[0,1] neg_hi:[0,1]
	v_lshlrev_b32_e32 v22, 16, v159
	v_and_b32_e32 v23, 0xffff0000, v159
	v_pk_add_f32 v[16:17], v[16:17], v[22:23] neg_lo:[0,1] neg_hi:[0,1]
	s_or_b64 exec, exec, s[10:11]
	v_pk_fma_f32 v[26:27], v[36:37], v[6:7], v[26:27] op_sel_hi:[0,1,1] neg_lo:[0,0,1] neg_hi:[0,0,1]
	v_pk_fma_f32 v[28:29], v[36:37], v[8:9], v[28:29] op_sel_hi:[0,1,1] neg_lo:[0,0,1] neg_hi:[0,0,1]
	v_pk_fma_f32 v[34:35], v[36:37], v[10:11], v[34:35] op_sel_hi:[0,1,1] neg_lo:[0,0,1] neg_hi:[0,0,1]
	v_pk_fma_f32 v[42:43], v[36:37], v[16:17], v[42:43] op_sel_hi:[0,1,1] neg_lo:[0,0,1] neg_hi:[0,0,1]
	v_cvt_pk_bf16_f32 v124, v26, v27
	v_cvt_pk_bf16_f32 v125, v28, v29
	v_cvt_pk_bf16_f32 v126, v34, v35
	v_cvt_pk_bf16_f32 v127, v42, v43
	v_add_u32_e32 v41, 0x1000, v41
	global_store_dwordx4 v41, v[124:127], s[16:17]
	v_add_u32_e32 v24, 14, v38
	v_min_u32_e32 v24, v24, v39
	v_cvt_f32_ubyte0_e32 v24, v24
	v_div_scale_f32 v25, s[0:1], v24, v24, 1.0
	v_rcp_f32_e32 v30, v25
	v_div_scale_f32 v31, vcc, 1.0, v24, 1.0
	v_fma_f32 v32, -v25, v30, 1.0
	v_fmac_f32_e32 v30, v32, v30
	v_mul_f32_e32 v32, v31, v30
	v_fma_f32 v33, -v25, v32, v31
	v_fmac_f32_e32 v32, v33, v30
	v_fma_f32 v25, -v25, v32, v31
	v_div_fmas_f32 v25, v25, v30, v32
	v_div_fixup_f32 v36, v25, v24, 1.0
	v_lshlrev_b32_e32 v26, 16, v128
	v_and_b32_e32 v27, 0xffff0000, v128
	v_pk_add_f32 v[6:7], v[6:7], v[26:27]
	v_lshlrev_b32_e32 v28, 16, v129
	v_and_b32_e32 v29, 0xffff0000, v129
	v_pk_add_f32 v[8:9], v[8:9], v[28:29]
	v_lshlrev_b32_e32 v34, 16, v130
	v_and_b32_e32 v35, 0xffff0000, v130
	v_pk_add_f32 v[10:11], v[10:11], v[34:35]
	v_lshlrev_b32_e32 v42, 16, v131
	v_and_b32_e32 v43, 0xffff0000, v131
	v_pk_add_f32 v[16:17], v[16:17], v[42:43]
	v_add_u32_e32 v18, 13, v38
	v_cmp_le_u32_e32 vcc, v39, v18
	s_and_saveexec_b64 s[10:11], vcc
	v_lshlrev_b32_e32 v22, 16, v160
	v_and_b32_e32 v23, 0xffff0000, v160
	v_pk_add_f32 v[6:7], v[6:7], v[22:23] neg_lo:[0,1] neg_hi:[0,1]
	v_lshlrev_b32_e32 v22, 16, v161
	v_and_b32_e32 v23, 0xffff0000, v161
	v_pk_add_f32 v[8:9], v[8:9], v[22:23] neg_lo:[0,1] neg_hi:[0,1]
	v_lshlrev_b32_e32 v22, 16, v162
	v_and_b32_e32 v23, 0xffff0000, v162
	v_pk_add_f32 v[10:11], v[10:11], v[22:23] neg_lo:[0,1] neg_hi:[0,1]
	v_lshlrev_b32_e32 v22, 16, v163
	v_and_b32_e32 v23, 0xffff0000, v163
	v_pk_add_f32 v[16:17], v[16:17], v[22:23] neg_lo:[0,1] neg_hi:[0,1]
	s_or_b64 exec, exec, s[10:11]
	v_pk_fma_f32 v[26:27], v[36:37], v[6:7], v[26:27] op_sel_hi:[0,1,1] neg_lo:[0,0,1] neg_hi:[0,0,1]
	v_pk_fma_f32 v[28:29], v[36:37], v[8:9], v[28:29] op_sel_hi:[0,1,1] neg_lo:[0,0,1] neg_hi:[0,0,1]
	v_pk_fma_f32 v[34:35], v[36:37], v[10:11], v[34:35] op_sel_hi:[0,1,1] neg_lo:[0,0,1] neg_hi:[0,0,1]
	v_pk_fma_f32 v[42:43], v[36:37], v[16:17], v[42:43] op_sel_hi:[0,1,1] neg_lo:[0,0,1] neg_hi:[0,0,1]
	v_cvt_pk_bf16_f32 v128, v26, v27
	v_cvt_pk_bf16_f32 v129, v28, v29
	v_cvt_pk_bf16_f32 v130, v34, v35
	v_cvt_pk_bf16_f32 v131, v42, v43
	global_store_dwordx4 v41, v[128:131], s[16:17] offset:2048
	v_add_u32_e32 v24, 15, v38
	v_min_u32_e32 v24, v24, v39
	v_cvt_f32_ubyte0_e32 v24, v24
	v_div_scale_f32 v25, s[0:1], v24, v24, 1.0
	v_rcp_f32_e32 v30, v25
	v_div_scale_f32 v31, vcc, 1.0, v24, 1.0
	v_fma_f32 v32, -v25, v30, 1.0
	v_fmac_f32_e32 v30, v32, v30
	v_mul_f32_e32 v32, v31, v30
	v_fma_f32 v33, -v25, v32, v31
	v_fmac_f32_e32 v32, v33, v30
	v_fma_f32 v25, -v25, v32, v31
	v_div_fmas_f32 v25, v25, v30, v32
	v_div_fixup_f32 v36, v25, v24, 1.0
	v_lshlrev_b32_e32 v26, 16, v132
	v_and_b32_e32 v27, 0xffff0000, v132
	v_pk_add_f32 v[6:7], v[6:7], v[26:27]
	v_lshlrev_b32_e32 v28, 16, v133
	v_and_b32_e32 v29, 0xffff0000, v133
	v_pk_add_f32 v[8:9], v[8:9], v[28:29]
	v_lshlrev_b32_e32 v34, 16, v134
	v_and_b32_e32 v35, 0xffff0000, v134
	v_pk_add_f32 v[10:11], v[10:11], v[34:35]
	v_lshlrev_b32_e32 v42, 16, v135
	v_and_b32_e32 v43, 0xffff0000, v135
	v_pk_add_f32 v[16:17], v[16:17], v[42:43]
	v_add_u32_e32 v18, 14, v38
	v_cmp_le_u32_e32 vcc, v39, v18
	s_and_saveexec_b64 s[10:11], vcc
	v_lshlrev_b32_e32 v22, 16, v164
	v_and_b32_e32 v23, 0xffff0000, v164
	v_pk_add_f32 v[6:7], v[6:7], v[22:23] neg_lo:[0,1] neg_hi:[0,1]
	v_lshlrev_b32_e32 v22, 16, v165
	v_and_b32_e32 v23, 0xffff0000, v165
	v_pk_add_f32 v[8:9], v[8:9], v[22:23] neg_lo:[0,1] neg_hi:[0,1]
	v_lshlrev_b32_e32 v22, 16, v166
	v_and_b32_e32 v23, 0xffff0000, v166
	v_pk_add_f32 v[10:11], v[10:11], v[22:23] neg_lo:[0,1] neg_hi:[0,1]
	v_lshlrev_b32_e32 v22, 16, v167
	v_and_b32_e32 v23, 0xffff0000, v167
	v_pk_add_f32 v[16:17], v[16:17], v[22:23] neg_lo:[0,1] neg_hi:[0,1]
	s_or_b64 exec, exec, s[10:11]
	v_pk_fma_f32 v[26:27], v[36:37], v[6:7], v[26:27] op_sel_hi:[0,1,1] neg_lo:[0,0,1] neg_hi:[0,0,1]
; __device__ __forceinline__ unsigned cvt_pk_bf16(float lo, float hi) { f32x2_t f = {lo, hi}; bf16x2_t v = __builtin_convertvector(f, bf16x2_t); return __builtin_bit_cast(unsigned, v); }
; __device__ __forceinline__ float bflo(unsigned w) { return __uint_as_float(w << 16); }
; __device__ __forceinline__ float bfhi(unsigned w) { return __uint_as_float(w & 0xffff0000u); }
; __device__ __forceinline__ void acc8(float (&s)[8], const u32x4 a, float sg) {
;     s[0] += sg * bflo(a.x); s[1] += sg * bfhi(a.x); s[2] += sg * bflo(a.y); s[3] += sg * bfhi(a.y); s[4] += sg * bflo(a.z); s[5] += sg * bfhi(a.z); s[6] += sg * bflo(a.w); s[7] += sg * bfhi(a.w);
; }
; __device__ NOINL void pool_diff(unsigned char* ws, int wv) {
;     ...
;         for (int j = 0; j < 32; ++j) { const int t = t0 + j;
;             const u32x4 cur = *(const u32x4*)(ap + (size_t)t * NPROJ);
;             acc8(s, cur, 1.0f);
;             if (t - w >= 0) acc8(s, *(const u32x4*)(ap + (size_t)(t - w) * NPROJ), -1.0f);
;             const int cnt = (t + 1) < w ? (t + 1) : w; const float inv = 1.0f / (float)cnt;
;             u32x4 o;
;             o.x = cvt_pk_bf16(s[0] * inv - bflo(cur.x), s[1] * inv - bfhi(cur.x)); o.y = cvt_pk_bf16(s[2] * inv - bflo(cur.y), s[3] * inv - bfhi(cur.y));
;             o.z = cvt_pk_bf16(s[4] * inv - bflo(cur.z), s[5] * inv - bfhi(cur.z)); o.w = cvt_pk_bf16(s[6] * inv - bflo(cur.w), s[7] * inv - bfhi(cur.w));
;             *(u32x4*)(Y0 + ((size_t)b * SEQ + t) * 1024 + c8 * 8) = o; }
	v_pk_fma_f32 v[28:29], v[36:37], v[8:9], v[28:29] op_sel_hi:[0,1,1] neg_lo:[0,0,1] neg_hi:[0,0,1]
	v_pk_fma_f32 v[34:35], v[36:37], v[10:11], v[34:35] op_sel_hi:[0,1,1] neg_lo:[0,0,1] neg_hi:[0,0,1]
	v_pk_fma_f32 v[42:43], v[36:37], v[16:17], v[42:43] op_sel_hi:[0,1,1] neg_lo:[0,0,1] neg_hi:[0,0,1]
	v_cvt_pk_bf16_f32 v132, v26, v27
	v_cvt_pk_bf16_f32 v133, v28, v29
	v_cvt_pk_bf16_f32 v134, v34, v35
	v_cvt_pk_bf16_f32 v135, v42, v43
	v_add_u32_e32 v41, 0x1000, v41
	global_store_dwordx4 v41, v[132:135], s[16:17]
	v_add_u32_e32 v24, 16, v38
	v_min_u32_e32 v24, v24, v39
	v_cvt_f32_ubyte0_e32 v24, v24
	v_div_scale_f32 v25, s[0:1], v24, v24, 1.0
	v_rcp_f32_e32 v30, v25
	v_div_scale_f32 v31, vcc, 1.0, v24, 1.0
	v_fma_f32 v32, -v25, v30, 1.0
	v_fmac_f32_e32 v30, v32, v30
	v_mul_f32_e32 v32, v31, v30
	v_fma_f32 v33, -v25, v32, v31
	v_fmac_f32_e32 v32, v33, v30
	v_fma_f32 v25, -v25, v32, v31
	v_div_fmas_f32 v25, v25, v30, v32
	v_div_fixup_f32 v36, v25, v24, 1.0
	v_lshlrev_b32_e32 v26, 16, v136
	v_and_b32_e32 v27, 0xffff0000, v136
	v_pk_add_f32 v[6:7], v[6:7], v[26:27]
	v_lshlrev_b32_e32 v28, 16, v137
	v_and_b32_e32 v29, 0xffff0000, v137
	v_pk_add_f32 v[8:9], v[8:9], v[28:29]
	v_lshlrev_b32_e32 v34, 16, v138
	v_and_b32_e32 v35, 0xffff0000, v138
	v_pk_add_f32 v[10:11], v[10:11], v[34:35]
	v_lshlrev_b32_e32 v42, 16, v139
	v_and_b32_e32 v43, 0xffff0000, v139
	v_pk_add_f32 v[16:17], v[16:17], v[42:43]
	v_add_u32_e32 v18, 15, v38
	v_cmp_le_u32_e32 vcc, v39, v18
	s_and_saveexec_b64 s[10:11], vcc
	v_lshlrev_b32_e32 v22, 16, v168
	v_and_b32_e32 v23, 0xffff0000, v168
	v_pk_add_f32 v[6:7], v[6:7], v[22:23] neg_lo:[0,1] neg_hi:[0,1]
	v_lshlrev_b32_e32 v22, 16, v169
	v_and_b32_e32 v23, 0xffff0000, v169
	v_pk_add_f32 v[8:9], v[8:9], v[22:23] neg_lo:[0,1] neg_hi:[0,1]
	v_lshlrev_b32_e32 v22, 16, v170
	v_and_b32_e32 v23, 0xffff0000, v170
	v_pk_add_f32 v[10:11], v[10:11], v[22:23] neg_lo:[0,1] neg_hi:[0,1]
	v_lshlrev_b32_e32 v22, 16, v171
	v_and_b32_e32 v23, 0xffff0000, v171
	v_pk_add_f32 v[16:17], v[16:17], v[22:23] neg_lo:[0,1] neg_hi:[0,1]
	s_or_b64 exec, exec, s[10:11]
	v_pk_fma_f32 v[26:27], v[36:37], v[6:7], v[26:27] op_sel_hi:[0,1,1] neg_lo:[0,0,1] neg_hi:[0,0,1]
	v_pk_fma_f32 v[28:29], v[36:37], v[8:9], v[28:29] op_sel_hi:[0,1,1] neg_lo:[0,0,1] neg_hi:[0,0,1]
	v_pk_fma_f32 v[34:35], v[36:37], v[10:11], v[34:35] op_sel_hi:[0,1,1] neg_lo:[0,0,1] neg_hi:[0,0,1]
	v_pk_fma_f32 v[42:43], v[36:37], v[16:17], v[42:43] op_sel_hi:[0,1,1] neg_lo:[0,0,1] neg_hi:[0,0,1]
	v_cvt_pk_bf16_f32 v136, v26, v27
	v_cvt_pk_bf16_f32 v137, v28, v29
	v_cvt_pk_bf16_f32 v138, v34, v35
	v_cvt_pk_bf16_f32 v139, v42, v43
	global_store_dwordx4 v41, v[136:139], s[16:17] offset:2048
	s_nop 1
	v_add_u32_e32 v18, 24, v38
	v_lshl_add_u32 v3, v18, 14, v40
	global_load_dwordx4 v[108:111], v3, s[6:7]
	v_sub_u32_e32 v19, v18, v39
	v_max_i32_e32 v19, 0, v19
	v_lshl_add_u32 v3, v19, 14, v40
	global_load_dwordx4 v[140:143], v3, s[6:7]
	v_add_u32_e32 v18, 25, v38
	v_lshl_add_u32 v3, v18, 14, v40
	global_load_dwordx4 v[112:115], v3, s[6:7]
	v_sub_u32_e32 v19, v18, v39
	v_max_i32_e32 v19, 0, v19
	v_lshl_add_u32 v3, v19, 14, v40
	global_load_dwordx4 v[144:147], v3, s[6:7]
	v_add_u32_e32 v18, 26, v38
	v_lshl_add_u32 v3, v18, 14, v40
	global_load_dwordx4 v[116:119], v3, s[6:7]
	v_sub_u32_e32 v19, v18, v39
	v_max_i32_e32 v19, 0, v19
	v_lshl_add_u32 v3, v19, 14, v40
	global_load_dwordx4 v[148:151], v3, s[6:7]
	v_add_u32_e32 v18, 27, v38
	v_lshl_add_u32 v3, v18, 14, v40
	global_load_dwordx4 v[120:123], v3, s[6:7]
	v_sub_u32_e32 v19, v18, v39
	v_max_i32_e32 v19, 0, v19
	v_lshl_add_u32 v3, v19, 14, v40
	global_load_dwordx4 v[152:155], v3, s[6:7]
	v_add_u32_e32 v18, 28, v38
	v_lshl_add_u32 v3, v18, 14, v40
	global_load_dwordx4 v[124:127], v3, s[6:7]
	v_sub_u32_e32 v19, v18, v39
	v_max_i32_e32 v19, 0, v19
	v_lshl_add_u32 v3, v19, 14, v40
	global_load_dwordx4 v[156:159], v3, s[6:7]
	v_add_u32_e32 v18, 29, v38
	v_lshl_add_u32 v3, v18, 14, v40
	global_load_dwordx4 v[128:131], v3, s[6:7]
	v_sub_u32_e32 v19, v18, v39
	v_max_i32_e32 v19, 0, v19
	v_lshl_add_u32 v3, v19, 14, v40
	global_load_dwordx4 v[160:163], v3, s[6:7]
	v_add_u32_e32 v18, 30, v38
	v_lshl_add_u32 v3, v18, 14, v40
	global_load_dwordx4 v[132:135], v3, s[6:7]
	v_sub_u32_e32 v19, v18, v39
	v_max_i32_e32 v19, 0, v19
	v_lshl_add_u32 v3, v19, 14, v40
	global_load_dwordx4 v[164:167], v3, s[6:7]
	v_add_u32_e32 v18, 31, v38
	v_lshl_add_u32 v3, v18, 14, v40
	global_load_dwordx4 v[136:139], v3, s[6:7]
	v_sub_u32_e32 v19, v18, v39
	v_max_i32_e32 v19, 0, v19
	v_lshl_add_u32 v3, v19, 14, v40
	global_load_dwordx4 v[168:171], v3, s[6:7]
	s_waitcnt vmcnt(24)
; __device__ __forceinline__ unsigned cvt_pk_bf16(float lo, float hi) { f32x2_t f = {lo, hi}; bf16x2_t v = __builtin_convertvector(f, bf16x2_t); return __builtin_bit_cast(unsigned, v); }
; __device__ __forceinline__ float bflo(unsigned w) { return __uint_as_float(w << 16); }
; __device__ __forceinline__ float bfhi(unsigned w) { return __uint_as_float(w & 0xffff0000u); }
; __device__ __forceinline__ void acc8(float (&s)[8], const u32x4 a, float sg) {
;     s[0] += sg * bflo(a.x); s[1] += sg * bfhi(a.x); s[2] += sg * bflo(a.y); s[3] += sg * bfhi(a.y); s[4] += sg * bflo(a.z); s[5] += sg * bfhi(a.z); s[6] += sg * bflo(a.w); s[7] += sg * bfhi(a.w);
; }
; __device__ NOINL void pool_diff(unsigned char* ws, int wv) {
;     ...
;         for (int j = 0; j < 32; ++j) { const int t = t0 + j;
;             const u32x4 cur = *(const u32x4*)(ap + (size_t)t * NPROJ);
;             acc8(s, cur, 1.0f);
;             if (t - w >= 0) acc8(s, *(const u32x4*)(ap + (size_t)(t - w) * NPROJ), -1.0f);
;             const int cnt = (t + 1) < w ? (t + 1) : w; const float inv = 1.0f / (float)cnt;
;             u32x4 o;
;             o.x = cvt_pk_bf16(s[0] * inv - bflo(cur.x), s[1] * inv - bfhi(cur.x)); o.y = cvt_pk_bf16(s[2] * inv - bflo(cur.y), s[3] * inv - bfhi(cur.y));
;             o.z = cvt_pk_bf16(s[4] * inv - bflo(cur.z), s[5] * inv - bfhi(cur.z)); o.w = cvt_pk_bf16(s[6] * inv - bflo(cur.w), s[7] * inv - bfhi(cur.w));
;             *(u32x4*)(Y0 + ((size_t)b * SEQ + t) * 1024 + c8 * 8) = o; }
	v_add_u32_e32 v24, 17, v38
	v_min_u32_e32 v24, v24, v39
	v_cvt_f32_ubyte0_e32 v24, v24
	v_div_scale_f32 v25, s[0:1], v24, v24, 1.0
	v_rcp_f32_e32 v30, v25
	v_div_scale_f32 v31, vcc, 1.0, v24, 1.0
	v_fma_f32 v32, -v25, v30, 1.0
	v_fmac_f32_e32 v30, v32, v30
	v_mul_f32_e32 v32, v31, v30
	v_fma_f32 v33, -v25, v32, v31
	v_fmac_f32_e32 v32, v33, v30
	v_fma_f32 v25, -v25, v32, v31
	v_div_fmas_f32 v25, v25, v30, v32
	v_div_fixup_f32 v36, v25, v24, 1.0
	v_lshlrev_b32_e32 v26, 16, v44
	v_and_b32_e32 v27, 0xffff0000, v44
	v_pk_add_f32 v[6:7], v[6:7], v[26:27]
	v_lshlrev_b32_e32 v28, 16, v45
	v_and_b32_e32 v29, 0xffff0000, v45
	v_pk_add_f32 v[8:9], v[8:9], v[28:29]
	v_lshlrev_b32_e32 v34, 16, v46
	v_and_b32_e32 v35, 0xffff0000, v46
	v_pk_add_f32 v[10:11], v[10:11], v[34:35]
	v_lshlrev_b32_e32 v42, 16, v47
	v_and_b32_e32 v43, 0xffff0000, v47
	v_pk_add_f32 v[16:17], v[16:17], v[42:43]
	v_add_u32_e32 v18, 16, v38
	v_cmp_le_u32_e32 vcc, v39, v18
	s_and_saveexec_b64 s[10:11], vcc
	v_lshlrev_b32_e32 v22, 16, v76
	v_and_b32_e32 v23, 0xffff0000, v76
	v_pk_add_f32 v[6:7], v[6:7], v[22:23] neg_lo:[0,1] neg_hi:[0,1]
	v_lshlrev_b32_e32 v22, 16, v77
	v_and_b32_e32 v23, 0xffff0000, v77
	v_pk_add_f32 v[8:9], v[8:9], v[22:23] neg_lo:[0,1] neg_hi:[0,1]
	v_lshlrev_b32_e32 v22, 16, v78
	v_and_b32_e32 v23, 0xffff0000, v78
	v_pk_add_f32 v[10:11], v[10:11], v[22:23] neg_lo:[0,1] neg_hi:[0,1]
	v_lshlrev_b32_e32 v22, 16, v79
	v_and_b32_e32 v23, 0xffff0000, v79
	v_pk_add_f32 v[16:17], v[16:17], v[22:23] neg_lo:[0,1] neg_hi:[0,1]
	s_or_b64 exec, exec, s[10:11]
	v_pk_fma_f32 v[26:27], v[36:37], v[6:7], v[26:27] op_sel_hi:[0,1,1] neg_lo:[0,0,1] neg_hi:[0,0,1]
	v_pk_fma_f32 v[28:29], v[36:37], v[8:9], v[28:29] op_sel_hi:[0,1,1] neg_lo:[0,0,1] neg_hi:[0,0,1]
	v_pk_fma_f32 v[34:35], v[36:37], v[10:11], v[34:35] op_sel_hi:[0,1,1] neg_lo:[0,0,1] neg_hi:[0,0,1]
	v_pk_fma_f32 v[42:43], v[36:37], v[16:17], v[42:43] op_sel_hi:[0,1,1] neg_lo:[0,0,1] neg_hi:[0,0,1]
	v_cvt_pk_bf16_f32 v44, v26, v27
	v_cvt_pk_bf16_f32 v45, v28, v29
	v_cvt_pk_bf16_f32 v46, v34, v35
	v_cvt_pk_bf16_f32 v47, v42, v43
	v_add_u32_e32 v41, 0x1000, v41
	global_store_dwordx4 v41, v[44:47], s[16:17]
	v_add_u32_e32 v24, 18, v38
	v_min_u32_e32 v24, v24, v39
	v_cvt_f32_ubyte0_e32 v24, v24
	v_div_scale_f32 v25, s[0:1], v24, v24, 1.0
	v_rcp_f32_e32 v30, v25
	v_div_scale_f32 v31, vcc, 1.0, v24, 1.0
	v_fma_f32 v32, -v25, v30, 1.0
	v_fmac_f32_e32 v30, v32, v30
	v_mul_f32_e32 v32, v31, v30
	v_fma_f32 v33, -v25, v32, v31
	v_fmac_f32_e32 v32, v33, v30
	v_fma_f32 v25, -v25, v32, v31
	v_div_fmas_f32 v25, v25, v30, v32
	v_div_fixup_f32 v36, v25, v24, 1.0
	v_lshlrev_b32_e32 v26, 16, v48
	v_and_b32_e32 v27, 0xffff0000, v48
	v_pk_add_f32 v[6:7], v[6:7], v[26:27]
	v_lshlrev_b32_e32 v28, 16, v49
	v_and_b32_e32 v29, 0xffff0000, v49
	v_pk_add_f32 v[8:9], v[8:9], v[28:29]
	v_lshlrev_b32_e32 v34, 16, v50
	v_and_b32_e32 v35, 0xffff0000, v50
	v_pk_add_f32 v[10:11], v[10:11], v[34:35]
	v_lshlrev_b32_e32 v42, 16, v51
	v_and_b32_e32 v43, 0xffff0000, v51
	v_pk_add_f32 v[16:17], v[16:17], v[42:43]
	v_add_u32_e32 v18, 17, v38
	v_cmp_le_u32_e32 vcc, v39, v18
	s_and_saveexec_b64 s[10:11], vcc
	v_lshlrev_b32_e32 v22, 16, v80
	v_and_b32_e32 v23, 0xffff0000, v80
	v_pk_add_f32 v[6:7], v[6:7], v[22:23] neg_lo:[0,1] neg_hi:[0,1]
	v_lshlrev_b32_e32 v22, 16, v81
	v_and_b32_e32 v23, 0xffff0000, v81
	v_pk_add_f32 v[8:9], v[8:9], v[22:23] neg_lo:[0,1] neg_hi:[0,1]
	v_lshlrev_b32_e32 v22, 16, v82
	v_and_b32_e32 v23, 0xffff0000, v82
	v_pk_add_f32 v[10:11], v[10:11], v[22:23] neg_lo:[0,1] neg_hi:[0,1]
	v_lshlrev_b32_e32 v22, 16, v83
	v_and_b32_e32 v23, 0xffff0000, v83
	v_pk_add_f32 v[16:17], v[16:17], v[22:23] neg_lo:[0,1] neg_hi:[0,1]
	s_or_b64 exec, exec, s[10:11]
	v_pk_fma_f32 v[26:27], v[36:37], v[6:7], v[26:27] op_sel_hi:[0,1,1] neg_lo:[0,0,1] neg_hi:[0,0,1]
	v_pk_fma_f32 v[28:29], v[36:37], v[8:9], v[28:29] op_sel_hi:[0,1,1] neg_lo:[0,0,1] neg_hi:[0,0,1]
	v_pk_fma_f32 v[34:35], v[36:37], v[10:11], v[34:35] op_sel_hi:[0,1,1] neg_lo:[0,0,1] neg_hi:[0,0,1]
	v_pk_fma_f32 v[42:43], v[36:37], v[16:17], v[42:43] op_sel_hi:[0,1,1] neg_lo:[0,0,1] neg_hi:[0,0,1]
	v_cvt_pk_bf16_f32 v48, v26, v27
	v_cvt_pk_bf16_f32 v49, v28, v29
	v_cvt_pk_bf16_f32 v50, v34, v35
	v_cvt_pk_bf16_f32 v51, v42, v43
	global_store_dwordx4 v41, v[48:51], s[16:17] offset:2048
	v_add_u32_e32 v24, 19, v38
	v_min_u32_e32 v24, v24, v39
	v_cvt_f32_ubyte0_e32 v24, v24
	v_div_scale_f32 v25, s[0:1], v24, v24, 1.0
	v_rcp_f32_e32 v30, v25
	v_div_scale_f32 v31, vcc, 1.0, v24, 1.0
	v_fma_f32 v32, -v25, v30, 1.0
	v_fmac_f32_e32 v30, v32, v30
	v_mul_f32_e32 v32, v31, v30
	v_fma_f32 v33, -v25, v32, v31
	v_fmac_f32_e32 v32, v33, v30
	v_fma_f32 v25, -v25, v32, v31
	v_div_fmas_f32 v25, v25, v30, v32
	v_div_fixup_f32 v36, v25, v24, 1.0
	v_lshlrev_b32_e32 v26, 16, v52
	v_and_b32_e32 v27, 0xffff0000, v52
	v_pk_add_f32 v[6:7], v[6:7], v[26:27]
	v_lshlrev_b32_e32 v28, 16, v53
	v_and_b32_e32 v29, 0xffff0000, v53
	v_pk_add_f32 v[8:9], v[8:9], v[28:29]
	v_lshlrev_b32_e32 v34, 16, v54
	v_and_b32_e32 v35, 0xffff0000, v54
	v_pk_add_f32 v[10:11], v[10:11], v[34:35]
	v_lshlrev_b32_e32 v42, 16, v55
	v_and_b32_e32 v43, 0xffff0000, v55
	v_pk_add_f32 v[16:17], v[16:17], v[42:43]
	v_add_u32_e32 v18, 18, v38
	v_cmp_le_u32_e32 vcc, v39, v18
	s_and_saveexec_b64 s[10:11], vcc
	v_lshlrev_b32_e32 v22, 16, v84
	v_and_b32_e32 v23, 0xffff0000, v84
	v_pk_add_f32 v[6:7], v[6:7], v[22:23] neg_lo:[0,1] neg_hi:[0,1]
	v_lshlrev_b32_e32 v22, 16, v85
	v_and_b32_e32 v23, 0xffff0000, v85
	v_pk_add_f32 v[8:9], v[8:9], v[22:23] neg_lo:[0,1] neg_hi:[0,1]
	v_lshlrev_b32_e32 v22, 16, v86
	v_and_b32_e32 v23, 0xffff0000, v86
; __device__ __forceinline__ unsigned cvt_pk_bf16(float lo, float hi) { f32x2_t f = {lo, hi}; bf16x2_t v = __builtin_convertvector(f, bf16x2_t); return __builtin_bit_cast(unsigned, v); }
; __device__ __forceinline__ float bflo(unsigned w) { return __uint_as_float(w << 16); }
; __device__ __forceinline__ float bfhi(unsigned w) { return __uint_as_float(w & 0xffff0000u); }
; __device__ __forceinline__ void acc8(float (&s)[8], const u32x4 a, float sg) {
;     s[0] += sg * bflo(a.x); s[1] += sg * bfhi(a.x); s[2] += sg * bflo(a.y); s[3] += sg * bfhi(a.y); s[4] += sg * bflo(a.z); s[5] += sg * bfhi(a.z); s[6] += sg * bflo(a.w); s[7] += sg * bfhi(a.w);
; }
; __device__ NOINL void pool_diff(unsigned char* ws, int wv) {
;     ...
;         for (int j = 0; j < 32; ++j) { const int t = t0 + j;
;             const u32x4 cur = *(const u32x4*)(ap + (size_t)t * NPROJ);
;             acc8(s, cur, 1.0f);
;             if (t - w >= 0) acc8(s, *(const u32x4*)(ap + (size_t)(t - w) * NPROJ), -1.0f);
;             const int cnt = (t + 1) < w ? (t + 1) : w; const float inv = 1.0f / (float)cnt;
;             u32x4 o;
;             o.x = cvt_pk_bf16(s[0] * inv - bflo(cur.x), s[1] * inv - bfhi(cur.x)); o.y = cvt_pk_bf16(s[2] * inv - bflo(cur.y), s[3] * inv - bfhi(cur.y));
;             o.z = cvt_pk_bf16(s[4] * inv - bflo(cur.z), s[5] * inv - bfhi(cur.z)); o.w = cvt_pk_bf16(s[6] * inv - bflo(cur.w), s[7] * inv - bfhi(cur.w));
;             *(u32x4*)(Y0 + ((size_t)b * SEQ + t) * 1024 + c8 * 8) = o; }
	v_pk_add_f32 v[10:11], v[10:11], v[22:23] neg_lo:[0,1] neg_hi:[0,1]
	v_lshlrev_b32_e32 v22, 16, v87
	v_and_b32_e32 v23, 0xffff0000, v87
	v_pk_add_f32 v[16:17], v[16:17], v[22:23] neg_lo:[0,1] neg_hi:[0,1]
	s_or_b64 exec, exec, s[10:11]
	v_pk_fma_f32 v[26:27], v[36:37], v[6:7], v[26:27] op_sel_hi:[0,1,1] neg_lo:[0,0,1] neg_hi:[0,0,1]
	v_pk_fma_f32 v[28:29], v[36:37], v[8:9], v[28:29] op_sel_hi:[0,1,1] neg_lo:[0,0,1] neg_hi:[0,0,1]
	v_pk_fma_f32 v[34:35], v[36:37], v[10:11], v[34:35] op_sel_hi:[0,1,1] neg_lo:[0,0,1] neg_hi:[0,0,1]
	v_pk_fma_f32 v[42:43], v[36:37], v[16:17], v[42:43] op_sel_hi:[0,1,1] neg_lo:[0,0,1] neg_hi:[0,0,1]
	v_cvt_pk_bf16_f32 v52, v26, v27
	v_cvt_pk_bf16_f32 v53, v28, v29
	v_cvt_pk_bf16_f32 v54, v34, v35
	v_cvt_pk_bf16_f32 v55, v42, v43
	v_add_u32_e32 v41, 0x1000, v41
	global_store_dwordx4 v41, v[52:55], s[16:17]
	v_add_u32_e32 v24, 20, v38
	v_min_u32_e32 v24, v24, v39
	v_cvt_f32_ubyte0_e32 v24, v24
	v_div_scale_f32 v25, s[0:1], v24, v24, 1.0
	v_rcp_f32_e32 v30, v25
	v_div_scale_f32 v31, vcc, 1.0, v24, 1.0
	v_fma_f32 v32, -v25, v30, 1.0
	v_fmac_f32_e32 v30, v32, v30
	v_mul_f32_e32 v32, v31, v30
	v_fma_f32 v33, -v25, v32, v31
	v_fmac_f32_e32 v32, v33, v30
	v_fma_f32 v25, -v25, v32, v31
	v_div_fmas_f32 v25, v25, v30, v32
	v_div_fixup_f32 v36, v25, v24, 1.0
	v_lshlrev_b32_e32 v26, 16, v56
	v_and_b32_e32 v27, 0xffff0000, v56
	v_pk_add_f32 v[6:7], v[6:7], v[26:27]
	v_lshlrev_b32_e32 v28, 16, v57
	v_and_b32_e32 v29, 0xffff0000, v57
	v_pk_add_f32 v[8:9], v[8:9], v[28:29]
	v_lshlrev_b32_e32 v34, 16, v58
	v_and_b32_e32 v35, 0xffff0000, v58
	v_pk_add_f32 v[10:11], v[10:11], v[34:35]
	v_lshlrev_b32_e32 v42, 16, v59
	v_and_b32_e32 v43, 0xffff0000, v59
	v_pk_add_f32 v[16:17], v[16:17], v[42:43]
	v_add_u32_e32 v18, 19, v38
	v_cmp_le_u32_e32 vcc, v39, v18
	s_and_saveexec_b64 s[10:11], vcc
	v_lshlrev_b32_e32 v22, 16, v88
	v_and_b32_e32 v23, 0xffff0000, v88
	v_pk_add_f32 v[6:7], v[6:7], v[22:23] neg_lo:[0,1] neg_hi:[0,1]
	v_lshlrev_b32_e32 v22, 16, v89
	v_and_b32_e32 v23, 0xffff0000, v89
	v_pk_add_f32 v[8:9], v[8:9], v[22:23] neg_lo:[0,1] neg_hi:[0,1]
	v_lshlrev_b32_e32 v22, 16, v90
	v_and_b32_e32 v23, 0xffff0000, v90
	v_pk_add_f32 v[10:11], v[10:11], v[22:23] neg_lo:[0,1] neg_hi:[0,1]
	v_lshlrev_b32_e32 v22, 16, v91
	v_and_b32_e32 v23, 0xffff0000, v91
	v_pk_add_f32 v[16:17], v[16:17], v[22:23] neg_lo:[0,1] neg_hi:[0,1]
	s_or_b64 exec, exec, s[10:11]
	v_pk_fma_f32 v[26:27], v[36:37], v[6:7], v[26:27] op_sel_hi:[0,1,1] neg_lo:[0,0,1] neg_hi:[0,0,1]
	v_pk_fma_f32 v[28:29], v[36:37], v[8:9], v[28:29] op_sel_hi:[0,1,1] neg_lo:[0,0,1] neg_hi:[0,0,1]
	v_pk_fma_f32 v[34:35], v[36:37], v[10:11], v[34:35] op_sel_hi:[0,1,1] neg_lo:[0,0,1] neg_hi:[0,0,1]
	v_pk_fma_f32 v[42:43], v[36:37], v[16:17], v[42:43] op_sel_hi:[0,1,1] neg_lo:[0,0,1] neg_hi:[0,0,1]
	v_cvt_pk_bf16_f32 v56, v26, v27
	v_cvt_pk_bf16_f32 v57, v28, v29
	v_cvt_pk_bf16_f32 v58, v34, v35
	v_cvt_pk_bf16_f32 v59, v42, v43
	global_store_dwordx4 v41, v[56:59], s[16:17] offset:2048
	v_add_u32_e32 v24, 21, v38
	v_min_u32_e32 v24, v24, v39
	v_cvt_f32_ubyte0_e32 v24, v24
	v_div_scale_f32 v25, s[0:1], v24, v24, 1.0
	v_rcp_f32_e32 v30, v25
	v_div_scale_f32 v31, vcc, 1.0, v24, 1.0
	v_fma_f32 v32, -v25, v30, 1.0
	v_fmac_f32_e32 v30, v32, v30
	v_mul_f32_e32 v32, v31, v30
	v_fma_f32 v33, -v25, v32, v31
	v_fmac_f32_e32 v32, v33, v30
	v_fma_f32 v25, -v25, v32, v31
	v_div_fmas_f32 v25, v25, v30, v32
	v_div_fixup_f32 v36, v25, v24, 1.0
	v_lshlrev_b32_e32 v26, 16, v60
	v_and_b32_e32 v27, 0xffff0000, v60
	v_pk_add_f32 v[6:7], v[6:7], v[26:27]
	v_lshlrev_b32_e32 v28, 16, v61
	v_and_b32_e32 v29, 0xffff0000, v61
	v_pk_add_f32 v[8:9], v[8:9], v[28:29]
	v_lshlrev_b32_e32 v34, 16, v62
	v_and_b32_e32 v35, 0xffff0000, v62
	v_pk_add_f32 v[10:11], v[10:11], v[34:35]
	v_lshlrev_b32_e32 v42, 16, v63
	v_and_b32_e32 v43, 0xffff0000, v63
	v_pk_add_f32 v[16:17], v[16:17], v[42:43]
	v_add_u32_e32 v18, 20, v38
	v_cmp_le_u32_e32 vcc, v39, v18
	s_and_saveexec_b64 s[10:11], vcc
	v_lshlrev_b32_e32 v22, 16, v92
	v_and_b32_e32 v23, 0xffff0000, v92
	v_pk_add_f32 v[6:7], v[6:7], v[22:23] neg_lo:[0,1] neg_hi:[0,1]
	v_lshlrev_b32_e32 v22, 16, v93
	v_and_b32_e32 v23, 0xffff0000, v93
	v_pk_add_f32 v[8:9], v[8:9], v[22:23] neg_lo:[0,1] neg_hi:[0,1]
	v_lshlrev_b32_e32 v22, 16, v94
	v_and_b32_e32 v23, 0xffff0000, v94
	v_pk_add_f32 v[10:11], v[10:11], v[22:23] neg_lo:[0,1] neg_hi:[0,1]
	v_lshlrev_b32_e32 v22, 16, v95
	v_and_b32_e32 v23, 0xffff0000, v95
	v_pk_add_f32 v[16:17], v[16:17], v[22:23] neg_lo:[0,1] neg_hi:[0,1]
	s_or_b64 exec, exec, s[10:11]
	v_pk_fma_f32 v[26:27], v[36:37], v[6:7], v[26:27] op_sel_hi:[0,1,1] neg_lo:[0,0,1] neg_hi:[0,0,1]
	v_pk_fma_f32 v[28:29], v[36:37], v[8:9], v[28:29] op_sel_hi:[0,1,1] neg_lo:[0,0,1] neg_hi:[0,0,1]
	v_pk_fma_f32 v[34:35], v[36:37], v[10:11], v[34:35] op_sel_hi:[0,1,1] neg_lo:[0,0,1] neg_hi:[0,0,1]
	v_pk_fma_f32 v[42:43], v[36:37], v[16:17], v[42:43] op_sel_hi:[0,1,1] neg_lo:[0,0,1] neg_hi:[0,0,1]
	v_cvt_pk_bf16_f32 v60, v26, v27
	v_cvt_pk_bf16_f32 v61, v28, v29
	v_cvt_pk_bf16_f32 v62, v34, v35
	v_cvt_pk_bf16_f32 v63, v42, v43
	v_add_u32_e32 v41, 0x1000, v41
	global_store_dwordx4 v41, v[60:63], s[16:17]
	v_add_u32_e32 v24, 22, v38
	v_min_u32_e32 v24, v24, v39
	v_cvt_f32_ubyte0_e32 v24, v24
	v_div_scale_f32 v25, s[0:1], v24, v24, 1.0
	v_rcp_f32_e32 v30, v25
	v_div_scale_f32 v31, vcc, 1.0, v24, 1.0
	v_fma_f32 v32, -v25, v30, 1.0
	v_fmac_f32_e32 v30, v32, v30
	v_mul_f32_e32 v32, v31, v30
	v_fma_f32 v33, -v25, v32, v31
	v_fmac_f32_e32 v32, v33, v30
	v_fma_f32 v25, -v25, v32, v31
	v_div_fmas_f32 v25, v25, v30, v32
	v_div_fixup_f32 v36, v25, v24, 1.0
	v_lshlrev_b32_e32 v26, 16, v64
; __device__ __forceinline__ unsigned cvt_pk_bf16(float lo, float hi) { f32x2_t f = {lo, hi}; bf16x2_t v = __builtin_convertvector(f, bf16x2_t); return __builtin_bit_cast(unsigned, v); }
; __device__ __forceinline__ float bflo(unsigned w) { return __uint_as_float(w << 16); }
; __device__ __forceinline__ float bfhi(unsigned w) { return __uint_as_float(w & 0xffff0000u); }
; __device__ __forceinline__ void acc8(float (&s)[8], const u32x4 a, float sg) {
;     s[0] += sg * bflo(a.x); s[1] += sg * bfhi(a.x); s[2] += sg * bflo(a.y); s[3] += sg * bfhi(a.y); s[4] += sg * bflo(a.z); s[5] += sg * bfhi(a.z); s[6] += sg * bflo(a.w); s[7] += sg * bfhi(a.w);
; }
; __device__ NOINL void pool_diff(unsigned char* ws, int wv) {
;     ...
;         for (int j = 0; j < 32; ++j) { const int t = t0 + j;
;             const u32x4 cur = *(const u32x4*)(ap + (size_t)t * NPROJ);
;             acc8(s, cur, 1.0f);
;             if (t - w >= 0) acc8(s, *(const u32x4*)(ap + (size_t)(t - w) * NPROJ), -1.0f);
;             const int cnt = (t + 1) < w ? (t + 1) : w; const float inv = 1.0f / (float)cnt;
;             u32x4 o;
;             o.x = cvt_pk_bf16(s[0] * inv - bflo(cur.x), s[1] * inv - bfhi(cur.x)); o.y = cvt_pk_bf16(s[2] * inv - bflo(cur.y), s[3] * inv - bfhi(cur.y));
;             o.z = cvt_pk_bf16(s[4] * inv - bflo(cur.z), s[5] * inv - bfhi(cur.z)); o.w = cvt_pk_bf16(s[6] * inv - bflo(cur.w), s[7] * inv - bfhi(cur.w));
;             *(u32x4*)(Y0 + ((size_t)b * SEQ + t) * 1024 + c8 * 8) = o; }
	v_and_b32_e32 v27, 0xffff0000, v64
	v_pk_add_f32 v[6:7], v[6:7], v[26:27]
	v_lshlrev_b32_e32 v28, 16, v65
	v_and_b32_e32 v29, 0xffff0000, v65
	v_pk_add_f32 v[8:9], v[8:9], v[28:29]
	v_lshlrev_b32_e32 v34, 16, v66
	v_and_b32_e32 v35, 0xffff0000, v66
	v_pk_add_f32 v[10:11], v[10:11], v[34:35]
	v_lshlrev_b32_e32 v42, 16, v67
	v_and_b32_e32 v43, 0xffff0000, v67
	v_pk_add_f32 v[16:17], v[16:17], v[42:43]
	v_add_u32_e32 v18, 21, v38
	v_cmp_le_u32_e32 vcc, v39, v18
	s_and_saveexec_b64 s[10:11], vcc
	v_lshlrev_b32_e32 v22, 16, v96
	v_and_b32_e32 v23, 0xffff0000, v96
	v_pk_add_f32 v[6:7], v[6:7], v[22:23] neg_lo:[0,1] neg_hi:[0,1]
	v_lshlrev_b32_e32 v22, 16, v97
	v_and_b32_e32 v23, 0xffff0000, v97
	v_pk_add_f32 v[8:9], v[8:9], v[22:23] neg_lo:[0,1] neg_hi:[0,1]
	v_lshlrev_b32_e32 v22, 16, v98
	v_and_b32_e32 v23, 0xffff0000, v98
	v_pk_add_f32 v[10:11], v[10:11], v[22:23] neg_lo:[0,1] neg_hi:[0,1]
	v_lshlrev_b32_e32 v22, 16, v99
	v_and_b32_e32 v23, 0xffff0000, v99
	v_pk_add_f32 v[16:17], v[16:17], v[22:23] neg_lo:[0,1] neg_hi:[0,1]
	s_or_b64 exec, exec, s[10:11]
	v_pk_fma_f32 v[26:27], v[36:37], v[6:7], v[26:27] op_sel_hi:[0,1,1] neg_lo:[0,0,1] neg_hi:[0,0,1]
	v_pk_fma_f32 v[28:29], v[36:37], v[8:9], v[28:29] op_sel_hi:[0,1,1] neg_lo:[0,0,1] neg_hi:[0,0,1]
	v_pk_fma_f32 v[34:35], v[36:37], v[10:11], v[34:35] op_sel_hi:[0,1,1] neg_lo:[0,0,1] neg_hi:[0,0,1]
	v_pk_fma_f32 v[42:43], v[36:37], v[16:17], v[42:43] op_sel_hi:[0,1,1] neg_lo:[0,0,1] neg_hi:[0,0,1]
	v_cvt_pk_bf16_f32 v64, v26, v27
	v_cvt_pk_bf16_f32 v65, v28, v29
	v_cvt_pk_bf16_f32 v66, v34, v35
	v_cvt_pk_bf16_f32 v67, v42, v43
	global_store_dwordx4 v41, v[64:67], s[16:17] offset:2048
	v_add_u32_e32 v24, 23, v38
	v_min_u32_e32 v24, v24, v39
	v_cvt_f32_ubyte0_e32 v24, v24
	v_div_scale_f32 v25, s[0:1], v24, v24, 1.0
	v_rcp_f32_e32 v30, v25
	v_div_scale_f32 v31, vcc, 1.0, v24, 1.0
	v_fma_f32 v32, -v25, v30, 1.0
	v_fmac_f32_e32 v30, v32, v30
	v_mul_f32_e32 v32, v31, v30
	v_fma_f32 v33, -v25, v32, v31
	v_fmac_f32_e32 v32, v33, v30
	v_fma_f32 v25, -v25, v32, v31
	v_div_fmas_f32 v25, v25, v30, v32
	v_div_fixup_f32 v36, v25, v24, 1.0
	v_lshlrev_b32_e32 v26, 16, v68
	v_and_b32_e32 v27, 0xffff0000, v68
	v_pk_add_f32 v[6:7], v[6:7], v[26:27]
	v_lshlrev_b32_e32 v28, 16, v69
	v_and_b32_e32 v29, 0xffff0000, v69
	v_pk_add_f32 v[8:9], v[8:9], v[28:29]
	v_lshlrev_b32_e32 v34, 16, v70
	v_and_b32_e32 v35, 0xffff0000, v70
	v_pk_add_f32 v[10:11], v[10:11], v[34:35]
	v_lshlrev_b32_e32 v42, 16, v71
	v_and_b32_e32 v43, 0xffff0000, v71
	v_pk_add_f32 v[16:17], v[16:17], v[42:43]
	v_add_u32_e32 v18, 22, v38
	v_cmp_le_u32_e32 vcc, v39, v18
	s_and_saveexec_b64 s[10:11], vcc
	v_lshlrev_b32_e32 v22, 16, v100
	v_and_b32_e32 v23, 0xffff0000, v100
	v_pk_add_f32 v[6:7], v[6:7], v[22:23] neg_lo:[0,1] neg_hi:[0,1]
	v_lshlrev_b32_e32 v22, 16, v101
	v_and_b32_e32 v23, 0xffff0000, v101
	v_pk_add_f32 v[8:9], v[8:9], v[22:23] neg_lo:[0,1] neg_hi:[0,1]
	v_lshlrev_b32_e32 v22, 16, v102
	v_and_b32_e32 v23, 0xffff0000, v102
	v_pk_add_f32 v[10:11], v[10:11], v[22:23] neg_lo:[0,1] neg_hi:[0,1]
	v_lshlrev_b32_e32 v22, 16, v103
	v_and_b32_e32 v23, 0xffff0000, v103
	v_pk_add_f32 v[16:17], v[16:17], v[22:23] neg_lo:[0,1] neg_hi:[0,1]
	s_or_b64 exec, exec, s[10:11]
	v_pk_fma_f32 v[26:27], v[36:37], v[6:7], v[26:27] op_sel_hi:[0,1,1] neg_lo:[0,0,1] neg_hi:[0,0,1]
	v_pk_fma_f32 v[28:29], v[36:37], v[8:9], v[28:29] op_sel_hi:[0,1,1] neg_lo:[0,0,1] neg_hi:[0,0,1]
	v_pk_fma_f32 v[34:35], v[36:37], v[10:11], v[34:35] op_sel_hi:[0,1,1] neg_lo:[0,0,1] neg_hi:[0,0,1]
	v_pk_fma_f32 v[42:43], v[36:37], v[16:17], v[42:43] op_sel_hi:[0,1,1] neg_lo:[0,0,1] neg_hi:[0,0,1]
	v_cvt_pk_bf16_f32 v68, v26, v27
	v_cvt_pk_bf16_f32 v69, v28, v29
	v_cvt_pk_bf16_f32 v70, v34, v35
	v_cvt_pk_bf16_f32 v71, v42, v43
	v_add_u32_e32 v41, 0x1000, v41
	global_store_dwordx4 v41, v[68:71], s[16:17]
	v_add_u32_e32 v24, 24, v38
	v_min_u32_e32 v24, v24, v39
	v_cvt_f32_ubyte0_e32 v24, v24
	v_div_scale_f32 v25, s[0:1], v24, v24, 1.0
	v_rcp_f32_e32 v30, v25
	v_div_scale_f32 v31, vcc, 1.0, v24, 1.0
	v_fma_f32 v32, -v25, v30, 1.0
	v_fmac_f32_e32 v30, v32, v30
	v_mul_f32_e32 v32, v31, v30
	v_fma_f32 v33, -v25, v32, v31
	v_fmac_f32_e32 v32, v33, v30
	v_fma_f32 v25, -v25, v32, v31
	v_div_fmas_f32 v25, v25, v30, v32
	v_div_fixup_f32 v36, v25, v24, 1.0
	v_lshlrev_b32_e32 v26, 16, v72
	v_and_b32_e32 v27, 0xffff0000, v72
	v_pk_add_f32 v[6:7], v[6:7], v[26:27]
	v_lshlrev_b32_e32 v28, 16, v73
	v_and_b32_e32 v29, 0xffff0000, v73
	v_pk_add_f32 v[8:9], v[8:9], v[28:29]
	v_lshlrev_b32_e32 v34, 16, v74
	v_and_b32_e32 v35, 0xffff0000, v74
	v_pk_add_f32 v[10:11], v[10:11], v[34:35]
	v_lshlrev_b32_e32 v42, 16, v75
	v_and_b32_e32 v43, 0xffff0000, v75
	v_pk_add_f32 v[16:17], v[16:17], v[42:43]
	v_add_u32_e32 v18, 23, v38
	v_cmp_le_u32_e32 vcc, v39, v18
	s_and_saveexec_b64 s[10:11], vcc
	v_lshlrev_b32_e32 v22, 16, v104
	v_and_b32_e32 v23, 0xffff0000, v104
	v_pk_add_f32 v[6:7], v[6:7], v[22:23] neg_lo:[0,1] neg_hi:[0,1]
	v_lshlrev_b32_e32 v22, 16, v105
	v_and_b32_e32 v23, 0xffff0000, v105
	v_pk_add_f32 v[8:9], v[8:9], v[22:23] neg_lo:[0,1] neg_hi:[0,1]
	v_lshlrev_b32_e32 v22, 16, v106
	v_and_b32_e32 v23, 0xffff0000, v106
	v_pk_add_f32 v[10:11], v[10:11], v[22:23] neg_lo:[0,1] neg_hi:[0,1]
	v_lshlrev_b32_e32 v22, 16, v107
	v_and_b32_e32 v23, 0xffff0000, v107
	v_pk_add_f32 v[16:17], v[16:17], v[22:23] neg_lo:[0,1] neg_hi:[0,1]
	s_or_b64 exec, exec, s[10:11]
	v_pk_fma_f32 v[26:27], v[36:37], v[6:7], v[26:27] op_sel_hi:[0,1,1] neg_lo:[0,0,1] neg_hi:[0,0,1]
	v_pk_fma_f32 v[28:29], v[36:37], v[8:9], v[28:29] op_sel_hi:[0,1,1] neg_lo:[0,0,1] neg_hi:[0,0,1]
	v_pk_fma_f32 v[34:35], v[36:37], v[10:11], v[34:35] op_sel_hi:[0,1,1] neg_lo:[0,0,1] neg_hi:[0,0,1]
	v_pk_fma_f32 v[42:43], v[36:37], v[16:17], v[42:43] op_sel_hi:[0,1,1] neg_lo:[0,0,1] neg_hi:[0,0,1]
	v_cvt_pk_bf16_f32 v72, v26, v27
	v_cvt_pk_bf16_f32 v73, v28, v29
	v_cvt_pk_bf16_f32 v74, v34, v35
	v_cvt_pk_bf16_f32 v75, v42, v43
	global_store_dwordx4 v41, v[72:75], s[16:17] offset:2048
	s_waitcnt vmcnt(8)
; __device__ __forceinline__ unsigned cvt_pk_bf16(float lo, float hi) { f32x2_t f = {lo, hi}; bf16x2_t v = __builtin_convertvector(f, bf16x2_t); return __builtin_bit_cast(unsigned, v); }
; __device__ __forceinline__ float bflo(unsigned w) { return __uint_as_float(w << 16); }
; __device__ __forceinline__ float bfhi(unsigned w) { return __uint_as_float(w & 0xffff0000u); }
; __device__ __forceinline__ void acc8(float (&s)[8], const u32x4 a, float sg) {
;     s[0] += sg * bflo(a.x); s[1] += sg * bfhi(a.x); s[2] += sg * bflo(a.y); s[3] += sg * bfhi(a.y); s[4] += sg * bflo(a.z); s[5] += sg * bfhi(a.z); s[6] += sg * bflo(a.w); s[7] += sg * bfhi(a.w);
; }
; __device__ NOINL void pool_diff(unsigned char* ws, int wv) {
;     ...
;         for (int j = 0; j < 32; ++j) { const int t = t0 + j;
;             const u32x4 cur = *(const u32x4*)(ap + (size_t)t * NPROJ);
;             acc8(s, cur, 1.0f);
;             if (t - w >= 0) acc8(s, *(const u32x4*)(ap + (size_t)(t - w) * NPROJ), -1.0f);
;             const int cnt = (t + 1) < w ? (t + 1) : w; const float inv = 1.0f / (float)cnt;
;             u32x4 o;
;             o.x = cvt_pk_bf16(s[0] * inv - bflo(cur.x), s[1] * inv - bfhi(cur.x)); o.y = cvt_pk_bf16(s[2] * inv - bflo(cur.y), s[3] * inv - bfhi(cur.y));
;             o.z = cvt_pk_bf16(s[4] * inv - bflo(cur.z), s[5] * inv - bfhi(cur.z)); o.w = cvt_pk_bf16(s[6] * inv - bflo(cur.w), s[7] * inv - bfhi(cur.w));
;             *(u32x4*)(Y0 + ((size_t)b * SEQ + t) * 1024 + c8 * 8) = o; }
	v_add_u32_e32 v24, 25, v38
	v_min_u32_e32 v24, v24, v39
	v_cvt_f32_ubyte0_e32 v24, v24
	v_div_scale_f32 v25, s[0:1], v24, v24, 1.0
	v_rcp_f32_e32 v30, v25
	v_div_scale_f32 v31, vcc, 1.0, v24, 1.0
	v_fma_f32 v32, -v25, v30, 1.0
	v_fmac_f32_e32 v30, v32, v30
	v_mul_f32_e32 v32, v31, v30
	v_fma_f32 v33, -v25, v32, v31
	v_fmac_f32_e32 v32, v33, v30
	v_fma_f32 v25, -v25, v32, v31
	v_div_fmas_f32 v25, v25, v30, v32
	v_div_fixup_f32 v36, v25, v24, 1.0
	v_lshlrev_b32_e32 v26, 16, v108
	v_and_b32_e32 v27, 0xffff0000, v108
	v_pk_add_f32 v[6:7], v[6:7], v[26:27]
	v_lshlrev_b32_e32 v28, 16, v109
	v_and_b32_e32 v29, 0xffff0000, v109
	v_pk_add_f32 v[8:9], v[8:9], v[28:29]
	v_lshlrev_b32_e32 v34, 16, v110
	v_and_b32_e32 v35, 0xffff0000, v110
	v_pk_add_f32 v[10:11], v[10:11], v[34:35]
	v_lshlrev_b32_e32 v42, 16, v111
	v_and_b32_e32 v43, 0xffff0000, v111
	v_pk_add_f32 v[16:17], v[16:17], v[42:43]
	v_add_u32_e32 v18, 24, v38
	v_cmp_le_u32_e32 vcc, v39, v18
	s_and_saveexec_b64 s[10:11], vcc
	v_lshlrev_b32_e32 v22, 16, v140
	v_and_b32_e32 v23, 0xffff0000, v140
	v_pk_add_f32 v[6:7], v[6:7], v[22:23] neg_lo:[0,1] neg_hi:[0,1]
	v_lshlrev_b32_e32 v22, 16, v141
	v_and_b32_e32 v23, 0xffff0000, v141
	v_pk_add_f32 v[8:9], v[8:9], v[22:23] neg_lo:[0,1] neg_hi:[0,1]
	v_lshlrev_b32_e32 v22, 16, v142
	v_and_b32_e32 v23, 0xffff0000, v142
	v_pk_add_f32 v[10:11], v[10:11], v[22:23] neg_lo:[0,1] neg_hi:[0,1]
	v_lshlrev_b32_e32 v22, 16, v143
	v_and_b32_e32 v23, 0xffff0000, v143
	v_pk_add_f32 v[16:17], v[16:17], v[22:23] neg_lo:[0,1] neg_hi:[0,1]
	s_or_b64 exec, exec, s[10:11]
	v_pk_fma_f32 v[26:27], v[36:37], v[6:7], v[26:27] op_sel_hi:[0,1,1] neg_lo:[0,0,1] neg_hi:[0,0,1]
	v_pk_fma_f32 v[28:29], v[36:37], v[8:9], v[28:29] op_sel_hi:[0,1,1] neg_lo:[0,0,1] neg_hi:[0,0,1]
	v_pk_fma_f32 v[34:35], v[36:37], v[10:11], v[34:35] op_sel_hi:[0,1,1] neg_lo:[0,0,1] neg_hi:[0,0,1]
	v_pk_fma_f32 v[42:43], v[36:37], v[16:17], v[42:43] op_sel_hi:[0,1,1] neg_lo:[0,0,1] neg_hi:[0,0,1]
	v_cvt_pk_bf16_f32 v108, v26, v27
	v_cvt_pk_bf16_f32 v109, v28, v29
	v_cvt_pk_bf16_f32 v110, v34, v35
	v_cvt_pk_bf16_f32 v111, v42, v43
	v_add_u32_e32 v41, 0x1000, v41
	global_store_dwordx4 v41, v[108:111], s[16:17]
	v_add_u32_e32 v24, 26, v38
	v_min_u32_e32 v24, v24, v39
	v_cvt_f32_ubyte0_e32 v24, v24
	v_div_scale_f32 v25, s[0:1], v24, v24, 1.0
	v_rcp_f32_e32 v30, v25
	v_div_scale_f32 v31, vcc, 1.0, v24, 1.0
	v_fma_f32 v32, -v25, v30, 1.0
	v_fmac_f32_e32 v30, v32, v30
	v_mul_f32_e32 v32, v31, v30
	v_fma_f32 v33, -v25, v32, v31
	v_fmac_f32_e32 v32, v33, v30
	v_fma_f32 v25, -v25, v32, v31
	v_div_fmas_f32 v25, v25, v30, v32
	v_div_fixup_f32 v36, v25, v24, 1.0
	v_lshlrev_b32_e32 v26, 16, v112
	v_and_b32_e32 v27, 0xffff0000, v112
	v_pk_add_f32 v[6:7], v[6:7], v[26:27]
	v_lshlrev_b32_e32 v28, 16, v113
	v_and_b32_e32 v29, 0xffff0000, v113
	v_pk_add_f32 v[8:9], v[8:9], v[28:29]
	v_lshlrev_b32_e32 v34, 16, v114
	v_and_b32_e32 v35, 0xffff0000, v114
	v_pk_add_f32 v[10:11], v[10:11], v[34:35]
	v_lshlrev_b32_e32 v42, 16, v115
	v_and_b32_e32 v43, 0xffff0000, v115
	v_pk_add_f32 v[16:17], v[16:17], v[42:43]
	v_add_u32_e32 v18, 25, v38
	v_cmp_le_u32_e32 vcc, v39, v18
	s_and_saveexec_b64 s[10:11], vcc
	v_lshlrev_b32_e32 v22, 16, v144
	v_and_b32_e32 v23, 0xffff0000, v144
	v_pk_add_f32 v[6:7], v[6:7], v[22:23] neg_lo:[0,1] neg_hi:[0,1]
	v_lshlrev_b32_e32 v22, 16, v145
	v_and_b32_e32 v23, 0xffff0000, v145
	v_pk_add_f32 v[8:9], v[8:9], v[22:23] neg_lo:[0,1] neg_hi:[0,1]
	v_lshlrev_b32_e32 v22, 16, v146
	v_and_b32_e32 v23, 0xffff0000, v146
	v_pk_add_f32 v[10:11], v[10:11], v[22:23] neg_lo:[0,1] neg_hi:[0,1]
	v_lshlrev_b32_e32 v22, 16, v147
	v_and_b32_e32 v23, 0xffff0000, v147
	v_pk_add_f32 v[16:17], v[16:17], v[22:23] neg_lo:[0,1] neg_hi:[0,1]
	s_or_b64 exec, exec, s[10:11]
	v_pk_fma_f32 v[26:27], v[36:37], v[6:7], v[26:27] op_sel_hi:[0,1,1] neg_lo:[0,0,1] neg_hi:[0,0,1]
	v_pk_fma_f32 v[28:29], v[36:37], v[8:9], v[28:29] op_sel_hi:[0,1,1] neg_lo:[0,0,1] neg_hi:[0,0,1]
	v_pk_fma_f32 v[34:35], v[36:37], v[10:11], v[34:35] op_sel_hi:[0,1,1] neg_lo:[0,0,1] neg_hi:[0,0,1]
	v_pk_fma_f32 v[42:43], v[36:37], v[16:17], v[42:43] op_sel_hi:[0,1,1] neg_lo:[0,0,1] neg_hi:[0,0,1]
	v_cvt_pk_bf16_f32 v112, v26, v27
	v_cvt_pk_bf16_f32 v113, v28, v29
	v_cvt_pk_bf16_f32 v114, v34, v35
	v_cvt_pk_bf16_f32 v115, v42, v43
	global_store_dwordx4 v41, v[112:115], s[16:17] offset:2048
	v_add_u32_e32 v24, 27, v38
	v_min_u32_e32 v24, v24, v39
	v_cvt_f32_ubyte0_e32 v24, v24
	v_div_scale_f32 v25, s[0:1], v24, v24, 1.0
	v_rcp_f32_e32 v30, v25
	v_div_scale_f32 v31, vcc, 1.0, v24, 1.0
	v_fma_f32 v32, -v25, v30, 1.0
	v_fmac_f32_e32 v30, v32, v30
	v_mul_f32_e32 v32, v31, v30
	v_fma_f32 v33, -v25, v32, v31
	v_fmac_f32_e32 v32, v33, v30
	v_fma_f32 v25, -v25, v32, v31
	v_div_fmas_f32 v25, v25, v30, v32
	v_div_fixup_f32 v36, v25, v24, 1.0
	v_lshlrev_b32_e32 v26, 16, v116
	v_and_b32_e32 v27, 0xffff0000, v116
	v_pk_add_f32 v[6:7], v[6:7], v[26:27]
	v_lshlrev_b32_e32 v28, 16, v117
	v_and_b32_e32 v29, 0xffff0000, v117
	v_pk_add_f32 v[8:9], v[8:9], v[28:29]
	v_lshlrev_b32_e32 v34, 16, v118
	v_and_b32_e32 v35, 0xffff0000, v118
	v_pk_add_f32 v[10:11], v[10:11], v[34:35]
	v_lshlrev_b32_e32 v42, 16, v119
	v_and_b32_e32 v43, 0xffff0000, v119
	v_pk_add_f32 v[16:17], v[16:17], v[42:43]
	v_add_u32_e32 v18, 26, v38
	v_cmp_le_u32_e32 vcc, v39, v18
	s_and_saveexec_b64 s[10:11], vcc
	v_lshlrev_b32_e32 v22, 16, v148
	v_and_b32_e32 v23, 0xffff0000, v148
	v_pk_add_f32 v[6:7], v[6:7], v[22:23] neg_lo:[0,1] neg_hi:[0,1]
	v_lshlrev_b32_e32 v22, 16, v149
	v_and_b32_e32 v23, 0xffff0000, v149
	v_pk_add_f32 v[8:9], v[8:9], v[22:23] neg_lo:[0,1] neg_hi:[0,1]
	v_lshlrev_b32_e32 v22, 16, v150
; __device__ __forceinline__ unsigned cvt_pk_bf16(float lo, float hi) { f32x2_t f = {lo, hi}; bf16x2_t v = __builtin_convertvector(f, bf16x2_t); return __builtin_bit_cast(unsigned, v); }
; __device__ __forceinline__ float bflo(unsigned w) { return __uint_as_float(w << 16); }
; __device__ __forceinline__ float bfhi(unsigned w) { return __uint_as_float(w & 0xffff0000u); }
; __device__ __forceinline__ void acc8(float (&s)[8], const u32x4 a, float sg) {
;     s[0] += sg * bflo(a.x); s[1] += sg * bfhi(a.x); s[2] += sg * bflo(a.y); s[3] += sg * bfhi(a.y); s[4] += sg * bflo(a.z); s[5] += sg * bfhi(a.z); s[6] += sg * bflo(a.w); s[7] += sg * bfhi(a.w);
; }
; __device__ NOINL void pool_diff(unsigned char* ws, int wv) {
;     ...
;         for (int j = 0; j < 32; ++j) { const int t = t0 + j;
;             const u32x4 cur = *(const u32x4*)(ap + (size_t)t * NPROJ);
;             acc8(s, cur, 1.0f);
;             if (t - w >= 0) acc8(s, *(const u32x4*)(ap + (size_t)(t - w) * NPROJ), -1.0f);
;             const int cnt = (t + 1) < w ? (t + 1) : w; const float inv = 1.0f / (float)cnt;
;             u32x4 o;
;             o.x = cvt_pk_bf16(s[0] * inv - bflo(cur.x), s[1] * inv - bfhi(cur.x)); o.y = cvt_pk_bf16(s[2] * inv - bflo(cur.y), s[3] * inv - bfhi(cur.y));
;             o.z = cvt_pk_bf16(s[4] * inv - bflo(cur.z), s[5] * inv - bfhi(cur.z)); o.w = cvt_pk_bf16(s[6] * inv - bflo(cur.w), s[7] * inv - bfhi(cur.w));
;             *(u32x4*)(Y0 + ((size_t)b * SEQ + t) * 1024 + c8 * 8) = o; }
	v_and_b32_e32 v23, 0xffff0000, v150
	v_pk_add_f32 v[10:11], v[10:11], v[22:23] neg_lo:[0,1] neg_hi:[0,1]
	v_lshlrev_b32_e32 v22, 16, v151
	v_and_b32_e32 v23, 0xffff0000, v151
	v_pk_add_f32 v[16:17], v[16:17], v[22:23] neg_lo:[0,1] neg_hi:[0,1]
	s_or_b64 exec, exec, s[10:11]
	v_pk_fma_f32 v[26:27], v[36:37], v[6:7], v[26:27] op_sel_hi:[0,1,1] neg_lo:[0,0,1] neg_hi:[0,0,1]
	v_pk_fma_f32 v[28:29], v[36:37], v[8:9], v[28:29] op_sel_hi:[0,1,1] neg_lo:[0,0,1] neg_hi:[0,0,1]
	v_pk_fma_f32 v[34:35], v[36:37], v[10:11], v[34:35] op_sel_hi:[0,1,1] neg_lo:[0,0,1] neg_hi:[0,0,1]
	v_pk_fma_f32 v[42:43], v[36:37], v[16:17], v[42:43] op_sel_hi:[0,1,1] neg_lo:[0,0,1] neg_hi:[0,0,1]
	v_cvt_pk_bf16_f32 v116, v26, v27
	v_cvt_pk_bf16_f32 v117, v28, v29
	v_cvt_pk_bf16_f32 v118, v34, v35
	v_cvt_pk_bf16_f32 v119, v42, v43
	v_add_u32_e32 v41, 0x1000, v41
	global_store_dwordx4 v41, v[116:119], s[16:17]
	v_add_u32_e32 v24, 28, v38
	v_min_u32_e32 v24, v24, v39
	v_cvt_f32_ubyte0_e32 v24, v24
	v_div_scale_f32 v25, s[0:1], v24, v24, 1.0
	v_rcp_f32_e32 v30, v25
	v_div_scale_f32 v31, vcc, 1.0, v24, 1.0
	v_fma_f32 v32, -v25, v30, 1.0
	v_fmac_f32_e32 v30, v32, v30
	v_mul_f32_e32 v32, v31, v30
	v_fma_f32 v33, -v25, v32, v31
	v_fmac_f32_e32 v32, v33, v30
	v_fma_f32 v25, -v25, v32, v31
	v_div_fmas_f32 v25, v25, v30, v32
	v_div_fixup_f32 v36, v25, v24, 1.0
	v_lshlrev_b32_e32 v26, 16, v120
	v_and_b32_e32 v27, 0xffff0000, v120
	v_pk_add_f32 v[6:7], v[6:7], v[26:27]
	v_lshlrev_b32_e32 v28, 16, v121
	v_and_b32_e32 v29, 0xffff0000, v121
	v_pk_add_f32 v[8:9], v[8:9], v[28:29]
	v_lshlrev_b32_e32 v34, 16, v122
	v_and_b32_e32 v35, 0xffff0000, v122
	v_pk_add_f32 v[10:11], v[10:11], v[34:35]
	v_lshlrev_b32_e32 v42, 16, v123
	v_and_b32_e32 v43, 0xffff0000, v123
	v_pk_add_f32 v[16:17], v[16:17], v[42:43]
	v_add_u32_e32 v18, 27, v38
	v_cmp_le_u32_e32 vcc, v39, v18
	s_and_saveexec_b64 s[10:11], vcc
	v_lshlrev_b32_e32 v22, 16, v152
	v_and_b32_e32 v23, 0xffff0000, v152
	v_pk_add_f32 v[6:7], v[6:7], v[22:23] neg_lo:[0,1] neg_hi:[0,1]
	v_lshlrev_b32_e32 v22, 16, v153
	v_and_b32_e32 v23, 0xffff0000, v153
	v_pk_add_f32 v[8:9], v[8:9], v[22:23] neg_lo:[0,1] neg_hi:[0,1]
	v_lshlrev_b32_e32 v22, 16, v154
	v_and_b32_e32 v23, 0xffff0000, v154
	v_pk_add_f32 v[10:11], v[10:11], v[22:23] neg_lo:[0,1] neg_hi:[0,1]
	v_lshlrev_b32_e32 v22, 16, v155
	v_and_b32_e32 v23, 0xffff0000, v155
	v_pk_add_f32 v[16:17], v[16:17], v[22:23] neg_lo:[0,1] neg_hi:[0,1]
	s_or_b64 exec, exec, s[10:11]
	v_pk_fma_f32 v[26:27], v[36:37], v[6:7], v[26:27] op_sel_hi:[0,1,1] neg_lo:[0,0,1] neg_hi:[0,0,1]
	v_pk_fma_f32 v[28:29], v[36:37], v[8:9], v[28:29] op_sel_hi:[0,1,1] neg_lo:[0,0,1] neg_hi:[0,0,1]
	v_pk_fma_f32 v[34:35], v[36:37], v[10:11], v[34:35] op_sel_hi:[0,1,1] neg_lo:[0,0,1] neg_hi:[0,0,1]
	v_pk_fma_f32 v[42:43], v[36:37], v[16:17], v[42:43] op_sel_hi:[0,1,1] neg_lo:[0,0,1] neg_hi:[0,0,1]
	v_cvt_pk_bf16_f32 v120, v26, v27
	v_cvt_pk_bf16_f32 v121, v28, v29
	v_cvt_pk_bf16_f32 v122, v34, v35
	v_cvt_pk_bf16_f32 v123, v42, v43
	global_store_dwordx4 v41, v[120:123], s[16:17] offset:2048
	v_add_u32_e32 v24, 29, v38
	v_min_u32_e32 v24, v24, v39
	v_cvt_f32_ubyte0_e32 v24, v24
	v_div_scale_f32 v25, s[0:1], v24, v24, 1.0
	v_rcp_f32_e32 v30, v25
	v_div_scale_f32 v31, vcc, 1.0, v24, 1.0
	v_fma_f32 v32, -v25, v30, 1.0
	v_fmac_f32_e32 v30, v32, v30
	v_mul_f32_e32 v32, v31, v30
	v_fma_f32 v33, -v25, v32, v31
	v_fmac_f32_e32 v32, v33, v30
	v_fma_f32 v25, -v25, v32, v31
	v_div_fmas_f32 v25, v25, v30, v32
	v_div_fixup_f32 v36, v25, v24, 1.0
	v_lshlrev_b32_e32 v26, 16, v124
	v_and_b32_e32 v27, 0xffff0000, v124
	v_pk_add_f32 v[6:7], v[6:7], v[26:27]
	v_lshlrev_b32_e32 v28, 16, v125
	v_and_b32_e32 v29, 0xffff0000, v125
	v_pk_add_f32 v[8:9], v[8:9], v[28:29]
	v_lshlrev_b32_e32 v34, 16, v126
	v_and_b32_e32 v35, 0xffff0000, v126
	v_pk_add_f32 v[10:11], v[10:11], v[34:35]
	v_lshlrev_b32_e32 v42, 16, v127
	v_and_b32_e32 v43, 0xffff0000, v127
	v_pk_add_f32 v[16:17], v[16:17], v[42:43]
	v_add_u32_e32 v18, 28, v38
	v_cmp_le_u32_e32 vcc, v39, v18
	s_and_saveexec_b64 s[10:11], vcc
	v_lshlrev_b32_e32 v22, 16, v156
	v_and_b32_e32 v23, 0xffff0000, v156
	v_pk_add_f32 v[6:7], v[6:7], v[22:23] neg_lo:[0,1] neg_hi:[0,1]
	v_lshlrev_b32_e32 v22, 16, v157
	v_and_b32_e32 v23, 0xffff0000, v157
	v_pk_add_f32 v[8:9], v[8:9], v[22:23] neg_lo:[0,1] neg_hi:[0,1]
	v_lshlrev_b32_e32 v22, 16, v158
	v_and_b32_e32 v23, 0xffff0000, v158
	v_pk_add_f32 v[10:11], v[10:11], v[22:23] neg_lo:[0,1] neg_hi:[0,1]
	v_lshlrev_b32_e32 v22, 16, v159
	v_and_b32_e32 v23, 0xffff0000, v159
	v_pk_add_f32 v[16:17], v[16:17], v[22:23] neg_lo:[0,1] neg_hi:[0,1]
	s_or_b64 exec, exec, s[10:11]
	v_pk_fma_f32 v[26:27], v[36:37], v[6:7], v[26:27] op_sel_hi:[0,1,1] neg_lo:[0,0,1] neg_hi:[0,0,1]
	v_pk_fma_f32 v[28:29], v[36:37], v[8:9], v[28:29] op_sel_hi:[0,1,1] neg_lo:[0,0,1] neg_hi:[0,0,1]
	v_pk_fma_f32 v[34:35], v[36:37], v[10:11], v[34:35] op_sel_hi:[0,1,1] neg_lo:[0,0,1] neg_hi:[0,0,1]
	v_pk_fma_f32 v[42:43], v[36:37], v[16:17], v[42:43] op_sel_hi:[0,1,1] neg_lo:[0,0,1] neg_hi:[0,0,1]
	v_cvt_pk_bf16_f32 v124, v26, v27
	v_cvt_pk_bf16_f32 v125, v28, v29
	v_cvt_pk_bf16_f32 v126, v34, v35
	v_cvt_pk_bf16_f32 v127, v42, v43
	v_add_u32_e32 v41, 0x1000, v41
	global_store_dwordx4 v41, v[124:127], s[16:17]
	v_add_u32_e32 v24, 30, v38
	v_min_u32_e32 v24, v24, v39
	v_cvt_f32_ubyte0_e32 v24, v24
	v_div_scale_f32 v25, s[0:1], v24, v24, 1.0
	v_rcp_f32_e32 v30, v25
	v_div_scale_f32 v31, vcc, 1.0, v24, 1.0
	v_fma_f32 v32, -v25, v30, 1.0
	v_fmac_f32_e32 v30, v32, v30
	v_mul_f32_e32 v32, v31, v30
	v_fma_f32 v33, -v25, v32, v31
	v_fmac_f32_e32 v32, v33, v30
	v_fma_f32 v25, -v25, v32, v31
	v_div_fmas_f32 v25, v25, v30, v32
; __device__ __forceinline__ unsigned cvt_pk_bf16(float lo, float hi) { f32x2_t f = {lo, hi}; bf16x2_t v = __builtin_convertvector(f, bf16x2_t); return __builtin_bit_cast(unsigned, v); }
; __device__ __forceinline__ float bflo(unsigned w) { return __uint_as_float(w << 16); }
; __device__ __forceinline__ float bfhi(unsigned w) { return __uint_as_float(w & 0xffff0000u); }
; __device__ __forceinline__ void acc8(float (&s)[8], const u32x4 a, float sg) {
;     s[0] += sg * bflo(a.x); s[1] += sg * bfhi(a.x); s[2] += sg * bflo(a.y); s[3] += sg * bfhi(a.y); s[4] += sg * bflo(a.z); s[5] += sg * bfhi(a.z); s[6] += sg * bflo(a.w); s[7] += sg * bfhi(a.w);
; }
; __device__ NOINL void pool_diff(unsigned char* ws, int wv) {
;     ...
;         for (int j = 0; j < 32; ++j) { const int t = t0 + j;
;             const u32x4 cur = *(const u32x4*)(ap + (size_t)t * NPROJ);
;             acc8(s, cur, 1.0f);
;             if (t - w >= 0) acc8(s, *(const u32x4*)(ap + (size_t)(t - w) * NPROJ), -1.0f);
;             const int cnt = (t + 1) < w ? (t + 1) : w; const float inv = 1.0f / (float)cnt;
;             u32x4 o;
;             o.x = cvt_pk_bf16(s[0] * inv - bflo(cur.x), s[1] * inv - bfhi(cur.x)); o.y = cvt_pk_bf16(s[2] * inv - bflo(cur.y), s[3] * inv - bfhi(cur.y));
;             o.z = cvt_pk_bf16(s[4] * inv - bflo(cur.z), s[5] * inv - bfhi(cur.z)); o.w = cvt_pk_bf16(s[6] * inv - bflo(cur.w), s[7] * inv - bfhi(cur.w));
;             *(u32x4*)(Y0 + ((size_t)b * SEQ + t) * 1024 + c8 * 8) = o; }
	v_div_fixup_f32 v36, v25, v24, 1.0
	v_lshlrev_b32_e32 v26, 16, v128
	v_and_b32_e32 v27, 0xffff0000, v128
	v_pk_add_f32 v[6:7], v[6:7], v[26:27]
	v_lshlrev_b32_e32 v28, 16, v129
	v_and_b32_e32 v29, 0xffff0000, v129
	v_pk_add_f32 v[8:9], v[8:9], v[28:29]
	v_lshlrev_b32_e32 v34, 16, v130
	v_and_b32_e32 v35, 0xffff0000, v130
	v_pk_add_f32 v[10:11], v[10:11], v[34:35]
	v_lshlrev_b32_e32 v42, 16, v131
	v_and_b32_e32 v43, 0xffff0000, v131
	v_pk_add_f32 v[16:17], v[16:17], v[42:43]
	v_add_u32_e32 v18, 29, v38
	v_cmp_le_u32_e32 vcc, v39, v18
	s_and_saveexec_b64 s[10:11], vcc
	v_lshlrev_b32_e32 v22, 16, v160
	v_and_b32_e32 v23, 0xffff0000, v160
	v_pk_add_f32 v[6:7], v[6:7], v[22:23] neg_lo:[0,1] neg_hi:[0,1]
	v_lshlrev_b32_e32 v22, 16, v161
	v_and_b32_e32 v23, 0xffff0000, v161
	v_pk_add_f32 v[8:9], v[8:9], v[22:23] neg_lo:[0,1] neg_hi:[0,1]
	v_lshlrev_b32_e32 v22, 16, v162
	v_and_b32_e32 v23, 0xffff0000, v162
	v_pk_add_f32 v[10:11], v[10:11], v[22:23] neg_lo:[0,1] neg_hi:[0,1]
	v_lshlrev_b32_e32 v22, 16, v163
	v_and_b32_e32 v23, 0xffff0000, v163
	v_pk_add_f32 v[16:17], v[16:17], v[22:23] neg_lo:[0,1] neg_hi:[0,1]
	s_or_b64 exec, exec, s[10:11]
	v_pk_fma_f32 v[26:27], v[36:37], v[6:7], v[26:27] op_sel_hi:[0,1,1] neg_lo:[0,0,1] neg_hi:[0,0,1]
	v_pk_fma_f32 v[28:29], v[36:37], v[8:9], v[28:29] op_sel_hi:[0,1,1] neg_lo:[0,0,1] neg_hi:[0,0,1]
	v_pk_fma_f32 v[34:35], v[36:37], v[10:11], v[34:35] op_sel_hi:[0,1,1] neg_lo:[0,0,1] neg_hi:[0,0,1]
	v_pk_fma_f32 v[42:43], v[36:37], v[16:17], v[42:43] op_sel_hi:[0,1,1] neg_lo:[0,0,1] neg_hi:[0,0,1]
	v_cvt_pk_bf16_f32 v128, v26, v27
	v_cvt_pk_bf16_f32 v129, v28, v29
	v_cvt_pk_bf16_f32 v130, v34, v35
	v_cvt_pk_bf16_f32 v131, v42, v43
	global_store_dwordx4 v41, v[128:131], s[16:17] offset:2048
	v_add_u32_e32 v24, 31, v38
	v_min_u32_e32 v24, v24, v39
	v_cvt_f32_ubyte0_e32 v24, v24
	v_div_scale_f32 v25, s[0:1], v24, v24, 1.0
	v_rcp_f32_e32 v30, v25
	v_div_scale_f32 v31, vcc, 1.0, v24, 1.0
	v_fma_f32 v32, -v25, v30, 1.0
	v_fmac_f32_e32 v30, v32, v30
	v_mul_f32_e32 v32, v31, v30
	v_fma_f32 v33, -v25, v32, v31
	v_fmac_f32_e32 v32, v33, v30
	v_fma_f32 v25, -v25, v32, v31
	v_div_fmas_f32 v25, v25, v30, v32
	v_div_fixup_f32 v36, v25, v24, 1.0
	v_lshlrev_b32_e32 v26, 16, v132
	v_and_b32_e32 v27, 0xffff0000, v132
	v_pk_add_f32 v[6:7], v[6:7], v[26:27]
	v_lshlrev_b32_e32 v28, 16, v133
	v_and_b32_e32 v29, 0xffff0000, v133
	v_pk_add_f32 v[8:9], v[8:9], v[28:29]
	v_lshlrev_b32_e32 v34, 16, v134
	v_and_b32_e32 v35, 0xffff0000, v134
	v_pk_add_f32 v[10:11], v[10:11], v[34:35]
	v_lshlrev_b32_e32 v42, 16, v135
	v_and_b32_e32 v43, 0xffff0000, v135
	v_pk_add_f32 v[16:17], v[16:17], v[42:43]
	v_add_u32_e32 v18, 30, v38
	v_cmp_le_u32_e32 vcc, v39, v18
	s_and_saveexec_b64 s[10:11], vcc
	v_lshlrev_b32_e32 v22, 16, v164
	v_and_b32_e32 v23, 0xffff0000, v164
	v_pk_add_f32 v[6:7], v[6:7], v[22:23] neg_lo:[0,1] neg_hi:[0,1]
	v_lshlrev_b32_e32 v22, 16, v165
	v_and_b32_e32 v23, 0xffff0000, v165
	v_pk_add_f32 v[8:9], v[8:9], v[22:23] neg_lo:[0,1] neg_hi:[0,1]
	v_lshlrev_b32_e32 v22, 16, v166
	v_and_b32_e32 v23, 0xffff0000, v166
	v_pk_add_f32 v[10:11], v[10:11], v[22:23] neg_lo:[0,1] neg_hi:[0,1]
	v_lshlrev_b32_e32 v22, 16, v167
	v_and_b32_e32 v23, 0xffff0000, v167
	v_pk_add_f32 v[16:17], v[16:17], v[22:23] neg_lo:[0,1] neg_hi:[0,1]
	s_or_b64 exec, exec, s[10:11]
	v_pk_fma_f32 v[26:27], v[36:37], v[6:7], v[26:27] op_sel_hi:[0,1,1] neg_lo:[0,0,1] neg_hi:[0,0,1]
	v_pk_fma_f32 v[28:29], v[36:37], v[8:9], v[28:29] op_sel_hi:[0,1,1] neg_lo:[0,0,1] neg_hi:[0,0,1]
	v_pk_fma_f32 v[34:35], v[36:37], v[10:11], v[34:35] op_sel_hi:[0,1,1] neg_lo:[0,0,1] neg_hi:[0,0,1]
	v_pk_fma_f32 v[42:43], v[36:37], v[16:17], v[42:43] op_sel_hi:[0,1,1] neg_lo:[0,0,1] neg_hi:[0,0,1]
	v_cvt_pk_bf16_f32 v132, v26, v27
	v_cvt_pk_bf16_f32 v133, v28, v29
	v_cvt_pk_bf16_f32 v134, v34, v35
	v_cvt_pk_bf16_f32 v135, v42, v43
	v_add_u32_e32 v41, 0x1000, v41
	global_store_dwordx4 v41, v[132:135], s[16:17]
	v_add_u32_e32 v24, 32, v38
	v_min_u32_e32 v24, v24, v39
	v_cvt_f32_ubyte0_e32 v24, v24
	v_div_scale_f32 v25, s[0:1], v24, v24, 1.0
	v_rcp_f32_e32 v30, v25
	v_div_scale_f32 v31, vcc, 1.0, v24, 1.0
	v_fma_f32 v32, -v25, v30, 1.0
	v_fmac_f32_e32 v30, v32, v30
	v_mul_f32_e32 v32, v31, v30
	v_fma_f32 v33, -v25, v32, v31
	v_fmac_f32_e32 v32, v33, v30
	v_fma_f32 v25, -v25, v32, v31
	v_div_fmas_f32 v25, v25, v30, v32
	v_div_fixup_f32 v36, v25, v24, 1.0
	v_lshlrev_b32_e32 v26, 16, v136
	v_and_b32_e32 v27, 0xffff0000, v136
	v_pk_add_f32 v[6:7], v[6:7], v[26:27]
	v_lshlrev_b32_e32 v28, 16, v137
	v_and_b32_e32 v29, 0xffff0000, v137
	v_pk_add_f32 v[8:9], v[8:9], v[28:29]
	v_lshlrev_b32_e32 v34, 16, v138
	v_and_b32_e32 v35, 0xffff0000, v138
	v_pk_add_f32 v[10:11], v[10:11], v[34:35]
	v_lshlrev_b32_e32 v42, 16, v139
	v_and_b32_e32 v43, 0xffff0000, v139
	v_pk_add_f32 v[16:17], v[16:17], v[42:43]
	v_add_u32_e32 v18, 31, v38
	v_cmp_le_u32_e32 vcc, v39, v18
	s_and_saveexec_b64 s[10:11], vcc
	v_lshlrev_b32_e32 v22, 16, v168
	v_and_b32_e32 v23, 0xffff0000, v168
	v_pk_add_f32 v[6:7], v[6:7], v[22:23] neg_lo:[0,1] neg_hi:[0,1]
	v_lshlrev_b32_e32 v22, 16, v169
	v_and_b32_e32 v23, 0xffff0000, v169
	v_pk_add_f32 v[8:9], v[8:9], v[22:23] neg_lo:[0,1] neg_hi:[0,1]
	v_lshlrev_b32_e32 v22, 16, v170
	v_and_b32_e32 v23, 0xffff0000, v170
	v_pk_add_f32 v[10:11], v[10:11], v[22:23] neg_lo:[0,1] neg_hi:[0,1]
	v_lshlrev_b32_e32 v22, 16, v171
	v_and_b32_e32 v23, 0xffff0000, v171
	v_pk_add_f32 v[16:17], v[16:17], v[22:23] neg_lo:[0,1] neg_hi:[0,1]
	s_or_b64 exec, exec, s[10:11]
	v_pk_fma_f32 v[26:27], v[36:37], v[6:7], v[26:27] op_sel_hi:[0,1,1] neg_lo:[0,0,1] neg_hi:[0,0,1]
	v_pk_fma_f32 v[28:29], v[36:37], v[8:9], v[28:29] op_sel_hi:[0,1,1] neg_lo:[0,0,1] neg_hi:[0,0,1]
	v_pk_fma_f32 v[34:35], v[36:37], v[10:11], v[34:35] op_sel_hi:[0,1,1] neg_lo:[0,0,1] neg_hi:[0,0,1]
	v_pk_fma_f32 v[42:43], v[36:37], v[16:17], v[42:43] op_sel_hi:[0,1,1] neg_lo:[0,0,1] neg_hi:[0,0,1]
	v_cvt_pk_bf16_f32 v136, v26, v27
	v_cvt_pk_bf16_f32 v137, v28, v29
	v_cvt_pk_bf16_f32 v138, v34, v35
	v_cvt_pk_bf16_f32 v139, v42, v43
	global_store_dwordx4 v41, v[136:139], s[16:17] offset:2048
	s_branch .LBB0_305

; __device__ __forceinline__ bf16_t f2bf(float f) { return (bf16_t)(cvt_pk_bf16(f, 0.f) & 0xffffu); }
; __device__ NOINL void sb_unit(unsigned char* ws, LAS unsigned char* lds, int unit, int wv) {
;     ...
; #pragma unroll
;     for (int c = 0; c < 8; ++c)
; #pragma unroll
;         for (int j = 0; j < 4; ++j) YSB[(tokbase + t0 + 4 * fq + j) * 1024 + hd * 128 + 16 * c + fr] = f2bf(oacc[c][j]);
.LBB0_357:
	s_lshl_b32 s0, s35, 1
	s_add_u32 s0, s22, s0
	s_addc_u32 s1, s23, 0
	v_lshlrev_b32_e32 v4, 1, v154
	v_mov_b32_e32 v5, v0
	v_or_b32_e32 v2, s31, v2
	v_mov_b32_e32 v3, s34
	v_lshl_add_u64 v[4:5], s[0:1], 0, v[4:5]
	s_mov_b64 s[0:1], 0x34e00000
	v_lshl_add_u64 v[4:5], v[4:5], 0, s[0:1]
	v_lshlrev_b64 v[2:3], 11, v[2:3]
	v_cvt_pk_bf16_f32 v1, v46, s0
	v_lshl_add_u64 v[6:7], v[4:5], 0, v[2:3]
	v_or_b32_e32 v8, 0x800, v2
	v_mov_b32_e32 v9, v3
	global_store_short v[6:7], v1, off
	v_cvt_pk_bf16_f32 v1, v47, s0
	v_lshl_add_u64 v[8:9], v[4:5], 0, v[8:9]
	v_or_b32_e32 v10, 0x1000, v2
	v_mov_b32_e32 v11, v3
	global_store_short v[8:9], v1, off
	v_cvt_pk_bf16_f32 v1, v48, s0
	v_lshl_add_u64 v[10:11], v[4:5], 0, v[10:11]
	v_or_b32_e32 v2, 0x1800, v2
	global_store_short v[10:11], v1, off
	v_cvt_pk_bf16_f32 v1, v49, s0
	v_lshl_add_u64 v[2:3], v[4:5], 0, v[2:3]
	global_store_short v[2:3], v1, off
	v_cvt_pk_bf16_f32 v1, v42, s0
	global_store_short v[6:7], v1, off offset:32
	v_cvt_pk_bf16_f32 v1, v43, s0
	global_store_short v[8:9], v1, off offset:32
	v_cvt_pk_bf16_f32 v1, v44, s0
	global_store_short v[10:11], v1, off offset:32
	v_cvt_pk_bf16_f32 v1, v45, s0
	global_store_short v[2:3], v1, off offset:32
	v_cvt_pk_bf16_f32 v1, v38, s0
	global_store_short v[6:7], v1, off offset:64
	v_cvt_pk_bf16_f32 v1, v39, s0
	global_store_short v[8:9], v1, off offset:64
	v_cvt_pk_bf16_f32 v1, v40, s0
	global_store_short v[10:11], v1, off offset:64
	v_cvt_pk_bf16_f32 v1, v41, s0
	global_store_short v[2:3], v1, off offset:64
	v_cvt_pk_bf16_f32 v1, v34, s0
	global_store_short v[6:7], v1, off offset:96
	v_cvt_pk_bf16_f32 v1, v35, s0
	global_store_short v[8:9], v1, off offset:96
	v_cvt_pk_bf16_f32 v1, v36, s0
	global_store_short v[10:11], v1, off offset:96
	v_cvt_pk_bf16_f32 v1, v37, s0
	global_store_short v[2:3], v1, off offset:96
	v_cvt_pk_bf16_f32 v1, v30, s0
	global_store_short v[6:7], v1, off offset:128
	v_cvt_pk_bf16_f32 v1, v31, s0
	global_store_short v[8:9], v1, off offset:128
	v_cvt_pk_bf16_f32 v1, v32, s0
	global_store_short v[10:11], v1, off offset:128
	v_cvt_pk_bf16_f32 v1, v33, s0
	global_store_short v[2:3], v1, off offset:128
	v_cvt_pk_bf16_f32 v1, v26, s0
	global_store_short v[6:7], v1, off offset:160
	v_cvt_pk_bf16_f32 v1, v27, s0
	global_store_short v[8:9], v1, off offset:160
	v_cvt_pk_bf16_f32 v1, v28, s0
	global_store_short v[10:11], v1, off offset:160
	v_cvt_pk_bf16_f32 v1, v29, s0
	global_store_short v[2:3], v1, off offset:160
	v_cvt_pk_bf16_f32 v1, v22, s0
	global_store_short v[6:7], v1, off offset:192
	v_cvt_pk_bf16_f32 v1, v23, s0
	global_store_short v[8:9], v1, off offset:192
	v_cvt_pk_bf16_f32 v1, v24, s0
	global_store_short v[10:11], v1, off offset:192
	v_cvt_pk_bf16_f32 v1, v25, s0
	global_store_short v[2:3], v1, off offset:192
	v_cvt_pk_bf16_f32 v1, v18, s0
	global_store_short v[6:7], v1, off offset:224
	v_cvt_pk_bf16_f32 v1, v19, s0
	global_store_short v[8:9], v1, off offset:224
	v_cvt_pk_bf16_f32 v1, v20, s0
	s_add_i32 s30, s30, s33
	global_store_short v[10:11], v1, off offset:224
	v_cvt_pk_bf16_f32 v1, v21, s0
	s_cmpk_gt_i32 s30, 0x7ff
	global_store_short v[2:3], v1, off offset:224
	s_cbranch_scc1 .LBB0_303

; #define LAS __attribute__((address_space(3)))
; __device__ NOINL void sb_unit(unsigned char* ws, LAS unsigned char* lds, int unit, int wv) {
;     ...
;     bf16x8 qf[4];
; #pragma unroll
;     for (int ks = 0; ks < 4; ++ks) qf[ks] = *(const bf16x8*)(PROJ + (tokbase + t0 + fr) * NPROJ + C_SBQ + hd * 128 + ks * 32 + fq * 8);
;     f32x4 oacc[8];
; #pragma unroll
;     for (int c = 0; c < 8; ++c) oacc[c] = (f32x4){0.f, 0.f, 0.f, 0.f};
;     float R = 0.f;
;     const int tq = t0 + fr;
;     const float scale = 0.08838834764831845f;
;     const int q4 = fr >> 2, p4 = fr & 3;
;     u32x4 vpf[8]; bf16x8 kpf[2][4];
;     ...
;     SB_ISSUE((t0 + 14) >> 5);
;     ...
;         const int s0 = tile * 32;
; #pragma unroll
;         for (int i = 0; i < 8; ++i) *(LAS u32x4*)(vb + ((lane >> 4) + 4 * i) * 256 + (lane & 15) * 16) = vpf[i];
;         bf16x8 kcur[2][4];
; #pragma unroll
;         for (int a = 0; a < 2; ++a)
; #pragma unroll
;             for (int ks = 0; ks < 4; ++ks) kcur[a][ks] = kpf[a][ks];
.LBB0_360:
	s_lshl_b32 s7, s7, 3
	v_mov_b32_e32 v21, 0
	v_and_b32_e32 v154, 15, v1
	s_and_b32 s35, s7, 0x380
	s_andn2_b64 vcc, exec, s[2:3]
	v_mov_b32_e32 v20, v21
	v_mov_b32_e32 v19, v21
	v_mov_b32_e32 v18, v21
	v_mov_b32_e32 v25, v21
	v_mov_b32_e32 v24, v21
	v_mov_b32_e32 v23, v21
	v_mov_b32_e32 v22, v21
	v_mov_b32_e32 v29, v21
	v_mov_b32_e32 v28, v21
	v_mov_b32_e32 v27, v21
	v_mov_b32_e32 v26, v21
	v_mov_b32_e32 v33, v21
	v_mov_b32_e32 v32, v21
	v_mov_b32_e32 v31, v21
	v_mov_b32_e32 v30, v21
	v_mov_b32_e32 v37, v21
	v_mov_b32_e32 v36, v21
	v_mov_b32_e32 v35, v21
	v_mov_b32_e32 v34, v21
	v_mov_b32_e32 v41, v21
	v_mov_b32_e32 v40, v21
	v_mov_b32_e32 v39, v21
	v_mov_b32_e32 v38, v21
	v_mov_b32_e32 v45, v21
	v_mov_b32_e32 v44, v21
	v_mov_b32_e32 v43, v21
	v_mov_b32_e32 v42, v21
	v_mov_b32_e32 v49, v21
	v_mov_b32_e32 v48, v21
	v_mov_b32_e32 v47, v21
	v_mov_b32_e32 v46, v21
	s_cbranch_vccnz .LBB0_357
	s_add_u32 s24, s22, 0x10e00000
	s_addc_u32 s25, s23, 0
	s_lshl_b32 s26, s35, 1
	v_or_b32_e32 v156, s5, v154
	s_andn2_b32 s5, s5, 31
	s_add_u32 s2, s0, s5
	s_addc_u32 s3, s1, 0
	v_mov_b32_e32 v3, s34
	v_or_b32_e32 v2, s31, v154
	v_mov_b32_e32 v25, s3
	v_or_b32_e32 v24, s2, v154
	v_lshlrev_b64 v[2:3], 14, v[2:3]
	v_lshlrev_b64 v[24:25], 14, v[24:25]
	v_lshl_add_u64 v[2:3], s[24:25], 0, v[2:3]
	s_mov_b32 s27, s71
	v_lshl_add_u64 v[24:25], s[24:25], 0, v[24:25]
	v_lshl_add_u64 v[2:3], v[2:3], 0, s[26:27]
	v_lshlrev_b32_e32 v20, 4, v82
	v_mov_b32_e32 v21, v0
	v_lshl_add_u64 v[24:25], v[24:25], 0, s[26:27]
	v_lshl_add_u64 v[14:15], v[2:3], 0, v[20:21]
	v_lshl_add_u64 v[20:21], v[24:25], 0, v[20:21]
	v_lshl_add_u64 v[24:25], v[20:21], 0, s[52:53]
	s_mov_b32 s5, 0x41000
	global_load_dwordx4 v[2:5], v[14:15], off offset:2048
	global_load_dwordx4 v[6:9], v[14:15], off offset:2112
	global_load_dwordx4 v[10:13], v[14:15], off offset:2176
	s_nop 0
	global_load_dwordx4 v[14:17], v[14:15], off offset:2240
	s_nop 0
	global_load_dwordx4 v[114:117], v[24:25], off offset:192
	global_load_dwordx4 v[118:121], v[24:25], off offset:128
	global_load_dwordx4 v[122:125], v[24:25], off offset:64
	v_add_co_u32_e32 v24, vcc, s5, v20
	v_and_b32_e32 v19, 63, v1
	s_nop 0
	v_addc_co_u32_e32 v25, vcc, 0, v21, vcc
	global_load_dwordx4 v[126:129], v[24:25], off
	v_lshl_add_u64 v[24:25], v[20:21], 0, s[94:95]
	v_add_co_u32_e32 v20, vcc, s43, v20
	global_load_dwordx4 v[130:133], v[24:25], off offset:192
	global_load_dwordx4 v[134:137], v[24:25], off offset:128
	global_load_dwordx4 v[138:141], v[24:25], off offset:64
	v_addc_co_u32_e32 v21, vcc, 0, v21, vcc
	global_load_dwordx4 v[142:145], v[20:21], off
	v_or_b32_e32 v20, s2, v82
	v_mov_b32_e32 v21, s3
	v_lshlrev_b64 v[20:21], 14, v[20:21]
	v_lshl_add_u64 v[20:21], s[24:25], 0, v[20:21]
	v_lshlrev_b32_e32 v24, 4, v154
	v_mov_b32_e32 v25, v0
	v_lshl_add_u64 v[20:21], v[20:21], 0, s[26:27]
	v_lshl_add_u64 v[20:21], v[20:21], 0, v[24:25]
	s_mov_b32 s2, 0x71000
	v_add_co_u32_e32 v26, vcc, s2, v20
	s_mov_b32 s2, 0x61000
	s_nop 0
	v_addc_co_u32_e32 v27, vcc, 0, v21, vcc
	global_load_dwordx4 v[70:73], v[26:27], off offset:2048
	v_add_co_u32_e32 v26, vcc, s2, v20
	s_mov_b32 s2, 0x51000
	s_nop 0
	v_addc_co_u32_e32 v27, vcc, 0, v21, vcc
	global_load_dwordx4 v[78:81], v[26:27], off offset:2048
	v_add_co_u32_e32 v26, vcc, s2, v20
	s_mov_b32 s2, 0x31000
	s_nop 0
	v_addc_co_u32_e32 v27, vcc, 0, v21, vcc
	global_load_dwordx4 v[62:65], v[26:27], off offset:2048
	v_add_co_u32_e32 v26, vcc, s5, v20
	v_or_b32_e32 v146, s0, v82
	s_nop 0
	v_addc_co_u32_e32 v27, vcc, 0, v21, vcc
	global_load_dwordx4 v[74:77], v[26:27], off offset:2048
	v_add_co_u32_e32 v26, vcc, s2, v20
	s_mov_b32 s2, 0x21000
	s_nop 0
	v_addc_co_u32_e32 v27, vcc, 0, v21, vcc
	global_load_dwordx4 v[54:57], v[26:27], off offset:2048
	v_add_co_u32_e32 v26, vcc, s2, v20
	s_mov_b32 s2, 0x11000
	s_nop 0
	v_addc_co_u32_e32 v27, vcc, 0, v21, vcc
	global_load_dwordx4 v[66:69], v[26:27], off offset:2048
	v_add_co_u32_e32 v26, vcc, s2, v20
	s_lshl_b32 s2, s4, 13
	s_nop 0
	v_addc_co_u32_e32 v27, vcc, 0, v21, vcc
	v_add_co_u32_e32 v20, vcc, s43, v20
	global_load_dwordx4 v[50:53], v[26:27], off offset:2048
	s_nop 0
	v_addc_co_u32_e32 v21, vcc, 0, v21, vcc
	global_load_dwordx4 v[58:61], v[20:21], off offset:2048
	v_lshlrev_b32_e32 v21, 2, v19
	v_xor_b32_e32 v157, 64, v21
	v_xor_b32_e32 v158, 0x80, v21
	v_xor_b32_e32 v159, 0xc0, v21
	v_lshlrev_b32_e32 v21, 6, v154
	s_add_i32 s7, s2, 0
	v_mov_b32_e32 v147, s1
	v_mov_b32_e32 v149, s1
	v_or_b32_e32 v148, s0, v154
	v_cmp_lt_u32_e64 s[0:1], 15, v19
	v_lshlrev_b32_e32 v19, 10, v82
	v_and_b32_e32 v21, 0x300, v21
	v_lshlrev_b32_e32 v1, 3, v1
	v_lshlrev_b32_e32 v18, 3, v82
	v_lshlrev_b32_e32 v22, 3, v154
	v_lshl_add_u32 v20, v82, 8, s7
	v_cmp_ne_u32_e64 s[2:3], 1, v82
	v_cmp_eq_u32_e64 s[4:5], 2, v82
	v_add3_u32 v19, s7, v19, v21
	v_and_b32_e32 v1, 24, v1
	s_lshl_b32 s7, s6, 5
	v_mov_b32_e32 v160, 0
	s_waitcnt vmcnt(0) lgkmcnt(0)
	v_mov_b64_e32 v[82:83], v[138:139]
	v_mov_b64_e32 v[86:87], v[142:143]
	v_mov_b64_e32 v[90:91], v[134:135]
	v_mov_b64_e32 v[94:95], v[130:131]
	v_mov_b64_e32 v[102:103], v[126:127]
	v_mov_b64_e32 v[98:99], v[122:123]
	v_mov_b64_e32 v[106:107], v[118:119]
	v_mov_b64_e32 v[110:111], v[114:115]
	s_sub_i32 s70, s7, 32
	v_mov_b32_e32 v163, s6
	v_add_u32_e32 v161, v20, v24
	v_lshlrev_b32_e32 v150, 1, v22
	v_lshlrev_b32_e32 v152, 1, v18
	v_add_u32_e32 v162, v19, v1
	v_mov_b32_e32 v46, 0
	v_mov_b32_e32 v47, v160
	v_mov_b32_e32 v48, v160
	v_mov_b32_e32 v49, v160
	v_mov_b32_e32 v42, 0
	v_mov_b32_e32 v43, v160
	v_mov_b32_e32 v44, v160
	v_mov_b32_e32 v45, v160
	v_mov_b32_e32 v38, 0
	v_mov_b32_e32 v39, v160
	v_mov_b32_e32 v40, v160
	v_mov_b32_e32 v41, v160
	v_mov_b32_e32 v34, 0
	v_mov_b32_e32 v35, v160
	v_mov_b32_e32 v36, v160
	v_mov_b32_e32 v37, v160
	v_mov_b32_e32 v30, 0
	v_mov_b32_e32 v31, v160
	v_mov_b32_e32 v32, v160
	v_mov_b32_e32 v33, v160
	v_mov_b32_e32 v26, 0
	v_mov_b32_e32 v27, v160
	v_mov_b32_e32 v28, v160
	v_mov_b32_e32 v29, v160
	v_mov_b32_e32 v22, 0
	v_mov_b32_e32 v23, v160
	v_mov_b32_e32 v24, v160
	v_mov_b32_e32 v25, v160
	v_mov_b32_e32 v18, 0
	v_mov_b32_e32 v19, v160
	v_mov_b32_e32 v20, v160
	v_mov_b32_e32 v21, v160
	v_mov_b64_e32 v[88:89], v[144:145]
	v_mov_b64_e32 v[84:85], v[140:141]
	v_mov_b64_e32 v[92:93], v[136:137]
	v_mov_b64_e32 v[96:97], v[132:133]
	v_mov_b64_e32 v[104:105], v[128:129]
	v_mov_b64_e32 v[100:101], v[124:125]
	v_mov_b64_e32 v[108:109], v[120:121]
	v_mov_b64_e32 v[112:113], v[116:117]
; #define LAS __attribute__((address_space(3)))
; __device__ NOINL void sb_unit(unsigned char* ws, LAS unsigned char* lds, int unit, int wv) {
;     ...
;     SB_ISSUE((t0 + 14) >> 5);
;     ...
;         const int s0 = tile * 32;
; #pragma unroll
;         for (int i = 0; i < 8; ++i) *(LAS u32x4*)(vb + ((lane >> 4) + 4 * i) * 256 + (lane & 15) * 16) = vpf[i];
;         bf16x8 kcur[2][4];
; #pragma unroll
;         for (int a = 0; a < 2; ++a)
; #pragma unroll
;             for (int ks = 0; ks < 4; ++ks) kcur[a][ks] = kpf[a][ks];
;         if (tile > 0) SB_ISSUE(tile - 1);
.LBB0_362:
	v_subrev_co_u32_e32 v164, vcc, 1, v163
	s_and_b64 vcc, exec, vcc
	ds_write_b128 v161, v[58:61]
	ds_write_b128 v161, v[50:53] offset:1024
	ds_write_b128 v161, v[66:69] offset:2048
	ds_write_b128 v161, v[54:57] offset:3072
	ds_write_b128 v161, v[74:77] offset:4096
	ds_write_b128 v161, v[62:65] offset:5120
	ds_write_b128 v161, v[78:81] offset:6144
	ds_write_b128 v161, v[70:73] offset:7168
	s_cbranch_vccnz .LBB0_364
	v_lshl_add_u64 v[50:51], v[146:147], 0, s[70:71]
	v_lshlrev_b64 v[70:71], 14, v[50:51]
	v_lshl_add_u64 v[50:51], s[24:25], 0, v[70:71]
	s_mov_b32 s27, s71
	v_lshl_add_u64 v[50:51], v[50:51], 0, s[26:27]
	v_mov_b32_e32 v151, v0
	v_or_b32_e32 v52, 0x10000, v70
	v_mov_b32_e32 v53, v71
	v_lshl_add_u64 v[50:51], v[50:51], 0, v[150:151]
	v_lshl_add_u64 v[52:53], s[24:25], 0, v[52:53]
	v_add_co_u32_e32 v50, vcc, 0x1000, v50
	v_lshl_add_u64 v[52:53], v[52:53], 0, s[26:27]
	v_or_b32_e32 v54, 0x20000, v70
	v_mov_b32_e32 v55, v71
	v_addc_co_u32_e32 v51, vcc, 0, v51, vcc
	v_lshl_add_u64 v[52:53], v[52:53], 0, v[150:151]
	v_lshl_add_u64 v[54:55], s[24:25], 0, v[54:55]
	v_add_co_u32_e32 v52, vcc, 0x1000, v52
	v_lshl_add_u64 v[54:55], v[54:55], 0, s[26:27]
	v_or_b32_e32 v56, 0x30000, v70
	v_mov_b32_e32 v57, v71
	v_addc_co_u32_e32 v53, vcc, 0, v53, vcc
	v_lshl_add_u64 v[54:55], v[54:55], 0, v[150:151]
	v_lshl_add_u64 v[56:57], s[24:25], 0, v[56:57]
	v_add_co_u32_e32 v54, vcc, 0x1000, v54
	v_lshl_add_u64 v[56:57], v[56:57], 0, s[26:27]
	v_or_b32_e32 v62, 0x40000, v70
	v_mov_b32_e32 v63, v71
	v_addc_co_u32_e32 v55, vcc, 0, v55, vcc
	v_lshl_add_u64 v[56:57], v[56:57], 0, v[150:151]
	v_lshl_add_u64 v[62:63], s[24:25], 0, v[62:63]
	v_add_co_u32_e32 v56, vcc, 0x1000, v56
	v_lshl_add_u64 v[62:63], v[62:63], 0, s[26:27]
	v_or_b32_e32 v64, 0x50000, v70
	v_mov_b32_e32 v65, v71
	v_addc_co_u32_e32 v57, vcc, 0, v57, vcc
	v_lshl_add_u64 v[62:63], v[62:63], 0, v[150:151]
	v_lshl_add_u64 v[64:65], s[24:25], 0, v[64:65]
	v_add_co_u32_e32 v62, vcc, 0x1000, v62
	v_lshl_add_u64 v[64:65], v[64:65], 0, s[26:27]
	v_or_b32_e32 v72, 0x60000, v70
	v_mov_b32_e32 v73, v71
	v_addc_co_u32_e32 v63, vcc, 0, v63, vcc
	v_lshl_add_u64 v[64:65], v[64:65], 0, v[150:151]
	v_lshl_add_u64 v[72:73], s[24:25], 0, v[72:73]
	v_add_co_u32_e32 v64, vcc, 0x1000, v64
	v_lshl_add_u64 v[72:73], v[72:73], 0, s[26:27]
	v_or_b32_e32 v70, 0x70000, v70
	v_addc_co_u32_e32 v65, vcc, 0, v65, vcc
	v_lshl_add_u64 v[72:73], v[72:73], 0, v[150:151]
	v_lshl_add_u64 v[70:71], s[24:25], 0, v[70:71]
	v_lshl_add_u64 v[82:83], v[148:149], 0, s[70:71]
	v_add_co_u32_e32 v72, vcc, 0x1000, v72
	v_lshl_add_u64 v[70:71], v[70:71], 0, s[26:27]
	v_lshlrev_b64 v[82:83], 14, v[82:83]
	v_addc_co_u32_e32 v73, vcc, 0, v73, vcc
	v_lshl_add_u64 v[70:71], v[70:71], 0, v[150:151]
	v_lshl_add_u64 v[82:83], s[24:25], 0, v[82:83]
	v_add_co_u32_e32 v70, vcc, 0x1000, v70
	v_mov_b32_e32 v153, v0
	v_lshl_add_u64 v[82:83], v[82:83], 0, s[26:27]
	v_addc_co_u32_e32 v71, vcc, 0, v71, vcc
	v_lshl_add_u64 v[98:99], v[82:83], 0, v[152:153]
	v_add_co_u32_e32 v86, vcc, 0x1000, v98
	v_lshl_add_u64 v[94:95], v[98:99], 0, s[94:95]
	s_nop 0
	v_addc_co_u32_e32 v87, vcc, 0, v99, vcc
	v_add_co_u32_e32 v102, vcc, 0x41000, v98
	v_lshl_add_u64 v[110:111], v[98:99], 0, s[52:53]
	s_nop 0
	v_addc_co_u32_e32 v103, vcc, 0, v99, vcc
	global_load_dwordx4 v[58:61], v[50:51], off offset:2048
	s_nop 0
	global_load_dwordx4 v[50:53], v[52:53], off offset:2048
	s_nop 0
	global_load_dwordx4 v[66:69], v[54:55], off offset:2048
	s_nop 0
	global_load_dwordx4 v[54:57], v[56:57], off offset:2048
	s_nop 0
	global_load_dwordx4 v[74:77], v[62:63], off offset:2048
	s_nop 0
	global_load_dwordx4 v[62:65], v[64:65], off offset:2048
	s_nop 0
	global_load_dwordx4 v[78:81], v[72:73], off offset:2048
	s_nop 0
	global_load_dwordx4 v[70:73], v[70:71], off offset:2048
	s_nop 0
	global_load_dwordx4 v[82:85], v[94:95], off offset:64
	global_load_dwordx4 v[90:93], v[94:95], off offset:128
	s_nop 0
	global_load_dwordx4 v[86:89], v[86:87], off
	s_nop 0
	global_load_dwordx4 v[94:97], v[94:95], off offset:192
	s_nop 0
	global_load_dwordx4 v[98:101], v[110:111], off offset:64
	global_load_dwordx4 v[106:109], v[110:111], off offset:128
	s_nop 0
	global_load_dwordx4 v[102:105], v[102:103], off
	s_nop 0
	global_load_dwordx4 v[110:113], v[110:111], off offset:192

; #define PG8_STAGE(bufoff, gbase, voff) do { _Pragma("unroll") for (int _i = 0; _i < 2; ++_i) \
;         __builtin_amdgcn_global_load_lds((const unsigned*)((const char*)(gbase) + (voff)[_i]), (LAS unsigned*)(lds + (bufoff) + ldsw + _i * 8192), 16, 0, 0); } while (0)
; #define PG8_LDA(dst, b, h) do { _Pragma("unroll") for (int m = 0; m < 4; ++m) _Pragma("unroll") for (int k = 0; k < 2; ++k) dst[m][k] = *(const LAS bf16x8*)(lds + PG8_SA(b, h) + aoff + m * 2048 + k * 1024); } while (0)
; #define PG8_LDB(dst, b, h) do { _Pragma("unroll") for (int n = 0; n < 2; ++n) _Pragma("unroll") for (int k = 0; k < 2; ++k) dst[n][k] = *(const LAS bf16x8*)(lds + PG8_SB(b, h) + boff + n * 2048 + k * 1024); } while (0)
; #define PG8_MMA(ai, bj, At, Bt) do { __builtin_amdgcn_s_setprio(1); _Pragma("unroll") for (int m = 0; m < 4; ++m) _Pragma("unroll") for (int n = 0; n < 2; ++n) _Pragma("unroll") for (int k = 0; k < 2; ++k) \
;         acc[ai][bj][m][n] = __builtin_amdgcn_mfma_f32_16x16x32_bf16(Bt[n][k], At[m][k], acc[ai][bj][m][n], 0, 0, 0); __builtin_amdgcn_s_setprio(0); } while (0)
; #define PG8_WAIT_V(n) asm volatile("s_waitcnt vmcnt(" #n ")" ::: "memory")
; #define PG8_WAIT_L(n) asm volatile("s_waitcnt lgkmcnt(" #n ")" ::: "memory")
; #define PG8_BAR __builtin_amdgcn_s_barrier()
; #define PG8_SCHED __builtin_amdgcn_sched_barrier(0)
; template <class Epi, class Sched, bool AREMAP>
; __device__ __forceinline__ void gemm_phase(LAS unsigned char* lds, const Gemm g, const Sched& S, const Epi& E, int wv) {
;     ...
;             PG8_LDB(B0, 0, 0); PG8_SCHED; PG8_LDA(At, 0, 0); PG8_STAGE(PG8_SA(1, 1), a1 + hstepA, voffA);
;             PG8_WAIT_L(8); PG8_BAR; PG8_WAIT_L(0); PG8_MMA(0, 0, At, B0); PG8_BAR; PG8_SCHED;
;             PG8_LDB(B1, 0, 1); PG8_STAGE(PG8_SB(0, 0), b2, voffB);
;             PG8_BAR; PG8_WAIT_L(0); PG8_MMA(0, 1, At, B1); PG8_BAR;
;             PG8_LDA(At, 0, 1); PG8_STAGE(PG8_SA(0, 0), a2, voffA);
;             PG8_BAR; PG8_WAIT_L(0); PG8_MMA(1, 0, At, B0); PG8_BAR; PG8_SCHED;
;             PG8_STAGE(PG8_SB(0, 1), b2 + hstepB, voffB);
;             PG8_WAIT_V(6); PG8_BAR; PG8_MMA(1, 1, At, B1); PG8_BAR;
.LBB0_397:
	s_add_u32 s14, s2, 0xfffc0080
	s_addc_u32 s15, s3, -1
	s_add_i32 s38, 0, 0x10000
	v_add_u32_e32 v145, s38, v142
	ds_read_b128 v[146:149], v145
	ds_read_b128 v[150:153], v145 offset:1024
	ds_read_b128 v[154:157], v145 offset:2048
	ds_read_b128 v[158:161], v145 offset:3072
	s_cmp_eq_u32 s53, 12
	s_cselect_b32 s17, s11, s15
	s_cselect_b32 s16, s10, s14
	s_cselect_b32 s15, s7, s52
	s_cselect_b32 s14, s9, s47
	v_lshl_add_u64 v[186:187], s[2:3], 0, v[140:141]
	s_add_i32 m0, s5, 0xc000
	ds_read_b128 v[162:165], v144
	ds_read_b128 v[166:169], v144 offset:1024
	ds_read_b128 v[170:173], v144 offset:2048
	ds_read_b128 v[174:177], v144 offset:3072
	ds_read_b128 v[178:181], v144 offset:4096
	ds_read_b128 v[182:185], v144 offset:5120
	ds_read_b128 v[192:195], v144 offset:6144
	ds_read_b128 v[196:199], v144 offset:7168
	global_load_lds_dwordx4 v[186:187], off
	v_lshl_add_u64 v[186:187], s[2:3], 0, v[138:139]
	s_add_i32 m0, s5, 0xe000
	s_nop 0
	global_load_lds_dwordx4 v[186:187], off
	s_waitcnt lgkmcnt(8)
	s_barrier
	s_waitcnt lgkmcnt(0)
	s_setprio 1
	s_waitcnt lgkmcnt(0)
	v_mfma_f32_16x16x32_bf16 v[126:129], v[146:149], v[162:165], v[126:129]
	v_mfma_f32_16x16x32_bf16 v[122:125], v[154:157], v[162:165], v[122:125]
	v_mfma_f32_16x16x32_bf16 v[118:121], v[146:149], v[170:173], v[118:121]
	v_mfma_f32_16x16x32_bf16 v[114:117], v[154:157], v[170:173], v[114:117]
	v_mfma_f32_16x16x32_bf16 v[102:105], v[146:149], v[178:181], v[102:105]
	v_mfma_f32_16x16x32_bf16 v[98:101], v[154:157], v[178:181], v[98:101]
	v_mfma_f32_16x16x32_bf16 v[86:89], v[146:149], v[192:195], v[86:89]
	v_mfma_f32_16x16x32_bf16 v[82:85], v[154:157], v[192:195], v[82:85]
	v_mfma_f32_16x16x32_bf16 v[126:129], v[150:153], v[166:169], v[126:129]
	v_mfma_f32_16x16x32_bf16 v[122:125], v[158:161], v[166:169], v[122:125]
	v_mfma_f32_16x16x32_bf16 v[118:121], v[150:153], v[174:177], v[118:121]
	v_mfma_f32_16x16x32_bf16 v[114:117], v[158:161], v[174:177], v[114:117]
	v_mfma_f32_16x16x32_bf16 v[102:105], v[150:153], v[182:185], v[102:105]
	v_mfma_f32_16x16x32_bf16 v[98:101], v[158:161], v[182:185], v[98:101]
	v_mfma_f32_16x16x32_bf16 v[86:89], v[150:153], v[196:199], v[86:89]
	v_mfma_f32_16x16x32_bf16 v[82:85], v[158:161], v[196:199], v[82:85]
	s_setprio 0
	s_barrier
	s_add_i32 s39, 0, 0x14000
	s_add_i32 s38, s38, s26
	v_add_u32_e32 v145, s39, v142
	v_lshl_add_u64 v[186:187], s[14:15], 0, v[134:135]
	s_mov_b32 m0, s38
	ds_read_b128 v[200:203], v145
	ds_read_b128 v[204:207], v145 offset:1024
	ds_read_b128 v[208:211], v145 offset:2048
	ds_read_b128 v[212:215], v145 offset:3072
	global_load_lds_dwordx4 v[186:187], off
	v_lshl_add_u64 v[216:217], s[14:15], 0, v[130:131]
	s_add_i32 m0, s38, 0x2000
	s_nop 0
	global_load_lds_dwordx4 v[216:217], off
	s_barrier
	s_waitcnt lgkmcnt(0)
	s_setprio 1
	s_waitcnt lgkmcnt(0)
	v_mfma_f32_16x16x32_bf16 v[110:113], v[200:203], v[162:165], v[110:113]
	v_mfma_f32_16x16x32_bf16 v[106:109], v[208:211], v[162:165], v[106:109]
	v_mfma_f32_16x16x32_bf16 v[94:97], v[200:203], v[170:173], v[94:97]
	v_mfma_f32_16x16x32_bf16 v[90:93], v[208:211], v[170:173], v[90:93]
	v_mfma_f32_16x16x32_bf16 v[78:81], v[200:203], v[178:181], v[78:81]
	v_mfma_f32_16x16x32_bf16 v[74:77], v[208:211], v[178:181], v[74:77]
	v_mfma_f32_16x16x32_bf16 v[70:73], v[200:203], v[192:195], v[70:73]
	v_mfma_f32_16x16x32_bf16 v[66:69], v[208:211], v[192:195], v[66:69]
	v_mfma_f32_16x16x32_bf16 v[110:113], v[204:207], v[166:169], v[110:113]
	v_mfma_f32_16x16x32_bf16 v[106:109], v[212:215], v[166:169], v[106:109]
	v_mfma_f32_16x16x32_bf16 v[94:97], v[204:207], v[174:177], v[94:97]
	v_mfma_f32_16x16x32_bf16 v[90:93], v[212:215], v[174:177], v[90:93]
	v_mfma_f32_16x16x32_bf16 v[78:81], v[204:207], v[182:185], v[78:81]
	v_mfma_f32_16x16x32_bf16 v[74:77], v[212:215], v[182:185], v[74:77]
	v_mfma_f32_16x16x32_bf16 v[70:73], v[204:207], v[196:199], v[70:73]
	v_mfma_f32_16x16x32_bf16 v[66:69], v[212:215], v[196:199], v[66:69]
	s_setprio 0
	s_mov_b32 m0, s5
	v_lshl_add_u64 v[218:219], s[16:17], 0, v[136:137]
	s_barrier
	ds_read_b128 v[162:165], v144 offset:16384
	ds_read_b128 v[166:169], v144 offset:17408
	ds_read_b128 v[170:173], v144 offset:18432
	ds_read_b128 v[174:177], v144 offset:19456
	ds_read_b128 v[178:181], v144 offset:20480
	ds_read_b128 v[182:185], v144 offset:21504
	ds_read_b128 v[192:195], v144 offset:22528
	ds_read_b128 v[196:199], v144 offset:23552
	global_load_lds_dwordx4 v[218:219], off
	v_lshl_add_u64 v[220:221], s[16:17], 0, v[132:133]
	s_mov_b32 m0, s28
	s_nop 0
	global_load_lds_dwordx4 v[220:221], off
	s_barrier
	s_waitcnt lgkmcnt(0)
	s_setprio 1
	s_waitcnt lgkmcnt(0)
	v_mfma_f32_16x16x32_bf16 v[62:65], v[146:149], v[162:165], v[62:65]
	v_mfma_f32_16x16x32_bf16 v[58:61], v[154:157], v[162:165], v[58:61]
	v_mfma_f32_16x16x32_bf16 v[54:57], v[146:149], v[170:173], v[54:57]
	v_mfma_f32_16x16x32_bf16 v[50:53], v[154:157], v[170:173], v[50:53]
	v_mfma_f32_16x16x32_bf16 v[38:41], v[146:149], v[178:181], v[38:41]
	v_mfma_f32_16x16x32_bf16 v[34:37], v[154:157], v[178:181], v[34:37]
	v_mfma_f32_16x16x32_bf16 v[22:25], v[146:149], v[192:195], v[22:25]
	v_mfma_f32_16x16x32_bf16 v[18:21], v[154:157], v[192:195], v[18:21]
	v_mfma_f32_16x16x32_bf16 v[62:65], v[150:153], v[166:169], v[62:65]
	v_mfma_f32_16x16x32_bf16 v[58:61], v[158:161], v[166:169], v[58:61]
	v_mfma_f32_16x16x32_bf16 v[54:57], v[150:153], v[174:177], v[54:57]
	v_mfma_f32_16x16x32_bf16 v[50:53], v[158:161], v[174:177], v[50:53]
	v_mfma_f32_16x16x32_bf16 v[38:41], v[150:153], v[182:185], v[38:41]
	v_mfma_f32_16x16x32_bf16 v[34:37], v[158:161], v[182:185], v[34:37]
	v_mfma_f32_16x16x32_bf16 v[22:25], v[150:153], v[196:199], v[22:25]
	v_mfma_f32_16x16x32_bf16 v[18:21], v[158:161], v[196:199], v[18:21]
	s_setprio 0
	s_barrier
; #define PG8_STAGE(bufoff, gbase, voff) do { _Pragma("unroll") for (int _i = 0; _i < 2; ++_i) \
;         __builtin_amdgcn_global_load_lds((const unsigned*)((const char*)(gbase) + (voff)[_i]), (LAS unsigned*)(lds + (bufoff) + ldsw + _i * 8192), 16, 0, 0); } while (0)
; #define PG8_LDA(dst, b, h) do { _Pragma("unroll") for (int m = 0; m < 4; ++m) _Pragma("unroll") for (int k = 0; k < 2; ++k) dst[m][k] = *(const LAS bf16x8*)(lds + PG8_SA(b, h) + aoff + m * 2048 + k * 1024); } while (0)
; #define PG8_LDB(dst, b, h) do { _Pragma("unroll") for (int n = 0; n < 2; ++n) _Pragma("unroll") for (int k = 0; k < 2; ++k) dst[n][k] = *(const LAS bf16x8*)(lds + PG8_SB(b, h) + boff + n * 2048 + k * 1024); } while (0)
; #define PG8_MMA(ai, bj, At, Bt) do { __builtin_amdgcn_s_setprio(1); _Pragma("unroll") for (int m = 0; m < 4; ++m) _Pragma("unroll") for (int n = 0; n < 2; ++n) _Pragma("unroll") for (int k = 0; k < 2; ++k) \
;         acc[ai][bj][m][n] = __builtin_amdgcn_mfma_f32_16x16x32_bf16(Bt[n][k], At[m][k], acc[ai][bj][m][n], 0, 0, 0); __builtin_amdgcn_s_setprio(0); } while (0)
; #define PG8_WAIT_V(n) asm volatile("s_waitcnt vmcnt(" #n ")" ::: "memory")
; #define PG8_WAIT_L(n) asm volatile("s_waitcnt lgkmcnt(" #n ")" ::: "memory")
; #define PG8_BAR __builtin_amdgcn_s_barrier()
; #define PG8_SCHED __builtin_amdgcn_sched_barrier(0)
; template <class Epi, class Sched, bool AREMAP>
; __device__ __forceinline__ void gemm_phase(LAS unsigned char* lds, const Gemm g, const Sched& S, const Epi& E, int wv) {
;     ...
;             PG8_WAIT_V(6); PG8_BAR; PG8_MMA(1, 1, At, B1); PG8_BAR;
;             PG8_LDB(B0, 1, 0); PG8_SCHED; PG8_LDA(At, 1, 0); PG8_STAGE(PG8_SA(0, 1), a2 + hstepA, voffA);
;             PG8_WAIT_L(8); PG8_BAR; PG8_WAIT_L(0); PG8_MMA(0, 0, At, B0); PG8_BAR; PG8_SCHED;
;             PG8_LDB(B1, 1, 1); PG8_STAGE(PG8_SB(1, 0), b3, voffB);
;             PG8_BAR; PG8_WAIT_L(0); PG8_MMA(0, 1, At, B1); PG8_BAR;
;             PG8_LDA(At, 1, 1); PG8_STAGE(PG8_SA(1, 0), a3, voffA);
;             PG8_BAR; PG8_WAIT_L(0); PG8_MMA(1, 0, At, B0); PG8_BAR; PG8_SCHED;
	s_add_u32 s56, s14, 0x40000
	s_addc_u32 s57, s15, 0
	s_add_i32 s38, s39, s26
	v_lshl_add_u64 v[146:147], s[56:57], 0, v[134:135]
	s_mov_b32 m0, s38
	s_nop 0
	global_load_lds_dwordx4 v[146:147], off
	v_lshl_add_u64 v[146:147], s[56:57], 0, v[130:131]
	s_add_i32 m0, s38, 0x2000
	s_nop 0
	global_load_lds_dwordx4 v[146:147], off
	s_waitcnt vmcnt(6)
	s_barrier
	s_setprio 1
	v_mfma_f32_16x16x32_bf16 v[46:49], v[200:203], v[162:165], v[46:49]
	v_mfma_f32_16x16x32_bf16 v[42:45], v[208:211], v[162:165], v[42:45]
	v_mfma_f32_16x16x32_bf16 v[30:33], v[200:203], v[170:173], v[30:33]
	v_mfma_f32_16x16x32_bf16 v[26:29], v[208:211], v[170:173], v[26:29]
	v_mfma_f32_16x16x32_bf16 v[14:17], v[200:203], v[178:181], v[14:17]
	v_mfma_f32_16x16x32_bf16 v[10:13], v[208:211], v[178:181], v[10:13]
	v_mfma_f32_16x16x32_bf16 v[6:9], v[200:203], v[192:195], v[6:9]
	v_mfma_f32_16x16x32_bf16 v[2:5], v[208:211], v[192:195], v[2:5]
	v_mfma_f32_16x16x32_bf16 v[46:49], v[204:207], v[166:169], v[46:49]
	v_mfma_f32_16x16x32_bf16 v[42:45], v[212:215], v[166:169], v[42:45]
	v_mfma_f32_16x16x32_bf16 v[30:33], v[204:207], v[174:177], v[30:33]
	v_mfma_f32_16x16x32_bf16 v[26:29], v[212:215], v[174:177], v[26:29]
	v_mfma_f32_16x16x32_bf16 v[14:17], v[204:207], v[182:185], v[14:17]
	v_mfma_f32_16x16x32_bf16 v[10:13], v[212:215], v[182:185], v[10:13]
	v_mfma_f32_16x16x32_bf16 v[6:9], v[204:207], v[196:199], v[6:9]
	v_mfma_f32_16x16x32_bf16 v[2:5], v[212:215], v[196:199], v[2:5]
	s_setprio 0
	s_add_i32 s38, 0, 0x18000
	v_add_u32_e32 v145, s38, v142
	s_barrier
	ds_read_b128 v[146:149], v145
	ds_read_b128 v[150:153], v145 offset:1024
	ds_read_b128 v[154:157], v145 offset:2048
	ds_read_b128 v[158:161], v145 offset:3072
	s_add_u32 s16, s16, 0x40000
	s_addc_u32 s17, s17, 0
	s_mov_b32 m0, s29
	v_lshl_add_u64 v[200:201], s[16:17], 0, v[136:137]
	ds_read_b128 v[162:165], v144 offset:32768
	ds_read_b128 v[166:169], v144 offset:33792
	ds_read_b128 v[170:173], v144 offset:34816
	ds_read_b128 v[174:177], v144 offset:35840
	ds_read_b128 v[178:181], v144 offset:36864
	ds_read_b128 v[182:185], v144 offset:37888
	ds_read_b128 v[192:195], v144 offset:38912
	ds_read_b128 v[196:199], v144 offset:39936
	global_load_lds_dwordx4 v[200:201], off
	v_lshl_add_u64 v[200:201], s[16:17], 0, v[132:133]
	s_mov_b32 m0, s30
	s_nop 0
	global_load_lds_dwordx4 v[200:201], off
	s_waitcnt lgkmcnt(8)
	s_barrier
	s_waitcnt lgkmcnt(0)
	s_setprio 1
	s_waitcnt lgkmcnt(0)
	v_mfma_f32_16x16x32_bf16 v[126:129], v[146:149], v[162:165], v[126:129]
	v_mfma_f32_16x16x32_bf16 v[122:125], v[154:157], v[162:165], v[122:125]
	v_mfma_f32_16x16x32_bf16 v[118:121], v[146:149], v[170:173], v[118:121]
	v_mfma_f32_16x16x32_bf16 v[114:117], v[154:157], v[170:173], v[114:117]
	v_mfma_f32_16x16x32_bf16 v[102:105], v[146:149], v[178:181], v[102:105]
	v_mfma_f32_16x16x32_bf16 v[98:101], v[154:157], v[178:181], v[98:101]
	v_mfma_f32_16x16x32_bf16 v[86:89], v[146:149], v[192:195], v[86:89]
	v_mfma_f32_16x16x32_bf16 v[82:85], v[154:157], v[192:195], v[82:85]
	v_mfma_f32_16x16x32_bf16 v[126:129], v[150:153], v[166:169], v[126:129]
	v_mfma_f32_16x16x32_bf16 v[122:125], v[158:161], v[166:169], v[122:125]
	v_mfma_f32_16x16x32_bf16 v[118:121], v[150:153], v[174:177], v[118:121]
	v_mfma_f32_16x16x32_bf16 v[114:117], v[158:161], v[174:177], v[114:117]
	v_mfma_f32_16x16x32_bf16 v[102:105], v[150:153], v[182:185], v[102:105]
	v_mfma_f32_16x16x32_bf16 v[98:101], v[158:161], v[182:185], v[98:101]
	v_mfma_f32_16x16x32_bf16 v[86:89], v[150:153], v[196:199], v[86:89]
	v_mfma_f32_16x16x32_bf16 v[82:85], v[158:161], v[196:199], v[82:85]
	s_setprio 0
	s_barrier
	s_add_i32 s16, 0, 0x1c000
	s_add_i32 s17, s38, s26
	v_add_u32_e32 v145, s16, v142
	v_lshl_add_u64 v[186:187], v[186:187], 0, s[86:87]
	s_mov_b32 m0, s17
	ds_read_b128 v[200:203], v145
	ds_read_b128 v[204:207], v145 offset:1024
	ds_read_b128 v[208:211], v145 offset:2048
	ds_read_b128 v[212:215], v145 offset:3072
	global_load_lds_dwordx4 v[186:187], off
	v_lshl_add_u64 v[186:187], v[216:217], 0, s[86:87]
	s_add_i32 m0, s17, 0x2000
	s_nop 0
	global_load_lds_dwordx4 v[186:187], off
	s_barrier
	s_waitcnt lgkmcnt(0)
	s_setprio 1
	s_waitcnt lgkmcnt(0)
	v_mfma_f32_16x16x32_bf16 v[110:113], v[200:203], v[162:165], v[110:113]
	v_mfma_f32_16x16x32_bf16 v[106:109], v[208:211], v[162:165], v[106:109]
	v_mfma_f32_16x16x32_bf16 v[94:97], v[200:203], v[170:173], v[94:97]
	v_mfma_f32_16x16x32_bf16 v[90:93], v[208:211], v[170:173], v[90:93]
	v_mfma_f32_16x16x32_bf16 v[78:81], v[200:203], v[178:181], v[78:81]
	v_mfma_f32_16x16x32_bf16 v[74:77], v[208:211], v[178:181], v[74:77]
	v_mfma_f32_16x16x32_bf16 v[70:73], v[200:203], v[192:195], v[70:73]
	v_mfma_f32_16x16x32_bf16 v[66:69], v[208:211], v[192:195], v[66:69]
	v_mfma_f32_16x16x32_bf16 v[110:113], v[204:207], v[166:169], v[110:113]
	v_mfma_f32_16x16x32_bf16 v[106:109], v[212:215], v[166:169], v[106:109]
	v_mfma_f32_16x16x32_bf16 v[94:97], v[204:207], v[174:177], v[94:97]
	v_mfma_f32_16x16x32_bf16 v[90:93], v[212:215], v[174:177], v[90:93]
	v_mfma_f32_16x16x32_bf16 v[78:81], v[204:207], v[182:185], v[78:81]
	v_mfma_f32_16x16x32_bf16 v[74:77], v[212:215], v[182:185], v[74:77]
	v_mfma_f32_16x16x32_bf16 v[70:73], v[204:207], v[196:199], v[70:73]
	v_mfma_f32_16x16x32_bf16 v[66:69], v[212:215], v[196:199], v[66:69]
	s_setprio 0
	s_mov_b32 m0, s35
	v_lshl_add_u64 v[186:187], v[218:219], 0, s[86:87]
	s_barrier
	ds_read_b128 v[162:165], v144 offset:49152
	ds_read_b128 v[166:169], v144 offset:50176
	ds_read_b128 v[170:173], v144 offset:51200
	ds_read_b128 v[174:177], v144 offset:52224
	ds_read_b128 v[178:181], v144 offset:53248
	ds_read_b128 v[182:185], v144 offset:54272
	ds_read_b128 v[192:195], v144 offset:55296
	ds_read_b128 v[196:199], v144 offset:56320
	global_load_lds_dwordx4 v[186:187], off
	v_lshl_add_u64 v[186:187], v[220:221], 0, s[86:87]
	s_mov_b32 m0, s36
	s_nop 0
	global_load_lds_dwordx4 v[186:187], off
	s_barrier
; #define PG8_STAGE(bufoff, gbase, voff) do { _Pragma("unroll") for (int _i = 0; _i < 2; ++_i) \
;         __builtin_amdgcn_global_load_lds((const unsigned*)((const char*)(gbase) + (voff)[_i]), (LAS unsigned*)(lds + (bufoff) + ldsw + _i * 8192), 16, 0, 0); } while (0)
; #define PG8_MMA(ai, bj, At, Bt) do { __builtin_amdgcn_s_setprio(1); _Pragma("unroll") for (int m = 0; m < 4; ++m) _Pragma("unroll") for (int n = 0; n < 2; ++n) _Pragma("unroll") for (int k = 0; k < 2; ++k) \
;         acc[ai][bj][m][n] = __builtin_amdgcn_mfma_f32_16x16x32_bf16(Bt[n][k], At[m][k], acc[ai][bj][m][n], 0, 0, 0); __builtin_amdgcn_s_setprio(0); } while (0)
; #define PG8_WAIT_V(n) asm volatile("s_waitcnt vmcnt(" #n ")" ::: "memory")
; #define PG8_WAIT_L(n) asm volatile("s_waitcnt lgkmcnt(" #n ")" ::: "memory")
; #define PG8_BAR __builtin_amdgcn_s_barrier()
; #define PG8_SCHED __builtin_amdgcn_sched_barrier(0)
; template <class Epi, class Sched, bool AREMAP>
; __device__ __forceinline__ void gemm_phase(LAS unsigned char* lds, const Gemm g, const Sched& S, const Epi& E, int wv) {
;     ...
;             PG8_BAR; PG8_WAIT_L(0); PG8_MMA(1, 0, At, B0); PG8_BAR; PG8_SCHED;
;             PG8_STAGE(PG8_SB(1, 1), b3 + hstepB, voffB);
;             PG8_WAIT_V(6); PG8_BAR; PG8_MMA(1, 1, At, B1); PG8_BAR;
;         }
	s_waitcnt lgkmcnt(0)
	s_setprio 1
	s_waitcnt lgkmcnt(0)
	v_mfma_f32_16x16x32_bf16 v[62:65], v[146:149], v[162:165], v[62:65]
	v_mfma_f32_16x16x32_bf16 v[58:61], v[154:157], v[162:165], v[58:61]
	v_mfma_f32_16x16x32_bf16 v[54:57], v[146:149], v[170:173], v[54:57]
	v_mfma_f32_16x16x32_bf16 v[50:53], v[154:157], v[170:173], v[50:53]
	v_mfma_f32_16x16x32_bf16 v[38:41], v[146:149], v[178:181], v[38:41]
	v_mfma_f32_16x16x32_bf16 v[34:37], v[154:157], v[178:181], v[34:37]
	v_mfma_f32_16x16x32_bf16 v[22:25], v[146:149], v[192:195], v[22:25]
	v_mfma_f32_16x16x32_bf16 v[18:21], v[154:157], v[192:195], v[18:21]
	v_mfma_f32_16x16x32_bf16 v[62:65], v[150:153], v[166:169], v[62:65]
	v_mfma_f32_16x16x32_bf16 v[58:61], v[158:161], v[166:169], v[58:61]
	v_mfma_f32_16x16x32_bf16 v[54:57], v[150:153], v[174:177], v[54:57]
	v_mfma_f32_16x16x32_bf16 v[50:53], v[158:161], v[174:177], v[50:53]
	v_mfma_f32_16x16x32_bf16 v[38:41], v[150:153], v[182:185], v[38:41]
	v_mfma_f32_16x16x32_bf16 v[34:37], v[158:161], v[182:185], v[34:37]
	v_mfma_f32_16x16x32_bf16 v[22:25], v[150:153], v[196:199], v[22:25]
	v_mfma_f32_16x16x32_bf16 v[18:21], v[158:161], v[196:199], v[18:21]
	s_setprio 0
	s_barrier
	s_add_u32 s14, s14, 0x40080
	s_addc_u32 s15, s15, 0
	s_add_i32 s16, s16, s26
	v_lshl_add_u64 v[146:147], s[14:15], 0, v[134:135]
	s_mov_b32 m0, s16
	s_nop 0
	global_load_lds_dwordx4 v[146:147], off
	v_lshl_add_u64 v[146:147], s[14:15], 0, v[130:131]
	s_add_i32 m0, s16, 0x2000
	s_nop 0
	global_load_lds_dwordx4 v[146:147], off
	s_waitcnt vmcnt(6)
	s_barrier
	s_setprio 1
	v_mfma_f32_16x16x32_bf16 v[46:49], v[200:203], v[162:165], v[46:49]
	v_mfma_f32_16x16x32_bf16 v[42:45], v[208:211], v[162:165], v[42:45]
	v_mfma_f32_16x16x32_bf16 v[30:33], v[200:203], v[170:173], v[30:33]
	v_mfma_f32_16x16x32_bf16 v[26:29], v[208:211], v[170:173], v[26:29]
	v_mfma_f32_16x16x32_bf16 v[14:17], v[200:203], v[178:181], v[14:17]
	v_mfma_f32_16x16x32_bf16 v[10:13], v[208:211], v[178:181], v[10:13]
	v_mfma_f32_16x16x32_bf16 v[6:9], v[200:203], v[192:195], v[6:9]
	v_mfma_f32_16x16x32_bf16 v[2:5], v[208:211], v[192:195], v[2:5]
	v_mfma_f32_16x16x32_bf16 v[46:49], v[204:207], v[166:169], v[46:49]
	v_mfma_f32_16x16x32_bf16 v[42:45], v[212:215], v[166:169], v[42:45]
	v_mfma_f32_16x16x32_bf16 v[30:33], v[204:207], v[174:177], v[30:33]
	v_mfma_f32_16x16x32_bf16 v[26:29], v[212:215], v[174:177], v[26:29]
	v_mfma_f32_16x16x32_bf16 v[14:17], v[204:207], v[182:185], v[14:17]
	v_mfma_f32_16x16x32_bf16 v[10:13], v[212:215], v[182:185], v[10:13]
	v_mfma_f32_16x16x32_bf16 v[6:9], v[204:207], v[196:199], v[6:9]
	v_mfma_f32_16x16x32_bf16 v[2:5], v[212:215], v[196:199], v[2:5]
	s_setprio 0
	s_add_i32 s53, s53, 2
	s_add_u32 s47, s47, 0x100
	s_addc_u32 s52, s52, 0
	s_add_u32 s2, s2, 0x100
	s_addc_u32 s3, s3, 0
	s_cmp_gt_u32 s53, 13
	s_barrier
	s_cbranch_scc0 .LBB0_397
; __device__ __forceinline__ unsigned cvt_pk_bf16(float lo, float hi) { f32x2_t f = {lo, hi}; bf16x2_t v = __builtin_convertvector(f, bf16x2_t); return __builtin_bit_cast(unsigned, v); }
;     __device__ __forceinline__ void operator()(const f32x4 (&acc)[2][2][4][2], const Unit& u, int wr, int wc, int fr, int fq) const {
;         const int row0 = u.pm * BM + wr * 64 + fr; int colt = u.pn * BM; bf16_t* base = O;
;         if (split_cols) { const int t = colt / split_cols; base += (size_t)t * split_stride; colt -= t * split_cols; }
;         const int col0 = colt + wc * 32 + 8 * fq;
; #pragma unroll
;         for (int ai = 0; ai < 2; ++ai)
; #pragma unroll
;             for (int m = 0; m < 4; ++m) { bf16_t* rowp = base + (size_t)(row0 + ai * HALF + m * 16) * ldc + col0;
; #pragma unroll
;                 for (int bj = 0; bj < 2; ++bj) { const f32x4 v0 = acc[ai][bj][m][0], v1 = acc[ai][bj][m][1];
;                     u32x4 w; w.x = cvt_pk_bf16(v0[0], v0[1]); w.y = cvt_pk_bf16(v0[2], v0[3]); w.z = cvt_pk_bf16(v1[0], v1[1]); w.w = cvt_pk_bf16(v1[2], v1[3]);
;                     *(u32x4*)(rowp + bj * HALF) = w; } }
;     }
	s_ashr_i32 s2, s46, 31
	s_lshr_b32 s2, s2, 29
	s_add_i32 s2, s46, s2
	s_ashr_i32 s2, s2, 3
	s_ashr_i32 s3, s2, 31
	s_lshl_b32 s7, s46, 8
	s_lshl_b64 s[14:15], s[2:3], 27
	s_add_u32 s14, s31, s14
	s_addc_u32 s15, s34, s15
	s_lshl_b32 s2, s2, 11
	s_sub_i32 s2, s7, s2
	v_lshl_add_u32 v146, s4, 8, v1
	v_or_b32_e32 v148, s2, v143
	v_ashrrev_i32_e32 v149, 31, v148
	v_ashrrev_i32_e32 v147, 31, v146
	v_lshl_add_u64 v[148:149], v[148:149], 1, s[14:15]
	v_lshlrev_b64 v[150:151], 12, v[146:147]
	v_lshl_add_u64 v[150:151], v[148:149], 0, v[150:151]
	s_mov_b64 s[2:3], 0x80000
	v_cvt_pk_bf16_f32 v70, v70, v71
	v_cvt_pk_bf16_f32 v71, v72, v73
	v_cvt_pk_bf16_f32 v72, v66, v67
	v_lshl_add_u64 v[66:67], v[150:151], 0, s[2:3]
	s_mov_b32 s2, 0x80000
	v_cvt_pk_bf16_f32 v62, v62, v63
	v_cvt_pk_bf16_f32 v63, v64, v65
	v_cvt_pk_bf16_f32 v64, v58, v59
	v_add_co_u32_e32 v58, vcc, s2, v150
	v_cvt_pk_bf16_f32 v46, v46, v47
	v_cvt_pk_bf16_f32 v47, v48, v49
	v_cvt_pk_bf16_f32 v48, v42, v43
	v_cvt_pk_bf16_f32 v49, v44, v45
	s_mov_b64 s[2:3], 0x90000
	v_addc_co_u32_e32 v59, vcc, 0, v151, vcc
	global_store_dwordx4 v[66:67], v[46:49], off offset:256
	v_cvt_pk_bf16_f32 v30, v30, v31
	v_cvt_pk_bf16_f32 v31, v32, v33
	v_lshl_add_u64 v[46:47], v[150:151], 0, s[2:3]
	s_mov_b32 s2, 0x90000
	v_add_co_u32_e32 v48, vcc, s2, v150
	v_cvt_pk_bf16_f32 v32, v26, v27
	v_cvt_pk_bf16_f32 v33, v28, v29
	s_mov_b64 s[2:3], 0xa0000
	v_cvt_pk_bf16_f32 v110, v110, v111
	v_cvt_pk_bf16_f32 v111, v112, v113
	v_cvt_pk_bf16_f32 v112, v106, v107
	v_or_b32_e32 v106, 16, v146
	v_addc_co_u32_e32 v49, vcc, 0, v151, vcc
	global_store_dwordx4 v[46:47], v[30:33], off offset:256
	v_ashrrev_i32_e32 v107, 31, v106
	v_cvt_pk_bf16_f32 v94, v94, v95
	v_lshl_add_u64 v[30:31], v[150:151], 0, s[2:3]
	s_mov_b32 s2, 0xa0000
	v_cvt_pk_bf16_f32 v95, v96, v97
	v_cvt_pk_bf16_f32 v96, v90, v91
	v_or_b32_e32 v90, 32, v146
	v_add_co_u32_e32 v32, vcc, s2, v150
	v_cvt_pk_bf16_f32 v14, v14, v15
	v_cvt_pk_bf16_f32 v15, v16, v17
	v_cvt_pk_bf16_f32 v16, v10, v11
	v_cvt_pk_bf16_f32 v17, v12, v13
	s_mov_b64 s[2:3], 0xb0000
	v_cvt_pk_bf16_f32 v113, v108, v109
	v_lshlrev_b64 v[106:107], 12, v[106:107]
	v_ashrrev_i32_e32 v91, 31, v90
	v_cvt_pk_bf16_f32 v78, v78, v79
	v_cvt_pk_bf16_f32 v79, v80, v81
	v_cvt_pk_bf16_f32 v80, v74, v75
	v_or_b32_e32 v74, 48, v146
	v_addc_co_u32_e32 v33, vcc, 0, v151, vcc
	global_store_dwordx4 v[30:31], v[14:17], off offset:256
	global_store_dwordx4 v[150:151], v[110:113], off offset:256
	v_cvt_pk_bf16_f32 v97, v92, v93
	v_lshl_add_u64 v[14:15], v[150:151], 0, s[2:3]
	s_mov_b32 s2, 0xb0000
	v_lshl_add_u64 v[110:111], v[148:149], 0, v[106:107]
	v_lshlrev_b64 v[90:91], 12, v[90:91]
	v_ashrrev_i32_e32 v75, 31, v74
	v_add_co_u32_e32 v16, vcc, s2, v150
	global_store_dwordx4 v[110:111], v[94:97], off offset:256
	v_cvt_pk_bf16_f32 v81, v76, v77
	v_lshlrev_b64 v[74:75], 12, v[74:75]
	v_lshl_add_u64 v[94:95], v[148:149], 0, v[90:91]
	v_addc_co_u32_e32 v17, vcc, 0, v151, vcc
	v_cvt_pk_bf16_f32 v126, v126, v127
	v_cvt_pk_bf16_f32 v127, v128, v129
	v_cvt_pk_bf16_f32 v128, v122, v123
	v_cvt_pk_bf16_f32 v129, v124, v125
	v_cvt_pk_bf16_f32 v106, v118, v119
	v_cvt_pk_bf16_f32 v107, v120, v121
	v_cvt_pk_bf16_f32 v108, v114, v115
	v_cvt_pk_bf16_f32 v109, v116, v117
	v_cvt_pk_bf16_f32 v90, v102, v103
	v_cvt_pk_bf16_f32 v91, v104, v105
	v_cvt_pk_bf16_f32 v92, v98, v99
	v_cvt_pk_bf16_f32 v93, v100, v101
	global_store_dwordx4 v[94:95], v[78:81], off offset:256
	v_cvt_pk_bf16_f32 v76, v82, v83
	v_cvt_pk_bf16_f32 v77, v84, v85
	v_lshl_add_u64 v[78:79], v[148:149], 0, v[74:75]
	v_cvt_pk_bf16_f32 v74, v86, v87
	v_cvt_pk_bf16_f32 v75, v88, v89
	v_cvt_pk_bf16_f32 v73, v68, v69
	v_cvt_pk_bf16_f32 v65, v60, v61
	v_cvt_pk_bf16_f32 v42, v54, v55
	v_cvt_pk_bf16_f32 v43, v56, v57
	v_cvt_pk_bf16_f32 v44, v50, v51
	v_cvt_pk_bf16_f32 v45, v52, v53
	v_cvt_pk_bf16_f32 v26, v38, v39
	v_cvt_pk_bf16_f32 v27, v40, v41
	v_cvt_pk_bf16_f32 v28, v34, v35
	v_cvt_pk_bf16_f32 v29, v36, v37
	v_cvt_pk_bf16_f32 v10, v22, v23
	v_cvt_pk_bf16_f32 v11, v24, v25
	v_cvt_pk_bf16_f32 v12, v18, v19
	v_cvt_pk_bf16_f32 v13, v20, v21
	v_cvt_pk_bf16_f32 v6, v6, v7
	v_cvt_pk_bf16_f32 v7, v8, v9
	v_cvt_pk_bf16_f32 v8, v2, v3
	v_cvt_pk_bf16_f32 v9, v4, v5
	s_and_b64 vcc, exec, s[0:1]
	s_mov_b32 s46, s6
	s_mov_b32 s4, s8
	s_mov_b64 s[14:15], s[12:13]
	s_mov_b64 s[16:17], s[10:11]
	s_mov_b32 s39, 0xb2a5705f
	global_store_dwordx4 v[150:151], v[126:129], off
	global_store_dwordx4 v[110:111], v[106:109], off
	global_store_dwordx4 v[94:95], v[90:93], off
	global_store_dwordx4 v[78:79], v[74:77], off
	global_store_dwordx4 v[78:79], v[70:73], off offset:256
	global_store_dwordx4 v[58:59], v[62:65], off
	global_store_dwordx4 v[48:49], v[42:45], off
	global_store_dwordx4 v[32:33], v[26:29], off
	global_store_dwordx4 v[16:17], v[10:13], off
	global_store_dwordx4 v[14:15], v[6:9], off offset:256
	s_cbranch_vccz .LBB0_392
	s_waitcnt vmcnt(0)
	s_cmpk_gt_u32 s20, 0xff
	v_readlane_b32 s31, v254, 22
	v_readlane_b32 s33, v254, 23
	s_mov_b32 s41, 0xe020
	s_cbranch_scc1 .LBB0_401
	s_barrier

; #define PG8_STAGE(bufoff, gbase, voff) do { _Pragma("unroll") for (int _i = 0; _i < 2; ++_i) \
;         __builtin_amdgcn_global_load_lds((const unsigned*)((const char*)(gbase) + (voff)[_i]), (LAS unsigned*)(lds + (bufoff) + ldsw + _i * 8192), 16, 0, 0); } while (0)
; #define PG8_LDA(dst, b, h) do { _Pragma("unroll") for (int m = 0; m < 4; ++m) _Pragma("unroll") for (int k = 0; k < 2; ++k) dst[m][k] = *(const LAS bf16x8*)(lds + PG8_SA(b, h) + aoff + m * 2048 + k * 1024); } while (0)
; #define PG8_LDB(dst, b, h) do { _Pragma("unroll") for (int n = 0; n < 2; ++n) _Pragma("unroll") for (int k = 0; k < 2; ++k) dst[n][k] = *(const LAS bf16x8*)(lds + PG8_SB(b, h) + boff + n * 2048 + k * 1024); } while (0)
; #define PG8_MMA(ai, bj, At, Bt) do { __builtin_amdgcn_s_setprio(1); _Pragma("unroll") for (int m = 0; m < 4; ++m) _Pragma("unroll") for (int n = 0; n < 2; ++n) _Pragma("unroll") for (int k = 0; k < 2; ++k) \
;         acc[ai][bj][m][n] = __builtin_amdgcn_mfma_f32_16x16x32_bf16(Bt[n][k], At[m][k], acc[ai][bj][m][n], 0, 0, 0); __builtin_amdgcn_s_setprio(0); } while (0)
; #define PG8_WAIT_V(n) asm volatile("s_waitcnt vmcnt(" #n ")" ::: "memory")
; #define PG8_WAIT_L(n) asm volatile("s_waitcnt lgkmcnt(" #n ")" ::: "memory")
; #define PG8_BAR __builtin_amdgcn_s_barrier()
; #define PG8_SCHED __builtin_amdgcn_sched_barrier(0)
; template <class Epi, class Sched, bool AREMAP>
; __device__ __forceinline__ void gemm_phase(LAS unsigned char* lds, const Gemm g, const Sched& S, const Epi& E, int wv) {
;     ...
;             PG8_LDB(B0, 0, 0); PG8_SCHED; PG8_LDA(At, 0, 0); PG8_STAGE(PG8_SA(1, 1), a1 + hstepA, voffA);
;             PG8_WAIT_L(8); PG8_BAR; PG8_WAIT_L(0); PG8_MMA(0, 0, At, B0); PG8_BAR; PG8_SCHED;
;             PG8_LDB(B1, 0, 1); PG8_STAGE(PG8_SB(0, 0), b2, voffB);
;             PG8_BAR; PG8_WAIT_L(0); PG8_MMA(0, 1, At, B1); PG8_BAR;
;             PG8_LDA(At, 0, 1); PG8_STAGE(PG8_SA(0, 0), a2, voffA);
;             PG8_BAR; PG8_WAIT_L(0); PG8_MMA(1, 0, At, B0); PG8_BAR; PG8_SCHED;
;             PG8_STAGE(PG8_SB(0, 1), b2 + hstepB, voffB);
;             PG8_WAIT_V(6); PG8_BAR; PG8_MMA(1, 1, At, B1); PG8_BAR;
.LBB0_426:
	s_add_u32 s20, s18, 0xfff80080
	s_addc_u32 s21, s19, -1
	s_add_i32 s38, 0, 0x10000
	v_add_u32_e32 v142, s38, v186
	ds_read_b128 v[130:133], v142
	ds_read_b128 v[134:137], v142 offset:1024
	ds_read_b128 v[138:141], v142 offset:2048
	ds_read_b128 v[142:145], v142 offset:3072
	s_cmp_eq_u32 s46, 28
	s_cselect_b32 s23, s3, s21
	s_cselect_b32 s22, s5, s20
	s_cselect_b32 s21, s11, s37
	s_cselect_b32 s20, s13, s36
	v_lshl_add_u64 v[198:199], s[18:19], 0, v[172:173]
	s_add_i32 m0, s35, 0xc000
	ds_read_b128 v[146:149], v196
	ds_read_b128 v[150:153], v196 offset:1024
	ds_read_b128 v[154:157], v196 offset:2048
	ds_read_b128 v[158:161], v196 offset:3072
	ds_read_b128 v[174:177], v196 offset:4096
	ds_read_b128 v[178:181], v196 offset:5120
	ds_read_b128 v[182:185], v196 offset:6144
	ds_read_b128 v[192:195], v196 offset:7168
	global_load_lds_dwordx4 v[198:199], off
	v_lshl_add_u64 v[198:199], s[18:19], 0, v[170:171]
	s_add_i32 m0, s35, 0xe000
	s_nop 0
	global_load_lds_dwordx4 v[198:199], off
	s_waitcnt lgkmcnt(8)
	s_barrier
	s_waitcnt lgkmcnt(0)
	s_setprio 1
	s_waitcnt lgkmcnt(0)
	v_mfma_f32_16x16x32_bf16 v[126:129], v[130:133], v[146:149], v[126:129]
	v_mfma_f32_16x16x32_bf16 v[122:125], v[138:141], v[146:149], v[122:125]
	v_mfma_f32_16x16x32_bf16 v[110:113], v[130:133], v[154:157], v[110:113]
	v_mfma_f32_16x16x32_bf16 v[106:109], v[138:141], v[154:157], v[106:109]
	v_mfma_f32_16x16x32_bf16 v[94:97], v[130:133], v[174:177], v[94:97]
	v_mfma_f32_16x16x32_bf16 v[90:93], v[138:141], v[174:177], v[90:93]
	v_mfma_f32_16x16x32_bf16 v[78:81], v[130:133], v[182:185], v[78:81]
	v_mfma_f32_16x16x32_bf16 v[74:77], v[138:141], v[182:185], v[74:77]
	v_mfma_f32_16x16x32_bf16 v[126:129], v[134:137], v[150:153], v[126:129]
	v_mfma_f32_16x16x32_bf16 v[122:125], v[142:145], v[150:153], v[122:125]
	v_mfma_f32_16x16x32_bf16 v[110:113], v[134:137], v[158:161], v[110:113]
	v_mfma_f32_16x16x32_bf16 v[106:109], v[142:145], v[158:161], v[106:109]
	v_mfma_f32_16x16x32_bf16 v[94:97], v[134:137], v[178:181], v[94:97]
	v_mfma_f32_16x16x32_bf16 v[90:93], v[142:145], v[178:181], v[90:93]
	v_mfma_f32_16x16x32_bf16 v[78:81], v[134:137], v[192:195], v[78:81]
	v_mfma_f32_16x16x32_bf16 v[74:77], v[142:145], v[192:195], v[74:77]
	s_setprio 0
	s_barrier
	s_add_i32 s39, 0, 0x14000
	s_add_i32 s38, s38, s34
	v_add_u32_e32 v197, s39, v186
	v_lshl_add_u64 v[214:215], s[20:21], 0, v[164:165]
	s_mov_b32 m0, s38
	ds_read_b128 v[198:201], v197
	ds_read_b128 v[202:205], v197 offset:1024
	ds_read_b128 v[206:209], v197 offset:2048
	ds_read_b128 v[210:213], v197 offset:3072
	global_load_lds_dwordx4 v[214:215], off
	v_lshl_add_u64 v[216:217], s[20:21], 0, v[168:169]
	s_add_i32 m0, s38, 0x2000
	s_nop 0
	global_load_lds_dwordx4 v[216:217], off
	s_barrier
	s_waitcnt lgkmcnt(0)
	s_setprio 1
	s_waitcnt lgkmcnt(0)
	v_mfma_f32_16x16x32_bf16 v[118:121], v[198:201], v[146:149], v[118:121]
	v_mfma_f32_16x16x32_bf16 v[114:117], v[206:209], v[146:149], v[114:117]
	v_mfma_f32_16x16x32_bf16 v[102:105], v[198:201], v[154:157], v[102:105]
	v_mfma_f32_16x16x32_bf16 v[98:101], v[206:209], v[154:157], v[98:101]
	v_mfma_f32_16x16x32_bf16 v[86:89], v[198:201], v[174:177], v[86:89]
	v_mfma_f32_16x16x32_bf16 v[82:85], v[206:209], v[174:177], v[82:85]
	v_mfma_f32_16x16x32_bf16 v[70:73], v[198:201], v[182:185], v[70:73]
	v_mfma_f32_16x16x32_bf16 v[66:69], v[206:209], v[182:185], v[66:69]
	v_mfma_f32_16x16x32_bf16 v[118:121], v[202:205], v[150:153], v[118:121]
	v_mfma_f32_16x16x32_bf16 v[114:117], v[210:213], v[150:153], v[114:117]
	v_mfma_f32_16x16x32_bf16 v[102:105], v[202:205], v[158:161], v[102:105]
	v_mfma_f32_16x16x32_bf16 v[98:101], v[210:213], v[158:161], v[98:101]
	v_mfma_f32_16x16x32_bf16 v[86:89], v[202:205], v[178:181], v[86:89]
	v_mfma_f32_16x16x32_bf16 v[82:85], v[210:213], v[178:181], v[82:85]
	v_mfma_f32_16x16x32_bf16 v[70:73], v[202:205], v[192:195], v[70:73]
	v_mfma_f32_16x16x32_bf16 v[66:69], v[210:213], v[192:195], v[66:69]
	s_setprio 0
	s_mov_b32 m0, s35
	v_lshl_add_u64 v[218:219], s[22:23], 0, v[162:163]
	s_barrier
	ds_read_b128 v[146:149], v196 offset:16384
	ds_read_b128 v[150:153], v196 offset:17408
	ds_read_b128 v[154:157], v196 offset:18432
	ds_read_b128 v[158:161], v196 offset:19456
	ds_read_b128 v[174:177], v196 offset:20480
	ds_read_b128 v[178:181], v196 offset:21504
	ds_read_b128 v[182:185], v196 offset:22528
	ds_read_b128 v[192:195], v196 offset:23552
	global_load_lds_dwordx4 v[218:219], off
	v_lshl_add_u64 v[220:221], s[22:23], 0, v[166:167]
	s_mov_b32 m0, s41
	s_nop 0
	global_load_lds_dwordx4 v[220:221], off
	s_barrier
	s_waitcnt lgkmcnt(0)
	s_setprio 1
	s_waitcnt lgkmcnt(0)
	v_mfma_f32_16x16x32_bf16 v[62:65], v[130:133], v[146:149], v[62:65]
	v_mfma_f32_16x16x32_bf16 v[58:61], v[138:141], v[146:149], v[58:61]
	v_mfma_f32_16x16x32_bf16 v[46:49], v[130:133], v[154:157], v[46:49]
	v_mfma_f32_16x16x32_bf16 v[42:45], v[138:141], v[154:157], v[42:45]
	v_mfma_f32_16x16x32_bf16 v[30:33], v[130:133], v[174:177], v[30:33]
	v_mfma_f32_16x16x32_bf16 v[26:29], v[138:141], v[174:177], v[26:29]
	v_mfma_f32_16x16x32_bf16 v[14:17], v[130:133], v[182:185], v[14:17]
	v_mfma_f32_16x16x32_bf16 v[10:13], v[138:141], v[182:185], v[10:13]
	v_mfma_f32_16x16x32_bf16 v[62:65], v[134:137], v[150:153], v[62:65]
	v_mfma_f32_16x16x32_bf16 v[58:61], v[142:145], v[150:153], v[58:61]
	v_mfma_f32_16x16x32_bf16 v[46:49], v[134:137], v[158:161], v[46:49]
	v_mfma_f32_16x16x32_bf16 v[42:45], v[142:145], v[158:161], v[42:45]
	v_mfma_f32_16x16x32_bf16 v[30:33], v[134:137], v[178:181], v[30:33]
	v_mfma_f32_16x16x32_bf16 v[26:29], v[142:145], v[178:181], v[26:29]
	v_mfma_f32_16x16x32_bf16 v[14:17], v[134:137], v[192:195], v[14:17]
	v_mfma_f32_16x16x32_bf16 v[10:13], v[142:145], v[192:195], v[10:13]
	s_setprio 0
	s_barrier
; #define PG8_STAGE(bufoff, gbase, voff) do { _Pragma("unroll") for (int _i = 0; _i < 2; ++_i) \
;         __builtin_amdgcn_global_load_lds((const unsigned*)((const char*)(gbase) + (voff)[_i]), (LAS unsigned*)(lds + (bufoff) + ldsw + _i * 8192), 16, 0, 0); } while (0)
; #define PG8_LDA(dst, b, h) do { _Pragma("unroll") for (int m = 0; m < 4; ++m) _Pragma("unroll") for (int k = 0; k < 2; ++k) dst[m][k] = *(const LAS bf16x8*)(lds + PG8_SA(b, h) + aoff + m * 2048 + k * 1024); } while (0)
; #define PG8_LDB(dst, b, h) do { _Pragma("unroll") for (int n = 0; n < 2; ++n) _Pragma("unroll") for (int k = 0; k < 2; ++k) dst[n][k] = *(const LAS bf16x8*)(lds + PG8_SB(b, h) + boff + n * 2048 + k * 1024); } while (0)
; #define PG8_MMA(ai, bj, At, Bt) do { __builtin_amdgcn_s_setprio(1); _Pragma("unroll") for (int m = 0; m < 4; ++m) _Pragma("unroll") for (int n = 0; n < 2; ++n) _Pragma("unroll") for (int k = 0; k < 2; ++k) \
;         acc[ai][bj][m][n] = __builtin_amdgcn_mfma_f32_16x16x32_bf16(Bt[n][k], At[m][k], acc[ai][bj][m][n], 0, 0, 0); __builtin_amdgcn_s_setprio(0); } while (0)
; #define PG8_WAIT_V(n) asm volatile("s_waitcnt vmcnt(" #n ")" ::: "memory")
; #define PG8_WAIT_L(n) asm volatile("s_waitcnt lgkmcnt(" #n ")" ::: "memory")
; #define PG8_BAR __builtin_amdgcn_s_barrier()
; #define PG8_SCHED __builtin_amdgcn_sched_barrier(0)
; template <class Epi, class Sched, bool AREMAP>
; __device__ __forceinline__ void gemm_phase(LAS unsigned char* lds, const Gemm g, const Sched& S, const Epi& E, int wv) {
;     ...
;             PG8_WAIT_V(6); PG8_BAR; PG8_MMA(1, 1, At, B1); PG8_BAR;
;             PG8_LDB(B0, 1, 0); PG8_SCHED; PG8_LDA(At, 1, 0); PG8_STAGE(PG8_SA(0, 1), a2 + hstepA, voffA);
;             PG8_WAIT_L(8); PG8_BAR; PG8_WAIT_L(0); PG8_MMA(0, 0, At, B0); PG8_BAR; PG8_SCHED;
;             PG8_LDB(B1, 1, 1); PG8_STAGE(PG8_SB(1, 0), b3, voffB);
;             PG8_BAR; PG8_WAIT_L(0); PG8_MMA(0, 1, At, B1); PG8_BAR;
;             PG8_LDA(At, 1, 1); PG8_STAGE(PG8_SA(1, 0), a3, voffA);
;             PG8_BAR; PG8_WAIT_L(0); PG8_MMA(1, 0, At, B0); PG8_BAR; PG8_SCHED;
	s_add_u32 s66, s20, 0x80000
	s_addc_u32 s67, s21, 0
	s_add_i32 s38, s39, s34
	v_lshl_add_u64 v[130:131], s[66:67], 0, v[164:165]
	s_mov_b32 m0, s38
	s_nop 0
	global_load_lds_dwordx4 v[130:131], off
	v_lshl_add_u64 v[130:131], s[66:67], 0, v[168:169]
	s_add_i32 m0, s38, 0x2000
	s_nop 0
	global_load_lds_dwordx4 v[130:131], off
	s_waitcnt vmcnt(6)
	s_barrier
	s_setprio 1
	v_mfma_f32_16x16x32_bf16 v[54:57], v[198:201], v[146:149], v[54:57]
	v_mfma_f32_16x16x32_bf16 v[50:53], v[206:209], v[146:149], v[50:53]
	v_mfma_f32_16x16x32_bf16 v[38:41], v[198:201], v[154:157], v[38:41]
	v_mfma_f32_16x16x32_bf16 v[34:37], v[206:209], v[154:157], v[34:37]
	v_mfma_f32_16x16x32_bf16 v[22:25], v[198:201], v[174:177], v[22:25]
	v_mfma_f32_16x16x32_bf16 v[18:21], v[206:209], v[174:177], v[18:21]
	v_mfma_f32_16x16x32_bf16 v[6:9], v[198:201], v[182:185], v[6:9]
	v_mfma_f32_16x16x32_bf16 v[2:5], v[206:209], v[182:185], v[2:5]
	v_mfma_f32_16x16x32_bf16 v[54:57], v[202:205], v[150:153], v[54:57]
	v_mfma_f32_16x16x32_bf16 v[50:53], v[210:213], v[150:153], v[50:53]
	v_mfma_f32_16x16x32_bf16 v[38:41], v[202:205], v[158:161], v[38:41]
	v_mfma_f32_16x16x32_bf16 v[34:37], v[210:213], v[158:161], v[34:37]
	v_mfma_f32_16x16x32_bf16 v[22:25], v[202:205], v[178:181], v[22:25]
	v_mfma_f32_16x16x32_bf16 v[18:21], v[210:213], v[178:181], v[18:21]
	v_mfma_f32_16x16x32_bf16 v[6:9], v[202:205], v[192:195], v[6:9]
	v_mfma_f32_16x16x32_bf16 v[2:5], v[210:213], v[192:195], v[2:5]
	s_setprio 0
	s_add_i32 s38, 0, 0x18000
	v_add_u32_e32 v142, s38, v186
	s_barrier
	ds_read_b128 v[130:133], v142
	ds_read_b128 v[134:137], v142 offset:1024
	ds_read_b128 v[138:141], v142 offset:2048
	ds_read_b128 v[142:145], v142 offset:3072
	s_add_u32 s22, s22, 0x80000
	s_addc_u32 s23, s23, 0
	s_mov_b32 m0, s52
	v_lshl_add_u64 v[198:199], s[22:23], 0, v[162:163]
	ds_read_b128 v[146:149], v196 offset:32768
	ds_read_b128 v[150:153], v196 offset:33792
	ds_read_b128 v[154:157], v196 offset:34816
	ds_read_b128 v[158:161], v196 offset:35840
	ds_read_b128 v[174:177], v196 offset:36864
	ds_read_b128 v[178:181], v196 offset:37888
	ds_read_b128 v[182:185], v196 offset:38912
	ds_read_b128 v[192:195], v196 offset:39936
	global_load_lds_dwordx4 v[198:199], off
	v_lshl_add_u64 v[198:199], s[22:23], 0, v[166:167]
	s_mov_b32 m0, s53
	s_nop 0
	global_load_lds_dwordx4 v[198:199], off
	s_waitcnt lgkmcnt(8)
	s_barrier
	s_waitcnt lgkmcnt(0)
	s_setprio 1
	s_waitcnt lgkmcnt(0)
	v_mfma_f32_16x16x32_bf16 v[126:129], v[130:133], v[146:149], v[126:129]
	v_mfma_f32_16x16x32_bf16 v[122:125], v[138:141], v[146:149], v[122:125]
	v_mfma_f32_16x16x32_bf16 v[110:113], v[130:133], v[154:157], v[110:113]
	v_mfma_f32_16x16x32_bf16 v[106:109], v[138:141], v[154:157], v[106:109]
	v_mfma_f32_16x16x32_bf16 v[94:97], v[130:133], v[174:177], v[94:97]
	v_mfma_f32_16x16x32_bf16 v[90:93], v[138:141], v[174:177], v[90:93]
	v_mfma_f32_16x16x32_bf16 v[78:81], v[130:133], v[182:185], v[78:81]
	v_mfma_f32_16x16x32_bf16 v[74:77], v[138:141], v[182:185], v[74:77]
	v_mfma_f32_16x16x32_bf16 v[126:129], v[134:137], v[150:153], v[126:129]
	v_mfma_f32_16x16x32_bf16 v[122:125], v[142:145], v[150:153], v[122:125]
	v_mfma_f32_16x16x32_bf16 v[110:113], v[134:137], v[158:161], v[110:113]
	v_mfma_f32_16x16x32_bf16 v[106:109], v[142:145], v[158:161], v[106:109]
	v_mfma_f32_16x16x32_bf16 v[94:97], v[134:137], v[178:181], v[94:97]
	v_mfma_f32_16x16x32_bf16 v[90:93], v[142:145], v[178:181], v[90:93]
	v_mfma_f32_16x16x32_bf16 v[78:81], v[134:137], v[192:195], v[78:81]
	v_mfma_f32_16x16x32_bf16 v[74:77], v[142:145], v[192:195], v[74:77]
	s_setprio 0
	s_barrier
	s_add_i32 s22, 0, 0x1c000
	s_add_i32 s23, s38, s34
	v_add_u32_e32 v197, s22, v186
	v_lshl_add_u64 v[214:215], v[214:215], 0, s[86:87]
	s_mov_b32 m0, s23
	ds_read_b128 v[198:201], v197
	ds_read_b128 v[202:205], v197 offset:1024
	ds_read_b128 v[206:209], v197 offset:2048
	ds_read_b128 v[210:213], v197 offset:3072
	global_load_lds_dwordx4 v[214:215], off
	v_lshl_add_u64 v[214:215], v[216:217], 0, s[86:87]
	s_add_i32 m0, s23, 0x2000
	s_nop 0
	global_load_lds_dwordx4 v[214:215], off
	s_barrier
	s_waitcnt lgkmcnt(0)
	s_setprio 1
	s_waitcnt lgkmcnt(0)
	v_mfma_f32_16x16x32_bf16 v[118:121], v[198:201], v[146:149], v[118:121]
	v_mfma_f32_16x16x32_bf16 v[114:117], v[206:209], v[146:149], v[114:117]
	v_mfma_f32_16x16x32_bf16 v[102:105], v[198:201], v[154:157], v[102:105]
	v_mfma_f32_16x16x32_bf16 v[98:101], v[206:209], v[154:157], v[98:101]
	v_mfma_f32_16x16x32_bf16 v[86:89], v[198:201], v[174:177], v[86:89]
	v_mfma_f32_16x16x32_bf16 v[82:85], v[206:209], v[174:177], v[82:85]
	v_mfma_f32_16x16x32_bf16 v[70:73], v[198:201], v[182:185], v[70:73]
	v_mfma_f32_16x16x32_bf16 v[66:69], v[206:209], v[182:185], v[66:69]
	v_mfma_f32_16x16x32_bf16 v[118:121], v[202:205], v[150:153], v[118:121]
	v_mfma_f32_16x16x32_bf16 v[114:117], v[210:213], v[150:153], v[114:117]
	v_mfma_f32_16x16x32_bf16 v[102:105], v[202:205], v[158:161], v[102:105]
	v_mfma_f32_16x16x32_bf16 v[98:101], v[210:213], v[158:161], v[98:101]
	v_mfma_f32_16x16x32_bf16 v[86:89], v[202:205], v[178:181], v[86:89]
	v_mfma_f32_16x16x32_bf16 v[82:85], v[210:213], v[178:181], v[82:85]
	v_mfma_f32_16x16x32_bf16 v[70:73], v[202:205], v[192:195], v[70:73]
	v_mfma_f32_16x16x32_bf16 v[66:69], v[210:213], v[192:195], v[66:69]
	s_setprio 0
	s_mov_b32 m0, s57
	v_lshl_add_u64 v[214:215], v[218:219], 0, s[86:87]
	s_barrier
; #define PG8_STAGE(bufoff, gbase, voff) do { _Pragma("unroll") for (int _i = 0; _i < 2; ++_i) \
;         __builtin_amdgcn_global_load_lds((const unsigned*)((const char*)(gbase) + (voff)[_i]), (LAS unsigned*)(lds + (bufoff) + ldsw + _i * 8192), 16, 0, 0); } while (0)
; #define PG8_MMA(ai, bj, At, Bt) do { __builtin_amdgcn_s_setprio(1); _Pragma("unroll") for (int m = 0; m < 4; ++m) _Pragma("unroll") for (int n = 0; n < 2; ++n) _Pragma("unroll") for (int k = 0; k < 2; ++k) \
;         acc[ai][bj][m][n] = __builtin_amdgcn_mfma_f32_16x16x32_bf16(Bt[n][k], At[m][k], acc[ai][bj][m][n], 0, 0, 0); __builtin_amdgcn_s_setprio(0); } while (0)
; #define PG8_WAIT_V(n) asm volatile("s_waitcnt vmcnt(" #n ")" ::: "memory")
; #define PG8_WAIT_L(n) asm volatile("s_waitcnt lgkmcnt(" #n ")" ::: "memory")
; #define PG8_BAR __builtin_amdgcn_s_barrier()
; #define PG8_SCHED __builtin_amdgcn_sched_barrier(0)
; template <class Epi, class Sched, bool AREMAP>
; __device__ __forceinline__ void gemm_phase(LAS unsigned char* lds, const Gemm g, const Sched& S, const Epi& E, int wv) {
;     ...
;             PG8_BAR; PG8_WAIT_L(0); PG8_MMA(1, 0, At, B0); PG8_BAR; PG8_SCHED;
;             PG8_STAGE(PG8_SB(1, 1), b3 + hstepB, voffB);
;             PG8_WAIT_V(6); PG8_BAR; PG8_MMA(1, 1, At, B1); PG8_BAR;
;         }
;     __device__ __forceinline__ void operator()(const f32x4 (&acc)[2][2][4][2], const Unit& u, int wr, int wc, int fr, int fq) const {
;     ...
;                 u32x4 y[2][2], pr[2][2];
; #pragma unroll
;                 for (int mm = 0; mm < 2; ++mm)
; #pragma unroll
;                     for (int bj = 0; bj < 2; ++bj) { const int m = mp * 2 + mm; const size_t off = (size_t)(row0 + ai * HALF + m * 16) * DM + col0;
;                         y[mm][bj] = *(const u32x4*)(yb + off + bj * HALF);
;                         const int slot = (ai * 4 + m) * 2 + bj;
;                         pr[mm][bj] = (u32x4){0u, 0u, 0u, 0u};
;                         if (b > 0) pr[mm][bj] = sc[(size_t)slot * NTHR]; }
	ds_read_b128 v[146:149], v196 offset:49152
	ds_read_b128 v[150:153], v196 offset:50176
	ds_read_b128 v[154:157], v196 offset:51200
	ds_read_b128 v[158:161], v196 offset:52224
	ds_read_b128 v[174:177], v196 offset:53248
	ds_read_b128 v[178:181], v196 offset:54272
	ds_read_b128 v[182:185], v196 offset:55296
	ds_read_b128 v[192:195], v196 offset:56320
	global_load_lds_dwordx4 v[214:215], off
	v_lshl_add_u64 v[214:215], v[220:221], 0, s[86:87]
	s_mov_b32 m0, s62
	s_nop 0
	global_load_lds_dwordx4 v[214:215], off
	s_barrier
	s_waitcnt lgkmcnt(0)
	s_setprio 1
	s_waitcnt lgkmcnt(0)
	v_mfma_f32_16x16x32_bf16 v[62:65], v[130:133], v[146:149], v[62:65]
	v_mfma_f32_16x16x32_bf16 v[58:61], v[138:141], v[146:149], v[58:61]
	v_mfma_f32_16x16x32_bf16 v[46:49], v[130:133], v[154:157], v[46:49]
	v_mfma_f32_16x16x32_bf16 v[42:45], v[138:141], v[154:157], v[42:45]
	v_mfma_f32_16x16x32_bf16 v[30:33], v[130:133], v[174:177], v[30:33]
	v_mfma_f32_16x16x32_bf16 v[26:29], v[138:141], v[174:177], v[26:29]
	v_mfma_f32_16x16x32_bf16 v[14:17], v[130:133], v[182:185], v[14:17]
	v_mfma_f32_16x16x32_bf16 v[10:13], v[138:141], v[182:185], v[10:13]
	v_mfma_f32_16x16x32_bf16 v[62:65], v[134:137], v[150:153], v[62:65]
	v_mfma_f32_16x16x32_bf16 v[58:61], v[142:145], v[150:153], v[58:61]
	v_mfma_f32_16x16x32_bf16 v[46:49], v[134:137], v[158:161], v[46:49]
	v_mfma_f32_16x16x32_bf16 v[42:45], v[142:145], v[158:161], v[42:45]
	v_mfma_f32_16x16x32_bf16 v[30:33], v[134:137], v[178:181], v[30:33]
	v_mfma_f32_16x16x32_bf16 v[26:29], v[142:145], v[178:181], v[26:29]
	v_mfma_f32_16x16x32_bf16 v[14:17], v[134:137], v[192:195], v[14:17]
	v_mfma_f32_16x16x32_bf16 v[10:13], v[142:145], v[192:195], v[10:13]
	s_setprio 0
	s_barrier
	s_add_u32 s20, s20, 0x80080
	s_addc_u32 s21, s21, 0
	s_add_i32 s22, s22, s34
	v_lshl_add_u64 v[130:131], s[20:21], 0, v[164:165]
	s_mov_b32 m0, s22
	s_nop 0
	global_load_lds_dwordx4 v[130:131], off
	v_lshl_add_u64 v[130:131], s[20:21], 0, v[168:169]
	s_add_i32 m0, s22, 0x2000
	s_nop 0
	global_load_lds_dwordx4 v[130:131], off
	s_waitcnt vmcnt(6)
	s_barrier
	s_setprio 1
	v_mfma_f32_16x16x32_bf16 v[54:57], v[198:201], v[146:149], v[54:57]
	v_mfma_f32_16x16x32_bf16 v[50:53], v[206:209], v[146:149], v[50:53]
	v_mfma_f32_16x16x32_bf16 v[38:41], v[198:201], v[154:157], v[38:41]
	v_mfma_f32_16x16x32_bf16 v[34:37], v[206:209], v[154:157], v[34:37]
	v_mfma_f32_16x16x32_bf16 v[22:25], v[198:201], v[174:177], v[22:25]
	v_mfma_f32_16x16x32_bf16 v[18:21], v[206:209], v[174:177], v[18:21]
	v_mfma_f32_16x16x32_bf16 v[6:9], v[198:201], v[182:185], v[6:9]
	v_mfma_f32_16x16x32_bf16 v[2:5], v[206:209], v[182:185], v[2:5]
	v_mfma_f32_16x16x32_bf16 v[54:57], v[202:205], v[150:153], v[54:57]
	v_mfma_f32_16x16x32_bf16 v[50:53], v[210:213], v[150:153], v[50:53]
	v_mfma_f32_16x16x32_bf16 v[38:41], v[202:205], v[158:161], v[38:41]
	v_mfma_f32_16x16x32_bf16 v[34:37], v[210:213], v[158:161], v[34:37]
	v_mfma_f32_16x16x32_bf16 v[22:25], v[202:205], v[178:181], v[22:25]
	v_mfma_f32_16x16x32_bf16 v[18:21], v[210:213], v[178:181], v[18:21]
	v_mfma_f32_16x16x32_bf16 v[6:9], v[202:205], v[192:195], v[6:9]
	v_mfma_f32_16x16x32_bf16 v[2:5], v[210:213], v[192:195], v[2:5]
	s_setprio 0
	s_add_i32 s46, s46, 2
	s_add_u32 s36, s36, 0x100
	s_addc_u32 s37, s37, 0
	s_add_u32 s18, s18, 0x100
	s_addc_u32 s19, s19, 0
	s_cmp_gt_u32 s46, 29
	s_barrier
	s_cbranch_scc0 .LBB0_426
	s_ashr_i32 s18, s4, 3
	v_lshl_add_u32 v178, s2, 8, v1
	s_lshl_b32 s2, s4, 8
	s_and_b32 s2, s2, 0x700
	s_ashr_i32 s19, s18, 31
	v_or_b32_e32 v132, s2, v187
	s_lshl_b64 s[2:3], s[18:19], 27
	s_add_u32 s2, s55, s2
	s_addc_u32 s3, s56, s3
	v_mov_b32_e32 v130, v236
	v_lshlrev_b32_e32 v176, 1, v132
	v_mov_b32_e32 v177, v0
	v_ashrrev_i32_e32 v179, 31, v178
	v_lshl_add_u64 v[180:181], s[2:3], 0, v[176:177]
	v_ashrrev_i32_e32 v131, 31, v130
	v_lshlrev_b64 v[184:185], 12, v[178:179]
	v_lshl_add_u64 v[174:175], v[130:131], 4, s[6:7]
	v_lshl_add_u64 v[130:131], v[180:181], 0, v[184:185]
	global_load_dwordx4 v[154:157], v[130:131], off
	s_cmp_gt_i32 s18, 0
	s_cselect_b64 s[2:3], -1, 0
	s_cmp_lt_i32 s18, 1
	s_cbranch_scc1 .LBB0_429
	global_load_dwordx4 v[158:161], v[174:175], off
	s_branch .LBB0_430

;     __device__ __forceinline__ void operator()(const f32x4 (&acc)[2][2][4][2], const Unit& u, int wr, int wc, int fr, int fq) const {
;     ...
;                 u32x4 y[2][2], pr[2][2];
; #pragma unroll
;                 for (int mm = 0; mm < 2; ++mm)
; #pragma unroll
;                     for (int bj = 0; bj < 2; ++bj) { const int m = mp * 2 + mm; const size_t off = (size_t)(row0 + ai * HALF + m * 16) * DM + col0;
;                         y[mm][bj] = *(const u32x4*)(yb + off + bj * HALF);
;                         const int slot = (ai * 4 + m) * 2 + bj;
;                         pr[mm][bj] = (u32x4){0u, 0u, 0u, 0u};
;                         if (b > 0) pr[mm][bj] = sc[(size_t)slot * NTHR]; }
.LBB0_430:
	global_load_dwordx4 v[146:149], v[130:131], off offset:256
	v_cndmask_b32_e64 v130, 0, 1, s[2:3]
	v_mov_b32_e32 v138, 0
	v_cmp_ne_u32_e64 s[4:5], 1, v130
	s_andn2_b64 vcc, exec, s[2:3]
	v_mov_b32_e32 v150, 0
	v_mov_b32_e32 v151, 0
	v_mov_b32_e32 v152, 0
	v_mov_b32_e32 v153, 0
	s_cbranch_vccnz .LBB0_432
	v_add_co_u32_e32 v130, vcc, 0x2000, v174
	s_nop 1
	v_addc_co_u32_e32 v131, vcc, 0, v175, vcc
	global_load_dwordx4 v[150:153], v[130:131], off
.LBB0_432:
	v_or_b32_e32 v130, 16, v178
	v_ashrrev_i32_e32 v131, 31, v130
	v_lshlrev_b64 v[182:183], 12, v[130:131]
	v_lshl_add_u64 v[130:131], v[180:181], 0, v[182:183]
	global_load_dwordx4 v[142:145], v[130:131], off
	s_and_b64 vcc, exec, s[4:5]
	v_mov_b32_e32 v139, 0
	v_mov_b32_e32 v140, 0
	v_mov_b32_e32 v141, 0
	s_mov_b32 s39, 0xb2a5705f
	s_mov_b32 s38, 0x42ce8ed0
	s_cbranch_vccnz .LBB0_434
	v_add_co_u32_e32 v132, vcc, 0x4000, v174
	s_nop 1
	v_addc_co_u32_e32 v133, vcc, 0, v175, vcc
	global_load_dwordx4 v[138:141], v[132:133], off
.LBB0_434:
	s_nop 0
	global_load_dwordx4 v[130:133], v[130:131], off offset:256
	s_and_b64 vcc, exec, s[4:5]
	s_cbranch_vccnz .LBB0_436
	v_add_co_u32_e32 v134, vcc, 0x6000, v174
	s_nop 1
	v_addc_co_u32_e32 v135, vcc, 0, v175, vcc
	global_load_dwordx4 v[134:137], v[134:135], off
	s_branch .LBB0_437

; __device__ __forceinline__ unsigned cvt_pk_bf16(float lo, float hi) { f32x2_t f = {lo, hi}; bf16x2_t v = __builtin_convertvector(f, bf16x2_t); return __builtin_bit_cast(unsigned, v); }
; __device__ __forceinline__ float bflo(unsigned w) { return __uint_as_float(w << 16); }
; __device__ __forceinline__ float bfhi(unsigned w) { return __uint_as_float(w & 0xffff0000u); }
; __device__ __forceinline__ float sigmoidf_(float x) { return __builtin_amdgcn_rcpf(1.0f + __expf(-x)); }
;     __device__ __forceinline__ void operator()(const f32x4 (&acc)[2][2][4][2], const Unit& u, int wr, int wc, int fr, int fq) const {
;     ...
; #pragma unroll
;                 for (int mm = 0; mm < 2; ++mm)
; #pragma unroll
;                     for (int bj = 0; bj < 2; ++bj) { const int m = mp * 2 + mm; const size_t off = (size_t)(row0 + ai * HALF + m * 16) * DM + col0;
;                         const u32x4 yy = y[mm][bj], pp = pr[mm][bj];
;                         const f32x4 a0 = acc[ai][bj][m][0], a1 = acc[ai][bj][m][1];
;                         f32x4 r0, r1;
;                         r0[0] = bflo(pp.x) + sigmoidf_(a0[0]) * bflo(yy.x); r0[1] = bfhi(pp.x) + sigmoidf_(a0[1]) * bfhi(yy.x); r0[2] = bflo(pp.y) + sigmoidf_(a0[2]) * bflo(yy.y); r0[3] = bfhi(pp.y) + sigmoidf_(a0[3]) * bfhi(yy.y);
;                         r1[0] = bflo(pp.z) + sigmoidf_(a1[0]) * bflo(yy.z); r1[1] = bfhi(pp.z) + sigmoidf_(a1[1]) * bfhi(yy.z); r1[2] = bflo(pp.w) + sigmoidf_(a1[2]) * bflo(yy.w); r1[3] = bfhi(pp.w) + sigmoidf_(a1[3]) * bfhi(yy.w);
;                         u32x4 w; w.x = cvt_pk_bf16(r0[0], r0[1]); w.y = cvt_pk_bf16(r0[2], r0[3]); w.z = cvt_pk_bf16(r1[0], r1[1]); w.w = cvt_pk_bf16(r1[2], r1[3]);
;                         const int slot = (ai * 4 + m) * 2 + bj;
;                         if (b < 2) sc[(size_t)slot * NTHR] = w;
;                         else *(u32x4*)(merged + off + bj * HALF) = w; }
.LBB0_437:
	v_mul_f32_e32 v128, 0xbfb8aa3b, v128
	v_mul_f32_e32 v129, 0xbfb8aa3b, v129
	v_exp_f32_e32 v128, v128
	v_exp_f32_e32 v129, v129
	v_mul_f32_e32 v122, 0xbfb8aa3b, v122
	v_mul_f32_e32 v123, 0xbfb8aa3b, v123
	v_add_f32_e32 v128, 1.0, v128
	v_add_f32_e32 v129, 1.0, v129
	v_rcp_f32_e32 v128, v128
	v_rcp_f32_e32 v129, v129
	v_exp_f32_e32 v122, v122
	v_exp_f32_e32 v123, v123
	s_waitcnt vmcnt(0) lgkmcnt(0)
	v_lshlrev_b32_e32 v192, 16, v158
	v_and_b32_e32 v193, 0xffff0000, v158
	v_lshlrev_b32_e32 v194, 16, v154
	v_and_b32_e32 v195, 0xffff0000, v154
	v_lshlrev_b32_e32 v158, 16, v159
	v_and_b32_e32 v159, 0xffff0000, v159
	v_lshlrev_b32_e32 v154, 16, v155
	v_and_b32_e32 v155, 0xffff0000, v155
	v_mul_f32_e32 v124, 0xbfb8aa3b, v124
	v_mul_f32_e32 v126, 0xbfb8aa3b, v126
	v_mul_f32_e32 v127, 0xbfb8aa3b, v127
	v_pk_fma_f32 v[128:129], v[128:129], v[154:155], v[158:159]
	v_add_f32_e32 v122, 1.0, v122
	v_add_f32_e32 v123, 1.0, v123
	v_lshlrev_b32_e32 v158, 16, v156
	v_and_b32_e32 v159, 0xffff0000, v156
	v_exp_f32_e32 v156, v124
	v_mul_f32_e32 v124, 0xbfb8aa3b, v125
	v_exp_f32_e32 v126, v126
	v_exp_f32_e32 v127, v127
	v_rcp_f32_e32 v122, v122
	v_rcp_f32_e32 v123, v123
	v_lshlrev_b32_e32 v154, 16, v160
	v_and_b32_e32 v155, 0xffff0000, v160
	v_exp_f32_e32 v160, v124
	v_add_f32_e32 v126, 1.0, v126
	v_add_f32_e32 v127, 1.0, v127
	v_pk_fma_f32 v[124:125], v[122:123], v[158:159], v[154:155]
	v_add_f32_e32 v122, 1.0, v156
	v_add_f32_e32 v123, 1.0, v160
	v_rcp_f32_e32 v126, v126
	v_rcp_f32_e32 v127, v127
	v_rcp_f32_e32 v122, v122
	v_rcp_f32_e32 v123, v123
	s_cmp_gt_i32 s18, 1
	v_lshlrev_b32_e32 v154, 16, v161
	v_and_b32_e32 v155, 0xffff0000, v161
	v_lshlrev_b32_e32 v156, 16, v157
	v_and_b32_e32 v157, 0xffff0000, v157
	s_cselect_b64 s[18:19], -1, 0
	v_pk_fma_f32 v[126:127], v[126:127], v[194:195], v[192:193]
	v_pk_fma_f32 v[154:155], v[122:123], v[156:157], v[154:155]
	v_cvt_pk_bf16_f32 v122, v126, v127
	v_cvt_pk_bf16_f32 v123, v128, v129
	v_cvt_pk_bf16_f32 v124, v124, v125
	v_cvt_pk_bf16_f32 v125, v154, v155
	s_mov_b64 s[2:3], -1
	s_and_b64 vcc, exec, s[18:19]
	v_lshl_add_u64 v[126:127], s[8:9], 0, v[184:185]
	s_cbranch_vccz .LBB0_439
	v_mov_b32_e32 v177, v0
	v_lshl_add_u64 v[128:129], v[126:127], 0, v[176:177]
	global_store_dwordx4 v[128:129], v[122:125], off
	s_mov_b64 s[2:3], 0
.LBB0_439:
	s_andn2_b64 vcc, exec, s[2:3]
	s_cbranch_vccnz .LBB0_441
	global_store_dwordx4 v[174:175], v[122:125], off
.LBB0_441:
	v_mul_f32_e32 v118, 0xbfb8aa3b, v118
	v_mul_f32_e32 v119, 0xbfb8aa3b, v119
	v_exp_f32_e32 v118, v118
	v_exp_f32_e32 v119, v119
	v_mul_f32_e32 v120, 0xbfb8aa3b, v120
	v_mul_f32_e32 v121, 0xbfb8aa3b, v121
	v_exp_f32_e32 v120, v120
	v_exp_f32_e32 v121, v121
	v_mul_f32_e32 v114, 0xbfb8aa3b, v114
	v_mul_f32_e32 v115, 0xbfb8aa3b, v115
	v_exp_f32_e32 v114, v114
	v_exp_f32_e32 v115, v115
	v_add_f32_e32 v118, 1.0, v118
	v_add_f32_e32 v119, 1.0, v119
	v_rcp_f32_e32 v118, v118
	v_rcp_f32_e32 v119, v119
	v_add_f32_e32 v120, 1.0, v120
	v_add_f32_e32 v121, 1.0, v121
	v_mul_f32_e32 v116, 0xbfb8aa3b, v116
	v_rcp_f32_e32 v120, v120
	v_rcp_f32_e32 v121, v121
	v_add_f32_e32 v114, 1.0, v114
	v_add_f32_e32 v115, 1.0, v115
	v_exp_f32_e32 v128, v116
	v_mul_f32_e32 v116, 0xbfb8aa3b, v117
	v_rcp_f32_e32 v114, v114
	v_rcp_f32_e32 v115, v115
	v_exp_f32_e32 v129, v116
	v_lshlrev_b32_e32 v122, 16, v150
	v_and_b32_e32 v123, 0xffff0000, v150
	v_lshlrev_b32_e32 v124, 16, v146
	v_and_b32_e32 v125, 0xffff0000, v146
	v_pk_fma_f32 v[118:119], v[118:119], v[124:125], v[122:123]
	v_lshlrev_b32_e32 v122, 16, v151
	v_and_b32_e32 v123, 0xffff0000, v151
	v_lshlrev_b32_e32 v124, 16, v147
	v_and_b32_e32 v125, 0xffff0000, v147
	v_pk_fma_f32 v[120:121], v[120:121], v[124:125], v[122:123]
	v_lshlrev_b32_e32 v122, 16, v152
	v_and_b32_e32 v123, 0xffff0000, v152
	v_lshlrev_b32_e32 v124, 16, v148
	v_and_b32_e32 v125, 0xffff0000, v148
	v_pk_fma_f32 v[116:117], v[114:115], v[124:125], v[122:123]
	v_add_f32_e32 v114, 1.0, v128
	v_add_f32_e32 v115, 1.0, v129
	v_rcp_f32_e32 v114, v114
	v_rcp_f32_e32 v115, v115
	v_lshlrev_b32_e32 v122, 16, v153
	v_and_b32_e32 v123, 0xffff0000, v153
	v_lshlrev_b32_e32 v124, 16, v149
	v_and_b32_e32 v125, 0xffff0000, v149
	v_pk_fma_f32 v[122:123], v[114:115], v[124:125], v[122:123]
	v_cvt_pk_bf16_f32 v114, v118, v119
	v_cndmask_b32_e64 v118, 0, 1, s[18:19]
	v_cvt_pk_bf16_f32 v115, v120, v121
	v_cvt_pk_bf16_f32 v116, v116, v117
	v_cvt_pk_bf16_f32 v117, v122, v123
	v_cmp_ne_u32_e64 s[2:3], 1, v118
	s_andn2_b64 vcc, exec, s[18:19]
	s_mov_b64 s[18:19], -1
	s_cbranch_vccnz .LBB0_443
	v_mov_b32_e32 v177, v0
	v_lshl_add_u64 v[118:119], v[126:127], 0, v[176:177]
	s_mov_b64 s[18:19], 0
	global_store_dwordx4 v[118:119], v[114:117], off offset:256
.LBB0_443:
	s_andn2_b64 vcc, exec, s[18:19]
	s_cbranch_vccnz .LBB0_445
	v_add_co_u32_e32 v118, vcc, 0x2000, v174
	s_nop 1
	v_addc_co_u32_e32 v119, vcc, 0, v175, vcc
	global_store_dwordx4 v[118:119], v[114:117], off
; __device__ __forceinline__ unsigned cvt_pk_bf16(float lo, float hi) { f32x2_t f = {lo, hi}; bf16x2_t v = __builtin_convertvector(f, bf16x2_t); return __builtin_bit_cast(unsigned, v); }
; __device__ __forceinline__ float bflo(unsigned w) { return __uint_as_float(w << 16); }
; __device__ __forceinline__ float bfhi(unsigned w) { return __uint_as_float(w & 0xffff0000u); }
;     __device__ __forceinline__ void operator()(const f32x4 (&acc)[2][2][4][2], const Unit& u, int wr, int wc, int fr, int fq) const {
;     ...
;                 u32x4 y[2][2], pr[2][2];
; #pragma unroll
;                 for (int mm = 0; mm < 2; ++mm)
; #pragma unroll
;                     for (int bj = 0; bj < 2; ++bj) { const int m = mp * 2 + mm; const size_t off = (size_t)(row0 + ai * HALF + m * 16) * DM + col0;
;                         y[mm][bj] = *(const u32x4*)(yb + off + bj * HALF);
;                         const int slot = (ai * 4 + m) * 2 + bj;
;                         pr[mm][bj] = (u32x4){0u, 0u, 0u, 0u};
;                         if (b > 0) pr[mm][bj] = sc[(size_t)slot * NTHR]; }
; #pragma unroll
;                 for (int mm = 0; mm < 2; ++mm)
; #pragma unroll
;                     for (int bj = 0; bj < 2; ++bj) { const int m = mp * 2 + mm; const size_t off = (size_t)(row0 + ai * HALF + m * 16) * DM + col0;
;                         const u32x4 yy = y[mm][bj], pp = pr[mm][bj];
;                         const f32x4 a0 = acc[ai][bj][m][0], a1 = acc[ai][bj][m][1];
;                         f32x4 r0, r1;
;                         r0[0] = bflo(pp.x) + sigmoidf_(a0[0]) * bflo(yy.x); r0[1] = bfhi(pp.x) + sigmoidf_(a0[1]) * bfhi(yy.x); r0[2] = bflo(pp.y) + sigmoidf_(a0[2]) * bflo(yy.y); r0[3] = bfhi(pp.y) + sigmoidf_(a0[3]) * bfhi(yy.y);
;                         r1[0] = bflo(pp.z) + sigmoidf_(a1[0]) * bflo(yy.z); r1[1] = bfhi(pp.z) + sigmoidf_(a1[1]) * bfhi(yy.z); r1[2] = bflo(pp.w) + sigmoidf_(a1[2]) * bflo(yy.w); r1[3] = bfhi(pp.w) + sigmoidf_(a1[3]) * bfhi(yy.w);
;                         u32x4 w; w.x = cvt_pk_bf16(r0[0], r0[1]); w.y = cvt_pk_bf16(r0[2], r0[3]); w.z = cvt_pk_bf16(r1[0], r1[1]); w.w = cvt_pk_bf16(r1[2], r1[3]);
;                         const int slot = (ai * 4 + m) * 2 + bj;
;                         if (b < 2) sc[(size_t)slot * NTHR] = w;
;                         else *(u32x4*)(merged + off + bj * HALF) = w; }
.LBB0_445:
	v_mul_f32_e32 v110, 0xbfb8aa3b, v110
	v_mul_f32_e32 v111, 0xbfb8aa3b, v111
	v_exp_f32_e32 v110, v110
	v_exp_f32_e32 v111, v111
	v_mul_f32_e32 v112, 0xbfb8aa3b, v112
	v_mul_f32_e32 v113, 0xbfb8aa3b, v113
	v_exp_f32_e32 v112, v112
	v_exp_f32_e32 v113, v113
	v_mul_f32_e32 v106, 0xbfb8aa3b, v106
	v_mul_f32_e32 v107, 0xbfb8aa3b, v107
	v_exp_f32_e32 v106, v106
	v_exp_f32_e32 v107, v107
	v_add_f32_e32 v110, 1.0, v110
	v_add_f32_e32 v111, 1.0, v111
	v_rcp_f32_e32 v110, v110
	v_rcp_f32_e32 v111, v111
	v_add_f32_e32 v112, 1.0, v112
	v_add_f32_e32 v113, 1.0, v113
	v_mul_f32_e32 v108, 0xbfb8aa3b, v108
	v_rcp_f32_e32 v112, v112
	v_rcp_f32_e32 v113, v113
	v_add_f32_e32 v106, 1.0, v106
	v_add_f32_e32 v107, 1.0, v107
	v_exp_f32_e32 v118, v108
	v_mul_f32_e32 v108, 0xbfb8aa3b, v109
	v_rcp_f32_e32 v106, v106
	v_rcp_f32_e32 v107, v107
	v_exp_f32_e32 v119, v108
	v_lshlrev_b32_e32 v114, 16, v138
	v_and_b32_e32 v115, 0xffff0000, v138
	v_lshlrev_b32_e32 v116, 16, v142
	v_and_b32_e32 v117, 0xffff0000, v142
	v_pk_fma_f32 v[110:111], v[110:111], v[116:117], v[114:115]
	v_lshlrev_b32_e32 v114, 16, v139
	v_and_b32_e32 v115, 0xffff0000, v139
	v_lshlrev_b32_e32 v116, 16, v143
	v_and_b32_e32 v117, 0xffff0000, v143
	v_pk_fma_f32 v[112:113], v[112:113], v[116:117], v[114:115]
	v_lshlrev_b32_e32 v114, 16, v140
	v_and_b32_e32 v115, 0xffff0000, v140
	v_lshlrev_b32_e32 v116, 16, v144
	v_and_b32_e32 v117, 0xffff0000, v144
	v_pk_fma_f32 v[108:109], v[106:107], v[116:117], v[114:115]
	v_add_f32_e32 v106, 1.0, v118
	v_add_f32_e32 v107, 1.0, v119
	v_rcp_f32_e32 v106, v106
	v_rcp_f32_e32 v107, v107
	v_lshlrev_b32_e32 v114, 16, v141
	v_and_b32_e32 v115, 0xffff0000, v141
	v_lshlrev_b32_e32 v116, 16, v145
	v_and_b32_e32 v117, 0xffff0000, v145
	v_pk_fma_f32 v[114:115], v[106:107], v[116:117], v[114:115]
	v_cvt_pk_bf16_f32 v106, v110, v111
	v_cvt_pk_bf16_f32 v107, v112, v113
	v_cvt_pk_bf16_f32 v108, v108, v109
	v_cvt_pk_bf16_f32 v109, v114, v115
	s_mov_b64 s[18:19], -1
	s_and_b64 vcc, exec, s[2:3]
	v_lshl_add_u64 v[110:111], s[8:9], 0, v[182:183]
	s_cbranch_vccnz .LBB0_447
	v_mov_b32_e32 v177, v0
	v_lshl_add_u64 v[112:113], v[110:111], 0, v[176:177]
	s_mov_b64 s[18:19], 0
	global_store_dwordx4 v[112:113], v[106:109], off
.LBB0_447:
	s_andn2_b64 vcc, exec, s[18:19]
	s_cbranch_vccnz .LBB0_449
	v_add_co_u32_e32 v112, vcc, 0x4000, v174
	s_nop 1
	v_addc_co_u32_e32 v113, vcc, 0, v175, vcc
	global_store_dwordx4 v[112:113], v[106:109], off
.LBB0_449:
	v_mul_f32_e32 v102, 0xbfb8aa3b, v102
	v_mul_f32_e32 v103, 0xbfb8aa3b, v103
	v_exp_f32_e32 v102, v102
	v_exp_f32_e32 v103, v103
	v_mul_f32_e32 v104, 0xbfb8aa3b, v104
	v_mul_f32_e32 v105, 0xbfb8aa3b, v105
	v_exp_f32_e32 v104, v104
	v_exp_f32_e32 v105, v105
	v_mul_f32_e32 v98, 0xbfb8aa3b, v98
	v_mul_f32_e32 v99, 0xbfb8aa3b, v99
	v_exp_f32_e32 v98, v98
	v_exp_f32_e32 v99, v99
	v_add_f32_e32 v102, 1.0, v102
	v_add_f32_e32 v103, 1.0, v103
	v_rcp_f32_e32 v102, v102
	v_rcp_f32_e32 v103, v103
	v_add_f32_e32 v104, 1.0, v104
	v_add_f32_e32 v105, 1.0, v105
	v_mul_f32_e32 v100, 0xbfb8aa3b, v100
	v_rcp_f32_e32 v104, v104
	v_rcp_f32_e32 v105, v105
	v_add_f32_e32 v98, 1.0, v98
	v_add_f32_e32 v99, 1.0, v99
	v_exp_f32_e32 v112, v100
	v_mul_f32_e32 v100, 0xbfb8aa3b, v101
	v_rcp_f32_e32 v98, v98
	v_rcp_f32_e32 v99, v99
	v_exp_f32_e32 v113, v100
	v_lshlrev_b32_e32 v106, 16, v134
	v_and_b32_e32 v107, 0xffff0000, v134
	v_lshlrev_b32_e32 v108, 16, v130
	v_and_b32_e32 v109, 0xffff0000, v130
	v_pk_fma_f32 v[102:103], v[102:103], v[108:109], v[106:107]
	v_lshlrev_b32_e32 v106, 16, v135
	v_and_b32_e32 v107, 0xffff0000, v135
	v_lshlrev_b32_e32 v108, 16, v131
	v_and_b32_e32 v109, 0xffff0000, v131
	v_pk_fma_f32 v[104:105], v[104:105], v[108:109], v[106:107]
	v_lshlrev_b32_e32 v106, 16, v136
	v_and_b32_e32 v107, 0xffff0000, v136
	v_lshlrev_b32_e32 v108, 16, v132
	v_and_b32_e32 v109, 0xffff0000, v132
	v_pk_fma_f32 v[100:101], v[98:99], v[108:109], v[106:107]
	v_add_f32_e32 v98, 1.0, v112
	v_add_f32_e32 v99, 1.0, v113
	v_rcp_f32_e32 v98, v98
	v_rcp_f32_e32 v99, v99
	v_lshlrev_b32_e32 v106, 16, v137
	v_and_b32_e32 v107, 0xffff0000, v137
	v_lshlrev_b32_e32 v108, 16, v133
	v_and_b32_e32 v109, 0xffff0000, v133
	v_pk_fma_f32 v[106:107], v[98:99], v[108:109], v[106:107]
	v_cvt_pk_bf16_f32 v98, v102, v103
	v_cvt_pk_bf16_f32 v99, v104, v105
	v_cvt_pk_bf16_f32 v100, v100, v101
	v_cvt_pk_bf16_f32 v101, v106, v107
	s_and_b64 vcc, exec, s[2:3]
	s_mov_b64 s[18:19], -1
	s_cbranch_vccnz .LBB0_451
	v_mov_b32_e32 v177, v0
	v_lshl_add_u64 v[102:103], v[110:111], 0, v[176:177]
	s_mov_b64 s[18:19], 0
	global_store_dwordx4 v[102:103], v[98:101], off offset:256
.LBB0_451:
	s_andn2_b64 vcc, exec, s[18:19]
	s_cbranch_vccnz .LBB0_453
	v_add_co_u32_e32 v102, vcc, 0x6000, v174
	s_nop 1
	v_addc_co_u32_e32 v103, vcc, 0, v175, vcc
	global_store_dwordx4 v[102:103], v[98:101], off
.LBB0_453:
	s_nop 1
	v_or_b32_e32 v98, 32, v178
	v_ashrrev_i32_e32 v99, 31, v98
	v_lshlrev_b64 v[132:133], 12, v[98:99]
	v_lshl_add_u64 v[98:99], v[180:181], 0, v[132:133]
	global_load_dwordx4 v[122:125], v[98:99], off
	v_mov_b32_e32 v114, 0
	s_and_b64 vcc, exec, s[4:5]
	v_mov_b32_e32 v126, 0
	v_mov_b32_e32 v127, 0
	v_mov_b32_e32 v128, 0
	v_mov_b32_e32 v129, 0
	s_cbranch_vccnz .LBB0_455
	v_add_co_u32_e32 v100, vcc, 0x8000, v174
	s_nop 1
	v_addc_co_u32_e32 v101, vcc, 0, v175, vcc
	global_load_dwordx4 v[126:129], v[100:101], off
.LBB0_455:
	global_load_dwordx4 v[118:121], v[98:99], off offset:256
	s_and_b64 vcc, exec, s[4:5]
	v_mov_b32_e32 v115, 0
	v_mov_b32_e32 v116, 0
	v_mov_b32_e32 v117, 0
	s_cbranch_vccnz .LBB0_457
	v_add_co_u32_e32 v98, vcc, 0xa000, v174
	s_nop 1
	v_addc_co_u32_e32 v99, vcc, 0, v175, vcc
	global_load_dwordx4 v[114:117], v[98:99], off
; __device__ __forceinline__ unsigned cvt_pk_bf16(float lo, float hi) { f32x2_t f = {lo, hi}; bf16x2_t v = __builtin_convertvector(f, bf16x2_t); return __builtin_bit_cast(unsigned, v); }
; __device__ __forceinline__ float bflo(unsigned w) { return __uint_as_float(w << 16); }
; __device__ __forceinline__ float bfhi(unsigned w) { return __uint_as_float(w & 0xffff0000u); }
;     __device__ __forceinline__ void operator()(const f32x4 (&acc)[2][2][4][2], const Unit& u, int wr, int wc, int fr, int fq) const {
;     ...
;                 u32x4 y[2][2], pr[2][2];
; #pragma unroll
;                 for (int mm = 0; mm < 2; ++mm)
; #pragma unroll
;                     for (int bj = 0; bj < 2; ++bj) { const int m = mp * 2 + mm; const size_t off = (size_t)(row0 + ai * HALF + m * 16) * DM + col0;
;                         y[mm][bj] = *(const u32x4*)(yb + off + bj * HALF);
;                         const int slot = (ai * 4 + m) * 2 + bj;
;                         pr[mm][bj] = (u32x4){0u, 0u, 0u, 0u};
;                         if (b > 0) pr[mm][bj] = sc[(size_t)slot * NTHR]; }
; #pragma unroll
;                 for (int mm = 0; mm < 2; ++mm)
; #pragma unroll
;                     for (int bj = 0; bj < 2; ++bj) { const int m = mp * 2 + mm; const size_t off = (size_t)(row0 + ai * HALF + m * 16) * DM + col0;
;                         const u32x4 yy = y[mm][bj], pp = pr[mm][bj];
;                         const f32x4 a0 = acc[ai][bj][m][0], a1 = acc[ai][bj][m][1];
;                         f32x4 r0, r1;
;                         r0[0] = bflo(pp.x) + sigmoidf_(a0[0]) * bflo(yy.x); r0[1] = bfhi(pp.x) + sigmoidf_(a0[1]) * bfhi(yy.x); r0[2] = bflo(pp.y) + sigmoidf_(a0[2]) * bflo(yy.y); r0[3] = bfhi(pp.y) + sigmoidf_(a0[3]) * bfhi(yy.y);
;                         r1[0] = bflo(pp.z) + sigmoidf_(a1[0]) * bflo(yy.z); r1[1] = bfhi(pp.z) + sigmoidf_(a1[1]) * bfhi(yy.z); r1[2] = bflo(pp.w) + sigmoidf_(a1[2]) * bflo(yy.w); r1[3] = bfhi(pp.w) + sigmoidf_(a1[3]) * bfhi(yy.w);
;                         u32x4 w; w.x = cvt_pk_bf16(r0[0], r0[1]); w.y = cvt_pk_bf16(r0[2], r0[3]); w.z = cvt_pk_bf16(r1[0], r1[1]); w.w = cvt_pk_bf16(r1[2], r1[3]);
;                         const int slot = (ai * 4 + m) * 2 + bj;
;                         if (b < 2) sc[(size_t)slot * NTHR] = w;
;                         else *(u32x4*)(merged + off + bj * HALF) = w; }
.LBB0_457:
	v_or_b32_e32 v98, 48, v178
	v_ashrrev_i32_e32 v99, 31, v98
	v_lshlrev_b64 v[130:131], 12, v[98:99]
	v_lshl_add_u64 v[100:101], v[180:181], 0, v[130:131]
	global_load_dwordx4 v[106:109], v[100:101], off
	v_mov_b32_e32 v98, 0
	s_and_b64 vcc, exec, s[4:5]
	v_mov_b32_e32 v110, 0
	v_mov_b32_e32 v111, 0
	v_mov_b32_e32 v112, 0
	v_mov_b32_e32 v113, 0
	s_cbranch_vccnz .LBB0_459
	v_add_co_u32_e32 v102, vcc, 0xc000, v174
	s_nop 1
	v_addc_co_u32_e32 v103, vcc, 0, v175, vcc
	global_load_dwordx4 v[110:113], v[102:103], off
.LBB0_459:
	s_nop 0
	global_load_dwordx4 v[102:105], v[100:101], off offset:256
	s_and_b64 vcc, exec, s[4:5]
	v_mov_b32_e32 v99, 0
	v_mov_b32_e32 v100, 0
	v_mov_b32_e32 v101, 0
	s_cbranch_vccnz .LBB0_461
	v_add_co_u32_e32 v98, vcc, 0xe000, v174
	s_nop 1
	v_addc_co_u32_e32 v99, vcc, 0, v175, vcc
	global_load_dwordx4 v[98:101], v[98:99], off
.LBB0_461:
	v_mul_f32_e32 v96, 0xbfb8aa3b, v96
	v_mul_f32_e32 v97, 0xbfb8aa3b, v97
	v_exp_f32_e32 v96, v96
	v_exp_f32_e32 v97, v97
	v_mul_f32_e32 v90, 0xbfb8aa3b, v90
	v_mul_f32_e32 v91, 0xbfb8aa3b, v91
	v_add_f32_e32 v96, 1.0, v96
	v_add_f32_e32 v97, 1.0, v97
	v_rcp_f32_e32 v96, v96
	v_rcp_f32_e32 v97, v97
	v_exp_f32_e32 v90, v90
	v_exp_f32_e32 v91, v91
	s_waitcnt vmcnt(0) lgkmcnt(0)
	v_lshlrev_b32_e32 v134, 16, v126
	v_and_b32_e32 v135, 0xffff0000, v126
	v_lshlrev_b32_e32 v136, 16, v122
	v_and_b32_e32 v137, 0xffff0000, v122
	v_lshlrev_b32_e32 v126, 16, v127
	v_and_b32_e32 v127, 0xffff0000, v127
	v_lshlrev_b32_e32 v122, 16, v123
	v_and_b32_e32 v123, 0xffff0000, v123
	v_mul_f32_e32 v92, 0xbfb8aa3b, v92
	v_mul_f32_e32 v94, 0xbfb8aa3b, v94
	v_mul_f32_e32 v95, 0xbfb8aa3b, v95
	v_pk_fma_f32 v[96:97], v[96:97], v[122:123], v[126:127]
	v_add_f32_e32 v90, 1.0, v90
	v_add_f32_e32 v91, 1.0, v91
	v_lshlrev_b32_e32 v126, 16, v124
	v_and_b32_e32 v127, 0xffff0000, v124
	v_exp_f32_e32 v124, v92
	v_mul_f32_e32 v92, 0xbfb8aa3b, v93
	v_exp_f32_e32 v94, v94
	v_exp_f32_e32 v95, v95
	v_rcp_f32_e32 v90, v90
	v_rcp_f32_e32 v91, v91
	v_lshlrev_b32_e32 v122, 16, v128
	v_and_b32_e32 v123, 0xffff0000, v128
	v_exp_f32_e32 v128, v92
	v_add_f32_e32 v94, 1.0, v94
	v_add_f32_e32 v95, 1.0, v95
	v_pk_fma_f32 v[92:93], v[90:91], v[126:127], v[122:123]
	v_add_f32_e32 v90, 1.0, v124
	v_add_f32_e32 v91, 1.0, v128
	v_rcp_f32_e32 v94, v94
	v_rcp_f32_e32 v95, v95
	v_rcp_f32_e32 v90, v90
	v_rcp_f32_e32 v91, v91
	v_lshlrev_b32_e32 v122, 16, v129
	v_and_b32_e32 v123, 0xffff0000, v129
	v_lshlrev_b32_e32 v124, 16, v125
	v_and_b32_e32 v125, 0xffff0000, v125
	v_pk_fma_f32 v[94:95], v[94:95], v[136:137], v[134:135]
	v_pk_fma_f32 v[122:123], v[90:91], v[124:125], v[122:123]
	v_cvt_pk_bf16_f32 v90, v94, v95
	v_cvt_pk_bf16_f32 v91, v96, v97
	v_cvt_pk_bf16_f32 v92, v92, v93
	v_cvt_pk_bf16_f32 v93, v122, v123
	s_mov_b64 s[18:19], -1
	s_and_b64 vcc, exec, s[2:3]
	v_lshl_add_u64 v[94:95], s[8:9], 0, v[132:133]
	s_cbranch_vccnz .LBB0_463
	v_mov_b32_e32 v177, v0
	v_lshl_add_u64 v[96:97], v[94:95], 0, v[176:177]
	s_mov_b64 s[18:19], 0
	global_store_dwordx4 v[96:97], v[90:93], off
.LBB0_463:
	s_andn2_b64 vcc, exec, s[18:19]
	s_cbranch_vccnz .LBB0_465
	v_add_co_u32_e32 v96, vcc, 0x8000, v174
	s_nop 1
	v_addc_co_u32_e32 v97, vcc, 0, v175, vcc
	global_store_dwordx4 v[96:97], v[90:93], off
.LBB0_465:
	v_mul_f32_e32 v86, 0xbfb8aa3b, v86
	v_mul_f32_e32 v87, 0xbfb8aa3b, v87
	v_exp_f32_e32 v86, v86
	v_exp_f32_e32 v87, v87
	v_mul_f32_e32 v88, 0xbfb8aa3b, v88
	v_mul_f32_e32 v89, 0xbfb8aa3b, v89
	v_exp_f32_e32 v88, v88
	v_exp_f32_e32 v89, v89
	v_mul_f32_e32 v82, 0xbfb8aa3b, v82
	v_mul_f32_e32 v83, 0xbfb8aa3b, v83
	v_exp_f32_e32 v82, v82
	v_exp_f32_e32 v83, v83
	v_add_f32_e32 v86, 1.0, v86
	v_add_f32_e32 v87, 1.0, v87
	v_rcp_f32_e32 v86, v86
	v_rcp_f32_e32 v87, v87
	v_add_f32_e32 v88, 1.0, v88
	v_add_f32_e32 v89, 1.0, v89
	v_mul_f32_e32 v84, 0xbfb8aa3b, v84
	v_rcp_f32_e32 v88, v88
	v_rcp_f32_e32 v89, v89
	v_add_f32_e32 v82, 1.0, v82
	v_add_f32_e32 v83, 1.0, v83
	v_exp_f32_e32 v96, v84
	v_mul_f32_e32 v84, 0xbfb8aa3b, v85
	v_rcp_f32_e32 v82, v82
	v_rcp_f32_e32 v83, v83
	v_exp_f32_e32 v97, v84
	v_lshlrev_b32_e32 v90, 16, v114
	v_and_b32_e32 v91, 0xffff0000, v114
	v_lshlrev_b32_e32 v92, 16, v118
	v_and_b32_e32 v93, 0xffff0000, v118
	v_pk_fma_f32 v[86:87], v[86:87], v[92:93], v[90:91]
	v_lshlrev_b32_e32 v90, 16, v115
	v_and_b32_e32 v91, 0xffff0000, v115
	v_lshlrev_b32_e32 v92, 16, v119
	v_and_b32_e32 v93, 0xffff0000, v119
	v_pk_fma_f32 v[88:89], v[88:89], v[92:93], v[90:91]
	v_lshlrev_b32_e32 v90, 16, v116
	v_and_b32_e32 v91, 0xffff0000, v116
	v_lshlrev_b32_e32 v92, 16, v120
	v_and_b32_e32 v93, 0xffff0000, v120
	v_pk_fma_f32 v[84:85], v[82:83], v[92:93], v[90:91]
	v_add_f32_e32 v82, 1.0, v96
	v_add_f32_e32 v83, 1.0, v97
	v_rcp_f32_e32 v82, v82
	v_rcp_f32_e32 v83, v83
	v_lshlrev_b32_e32 v90, 16, v117
	v_and_b32_e32 v91, 0xffff0000, v117
	v_lshlrev_b32_e32 v92, 16, v121
	v_and_b32_e32 v93, 0xffff0000, v121
	v_pk_fma_f32 v[90:91], v[82:83], v[92:93], v[90:91]
	v_cvt_pk_bf16_f32 v82, v86, v87
	v_cvt_pk_bf16_f32 v83, v88, v89
	v_cvt_pk_bf16_f32 v84, v84, v85
	v_cvt_pk_bf16_f32 v85, v90, v91
	s_and_b64 vcc, exec, s[2:3]
	s_mov_b64 s[18:19], -1
	s_cbranch_vccnz .LBB0_467
	v_mov_b32_e32 v177, v0
	v_lshl_add_u64 v[86:87], v[94:95], 0, v[176:177]
	s_mov_b64 s[18:19], 0
	global_store_dwordx4 v[86:87], v[82:85], off offset:256
.LBB0_467:
	s_andn2_b64 vcc, exec, s[18:19]
	s_cbranch_vccnz .LBB0_469
	v_add_co_u32_e32 v86, vcc, 0xa000, v174
	s_nop 1
	v_addc_co_u32_e32 v87, vcc, 0, v175, vcc
	global_store_dwordx4 v[86:87], v[82:85], off
; __device__ __forceinline__ unsigned cvt_pk_bf16(float lo, float hi) { f32x2_t f = {lo, hi}; bf16x2_t v = __builtin_convertvector(f, bf16x2_t); return __builtin_bit_cast(unsigned, v); }
; __device__ __forceinline__ float bflo(unsigned w) { return __uint_as_float(w << 16); }
; __device__ __forceinline__ float bfhi(unsigned w) { return __uint_as_float(w & 0xffff0000u); }
;     __device__ __forceinline__ void operator()(const f32x4 (&acc)[2][2][4][2], const Unit& u, int wr, int wc, int fr, int fq) const {
;     ...
;                 u32x4 y[2][2], pr[2][2];
; #pragma unroll
;                 for (int mm = 0; mm < 2; ++mm)
; #pragma unroll
;                     for (int bj = 0; bj < 2; ++bj) { const int m = mp * 2 + mm; const size_t off = (size_t)(row0 + ai * HALF + m * 16) * DM + col0;
;                         y[mm][bj] = *(const u32x4*)(yb + off + bj * HALF);
;                         const int slot = (ai * 4 + m) * 2 + bj;
;                         pr[mm][bj] = (u32x4){0u, 0u, 0u, 0u};
;                         if (b > 0) pr[mm][bj] = sc[(size_t)slot * NTHR]; }
; #pragma unroll
;                 for (int mm = 0; mm < 2; ++mm)
; #pragma unroll
;                     for (int bj = 0; bj < 2; ++bj) { const int m = mp * 2 + mm; const size_t off = (size_t)(row0 + ai * HALF + m * 16) * DM + col0;
;                         const u32x4 yy = y[mm][bj], pp = pr[mm][bj];
;                         const f32x4 a0 = acc[ai][bj][m][0], a1 = acc[ai][bj][m][1];
;                         f32x4 r0, r1;
;                         r0[0] = bflo(pp.x) + sigmoidf_(a0[0]) * bflo(yy.x); r0[1] = bfhi(pp.x) + sigmoidf_(a0[1]) * bfhi(yy.x); r0[2] = bflo(pp.y) + sigmoidf_(a0[2]) * bflo(yy.y); r0[3] = bfhi(pp.y) + sigmoidf_(a0[3]) * bfhi(yy.y);
;                         r1[0] = bflo(pp.z) + sigmoidf_(a1[0]) * bflo(yy.z); r1[1] = bfhi(pp.z) + sigmoidf_(a1[1]) * bfhi(yy.z); r1[2] = bflo(pp.w) + sigmoidf_(a1[2]) * bflo(yy.w); r1[3] = bfhi(pp.w) + sigmoidf_(a1[3]) * bfhi(yy.w);
;                         u32x4 w; w.x = cvt_pk_bf16(r0[0], r0[1]); w.y = cvt_pk_bf16(r0[2], r0[3]); w.z = cvt_pk_bf16(r1[0], r1[1]); w.w = cvt_pk_bf16(r1[2], r1[3]);
;                         const int slot = (ai * 4 + m) * 2 + bj;
;                         if (b < 2) sc[(size_t)slot * NTHR] = w;
;                         else *(u32x4*)(merged + off + bj * HALF) = w; }
.LBB0_469:
	v_mul_f32_e32 v78, 0xbfb8aa3b, v78
	v_mul_f32_e32 v79, 0xbfb8aa3b, v79
	v_exp_f32_e32 v78, v78
	v_exp_f32_e32 v79, v79
	v_mul_f32_e32 v80, 0xbfb8aa3b, v80
	v_mul_f32_e32 v81, 0xbfb8aa3b, v81
	v_exp_f32_e32 v80, v80
	v_exp_f32_e32 v81, v81
	v_mul_f32_e32 v74, 0xbfb8aa3b, v74
	v_mul_f32_e32 v75, 0xbfb8aa3b, v75
	v_exp_f32_e32 v74, v74
	v_exp_f32_e32 v75, v75
	v_add_f32_e32 v78, 1.0, v78
	v_add_f32_e32 v79, 1.0, v79
	v_rcp_f32_e32 v78, v78
	v_rcp_f32_e32 v79, v79
	v_add_f32_e32 v80, 1.0, v80
	v_add_f32_e32 v81, 1.0, v81
	v_mul_f32_e32 v76, 0xbfb8aa3b, v76
	v_rcp_f32_e32 v80, v80
	v_rcp_f32_e32 v81, v81
	v_add_f32_e32 v74, 1.0, v74
	v_add_f32_e32 v75, 1.0, v75
	v_exp_f32_e32 v86, v76
	v_mul_f32_e32 v76, 0xbfb8aa3b, v77
	v_rcp_f32_e32 v74, v74
	v_rcp_f32_e32 v75, v75
	v_exp_f32_e32 v87, v76
	v_lshlrev_b32_e32 v82, 16, v110
	v_and_b32_e32 v83, 0xffff0000, v110
	v_lshlrev_b32_e32 v84, 16, v106
	v_and_b32_e32 v85, 0xffff0000, v106
	v_pk_fma_f32 v[78:79], v[78:79], v[84:85], v[82:83]
	v_lshlrev_b32_e32 v82, 16, v111
	v_and_b32_e32 v83, 0xffff0000, v111
	v_lshlrev_b32_e32 v84, 16, v107
	v_and_b32_e32 v85, 0xffff0000, v107
	v_pk_fma_f32 v[80:81], v[80:81], v[84:85], v[82:83]
	v_lshlrev_b32_e32 v82, 16, v112
	v_and_b32_e32 v83, 0xffff0000, v112
	v_lshlrev_b32_e32 v84, 16, v108
	v_and_b32_e32 v85, 0xffff0000, v108
	v_pk_fma_f32 v[76:77], v[74:75], v[84:85], v[82:83]
	v_add_f32_e32 v74, 1.0, v86
	v_add_f32_e32 v75, 1.0, v87
	v_rcp_f32_e32 v74, v74
	v_rcp_f32_e32 v75, v75
	v_lshlrev_b32_e32 v82, 16, v113
	v_and_b32_e32 v83, 0xffff0000, v113
	v_lshlrev_b32_e32 v84, 16, v109
	v_and_b32_e32 v85, 0xffff0000, v109
	v_pk_fma_f32 v[82:83], v[74:75], v[84:85], v[82:83]
	v_cvt_pk_bf16_f32 v74, v78, v79
	v_cvt_pk_bf16_f32 v75, v80, v81
	v_cvt_pk_bf16_f32 v76, v76, v77
	v_cvt_pk_bf16_f32 v77, v82, v83
	s_mov_b64 s[18:19], -1
	s_and_b64 vcc, exec, s[2:3]
	v_lshl_add_u64 v[78:79], s[8:9], 0, v[130:131]
	s_cbranch_vccnz .LBB0_471
	v_mov_b32_e32 v177, v0
	v_lshl_add_u64 v[80:81], v[78:79], 0, v[176:177]
	s_mov_b64 s[18:19], 0
	global_store_dwordx4 v[80:81], v[74:77], off
.LBB0_471:
	s_andn2_b64 vcc, exec, s[18:19]
	s_cbranch_vccnz .LBB0_473
	v_add_co_u32_e32 v80, vcc, 0xc000, v174
	s_nop 1
	v_addc_co_u32_e32 v81, vcc, 0, v175, vcc
	global_store_dwordx4 v[80:81], v[74:77], off
.LBB0_473:
	v_mul_f32_e32 v70, 0xbfb8aa3b, v70
	v_mul_f32_e32 v71, 0xbfb8aa3b, v71
	v_exp_f32_e32 v70, v70
	v_exp_f32_e32 v71, v71
	v_mul_f32_e32 v72, 0xbfb8aa3b, v72
	v_mul_f32_e32 v73, 0xbfb8aa3b, v73
	v_exp_f32_e32 v72, v72
	v_exp_f32_e32 v73, v73
	v_mul_f32_e32 v66, 0xbfb8aa3b, v66
	v_mul_f32_e32 v67, 0xbfb8aa3b, v67
	v_exp_f32_e32 v66, v66
	v_exp_f32_e32 v67, v67
	v_add_f32_e32 v70, 1.0, v70
	v_add_f32_e32 v71, 1.0, v71
	v_rcp_f32_e32 v70, v70
	v_rcp_f32_e32 v71, v71
	v_add_f32_e32 v72, 1.0, v72
	v_add_f32_e32 v73, 1.0, v73
	v_mul_f32_e32 v68, 0xbfb8aa3b, v68
	v_rcp_f32_e32 v72, v72
	v_rcp_f32_e32 v73, v73
	v_add_f32_e32 v66, 1.0, v66
	v_add_f32_e32 v67, 1.0, v67
	v_exp_f32_e32 v80, v68
	v_mul_f32_e32 v68, 0xbfb8aa3b, v69
	v_rcp_f32_e32 v66, v66
	v_rcp_f32_e32 v67, v67
	v_exp_f32_e32 v81, v68
	v_lshlrev_b32_e32 v74, 16, v98
	v_and_b32_e32 v75, 0xffff0000, v98
	v_lshlrev_b32_e32 v76, 16, v102
	v_and_b32_e32 v77, 0xffff0000, v102
	v_pk_fma_f32 v[70:71], v[70:71], v[76:77], v[74:75]
	v_lshlrev_b32_e32 v74, 16, v99
	v_and_b32_e32 v75, 0xffff0000, v99
	v_lshlrev_b32_e32 v76, 16, v103
	v_and_b32_e32 v77, 0xffff0000, v103
	v_pk_fma_f32 v[72:73], v[72:73], v[76:77], v[74:75]
	v_lshlrev_b32_e32 v74, 16, v100
	v_and_b32_e32 v75, 0xffff0000, v100
	v_lshlrev_b32_e32 v76, 16, v104
	v_and_b32_e32 v77, 0xffff0000, v104
	v_pk_fma_f32 v[68:69], v[66:67], v[76:77], v[74:75]
	v_add_f32_e32 v66, 1.0, v80
	v_add_f32_e32 v67, 1.0, v81
	v_rcp_f32_e32 v66, v66
	v_rcp_f32_e32 v67, v67
	v_lshlrev_b32_e32 v74, 16, v101
	v_and_b32_e32 v75, 0xffff0000, v101
	v_lshlrev_b32_e32 v76, 16, v105
	v_and_b32_e32 v77, 0xffff0000, v105
	v_pk_fma_f32 v[74:75], v[66:67], v[76:77], v[74:75]
	v_cvt_pk_bf16_f32 v66, v70, v71
	v_cvt_pk_bf16_f32 v67, v72, v73
	v_cvt_pk_bf16_f32 v68, v68, v69
	v_cvt_pk_bf16_f32 v69, v74, v75
	s_and_b64 vcc, exec, s[2:3]
	s_mov_b64 s[18:19], -1
	s_cbranch_vccnz .LBB0_475
	v_mov_b32_e32 v177, v0
	v_lshl_add_u64 v[70:71], v[78:79], 0, v[176:177]
	s_mov_b64 s[18:19], 0
	global_store_dwordx4 v[70:71], v[66:69], off offset:256
.LBB0_475:
	s_andn2_b64 vcc, exec, s[18:19]
	s_cbranch_vccnz .LBB0_477
	v_add_co_u32_e32 v70, vcc, 0xe000, v174
	s_nop 1
	v_addc_co_u32_e32 v71, vcc, 0, v175, vcc
	global_store_dwordx4 v[70:71], v[66:69], off
.LBB0_477:
	s_nop 1
	v_lshlrev_b64 v[66:67], 12, v[178:179]
	s_mov_b64 s[18:19], 0x80000
	v_lshl_add_u64 v[100:101], v[66:67], 0, s[18:19]
	v_lshl_add_u64 v[66:67], v[180:181], 0, v[100:101]
	global_load_dwordx4 v[90:93], v[66:67], off
	v_mov_b32_e32 v82, 0
	s_and_b64 vcc, exec, s[4:5]
	v_mov_b32_e32 v94, 0
	v_mov_b32_e32 v95, 0
	v_mov_b32_e32 v96, 0
	v_mov_b32_e32 v97, 0
	s_cbranch_vccnz .LBB0_479
	v_add_co_u32_e32 v68, vcc, 0x10000, v174
	s_nop 1
	v_addc_co_u32_e32 v69, vcc, 0, v175, vcc
	global_load_dwordx4 v[94:97], v[68:69], off
.LBB0_479:
	global_load_dwordx4 v[86:89], v[66:67], off offset:256
	s_and_b64 vcc, exec, s[4:5]
	v_mov_b32_e32 v83, 0
	v_mov_b32_e32 v84, 0
	v_mov_b32_e32 v85, 0
	s_cbranch_vccnz .LBB0_481
	v_add_co_u32_e32 v66, vcc, 0x12000, v174
	s_nop 1
	v_addc_co_u32_e32 v67, vcc, 0, v175, vcc
	global_load_dwordx4 v[82:85], v[66:67], off
; __device__ __forceinline__ unsigned cvt_pk_bf16(float lo, float hi) { f32x2_t f = {lo, hi}; bf16x2_t v = __builtin_convertvector(f, bf16x2_t); return __builtin_bit_cast(unsigned, v); }
; __device__ __forceinline__ float bflo(unsigned w) { return __uint_as_float(w << 16); }
; __device__ __forceinline__ float bfhi(unsigned w) { return __uint_as_float(w & 0xffff0000u); }
;     __device__ __forceinline__ void operator()(const f32x4 (&acc)[2][2][4][2], const Unit& u, int wr, int wc, int fr, int fq) const {
;     ...
;                 u32x4 y[2][2], pr[2][2];
; #pragma unroll
;                 for (int mm = 0; mm < 2; ++mm)
; #pragma unroll
;                     for (int bj = 0; bj < 2; ++bj) { const int m = mp * 2 + mm; const size_t off = (size_t)(row0 + ai * HALF + m * 16) * DM + col0;
;                         y[mm][bj] = *(const u32x4*)(yb + off + bj * HALF);
;                         const int slot = (ai * 4 + m) * 2 + bj;
;                         pr[mm][bj] = (u32x4){0u, 0u, 0u, 0u};
;                         if (b > 0) pr[mm][bj] = sc[(size_t)slot * NTHR]; }
; #pragma unroll
;                 for (int mm = 0; mm < 2; ++mm)
; #pragma unroll
;                     for (int bj = 0; bj < 2; ++bj) { const int m = mp * 2 + mm; const size_t off = (size_t)(row0 + ai * HALF + m * 16) * DM + col0;
;                         const u32x4 yy = y[mm][bj], pp = pr[mm][bj];
;                         const f32x4 a0 = acc[ai][bj][m][0], a1 = acc[ai][bj][m][1];
;                         f32x4 r0, r1;
;                         r0[0] = bflo(pp.x) + sigmoidf_(a0[0]) * bflo(yy.x); r0[1] = bfhi(pp.x) + sigmoidf_(a0[1]) * bfhi(yy.x); r0[2] = bflo(pp.y) + sigmoidf_(a0[2]) * bflo(yy.y); r0[3] = bfhi(pp.y) + sigmoidf_(a0[3]) * bfhi(yy.y);
;                         r1[0] = bflo(pp.z) + sigmoidf_(a1[0]) * bflo(yy.z); r1[1] = bfhi(pp.z) + sigmoidf_(a1[1]) * bfhi(yy.z); r1[2] = bflo(pp.w) + sigmoidf_(a1[2]) * bflo(yy.w); r1[3] = bfhi(pp.w) + sigmoidf_(a1[3]) * bfhi(yy.w);
;                         u32x4 w; w.x = cvt_pk_bf16(r0[0], r0[1]); w.y = cvt_pk_bf16(r0[2], r0[3]); w.z = cvt_pk_bf16(r1[0], r1[1]); w.w = cvt_pk_bf16(r1[2], r1[3]);
;                         const int slot = (ai * 4 + m) * 2 + bj;
;                         if (b < 2) sc[(size_t)slot * NTHR] = w;
;                         else *(u32x4*)(merged + off + bj * HALF) = w; }
.LBB0_481:
	v_lshlrev_b64 v[66:67], 12, v[178:179]
	s_mov_b64 s[18:19], 0x90000
	v_lshl_add_u64 v[98:99], v[66:67], 0, s[18:19]
	v_lshl_add_u64 v[68:69], v[180:181], 0, v[98:99]
	global_load_dwordx4 v[74:77], v[68:69], off
	v_mov_b32_e32 v66, 0
	s_and_b64 vcc, exec, s[4:5]
	v_mov_b32_e32 v78, 0
	v_mov_b32_e32 v79, 0
	v_mov_b32_e32 v80, 0
	v_mov_b32_e32 v81, 0
	s_cbranch_vccnz .LBB0_483
	v_add_co_u32_e32 v70, vcc, 0x14000, v174
	s_nop 1
	v_addc_co_u32_e32 v71, vcc, 0, v175, vcc
	global_load_dwordx4 v[78:81], v[70:71], off
.LBB0_483:
	s_nop 0
	global_load_dwordx4 v[70:73], v[68:69], off offset:256
	s_and_b64 vcc, exec, s[4:5]
	v_mov_b32_e32 v67, 0
	v_mov_b32_e32 v68, 0
	v_mov_b32_e32 v69, 0
	s_cbranch_vccnz .LBB0_485
	v_add_co_u32_e32 v66, vcc, 0x16000, v174
	s_nop 1
	v_addc_co_u32_e32 v67, vcc, 0, v175, vcc
	global_load_dwordx4 v[66:69], v[66:67], off
.LBB0_485:
	v_mul_f32_e32 v64, 0xbfb8aa3b, v64
	v_mul_f32_e32 v65, 0xbfb8aa3b, v65
	v_exp_f32_e32 v64, v64
	v_exp_f32_e32 v65, v65
	v_mul_f32_e32 v58, 0xbfb8aa3b, v58
	v_mul_f32_e32 v59, 0xbfb8aa3b, v59
	v_add_f32_e32 v64, 1.0, v64
	v_add_f32_e32 v65, 1.0, v65
	v_rcp_f32_e32 v64, v64
	v_rcp_f32_e32 v65, v65
	v_exp_f32_e32 v58, v58
	v_exp_f32_e32 v59, v59
	s_waitcnt vmcnt(0) lgkmcnt(0)
	v_lshlrev_b32_e32 v102, 16, v94
	v_and_b32_e32 v103, 0xffff0000, v94
	v_lshlrev_b32_e32 v104, 16, v90
	v_and_b32_e32 v105, 0xffff0000, v90
	v_lshlrev_b32_e32 v94, 16, v95
	v_and_b32_e32 v95, 0xffff0000, v95
	v_lshlrev_b32_e32 v90, 16, v91
	v_and_b32_e32 v91, 0xffff0000, v91
	v_mul_f32_e32 v60, 0xbfb8aa3b, v60
	v_mul_f32_e32 v62, 0xbfb8aa3b, v62
	v_mul_f32_e32 v63, 0xbfb8aa3b, v63
	v_pk_fma_f32 v[64:65], v[64:65], v[90:91], v[94:95]
	v_add_f32_e32 v58, 1.0, v58
	v_add_f32_e32 v59, 1.0, v59
	v_lshlrev_b32_e32 v94, 16, v92
	v_and_b32_e32 v95, 0xffff0000, v92
	v_exp_f32_e32 v92, v60
	v_mul_f32_e32 v60, 0xbfb8aa3b, v61
	v_exp_f32_e32 v62, v62
	v_exp_f32_e32 v63, v63
	v_rcp_f32_e32 v58, v58
	v_rcp_f32_e32 v59, v59
	v_lshlrev_b32_e32 v90, 16, v96
	v_and_b32_e32 v91, 0xffff0000, v96
	v_exp_f32_e32 v96, v60
	v_add_f32_e32 v62, 1.0, v62
	v_add_f32_e32 v63, 1.0, v63
	v_pk_fma_f32 v[60:61], v[58:59], v[94:95], v[90:91]
	v_add_f32_e32 v58, 1.0, v92
	v_add_f32_e32 v59, 1.0, v96
	v_rcp_f32_e32 v62, v62
	v_rcp_f32_e32 v63, v63
	v_rcp_f32_e32 v58, v58
	v_rcp_f32_e32 v59, v59
	v_lshlrev_b32_e32 v90, 16, v97
	v_and_b32_e32 v91, 0xffff0000, v97
	v_lshlrev_b32_e32 v92, 16, v93
	v_and_b32_e32 v93, 0xffff0000, v93
	v_pk_fma_f32 v[62:63], v[62:63], v[104:105], v[102:103]
	v_pk_fma_f32 v[90:91], v[58:59], v[92:93], v[90:91]
	v_cvt_pk_bf16_f32 v58, v62, v63
	v_cvt_pk_bf16_f32 v59, v64, v65
	v_cvt_pk_bf16_f32 v60, v60, v61
	v_cvt_pk_bf16_f32 v61, v90, v91
	s_mov_b64 s[18:19], -1
	s_and_b64 vcc, exec, s[2:3]
	v_lshl_add_u64 v[62:63], s[8:9], 0, v[100:101]
	s_cbranch_vccnz .LBB0_487
	v_mov_b32_e32 v177, v0
	v_lshl_add_u64 v[64:65], v[62:63], 0, v[176:177]
	s_mov_b64 s[18:19], 0
	global_store_dwordx4 v[64:65], v[58:61], off
.LBB0_487:
	s_andn2_b64 vcc, exec, s[18:19]
	s_cbranch_vccnz .LBB0_489
	v_add_co_u32_e32 v64, vcc, 0x10000, v174
	s_nop 1
	v_addc_co_u32_e32 v65, vcc, 0, v175, vcc
	global_store_dwordx4 v[64:65], v[58:61], off
.LBB0_489:
	v_mul_f32_e32 v54, 0xbfb8aa3b, v54
	v_mul_f32_e32 v55, 0xbfb8aa3b, v55
	v_exp_f32_e32 v54, v54
	v_exp_f32_e32 v55, v55
	v_mul_f32_e32 v56, 0xbfb8aa3b, v56
	v_mul_f32_e32 v57, 0xbfb8aa3b, v57
	v_exp_f32_e32 v56, v56
	v_exp_f32_e32 v57, v57
	v_mul_f32_e32 v50, 0xbfb8aa3b, v50
	v_mul_f32_e32 v51, 0xbfb8aa3b, v51
	v_exp_f32_e32 v50, v50
	v_exp_f32_e32 v51, v51
	v_add_f32_e32 v54, 1.0, v54
	v_add_f32_e32 v55, 1.0, v55
	v_rcp_f32_e32 v54, v54
	v_rcp_f32_e32 v55, v55
	v_add_f32_e32 v56, 1.0, v56
	v_add_f32_e32 v57, 1.0, v57
	v_mul_f32_e32 v52, 0xbfb8aa3b, v52
	v_rcp_f32_e32 v56, v56
	v_rcp_f32_e32 v57, v57
	v_add_f32_e32 v50, 1.0, v50
	v_add_f32_e32 v51, 1.0, v51
	v_exp_f32_e32 v64, v52
	v_mul_f32_e32 v52, 0xbfb8aa3b, v53
	v_rcp_f32_e32 v50, v50
	v_rcp_f32_e32 v51, v51
	v_exp_f32_e32 v65, v52
	v_lshlrev_b32_e32 v58, 16, v82
	v_and_b32_e32 v59, 0xffff0000, v82
	v_lshlrev_b32_e32 v60, 16, v86
	v_and_b32_e32 v61, 0xffff0000, v86
	v_pk_fma_f32 v[54:55], v[54:55], v[60:61], v[58:59]
	v_lshlrev_b32_e32 v58, 16, v83
	v_and_b32_e32 v59, 0xffff0000, v83
	v_lshlrev_b32_e32 v60, 16, v87
	v_and_b32_e32 v61, 0xffff0000, v87
	v_pk_fma_f32 v[56:57], v[56:57], v[60:61], v[58:59]
	v_lshlrev_b32_e32 v58, 16, v84
	v_and_b32_e32 v59, 0xffff0000, v84
	v_lshlrev_b32_e32 v60, 16, v88
	v_and_b32_e32 v61, 0xffff0000, v88
	v_pk_fma_f32 v[52:53], v[50:51], v[60:61], v[58:59]
	v_add_f32_e32 v50, 1.0, v64
	v_add_f32_e32 v51, 1.0, v65
	v_rcp_f32_e32 v50, v50
	v_rcp_f32_e32 v51, v51
	v_lshlrev_b32_e32 v58, 16, v85
	v_and_b32_e32 v59, 0xffff0000, v85
	v_lshlrev_b32_e32 v60, 16, v89
	v_and_b32_e32 v61, 0xffff0000, v89
	v_pk_fma_f32 v[58:59], v[50:51], v[60:61], v[58:59]
	v_cvt_pk_bf16_f32 v50, v54, v55
	v_cvt_pk_bf16_f32 v51, v56, v57
	v_cvt_pk_bf16_f32 v52, v52, v53
	v_cvt_pk_bf16_f32 v53, v58, v59
	s_and_b64 vcc, exec, s[2:3]
	s_mov_b64 s[18:19], -1
	s_cbranch_vccnz .LBB0_491
	v_mov_b32_e32 v177, v0
	v_lshl_add_u64 v[54:55], v[62:63], 0, v[176:177]
	s_mov_b64 s[18:19], 0
	global_store_dwordx4 v[54:55], v[50:53], off offset:256
.LBB0_491:
	s_andn2_b64 vcc, exec, s[18:19]
	s_cbranch_vccnz .LBB0_493
	v_add_co_u32_e32 v54, vcc, 0x12000, v174
	s_nop 1
	v_addc_co_u32_e32 v55, vcc, 0, v175, vcc
	global_store_dwordx4 v[54:55], v[50:53], off
; __device__ __forceinline__ unsigned cvt_pk_bf16(float lo, float hi) { f32x2_t f = {lo, hi}; bf16x2_t v = __builtin_convertvector(f, bf16x2_t); return __builtin_bit_cast(unsigned, v); }
; __device__ __forceinline__ float bflo(unsigned w) { return __uint_as_float(w << 16); }
; __device__ __forceinline__ float bfhi(unsigned w) { return __uint_as_float(w & 0xffff0000u); }
;     __device__ __forceinline__ void operator()(const f32x4 (&acc)[2][2][4][2], const Unit& u, int wr, int wc, int fr, int fq) const {
;     ...
;                 u32x4 y[2][2], pr[2][2];
; #pragma unroll
;                 for (int mm = 0; mm < 2; ++mm)
; #pragma unroll
;                     for (int bj = 0; bj < 2; ++bj) { const int m = mp * 2 + mm; const size_t off = (size_t)(row0 + ai * HALF + m * 16) * DM + col0;
;                         y[mm][bj] = *(const u32x4*)(yb + off + bj * HALF);
;                         const int slot = (ai * 4 + m) * 2 + bj;
;                         pr[mm][bj] = (u32x4){0u, 0u, 0u, 0u};
;                         if (b > 0) pr[mm][bj] = sc[(size_t)slot * NTHR]; }
; #pragma unroll
;                 for (int mm = 0; mm < 2; ++mm)
; #pragma unroll
;                     for (int bj = 0; bj < 2; ++bj) { const int m = mp * 2 + mm; const size_t off = (size_t)(row0 + ai * HALF + m * 16) * DM + col0;
;                         const u32x4 yy = y[mm][bj], pp = pr[mm][bj];
;                         const f32x4 a0 = acc[ai][bj][m][0], a1 = acc[ai][bj][m][1];
;                         f32x4 r0, r1;
;                         r0[0] = bflo(pp.x) + sigmoidf_(a0[0]) * bflo(yy.x); r0[1] = bfhi(pp.x) + sigmoidf_(a0[1]) * bfhi(yy.x); r0[2] = bflo(pp.y) + sigmoidf_(a0[2]) * bflo(yy.y); r0[3] = bfhi(pp.y) + sigmoidf_(a0[3]) * bfhi(yy.y);
;                         r1[0] = bflo(pp.z) + sigmoidf_(a1[0]) * bflo(yy.z); r1[1] = bfhi(pp.z) + sigmoidf_(a1[1]) * bfhi(yy.z); r1[2] = bflo(pp.w) + sigmoidf_(a1[2]) * bflo(yy.w); r1[3] = bfhi(pp.w) + sigmoidf_(a1[3]) * bfhi(yy.w);
;                         u32x4 w; w.x = cvt_pk_bf16(r0[0], r0[1]); w.y = cvt_pk_bf16(r0[2], r0[3]); w.z = cvt_pk_bf16(r1[0], r1[1]); w.w = cvt_pk_bf16(r1[2], r1[3]);
;                         const int slot = (ai * 4 + m) * 2 + bj;
;                         if (b < 2) sc[(size_t)slot * NTHR] = w;
;                         else *(u32x4*)(merged + off + bj * HALF) = w; }
.LBB0_493:
	v_mul_f32_e32 v46, 0xbfb8aa3b, v46
	v_mul_f32_e32 v47, 0xbfb8aa3b, v47
	v_exp_f32_e32 v46, v46
	v_exp_f32_e32 v47, v47
	v_mul_f32_e32 v48, 0xbfb8aa3b, v48
	v_mul_f32_e32 v49, 0xbfb8aa3b, v49
	v_exp_f32_e32 v48, v48
	v_exp_f32_e32 v49, v49
	v_mul_f32_e32 v42, 0xbfb8aa3b, v42
	v_mul_f32_e32 v43, 0xbfb8aa3b, v43
	v_exp_f32_e32 v42, v42
	v_exp_f32_e32 v43, v43
	v_add_f32_e32 v46, 1.0, v46
	v_add_f32_e32 v47, 1.0, v47
	v_rcp_f32_e32 v46, v46
	v_rcp_f32_e32 v47, v47
	v_add_f32_e32 v48, 1.0, v48
	v_add_f32_e32 v49, 1.0, v49
	v_mul_f32_e32 v44, 0xbfb8aa3b, v44
	v_rcp_f32_e32 v48, v48
	v_rcp_f32_e32 v49, v49
	v_add_f32_e32 v42, 1.0, v42
	v_add_f32_e32 v43, 1.0, v43
	v_exp_f32_e32 v54, v44
	v_mul_f32_e32 v44, 0xbfb8aa3b, v45
	v_rcp_f32_e32 v42, v42
	v_rcp_f32_e32 v43, v43
	v_exp_f32_e32 v55, v44
	v_lshlrev_b32_e32 v50, 16, v78
	v_and_b32_e32 v51, 0xffff0000, v78
	v_lshlrev_b32_e32 v52, 16, v74
	v_and_b32_e32 v53, 0xffff0000, v74
	v_pk_fma_f32 v[46:47], v[46:47], v[52:53], v[50:51]
	v_lshlrev_b32_e32 v50, 16, v79
	v_and_b32_e32 v51, 0xffff0000, v79
	v_lshlrev_b32_e32 v52, 16, v75
	v_and_b32_e32 v53, 0xffff0000, v75
	v_pk_fma_f32 v[48:49], v[48:49], v[52:53], v[50:51]
	v_lshlrev_b32_e32 v50, 16, v80
	v_and_b32_e32 v51, 0xffff0000, v80
	v_lshlrev_b32_e32 v52, 16, v76
	v_and_b32_e32 v53, 0xffff0000, v76
	v_pk_fma_f32 v[44:45], v[42:43], v[52:53], v[50:51]
	v_add_f32_e32 v42, 1.0, v54
	v_add_f32_e32 v43, 1.0, v55
	v_rcp_f32_e32 v42, v42
	v_rcp_f32_e32 v43, v43
	v_lshlrev_b32_e32 v50, 16, v81
	v_and_b32_e32 v51, 0xffff0000, v81
	v_lshlrev_b32_e32 v52, 16, v77
	v_and_b32_e32 v53, 0xffff0000, v77
	v_pk_fma_f32 v[50:51], v[42:43], v[52:53], v[50:51]
	v_cvt_pk_bf16_f32 v42, v46, v47
	v_cvt_pk_bf16_f32 v43, v48, v49
	v_cvt_pk_bf16_f32 v44, v44, v45
	v_cvt_pk_bf16_f32 v45, v50, v51
	s_mov_b64 s[18:19], -1
	s_and_b64 vcc, exec, s[2:3]
	v_lshl_add_u64 v[46:47], s[8:9], 0, v[98:99]
	s_cbranch_vccnz .LBB0_495
	v_mov_b32_e32 v177, v0
	v_lshl_add_u64 v[48:49], v[46:47], 0, v[176:177]
	s_mov_b64 s[18:19], 0
	global_store_dwordx4 v[48:49], v[42:45], off
.LBB0_495:
	s_andn2_b64 vcc, exec, s[18:19]
	s_cbranch_vccnz .LBB0_497
	v_add_co_u32_e32 v48, vcc, 0x14000, v174
	s_nop 1
	v_addc_co_u32_e32 v49, vcc, 0, v175, vcc
	global_store_dwordx4 v[48:49], v[42:45], off
.LBB0_497:
	v_mul_f32_e32 v38, 0xbfb8aa3b, v38
	v_mul_f32_e32 v39, 0xbfb8aa3b, v39
	v_exp_f32_e32 v38, v38
	v_exp_f32_e32 v39, v39
	v_mul_f32_e32 v40, 0xbfb8aa3b, v40
	v_mul_f32_e32 v41, 0xbfb8aa3b, v41
	v_exp_f32_e32 v40, v40
	v_exp_f32_e32 v41, v41
	v_mul_f32_e32 v34, 0xbfb8aa3b, v34
	v_mul_f32_e32 v35, 0xbfb8aa3b, v35
	v_exp_f32_e32 v34, v34
	v_exp_f32_e32 v35, v35
	v_add_f32_e32 v38, 1.0, v38
	v_add_f32_e32 v39, 1.0, v39
	v_rcp_f32_e32 v38, v38
	v_rcp_f32_e32 v39, v39
	v_add_f32_e32 v40, 1.0, v40
	v_add_f32_e32 v41, 1.0, v41
	v_mul_f32_e32 v36, 0xbfb8aa3b, v36
	v_rcp_f32_e32 v40, v40
	v_rcp_f32_e32 v41, v41
	v_add_f32_e32 v34, 1.0, v34
	v_add_f32_e32 v35, 1.0, v35
	v_exp_f32_e32 v48, v36
	v_mul_f32_e32 v36, 0xbfb8aa3b, v37
	v_rcp_f32_e32 v34, v34
	v_rcp_f32_e32 v35, v35
	v_exp_f32_e32 v49, v36
	v_lshlrev_b32_e32 v42, 16, v66
	v_and_b32_e32 v43, 0xffff0000, v66
	v_lshlrev_b32_e32 v44, 16, v70
	v_and_b32_e32 v45, 0xffff0000, v70
	v_pk_fma_f32 v[38:39], v[38:39], v[44:45], v[42:43]
	v_lshlrev_b32_e32 v42, 16, v67
	v_and_b32_e32 v43, 0xffff0000, v67
	v_lshlrev_b32_e32 v44, 16, v71
	v_and_b32_e32 v45, 0xffff0000, v71
	v_pk_fma_f32 v[40:41], v[40:41], v[44:45], v[42:43]
	v_lshlrev_b32_e32 v42, 16, v68
	v_and_b32_e32 v43, 0xffff0000, v68
	v_lshlrev_b32_e32 v44, 16, v72
	v_and_b32_e32 v45, 0xffff0000, v72
	v_pk_fma_f32 v[36:37], v[34:35], v[44:45], v[42:43]
	v_add_f32_e32 v34, 1.0, v48
	v_add_f32_e32 v35, 1.0, v49
	v_rcp_f32_e32 v34, v34
	v_rcp_f32_e32 v35, v35
	v_lshlrev_b32_e32 v42, 16, v69
	v_and_b32_e32 v43, 0xffff0000, v69
	v_lshlrev_b32_e32 v44, 16, v73
	v_and_b32_e32 v45, 0xffff0000, v73
	v_pk_fma_f32 v[42:43], v[34:35], v[44:45], v[42:43]
	v_cvt_pk_bf16_f32 v34, v38, v39
	v_cvt_pk_bf16_f32 v35, v40, v41
	v_cvt_pk_bf16_f32 v36, v36, v37
	v_cvt_pk_bf16_f32 v37, v42, v43
	s_and_b64 vcc, exec, s[2:3]
	s_mov_b64 s[18:19], -1
	s_cbranch_vccnz .LBB0_499
	v_mov_b32_e32 v177, v0
	v_lshl_add_u64 v[38:39], v[46:47], 0, v[176:177]
	s_mov_b64 s[18:19], 0
	global_store_dwordx4 v[38:39], v[34:37], off offset:256
.LBB0_499:
	s_andn2_b64 vcc, exec, s[18:19]
	s_cbranch_vccnz .LBB0_501
	v_add_co_u32_e32 v38, vcc, 0x16000, v174
	s_nop 1
	v_addc_co_u32_e32 v39, vcc, 0, v175, vcc
	global_store_dwordx4 v[38:39], v[34:37], off
.LBB0_501:
	s_nop 1
	v_lshlrev_b64 v[34:35], 12, v[178:179]
	s_mov_b64 s[18:19], 0xa0000
	v_lshl_add_u64 v[68:69], v[34:35], 0, s[18:19]
	v_lshl_add_u64 v[34:35], v[180:181], 0, v[68:69]
	global_load_dwordx4 v[58:61], v[34:35], off
	v_mov_b32_e32 v50, 0
	s_and_b64 vcc, exec, s[4:5]
	v_mov_b32_e32 v62, 0
	v_mov_b32_e32 v63, 0
	v_mov_b32_e32 v64, 0
	v_mov_b32_e32 v65, 0
	s_cbranch_vccnz .LBB0_503
	v_add_co_u32_e32 v36, vcc, 0x18000, v174
	s_nop 1
	v_addc_co_u32_e32 v37, vcc, 0, v175, vcc
	global_load_dwordx4 v[62:65], v[36:37], off
.LBB0_503:
	global_load_dwordx4 v[54:57], v[34:35], off offset:256
	s_and_b64 vcc, exec, s[4:5]
	v_mov_b32_e32 v51, 0
	v_mov_b32_e32 v52, 0
	v_mov_b32_e32 v53, 0
	s_cbranch_vccnz .LBB0_505
	v_add_co_u32_e32 v34, vcc, 0x1a000, v174
	s_nop 1
	v_addc_co_u32_e32 v35, vcc, 0, v175, vcc
	global_load_dwordx4 v[50:53], v[34:35], off
; __device__ __forceinline__ unsigned cvt_pk_bf16(float lo, float hi) { f32x2_t f = {lo, hi}; bf16x2_t v = __builtin_convertvector(f, bf16x2_t); return __builtin_bit_cast(unsigned, v); }
; __device__ __forceinline__ float bflo(unsigned w) { return __uint_as_float(w << 16); }
; __device__ __forceinline__ float bfhi(unsigned w) { return __uint_as_float(w & 0xffff0000u); }
;     __device__ __forceinline__ void operator()(const f32x4 (&acc)[2][2][4][2], const Unit& u, int wr, int wc, int fr, int fq) const {
;     ...
;                 u32x4 y[2][2], pr[2][2];
; #pragma unroll
;                 for (int mm = 0; mm < 2; ++mm)
; #pragma unroll
;                     for (int bj = 0; bj < 2; ++bj) { const int m = mp * 2 + mm; const size_t off = (size_t)(row0 + ai * HALF + m * 16) * DM + col0;
;                         y[mm][bj] = *(const u32x4*)(yb + off + bj * HALF);
;                         const int slot = (ai * 4 + m) * 2 + bj;
;                         pr[mm][bj] = (u32x4){0u, 0u, 0u, 0u};
;                         if (b > 0) pr[mm][bj] = sc[(size_t)slot * NTHR]; }
; #pragma unroll
;                 for (int mm = 0; mm < 2; ++mm)
; #pragma unroll
;                     for (int bj = 0; bj < 2; ++bj) { const int m = mp * 2 + mm; const size_t off = (size_t)(row0 + ai * HALF + m * 16) * DM + col0;
;                         const u32x4 yy = y[mm][bj], pp = pr[mm][bj];
;                         const f32x4 a0 = acc[ai][bj][m][0], a1 = acc[ai][bj][m][1];
;                         f32x4 r0, r1;
;                         r0[0] = bflo(pp.x) + sigmoidf_(a0[0]) * bflo(yy.x); r0[1] = bfhi(pp.x) + sigmoidf_(a0[1]) * bfhi(yy.x); r0[2] = bflo(pp.y) + sigmoidf_(a0[2]) * bflo(yy.y); r0[3] = bfhi(pp.y) + sigmoidf_(a0[3]) * bfhi(yy.y);
;                         r1[0] = bflo(pp.z) + sigmoidf_(a1[0]) * bflo(yy.z); r1[1] = bfhi(pp.z) + sigmoidf_(a1[1]) * bfhi(yy.z); r1[2] = bflo(pp.w) + sigmoidf_(a1[2]) * bflo(yy.w); r1[3] = bfhi(pp.w) + sigmoidf_(a1[3]) * bfhi(yy.w);
;                         u32x4 w; w.x = cvt_pk_bf16(r0[0], r0[1]); w.y = cvt_pk_bf16(r0[2], r0[3]); w.z = cvt_pk_bf16(r1[0], r1[1]); w.w = cvt_pk_bf16(r1[2], r1[3]);
;                         const int slot = (ai * 4 + m) * 2 + bj;
;                         if (b < 2) sc[(size_t)slot * NTHR] = w;
;                         else *(u32x4*)(merged + off + bj * HALF) = w; }
.LBB0_505:
	v_lshlrev_b64 v[34:35], 12, v[178:179]
	s_mov_b64 s[18:19], 0xb0000
	v_lshl_add_u64 v[66:67], v[34:35], 0, s[18:19]
	v_lshl_add_u64 v[36:37], v[180:181], 0, v[66:67]
	global_load_dwordx4 v[42:45], v[36:37], off
	v_mov_b32_e32 v34, 0
	s_and_b64 vcc, exec, s[4:5]
	v_mov_b32_e32 v46, 0
	v_mov_b32_e32 v47, 0
	v_mov_b32_e32 v48, 0
	v_mov_b32_e32 v49, 0
	s_cbranch_vccnz .LBB0_507
	v_add_co_u32_e32 v38, vcc, 0x1c000, v174
	s_nop 1
	v_addc_co_u32_e32 v39, vcc, 0, v175, vcc
	global_load_dwordx4 v[46:49], v[38:39], off
.LBB0_507:
	s_nop 0
	global_load_dwordx4 v[38:41], v[36:37], off offset:256
	s_and_b64 vcc, exec, s[4:5]
	v_mov_b32_e32 v35, 0
	v_mov_b32_e32 v36, 0
	v_mov_b32_e32 v37, 0
	s_cbranch_vccnz .LBB0_509
	v_add_co_u32_e32 v34, vcc, 0x1e000, v174
	s_nop 1
	v_addc_co_u32_e32 v35, vcc, 0, v175, vcc
	global_load_dwordx4 v[34:37], v[34:35], off
.LBB0_509:
	v_mul_f32_e32 v32, 0xbfb8aa3b, v32
	v_mul_f32_e32 v33, 0xbfb8aa3b, v33
	v_exp_f32_e32 v32, v32
	v_exp_f32_e32 v33, v33
	v_mul_f32_e32 v26, 0xbfb8aa3b, v26
	v_mul_f32_e32 v27, 0xbfb8aa3b, v27
	v_add_f32_e32 v32, 1.0, v32
	v_add_f32_e32 v33, 1.0, v33
	v_rcp_f32_e32 v32, v32
	v_rcp_f32_e32 v33, v33
	v_exp_f32_e32 v26, v26
	v_exp_f32_e32 v27, v27
	s_waitcnt vmcnt(0) lgkmcnt(0)
	v_lshlrev_b32_e32 v70, 16, v62
	v_and_b32_e32 v71, 0xffff0000, v62
	v_lshlrev_b32_e32 v72, 16, v58
	v_and_b32_e32 v73, 0xffff0000, v58
	v_lshlrev_b32_e32 v62, 16, v63
	v_and_b32_e32 v63, 0xffff0000, v63
	v_lshlrev_b32_e32 v58, 16, v59
	v_and_b32_e32 v59, 0xffff0000, v59
	v_mul_f32_e32 v28, 0xbfb8aa3b, v28
	v_mul_f32_e32 v30, 0xbfb8aa3b, v30
	v_mul_f32_e32 v31, 0xbfb8aa3b, v31
	v_pk_fma_f32 v[32:33], v[32:33], v[58:59], v[62:63]
	v_add_f32_e32 v26, 1.0, v26
	v_add_f32_e32 v27, 1.0, v27
	v_lshlrev_b32_e32 v62, 16, v60
	v_and_b32_e32 v63, 0xffff0000, v60
	v_exp_f32_e32 v60, v28
	v_mul_f32_e32 v28, 0xbfb8aa3b, v29
	v_exp_f32_e32 v30, v30
	v_exp_f32_e32 v31, v31
	v_rcp_f32_e32 v26, v26
	v_rcp_f32_e32 v27, v27
	v_lshlrev_b32_e32 v58, 16, v64
	v_and_b32_e32 v59, 0xffff0000, v64
	v_exp_f32_e32 v64, v28
	v_add_f32_e32 v30, 1.0, v30
	v_add_f32_e32 v31, 1.0, v31
	v_pk_fma_f32 v[28:29], v[26:27], v[62:63], v[58:59]
	v_add_f32_e32 v26, 1.0, v60
	v_add_f32_e32 v27, 1.0, v64
	v_rcp_f32_e32 v30, v30
	v_rcp_f32_e32 v31, v31
	v_rcp_f32_e32 v26, v26
	v_rcp_f32_e32 v27, v27
	v_lshlrev_b32_e32 v58, 16, v65
	v_and_b32_e32 v59, 0xffff0000, v65
	v_lshlrev_b32_e32 v60, 16, v61
	v_and_b32_e32 v61, 0xffff0000, v61
	v_pk_fma_f32 v[30:31], v[30:31], v[72:73], v[70:71]
	v_pk_fma_f32 v[58:59], v[26:27], v[60:61], v[58:59]
	v_cvt_pk_bf16_f32 v26, v30, v31
	v_cvt_pk_bf16_f32 v27, v32, v33
	v_cvt_pk_bf16_f32 v28, v28, v29
	v_cvt_pk_bf16_f32 v29, v58, v59
	s_mov_b64 s[4:5], -1
	s_and_b64 vcc, exec, s[2:3]
	v_lshl_add_u64 v[30:31], s[8:9], 0, v[68:69]
	s_cbranch_vccnz .LBB0_511
	v_mov_b32_e32 v177, v0
	v_lshl_add_u64 v[32:33], v[30:31], 0, v[176:177]
	s_mov_b64 s[4:5], 0
	global_store_dwordx4 v[32:33], v[26:29], off
.LBB0_511:
	s_andn2_b64 vcc, exec, s[4:5]
	s_cbranch_vccnz .LBB0_513
	v_add_co_u32_e32 v32, vcc, 0x18000, v174
	s_nop 1
	v_addc_co_u32_e32 v33, vcc, 0, v175, vcc
	global_store_dwordx4 v[32:33], v[26:29], off
.LBB0_513:
	v_mul_f32_e32 v22, 0xbfb8aa3b, v22
	v_mul_f32_e32 v23, 0xbfb8aa3b, v23
	v_exp_f32_e32 v22, v22
	v_exp_f32_e32 v23, v23
	v_mul_f32_e32 v24, 0xbfb8aa3b, v24
	v_mul_f32_e32 v25, 0xbfb8aa3b, v25
	v_exp_f32_e32 v24, v24
	v_exp_f32_e32 v25, v25
	v_mul_f32_e32 v18, 0xbfb8aa3b, v18
	v_mul_f32_e32 v19, 0xbfb8aa3b, v19
	v_exp_f32_e32 v18, v18
	v_exp_f32_e32 v19, v19
	v_add_f32_e32 v22, 1.0, v22
	v_add_f32_e32 v23, 1.0, v23
	v_rcp_f32_e32 v22, v22
	v_rcp_f32_e32 v23, v23
	v_add_f32_e32 v24, 1.0, v24
	v_add_f32_e32 v25, 1.0, v25
	v_mul_f32_e32 v20, 0xbfb8aa3b, v20
	v_rcp_f32_e32 v24, v24
	v_rcp_f32_e32 v25, v25
	v_add_f32_e32 v18, 1.0, v18
	v_add_f32_e32 v19, 1.0, v19
	v_exp_f32_e32 v32, v20
	v_mul_f32_e32 v20, 0xbfb8aa3b, v21
	v_rcp_f32_e32 v18, v18
	v_rcp_f32_e32 v19, v19
	v_exp_f32_e32 v33, v20
	v_lshlrev_b32_e32 v26, 16, v50
	v_and_b32_e32 v27, 0xffff0000, v50
	v_lshlrev_b32_e32 v28, 16, v54
	v_and_b32_e32 v29, 0xffff0000, v54
	v_pk_fma_f32 v[22:23], v[22:23], v[28:29], v[26:27]
	v_lshlrev_b32_e32 v26, 16, v51
	v_and_b32_e32 v27, 0xffff0000, v51
	v_lshlrev_b32_e32 v28, 16, v55
	v_and_b32_e32 v29, 0xffff0000, v55
	v_pk_fma_f32 v[24:25], v[24:25], v[28:29], v[26:27]
	v_lshlrev_b32_e32 v26, 16, v52
	v_and_b32_e32 v27, 0xffff0000, v52
	v_lshlrev_b32_e32 v28, 16, v56
	v_and_b32_e32 v29, 0xffff0000, v56
	v_pk_fma_f32 v[20:21], v[18:19], v[28:29], v[26:27]
	v_add_f32_e32 v18, 1.0, v32
	v_add_f32_e32 v19, 1.0, v33
	v_rcp_f32_e32 v18, v18
	v_rcp_f32_e32 v19, v19
	v_lshlrev_b32_e32 v26, 16, v53
	v_and_b32_e32 v27, 0xffff0000, v53
	v_lshlrev_b32_e32 v28, 16, v57
	v_and_b32_e32 v29, 0xffff0000, v57
	v_pk_fma_f32 v[26:27], v[18:19], v[28:29], v[26:27]
	v_cvt_pk_bf16_f32 v18, v22, v23
	v_cvt_pk_bf16_f32 v19, v24, v25
	v_cvt_pk_bf16_f32 v20, v20, v21
	v_cvt_pk_bf16_f32 v21, v26, v27
	s_and_b64 vcc, exec, s[2:3]
	s_mov_b64 s[4:5], -1
	s_cbranch_vccnz .LBB0_515
	v_mov_b32_e32 v177, v0
	v_lshl_add_u64 v[22:23], v[30:31], 0, v[176:177]
	s_mov_b64 s[4:5], 0
	global_store_dwordx4 v[22:23], v[18:21], off offset:256
; __device__ __forceinline__ unsigned cvt_pk_bf16(float lo, float hi) { f32x2_t f = {lo, hi}; bf16x2_t v = __builtin_convertvector(f, bf16x2_t); return __builtin_bit_cast(unsigned, v); }
; __device__ __forceinline__ float bflo(unsigned w) { return __uint_as_float(w << 16); }
; __device__ __forceinline__ float bfhi(unsigned w) { return __uint_as_float(w & 0xffff0000u); }
; __device__ __forceinline__ float sigmoidf_(float x) { return __builtin_amdgcn_rcpf(1.0f + __expf(-x)); }
;     __device__ __forceinline__ void operator()(const f32x4 (&acc)[2][2][4][2], const Unit& u, int wr, int wc, int fr, int fq) const {
;     ...
; #pragma unroll
;                 for (int mm = 0; mm < 2; ++mm)
; #pragma unroll
;                     for (int bj = 0; bj < 2; ++bj) { const int m = mp * 2 + mm; const size_t off = (size_t)(row0 + ai * HALF + m * 16) * DM + col0;
;                         const u32x4 yy = y[mm][bj], pp = pr[mm][bj];
;                         const f32x4 a0 = acc[ai][bj][m][0], a1 = acc[ai][bj][m][1];
;                         f32x4 r0, r1;
;                         r0[0] = bflo(pp.x) + sigmoidf_(a0[0]) * bflo(yy.x); r0[1] = bfhi(pp.x) + sigmoidf_(a0[1]) * bfhi(yy.x); r0[2] = bflo(pp.y) + sigmoidf_(a0[2]) * bflo(yy.y); r0[3] = bfhi(pp.y) + sigmoidf_(a0[3]) * bfhi(yy.y);
;                         r1[0] = bflo(pp.z) + sigmoidf_(a1[0]) * bflo(yy.z); r1[1] = bfhi(pp.z) + sigmoidf_(a1[1]) * bfhi(yy.z); r1[2] = bflo(pp.w) + sigmoidf_(a1[2]) * bflo(yy.w); r1[3] = bfhi(pp.w) + sigmoidf_(a1[3]) * bfhi(yy.w);
;                         u32x4 w; w.x = cvt_pk_bf16(r0[0], r0[1]); w.y = cvt_pk_bf16(r0[2], r0[3]); w.z = cvt_pk_bf16(r1[0], r1[1]); w.w = cvt_pk_bf16(r1[2], r1[3]);
;                         const int slot = (ai * 4 + m) * 2 + bj;
;                         if (b < 2) sc[(size_t)slot * NTHR] = w;
;                         else *(u32x4*)(merged + off + bj * HALF) = w; }
;                 asm volatile("" ::: "memory");
;             }
.LBB0_515:
	s_andn2_b64 vcc, exec, s[4:5]
	s_cbranch_vccnz .LBB0_517
	v_add_co_u32_e32 v22, vcc, 0x1a000, v174
	s_nop 1
	v_addc_co_u32_e32 v23, vcc, 0, v175, vcc
	global_store_dwordx4 v[22:23], v[18:21], off
.LBB0_517:
	v_mul_f32_e32 v14, 0xbfb8aa3b, v14
	v_mul_f32_e32 v15, 0xbfb8aa3b, v15
	v_exp_f32_e32 v14, v14
	v_exp_f32_e32 v15, v15
	v_mul_f32_e32 v16, 0xbfb8aa3b, v16
	v_mul_f32_e32 v17, 0xbfb8aa3b, v17
	v_exp_f32_e32 v16, v16
	v_exp_f32_e32 v17, v17
	v_mul_f32_e32 v10, 0xbfb8aa3b, v10
	v_mul_f32_e32 v11, 0xbfb8aa3b, v11
	v_exp_f32_e32 v10, v10
	v_exp_f32_e32 v11, v11
	v_add_f32_e32 v14, 1.0, v14
	v_add_f32_e32 v15, 1.0, v15
	v_rcp_f32_e32 v14, v14
	v_rcp_f32_e32 v15, v15
	v_add_f32_e32 v16, 1.0, v16
	v_add_f32_e32 v17, 1.0, v17
	v_mul_f32_e32 v12, 0xbfb8aa3b, v12
	v_rcp_f32_e32 v16, v16
	v_rcp_f32_e32 v17, v17
	v_add_f32_e32 v10, 1.0, v10
	v_add_f32_e32 v11, 1.0, v11
	v_exp_f32_e32 v22, v12
	v_mul_f32_e32 v12, 0xbfb8aa3b, v13
	v_rcp_f32_e32 v10, v10
	v_rcp_f32_e32 v11, v11
	v_exp_f32_e32 v23, v12
	v_lshlrev_b32_e32 v18, 16, v46
	v_and_b32_e32 v19, 0xffff0000, v46
	v_lshlrev_b32_e32 v20, 16, v42
	v_and_b32_e32 v21, 0xffff0000, v42
	v_pk_fma_f32 v[14:15], v[14:15], v[20:21], v[18:19]
	v_lshlrev_b32_e32 v18, 16, v47
	v_and_b32_e32 v19, 0xffff0000, v47
	v_lshlrev_b32_e32 v20, 16, v43
	v_and_b32_e32 v21, 0xffff0000, v43
	v_pk_fma_f32 v[16:17], v[16:17], v[20:21], v[18:19]
	v_lshlrev_b32_e32 v18, 16, v48
	v_and_b32_e32 v19, 0xffff0000, v48
	v_lshlrev_b32_e32 v20, 16, v44
	v_and_b32_e32 v21, 0xffff0000, v44
	v_pk_fma_f32 v[12:13], v[10:11], v[20:21], v[18:19]
	v_add_f32_e32 v10, 1.0, v22
	v_add_f32_e32 v11, 1.0, v23
	v_rcp_f32_e32 v10, v10
	v_rcp_f32_e32 v11, v11
	v_lshlrev_b32_e32 v18, 16, v49
	v_and_b32_e32 v19, 0xffff0000, v49
	v_lshlrev_b32_e32 v20, 16, v45
	v_and_b32_e32 v21, 0xffff0000, v45
	v_pk_fma_f32 v[18:19], v[10:11], v[20:21], v[18:19]
	v_cvt_pk_bf16_f32 v10, v14, v15
	v_cvt_pk_bf16_f32 v11, v16, v17
	v_cvt_pk_bf16_f32 v12, v12, v13
	v_cvt_pk_bf16_f32 v13, v18, v19
	s_mov_b64 s[4:5], -1
	s_and_b64 vcc, exec, s[2:3]
	v_lshl_add_u64 v[14:15], s[8:9], 0, v[66:67]
	s_cbranch_vccnz .LBB0_519
	v_mov_b32_e32 v177, v0
	v_lshl_add_u64 v[16:17], v[14:15], 0, v[176:177]
	s_mov_b64 s[4:5], 0
	global_store_dwordx4 v[16:17], v[10:13], off
.LBB0_519:
	s_andn2_b64 vcc, exec, s[4:5]
	s_cbranch_vccnz .LBB0_521
	v_add_co_u32_e32 v16, vcc, 0x1c000, v174
	s_nop 1
	v_addc_co_u32_e32 v17, vcc, 0, v175, vcc
	global_store_dwordx4 v[16:17], v[10:13], off
.LBB0_521:
	v_mul_f32_e32 v6, 0xbfb8aa3b, v6
	v_mul_f32_e32 v7, 0xbfb8aa3b, v7
	v_exp_f32_e32 v6, v6
	v_exp_f32_e32 v7, v7
	v_mul_f32_e32 v8, 0xbfb8aa3b, v8
	v_mul_f32_e32 v9, 0xbfb8aa3b, v9
	v_exp_f32_e32 v8, v8
	v_exp_f32_e32 v9, v9
	v_mul_f32_e32 v2, 0xbfb8aa3b, v2
	v_mul_f32_e32 v3, 0xbfb8aa3b, v3
	v_exp_f32_e32 v2, v2
	v_exp_f32_e32 v3, v3
	v_add_f32_e32 v6, 1.0, v6
	v_add_f32_e32 v7, 1.0, v7
	v_rcp_f32_e32 v6, v6
	v_rcp_f32_e32 v7, v7
	v_add_f32_e32 v8, 1.0, v8
	v_add_f32_e32 v9, 1.0, v9
	v_mul_f32_e32 v4, 0xbfb8aa3b, v4
	v_rcp_f32_e32 v8, v8
	v_rcp_f32_e32 v9, v9
	v_add_f32_e32 v2, 1.0, v2
	v_add_f32_e32 v3, 1.0, v3
	v_exp_f32_e32 v16, v4
	v_mul_f32_e32 v4, 0xbfb8aa3b, v5
	v_rcp_f32_e32 v2, v2
	v_rcp_f32_e32 v3, v3
	v_exp_f32_e32 v17, v4
	v_lshlrev_b32_e32 v10, 16, v34
	v_and_b32_e32 v11, 0xffff0000, v34
	v_lshlrev_b32_e32 v12, 16, v38
	v_and_b32_e32 v13, 0xffff0000, v38
	v_pk_fma_f32 v[6:7], v[6:7], v[12:13], v[10:11]
	v_lshlrev_b32_e32 v10, 16, v35
	v_and_b32_e32 v11, 0xffff0000, v35
	v_lshlrev_b32_e32 v12, 16, v39
	v_and_b32_e32 v13, 0xffff0000, v39
	v_pk_fma_f32 v[8:9], v[8:9], v[12:13], v[10:11]
	v_lshlrev_b32_e32 v10, 16, v36
	v_and_b32_e32 v11, 0xffff0000, v36
	v_lshlrev_b32_e32 v12, 16, v40
	v_and_b32_e32 v13, 0xffff0000, v40
	v_pk_fma_f32 v[4:5], v[2:3], v[12:13], v[10:11]
	v_add_f32_e32 v2, 1.0, v16
	v_add_f32_e32 v3, 1.0, v17
	v_rcp_f32_e32 v2, v2
	v_rcp_f32_e32 v3, v3
	v_lshlrev_b32_e32 v10, 16, v37
	v_and_b32_e32 v11, 0xffff0000, v37
	v_lshlrev_b32_e32 v12, 16, v41
	v_and_b32_e32 v13, 0xffff0000, v41
	v_pk_fma_f32 v[10:11], v[2:3], v[12:13], v[10:11]
	v_cvt_pk_bf16_f32 v2, v6, v7
	v_cvt_pk_bf16_f32 v3, v8, v9
	v_cvt_pk_bf16_f32 v4, v4, v5
	v_cvt_pk_bf16_f32 v5, v10, v11
	s_and_b64 vcc, exec, s[2:3]
	s_mov_b64 s[2:3], -1
	s_cbranch_vccnz .LBB0_523
	v_mov_b32_e32 v177, v0
	v_lshl_add_u64 v[6:7], v[14:15], 0, v[176:177]
	s_mov_b64 s[2:3], 0
	global_store_dwordx4 v[6:7], v[2:5], off offset:256
.LBB0_523:
	s_andn2_b64 vcc, exec, s[2:3]
	s_cbranch_vccnz .LBB0_418
	v_add_co_u32_e32 v6, vcc, 0x1e000, v174
	s_nop 1
	v_addc_co_u32_e32 v7, vcc, 0, v175, vcc
	global_store_dwordx4 v[6:7], v[2:5], off
	s_branch .LBB0_418

;     __device__ __forceinline__ void operator()(const f32x4 (&acc)[2][2][4][2], const Unit& u, int wr, int wc, int fr, int fq) const {
;     ...
;                 for (int n = 0; n < 2; ++n) {
;                     const int cofs = bj * HALF + n * 16;
;                     const f32x4 g4 = *(const f32x4*)(gv + cofs) + 1.0f;
;                     f32x4 lg = {1.f, 1.f, 1.f, 1.f}, lb = {0.f, 0.f, 0.f, 0.f};
;                     if (stats) { lg = *(const f32x4*)(lng + col0 + cofs); lb = *(const f32x4*)(lnb + col0 + cofs); }
; #pragma unroll
;                     for (int m = 0; m < 4; ++m) { const f32x4 x = (xv[n][m] - mu[m]) * rs[m] * lg + lb;
;                         *(f32x4*)(out + (size_t)(row0 + ai * HALF + m * 16) * DM + col0 + cofs) = x * ALPHA + g4 * acc[ai][bj][m][n]; }
;                 }
.LBB0_544:
	v_sub_f32_e32 v23, v57, v124
	v_sub_f32_e32 v22, v56, v124
	v_sub_f32_e32 v25, v55, v124
	v_sub_f32_e32 v24, v54, v124
	v_mov_b32_e32 v26, v120
	v_mov_b32_e32 v27, v120
	v_pk_mul_f32 v[24:25], v[100:101], v[24:25]
	v_pk_mul_f32 v[22:23], v[26:27], v[22:23]
	s_waitcnt vmcnt(0) lgkmcnt(0)
	v_pk_fma_f32 v[24:25], v[24:25], v[34:35], v[38:39]
	v_pk_fma_f32 v[22:23], v[22:23], v[36:37], v[40:41]
	v_pk_add_f32 v[20:21], v[20:21], 1.0 op_sel_hi:[1,0]
	v_pk_add_f32 v[18:19], v[18:19], 1.0 op_sel_hi:[1,0]
	v_pk_mul_f32 v[24:25], v[24:25], s[64:65] op_sel_hi:[1,0]
	v_pk_mul_f32 v[22:23], v[22:23], s[64:65] op_sel_hi:[1,0]
	v_pk_fma_f32 v[14:15], v[14:15], v[18:19], v[24:25]
	v_pk_fma_f32 v[16:17], v[16:17], v[20:21], v[22:23]
	global_store_dwordx4 v[112:113], v[14:17], off offset:576
	v_mov_b32_e32 v120, v121
	s_and_b64 vcc, exec, s[0:1]
	v_sub_f32_e32 v15, v53, v1
	v_sub_f32_e32 v14, v52, v1
	v_sub_f32_e32 v17, v51, v1
	v_sub_f32_e32 v16, v50, v1
	v_pk_mul_f32 v[16:17], v[98:99], v[16:17]
	v_pk_mul_f32 v[14:15], v[120:121], v[14:15]
	v_pk_fma_f32 v[16:17], v[16:17], v[34:35], v[38:39]
	v_pk_fma_f32 v[14:15], v[14:15], v[36:37], v[40:41]
	v_pk_mul_f32 v[16:17], v[16:17], s[64:65] op_sel_hi:[1,0]
	v_pk_mul_f32 v[14:15], v[14:15], s[64:65] op_sel_hi:[1,0]
	v_pk_fma_f32 v[10:11], v[10:11], v[18:19], v[16:17]
	v_pk_fma_f32 v[12:13], v[12:13], v[20:21], v[14:15]
	global_store_dwordx4 v[108:109], v[10:13], off offset:576
	v_mov_b32_e32 v14, v122
	v_mov_b32_e32 v15, v122
	v_sub_f32_e32 v11, v49, v66
	v_sub_f32_e32 v10, v48, v66
	v_sub_f32_e32 v13, v47, v66
	v_sub_f32_e32 v12, v46, v66
	v_pk_mul_f32 v[12:13], v[96:97], v[12:13]
	v_pk_mul_f32 v[10:11], v[14:15], v[10:11]
	v_pk_fma_f32 v[12:13], v[12:13], v[34:35], v[38:39]
	v_pk_fma_f32 v[10:11], v[10:11], v[36:37], v[40:41]
	v_pk_mul_f32 v[12:13], v[12:13], s[64:65] op_sel_hi:[1,0]
	v_pk_mul_f32 v[10:11], v[10:11], s[64:65] op_sel_hi:[1,0]
	v_pk_fma_f32 v[6:7], v[6:7], v[18:19], v[12:13]
	v_pk_fma_f32 v[8:9], v[8:9], v[20:21], v[10:11]
	global_store_dwordx4 v[104:105], v[6:9], off offset:576
	v_mov_b32_e32 v122, v123
	s_mov_b32 s30, s20
	v_sub_f32_e32 v7, v45, v67
	v_sub_f32_e32 v6, v44, v67
	v_sub_f32_e32 v9, v43, v67
	v_sub_f32_e32 v8, v42, v67
	v_pk_mul_f32 v[8:9], v[94:95], v[8:9]
	v_pk_mul_f32 v[6:7], v[122:123], v[6:7]
	v_pk_fma_f32 v[8:9], v[8:9], v[34:35], v[38:39]
	v_pk_fma_f32 v[6:7], v[6:7], v[36:37], v[40:41]
	v_pk_mul_f32 v[8:9], v[8:9], s[64:65] op_sel_hi:[1,0]
	v_pk_mul_f32 v[6:7], v[6:7], s[64:65] op_sel_hi:[1,0]
	v_pk_fma_f32 v[2:3], v[2:3], v[18:19], v[8:9]
	v_pk_fma_f32 v[4:5], v[4:5], v[20:21], v[6:7]
	global_store_dwordx4 v[92:93], v[2:5], off offset:576
	s_mov_b32 s28, s22
	s_mov_b64 s[34:35], s[26:27]
	s_mov_b64 s[2:3], s[24:25]
	s_cbranch_vccnz .LBB0_587

; #define PG8_STAGE(bufoff, gbase, voff) do { _Pragma("unroll") for (int _i = 0; _i < 2; ++_i) \
;         __builtin_amdgcn_global_load_lds((const unsigned*)((const char*)(gbase) + (voff)[_i]), (LAS unsigned*)(lds + (bufoff) + ldsw + _i * 8192), 16, 0, 0); } while (0)
; #define PG8_LDA(dst, b, h) do { _Pragma("unroll") for (int m = 0; m < 4; ++m) _Pragma("unroll") for (int k = 0; k < 2; ++k) dst[m][k] = *(const LAS bf16x8*)(lds + PG8_SA(b, h) + aoff + m * 2048 + k * 1024); } while (0)
; #define PG8_LDB(dst, b, h) do { _Pragma("unroll") for (int n = 0; n < 2; ++n) _Pragma("unroll") for (int k = 0; k < 2; ++k) dst[n][k] = *(const LAS bf16x8*)(lds + PG8_SB(b, h) + boff + n * 2048 + k * 1024); } while (0)
; #define PG8_MMA(ai, bj, At, Bt) do { __builtin_amdgcn_s_setprio(1); _Pragma("unroll") for (int m = 0; m < 4; ++m) _Pragma("unroll") for (int n = 0; n < 2; ++n) _Pragma("unroll") for (int k = 0; k < 2; ++k) \
;         acc[ai][bj][m][n] = __builtin_amdgcn_mfma_f32_16x16x32_bf16(Bt[n][k], At[m][k], acc[ai][bj][m][n], 0, 0, 0); __builtin_amdgcn_s_setprio(0); } while (0)
; #define PG8_WAIT_V(n) asm volatile("s_waitcnt vmcnt(" #n ")" ::: "memory")
; #define PG8_WAIT_L(n) asm volatile("s_waitcnt lgkmcnt(" #n ")" ::: "memory")
; #define PG8_BAR __builtin_amdgcn_s_barrier()
; #define PG8_SCHED __builtin_amdgcn_sched_barrier(0)
; template <class Epi, class Sched, bool AREMAP>
; __device__ __forceinline__ void gemm_phase(LAS unsigned char* lds, const Gemm g, const Sched& S, const Epi& E, int wv) {
;     ...
;             PG8_LDB(B0, 0, 0); PG8_SCHED; PG8_LDA(At, 0, 0); PG8_STAGE(PG8_SA(1, 1), a1 + hstepA, voffA);
;             PG8_WAIT_L(8); PG8_BAR; PG8_WAIT_L(0); PG8_MMA(0, 0, At, B0); PG8_BAR; PG8_SCHED;
;             PG8_LDB(B1, 0, 1); PG8_STAGE(PG8_SB(0, 0), b2, voffB);
;             PG8_BAR; PG8_WAIT_L(0); PG8_MMA(0, 1, At, B1); PG8_BAR;
;             PG8_LDA(At, 0, 1); PG8_STAGE(PG8_SA(0, 0), a2, voffA);
;             PG8_BAR; PG8_WAIT_L(0); PG8_MMA(1, 0, At, B0); PG8_BAR; PG8_SCHED;
;             PG8_STAGE(PG8_SB(0, 1), b2 + hstepB, voffB);
;             PG8_WAIT_V(6); PG8_BAR; PG8_MMA(1, 1, At, B1); PG8_BAR;
.LBB0_552:
	s_add_u32 s34, s2, 0x100
	s_addc_u32 s35, s3, 0
	s_add_i32 s38, 0, 0x10000
	v_add_u32_e32 v1, s38, v250
	ds_read_b128 v[130:133], v1
	ds_read_b128 v[134:137], v1 offset:1024
	ds_read_b128 v[138:141], v1 offset:2048
	ds_read_b128 v[142:145], v1 offset:3072
	s_cmp_eq_u32 s76, 28
	s_cselect_b32 s67, s23, s35
	s_cselect_b32 s66, s72, s34
	s_cselect_b32 s63, s21, s75
	s_cselect_b32 s62, s73, s74
	v_lshl_add_u64 v[178:179], s[2:3], 0, v[202:203]
	s_add_i32 m0, s29, 0xc000
	ds_read_b128 v[146:149], v252
	ds_read_b128 v[150:153], v252 offset:1024
	ds_read_b128 v[154:157], v252 offset:2048
	ds_read_b128 v[158:161], v252 offset:3072
	ds_read_b128 v[162:165], v252 offset:4096
	ds_read_b128 v[166:169], v252 offset:5120
	ds_read_b128 v[170:173], v252 offset:6144
	ds_read_b128 v[174:177], v252 offset:7168
	global_load_lds_dwordx4 v[178:179], off
	v_lshl_add_u64 v[178:179], s[2:3], 0, v[200:201]
	s_add_i32 m0, s29, 0xe000
	s_nop 0
	global_load_lds_dwordx4 v[178:179], off
	s_waitcnt lgkmcnt(8)
	s_barrier
	s_waitcnt lgkmcnt(0)
	s_setprio 1
	s_waitcnt lgkmcnt(0)
	v_mfma_f32_16x16x32_bf16 v[126:129], v[130:133], v[146:149], v[126:129]
	v_mfma_f32_16x16x32_bf16 v[110:113], v[138:141], v[146:149], v[110:113]
	v_mfma_f32_16x16x32_bf16 v[122:125], v[130:133], v[154:157], v[122:125]
	v_mfma_f32_16x16x32_bf16 v[106:109], v[138:141], v[154:157], v[106:109]
	v_mfma_f32_16x16x32_bf16 v[118:121], v[130:133], v[162:165], v[118:121]
	v_mfma_f32_16x16x32_bf16 v[102:105], v[138:141], v[162:165], v[102:105]
	v_mfma_f32_16x16x32_bf16 v[114:117], v[130:133], v[170:173], v[114:117]
	v_mfma_f32_16x16x32_bf16 v[98:101], v[138:141], v[170:173], v[98:101]
	v_mfma_f32_16x16x32_bf16 v[126:129], v[134:137], v[150:153], v[126:129]
	v_mfma_f32_16x16x32_bf16 v[110:113], v[142:145], v[150:153], v[110:113]
	v_mfma_f32_16x16x32_bf16 v[122:125], v[134:137], v[158:161], v[122:125]
	v_mfma_f32_16x16x32_bf16 v[106:109], v[142:145], v[158:161], v[106:109]
	v_mfma_f32_16x16x32_bf16 v[118:121], v[134:137], v[166:169], v[118:121]
	v_mfma_f32_16x16x32_bf16 v[102:105], v[142:145], v[166:169], v[102:105]
	v_mfma_f32_16x16x32_bf16 v[114:117], v[134:137], v[174:177], v[114:117]
	v_mfma_f32_16x16x32_bf16 v[98:101], v[142:145], v[174:177], v[98:101]
	s_setprio 0
	s_barrier
	s_add_i32 s39, 0, 0x14000
	s_add_i32 s2, s38, s53
	v_add_u32_e32 v1, s39, v250
	v_lshl_add_u64 v[186:187], s[62:63], 0, v[196:197]
	s_mov_b32 m0, s2
	ds_read_b128 v[178:181], v1
	ds_read_b128 v[182:185], v1 offset:1024
	ds_read_b128 v[192:195], v1 offset:2048
	ds_read_b128 v[204:207], v1 offset:3072
	global_load_lds_dwordx4 v[186:187], off
	v_lshl_add_u64 v[208:209], s[62:63], 0, v[198:199]
	s_add_i32 m0, s2, 0x2000
	s_nop 0
	global_load_lds_dwordx4 v[208:209], off
	s_barrier
	s_waitcnt lgkmcnt(0)
	s_setprio 1
	s_waitcnt lgkmcnt(0)
	v_mfma_f32_16x16x32_bf16 v[94:97], v[178:181], v[146:149], v[94:97]
	v_mfma_f32_16x16x32_bf16 v[78:81], v[192:195], v[146:149], v[78:81]
	v_mfma_f32_16x16x32_bf16 v[90:93], v[178:181], v[154:157], v[90:93]
	v_mfma_f32_16x16x32_bf16 v[74:77], v[192:195], v[154:157], v[74:77]
	v_mfma_f32_16x16x32_bf16 v[86:89], v[178:181], v[162:165], v[86:89]
	v_mfma_f32_16x16x32_bf16 v[70:73], v[192:195], v[162:165], v[70:73]
	v_mfma_f32_16x16x32_bf16 v[82:85], v[178:181], v[170:173], v[82:85]
	v_mfma_f32_16x16x32_bf16 v[66:69], v[192:195], v[170:173], v[66:69]
	v_mfma_f32_16x16x32_bf16 v[94:97], v[182:185], v[150:153], v[94:97]
	v_mfma_f32_16x16x32_bf16 v[78:81], v[204:207], v[150:153], v[78:81]
	v_mfma_f32_16x16x32_bf16 v[90:93], v[182:185], v[158:161], v[90:93]
	v_mfma_f32_16x16x32_bf16 v[74:77], v[204:207], v[158:161], v[74:77]
	v_mfma_f32_16x16x32_bf16 v[86:89], v[182:185], v[166:169], v[86:89]
	v_mfma_f32_16x16x32_bf16 v[70:73], v[204:207], v[166:169], v[70:73]
	v_mfma_f32_16x16x32_bf16 v[82:85], v[182:185], v[174:177], v[82:85]
	v_mfma_f32_16x16x32_bf16 v[66:69], v[204:207], v[174:177], v[66:69]
	s_setprio 0
	s_mov_b32 m0, s29
	v_lshl_add_u64 v[210:211], s[66:67], 0, v[196:197]
	s_barrier
	ds_read_b128 v[146:149], v252 offset:16384
	ds_read_b128 v[150:153], v252 offset:17408
	ds_read_b128 v[154:157], v252 offset:18432
	ds_read_b128 v[158:161], v252 offset:19456
	ds_read_b128 v[162:165], v252 offset:20480
	ds_read_b128 v[166:169], v252 offset:21504
	ds_read_b128 v[170:173], v252 offset:22528
	ds_read_b128 v[174:177], v252 offset:23552
	global_load_lds_dwordx4 v[210:211], off
	v_lshl_add_u64 v[212:213], s[66:67], 0, v[198:199]
	s_mov_b32 m0, s31
	s_nop 0
	global_load_lds_dwordx4 v[212:213], off
	s_barrier
	s_waitcnt lgkmcnt(0)
	s_setprio 1
	s_waitcnt lgkmcnt(0)
	v_mfma_f32_16x16x32_bf16 v[62:65], v[130:133], v[146:149], v[62:65]
	v_mfma_f32_16x16x32_bf16 v[46:49], v[138:141], v[146:149], v[46:49]
	v_mfma_f32_16x16x32_bf16 v[58:61], v[130:133], v[154:157], v[58:61]
	v_mfma_f32_16x16x32_bf16 v[42:45], v[138:141], v[154:157], v[42:45]
	v_mfma_f32_16x16x32_bf16 v[54:57], v[130:133], v[162:165], v[54:57]
	v_mfma_f32_16x16x32_bf16 v[38:41], v[138:141], v[162:165], v[38:41]
	v_mfma_f32_16x16x32_bf16 v[50:53], v[130:133], v[170:173], v[50:53]
	v_mfma_f32_16x16x32_bf16 v[34:37], v[138:141], v[170:173], v[34:37]
	v_mfma_f32_16x16x32_bf16 v[62:65], v[134:137], v[150:153], v[62:65]
	v_mfma_f32_16x16x32_bf16 v[46:49], v[142:145], v[150:153], v[46:49]
	v_mfma_f32_16x16x32_bf16 v[58:61], v[134:137], v[158:161], v[58:61]
	v_mfma_f32_16x16x32_bf16 v[42:45], v[142:145], v[158:161], v[42:45]
	v_mfma_f32_16x16x32_bf16 v[54:57], v[134:137], v[166:169], v[54:57]
	v_mfma_f32_16x16x32_bf16 v[38:41], v[142:145], v[166:169], v[38:41]
	v_mfma_f32_16x16x32_bf16 v[50:53], v[134:137], v[174:177], v[50:53]
	v_mfma_f32_16x16x32_bf16 v[34:37], v[142:145], v[174:177], v[34:37]
	s_setprio 0
	s_barrier
; #define PG8_STAGE(bufoff, gbase, voff) do { _Pragma("unroll") for (int _i = 0; _i < 2; ++_i) \
;         __builtin_amdgcn_global_load_lds((const unsigned*)((const char*)(gbase) + (voff)[_i]), (LAS unsigned*)(lds + (bufoff) + ldsw + _i * 8192), 16, 0, 0); } while (0)
; #define PG8_LDA(dst, b, h) do { _Pragma("unroll") for (int m = 0; m < 4; ++m) _Pragma("unroll") for (int k = 0; k < 2; ++k) dst[m][k] = *(const LAS bf16x8*)(lds + PG8_SA(b, h) + aoff + m * 2048 + k * 1024); } while (0)
; #define PG8_LDB(dst, b, h) do { _Pragma("unroll") for (int n = 0; n < 2; ++n) _Pragma("unroll") for (int k = 0; k < 2; ++k) dst[n][k] = *(const LAS bf16x8*)(lds + PG8_SB(b, h) + boff + n * 2048 + k * 1024); } while (0)
; #define PG8_MMA(ai, bj, At, Bt) do { __builtin_amdgcn_s_setprio(1); _Pragma("unroll") for (int m = 0; m < 4; ++m) _Pragma("unroll") for (int n = 0; n < 2; ++n) _Pragma("unroll") for (int k = 0; k < 2; ++k) \
;         acc[ai][bj][m][n] = __builtin_amdgcn_mfma_f32_16x16x32_bf16(Bt[n][k], At[m][k], acc[ai][bj][m][n], 0, 0, 0); __builtin_amdgcn_s_setprio(0); } while (0)
; #define PG8_WAIT_V(n) asm volatile("s_waitcnt vmcnt(" #n ")" ::: "memory")
; #define PG8_WAIT_L(n) asm volatile("s_waitcnt lgkmcnt(" #n ")" ::: "memory")
; #define PG8_BAR __builtin_amdgcn_s_barrier()
; #define PG8_SCHED __builtin_amdgcn_sched_barrier(0)
; template <class Epi, class Sched, bool AREMAP>
; __device__ __forceinline__ void gemm_phase(LAS unsigned char* lds, const Gemm g, const Sched& S, const Epi& E, int wv) {
;     ...
;             PG8_WAIT_V(6); PG8_BAR; PG8_MMA(1, 1, At, B1); PG8_BAR;
;             PG8_LDB(B0, 1, 0); PG8_SCHED; PG8_LDA(At, 1, 0); PG8_STAGE(PG8_SA(0, 1), a2 + hstepA, voffA);
;             PG8_WAIT_L(8); PG8_BAR; PG8_WAIT_L(0); PG8_MMA(0, 0, At, B0); PG8_BAR; PG8_SCHED;
;             PG8_LDB(B1, 1, 1); PG8_STAGE(PG8_SB(1, 0), b3, voffB);
;             PG8_BAR; PG8_WAIT_L(0); PG8_MMA(0, 1, At, B1); PG8_BAR;
;             PG8_LDA(At, 1, 1); PG8_STAGE(PG8_SA(1, 0), a3, voffA);
;             PG8_BAR; PG8_WAIT_L(0); PG8_MMA(1, 0, At, B0); PG8_BAR; PG8_SCHED;
	s_add_u32 s2, s62, 0x80000
	s_addc_u32 s3, s63, 0
	s_add_i32 s38, s39, s53
	v_lshl_add_u64 v[130:131], s[2:3], 0, v[196:197]
	s_mov_b32 m0, s38
	s_nop 0
	global_load_lds_dwordx4 v[130:131], off
	v_lshl_add_u64 v[130:131], s[2:3], 0, v[198:199]
	s_add_i32 m0, s38, 0x2000
	s_nop 0
	global_load_lds_dwordx4 v[130:131], off
	s_waitcnt vmcnt(6)
	s_barrier
	s_setprio 1
	v_mfma_f32_16x16x32_bf16 v[30:33], v[178:181], v[146:149], v[30:33]
	v_mfma_f32_16x16x32_bf16 v[14:17], v[192:195], v[146:149], v[14:17]
	v_mfma_f32_16x16x32_bf16 v[26:29], v[178:181], v[154:157], v[26:29]
	v_mfma_f32_16x16x32_bf16 v[10:13], v[192:195], v[154:157], v[10:13]
	v_mfma_f32_16x16x32_bf16 v[22:25], v[178:181], v[162:165], v[22:25]
	v_mfma_f32_16x16x32_bf16 v[6:9], v[192:195], v[162:165], v[6:9]
	v_mfma_f32_16x16x32_bf16 v[18:21], v[178:181], v[170:173], v[18:21]
	v_mfma_f32_16x16x32_bf16 v[2:5], v[192:195], v[170:173], v[2:5]
	v_mfma_f32_16x16x32_bf16 v[30:33], v[182:185], v[150:153], v[30:33]
	v_mfma_f32_16x16x32_bf16 v[14:17], v[204:207], v[150:153], v[14:17]
	v_mfma_f32_16x16x32_bf16 v[26:29], v[182:185], v[158:161], v[26:29]
	v_mfma_f32_16x16x32_bf16 v[10:13], v[204:207], v[158:161], v[10:13]
	v_mfma_f32_16x16x32_bf16 v[22:25], v[182:185], v[166:169], v[22:25]
	v_mfma_f32_16x16x32_bf16 v[6:9], v[204:207], v[166:169], v[6:9]
	v_mfma_f32_16x16x32_bf16 v[18:21], v[182:185], v[174:177], v[18:21]
	v_mfma_f32_16x16x32_bf16 v[2:5], v[204:207], v[174:177], v[2:5]
	s_setprio 0
	s_add_i32 s38, 0, 0x18000
	v_add_u32_e32 v1, s38, v250
	s_barrier
	ds_read_b128 v[130:133], v1
	ds_read_b128 v[134:137], v1 offset:1024
	ds_read_b128 v[138:141], v1 offset:2048
	ds_read_b128 v[142:145], v1 offset:3072
	s_add_u32 s2, s66, 0x80000
	s_addc_u32 s3, s67, 0
	s_mov_b32 m0, s55
	v_lshl_add_u64 v[178:179], s[2:3], 0, v[196:197]
	ds_read_b128 v[146:149], v252 offset:32768
	ds_read_b128 v[150:153], v252 offset:33792
	ds_read_b128 v[154:157], v252 offset:34816
	ds_read_b128 v[158:161], v252 offset:35840
	ds_read_b128 v[162:165], v252 offset:36864
	ds_read_b128 v[166:169], v252 offset:37888
	ds_read_b128 v[170:173], v252 offset:38912
	ds_read_b128 v[174:177], v252 offset:39936
	global_load_lds_dwordx4 v[178:179], off
	v_lshl_add_u64 v[178:179], s[2:3], 0, v[198:199]
	s_mov_b32 m0, s56
	s_nop 0
	global_load_lds_dwordx4 v[178:179], off
	s_waitcnt lgkmcnt(8)
	s_barrier
	s_waitcnt lgkmcnt(0)
	s_setprio 1
	s_waitcnt lgkmcnt(0)
	v_mfma_f32_16x16x32_bf16 v[126:129], v[130:133], v[146:149], v[126:129]
	v_mfma_f32_16x16x32_bf16 v[110:113], v[138:141], v[146:149], v[110:113]
	v_mfma_f32_16x16x32_bf16 v[122:125], v[130:133], v[154:157], v[122:125]
	v_mfma_f32_16x16x32_bf16 v[106:109], v[138:141], v[154:157], v[106:109]
	v_mfma_f32_16x16x32_bf16 v[118:121], v[130:133], v[162:165], v[118:121]
	v_mfma_f32_16x16x32_bf16 v[102:105], v[138:141], v[162:165], v[102:105]
	v_mfma_f32_16x16x32_bf16 v[114:117], v[130:133], v[170:173], v[114:117]
	v_mfma_f32_16x16x32_bf16 v[98:101], v[138:141], v[170:173], v[98:101]
	v_mfma_f32_16x16x32_bf16 v[126:129], v[134:137], v[150:153], v[126:129]
	v_mfma_f32_16x16x32_bf16 v[110:113], v[142:145], v[150:153], v[110:113]
	v_mfma_f32_16x16x32_bf16 v[122:125], v[134:137], v[158:161], v[122:125]
	v_mfma_f32_16x16x32_bf16 v[106:109], v[142:145], v[158:161], v[106:109]
	v_mfma_f32_16x16x32_bf16 v[118:121], v[134:137], v[166:169], v[118:121]
	v_mfma_f32_16x16x32_bf16 v[102:105], v[142:145], v[166:169], v[102:105]
	v_mfma_f32_16x16x32_bf16 v[114:117], v[134:137], v[174:177], v[114:117]
	v_mfma_f32_16x16x32_bf16 v[98:101], v[142:145], v[174:177], v[98:101]
	s_setprio 0
	s_barrier
	s_add_i32 s39, 0, 0x1c000
	s_add_i32 s2, s38, s53
	v_add_u32_e32 v1, s39, v250
	v_lshl_add_u64 v[186:187], v[186:187], 0, s[86:87]
	s_mov_b32 m0, s2
	ds_read_b128 v[178:181], v1
	ds_read_b128 v[182:185], v1 offset:1024
	ds_read_b128 v[192:195], v1 offset:2048
	ds_read_b128 v[204:207], v1 offset:3072
	global_load_lds_dwordx4 v[186:187], off
	v_lshl_add_u64 v[186:187], v[208:209], 0, s[86:87]
	s_add_i32 m0, s2, 0x2000
	s_nop 0
	global_load_lds_dwordx4 v[186:187], off
	s_barrier
	s_waitcnt lgkmcnt(0)
	s_setprio 1
	s_waitcnt lgkmcnt(0)
	v_mfma_f32_16x16x32_bf16 v[94:97], v[178:181], v[146:149], v[94:97]
	v_mfma_f32_16x16x32_bf16 v[78:81], v[192:195], v[146:149], v[78:81]
	v_mfma_f32_16x16x32_bf16 v[90:93], v[178:181], v[154:157], v[90:93]
	v_mfma_f32_16x16x32_bf16 v[74:77], v[192:195], v[154:157], v[74:77]
	v_mfma_f32_16x16x32_bf16 v[86:89], v[178:181], v[162:165], v[86:89]
	v_mfma_f32_16x16x32_bf16 v[70:73], v[192:195], v[162:165], v[70:73]
	v_mfma_f32_16x16x32_bf16 v[82:85], v[178:181], v[170:173], v[82:85]
	v_mfma_f32_16x16x32_bf16 v[66:69], v[192:195], v[170:173], v[66:69]
	v_mfma_f32_16x16x32_bf16 v[94:97], v[182:185], v[150:153], v[94:97]
	v_mfma_f32_16x16x32_bf16 v[78:81], v[204:207], v[150:153], v[78:81]
	v_mfma_f32_16x16x32_bf16 v[90:93], v[182:185], v[158:161], v[90:93]
	v_mfma_f32_16x16x32_bf16 v[74:77], v[204:207], v[158:161], v[74:77]
	v_mfma_f32_16x16x32_bf16 v[86:89], v[182:185], v[166:169], v[86:89]
	v_mfma_f32_16x16x32_bf16 v[70:73], v[204:207], v[166:169], v[70:73]
	v_mfma_f32_16x16x32_bf16 v[82:85], v[182:185], v[174:177], v[82:85]
	v_mfma_f32_16x16x32_bf16 v[66:69], v[204:207], v[174:177], v[66:69]
	s_setprio 0
	s_mov_b32 m0, s57
	v_lshl_add_u64 v[186:187], v[210:211], 0, s[86:87]
	s_barrier
; #define PG8_STAGE(bufoff, gbase, voff) do { _Pragma("unroll") for (int _i = 0; _i < 2; ++_i) \
;         __builtin_amdgcn_global_load_lds((const unsigned*)((const char*)(gbase) + (voff)[_i]), (LAS unsigned*)(lds + (bufoff) + ldsw + _i * 8192), 16, 0, 0); } while (0)
; #define PG8_MMA(ai, bj, At, Bt) do { __builtin_amdgcn_s_setprio(1); _Pragma("unroll") for (int m = 0; m < 4; ++m) _Pragma("unroll") for (int n = 0; n < 2; ++n) _Pragma("unroll") for (int k = 0; k < 2; ++k) \
;         acc[ai][bj][m][n] = __builtin_amdgcn_mfma_f32_16x16x32_bf16(Bt[n][k], At[m][k], acc[ai][bj][m][n], 0, 0, 0); __builtin_amdgcn_s_setprio(0); } while (0)
; #define PG8_WAIT_V(n) asm volatile("s_waitcnt vmcnt(" #n ")" ::: "memory")
; #define PG8_WAIT_L(n) asm volatile("s_waitcnt lgkmcnt(" #n ")" ::: "memory")
; #define PG8_BAR __builtin_amdgcn_s_barrier()
; #define PG8_SCHED __builtin_amdgcn_sched_barrier(0)
; template <class Epi, class Sched, bool AREMAP>
; __device__ __forceinline__ void gemm_phase(LAS unsigned char* lds, const Gemm g, const Sched& S, const Epi& E, int wv) {
;     ...
;             PG8_BAR; PG8_WAIT_L(0); PG8_MMA(1, 0, At, B0); PG8_BAR; PG8_SCHED;
;             PG8_STAGE(PG8_SB(1, 1), b3 + hstepB, voffB);
;             PG8_WAIT_V(6); PG8_BAR; PG8_MMA(1, 1, At, B1); PG8_BAR;
;         }
;     __device__ __forceinline__ void operator()(const f32x4 (&acc)[2][2][4][2], const Unit& u, int wr, int wc, int fr, int fq) const {
;     ...
;             float mu[4], rs[4];
; #pragma unroll
;             for (int m = 0; m < 4; ++m) { mu[m] = 0.f; rs[m] = 1.f;
;                 if (stats) { const float* sp = stats + (size_t)(row0 + ai * HALF + m * 16) * 2; mu[m] = sp[0]; rs[m] = sp[1]; } }
	ds_read_b128 v[146:149], v252 offset:49152
	ds_read_b128 v[150:153], v252 offset:50176
	ds_read_b128 v[154:157], v252 offset:51200
	ds_read_b128 v[158:161], v252 offset:52224
	ds_read_b128 v[162:165], v252 offset:53248
	ds_read_b128 v[166:169], v252 offset:54272
	ds_read_b128 v[170:173], v252 offset:55296
	ds_read_b128 v[174:177], v252 offset:56320
	global_load_lds_dwordx4 v[186:187], off
	v_lshl_add_u64 v[186:187], v[212:213], 0, s[86:87]
	s_mov_b32 m0, s65
	s_nop 0
	global_load_lds_dwordx4 v[186:187], off
	s_barrier
	s_waitcnt lgkmcnt(0)
	s_setprio 1
	s_waitcnt lgkmcnt(0)
	v_mfma_f32_16x16x32_bf16 v[62:65], v[130:133], v[146:149], v[62:65]
	v_mfma_f32_16x16x32_bf16 v[46:49], v[138:141], v[146:149], v[46:49]
	v_mfma_f32_16x16x32_bf16 v[58:61], v[130:133], v[154:157], v[58:61]
	v_mfma_f32_16x16x32_bf16 v[42:45], v[138:141], v[154:157], v[42:45]
	v_mfma_f32_16x16x32_bf16 v[54:57], v[130:133], v[162:165], v[54:57]
	v_mfma_f32_16x16x32_bf16 v[38:41], v[138:141], v[162:165], v[38:41]
	v_mfma_f32_16x16x32_bf16 v[50:53], v[130:133], v[170:173], v[50:53]
	v_mfma_f32_16x16x32_bf16 v[34:37], v[138:141], v[170:173], v[34:37]
	v_mfma_f32_16x16x32_bf16 v[62:65], v[134:137], v[150:153], v[62:65]
	v_mfma_f32_16x16x32_bf16 v[46:49], v[142:145], v[150:153], v[46:49]
	v_mfma_f32_16x16x32_bf16 v[58:61], v[134:137], v[158:161], v[58:61]
	v_mfma_f32_16x16x32_bf16 v[42:45], v[142:145], v[158:161], v[42:45]
	v_mfma_f32_16x16x32_bf16 v[54:57], v[134:137], v[166:169], v[54:57]
	v_mfma_f32_16x16x32_bf16 v[38:41], v[142:145], v[166:169], v[38:41]
	v_mfma_f32_16x16x32_bf16 v[50:53], v[134:137], v[174:177], v[50:53]
	v_mfma_f32_16x16x32_bf16 v[34:37], v[142:145], v[174:177], v[34:37]
	s_setprio 0
	s_barrier
	s_add_u32 s2, s62, 0x80080
	s_addc_u32 s3, s63, 0
	s_add_i32 s38, s39, s53
	v_lshl_add_u64 v[130:131], s[2:3], 0, v[196:197]
	s_mov_b32 m0, s38
	s_nop 0
	global_load_lds_dwordx4 v[130:131], off
	v_lshl_add_u64 v[130:131], s[2:3], 0, v[198:199]
	s_add_i32 m0, s38, 0x2000
	s_nop 0
	global_load_lds_dwordx4 v[130:131], off
	s_waitcnt vmcnt(6)
	s_barrier
	s_setprio 1
	v_mfma_f32_16x16x32_bf16 v[30:33], v[178:181], v[146:149], v[30:33]
	v_mfma_f32_16x16x32_bf16 v[14:17], v[192:195], v[146:149], v[14:17]
	v_mfma_f32_16x16x32_bf16 v[26:29], v[178:181], v[154:157], v[26:29]
	v_mfma_f32_16x16x32_bf16 v[10:13], v[192:195], v[154:157], v[10:13]
	v_mfma_f32_16x16x32_bf16 v[22:25], v[178:181], v[162:165], v[22:25]
	v_mfma_f32_16x16x32_bf16 v[6:9], v[192:195], v[162:165], v[6:9]
	v_mfma_f32_16x16x32_bf16 v[18:21], v[178:181], v[170:173], v[18:21]
	v_mfma_f32_16x16x32_bf16 v[2:5], v[192:195], v[170:173], v[2:5]
	v_mfma_f32_16x16x32_bf16 v[30:33], v[182:185], v[150:153], v[30:33]
	v_mfma_f32_16x16x32_bf16 v[14:17], v[204:207], v[150:153], v[14:17]
	v_mfma_f32_16x16x32_bf16 v[26:29], v[182:185], v[158:161], v[26:29]
	v_mfma_f32_16x16x32_bf16 v[10:13], v[204:207], v[158:161], v[10:13]
	v_mfma_f32_16x16x32_bf16 v[22:25], v[182:185], v[166:169], v[22:25]
	v_mfma_f32_16x16x32_bf16 v[6:9], v[204:207], v[166:169], v[6:9]
	v_mfma_f32_16x16x32_bf16 v[18:21], v[182:185], v[174:177], v[18:21]
	v_mfma_f32_16x16x32_bf16 v[2:5], v[204:207], v[174:177], v[2:5]
	s_setprio 0
	s_add_i32 s76, s76, 2
	s_add_u32 s74, s74, 0x100
	s_addc_u32 s75, s75, 0
	s_cmp_gt_u32 s76, 29
	s_mov_b64 s[2:3], s[34:35]
	s_barrier
	s_cbranch_scc0 .LBB0_552
	v_lshl_add_u32 v212, s28, 8, v249
	v_cndmask_b32_e64 v1, 0, 1, s[18:19]
	v_mov_b32_e32 v216, 1.0
	v_cmp_ne_u32_e64 s[2:3], 1, v1
	s_andn2_b64 vcc, exec, s[18:19]
	v_ashrrev_i32_e32 v213, 31, v212
	s_cbranch_vccnz .LBB0_556
	v_lshl_add_u64 v[130:131], v[212:213], 3, s[12:13]
	global_load_dwordx2 v[134:135], v[130:131], off
	v_or_b32_e32 v140, 16, v212
	s_and_b64 vcc, exec, s[2:3]
	v_ashrrev_i32_e32 v141, 31, v140
	s_cbranch_vccnz .LBB0_557
.LBB0_555:
	v_lshl_add_u64 v[130:131], v[140:141], 3, s[12:13]
	global_load_dwordx2 v[142:143], v[130:131], off
	s_waitcnt vmcnt(0) lgkmcnt(0)
	v_mov_b64_e32 v[138:139], v[136:137]
	v_mov_b64_e32 v[136:137], v[134:135]
	v_mov_b32_e32 v138, s71
	v_mov_b32_e32 v137, v142
	v_mov_b64_e32 v[130:131], v[136:137]
	v_mov_b64_e32 v[132:133], v[138:139]
	v_mov_b32_e32 v133, s71
	v_mov_b32_e32 v216, v143
	s_branch .LBB0_558

;     __device__ __forceinline__ void operator()(const f32x4 (&acc)[2][2][4][2], const Unit& u, int wr, int wc, int fr, int fq) const {
;     ...
;         for (int ai = 0; ai < 2; ++ai) {
;             float mu[4], rs[4];
; #pragma unroll
;             for (int m = 0; m < 4; ++m) { mu[m] = 0.f; rs[m] = 1.f;
;                 if (stats) { const float* sp = stats + (size_t)(row0 + ai * HALF + m * 16) * 2; mu[m] = sp[0]; rs[m] = sp[1]; } }
; #pragma unroll
;             for (int bj = 0; bj < 2; ++bj) {
;                 f32x4 xv[2][4];
; #pragma unroll
;                 for (int n = 0; n < 2; ++n)
; #pragma unroll
;                     for (int m = 0; m < 4; ++m) xv[n][m] = *(const f32x4*)(xin + (size_t)(row0 + ai * HALF + m * 16) * DM + col0 + bj * HALF + n * 16);
; #pragma unroll
;                 for (int n = 0; n < 2; ++n) {
;                     const int cofs = bj * HALF + n * 16;
;                     const f32x4 g4 = *(const f32x4*)(gv + cofs) + 1.0f;
;                     f32x4 lg = {1.f, 1.f, 1.f, 1.f}, lb = {0.f, 0.f, 0.f, 0.f};
;                     if (stats) { lg = *(const f32x4*)(lng + col0 + cofs); lb = *(const f32x4*)(lnb + col0 + cofs); }
; #pragma unroll
;                     for (int m = 0; m < 4; ++m) { const f32x4 x = (xv[n][m] - mu[m]) * rs[m] * lg + lb;
;                         *(f32x4*)(out + (size_t)(row0 + ai * HALF + m * 16) * DM + col0 + cofs) = x * ALPHA + g4 * acc[ai][bj][m][n]; }
.LBB0_558:
	v_or_b32_e32 v142, 32, v212
	s_mov_b32 s39, 0xb2a5705f
	s_mov_b32 s38, 0x42ce8ed0
	v_mov_b32_e32 v218, 1.0
	s_and_b64 vcc, exec, s[2:3]
	v_ashrrev_i32_e32 v143, 31, v142
	v_mov_b32_e32 v220, 1.0
	s_cbranch_vccnz .LBB0_560
	v_lshl_add_u64 v[130:131], v[142:143], 3, s[12:13]
	global_load_dwordx2 v[144:145], v[130:131], off
	s_waitcnt vmcnt(0) lgkmcnt(0)
	v_mov_b32_e32 v138, v144
	v_mov_b64_e32 v[130:131], v[136:137]
	v_mov_b64_e32 v[132:133], v[138:139]
	v_mov_b32_e32 v133, s71
	v_mov_b32_e32 v220, v145
.LBB0_560:
	v_or_b32_e32 v144, 48, v212
	s_and_b64 vcc, exec, s[2:3]
	v_ashrrev_i32_e32 v145, 31, v144
	s_cbranch_vccnz .LBB0_562
	v_lshl_add_u64 v[130:131], v[144:145], 3, s[12:13]
	global_load_dwordx2 v[146:147], v[130:131], off
	s_waitcnt vmcnt(0) lgkmcnt(0)
	v_mov_b32_e32 v139, v146
	v_mov_b64_e32 v[130:131], v[136:137]
	v_mov_b64_e32 v[132:133], v[138:139]
	v_mov_b32_e32 v218, v147
.LBB0_562:
	v_lshl_or_b32 v136, s30, 8, v251
	s_ashr_i32 s21, s28, 3
	v_ashrrev_i32_e32 v137, 31, v136
	s_mul_hi_i32 s23, s21, 0xc000
	s_mul_i32 s21, s21, 0xc000
	v_lshlrev_b64 v[210:211], 2, v[136:137]
	s_add_u32 s34, s6, s21
	v_lshl_add_u64 v[214:215], s[4:5], 0, v[210:211]
	v_lshlrev_b64 v[234:235], 13, v[212:213]
	s_addc_u32 s35, s7, s23
	v_lshl_add_u64 v[224:225], v[214:215], 0, v[234:235]
	v_lshlrev_b64 v[232:233], 13, v[140:141]
	v_lshlrev_b64 v[142:143], 13, v[142:143]
	v_lshlrev_b64 v[138:139], 13, v[144:145]
	v_lshl_add_u64 v[204:205], s[34:35], 0, v[210:211]
	v_lshl_add_u64 v[226:227], v[214:215], 0, v[232:233]
	v_lshl_add_u64 v[228:229], v[214:215], 0, v[142:143]
	v_lshl_add_u64 v[230:231], v[214:215], 0, v[138:139]
	global_load_dwordx4 v[180:183], v[224:225], off
	global_load_dwordx4 v[156:159], v[224:225], off offset:64
	global_load_dwordx4 v[176:179], v[226:227], off
	global_load_dwordx4 v[152:155], v[226:227], off offset:64
	global_load_dwordx4 v[172:175], v[228:229], off
	global_load_dwordx4 v[148:151], v[228:229], off offset:64
	global_load_dwordx4 v[160:163], v[230:231], off
	global_load_dwordx4 v[144:147], v[230:231], off offset:64
	global_load_dwordx4 v[184:187], v[204:205], off
	v_mov_b32_e32 v140, 0
	v_mov_b32_e32 v136, 1.0
	s_and_b64 vcc, exec, s[2:3]
	v_lshl_add_u64 v[206:207], s[14:15], 0, v[210:211]
	v_lshl_add_u64 v[208:209], s[16:17], 0, v[210:211]
	v_mov_b32_e32 v164, 1.0
	v_mov_b32_e32 v165, 1.0
	v_mov_b32_e32 v166, 1.0
	v_mov_b32_e32 v167, 1.0
	v_mov_b32_e32 v168, 0
	v_mov_b32_e32 v169, 0
	v_mov_b32_e32 v170, 0
	v_mov_b32_e32 v171, 0
	s_cbranch_vccnz .LBB0_564
	global_load_dwordx4 v[164:167], v[206:207], off
	global_load_dwordx4 v[168:171], v[208:209], off
.LBB0_564:
	v_mov_b32_e32 v222, v135
	v_mov_b32_e32 v223, v216
	s_waitcnt vmcnt(0) lgkmcnt(0)
	v_sub_f32_e32 v181, v181, v130
	v_sub_f32_e32 v180, v180, v130
	v_sub_f32_e32 v183, v183, v130
	v_sub_f32_e32 v182, v182, v130
	v_pk_mul_f32 v[180:181], v[222:223], v[180:181] op_sel_hi:[0,1]
	v_pk_mul_f32 v[182:183], v[222:223], v[182:183] op_sel_hi:[0,1]
	v_pk_fma_f32 v[180:181], v[180:181], v[164:165], v[168:169]
	v_pk_add_f32 v[184:185], v[184:185], 1.0 op_sel_hi:[1,0]
	v_pk_fma_f32 v[182:183], v[182:183], v[166:167], v[170:171]
	v_pk_mul_f32 v[180:181], v[180:181], s[64:65] op_sel_hi:[1,0]
	v_pk_add_f32 v[186:187], v[186:187], 1.0 op_sel_hi:[1,0]
	v_pk_mul_f32 v[182:183], v[182:183], s[64:65] op_sel_hi:[1,0]
	v_pk_fma_f32 v[126:127], v[126:127], v[184:185], v[180:181]
	v_lshl_add_u64 v[180:181], s[8:9], 0, v[234:235]
	v_pk_fma_f32 v[128:129], v[128:129], v[186:187], v[182:183]
	v_lshl_add_u64 v[180:181], v[180:181], 0, v[210:211]
	global_store_dwordx4 v[180:181], v[126:129], off
	s_and_b64 vcc, exec, s[2:3]
	v_mov_b32_e32 v137, 1.0
	v_sub_f32_e32 v127, v179, v131
	v_sub_f32_e32 v126, v178, v131
	v_sub_f32_e32 v129, v177, v131
	v_sub_f32_e32 v128, v176, v131
	v_pk_mul_f32 v[126:127], v[222:223], v[126:127] op_sel:[1,0]
	v_pk_mul_f32 v[128:129], v[222:223], v[128:129] op_sel:[1,0]
	v_pk_fma_f32 v[126:127], v[126:127], v[166:167], v[170:171]
	v_pk_fma_f32 v[128:129], v[128:129], v[164:165], v[168:169]
	v_pk_mul_f32 v[126:127], v[126:127], s[64:65] op_sel_hi:[1,0]
	v_pk_mul_f32 v[128:129], v[128:129], s[64:65] op_sel_hi:[1,0]
	v_pk_fma_f32 v[124:125], v[124:125], v[186:187], v[126:127]
	v_lshl_add_u64 v[126:127], s[8:9], 0, v[232:233]
	v_pk_fma_f32 v[122:123], v[122:123], v[184:185], v[128:129]
	v_lshl_add_u64 v[176:177], v[126:127], 0, v[210:211]
	global_store_dwordx4 v[176:177], v[122:125], off
	v_mov_b32_e32 v141, 0
	s_nop 0
	v_sub_f32_e32 v123, v175, v132
	v_sub_f32_e32 v122, v174, v132
	v_sub_f32_e32 v125, v173, v132
	v_sub_f32_e32 v124, v172, v132
	v_pk_mul_f32 v[122:123], v[220:221], v[122:123] op_sel_hi:[0,1]
	v_pk_mul_f32 v[124:125], v[220:221], v[124:125] op_sel_hi:[0,1]
	v_pk_fma_f32 v[122:123], v[122:123], v[166:167], v[170:171]
	v_pk_fma_f32 v[124:125], v[124:125], v[164:165], v[168:169]
	v_pk_mul_f32 v[122:123], v[122:123], s[64:65] op_sel_hi:[1,0]
	v_pk_mul_f32 v[124:125], v[124:125], s[64:65] op_sel_hi:[1,0]
	v_pk_fma_f32 v[120:121], v[120:121], v[186:187], v[122:123]
	v_lshl_add_u64 v[122:123], s[8:9], 0, v[142:143]
	v_pk_fma_f32 v[118:119], v[118:119], v[184:185], v[124:125]
	v_lshl_add_u64 v[172:173], v[122:123], 0, v[210:211]
	global_store_dwordx4 v[172:173], v[118:121], off
	v_mov_b32_e32 v142, 0
	v_mov_b32_e32 v143, 0
	v_sub_f32_e32 v119, v163, v133
	v_sub_f32_e32 v118, v162, v133
	v_sub_f32_e32 v121, v161, v133
	v_sub_f32_e32 v120, v160, v133
	v_pk_mul_f32 v[118:119], v[218:219], v[118:119] op_sel_hi:[0,1]
	v_pk_mul_f32 v[120:121], v[218:219], v[120:121] op_sel_hi:[0,1]
	v_pk_fma_f32 v[118:119], v[118:119], v[166:167], v[170:171]
	v_pk_fma_f32 v[120:121], v[120:121], v[164:165], v[168:169]
	v_pk_mul_f32 v[118:119], v[118:119], s[64:65] op_sel_hi:[1,0]
	v_pk_mul_f32 v[120:121], v[120:121], s[64:65] op_sel_hi:[1,0]
	v_pk_fma_f32 v[116:117], v[116:117], v[186:187], v[118:119]
	v_lshl_add_u64 v[118:119], s[8:9], 0, v[138:139]
	v_pk_fma_f32 v[114:115], v[114:115], v[184:185], v[120:121]
	v_lshl_add_u64 v[160:161], v[118:119], 0, v[210:211]
	global_store_dwordx4 v[160:161], v[114:117], off
	global_load_dwordx4 v[114:117], v[204:205], off offset:64
	v_mov_b32_e32 v138, 1.0
	v_mov_b32_e32 v139, 1.0
	s_cbranch_vccnz .LBB0_566
	global_load_dwordx4 v[136:139], v[206:207], off offset:64
	global_load_dwordx4 v[140:143], v[208:209], off offset:64
;     __device__ __forceinline__ void operator()(const f32x4 (&acc)[2][2][4][2], const Unit& u, int wr, int wc, int fr, int fq) const {
;     ...
;             for (int bj = 0; bj < 2; ++bj) {
;                 f32x4 xv[2][4];
; #pragma unroll
;                 for (int n = 0; n < 2; ++n)
; #pragma unroll
;                     for (int m = 0; m < 4; ++m) xv[n][m] = *(const f32x4*)(xin + (size_t)(row0 + ai * HALF + m * 16) * DM + col0 + bj * HALF + n * 16);
; #pragma unroll
;                 for (int n = 0; n < 2; ++n) {
;                     const int cofs = bj * HALF + n * 16;
;                     const f32x4 g4 = *(const f32x4*)(gv + cofs) + 1.0f;
;                     f32x4 lg = {1.f, 1.f, 1.f, 1.f}, lb = {0.f, 0.f, 0.f, 0.f};
;                     if (stats) { lg = *(const f32x4*)(lng + col0 + cofs); lb = *(const f32x4*)(lnb + col0 + cofs); }
; #pragma unroll
;                     for (int m = 0; m < 4; ++m) { const f32x4 x = (xv[n][m] - mu[m]) * rs[m] * lg + lb;
;                         *(f32x4*)(out + (size_t)(row0 + ai * HALF + m * 16) * DM + col0 + cofs) = x * ALPHA + g4 * acc[ai][bj][m][n]; }
.LBB0_566:
	v_mov_b32_e32 v134, v222
	v_sub_f32_e32 v119, v159, v130
	v_sub_f32_e32 v118, v158, v130
	v_sub_f32_e32 v121, v157, v130
	v_sub_f32_e32 v120, v156, v130
	v_mov_b32_e32 v156, v222
	v_mov_b32_e32 v157, v135
	v_pk_mul_f32 v[120:121], v[134:135], v[120:121]
	v_pk_mul_f32 v[118:119], v[156:157], v[118:119]
	s_waitcnt vmcnt(0) lgkmcnt(0)
	v_pk_fma_f32 v[120:121], v[120:121], v[136:137], v[140:141]
	v_pk_fma_f32 v[118:119], v[118:119], v[138:139], v[142:143]
	v_pk_add_f32 v[116:117], v[116:117], 1.0 op_sel_hi:[1,0]
	v_pk_add_f32 v[114:115], v[114:115], 1.0 op_sel_hi:[1,0]
	v_pk_mul_f32 v[120:121], v[120:121], s[64:65] op_sel_hi:[1,0]
	v_pk_mul_f32 v[118:119], v[118:119], s[64:65] op_sel_hi:[1,0]
	v_pk_fma_f32 v[110:111], v[110:111], v[114:115], v[120:121]
	v_pk_fma_f32 v[112:113], v[112:113], v[116:117], v[118:119]
	v_mov_b32_e32 v217, v223
	global_store_dwordx4 v[180:181], v[110:113], off offset:64
	v_mov_b32_e32 v158, v216
	v_mov_b32_e32 v159, v223
	v_sub_f32_e32 v111, v155, v131
	v_sub_f32_e32 v110, v154, v131
	v_sub_f32_e32 v113, v153, v131
	v_sub_f32_e32 v112, v152, v131
	v_pk_mul_f32 v[112:113], v[216:217], v[112:113]
	v_pk_mul_f32 v[110:111], v[158:159], v[110:111]
	v_pk_fma_f32 v[112:113], v[112:113], v[136:137], v[140:141]
	v_pk_fma_f32 v[110:111], v[110:111], v[138:139], v[142:143]
	v_pk_mul_f32 v[112:113], v[112:113], s[64:65] op_sel_hi:[1,0]
	v_pk_mul_f32 v[110:111], v[110:111], s[64:65] op_sel_hi:[1,0]
	v_pk_fma_f32 v[106:107], v[106:107], v[114:115], v[112:113]
	v_pk_fma_f32 v[108:109], v[108:109], v[116:117], v[110:111]
	v_mov_b32_e32 v221, v220
	global_store_dwordx4 v[176:177], v[106:109], off offset:64
	v_mov_b32_e32 v162, v220
	v_mov_b32_e32 v163, v220
	v_sub_f32_e32 v107, v151, v132
	v_sub_f32_e32 v106, v150, v132
	v_sub_f32_e32 v109, v149, v132
	v_sub_f32_e32 v108, v148, v132
	v_pk_mul_f32 v[108:109], v[220:221], v[108:109]
	v_pk_mul_f32 v[106:107], v[162:163], v[106:107]
	v_pk_fma_f32 v[108:109], v[108:109], v[136:137], v[140:141]
	v_pk_fma_f32 v[106:107], v[106:107], v[138:139], v[142:143]
	v_pk_mul_f32 v[108:109], v[108:109], s[64:65] op_sel_hi:[1,0]
	v_pk_mul_f32 v[106:107], v[106:107], s[64:65] op_sel_hi:[1,0]
	v_pk_fma_f32 v[102:103], v[102:103], v[114:115], v[108:109]
	v_pk_fma_f32 v[104:105], v[104:105], v[116:117], v[106:107]
	v_mov_b32_e32 v219, v218
	global_store_dwordx4 v[172:173], v[102:105], off offset:64
	s_and_b64 vcc, exec, s[2:3]
	v_mov_b32_e32 v122, 1.0
	v_sub_f32_e32 v105, v145, v133
	v_sub_f32_e32 v104, v144, v133
	v_sub_f32_e32 v103, v147, v133
	v_sub_f32_e32 v102, v146, v133
	v_pk_mul_f32 v[106:107], v[218:219], v[104:105]
	v_mov_b32_e32 v104, v218
	v_mov_b32_e32 v105, v218
	v_pk_mul_f32 v[102:103], v[104:105], v[102:103]
	v_pk_fma_f32 v[106:107], v[106:107], v[136:137], v[140:141]
	v_pk_fma_f32 v[102:103], v[102:103], v[138:139], v[142:143]
	v_pk_mul_f32 v[106:107], v[106:107], s[64:65] op_sel_hi:[1,0]
	v_pk_mul_f32 v[102:103], v[102:103], s[64:65] op_sel_hi:[1,0]
	v_pk_fma_f32 v[98:99], v[98:99], v[114:115], v[106:107]
	v_pk_fma_f32 v[100:101], v[100:101], v[116:117], v[102:103]
	global_store_dwordx4 v[160:161], v[98:101], off offset:64
	global_load_dwordx4 v[148:151], v[224:225], off offset:512
	global_load_dwordx4 v[118:121], v[224:225], off offset:576
	global_load_dwordx4 v[144:147], v[226:227], off offset:512
	global_load_dwordx4 v[114:117], v[226:227], off offset:576
	global_load_dwordx4 v[140:143], v[228:229], off offset:512
	global_load_dwordx4 v[110:113], v[228:229], off offset:576
	global_load_dwordx4 v[126:129], v[230:231], off offset:512
	global_load_dwordx4 v[106:109], v[230:231], off offset:576
	global_load_dwordx4 v[152:155], v[204:205], off offset:512
	v_mov_b32_e32 v102, 0
	v_mov_b32_e32 v98, 1.0
	v_mov_b32_e32 v123, 1.0
	v_mov_b32_e32 v124, 1.0
	v_mov_b32_e32 v125, 1.0
	v_mov_b32_e32 v136, 0
	v_mov_b32_e32 v137, 0
	v_mov_b32_e32 v138, 0
	v_mov_b32_e32 v139, 0
	s_cbranch_vccnz .LBB0_568
	global_load_dwordx4 v[122:125], v[206:207], off offset:512
	global_load_dwordx4 v[136:139], v[208:209], off offset:512
;     __device__ __forceinline__ void operator()(const f32x4 (&acc)[2][2][4][2], const Unit& u, int wr, int wc, int fr, int fq) const {
;     ...
;         for (int ai = 0; ai < 2; ++ai) {
;             float mu[4], rs[4];
; #pragma unroll
;             for (int m = 0; m < 4; ++m) { mu[m] = 0.f; rs[m] = 1.f;
;                 if (stats) { const float* sp = stats + (size_t)(row0 + ai * HALF + m * 16) * 2; mu[m] = sp[0]; rs[m] = sp[1]; } }
; #pragma unroll
;             for (int bj = 0; bj < 2; ++bj) {
;                 f32x4 xv[2][4];
; #pragma unroll
;                 for (int n = 0; n < 2; ++n)
; #pragma unroll
;                     for (int m = 0; m < 4; ++m) xv[n][m] = *(const f32x4*)(xin + (size_t)(row0 + ai * HALF + m * 16) * DM + col0 + bj * HALF + n * 16);
; #pragma unroll
;                 for (int n = 0; n < 2; ++n) {
;                     const int cofs = bj * HALF + n * 16;
;                     const f32x4 g4 = *(const f32x4*)(gv + cofs) + 1.0f;
;                     f32x4 lg = {1.f, 1.f, 1.f, 1.f}, lb = {0.f, 0.f, 0.f, 0.f};
;                     if (stats) { lg = *(const f32x4*)(lng + col0 + cofs); lb = *(const f32x4*)(lnb + col0 + cofs); }
; #pragma unroll
;                     for (int m = 0; m < 4; ++m) { const f32x4 x = (xv[n][m] - mu[m]) * rs[m] * lg + lb;
;                         *(f32x4*)(out + (size_t)(row0 + ai * HALF + m * 16) * DM + col0 + cofs) = x * ALPHA + g4 * acc[ai][bj][m][n]; }
.LBB0_568:
	s_waitcnt vmcnt(0) lgkmcnt(0)
	v_sub_f32_e32 v151, v151, v130
	v_sub_f32_e32 v150, v150, v130
	v_sub_f32_e32 v149, v149, v130
	v_sub_f32_e32 v148, v148, v130
	v_pk_mul_f32 v[148:149], v[134:135], v[148:149]
	v_pk_mul_f32 v[150:151], v[156:157], v[150:151]
	v_pk_fma_f32 v[148:149], v[148:149], v[122:123], v[136:137]
	v_pk_fma_f32 v[150:151], v[150:151], v[124:125], v[138:139]
	v_pk_add_f32 v[100:101], v[154:155], 1.0 op_sel_hi:[1,0]
	v_pk_add_f32 v[152:153], v[152:153], 1.0 op_sel_hi:[1,0]
	v_pk_mul_f32 v[148:149], v[148:149], s[64:65] op_sel_hi:[1,0]
	v_pk_mul_f32 v[150:151], v[150:151], s[64:65] op_sel_hi:[1,0]
	v_pk_fma_f32 v[94:95], v[94:95], v[152:153], v[148:149]
	v_pk_fma_f32 v[96:97], v[96:97], v[100:101], v[150:151]
	global_store_dwordx4 v[180:181], v[94:97], off offset:512
	s_and_b64 vcc, exec, s[2:3]
	v_mov_b32_e32 v99, 1.0
	v_sub_f32_e32 v95, v147, v131
	v_sub_f32_e32 v94, v146, v131
	v_sub_f32_e32 v97, v145, v131
	v_sub_f32_e32 v96, v144, v131
	v_pk_mul_f32 v[96:97], v[216:217], v[96:97]
	v_pk_mul_f32 v[94:95], v[158:159], v[94:95]
	v_pk_fma_f32 v[96:97], v[96:97], v[122:123], v[136:137]
	v_pk_fma_f32 v[94:95], v[94:95], v[124:125], v[138:139]
	v_pk_mul_f32 v[96:97], v[96:97], s[64:65] op_sel_hi:[1,0]
	v_pk_mul_f32 v[94:95], v[94:95], s[64:65] op_sel_hi:[1,0]
	v_pk_fma_f32 v[90:91], v[90:91], v[152:153], v[96:97]
	v_pk_fma_f32 v[92:93], v[92:93], v[100:101], v[94:95]
	global_store_dwordx4 v[176:177], v[90:93], off offset:512
	v_mov_b32_e32 v103, 0
	s_nop 0
	v_sub_f32_e32 v91, v143, v132
	v_sub_f32_e32 v90, v142, v132
	v_sub_f32_e32 v93, v141, v132
	v_sub_f32_e32 v92, v140, v132
	v_pk_mul_f32 v[92:93], v[220:221], v[92:93]
	v_pk_mul_f32 v[90:91], v[162:163], v[90:91]
	v_pk_fma_f32 v[92:93], v[92:93], v[122:123], v[136:137]
	v_pk_fma_f32 v[90:91], v[90:91], v[124:125], v[138:139]
	v_pk_mul_f32 v[92:93], v[92:93], s[64:65] op_sel_hi:[1,0]
	v_pk_mul_f32 v[90:91], v[90:91], s[64:65] op_sel_hi:[1,0]
	v_pk_fma_f32 v[86:87], v[86:87], v[152:153], v[92:93]
	v_pk_fma_f32 v[88:89], v[88:89], v[100:101], v[90:91]
	global_store_dwordx4 v[172:173], v[86:89], off offset:512
	s_nop 1
	v_sub_f32_e32 v87, v129, v133
	v_sub_f32_e32 v86, v128, v133
	v_sub_f32_e32 v89, v127, v133
	v_sub_f32_e32 v88, v126, v133
	v_pk_mul_f32 v[88:89], v[218:219], v[88:89]
	v_pk_mul_f32 v[86:87], v[104:105], v[86:87]
	v_pk_fma_f32 v[88:89], v[88:89], v[122:123], v[136:137]
	v_pk_fma_f32 v[86:87], v[86:87], v[124:125], v[138:139]
	v_pk_mul_f32 v[88:89], v[88:89], s[64:65] op_sel_hi:[1,0]
	v_pk_mul_f32 v[86:87], v[86:87], s[64:65] op_sel_hi:[1,0]
	v_pk_fma_f32 v[82:83], v[82:83], v[152:153], v[88:89]
	v_pk_fma_f32 v[84:85], v[84:85], v[100:101], v[86:87]
	global_store_dwordx4 v[160:161], v[82:85], off offset:512
	global_load_dwordx4 v[82:85], v[204:205], off offset:576
	v_mov_b32_e32 v100, 1.0
	v_mov_b32_e32 v101, 1.0
	v_mov_b32_e32 v104, 0
	v_mov_b32_e32 v105, 0
	s_cbranch_vccnz .LBB0_570
	global_load_dwordx4 v[98:101], v[206:207], off offset:576
	global_load_dwordx4 v[102:105], v[208:209], off offset:576
.LBB0_570:
	v_sub_f32_e32 v89, v119, v130
	v_sub_f32_e32 v88, v118, v130
	v_sub_f32_e32 v87, v121, v130
	v_sub_f32_e32 v86, v120, v130
	v_pk_mul_f32 v[88:89], v[134:135], v[88:89]
	v_mov_b32_e32 v134, v222
	v_pk_mul_f32 v[86:87], v[134:135], v[86:87]
	s_waitcnt vmcnt(0) lgkmcnt(0)
	v_pk_fma_f32 v[88:89], v[88:89], v[98:99], v[102:103]
	v_pk_fma_f32 v[86:87], v[86:87], v[100:101], v[104:105]
	v_pk_add_f32 v[84:85], v[84:85], 1.0 op_sel_hi:[1,0]
	v_pk_add_f32 v[82:83], v[82:83], 1.0 op_sel_hi:[1,0]
	v_pk_mul_f32 v[88:89], v[88:89], s[64:65] op_sel_hi:[1,0]
	v_pk_mul_f32 v[86:87], v[86:87], s[64:65] op_sel_hi:[1,0]
	v_pk_fma_f32 v[78:79], v[78:79], v[82:83], v[88:89]
	v_pk_fma_f32 v[80:81], v[80:81], v[84:85], v[86:87]
	global_store_dwordx4 v[180:181], v[78:81], off offset:576
	v_mov_b32_e32 v124, s71
	v_mov_b32_e32 v120, s33
	v_sub_f32_e32 v81, v115, v131
	v_sub_f32_e32 v80, v114, v131
	v_sub_f32_e32 v79, v117, v131
	v_sub_f32_e32 v78, v116, v131
	v_pk_mul_f32 v[80:81], v[216:217], v[80:81]
	v_mov_b32_e32 v217, v223
	v_pk_mul_f32 v[78:79], v[216:217], v[78:79]
	v_pk_fma_f32 v[80:81], v[80:81], v[98:99], v[102:103]
	v_pk_fma_f32 v[78:79], v[78:79], v[100:101], v[104:105]
	v_pk_mul_f32 v[80:81], v[80:81], s[64:65] op_sel_hi:[1,0]
	v_pk_mul_f32 v[78:79], v[78:79], s[64:65] op_sel_hi:[1,0]
	v_pk_fma_f32 v[74:75], v[74:75], v[82:83], v[80:81]
	v_pk_fma_f32 v[76:77], v[76:77], v[84:85], v[78:79]
	global_store_dwordx4 v[176:177], v[74:77], off offset:576
	s_and_b64 vcc, exec, s[2:3]
	s_nop 0
	v_sub_f32_e32 v77, v111, v132
	v_sub_f32_e32 v76, v110, v132
	v_sub_f32_e32 v75, v113, v132
	v_sub_f32_e32 v74, v112, v132
	v_pk_mul_f32 v[76:77], v[220:221], v[76:77]
	v_mov_b32_e32 v221, v220
	v_pk_mul_f32 v[74:75], v[220:221], v[74:75]
	v_pk_fma_f32 v[76:77], v[76:77], v[98:99], v[102:103]
	v_pk_fma_f32 v[74:75], v[74:75], v[100:101], v[104:105]
	v_pk_mul_f32 v[76:77], v[76:77], s[64:65] op_sel_hi:[1,0]
	v_pk_mul_f32 v[74:75], v[74:75], s[64:65] op_sel_hi:[1,0]
	v_pk_fma_f32 v[70:71], v[70:71], v[82:83], v[76:77]
	v_pk_fma_f32 v[72:73], v[72:73], v[84:85], v[74:75]
	global_store_dwordx4 v[172:173], v[70:73], off offset:576
	s_nop 1
	v_sub_f32_e32 v73, v107, v133
	v_sub_f32_e32 v72, v106, v133
	v_sub_f32_e32 v71, v109, v133
	v_sub_f32_e32 v70, v108, v133
	v_pk_mul_f32 v[72:73], v[218:219], v[72:73]
	v_mov_b32_e32 v219, v218
	v_pk_mul_f32 v[70:71], v[218:219], v[70:71]
	v_pk_fma_f32 v[72:73], v[72:73], v[98:99], v[102:103]
	v_pk_fma_f32 v[70:71], v[70:71], v[100:101], v[104:105]
	v_pk_mul_f32 v[72:73], v[72:73], s[64:65] op_sel_hi:[1,0]
	v_pk_mul_f32 v[70:71], v[70:71], s[64:65] op_sel_hi:[1,0]
	v_pk_fma_f32 v[66:67], v[66:67], v[82:83], v[72:73]
	v_pk_fma_f32 v[68:69], v[68:69], v[84:85], v[70:71]
	global_store_dwordx4 v[160:161], v[66:69], off offset:576
	s_nop 1
	v_add_u32_e32 v68, 0x80, v212
	v_ashrrev_i32_e32 v69, 31, v68
	s_cbranch_vccnz .LBB0_572
	v_lshl_add_u64 v[66:67], v[68:69], 3, s[12:13]
	global_load_dwordx2 v[124:125], v[66:67], off
	s_waitcnt vmcnt(0) lgkmcnt(0)
	v_mov_b32_e32 v120, v125
.LBB0_572:
	s_and_b64 vcc, exec, s[2:3]
	s_cbranch_vccnz .LBB0_576
	v_lshl_add_u64 v[66:67], v[212:213], 3, s[12:13]
	global_load_dwordx2 v[66:67], v[66:67], off offset:1152
	s_waitcnt vmcnt(0) lgkmcnt(0)
	v_mov_b32_e32 v1, v66
	v_mov_b32_e32 v121, v67
	s_and_b64 vcc, exec, s[2:3]
	s_cbranch_vccnz .LBB0_577
.LBB0_574:
	v_lshl_add_u64 v[66:67], v[212:213], 3, s[12:13]
	global_load_dwordx2 v[66:67], v[66:67], off offset:1280
	s_waitcnt vmcnt(0) lgkmcnt(0)
	v_mov_b32_e32 v122, v67
	v_add_u32_e32 v70, 0xb0, v212
	s_and_b64 vcc, exec, s[2:3]
	v_ashrrev_i32_e32 v71, 31, v70
	s_cbranch_vccnz .LBB0_578
.LBB0_575:
	v_lshl_add_u64 v[72:73], v[70:71], 3, s[12:13]
	global_load_dwordx2 v[72:73], v[72:73], off
	s_waitcnt vmcnt(0) lgkmcnt(0)
	v_mov_b32_e32 v67, v72
	v_mov_b32_e32 v123, v73
	s_branch .LBB0_579

;     __device__ __forceinline__ void operator()(const f32x4 (&acc)[2][2][4][2], const Unit& u, int wr, int wc, int fr, int fq) const {
;     ...
;             for (int bj = 0; bj < 2; ++bj) {
;                 f32x4 xv[2][4];
; #pragma unroll
;                 for (int n = 0; n < 2; ++n)
; #pragma unroll
;                     for (int m = 0; m < 4; ++m) xv[n][m] = *(const f32x4*)(xin + (size_t)(row0 + ai * HALF + m * 16) * DM + col0 + bj * HALF + n * 16);
; #pragma unroll
;                 for (int n = 0; n < 2; ++n) {
;                     const int cofs = bj * HALF + n * 16;
;                     const f32x4 g4 = *(const f32x4*)(gv + cofs) + 1.0f;
;                     f32x4 lg = {1.f, 1.f, 1.f, 1.f}, lb = {0.f, 0.f, 0.f, 0.f};
;                     if (stats) { lg = *(const f32x4*)(lng + col0 + cofs); lb = *(const f32x4*)(lnb + col0 + cofs); }
; #pragma unroll
;                     for (int m = 0; m < 4; ++m) { const f32x4 x = (xv[n][m] - mu[m]) * rs[m] * lg + lb;
;                         *(f32x4*)(out + (size_t)(row0 + ai * HALF + m * 16) * DM + col0 + cofs) = x * ALPHA + g4 * acc[ai][bj][m][n]; }
.LBB0_579:
	v_lshlrev_b64 v[136:137], 13, v[68:69]
	v_lshlrev_b64 v[68:69], 13, v[212:213]
	s_mov_b64 s[34:35], 0x120000
	v_lshl_add_u64 v[134:135], v[68:69], 0, s[34:35]
	s_mov_b64 s[34:35], 0x140000
	v_lshl_add_u64 v[126:127], v[214:215], 0, v[136:137]
	v_lshl_add_u64 v[74:75], v[68:69], 0, s[34:35]
	v_lshlrev_b64 v[70:71], 13, v[70:71]
	v_lshl_add_u64 v[128:129], v[214:215], 0, v[134:135]
	v_lshl_add_u64 v[130:131], v[214:215], 0, v[74:75]
	v_lshl_add_u64 v[132:133], v[214:215], 0, v[70:71]
	global_load_dwordx4 v[112:115], v[126:127], off
	global_load_dwordx4 v[88:91], v[126:127], off offset:64
	global_load_dwordx4 v[108:111], v[128:129], off
	global_load_dwordx4 v[84:87], v[128:129], off offset:64
	global_load_dwordx4 v[104:107], v[130:131], off
	global_load_dwordx4 v[80:83], v[130:131], off offset:64
	global_load_dwordx4 v[96:99], v[132:133], off
	global_load_dwordx4 v[76:79], v[132:133], off offset:64
	global_load_dwordx4 v[116:119], v[204:205], off
	v_mov_b32_e32 v72, 0
	v_mov_b32_e32 v68, 1.0
	s_and_b64 vcc, exec, s[2:3]
	v_mov_b32_e32 v92, 1.0
	v_mov_b32_e32 v93, 1.0
	v_mov_b32_e32 v94, 1.0
	v_mov_b32_e32 v95, 1.0
	v_mov_b32_e32 v100, 0
	v_mov_b32_e32 v101, 0
	v_mov_b32_e32 v102, 0
	v_mov_b32_e32 v103, 0
	s_cbranch_vccnz .LBB0_581
	global_load_dwordx4 v[92:95], v[206:207], off
	global_load_dwordx4 v[100:103], v[208:209], off
.LBB0_581:
	s_waitcnt vmcnt(0) lgkmcnt(0)
	v_sub_f32_e32 v113, v113, v124
	v_sub_f32_e32 v112, v112, v124
	v_sub_f32_e32 v115, v115, v124
	v_sub_f32_e32 v114, v114, v124
	v_pk_mul_f32 v[112:113], v[120:121], v[112:113] op_sel_hi:[0,1]
	v_pk_mul_f32 v[114:115], v[120:121], v[114:115] op_sel_hi:[0,1]
	v_pk_fma_f32 v[112:113], v[112:113], v[92:93], v[100:101]
	v_pk_add_f32 v[116:117], v[116:117], 1.0 op_sel_hi:[1,0]
	v_pk_fma_f32 v[114:115], v[114:115], v[94:95], v[102:103]
	v_pk_mul_f32 v[112:113], v[112:113], s[64:65] op_sel_hi:[1,0]
	v_pk_add_f32 v[118:119], v[118:119], 1.0 op_sel_hi:[1,0]
	v_pk_mul_f32 v[114:115], v[114:115], s[64:65] op_sel_hi:[1,0]
	v_pk_fma_f32 v[62:63], v[62:63], v[116:117], v[112:113]
	v_lshl_add_u64 v[112:113], s[8:9], 0, v[136:137]
	v_pk_fma_f32 v[64:65], v[64:65], v[118:119], v[114:115]
	v_lshl_add_u64 v[112:113], v[112:113], 0, v[210:211]
	global_store_dwordx4 v[112:113], v[62:65], off
	s_and_b64 vcc, exec, s[2:3]
	v_mov_b32_e32 v69, 1.0
	v_sub_f32_e32 v63, v111, v1
	v_sub_f32_e32 v62, v110, v1
	v_sub_f32_e32 v65, v109, v1
	v_sub_f32_e32 v64, v108, v1
	v_pk_mul_f32 v[62:63], v[120:121], v[62:63] op_sel:[1,0]
	v_pk_mul_f32 v[64:65], v[120:121], v[64:65] op_sel:[1,0]
	v_pk_fma_f32 v[62:63], v[62:63], v[94:95], v[102:103]
	v_pk_fma_f32 v[64:65], v[64:65], v[92:93], v[100:101]
	v_pk_mul_f32 v[62:63], v[62:63], s[64:65] op_sel_hi:[1,0]
	v_pk_mul_f32 v[64:65], v[64:65], s[64:65] op_sel_hi:[1,0]
	v_pk_fma_f32 v[60:61], v[60:61], v[118:119], v[62:63]
	v_lshl_add_u64 v[62:63], s[8:9], 0, v[134:135]
	v_pk_fma_f32 v[58:59], v[58:59], v[116:117], v[64:65]
	v_lshl_add_u64 v[108:109], v[62:63], 0, v[210:211]
	global_store_dwordx4 v[108:109], v[58:61], off
	v_mov_b32_e32 v73, 0
	s_nop 0
	v_sub_f32_e32 v59, v107, v66
	v_sub_f32_e32 v58, v106, v66
	v_sub_f32_e32 v61, v105, v66
	v_sub_f32_e32 v60, v104, v66
	v_pk_mul_f32 v[58:59], v[122:123], v[58:59] op_sel_hi:[0,1]
	v_pk_mul_f32 v[60:61], v[122:123], v[60:61] op_sel_hi:[0,1]
	v_pk_fma_f32 v[58:59], v[58:59], v[94:95], v[102:103]
	v_pk_fma_f32 v[60:61], v[60:61], v[92:93], v[100:101]
	v_pk_mul_f32 v[58:59], v[58:59], s[64:65] op_sel_hi:[1,0]
	v_pk_mul_f32 v[60:61], v[60:61], s[64:65] op_sel_hi:[1,0]
	v_pk_fma_f32 v[56:57], v[56:57], v[118:119], v[58:59]
	v_lshl_add_u64 v[58:59], s[8:9], 0, v[74:75]
	v_pk_fma_f32 v[54:55], v[54:55], v[116:117], v[60:61]
	v_lshl_add_u64 v[104:105], v[58:59], 0, v[210:211]
	global_store_dwordx4 v[104:105], v[54:57], off
	v_mov_b32_e32 v58, v123
	v_mov_b32_e32 v74, 0
	v_sub_f32_e32 v55, v99, v67
	v_sub_f32_e32 v54, v98, v67
	v_sub_f32_e32 v57, v97, v67
	v_sub_f32_e32 v56, v96, v67
	v_pk_mul_f32 v[54:55], v[58:59], v[54:55] op_sel_hi:[0,1]
	v_pk_mul_f32 v[56:57], v[58:59], v[56:57] op_sel_hi:[0,1]
	v_pk_fma_f32 v[54:55], v[54:55], v[94:95], v[102:103]
	v_pk_fma_f32 v[56:57], v[56:57], v[92:93], v[100:101]
	v_pk_mul_f32 v[54:55], v[54:55], s[64:65] op_sel_hi:[1,0]
	v_pk_mul_f32 v[56:57], v[56:57], s[64:65] op_sel_hi:[1,0]
	v_pk_fma_f32 v[52:53], v[52:53], v[118:119], v[54:55]
	v_lshl_add_u64 v[54:55], s[8:9], 0, v[70:71]
	v_pk_fma_f32 v[50:51], v[50:51], v[116:117], v[56:57]
	v_lshl_add_u64 v[92:93], v[54:55], 0, v[210:211]
	global_store_dwordx4 v[92:93], v[50:53], off
	global_load_dwordx4 v[50:53], v[204:205], off offset:64
	v_mov_b32_e32 v70, 1.0
	v_mov_b32_e32 v71, 1.0
	v_mov_b32_e32 v75, 0
	s_cbranch_vccnz .LBB0_583
	global_load_dwordx4 v[68:71], v[206:207], off offset:64
	global_load_dwordx4 v[72:75], v[208:209], off offset:64
;     __device__ __forceinline__ void operator()(const f32x4 (&acc)[2][2][4][2], const Unit& u, int wr, int wc, int fr, int fq) const {
;     ...
;             for (int bj = 0; bj < 2; ++bj) {
;                 f32x4 xv[2][4];
; #pragma unroll
;                 for (int n = 0; n < 2; ++n)
; #pragma unroll
;                     for (int m = 0; m < 4; ++m) xv[n][m] = *(const f32x4*)(xin + (size_t)(row0 + ai * HALF + m * 16) * DM + col0 + bj * HALF + n * 16);
; #pragma unroll
;                 for (int n = 0; n < 2; ++n) {
;                     const int cofs = bj * HALF + n * 16;
;                     const f32x4 g4 = *(const f32x4*)(gv + cofs) + 1.0f;
;                     f32x4 lg = {1.f, 1.f, 1.f, 1.f}, lb = {0.f, 0.f, 0.f, 0.f};
;                     if (stats) { lg = *(const f32x4*)(lng + col0 + cofs); lb = *(const f32x4*)(lnb + col0 + cofs); }
; #pragma unroll
;                     for (int m = 0; m < 4; ++m) { const f32x4 x = (xv[n][m] - mu[m]) * rs[m] * lg + lb;
;                         *(f32x4*)(out + (size_t)(row0 + ai * HALF + m * 16) * DM + col0 + cofs) = x * ALPHA + g4 * acc[ai][bj][m][n]; }
.LBB0_583:
	v_mov_b32_e32 v100, v120
	v_mov_b32_e32 v101, v120
	v_sub_f32_e32 v55, v91, v124
	v_sub_f32_e32 v54, v90, v124
	v_sub_f32_e32 v57, v89, v124
	v_sub_f32_e32 v56, v88, v124
	v_mov_b32_e32 v88, v120
	v_mov_b32_e32 v89, v120
	v_pk_mul_f32 v[56:57], v[100:101], v[56:57]
	v_pk_mul_f32 v[54:55], v[88:89], v[54:55]
	s_waitcnt vmcnt(0) lgkmcnt(0)
	v_pk_fma_f32 v[56:57], v[56:57], v[68:69], v[72:73]
	v_pk_fma_f32 v[54:55], v[54:55], v[70:71], v[74:75]
	v_pk_add_f32 v[52:53], v[52:53], 1.0 op_sel_hi:[1,0]
	v_pk_add_f32 v[50:51], v[50:51], 1.0 op_sel_hi:[1,0]
	v_pk_mul_f32 v[56:57], v[56:57], s[64:65] op_sel_hi:[1,0]
	v_pk_mul_f32 v[54:55], v[54:55], s[64:65] op_sel_hi:[1,0]
	v_pk_fma_f32 v[46:47], v[46:47], v[50:51], v[56:57]
	v_pk_fma_f32 v[48:49], v[48:49], v[52:53], v[54:55]
	v_mov_b32_e32 v98, v121
	v_mov_b32_e32 v99, v121
	global_store_dwordx4 v[112:113], v[46:49], off offset:64
	v_mov_b32_e32 v90, v121
	v_mov_b32_e32 v91, v121
	v_sub_f32_e32 v47, v87, v1
	v_sub_f32_e32 v46, v86, v1
	v_sub_f32_e32 v49, v85, v1
	v_sub_f32_e32 v48, v84, v1
	v_pk_mul_f32 v[48:49], v[98:99], v[48:49]
	v_pk_mul_f32 v[46:47], v[90:91], v[46:47]
	v_pk_fma_f32 v[48:49], v[48:49], v[68:69], v[72:73]
	v_pk_fma_f32 v[46:47], v[46:47], v[70:71], v[74:75]
	v_pk_mul_f32 v[48:49], v[48:49], s[64:65] op_sel_hi:[1,0]
	v_pk_mul_f32 v[46:47], v[46:47], s[64:65] op_sel_hi:[1,0]
	v_pk_fma_f32 v[42:43], v[42:43], v[50:51], v[48:49]
	v_pk_fma_f32 v[44:45], v[44:45], v[52:53], v[46:47]
	v_mov_b32_e32 v96, v122
	v_mov_b32_e32 v97, v122
	global_store_dwordx4 v[108:109], v[42:45], off offset:64
	v_mov_b32_e32 v102, v122
	v_mov_b32_e32 v103, v122
	v_sub_f32_e32 v43, v83, v66
	v_sub_f32_e32 v42, v82, v66
	v_sub_f32_e32 v45, v81, v66
	v_sub_f32_e32 v44, v80, v66
	v_pk_mul_f32 v[44:45], v[96:97], v[44:45]
	v_pk_mul_f32 v[42:43], v[102:103], v[42:43]
	v_pk_fma_f32 v[44:45], v[44:45], v[68:69], v[72:73]
	v_pk_fma_f32 v[42:43], v[42:43], v[70:71], v[74:75]
	v_pk_mul_f32 v[44:45], v[44:45], s[64:65] op_sel_hi:[1,0]
	v_pk_mul_f32 v[42:43], v[42:43], s[64:65] op_sel_hi:[1,0]
	v_pk_fma_f32 v[38:39], v[38:39], v[50:51], v[44:45]
	v_pk_fma_f32 v[40:41], v[40:41], v[52:53], v[42:43]
	v_mov_b32_e32 v94, v123
	v_mov_b32_e32 v95, v123
	global_store_dwordx4 v[104:105], v[38:41], off offset:64
	s_and_b64 vcc, exec, s[2:3]
	v_mov_b32_e32 v58, 1.0
	v_sub_f32_e32 v41, v77, v67
	v_sub_f32_e32 v40, v76, v67
	v_sub_f32_e32 v39, v79, v67
	v_sub_f32_e32 v38, v78, v67
	v_pk_mul_f32 v[42:43], v[94:95], v[40:41]
	v_mov_b32_e32 v40, v123
	v_mov_b32_e32 v41, v123
	v_pk_mul_f32 v[38:39], v[40:41], v[38:39]
	v_pk_fma_f32 v[42:43], v[42:43], v[68:69], v[72:73]
	v_pk_fma_f32 v[38:39], v[38:39], v[70:71], v[74:75]
	v_pk_mul_f32 v[42:43], v[42:43], s[64:65] op_sel_hi:[1,0]
	v_pk_mul_f32 v[38:39], v[38:39], s[64:65] op_sel_hi:[1,0]
	v_pk_fma_f32 v[34:35], v[34:35], v[50:51], v[42:43]
	v_pk_fma_f32 v[36:37], v[36:37], v[52:53], v[38:39]
	global_store_dwordx4 v[92:93], v[34:37], off offset:64
	global_load_dwordx4 v[80:83], v[126:127], off offset:512
	global_load_dwordx4 v[54:57], v[126:127], off offset:576
	global_load_dwordx4 v[76:79], v[128:129], off offset:512
	global_load_dwordx4 v[50:53], v[128:129], off offset:576
	global_load_dwordx4 v[72:75], v[130:131], off offset:512
	global_load_dwordx4 v[46:49], v[130:131], off offset:576
	global_load_dwordx4 v[62:65], v[132:133], off offset:512
	global_load_dwordx4 v[42:45], v[132:133], off offset:576
	global_load_dwordx4 v[84:87], v[204:205], off offset:512
	v_mov_b32_e32 v38, 0
	v_mov_b32_e32 v34, 1.0
	v_mov_b32_e32 v59, 1.0
	v_mov_b32_e32 v60, 1.0
	v_mov_b32_e32 v61, 1.0
	v_mov_b32_e32 v68, 0
	v_mov_b32_e32 v69, 0
	v_mov_b32_e32 v70, 0
	v_mov_b32_e32 v71, 0
	s_cbranch_vccnz .LBB0_585
	global_load_dwordx4 v[58:61], v[206:207], off offset:512
	global_load_dwordx4 v[68:71], v[208:209], off offset:512
.LBB0_585:
	s_waitcnt vmcnt(0) lgkmcnt(0)
	v_sub_f32_e32 v83, v83, v124
	v_sub_f32_e32 v82, v82, v124
	v_sub_f32_e32 v81, v81, v124
	v_sub_f32_e32 v80, v80, v124
	v_pk_mul_f32 v[80:81], v[100:101], v[80:81]
	v_pk_mul_f32 v[82:83], v[88:89], v[82:83]
	v_pk_fma_f32 v[80:81], v[80:81], v[58:59], v[68:69]
	v_pk_fma_f32 v[82:83], v[82:83], v[60:61], v[70:71]
	v_pk_add_f32 v[36:37], v[86:87], 1.0 op_sel_hi:[1,0]
	v_pk_add_f32 v[84:85], v[84:85], 1.0 op_sel_hi:[1,0]
	v_pk_mul_f32 v[80:81], v[80:81], s[64:65] op_sel_hi:[1,0]
	v_pk_mul_f32 v[82:83], v[82:83], s[64:65] op_sel_hi:[1,0]
	v_pk_fma_f32 v[30:31], v[30:31], v[84:85], v[80:81]
	v_pk_fma_f32 v[32:33], v[32:33], v[36:37], v[82:83]
	global_store_dwordx4 v[112:113], v[30:33], off offset:512
	s_and_b64 vcc, exec, s[2:3]
	v_mov_b32_e32 v35, 1.0
	v_sub_f32_e32 v31, v79, v1
	v_sub_f32_e32 v30, v78, v1
	v_sub_f32_e32 v33, v77, v1
	v_sub_f32_e32 v32, v76, v1
	v_pk_mul_f32 v[32:33], v[98:99], v[32:33]
	v_pk_mul_f32 v[30:31], v[90:91], v[30:31]
	v_pk_fma_f32 v[32:33], v[32:33], v[58:59], v[68:69]
	v_pk_fma_f32 v[30:31], v[30:31], v[60:61], v[70:71]
	v_pk_mul_f32 v[32:33], v[32:33], s[64:65] op_sel_hi:[1,0]
	v_pk_mul_f32 v[30:31], v[30:31], s[64:65] op_sel_hi:[1,0]
	v_pk_fma_f32 v[26:27], v[26:27], v[84:85], v[32:33]
	v_pk_fma_f32 v[28:29], v[28:29], v[36:37], v[30:31]
	global_store_dwordx4 v[108:109], v[26:29], off offset:512
	v_mov_b32_e32 v39, 0
	s_nop 0
	v_sub_f32_e32 v27, v75, v66
	v_sub_f32_e32 v26, v74, v66
	v_sub_f32_e32 v29, v73, v66
	v_sub_f32_e32 v28, v72, v66
	v_pk_mul_f32 v[28:29], v[96:97], v[28:29]
	v_pk_mul_f32 v[26:27], v[102:103], v[26:27]
	v_pk_fma_f32 v[28:29], v[28:29], v[58:59], v[68:69]
	v_pk_fma_f32 v[26:27], v[26:27], v[60:61], v[70:71]
	v_pk_mul_f32 v[28:29], v[28:29], s[64:65] op_sel_hi:[1,0]
	v_pk_mul_f32 v[26:27], v[26:27], s[64:65] op_sel_hi:[1,0]
	v_pk_fma_f32 v[22:23], v[22:23], v[84:85], v[28:29]
	v_pk_fma_f32 v[24:25], v[24:25], v[36:37], v[26:27]
	global_store_dwordx4 v[104:105], v[22:25], off offset:512
	s_nop 1
	v_sub_f32_e32 v23, v65, v67
	v_sub_f32_e32 v22, v64, v67
	v_sub_f32_e32 v25, v63, v67
	v_sub_f32_e32 v24, v62, v67
	v_pk_mul_f32 v[24:25], v[94:95], v[24:25]
	v_pk_mul_f32 v[22:23], v[40:41], v[22:23]
	v_pk_fma_f32 v[24:25], v[24:25], v[58:59], v[68:69]
	v_pk_fma_f32 v[22:23], v[22:23], v[60:61], v[70:71]
	v_pk_mul_f32 v[24:25], v[24:25], s[64:65] op_sel_hi:[1,0]
	v_pk_mul_f32 v[22:23], v[22:23], s[64:65] op_sel_hi:[1,0]
	v_pk_fma_f32 v[18:19], v[18:19], v[84:85], v[24:25]
	v_pk_fma_f32 v[20:21], v[20:21], v[36:37], v[22:23]
	global_store_dwordx4 v[92:93], v[18:21], off offset:512
	global_load_dwordx4 v[18:21], v[204:205], off offset:576
	v_mov_b32_e32 v36, 1.0
	v_mov_b32_e32 v37, 1.0
	v_mov_b32_e32 v40, 0
	v_mov_b32_e32 v41, 0
	s_cbranch_vccnz .LBB0_544
	global_load_dwordx4 v[34:37], v[206:207], off offset:576
	global_load_dwordx4 v[38:41], v[208:209], off offset:576
	s_branch .LBB0_544

; template <bool DO_LN, bool DO_H, bool DO_GATES, bool WRITE_X> ...
;     ...
;         const int row0 = grp * 16;
;         const float* mb = modl + (size_t)(row0 >> 11) * 12288 + lane * 4;
;         f32x4 PA[8], PB[8];
; #pragma unroll
;         for (int i = 0; i < 8; ++i) {
;             f32x4 g4 = {1.f, 1.f, 1.f, 1.f}, b4 = {0.f, 0.f, 0.f, 0.f};
;             if (DO_LN) { g4 = *(const f32x4*)(lng + lane * 4 + i * 256); b4 = *(const f32x4*)(lnb + lane * 4 + i * 256); }
;             if (DO_H) { const f32x4 sc = *(const f32x4*)(mb + sc_idx * 2048 + i * 256) + 1.0f, sh = *(const f32x4*)(mb + sh_idx * 2048 + i * 256);
;                 PA[i] = g4 * sc; PB[i] = b4 * sc + sh; }
;             else { PA[i] = g4; PB[i] = b4; }
;         }
;         f32x4 nv[8];
; #pragma unroll
;         for (int i = 0; i < 8; ++i) nv[i] = __builtin_nontemporal_load((const f32x4*)(src + (size_t)row0 * DM + lane * 4 + i * 256));
.LBB0_599:
	v_ashrrev_i32_e32 v2, 7, v1
	s_mov_b32 s2, 0xc000
	v_mad_i64_i32 v[2:3], s[2:3], v2, s2, v[66:67]
	v_add_co_u32_e32 v16, vcc, 0x8000, v2
	global_load_dwordx4 v[4:7], v[68:69], off
	global_load_dwordx4 v[8:11], v[70:71], off
	v_addc_co_u32_e32 v17, vcc, 0, v3, vcc
	global_load_dwordx4 v[12:15], v[16:17], off
	v_add_co_u32_e32 v22, vcc, s42, v2
	s_mov_b32 s2, 0x9000
	s_nop 0
	v_addc_co_u32_e32 v23, vcc, 0, v3, vcc
	v_lshlrev_b32_e32 v34, 4, v1
	v_ashrrev_i32_e32 v35, 31, v34
	v_lshlrev_b64 v[36:37], 12, v[34:35]
	v_lshl_add_u64 v[156:157], v[34:35], 3, s[6:7]
	v_lshl_add_u64 v[158:159], v[90:91], 0, v[36:37]
	v_or_b32_e32 v160, 1, v34
	s_mov_b64 s[16:17], 0
	s_waitcnt vmcnt(0) lgkmcnt(0)
	v_pk_add_f32 v[18:19], v[14:15], 1.0 op_sel_hi:[1,0]
	v_pk_add_f32 v[20:21], v[12:13], 1.0 op_sel_hi:[1,0]
	global_load_dwordx4 v[12:15], v[22:23], off
	v_pk_mul_f32 v[92:93], v[6:7], v[18:19]
	v_pk_mul_f32 v[94:95], v[4:5], v[20:21]
	s_waitcnt vmcnt(0) lgkmcnt(0)
	v_pk_fma_f32 v[96:97], v[10:11], v[18:19], v[14:15]
	v_pk_fma_f32 v[98:99], v[8:9], v[20:21], v[12:13]
	global_load_dwordx4 v[4:7], v[68:69], off offset:1024
	global_load_dwordx4 v[8:11], v[70:71], off offset:1024
	global_load_dwordx4 v[12:15], v[16:17], off offset:1024
	s_waitcnt vmcnt(0) lgkmcnt(0)
	v_pk_add_f32 v[18:19], v[14:15], 1.0 op_sel_hi:[1,0]
	v_pk_add_f32 v[20:21], v[12:13], 1.0 op_sel_hi:[1,0]
	global_load_dwordx4 v[12:15], v[22:23], off offset:1024
	v_pk_mul_f32 v[100:101], v[6:7], v[18:19]
	v_pk_mul_f32 v[102:103], v[4:5], v[20:21]
	s_waitcnt vmcnt(0) lgkmcnt(0)
	v_pk_fma_f32 v[104:105], v[10:11], v[18:19], v[14:15]
	v_pk_fma_f32 v[106:107], v[8:9], v[20:21], v[12:13]
	global_load_dwordx4 v[4:7], v[68:69], off offset:2048
	global_load_dwordx4 v[8:11], v[70:71], off offset:2048
	global_load_dwordx4 v[12:15], v[16:17], off offset:2048
	s_waitcnt vmcnt(0) lgkmcnt(0)
	v_pk_add_f32 v[18:19], v[14:15], 1.0 op_sel_hi:[1,0]
	v_pk_add_f32 v[20:21], v[12:13], 1.0 op_sel_hi:[1,0]
	global_load_dwordx4 v[12:15], v[22:23], off offset:2048
	v_pk_mul_f32 v[108:109], v[6:7], v[18:19]
	v_pk_mul_f32 v[110:111], v[4:5], v[20:21]
	s_waitcnt vmcnt(0) lgkmcnt(0)
	v_pk_fma_f32 v[112:113], v[10:11], v[18:19], v[14:15]
	v_pk_fma_f32 v[114:115], v[8:9], v[20:21], v[12:13]
	global_load_dwordx4 v[4:7], v[68:69], off offset:3072
	global_load_dwordx4 v[8:11], v[70:71], off offset:3072
	global_load_dwordx4 v[12:15], v[16:17], off offset:3072
	s_waitcnt vmcnt(0) lgkmcnt(0)
	v_pk_add_f32 v[16:17], v[14:15], 1.0 op_sel_hi:[1,0]
	v_pk_add_f32 v[18:19], v[12:13], 1.0 op_sel_hi:[1,0]
	global_load_dwordx4 v[12:15], v[22:23], off offset:3072
	v_pk_mul_f32 v[116:117], v[6:7], v[16:17]
	v_pk_mul_f32 v[118:119], v[4:5], v[18:19]
	s_waitcnt vmcnt(0) lgkmcnt(0)
	v_pk_fma_f32 v[120:121], v[10:11], v[16:17], v[14:15]
	v_add_co_u32_e32 v16, vcc, s2, v2
	v_pk_fma_f32 v[122:123], v[8:9], v[18:19], v[12:13]
	s_nop 0
	v_addc_co_u32_e32 v17, vcc, 0, v3, vcc
	global_load_dwordx4 v[4:7], v[74:75], off
	global_load_dwordx4 v[8:11], v[76:77], off
	global_load_dwordx4 v[12:15], v[16:17], off
	s_movk_i32 s2, 0x7000
	v_add_co_u32_e32 v22, vcc, s2, v2
	s_waitcnt vmcnt(0) lgkmcnt(0)
	v_pk_add_f32 v[18:19], v[14:15], 1.0 op_sel_hi:[1,0]
	v_addc_co_u32_e32 v23, vcc, 0, v3, vcc
	v_pk_add_f32 v[20:21], v[12:13], 1.0 op_sel_hi:[1,0]
	global_load_dwordx4 v[12:15], v[22:23], off
	v_pk_mul_f32 v[124:125], v[6:7], v[18:19]
	v_pk_mul_f32 v[126:127], v[4:5], v[20:21]
	s_waitcnt vmcnt(0) lgkmcnt(0)
	v_pk_fma_f32 v[128:129], v[10:11], v[18:19], v[14:15]
	v_pk_fma_f32 v[130:131], v[8:9], v[20:21], v[12:13]
	global_load_dwordx4 v[2:5], v[78:79], off
	global_load_dwordx4 v[6:9], v[80:81], off
	global_load_dwordx4 v[10:13], v[16:17], off offset:1024
	s_waitcnt vmcnt(0) lgkmcnt(0)
	v_pk_add_f32 v[14:15], v[12:13], 1.0 op_sel_hi:[1,0]
	v_pk_add_f32 v[18:19], v[10:11], 1.0 op_sel_hi:[1,0]
	global_load_dwordx4 v[10:13], v[22:23], off offset:1024
	v_pk_mul_f32 v[132:133], v[4:5], v[14:15]
	v_pk_mul_f32 v[134:135], v[2:3], v[18:19]
	s_waitcnt vmcnt(0) lgkmcnt(0)
	v_pk_fma_f32 v[136:137], v[8:9], v[14:15], v[12:13]
	v_pk_fma_f32 v[138:139], v[6:7], v[18:19], v[10:11]
	global_load_dwordx4 v[2:5], v[82:83], off
	global_load_dwordx4 v[6:9], v[84:85], off
	global_load_dwordx4 v[10:13], v[16:17], off offset:2048
	s_waitcnt vmcnt(0) lgkmcnt(0)
	v_pk_add_f32 v[14:15], v[12:13], 1.0 op_sel_hi:[1,0]
	v_pk_add_f32 v[18:19], v[10:11], 1.0 op_sel_hi:[1,0]
	global_load_dwordx4 v[10:13], v[22:23], off offset:2048
	v_pk_mul_f32 v[140:141], v[4:5], v[14:15]
	v_pk_mul_f32 v[142:143], v[2:3], v[18:19]
	s_waitcnt vmcnt(0) lgkmcnt(0)
	v_pk_fma_f32 v[144:145], v[8:9], v[14:15], v[12:13]
	v_pk_fma_f32 v[146:147], v[6:7], v[18:19], v[10:11]
	global_load_dwordx4 v[2:5], v[86:87], off
	global_load_dwordx4 v[6:9], v[88:89], off
	global_load_dwordx4 v[10:13], v[16:17], off offset:3072
	s_waitcnt vmcnt(0) lgkmcnt(0)
	v_pk_add_f32 v[14:15], v[12:13], 1.0 op_sel_hi:[1,0]
	v_pk_add_f32 v[16:17], v[10:11], 1.0 op_sel_hi:[1,0]
	global_load_dwordx4 v[10:13], v[22:23], off offset:3072
	v_pk_mul_f32 v[150:151], v[2:3], v[16:17]
	v_lshlrev_b64 v[2:3], 13, v[34:35]
	v_lshl_add_u64 v[18:19], v[72:73], 0, v[2:3]
	v_add_co_u32_e32 v30, vcc, 0x1000, v18
	v_pk_mul_f32 v[148:149], v[4:5], v[14:15]
	s_nop 0
	v_addc_co_u32_e32 v31, vcc, 0, v19, vcc
	s_waitcnt vmcnt(0) lgkmcnt(0)
	v_pk_fma_f32 v[152:153], v[8:9], v[14:15], v[12:13]
	v_pk_fma_f32 v[154:155], v[6:7], v[16:17], v[10:11]
	global_load_dwordx4 v[14:17], v[18:19], off nt
	global_load_dwordx4 v[10:13], v[18:19], off offset:1024 nt
	global_load_dwordx4 v[6:9], v[18:19], off offset:2048 nt
	global_load_dwordx4 v[2:5], v[18:19], off offset:3072 nt
	global_load_dwordx4 v[26:29], v[30:31], off nt
	global_load_dwordx4 v[22:25], v[30:31], off offset:1024 nt
	s_nop 0
	global_load_dwordx4 v[18:21], v[30:31], off offset:2048 nt
	s_nop 0
	global_load_dwordx4 v[30:33], v[30:31], off offset:3072 nt
	s_waitcnt vmcnt(0) lgkmcnt(0)
	v_mov_b64_e32 v[48:49], v[16:17]
	v_mov_b64_e32 v[64:65], v[28:29]
	v_mov_b64_e32 v[60:61], v[24:25]
	v_mov_b64_e32 v[56:57], v[20:21]
	v_mov_b64_e32 v[52:53], v[32:33]
	v_mov_b64_e32 v[36:37], v[4:5]
	v_mov_b64_e32 v[40:41], v[8:9]
	v_mov_b64_e32 v[44:45], v[12:13]
	v_mov_b64_e32 v[50:51], v[30:31]
	v_mov_b64_e32 v[54:55], v[18:19]
	v_mov_b64_e32 v[58:59], v[22:23]
	v_mov_b64_e32 v[62:63], v[26:27]
	v_mov_b64_e32 v[34:35], v[2:3]
	v_mov_b64_e32 v[38:39], v[6:7]
	v_mov_b64_e32 v[42:43], v[10:11]
	v_mov_b64_e32 v[46:47], v[14:15]
	s_branch .LBB0_601
; #define LAS __attribute__((address_space(3)))
; __device__ __forceinline__ unsigned cvt_pk_bf16(float lo, float hi) { f32x2_t f = {lo, hi}; bf16x2_t v = __builtin_convertvector(f, bf16x2_t); return __builtin_bit_cast(unsigned, v); }
; template <bool DO_LN, bool DO_H, bool DO_GATES, bool WRITE_X> ...
;     ...
;         for (int rr = 0; rr < 16; ++rr) {
;             const int row = row0 + rr;
;             f32x4 v[8];
; #pragma unroll
;             for (int i = 0; i < 8; ++i) v[i] = nv[i];
;             if (rr + 1 < 16) {
; #pragma unroll
;                 for (int i = 0; i < 8; ++i) nv[i] = __builtin_nontemporal_load((const f32x4*)(src + (size_t)(row + 1) * DM + lane * 4 + i * 256)); }
;             if (DO_LN) {
;                 float s = 0.f;
; #pragma unroll
;                 for (int i = 0; i < 8; ++i) s += (v[i][0] + v[i][1]) + (v[i][2] + v[i][3]);
;                 const float mu = wave_sum(s, lane) * (1.0f / DM);
;                 float q = 0.f;
; #pragma unroll
;                 for (int i = 0; i < 8; ++i) { const f32x4 d = v[i] - mu; q += (d[0] * d[0] + d[1] * d[1]) + (d[2] * d[2] + d[3] * d[3]); }
;                 const float rstd = 1.0f / sqrtf(wave_sum(q, lane) * (1.0f / DM) + LN_EPS);
; #pragma unroll
;                 for (int i = 0; i < 8; ++i) v[i] = (v[i] - mu) * rstd;
;                 if (!WRITE_X && lane == 0) { float* st = (float*)(ws + WS_STATS) + (size_t)row * 2; st[0] = mu; st[1] = rstd; }
;             }
;             if (WRITE_X && !DO_H) {
; #pragma unroll
;                 for (int i = 0; i < 8; ++i) __builtin_nontemporal_store(v[i] * PA[i] + PB[i], (f32x4*)(xout + (size_t)row * DM + lane * 4 + i * 256));
;             }
;             if (DO_H) {
;                 float ga[8];
; #pragma unroll
;                 for (int gg = 0; gg < 8; ++gg) ga[gg] = 0.f;
; #pragma unroll
;                 for (int i = 0; i < 8; ++i) { const f32x4 h = v[i] * PA[i] + PB[i];
;                     u32x2 w; w.x = cvt_pk_bf16(h[0], h[1]); w.y = cvt_pk_bf16(h[2], h[3]);
;                     *(u32x2*)(H + (size_t)row * DM + lane * 4 + i * 256) = w;
;                     if (DO_GATES) {
; #pragma unroll
;                         for (int gg = 0; gg < 8; ++gg) { const f32x4 w4 = *(const LAS f32x4*)(wif + gg * 2048 + lane * 4 + i * 256); ga[gg] += (h[0] * w4[0] + h[1] * w4[1]) + (h[2] * w4[2] + h[3] * w4[3]); }
;                     } }
.LBB0_600:
	s_or_b64 exec, exec, s[2:3]
	v_mov_b32_e32 v15, v164
	v_mov_b32_e32 v11, v165
	v_mov_b32_e32 v164, v16
	v_mov_b32_e32 v165, v162
	v_mov_b32_e32 v162, v17
	v_pk_mul_f32 v[164:165], v[164:165], v[32:33] op_sel_hi:[1,0]
	v_pk_mul_f32 v[14:15], v[14:15], v[32:33] op_sel_hi:[1,0]
	v_pk_mul_f32 v[16:17], v[162:163], v[32:33] op_sel_hi:[1,0]
	v_pk_mul_f32 v[10:11], v[10:11], v[32:33] op_sel_hi:[1,0]
	v_pk_mul_f32 v[8:9], v[8:9], v[32:33] op_sel_hi:[1,0]
	v_pk_mul_f32 v[6:7], v[6:7], v[32:33] op_sel_hi:[1,0]
	v_pk_mul_f32 v[4:5], v[4:5], v[32:33] op_sel_hi:[1,0]
	v_pk_mul_f32 v[2:3], v[2:3], v[32:33] op_sel_hi:[1,0]
	v_pk_mul_f32 v[12:13], v[12:13], v[32:33] op_sel_hi:[1,0]
	v_pk_mul_f32 v[26:27], v[26:27], v[32:33] op_sel_hi:[1,0]
	v_pk_mul_f32 v[24:25], v[24:25], v[32:33] op_sel_hi:[1,0]
	v_pk_mul_f32 v[22:23], v[22:23], v[32:33] op_sel_hi:[1,0]
	v_pk_mul_f32 v[20:21], v[20:21], v[32:33] op_sel_hi:[1,0]
	v_pk_mul_f32 v[18:19], v[18:19], v[32:33] op_sel_hi:[1,0]
	v_pk_mul_f32 v[28:29], v[28:29], v[32:33] op_sel_hi:[1,0]
	v_pk_mul_f32 v[30:31], v[30:31], v[32:33] op_sel_hi:[1,0]
	v_lshl_add_u64 v[32:33], v[158:159], 0, s[16:17]
	v_add_co_u32_e32 v32, vcc, s85, v32
	v_pk_fma_f32 v[4:5], v[116:117], v[4:5], v[120:121]
	v_pk_fma_f32 v[2:3], v[118:119], v[2:3], v[122:123]
	v_addc_co_u32_e32 v33, vcc, 0, v33, vcc
	v_cvt_pk_bf16_f32 v2, v2, v3
	v_cvt_pk_bf16_f32 v3, v4, v5
	global_store_dwordx2 v[32:33], v[2:3], off offset:1536
	v_pk_fma_f32 v[2:3], v[124:125], v[12:13], v[128:129]
	v_pk_fma_f32 v[4:5], v[126:127], v[26:27], v[130:131]
	v_pk_fma_f32 v[162:163], v[92:93], v[164:165], v[96:97]
	v_cvt_pk_bf16_f32 v4, v4, v5
	v_cvt_pk_bf16_f32 v5, v2, v3
	global_store_dwordx2 v[32:33], v[4:5], off offset:2048
	v_pk_fma_f32 v[2:3], v[132:133], v[24:25], v[136:137]
	v_pk_fma_f32 v[4:5], v[134:135], v[22:23], v[138:139]
	v_pk_fma_f32 v[14:15], v[94:95], v[14:15], v[98:99]
	v_cvt_pk_bf16_f32 v4, v4, v5
	v_cvt_pk_bf16_f32 v5, v2, v3
	global_store_dwordx2 v[32:33], v[4:5], off offset:2560
	v_pk_fma_f32 v[2:3], v[140:141], v[20:21], v[144:145]
	v_pk_fma_f32 v[4:5], v[142:143], v[18:19], v[146:147]
	v_cvt_pk_bf16_f32 v14, v14, v15
	v_cvt_pk_bf16_f32 v15, v162, v163
	v_cvt_pk_bf16_f32 v4, v4, v5
	v_cvt_pk_bf16_f32 v5, v2, v3
	global_store_dwordx2 v[32:33], v[14:15], off
	v_pk_fma_f32 v[14:15], v[100:101], v[16:17], v[104:105]
	v_pk_fma_f32 v[10:11], v[102:103], v[10:11], v[106:107]
	v_pk_fma_f32 v[8:9], v[108:109], v[8:9], v[112:113]
	v_pk_fma_f32 v[6:7], v[110:111], v[6:7], v[114:115]
	global_store_dwordx2 v[32:33], v[4:5], off offset:3072
	v_pk_fma_f32 v[2:3], v[148:149], v[28:29], v[152:153]
	v_pk_fma_f32 v[4:5], v[150:151], v[30:31], v[154:155]
	v_cvt_pk_bf16_f32 v10, v10, v11
	v_cvt_pk_bf16_f32 v11, v14, v15
	v_cvt_pk_bf16_f32 v6, v6, v7
	v_cvt_pk_bf16_f32 v7, v8, v9
	v_cvt_pk_bf16_f32 v4, v4, v5
	v_cvt_pk_bf16_f32 v5, v2, v3
	s_add_u32 s16, s16, 0x1000
	global_store_dwordx2 v[32:33], v[10:11], off offset:512
	global_store_dwordx2 v[32:33], v[6:7], off offset:1024
	global_store_dwordx2 v[32:33], v[4:5], off offset:3584
	s_addc_u32 s17, s17, 0
	s_waitcnt vmcnt(0)
	v_mov_b64_e32 v[30:31], v[50:51]
	v_mov_b64_e32 v[18:19], v[54:55]
	v_mov_b64_e32 v[22:23], v[58:59]
	v_mov_b64_e32 v[26:27], v[62:63]
	v_mov_b64_e32 v[2:3], v[34:35]
	v_mov_b64_e32 v[6:7], v[38:39]
	v_mov_b64_e32 v[10:11], v[42:43]
	v_mov_b64_e32 v[14:15], v[46:47]
	v_lshl_add_u64 v[156:157], v[156:157], 0, 8
	v_add_u32_e32 v160, 1, v160
	s_cmp_eq_u32 s16, 0x10000
	v_mov_b64_e32 v[32:33], v[52:53]
	v_mov_b64_e32 v[20:21], v[56:57]
	v_mov_b64_e32 v[24:25], v[60:61]
	v_mov_b64_e32 v[28:29], v[64:65]
	v_mov_b64_e32 v[4:5], v[36:37]
	v_mov_b64_e32 v[8:9], v[40:41]
	v_mov_b64_e32 v[12:13], v[44:45]
	v_mov_b64_e32 v[16:17], v[48:49]
	s_cbranch_scc1 .LBB0_598
.LBB0_601:
	s_cmpk_eq_u32 s16, 0xf000
	s_cbranch_scc1 .LBB0_603
	v_ashrrev_i32_e32 v161, 31, v160
	v_lshlrev_b64 v[34:35], 13, v[160:161]
	v_lshl_add_u64 v[50:51], v[72:73], 0, v[34:35]
	global_load_dwordx4 v[46:49], v[50:51], off nt
	global_load_dwordx4 v[42:45], v[50:51], off offset:1024 nt
	global_load_dwordx4 v[38:41], v[50:51], off offset:2048 nt
	global_load_dwordx4 v[34:37], v[50:51], off offset:3072 nt
	v_add_co_u32_e32 v50, vcc, 0x1000, v50
	s_nop 1
	v_addc_co_u32_e32 v51, vcc, 0, v51, vcc
	global_load_dwordx4 v[62:65], v[50:51], off nt
	global_load_dwordx4 v[58:61], v[50:51], off offset:1024 nt
	global_load_dwordx4 v[54:57], v[50:51], off offset:2048 nt
	s_nop 0
	global_load_dwordx4 v[50:53], v[50:51], off offset:3072 nt
; template <bool DO_LN, bool DO_H, bool DO_GATES, bool WRITE_X> ...
;     ...
;             if (DO_LN) {
;                 float s = 0.f;
; #pragma unroll
;                 for (int i = 0; i < 8; ++i) s += (v[i][0] + v[i][1]) + (v[i][2] + v[i][3]);
;                 const float mu = wave_sum(s, lane) * (1.0f / DM);
;                 float q = 0.f;
; #pragma unroll
;                 for (int i = 0; i < 8; ++i) { const f32x4 d = v[i] - mu; q += (d[0] * d[0] + d[1] * d[1]) + (d[2] * d[2] + d[3] * d[3]); }
;                 const float rstd = 1.0f / sqrtf(wave_sum(q, lane) * (1.0f / DM) + LN_EPS);
; #pragma unroll
;                 for (int i = 0; i < 8; ++i) v[i] = (v[i] - mu) * rstd;
;                 if (!WRITE_X && lane == 0) { float* st = (float*)(ws + WS_STATS) + (size_t)row * 2; st[0] = mu; st[1] = rstd; }
.LBB0_603:
	v_mov_b32_e32 v162, v10
	v_mov_b32_e32 v163, v14
	v_mov_b32_e32 v164, v11
	v_mov_b32_e32 v165, v15
	v_pk_add_f32 v[162:163], v[162:163], v[164:165]
	v_mov_b32_e32 v164, v12
	v_mov_b32_e32 v165, v16
	v_mov_b32_e32 v172, v13
	v_mov_b32_e32 v173, v17
	v_pk_add_f32 v[164:165], v[164:165], v[172:173]
	v_mov_b32_e32 v172, v6
	v_pk_add_f32 v[162:163], v[162:163], v[164:165]
	v_mov_b32_e32 v164, v7
	v_mov_b32_e32 v165, v8
	v_mov_b32_e32 v173, v9
	v_pk_add_f32 v[164:165], v[164:165], v[172:173]
	v_add_f32_e32 v161, 0, v163
	v_pk_add_f32 v[164:165], v[164:165], v[164:165] op_sel_hi:[0,1]
	v_add_f32_e32 v163, v162, v161
	v_add_f32_e32 v173, v2, v3
	v_add_f32_e32 v175, v4, v5
	v_mov_b32_e32 v172, v26
	v_mov_b32_e32 v174, v27
	v_mov_b32_e32 v164, v28
	v_mov_b32_e32 v162, v29
	v_pk_add_f32 v[172:173], v[172:173], v[174:175]
	v_pk_add_f32 v[162:163], v[164:165], v[162:163]
	v_mov_b32_e32 v164, v23
	v_pk_add_f32 v[162:163], v[172:173], v[162:163]
	v_mov_b32_e32 v165, v24
	v_mov_b32_e32 v172, v22
	v_mov_b32_e32 v173, v25
	v_pk_add_f32 v[164:165], v[164:165], v[172:173]
	v_pk_add_f32 v[162:163], v[162:163], v[162:163] op_sel_hi:[0,1]
	v_pk_add_f32 v[164:165], v[164:165], v[164:165] op_sel_hi:[0,1]
	v_add_f32_e32 v173, v18, v19
	v_add_f32_e32 v175, v20, v21
	v_mov_b32_e32 v172, v30
	v_mov_b32_e32 v174, v31
	v_mov_b32_e32 v164, v32
	v_mov_b32_e32 v162, v33
	v_pk_add_f32 v[172:173], v[172:173], v[174:175]
	v_pk_add_f32 v[162:163], v[164:165], v[162:163]
	s_nop 0
	v_pk_add_f32 v[162:163], v[172:173], v[162:163]
	s_nop 0
	v_add_f32_e32 v161, v162, v163
	ds_bpermute_b32 v162, v166, v161
	s_waitcnt lgkmcnt(0)
	v_add_f32_e32 v161, v161, v162
	ds_bpermute_b32 v162, v167, v161
	s_waitcnt lgkmcnt(0)
	v_add_f32_e32 v161, v161, v162
	ds_bpermute_b32 v162, v168, v161
	s_waitcnt lgkmcnt(0)
	v_add_f32_e32 v161, v161, v162
	ds_bpermute_b32 v162, v169, v161
	s_waitcnt lgkmcnt(0)
	v_add_f32_e32 v161, v161, v162
	ds_bpermute_b32 v162, v170, v161
	s_waitcnt lgkmcnt(0)
	v_add_f32_e32 v161, v161, v162
	ds_bpermute_b32 v162, v171, v161
	s_waitcnt lgkmcnt(0)
	v_add_f32_e32 v161, v161, v162
	v_fmamk_f32 v162, v161, 0xba000000, v17
	v_fmamk_f32 v164, v161, 0xba000000, v15
	v_fmamk_f32 v163, v161, 0xba000000, v13
	v_fmamk_f32 v165, v161, 0xba000000, v11
	v_fmac_f32_e32 v10, 0xba000000, v161
	v_fmamk_f32 v16, v161, 0xba000000, v16
	v_fmac_f32_e32 v14, 0xba000000, v161
	v_fmamk_f32 v17, v161, 0xba000000, v12
	v_mov_b32_e32 v15, v10
	v_pk_mul_f32 v[12:13], v[164:165], v[164:165]
	v_pk_mul_f32 v[172:173], v[162:163], v[162:163]
	v_pk_fma_f32 v[12:13], v[14:15], v[14:15], v[12:13]
	v_pk_fma_f32 v[172:173], v[16:17], v[16:17], v[172:173]
	v_fmamk_f32 v9, v161, 0xba000000, v9
	v_pk_add_f32 v[12:13], v[12:13], v[172:173]
	v_fmamk_f32 v8, v161, 0xba000000, v8
	v_fmamk_f32 v7, v161, 0xba000000, v7
	v_fmac_f32_e32 v6, 0xba000000, v161
	v_pk_add_f32 v[172:173], v[12:13], v[12:13] op_sel_hi:[0,1]
	v_pk_mul_f32 v[12:13], v[8:9], v[8:9]
	v_pk_mul_f32 v[174:175], v[6:7], v[6:7]
	v_fmac_f32_e32 v2, 0xba000000, v161
	v_pk_mov_b32 v[176:177], v[174:175], v[12:13] op_sel:[1,0]
	v_mov_b32_e32 v175, v13
	v_pk_add_f32 v[12:13], v[176:177], v[174:175]
	v_fmamk_f32 v4, v161, 0xba000000, v4
	v_pk_add_f32 v[174:175], v[12:13], v[12:13] op_sel_hi:[0,1]
	v_fmamk_f32 v3, v161, 0xba000000, v3
	v_mul_f32_e32 v12, v2, v2
	v_fmamk_f32 v5, v161, 0xba000000, v5
	v_pk_fma_f32 v[176:177], v[2:3], v[2:3], v[12:13] op_sel_hi:[1,1,0]
	v_mul_f32_e32 v12, v4, v4
	v_pk_fma_f32 v[178:179], v[4:5], v[4:5], v[12:13] op_sel_hi:[1,1,0]
	v_fmamk_f32 v13, v161, 0xba000000, v29
	v_fmamk_f32 v12, v161, 0xba000000, v28
	v_fmamk_f32 v27, v161, 0xba000000, v27
	v_fmac_f32_e32 v26, 0xba000000, v161
	v_mul_f32_e32 v176, v26, v26
	v_mul_f32_e32 v178, v27, v27
	v_mul_f32_e32 v174, v12, v12
	v_mul_f32_e32 v172, v13, v13
	v_pk_add_f32 v[28:29], v[176:177], v[178:179]
	v_pk_add_f32 v[172:173], v[174:175], v[172:173]
	v_fmamk_f32 v25, v161, 0xba000000, v25
	v_pk_add_f32 v[28:29], v[28:29], v[172:173]
	v_fmamk_f32 v24, v161, 0xba000000, v24
	v_fmamk_f32 v23, v161, 0xba000000, v23
	v_fmac_f32_e32 v22, 0xba000000, v161
	v_pk_add_f32 v[172:173], v[28:29], v[28:29] op_sel_hi:[0,1]
	v_pk_mul_f32 v[28:29], v[24:25], v[24:25]
	v_pk_mul_f32 v[174:175], v[22:23], v[22:23]
	v_fmac_f32_e32 v18, 0xba000000, v161
	v_pk_mov_b32 v[176:177], v[174:175], v[28:29] op_sel:[1,0]
	v_mov_b32_e32 v175, v29
	v_pk_add_f32 v[28:29], v[176:177], v[174:175]
	v_fmamk_f32 v20, v161, 0xba000000, v20
	v_pk_add_f32 v[174:175], v[28:29], v[28:29] op_sel_hi:[0,1]
	v_fmamk_f32 v19, v161, 0xba000000, v19
	v_mul_f32_e32 v28, v18, v18
	v_fmamk_f32 v21, v161, 0xba000000, v21
	v_pk_fma_f32 v[176:177], v[18:19], v[18:19], v[28:29] op_sel_hi:[1,1,0]
	v_mul_f32_e32 v28, v20, v20
	v_pk_fma_f32 v[178:179], v[20:21], v[20:21], v[28:29] op_sel_hi:[1,1,0]
	v_fmamk_f32 v29, v161, 0xba000000, v33
	v_fmamk_f32 v28, v161, 0xba000000, v32
	v_fmamk_f32 v31, v161, 0xba000000, v31
	v_fmac_f32_e32 v30, 0xba000000, v161
	v_mul_f32_e32 v176, v30, v30
	v_mul_f32_e32 v178, v31, v31
	v_mul_f32_e32 v174, v28, v28
	v_mul_f32_e32 v172, v29, v29
	v_pk_add_f32 v[32:33], v[176:177], v[178:179]
	v_pk_add_f32 v[172:173], v[174:175], v[172:173]
	s_nop 0
	v_pk_add_f32 v[32:33], v[32:33], v[172:173]
	s_nop 0
	v_add_f32_e32 v11, v32, v33
	ds_bpermute_b32 v15, v166, v11
	s_waitcnt lgkmcnt(0)
	v_add_f32_e32 v11, v11, v15
	ds_bpermute_b32 v15, v167, v11
	s_waitcnt lgkmcnt(0)
	v_add_f32_e32 v11, v11, v15
	ds_bpermute_b32 v15, v168, v11
	s_waitcnt lgkmcnt(0)
	v_add_f32_e32 v11, v11, v15
	ds_bpermute_b32 v15, v169, v11
	s_waitcnt lgkmcnt(0)
	v_add_f32_e32 v11, v11, v15
	ds_bpermute_b32 v15, v170, v11
	s_waitcnt lgkmcnt(0)
	v_add_f32_e32 v11, v11, v15
	ds_bpermute_b32 v15, v171, v11
	s_waitcnt lgkmcnt(0)
	v_add_f32_e32 v11, v11, v15
	v_fmamk_f32 v11, v11, 0x3a000000, v238
	v_mul_f32_e32 v15, 0x4f800000, v11
	v_cmp_gt_f32_e32 vcc, s84, v11
	s_nop 1
	v_cndmask_b32_e32 v11, v11, v15, vcc
	v_sqrt_f32_e32 v15, v11
	s_nop 0
	v_add_u32_e32 v32, -1, v15
	v_fma_f32 v33, -v32, v15, v11
	v_cmp_ge_f32_e64 s[2:3], 0, v33
	v_add_u32_e32 v33, 1, v15
	s_nop 0
	v_cndmask_b32_e64 v32, v15, v32, s[2:3]
	v_fma_f32 v15, -v33, v15, v11
	v_cmp_lt_f32_e64 s[2:3], 0, v15
	s_nop 1
	v_cndmask_b32_e64 v15, v32, v33, s[2:3]
	v_mul_f32_e32 v32, 0x37800000, v15
	v_cndmask_b32_e32 v15, v15, v32, vcc
	v_cmp_class_f32_e32 vcc, v11, v239
	s_nop 1
	v_cndmask_b32_e32 v11, v15, v11, vcc
	v_div_scale_f32 v15, s[2:3], v11, v11, 1.0
	v_rcp_f32_e32 v32, v15
	s_nop 0
	v_fma_f32 v33, -v15, v32, 1.0
	v_fmac_f32_e32 v32, v33, v32
	v_div_scale_f32 v33, vcc, 1.0, v11, 1.0
	v_mul_f32_e32 v172, v33, v32
	v_fma_f32 v173, -v15, v172, v33
	v_fmac_f32_e32 v172, v173, v32
	v_fma_f32 v15, -v15, v172, v33
	v_div_fmas_f32 v15, v15, v32, v172
	v_div_fixup_f32 v32, v15, v11, 1.0
	s_and_saveexec_b64 s[2:3], s[0:1]
	s_cbranch_execz .LBB0_600
	v_mul_f32_e32 v172, 0x3a000000, v161
	v_mov_b32_e32 v173, v32
	global_store_dwordx2 v[156:157], v[172:173], off
	s_branch .LBB0_600

; #define PG8_STAGE(bufoff, gbase, voff) do { _Pragma("unroll") for (int _i = 0; _i < 2; ++_i) \
;         __builtin_amdgcn_global_load_lds((const unsigned*)((const char*)(gbase) + (voff)[_i]), (LAS unsigned*)(lds + (bufoff) + ldsw + _i * 8192), 16, 0, 0); } while (0)
; #define PG8_LDA(dst, b, h) do { _Pragma("unroll") for (int m = 0; m < 4; ++m) _Pragma("unroll") for (int k = 0; k < 2; ++k) dst[m][k] = *(const LAS bf16x8*)(lds + PG8_SA(b, h) + aoff + m * 2048 + k * 1024); } while (0)
; #define PG8_LDB(dst, b, h) do { _Pragma("unroll") for (int n = 0; n < 2; ++n) _Pragma("unroll") for (int k = 0; k < 2; ++k) dst[n][k] = *(const LAS bf16x8*)(lds + PG8_SB(b, h) + boff + n * 2048 + k * 1024); } while (0)
; #define PG8_MMA(ai, bj, At, Bt) do { __builtin_amdgcn_s_setprio(1); _Pragma("unroll") for (int m = 0; m < 4; ++m) _Pragma("unroll") for (int n = 0; n < 2; ++n) _Pragma("unroll") for (int k = 0; k < 2; ++k) \
;         acc[ai][bj][m][n] = __builtin_amdgcn_mfma_f32_16x16x32_bf16(Bt[n][k], At[m][k], acc[ai][bj][m][n], 0, 0, 0); __builtin_amdgcn_s_setprio(0); } while (0)
; #define PG8_WAIT_L(n) asm volatile("s_waitcnt lgkmcnt(" #n ")" ::: "memory")
; #define PG8_BAR __builtin_amdgcn_s_barrier()
; #define PG8_SCHED __builtin_amdgcn_sched_barrier(0)
; template <class Epi, class Sched, bool AREMAP>
; __device__ __forceinline__ void gemm_phase(LAS unsigned char* lds, const Gemm g, const Sched& S, const Epi& E, int wv) {
;     ...
;         for (int t = 0; t < nt; t += 2) {
;             const bool last = (t == nt - 2);
;             const char* a1 = cA + (size_t)(t + 1) * kstep;
;             const char* a2 = last ? nA : cA + (size_t)(t + 2) * kstep; const char* b2 = last ? nB : cB + (size_t)(t + 2) * kstep;
;             const char* a3 = a2 + kstep; const char* b3 = b2 + kstep;
;             PG8_LDB(B0, 0, 0); PG8_SCHED; PG8_LDA(At, 0, 0); PG8_STAGE(PG8_SA(1, 1), a1 + hstepA, voffA);
;             PG8_WAIT_L(8); PG8_BAR; PG8_WAIT_L(0); PG8_MMA(0, 0, At, B0); PG8_BAR; PG8_SCHED;
;             PG8_LDB(B1, 0, 1); PG8_STAGE(PG8_SB(0, 0), b2, voffB);
;             PG8_BAR; PG8_WAIT_L(0); PG8_MMA(0, 1, At, B1); PG8_BAR;
;             PG8_LDA(At, 0, 1); PG8_STAGE(PG8_SA(0, 0), a2, voffA);
;             PG8_BAR; PG8_WAIT_L(0); PG8_MMA(1, 0, At, B0); PG8_BAR; PG8_SCHED;
.LBB0_619:
	s_add_u32 s38, s78, 0xfffc0080
	s_addc_u32 s39, s79, -1
	s_add_i32 s33, 0, 0x10000
	v_add_u32_e32 v142, s33, v1
	ds_read_b128 v[130:133], v142
	ds_read_b128 v[134:137], v142 offset:1024
	ds_read_b128 v[138:141], v142 offset:2048
	ds_read_b128 v[142:145], v142 offset:3072
	s_cmp_eq_u32 vcc_hi, 28
	s_cselect_b32 s97, s46, s39
	s_cselect_b32 s96, s47, s38
	s_cselect_b32 s81, s63, vcc_lo
	s_cselect_b32 s80, s67, s77
	v_lshl_add_u64 v[178:179], s[78:79], 0, v[168:169]
	s_add_i32 m0, s10, 0xc000
	ds_read_b128 v[146:149], v183
	ds_read_b128 v[150:153], v183 offset:1024
	ds_read_b128 v[170:173], v183 offset:2048
	ds_read_b128 v[174:177], v183 offset:3072
	ds_read_b128 v[184:187], v183 offset:4096
	ds_read_b128 v[192:195], v183 offset:5120
	ds_read_b128 v[196:199], v183 offset:6144
	ds_read_b128 v[200:203], v183 offset:7168
	global_load_lds_dwordx4 v[178:179], off
	v_lshl_add_u64 v[178:179], s[78:79], 0, v[166:167]
	s_add_i32 m0, s10, 0xe000
	s_nop 0
	global_load_lds_dwordx4 v[178:179], off
	s_waitcnt lgkmcnt(8)
	s_barrier
	s_waitcnt lgkmcnt(0)
	s_setprio 1
	s_waitcnt lgkmcnt(0)
	v_mfma_f32_16x16x32_bf16 v[126:129], v[130:133], v[146:149], v[126:129]
	v_mfma_f32_16x16x32_bf16 v[62:65], v[138:141], v[146:149], v[62:65]
	v_mfma_f32_16x16x32_bf16 v[118:121], v[130:133], v[170:173], v[118:121]
	v_mfma_f32_16x16x32_bf16 v[54:57], v[138:141], v[170:173], v[54:57]
	v_mfma_f32_16x16x32_bf16 v[110:113], v[130:133], v[184:187], v[110:113]
	v_mfma_f32_16x16x32_bf16 v[46:49], v[138:141], v[184:187], v[46:49]
	v_mfma_f32_16x16x32_bf16 v[102:105], v[130:133], v[196:199], v[102:105]
	v_mfma_f32_16x16x32_bf16 v[38:41], v[138:141], v[196:199], v[38:41]
	v_mfma_f32_16x16x32_bf16 v[126:129], v[134:137], v[150:153], v[126:129]
	v_mfma_f32_16x16x32_bf16 v[62:65], v[142:145], v[150:153], v[62:65]
	v_mfma_f32_16x16x32_bf16 v[118:121], v[134:137], v[174:177], v[118:121]
	v_mfma_f32_16x16x32_bf16 v[54:57], v[142:145], v[174:177], v[54:57]
	v_mfma_f32_16x16x32_bf16 v[110:113], v[134:137], v[192:195], v[110:113]
	v_mfma_f32_16x16x32_bf16 v[46:49], v[142:145], v[192:195], v[46:49]
	v_mfma_f32_16x16x32_bf16 v[102:105], v[134:137], v[200:203], v[102:105]
	v_mfma_f32_16x16x32_bf16 v[38:41], v[142:145], v[200:203], v[38:41]
	s_setprio 0
	s_barrier
	s_add_i32 s58, 0, 0x14000
	v_add_u32_e32 v178, s58, v1
	s_add_i32 s33, s33, s91
	ds_read_b128 v[204:207], v178
	ds_read_b128 v[208:211], v178 offset:1024
	ds_read_b128 v[212:215], v178 offset:2048
	ds_read_b128 v[216:219], v178 offset:3072
	v_lshl_add_u64 v[178:179], s[80:81], 0, v[158:159]
	s_mov_b32 m0, s33
	v_lshl_add_u64 v[220:221], s[80:81], 0, v[154:155]
	global_load_lds_dwordx4 v[178:179], off
	s_add_i32 m0, s33, 0x2000
	s_nop 0
	global_load_lds_dwordx4 v[220:221], off
	s_barrier
	s_waitcnt lgkmcnt(0)
	s_setprio 1
	s_waitcnt lgkmcnt(0)
	v_mfma_f32_16x16x32_bf16 v[122:125], v[204:207], v[146:149], v[122:125]
	v_mfma_f32_16x16x32_bf16 v[58:61], v[212:215], v[146:149], v[58:61]
	v_mfma_f32_16x16x32_bf16 v[114:117], v[204:207], v[170:173], v[114:117]
	v_mfma_f32_16x16x32_bf16 v[50:53], v[212:215], v[170:173], v[50:53]
	v_mfma_f32_16x16x32_bf16 v[106:109], v[204:207], v[184:187], v[106:109]
	v_mfma_f32_16x16x32_bf16 v[42:45], v[212:215], v[184:187], v[42:45]
	v_mfma_f32_16x16x32_bf16 v[98:101], v[204:207], v[196:199], v[98:101]
	v_mfma_f32_16x16x32_bf16 v[34:37], v[212:215], v[196:199], v[34:37]
	v_mfma_f32_16x16x32_bf16 v[122:125], v[208:211], v[150:153], v[122:125]
	v_mfma_f32_16x16x32_bf16 v[58:61], v[216:219], v[150:153], v[58:61]
	v_mfma_f32_16x16x32_bf16 v[114:117], v[208:211], v[174:177], v[114:117]
	v_mfma_f32_16x16x32_bf16 v[50:53], v[216:219], v[174:177], v[50:53]
	v_mfma_f32_16x16x32_bf16 v[106:109], v[208:211], v[192:195], v[106:109]
	v_mfma_f32_16x16x32_bf16 v[42:45], v[216:219], v[192:195], v[42:45]
	v_mfma_f32_16x16x32_bf16 v[98:101], v[208:211], v[200:203], v[98:101]
	v_mfma_f32_16x16x32_bf16 v[34:37], v[216:219], v[200:203], v[34:37]
	s_setprio 0
	s_mov_b32 m0, s10
	v_lshl_add_u64 v[222:223], s[96:97], 0, v[160:161]
	s_barrier
	ds_read_b128 v[146:149], v183 offset:16384
	ds_read_b128 v[150:153], v183 offset:17408
	ds_read_b128 v[170:173], v183 offset:18432
	ds_read_b128 v[174:177], v183 offset:19456
	ds_read_b128 v[184:187], v183 offset:20480
	ds_read_b128 v[192:195], v183 offset:21504
	ds_read_b128 v[196:199], v183 offset:22528
	ds_read_b128 v[200:203], v183 offset:23552
	global_load_lds_dwordx4 v[222:223], off
	v_lshl_add_u64 v[224:225], s[96:97], 0, v[156:157]
	s_mov_b32 m0, s11
	s_nop 0
	global_load_lds_dwordx4 v[224:225], off
	s_barrier
	s_waitcnt lgkmcnt(0)
	s_setprio 1
	s_waitcnt lgkmcnt(0)
	v_mfma_f32_16x16x32_bf16 v[94:97], v[130:133], v[146:149], v[94:97]
	v_mfma_f32_16x16x32_bf16 v[30:33], v[138:141], v[146:149], v[30:33]
	v_mfma_f32_16x16x32_bf16 v[86:89], v[130:133], v[170:173], v[86:89]
	v_mfma_f32_16x16x32_bf16 v[22:25], v[138:141], v[170:173], v[22:25]
	v_mfma_f32_16x16x32_bf16 v[78:81], v[130:133], v[184:187], v[78:81]
	v_mfma_f32_16x16x32_bf16 v[14:17], v[138:141], v[184:187], v[14:17]
	v_mfma_f32_16x16x32_bf16 v[70:73], v[130:133], v[196:199], v[70:73]
	v_mfma_f32_16x16x32_bf16 v[6:9], v[138:141], v[196:199], v[6:9]
	v_mfma_f32_16x16x32_bf16 v[94:97], v[134:137], v[150:153], v[94:97]
	v_mfma_f32_16x16x32_bf16 v[30:33], v[142:145], v[150:153], v[30:33]
	v_mfma_f32_16x16x32_bf16 v[86:89], v[134:137], v[174:177], v[86:89]
	v_mfma_f32_16x16x32_bf16 v[22:25], v[142:145], v[174:177], v[22:25]
	v_mfma_f32_16x16x32_bf16 v[78:81], v[134:137], v[192:195], v[78:81]
	v_mfma_f32_16x16x32_bf16 v[14:17], v[142:145], v[192:195], v[14:17]
	v_mfma_f32_16x16x32_bf16 v[70:73], v[134:137], v[200:203], v[70:73]
	v_mfma_f32_16x16x32_bf16 v[6:9], v[142:145], v[200:203], v[6:9]
	s_setprio 0
	s_barrier
; #define PG8_STAGE(bufoff, gbase, voff) do { _Pragma("unroll") for (int _i = 0; _i < 2; ++_i) \
;         __builtin_amdgcn_global_load_lds((const unsigned*)((const char*)(gbase) + (voff)[_i]), (LAS unsigned*)(lds + (bufoff) + ldsw + _i * 8192), 16, 0, 0); } while (0)
; #define PG8_LDA(dst, b, h) do { _Pragma("unroll") for (int m = 0; m < 4; ++m) _Pragma("unroll") for (int k = 0; k < 2; ++k) dst[m][k] = *(const LAS bf16x8*)(lds + PG8_SA(b, h) + aoff + m * 2048 + k * 1024); } while (0)
; #define PG8_LDB(dst, b, h) do { _Pragma("unroll") for (int n = 0; n < 2; ++n) _Pragma("unroll") for (int k = 0; k < 2; ++k) dst[n][k] = *(const LAS bf16x8*)(lds + PG8_SB(b, h) + boff + n * 2048 + k * 1024); } while (0)
; #define PG8_MMA(ai, bj, At, Bt) do { __builtin_amdgcn_s_setprio(1); _Pragma("unroll") for (int m = 0; m < 4; ++m) _Pragma("unroll") for (int n = 0; n < 2; ++n) _Pragma("unroll") for (int k = 0; k < 2; ++k) \
;         acc[ai][bj][m][n] = __builtin_amdgcn_mfma_f32_16x16x32_bf16(Bt[n][k], At[m][k], acc[ai][bj][m][n], 0, 0, 0); __builtin_amdgcn_s_setprio(0); } while (0)
; #define PG8_WAIT_V(n) asm volatile("s_waitcnt vmcnt(" #n ")" ::: "memory")
; #define PG8_WAIT_L(n) asm volatile("s_waitcnt lgkmcnt(" #n ")" ::: "memory")
; #define PG8_BAR __builtin_amdgcn_s_barrier()
; #define PG8_SCHED __builtin_amdgcn_sched_barrier(0)
; template <class Epi, class Sched, bool AREMAP>
; __device__ __forceinline__ void gemm_phase(LAS unsigned char* lds, const Gemm g, const Sched& S, const Epi& E, int wv) {
;     ...
;             PG8_STAGE(PG8_SB(0, 1), b2 + hstepB, voffB);
;             PG8_WAIT_V(6); PG8_BAR; PG8_MMA(1, 1, At, B1); PG8_BAR;
;             PG8_LDB(B0, 1, 0); PG8_SCHED; PG8_LDA(At, 1, 0); PG8_STAGE(PG8_SA(0, 1), a2 + hstepA, voffA);
;             PG8_WAIT_L(8); PG8_BAR; PG8_WAIT_L(0); PG8_MMA(0, 0, At, B0); PG8_BAR; PG8_SCHED;
;             PG8_LDB(B1, 1, 1); PG8_STAGE(PG8_SB(1, 0), b3, voffB);
;             PG8_BAR; PG8_WAIT_L(0); PG8_MMA(0, 1, At, B1); PG8_BAR;
;             PG8_LDA(At, 1, 1); PG8_STAGE(PG8_SA(1, 0), a3, voffA);
;             PG8_BAR; PG8_WAIT_L(0); PG8_MMA(1, 0, At, B0); PG8_BAR; PG8_SCHED;
	s_add_u32 s38, s80, 0x80000
	s_addc_u32 s39, s81, 0
	s_add_i32 s33, s58, s91
	v_lshl_add_u64 v[130:131], s[38:39], 0, v[158:159]
	s_mov_b32 m0, s33
	s_nop 0
	global_load_lds_dwordx4 v[130:131], off
	v_lshl_add_u64 v[130:131], s[38:39], 0, v[154:155]
	s_add_i32 m0, s33, 0x2000
	s_nop 0
	global_load_lds_dwordx4 v[130:131], off
	s_waitcnt vmcnt(6)
	s_barrier
	s_setprio 1
	v_mfma_f32_16x16x32_bf16 v[90:93], v[204:207], v[146:149], v[90:93]
	v_mfma_f32_16x16x32_bf16 v[26:29], v[212:215], v[146:149], v[26:29]
	v_mfma_f32_16x16x32_bf16 v[82:85], v[204:207], v[170:173], v[82:85]
	v_mfma_f32_16x16x32_bf16 v[18:21], v[212:215], v[170:173], v[18:21]
	v_mfma_f32_16x16x32_bf16 v[74:77], v[204:207], v[184:187], v[74:77]
	v_mfma_f32_16x16x32_bf16 v[10:13], v[212:215], v[184:187], v[10:13]
	v_mfma_f32_16x16x32_bf16 v[66:69], v[204:207], v[196:199], v[66:69]
	v_mfma_f32_16x16x32_bf16 v[2:5], v[212:215], v[196:199], v[2:5]
	v_mfma_f32_16x16x32_bf16 v[90:93], v[208:211], v[150:153], v[90:93]
	v_mfma_f32_16x16x32_bf16 v[26:29], v[216:219], v[150:153], v[26:29]
	v_mfma_f32_16x16x32_bf16 v[82:85], v[208:211], v[174:177], v[82:85]
	v_mfma_f32_16x16x32_bf16 v[18:21], v[216:219], v[174:177], v[18:21]
	v_mfma_f32_16x16x32_bf16 v[74:77], v[208:211], v[192:195], v[74:77]
	v_mfma_f32_16x16x32_bf16 v[10:13], v[216:219], v[192:195], v[10:13]
	v_mfma_f32_16x16x32_bf16 v[66:69], v[208:211], v[200:203], v[66:69]
	v_mfma_f32_16x16x32_bf16 v[2:5], v[216:219], v[200:203], v[2:5]
	s_setprio 0
	s_add_i32 s33, 0, 0x18000
	v_add_u32_e32 v142, s33, v1
	s_barrier
	ds_read_b128 v[130:133], v142
	ds_read_b128 v[134:137], v142 offset:1024
	ds_read_b128 v[138:141], v142 offset:2048
	ds_read_b128 v[142:145], v142 offset:3072
	s_add_u32 s38, s96, 0x40000
	s_addc_u32 s39, s97, 0
	s_mov_b32 m0, s12
	v_lshl_add_u64 v[204:205], s[38:39], 0, v[160:161]
	ds_read_b128 v[146:149], v183 offset:32768
	ds_read_b128 v[150:153], v183 offset:33792
	ds_read_b128 v[170:173], v183 offset:34816
	ds_read_b128 v[174:177], v183 offset:35840
	ds_read_b128 v[184:187], v183 offset:36864
	ds_read_b128 v[192:195], v183 offset:37888
	ds_read_b128 v[196:199], v183 offset:38912
	ds_read_b128 v[200:203], v183 offset:39936
	global_load_lds_dwordx4 v[204:205], off
	v_lshl_add_u64 v[204:205], s[38:39], 0, v[156:157]
	s_mov_b32 m0, s13
	s_nop 0
	global_load_lds_dwordx4 v[204:205], off
	s_waitcnt lgkmcnt(8)
	s_barrier
	s_waitcnt lgkmcnt(0)
	s_setprio 1
	s_waitcnt lgkmcnt(0)
	v_mfma_f32_16x16x32_bf16 v[126:129], v[130:133], v[146:149], v[126:129]
	v_mfma_f32_16x16x32_bf16 v[62:65], v[138:141], v[146:149], v[62:65]
	v_mfma_f32_16x16x32_bf16 v[118:121], v[130:133], v[170:173], v[118:121]
	v_mfma_f32_16x16x32_bf16 v[54:57], v[138:141], v[170:173], v[54:57]
	v_mfma_f32_16x16x32_bf16 v[110:113], v[130:133], v[184:187], v[110:113]
	v_mfma_f32_16x16x32_bf16 v[46:49], v[138:141], v[184:187], v[46:49]
	v_mfma_f32_16x16x32_bf16 v[102:105], v[130:133], v[196:199], v[102:105]
	v_mfma_f32_16x16x32_bf16 v[38:41], v[138:141], v[196:199], v[38:41]
	v_mfma_f32_16x16x32_bf16 v[126:129], v[134:137], v[150:153], v[126:129]
	v_mfma_f32_16x16x32_bf16 v[62:65], v[142:145], v[150:153], v[62:65]
	v_mfma_f32_16x16x32_bf16 v[118:121], v[134:137], v[174:177], v[118:121]
	v_mfma_f32_16x16x32_bf16 v[54:57], v[142:145], v[174:177], v[54:57]
	v_mfma_f32_16x16x32_bf16 v[110:113], v[134:137], v[192:195], v[110:113]
	v_mfma_f32_16x16x32_bf16 v[46:49], v[142:145], v[192:195], v[46:49]
	v_mfma_f32_16x16x32_bf16 v[102:105], v[134:137], v[200:203], v[102:105]
	v_mfma_f32_16x16x32_bf16 v[38:41], v[142:145], v[200:203], v[38:41]
	s_setprio 0
	s_barrier
	s_add_i32 s58, 0, 0x1c000
	s_add_i32 s33, s33, s91
	v_add_u32_e32 v216, s58, v1
	v_lshl_add_u64 v[178:179], v[178:179], 0, s[86:87]
	s_mov_b32 m0, s33
	ds_read_b128 v[204:207], v216
	ds_read_b128 v[208:211], v216 offset:1024
	ds_read_b128 v[212:215], v216 offset:2048
	ds_read_b128 v[216:219], v216 offset:3072
	global_load_lds_dwordx4 v[178:179], off
	v_lshl_add_u64 v[178:179], v[220:221], 0, s[86:87]
	s_add_i32 m0, s33, 0x2000
	s_nop 0
	global_load_lds_dwordx4 v[178:179], off
	s_barrier
	s_waitcnt lgkmcnt(0)
	s_setprio 1
	s_waitcnt lgkmcnt(0)
	v_mfma_f32_16x16x32_bf16 v[122:125], v[204:207], v[146:149], v[122:125]
	v_mfma_f32_16x16x32_bf16 v[58:61], v[212:215], v[146:149], v[58:61]
	v_mfma_f32_16x16x32_bf16 v[114:117], v[204:207], v[170:173], v[114:117]
	v_mfma_f32_16x16x32_bf16 v[50:53], v[212:215], v[170:173], v[50:53]
	v_mfma_f32_16x16x32_bf16 v[106:109], v[204:207], v[184:187], v[106:109]
	v_mfma_f32_16x16x32_bf16 v[42:45], v[212:215], v[184:187], v[42:45]
	v_mfma_f32_16x16x32_bf16 v[98:101], v[204:207], v[196:199], v[98:101]
	v_mfma_f32_16x16x32_bf16 v[34:37], v[212:215], v[196:199], v[34:37]
	v_mfma_f32_16x16x32_bf16 v[122:125], v[208:211], v[150:153], v[122:125]
	v_mfma_f32_16x16x32_bf16 v[58:61], v[216:219], v[150:153], v[58:61]
	v_mfma_f32_16x16x32_bf16 v[114:117], v[208:211], v[174:177], v[114:117]
	v_mfma_f32_16x16x32_bf16 v[50:53], v[216:219], v[174:177], v[50:53]
	v_mfma_f32_16x16x32_bf16 v[106:109], v[208:211], v[192:195], v[106:109]
	v_mfma_f32_16x16x32_bf16 v[42:45], v[216:219], v[192:195], v[42:45]
	v_mfma_f32_16x16x32_bf16 v[98:101], v[208:211], v[200:203], v[98:101]
	v_mfma_f32_16x16x32_bf16 v[34:37], v[216:219], v[200:203], v[34:37]
	s_setprio 0
	s_mov_b32 m0, s14
	v_lshl_add_u64 v[178:179], v[222:223], 0, s[86:87]
	s_barrier
	ds_read_b128 v[146:149], v183 offset:49152
	ds_read_b128 v[150:153], v183 offset:50176
	ds_read_b128 v[170:173], v183 offset:51200
	ds_read_b128 v[174:177], v183 offset:52224
	ds_read_b128 v[184:187], v183 offset:53248
	ds_read_b128 v[192:195], v183 offset:54272
	ds_read_b128 v[196:199], v183 offset:55296
	ds_read_b128 v[200:203], v183 offset:56320
	global_load_lds_dwordx4 v[178:179], off
	v_lshl_add_u64 v[178:179], v[224:225], 0, s[86:87]
	s_mov_b32 m0, s15
	s_nop 0
	global_load_lds_dwordx4 v[178:179], off
	s_barrier
; template <class Epi, class Sched, bool AREMAP>
; __device__ __forceinline__ void gemm_phase(LAS unsigned char* lds, const Gemm g, const Sched& S, const Epi& E, int wv) {
;     ...
;             PG8_WAIT_V(6); PG8_BAR; PG8_MMA(1, 1, At, B1); PG8_BAR;
;             PG8_LDB(B0, 1, 0); PG8_SCHED; PG8_LDA(At, 1, 0); PG8_STAGE(PG8_SA(0, 1), a2 + hstepA, voffA);
;             PG8_WAIT_L(8); PG8_BAR; PG8_WAIT_L(0); PG8_MMA(0, 0, At, B0); PG8_BAR; PG8_SCHED;
;             PG8_LDB(B1, 1, 1); PG8_STAGE(PG8_SB(1, 0), b3, voffB);
;             PG8_BAR; PG8_WAIT_L(0); PG8_MMA(0, 1, At, B1); PG8_BAR;
;             PG8_LDA(At, 1, 1); PG8_STAGE(PG8_SA(1, 0), a3, voffA);
;             PG8_BAR; PG8_WAIT_L(0); PG8_MMA(1, 0, At, B0); PG8_BAR; PG8_SCHED;
;             PG8_STAGE(PG8_SB(1, 1), b3 + hstepB, voffB);
;             PG8_WAIT_V(6); PG8_BAR; PG8_MMA(1, 1, At, B1); PG8_BAR;
;     __device__ __forceinline__ void operator()(const f32x4 (&acc)[2][2][4][2], const Unit& u, int wr, int wc, int fr, int fq) const {
;         const int lane = fq * 16 + fr;
;         const int ch0 = u.pn * 128 + wc * 32 + 8 * fq;
;         const int seg = u.pm * 2 + wr, tok0 = seg * 128 + fr;
;         const int src1 = (lane & 48) | ((fr + 15) & 15), src2 = (lane & 48) | ((fr + 14) & 15);
; #pragma unroll
;         for (int n = 0; n < 2; ++n) {
;             const int ch = ch0 + 4 * n;
;             f32x4 wv[3], wg[3];
; #pragma unroll
;             for (int k = 0; k < 3; ++k) { wv[k] = *(const f32x4*)(cw + k * NUP + ch); wg[k] = *(const f32x4*)(cw + k * NUP + DFF + ch); }
;             f32x4 pv1 = {0.f, 0.f, 0.f, 0.f}, pv2 = pv1, pg1 = pv1, pg2 = pv1;
; #pragma unroll
;             for (int q = 0; q < 8; ++q) {
;                 const int ai = q >> 2, m = q & 3;
;                 const f32x4 av = acc[ai][0][m][n], ag = acc[ai][1][m][n];
;                 f32x4 rv1, rv2, rg1, rg2;
; #pragma unroll
;                 for (int j = 0; j < 4; ++j) { rv1[j] = SHI(lane, av[j], src1); rv2[j] = SHI(lane, av[j], src2); rg1[j] = SHI(lane, ag[j], src1); rg2[j] = SHI(lane, ag[j], src2); }
;                 const f32x4 sv1 = fr >= 1 ? rv1 : pv1, sv2 = fr >= 2 ? rv2 : pv2, sg1 = fr >= 1 ? rg1 : pg1, sg2 = fr >= 2 ? rg2 : pg2;
;                 const f32x4 ov = wv[2] * av + wv[1] * sv1 + wv[0] * sv2;
;                 const f32x4 og = wg[2] * ag + wg[1] * sg1 + wg[0] * sg2;
;                 u32x2 w;
	s_waitcnt lgkmcnt(0)
	s_setprio 1
	s_waitcnt lgkmcnt(0)
	v_mfma_f32_16x16x32_bf16 v[94:97], v[130:133], v[146:149], v[94:97]
	v_mfma_f32_16x16x32_bf16 v[30:33], v[138:141], v[146:149], v[30:33]
	v_mfma_f32_16x16x32_bf16 v[86:89], v[130:133], v[170:173], v[86:89]
	v_mfma_f32_16x16x32_bf16 v[22:25], v[138:141], v[170:173], v[22:25]
	v_mfma_f32_16x16x32_bf16 v[78:81], v[130:133], v[184:187], v[78:81]
	v_mfma_f32_16x16x32_bf16 v[14:17], v[138:141], v[184:187], v[14:17]
	v_mfma_f32_16x16x32_bf16 v[70:73], v[130:133], v[196:199], v[70:73]
	v_mfma_f32_16x16x32_bf16 v[6:9], v[138:141], v[196:199], v[6:9]
	v_mfma_f32_16x16x32_bf16 v[94:97], v[134:137], v[150:153], v[94:97]
	v_mfma_f32_16x16x32_bf16 v[30:33], v[142:145], v[150:153], v[30:33]
	v_mfma_f32_16x16x32_bf16 v[86:89], v[134:137], v[174:177], v[86:89]
	v_mfma_f32_16x16x32_bf16 v[22:25], v[142:145], v[174:177], v[22:25]
	v_mfma_f32_16x16x32_bf16 v[78:81], v[134:137], v[192:195], v[78:81]
	v_mfma_f32_16x16x32_bf16 v[14:17], v[142:145], v[192:195], v[14:17]
	v_mfma_f32_16x16x32_bf16 v[70:73], v[134:137], v[200:203], v[70:73]
	v_mfma_f32_16x16x32_bf16 v[6:9], v[142:145], v[200:203], v[6:9]
	s_setprio 0
	s_barrier
	s_add_u32 s38, s80, 0x80080
	s_addc_u32 s39, s81, 0
	s_add_i32 s33, s58, s91
	v_lshl_add_u64 v[130:131], s[38:39], 0, v[158:159]
	s_mov_b32 m0, s33
	s_nop 0
	global_load_lds_dwordx4 v[130:131], off
	v_lshl_add_u64 v[130:131], s[38:39], 0, v[154:155]
	s_add_i32 m0, s33, 0x2000
	s_nop 0
	global_load_lds_dwordx4 v[130:131], off
	s_waitcnt vmcnt(6)
	s_barrier
	s_setprio 1
	v_mfma_f32_16x16x32_bf16 v[90:93], v[204:207], v[146:149], v[90:93]
	v_mfma_f32_16x16x32_bf16 v[26:29], v[212:215], v[146:149], v[26:29]
	v_mfma_f32_16x16x32_bf16 v[82:85], v[204:207], v[170:173], v[82:85]
	v_mfma_f32_16x16x32_bf16 v[18:21], v[212:215], v[170:173], v[18:21]
	v_mfma_f32_16x16x32_bf16 v[74:77], v[204:207], v[184:187], v[74:77]
	v_mfma_f32_16x16x32_bf16 v[10:13], v[212:215], v[184:187], v[10:13]
	v_mfma_f32_16x16x32_bf16 v[66:69], v[204:207], v[196:199], v[66:69]
	v_mfma_f32_16x16x32_bf16 v[2:5], v[212:215], v[196:199], v[2:5]
	v_mfma_f32_16x16x32_bf16 v[90:93], v[208:211], v[150:153], v[90:93]
	v_mfma_f32_16x16x32_bf16 v[26:29], v[216:219], v[150:153], v[26:29]
	v_mfma_f32_16x16x32_bf16 v[82:85], v[208:211], v[174:177], v[82:85]
	v_mfma_f32_16x16x32_bf16 v[18:21], v[216:219], v[174:177], v[18:21]
	v_mfma_f32_16x16x32_bf16 v[74:77], v[208:211], v[192:195], v[74:77]
	v_mfma_f32_16x16x32_bf16 v[10:13], v[216:219], v[192:195], v[10:13]
	v_mfma_f32_16x16x32_bf16 v[66:69], v[208:211], v[200:203], v[66:69]
	v_mfma_f32_16x16x32_bf16 v[2:5], v[216:219], v[200:203], v[2:5]
	s_setprio 0
	s_add_i32 vcc_hi, vcc_hi, 2
	s_add_u32 s77, s77, 0x100
	s_addc_u32 vcc_lo, vcc_lo, 0
	s_add_u32 s78, s78, 0x100
	s_addc_u32 s79, s79, 0
	s_cmp_gt_u32 vcc_hi, 29
	s_barrier
	s_cbranch_scc0 .LBB0_619
	v_lshl_or_b32 v170, s37, 7, v182
	s_lshl_b32 s37, s76, 1
	s_add_i32 s46, s37, s75
	s_ashr_i32 s47, s46, 31
	s_lshl_b64 s[76:77], s[46:47], 2
	v_lshl_add_u64 v[130:131], s[76:77], 0, v[162:163]
	s_mov_b32 s33, 0xb000
	v_ashrrev_i32_e32 v171, 31, v170
	v_lshl_or_b32 v184, s46, 7, v162
	v_mad_u64_u32 v[176:177], s[46:47], v130, s33, 0
	v_lshlrev_b64 v[142:143], 2, v[170:171]
	v_mad_i32_i24 v177, v131, s33, v177
	v_lshl_add_u64 v[130:131], s[24:25], 0, v[142:143]
	v_lshl_add_u64 v[138:139], s[26:27], 0, v[142:143]
	global_load_dwordx4 v[130:133], v[130:131], off
	v_lshl_add_u64 v[144:145], s[30:31], 0, v[142:143]
	global_load_dwordx4 v[146:149], v[138:139], off
	v_lshl_add_u64 v[172:173], s[18:19], 0, v[142:143]
	v_lshl_add_u64 v[138:139], s[28:29], 0, v[142:143]
	global_load_dwordx4 v[150:153], v[144:145], off
	global_load_dwordx4 v[134:137], v[172:173], off
	v_lshl_add_u64 v[142:143], s[34:35], 0, v[142:143]
	global_load_dwordx4 v[138:141], v[138:139], off
	ds_bpermute_b32 v199, v180, v126
	global_load_dwordx4 v[142:145], v[142:143], off
	ds_bpermute_b32 v204, v180, v127
	ds_bpermute_b32 v206, v180, v128
	ds_bpermute_b32 v208, v180, v129
	ds_bpermute_b32 v196, v181, v126
	ds_bpermute_b32 v186, v180, v122
	ds_bpermute_b32 v201, v181, v127
	ds_bpermute_b32 v198, v180, v123
	ds_bpermute_b32 v203, v181, v128
	ds_bpermute_b32 v200, v180, v124
	ds_bpermute_b32 v207, v181, v129
	ds_bpermute_b32 v205, v180, v125
	ds_bpermute_b32 v185, v181, v122
	ds_bpermute_b32 v187, v181, v123
	ds_bpermute_b32 v197, v181, v124
	ds_bpermute_b32 v202, v181, v125
	s_waitcnt lgkmcnt(0)
	v_cndmask_b32_e64 v175, v204, 0, s[0:1]
	v_cndmask_b32_e64 v174, v199, 0, s[0:1]
	v_cndmask_b32_e64 v179, v208, 0, s[0:1]
	v_cndmask_b32_e64 v178, v206, 0, s[0:1]
	v_cndmask_b32_e64 v193, 0, v201, s[2:3]
	v_cndmask_b32_e64 v192, 0, v196, s[2:3]
	v_cndmask_b32_e64 v195, 0, v207, s[2:3]
	v_cndmask_b32_e64 v194, 0, v203, s[2:3]
	v_cndmask_b32_e64 v211, v198, 0, s[0:1]
	v_cndmask_b32_e64 v210, v186, 0, s[0:1]
	v_cndmask_b32_e64 v213, v205, 0, s[0:1]
	v_cndmask_b32_e64 v212, v200, 0, s[0:1]
	v_cndmask_b32_e64 v215, 0, v187, s[2:3]
	v_cndmask_b32_e64 v214, 0, v185, s[2:3]
	v_cndmask_b32_e64 v217, 0, v202, s[2:3]
	v_cndmask_b32_e64 v216, 0, v197, s[2:3]
	s_movk_i32 s33, 0x2c00
	v_lshl_add_u64 v[176:177], s[22:23], 0, v[176:177]
	v_lshl_add_u64 v[176:177], v[170:171], 2, v[176:177]
	s_waitcnt vmcnt(0)
	v_pk_mul_f32 v[178:179], v[148:149], v[178:179]
	v_pk_mul_f32 v[174:175], v[146:147], v[174:175]
	v_pk_fma_f32 v[178:179], v[128:129], v[152:153], v[178:179]
	v_pk_fma_f32 v[174:175], v[126:127], v[150:151], v[174:175]
	v_pk_fma_f32 v[194:195], v[136:137], v[194:195], v[178:179]
	v_pk_fma_f32 v[174:175], v[134:135], v[192:193], v[174:175]
	v_pk_mul_f32 v[178:179], v[140:141], v[212:213]
	v_pk_mul_f32 v[192:193], v[138:139], v[210:211]
	v_pk_fma_f32 v[178:179], v[124:125], v[144:145], v[178:179]
	v_pk_fma_f32 v[192:193], v[122:123], v[142:143], v[192:193]
	v_pk_fma_f32 v[210:211], v[132:133], v[216:217], v[178:179]
	v_pk_fma_f32 v[178:179], v[130:131], v[214:215], v[192:193]
	s_nop 0
	v_mul_f32_e32 v192, 0xbfb8aa3b, v178
	v_mul_f32_e32 v193, 0xbfb8aa3b, v179
	v_exp_f32_e32 v192, v192
	v_exp_f32_e32 v193, v193
	v_add_f32_e32 v192, 1.0, v192
	v_add_f32_e32 v193, 1.0, v193
	v_rcp_f32_e32 v192, v192
	v_rcp_f32_e32 v193, v193
	s_nop 0
	v_pk_mul_f32 v[178:179], v[178:179], v[192:193]
	s_nop 0
	v_pk_mul_f32 v[174:175], v[174:175], v[178:179]
	s_nop 0
	v_cvt_pk_bf16_f32 v178, v174, v175
	v_mul_f32_e32 v174, 0xbfb8aa3b, v210
	v_mul_f32_e32 v175, 0xbfb8aa3b, v211
	v_exp_f32_e32 v174, v174
	v_exp_f32_e32 v175, v175
	v_add_f32_e32 v174, 1.0, v174
	v_add_f32_e32 v175, 1.0, v175
	v_rcp_f32_e32 v174, v174
	v_rcp_f32_e32 v175, v175
	s_nop 0
	v_pk_mul_f32 v[174:175], v[210:211], v[174:175]
	s_nop 0
	v_pk_mul_f32 v[174:175], v[194:195], v[174:175]
	s_nop 0
	v_cvt_pk_bf16_f32 v179, v174, v175
	v_mov_b64_e32 v[174:175], s[20:21]
	v_mad_i64_i32 v[174:175], s[46:47], v184, s33, v[174:175]
	v_lshl_add_u64 v[174:175], v[170:171], 1, v[174:175]
	global_store_dwordx2 v[174:175], v[178:179], off
	s_and_saveexec_b64 s[78:79], s[4:5]
	s_cbranch_execz .LBB0_622
; __device__ __forceinline__ unsigned cvt_pk_bf16(float lo, float hi) { f32x2_t f = {lo, hi}; bf16x2_t v = __builtin_convertvector(f, bf16x2_t); return __builtin_bit_cast(unsigned, v); }
; __device__ __forceinline__ float sigmoidf_(float x) { return __builtin_amdgcn_rcpf(1.0f + __expf(-x)); }
; #define SHI(lane, v, src) shfl_idx(lane, (v), (src))
;     __device__ __forceinline__ void operator()(const f32x4 (&acc)[2][2][4][2], const Unit& u, int wr, int wc, int fr, int fq) const {
;     ...
;             for (int q = 0; q < 8; ++q) {
;                 const int ai = q >> 2, m = q & 3;
;                 const f32x4 av = acc[ai][0][m][n], ag = acc[ai][1][m][n];
;                 f32x4 rv1, rv2, rg1, rg2;
; #pragma unroll
;                 for (int j = 0; j < 4; ++j) { rv1[j] = SHI(lane, av[j], src1); rv2[j] = SHI(lane, av[j], src2); rg1[j] = SHI(lane, ag[j], src1); rg2[j] = SHI(lane, ag[j], src2); }
;                 const f32x4 sv1 = fr >= 1 ? rv1 : pv1, sv2 = fr >= 2 ? rv2 : pv2, sg1 = fr >= 1 ? rg1 : pg1, sg2 = fr >= 2 ? rg2 : pg2;
;                 const f32x4 ov = wv[2] * av + wv[1] * sv1 + wv[0] * sv2;
;                 const f32x4 og = wg[2] * ag + wg[1] * sg1 + wg[0] * sg2;
;                 u32x2 w;
;                 w.x = cvt_pk_bf16(og[0] * sigmoidf_(og[0]) * ov[0], og[1] * sigmoidf_(og[1]) * ov[1]);
;                 w.y = cvt_pk_bf16(og[2] * sigmoidf_(og[2]) * ov[2], og[3] * sigmoidf_(og[3]) * ov[3]);
;                 *(u32x2*)(act + (size_t)(tok0 + q * 16) * DFF + ch) = w;
;                 if (q == 0 && fr < 2) { float* hp = halo + ((size_t)seg * 4 + fr) * NUP + ch; *(f32x4*)hp = av; *(f32x4*)(hp + DFF) = ag; }
;                 if (q == 7 && fr >= 14) { float* hp = halo + ((size_t)seg * 4 + (fr - 12)) * NUP + ch; *(f32x4*)hp = av; *(f32x4*)(hp + DFF) = ag; }
;                 pv1 = rv1; pv2 = rv2; pg1 = rg1; pg2 = rg2;
	global_store_dwordx4 v[176:177], v[126:129], off
	s_nop 1
	v_add_co_u32_e32 v126, vcc, 0x5000, v176
	s_nop 1
	v_addc_co_u32_e32 v127, vcc, 0, v177, vcc
	global_store_dwordx4 v[126:127], v[122:125], off offset:2048
.LBB0_622:
	s_or_b64 exec, exec, s[78:79]
	ds_bpermute_b32 v217, v180, v120
	ds_bpermute_b32 v221, v180, v121
	ds_bpermute_b32 v211, v180, v114
	ds_bpermute_b32 v215, v180, v115
	ds_bpermute_b32 v209, v180, v118
	ds_bpermute_b32 v213, v180, v119
	ds_bpermute_b32 v212, v181, v114
	ds_bpermute_b32 v216, v181, v115
	ds_bpermute_b32 v219, v180, v116
	ds_bpermute_b32 v223, v180, v117
	v_lshl_add_u64 v[124:125], s[76:77], 0, v[164:165]
	s_mov_b32 s33, 0xb000
	ds_bpermute_b32 v220, v181, v116
	ds_bpermute_b32 v224, v181, v117
	s_waitcnt lgkmcnt(0)
	v_cndmask_b32_e64 v127, v221, v208, s[0:1]
	v_cndmask_b32_e64 v126, v217, v206, s[0:1]
	v_mad_u64_u32 v[122:123], s[46:47], v124, s33, 0
	v_cndmask_b32_e64 v193, v215, v198, s[0:1]
	v_cndmask_b32_e64 v192, v211, v186, s[0:1]
	v_pk_mul_f32 v[126:127], v[148:149], v[126:127]
	v_mad_i32_i24 v123, v125, s33, v123
	ds_bpermute_b32 v218, v181, v120
	ds_bpermute_b32 v222, v181, v121
	v_cndmask_b32_e64 v125, v213, v204, s[0:1]
	v_cndmask_b32_e64 v124, v209, v199, s[0:1]
	v_pk_fma_f32 v[120:121], v[120:121], v[152:153], v[126:127]
	v_pk_mul_f32 v[126:127], v[138:139], v[192:193]
	v_cndmask_b32_e64 v195, v223, v205, s[0:1]
	v_cndmask_b32_e64 v194, v219, v200, s[0:1]
	v_cndmask_b32_e64 v187, v187, v216, s[2:3]
	v_cndmask_b32_e64 v186, v185, v212, s[2:3]
	v_pk_mul_f32 v[124:125], v[146:147], v[124:125]
	v_pk_fma_f32 v[114:115], v[114:115], v[142:143], v[126:127]
	ds_bpermute_b32 v210, v181, v118
	ds_bpermute_b32 v214, v181, v119
	v_pk_fma_f32 v[118:119], v[118:119], v[150:151], v[124:125]
	v_pk_mul_f32 v[124:125], v[140:141], v[194:195]
	v_pk_fma_f32 v[114:115], v[130:131], v[186:187], v[114:115]
	v_cndmask_b32_e64 v199, v202, v224, s[2:3]
	v_cndmask_b32_e64 v198, v197, v220, s[2:3]
	v_pk_fma_f32 v[116:117], v[116:117], v[144:145], v[124:125]
	v_mul_f32_e32 v124, 0xbfb8aa3b, v114
	v_mul_f32_e32 v125, 0xbfb8aa3b, v115
	v_exp_f32_e32 v124, v124
	v_exp_f32_e32 v125, v125
	v_pk_fma_f32 v[116:117], v[132:133], v[198:199], v[116:117]
	s_waitcnt lgkmcnt(0)
	v_cndmask_b32_e64 v129, v201, v214, s[2:3]
	v_mul_f32_e32 v126, 0xbfb8aa3b, v116
	v_mul_f32_e32 v127, 0xbfb8aa3b, v117
	v_exp_f32_e32 v126, v126
	v_exp_f32_e32 v127, v127
	v_add_f32_e32 v124, 1.0, v124
	v_add_f32_e32 v125, 1.0, v125
	v_rcp_f32_e32 v124, v124
	v_rcp_f32_e32 v125, v125
	v_add_f32_e32 v126, 1.0, v126
	v_add_f32_e32 v127, 1.0, v127
	v_rcp_f32_e32 v126, v126
	v_rcp_f32_e32 v127, v127
	v_cndmask_b32_e64 v128, v196, v210, s[2:3]
	v_pk_fma_f32 v[118:119], v[134:135], v[128:129], v[118:119]
	v_pk_mul_f32 v[114:115], v[114:115], v[124:125]
	v_cndmask_b32_e64 v179, v207, v222, s[2:3]
	v_cndmask_b32_e64 v178, v203, v218, s[2:3]
	v_pk_mul_f32 v[114:115], v[118:119], v[114:115]
	v_pk_fma_f32 v[120:121], v[136:137], v[178:179], v[120:121]
	v_cvt_pk_bf16_f32 v124, v114, v115
	v_pk_mul_f32 v[114:115], v[116:117], v[126:127]
	ds_bpermute_b32 v203, v180, v112
	ds_bpermute_b32 v207, v180, v113
	v_pk_mul_f32 v[114:115], v[120:121], v[114:115]
	ds_bpermute_b32 v197, v180, v106
	ds_bpermute_b32 v201, v180, v107
	v_cvt_pk_bf16_f32 v125, v114, v115
	v_or_b32_e32 v114, 16, v184
	v_mov_b64_e32 v[116:117], s[20:21]
	s_movk_i32 s33, 0x2c00
	ds_bpermute_b32 v185, v180, v110
	ds_bpermute_b32 v199, v180, v111
	v_mad_i64_i32 v[114:115], s[46:47], v114, s33, v[116:117]
	v_lshlrev_b64 v[118:119], 1, v[170:171]
	ds_bpermute_b32 v198, v181, v106
	ds_bpermute_b32 v202, v181, v107
	ds_bpermute_b32 v205, v180, v108
	ds_bpermute_b32 v225, v180, v109
	v_lshl_add_u64 v[114:115], v[114:115], 0, v[118:119]
	global_store_dwordx2 v[114:115], v[124:125], off
	ds_bpermute_b32 v206, v181, v108
	ds_bpermute_b32 v226, v181, v109
	s_waitcnt lgkmcnt(0)
	v_cndmask_b32_e64 v125, v207, v221, s[0:1]
	v_cndmask_b32_e64 v124, v203, v217, s[0:1]
	v_cndmask_b32_e64 v179, v201, v215, s[0:1]
	v_cndmask_b32_e64 v178, v197, v211, s[0:1]
	v_pk_mul_f32 v[124:125], v[148:149], v[124:125]
	ds_bpermute_b32 v204, v181, v112
	ds_bpermute_b32 v208, v181, v113
	v_cndmask_b32_e64 v121, v199, v213, s[0:1]
	v_cndmask_b32_e64 v120, v185, v209, s[0:1]
	v_pk_fma_f32 v[112:113], v[112:113], v[152:153], v[124:125]
	v_pk_mul_f32 v[124:125], v[138:139], v[178:179]
	v_cndmask_b32_e64 v187, v225, v223, s[0:1]
	v_cndmask_b32_e64 v186, v205, v219, s[0:1]
	v_cndmask_b32_e64 v193, v216, v202, s[2:3]
	v_cndmask_b32_e64 v192, v212, v198, s[2:3]
	v_pk_mul_f32 v[120:121], v[146:147], v[120:121]
	v_pk_fma_f32 v[106:107], v[106:107], v[142:143], v[124:125]
	ds_bpermute_b32 v196, v181, v110
	ds_bpermute_b32 v200, v181, v111
	v_pk_fma_f32 v[110:111], v[110:111], v[150:151], v[120:121]
	v_pk_mul_f32 v[120:121], v[140:141], v[186:187]
	v_pk_fma_f32 v[106:107], v[130:131], v[192:193], v[106:107]
	v_cndmask_b32_e64 v195, v224, v226, s[2:3]
	v_cndmask_b32_e64 v194, v220, v206, s[2:3]
	v_pk_fma_f32 v[108:109], v[108:109], v[144:145], v[120:121]
	v_mul_f32_e32 v120, 0xbfb8aa3b, v106
	v_mul_f32_e32 v121, 0xbfb8aa3b, v107
	v_exp_f32_e32 v120, v120
	v_exp_f32_e32 v121, v121
	v_pk_fma_f32 v[108:109], v[132:133], v[194:195], v[108:109]
	s_waitcnt lgkmcnt(0)
; __device__ __forceinline__ unsigned cvt_pk_bf16(float lo, float hi) { f32x2_t f = {lo, hi}; bf16x2_t v = __builtin_convertvector(f, bf16x2_t); return __builtin_bit_cast(unsigned, v); }
; __device__ __forceinline__ float sigmoidf_(float x) { return __builtin_amdgcn_rcpf(1.0f + __expf(-x)); }
; #define SHI(lane, v, src) shfl_idx(lane, (v), (src))
;     __device__ __forceinline__ void operator()(const f32x4 (&acc)[2][2][4][2], const Unit& u, int wr, int wc, int fr, int fq) const {
;     ...
;             for (int q = 0; q < 8; ++q) {
;                 const int ai = q >> 2, m = q & 3;
;                 const f32x4 av = acc[ai][0][m][n], ag = acc[ai][1][m][n];
;                 f32x4 rv1, rv2, rg1, rg2;
; #pragma unroll
;                 for (int j = 0; j < 4; ++j) { rv1[j] = SHI(lane, av[j], src1); rv2[j] = SHI(lane, av[j], src2); rg1[j] = SHI(lane, ag[j], src1); rg2[j] = SHI(lane, ag[j], src2); }
;                 const f32x4 sv1 = fr >= 1 ? rv1 : pv1, sv2 = fr >= 2 ? rv2 : pv2, sg1 = fr >= 1 ? rg1 : pg1, sg2 = fr >= 2 ? rg2 : pg2;
;                 const f32x4 ov = wv[2] * av + wv[1] * sv1 + wv[0] * sv2;
;                 const f32x4 og = wg[2] * ag + wg[1] * sg1 + wg[0] * sg2;
;                 u32x2 w;
;                 w.x = cvt_pk_bf16(og[0] * sigmoidf_(og[0]) * ov[0], og[1] * sigmoidf_(og[1]) * ov[1]);
;                 w.y = cvt_pk_bf16(og[2] * sigmoidf_(og[2]) * ov[2], og[3] * sigmoidf_(og[3]) * ov[3]);
;                 *(u32x2*)(act + (size_t)(tok0 + q * 16) * DFF + ch) = w;
;                 if (q == 0 && fr < 2) { float* hp = halo + ((size_t)seg * 4 + fr) * NUP + ch; *(f32x4*)hp = av; *(f32x4*)(hp + DFF) = ag; }
;                 if (q == 7 && fr >= 14) { float* hp = halo + ((size_t)seg * 4 + (fr - 12)) * NUP + ch; *(f32x4*)hp = av; *(f32x4*)(hp + DFF) = ag; }
;                 pv1 = rv1; pv2 = rv2; pg1 = rg1; pg2 = rg2;
	v_cndmask_b32_e64 v127, v214, v200, s[2:3]
	v_mul_f32_e32 v124, 0xbfb8aa3b, v108
	v_mul_f32_e32 v125, 0xbfb8aa3b, v109
	v_exp_f32_e32 v124, v124
	v_exp_f32_e32 v125, v125
	v_add_f32_e32 v120, 1.0, v120
	v_add_f32_e32 v121, 1.0, v121
	v_rcp_f32_e32 v120, v120
	v_rcp_f32_e32 v121, v121
	v_add_f32_e32 v124, 1.0, v124
	v_add_f32_e32 v125, 1.0, v125
	v_rcp_f32_e32 v124, v124
	v_rcp_f32_e32 v125, v125
	v_cndmask_b32_e64 v126, v210, v196, s[2:3]
	v_pk_fma_f32 v[110:111], v[134:135], v[126:127], v[110:111]
	v_pk_mul_f32 v[106:107], v[106:107], v[120:121]
	v_cndmask_b32_e64 v129, v222, v208, s[2:3]
	v_cndmask_b32_e64 v128, v218, v204, s[2:3]
	v_pk_mul_f32 v[106:107], v[110:111], v[106:107]
	v_pk_fma_f32 v[112:113], v[136:137], v[128:129], v[112:113]
	v_cvt_pk_bf16_f32 v110, v106, v107
	v_pk_mul_f32 v[106:107], v[108:109], v[124:125]
	ds_bpermute_b32 v211, v180, v104
	ds_bpermute_b32 v215, v180, v105
	v_pk_mul_f32 v[106:107], v[112:113], v[106:107]
	ds_bpermute_b32 v192, v180, v98
	ds_bpermute_b32 v209, v180, v99
	v_cvt_pk_bf16_f32 v111, v106, v107
	v_or_b32_e32 v106, 32, v184
	ds_bpermute_b32 v186, v180, v102
	ds_bpermute_b32 v194, v180, v103
	v_mad_i64_i32 v[106:107], s[46:47], v106, s33, v[116:117]
	ds_bpermute_b32 v193, v181, v98
	ds_bpermute_b32 v210, v181, v99
	ds_bpermute_b32 v213, v180, v100
	ds_bpermute_b32 v217, v180, v101
	v_lshl_add_u64 v[106:107], v[106:107], 0, v[118:119]
	global_store_dwordx2 v[106:107], v[110:111], off
	ds_bpermute_b32 v214, v181, v100
	ds_bpermute_b32 v218, v181, v101
	s_waitcnt lgkmcnt(0)
	v_cndmask_b32_e64 v111, v215, v207, s[0:1]
	v_cndmask_b32_e64 v110, v211, v203, s[0:1]
	v_cndmask_b32_e64 v125, v209, v201, s[0:1]
	v_cndmask_b32_e64 v124, v192, v197, s[0:1]
	v_pk_mul_f32 v[110:111], v[148:149], v[110:111]
	ds_bpermute_b32 v212, v181, v104
	ds_bpermute_b32 v216, v181, v105
	v_cndmask_b32_e64 v109, v194, v199, s[0:1]
	v_cndmask_b32_e64 v108, v186, v185, s[0:1]
	v_pk_fma_f32 v[104:105], v[104:105], v[152:153], v[110:111]
	v_pk_mul_f32 v[110:111], v[138:139], v[124:125]
	v_cndmask_b32_e64 v127, v217, v225, s[0:1]
	v_cndmask_b32_e64 v126, v213, v205, s[0:1]
	v_cndmask_b32_e64 v129, v202, v210, s[2:3]
	v_cndmask_b32_e64 v128, v198, v193, s[2:3]
	v_pk_mul_f32 v[108:109], v[146:147], v[108:109]
	v_pk_fma_f32 v[98:99], v[98:99], v[142:143], v[110:111]
	ds_bpermute_b32 v187, v181, v102
	ds_bpermute_b32 v195, v181, v103
	v_pk_fma_f32 v[102:103], v[102:103], v[150:151], v[108:109]
	v_pk_mul_f32 v[108:109], v[140:141], v[126:127]
	v_pk_fma_f32 v[98:99], v[130:131], v[128:129], v[98:99]
	v_cndmask_b32_e64 v179, v226, v218, s[2:3]
	v_cndmask_b32_e64 v178, v206, v214, s[2:3]
	v_pk_fma_f32 v[100:101], v[100:101], v[144:145], v[108:109]
	v_mul_f32_e32 v108, 0xbfb8aa3b, v98
	v_mul_f32_e32 v109, 0xbfb8aa3b, v99
	v_exp_f32_e32 v108, v108
	v_exp_f32_e32 v109, v109
	v_pk_fma_f32 v[100:101], v[132:133], v[178:179], v[100:101]
	s_waitcnt lgkmcnt(0)
	v_cndmask_b32_e64 v113, v200, v195, s[2:3]
	v_mul_f32_e32 v110, 0xbfb8aa3b, v100
	v_mul_f32_e32 v111, 0xbfb8aa3b, v101
	v_exp_f32_e32 v110, v110
	v_exp_f32_e32 v111, v111
	v_add_f32_e32 v108, 1.0, v108
	v_add_f32_e32 v109, 1.0, v109
	v_rcp_f32_e32 v108, v108
	v_rcp_f32_e32 v109, v109
	v_add_f32_e32 v110, 1.0, v110
	v_add_f32_e32 v111, 1.0, v111
	v_rcp_f32_e32 v110, v110
	v_rcp_f32_e32 v111, v111
	v_cndmask_b32_e64 v112, v196, v187, s[2:3]
	v_pk_fma_f32 v[102:103], v[134:135], v[112:113], v[102:103]
	v_pk_mul_f32 v[98:99], v[98:99], v[108:109]
	v_cndmask_b32_e64 v121, v208, v216, s[2:3]
	v_cndmask_b32_e64 v120, v204, v212, s[2:3]
	v_pk_mul_f32 v[98:99], v[102:103], v[98:99]
	v_pk_fma_f32 v[104:105], v[136:137], v[120:121], v[104:105]
	v_cvt_pk_bf16_f32 v102, v98, v99
	v_pk_mul_f32 v[98:99], v[100:101], v[110:111]
	ds_bpermute_b32 v126, v180, v94
	ds_bpermute_b32 v178, v180, v95
	ds_bpermute_b32 v197, v180, v96
	ds_bpermute_b32 v201, v180, v97
	v_pk_mul_f32 v[98:99], v[104:105], v[98:99]
	ds_bpermute_b32 v128, v180, v90
	ds_bpermute_b32 v185, v180, v91
	ds_bpermute_b32 v199, v180, v92
	ds_bpermute_b32 v203, v180, v93
	v_cvt_pk_bf16_f32 v103, v98, v99
	v_or_b32_e32 v98, 48, v184
	v_mad_i64_i32 v[98:99], s[46:47], v98, s33, v[116:117]
	ds_bpermute_b32 v129, v181, v90
	ds_bpermute_b32 v196, v181, v91
	ds_bpermute_b32 v200, v181, v92
	ds_bpermute_b32 v204, v181, v93
	v_lshl_add_u64 v[98:99], v[98:99], 0, v[118:119]
	global_store_dwordx2 v[98:99], v[102:103], off
	s_waitcnt lgkmcnt(0)
	v_cndmask_b32_e64 v101, v178, v194, s[0:1]
	v_cndmask_b32_e64 v100, v126, v186, s[0:1]
	v_cndmask_b32_e64 v103, v201, v215, s[0:1]
	v_cndmask_b32_e64 v102, v197, v211, s[0:1]
	v_cndmask_b32_e64 v111, v185, v209, s[0:1]
	v_cndmask_b32_e64 v110, v128, v192, s[0:1]
	v_cndmask_b32_e64 v113, v203, v217, s[0:1]
	v_cndmask_b32_e64 v112, v199, v213, s[0:1]
	v_pk_mul_f32 v[102:103], v[148:149], v[102:103]
	v_pk_mul_f32 v[100:101], v[146:147], v[100:101]
	ds_bpermute_b32 v127, v181, v94
	ds_bpermute_b32 v179, v181, v95
	ds_bpermute_b32 v198, v181, v96
	ds_bpermute_b32 v202, v181, v97
	v_pk_fma_f32 v[94:95], v[94:95], v[150:151], v[100:101]
	v_pk_fma_f32 v[96:97], v[96:97], v[152:153], v[102:103]
	v_pk_mul_f32 v[100:101], v[140:141], v[112:113]
	v_pk_mul_f32 v[102:103], v[138:139], v[110:111]
	v_cndmask_b32_e64 v121, v210, v196, s[2:3]
	v_cndmask_b32_e64 v120, v193, v129, s[2:3]
	v_cndmask_b32_e64 v125, v218, v204, s[2:3]
	v_cndmask_b32_e64 v124, v214, v200, s[2:3]
	v_pk_fma_f32 v[90:91], v[90:91], v[142:143], v[102:103]
	v_pk_fma_f32 v[92:93], v[92:93], v[144:145], v[100:101]
	v_pk_fma_f32 v[90:91], v[130:131], v[120:121], v[90:91]
	v_pk_fma_f32 v[92:93], v[132:133], v[124:125], v[92:93]
	v_mul_f32_e32 v100, 0xbfb8aa3b, v90
	v_mul_f32_e32 v101, 0xbfb8aa3b, v91
	v_mul_f32_e32 v102, 0xbfb8aa3b, v92
	v_mul_f32_e32 v103, 0xbfb8aa3b, v93
	v_exp_f32_e32 v100, v100
	v_exp_f32_e32 v101, v101
	v_exp_f32_e32 v102, v102
	v_exp_f32_e32 v103, v103
	v_add_f32_e32 v100, 1.0, v100
	v_add_f32_e32 v101, 1.0, v101
	v_add_f32_e32 v102, 1.0, v102
	v_add_f32_e32 v103, 1.0, v103
	v_rcp_f32_e32 v100, v100
	v_rcp_f32_e32 v101, v101
	v_rcp_f32_e32 v102, v102
	v_rcp_f32_e32 v103, v103
	s_waitcnt lgkmcnt(0)
; __device__ __forceinline__ unsigned cvt_pk_bf16(float lo, float hi) { f32x2_t f = {lo, hi}; bf16x2_t v = __builtin_convertvector(f, bf16x2_t); return __builtin_bit_cast(unsigned, v); }
; __device__ __forceinline__ float sigmoidf_(float x) { return __builtin_amdgcn_rcpf(1.0f + __expf(-x)); }
; #define SHI(lane, v, src) shfl_idx(lane, (v), (src))
;     __device__ __forceinline__ void operator()(const f32x4 (&acc)[2][2][4][2], const Unit& u, int wr, int wc, int fr, int fq) const {
;     ...
;             for (int q = 0; q < 8; ++q) {
;                 const int ai = q >> 2, m = q & 3;
;                 const f32x4 av = acc[ai][0][m][n], ag = acc[ai][1][m][n];
;                 f32x4 rv1, rv2, rg1, rg2;
; #pragma unroll
;                 for (int j = 0; j < 4; ++j) { rv1[j] = SHI(lane, av[j], src1); rv2[j] = SHI(lane, av[j], src2); rg1[j] = SHI(lane, ag[j], src1); rg2[j] = SHI(lane, ag[j], src2); }
;                 const f32x4 sv1 = fr >= 1 ? rv1 : pv1, sv2 = fr >= 2 ? rv2 : pv2, sg1 = fr >= 1 ? rg1 : pg1, sg2 = fr >= 2 ? rg2 : pg2;
;                 const f32x4 ov = wv[2] * av + wv[1] * sv1 + wv[0] * sv2;
;                 const f32x4 og = wg[2] * ag + wg[1] * sg1 + wg[0] * sg2;
;                 u32x2 w;
;                 w.x = cvt_pk_bf16(og[0] * sigmoidf_(og[0]) * ov[0], og[1] * sigmoidf_(og[1]) * ov[1]);
;                 w.y = cvt_pk_bf16(og[2] * sigmoidf_(og[2]) * ov[2], og[3] * sigmoidf_(og[3]) * ov[3]);
;                 *(u32x2*)(act + (size_t)(tok0 + q * 16) * DFF + ch) = w;
;                 if (q == 0 && fr < 2) { float* hp = halo + ((size_t)seg * 4 + fr) * NUP + ch; *(f32x4*)hp = av; *(f32x4*)(hp + DFF) = ag; }
;                 if (q == 7 && fr >= 14) { float* hp = halo + ((size_t)seg * 4 + (fr - 12)) * NUP + ch; *(f32x4*)hp = av; *(f32x4*)(hp + DFF) = ag; }
;                 pv1 = rv1; pv2 = rv2; pg1 = rg1; pg2 = rg2;
	v_cndmask_b32_e64 v105, v195, v179, s[2:3]
	v_cndmask_b32_e64 v104, v187, v127, s[2:3]
	v_cndmask_b32_e64 v109, v216, v202, s[2:3]
	v_cndmask_b32_e64 v108, v212, v198, s[2:3]
	v_pk_fma_f32 v[96:97], v[136:137], v[108:109], v[96:97]
	v_pk_fma_f32 v[94:95], v[134:135], v[104:105], v[94:95]
	v_pk_mul_f32 v[90:91], v[90:91], v[100:101]
	v_pk_mul_f32 v[92:93], v[92:93], v[102:103]
	ds_bpermute_b32 v112, v180, v86
	ds_bpermute_b32 v124, v180, v87
	ds_bpermute_b32 v192, v180, v88
	ds_bpermute_b32 v205, v180, v89
	v_pk_mul_f32 v[90:91], v[94:95], v[90:91]
	v_pk_mul_f32 v[92:93], v[96:97], v[92:93]
	ds_bpermute_b32 v120, v180, v82
	ds_bpermute_b32 v186, v180, v83
	ds_bpermute_b32 v194, v180, v84
	ds_bpermute_b32 v207, v180, v85
	v_cvt_pk_bf16_f32 v90, v90, v91
	v_cvt_pk_bf16_f32 v91, v92, v93
	v_or_b32_e32 v92, 64, v184
	v_mad_i64_i32 v[92:93], s[46:47], v92, s33, v[116:117]
	ds_bpermute_b32 v121, v181, v82
	ds_bpermute_b32 v187, v181, v83
	ds_bpermute_b32 v195, v181, v84
	ds_bpermute_b32 v208, v181, v85
	v_lshl_add_u64 v[92:93], v[92:93], 0, v[118:119]
	global_store_dwordx2 v[92:93], v[90:91], off
	s_waitcnt lgkmcnt(0)
	v_cndmask_b32_e64 v91, v124, v178, s[0:1]
	v_cndmask_b32_e64 v90, v112, v126, s[0:1]
	v_cndmask_b32_e64 v95, v205, v201, s[0:1]
	v_cndmask_b32_e64 v94, v192, v197, s[0:1]
	v_cndmask_b32_e64 v103, v186, v185, s[0:1]
	v_cndmask_b32_e64 v102, v120, v128, s[0:1]
	v_cndmask_b32_e64 v105, v207, v203, s[0:1]
	v_cndmask_b32_e64 v104, v194, v199, s[0:1]
	v_pk_mul_f32 v[94:95], v[148:149], v[94:95]
	v_pk_mul_f32 v[90:91], v[146:147], v[90:91]
	ds_bpermute_b32 v113, v181, v86
	ds_bpermute_b32 v125, v181, v87
	ds_bpermute_b32 v193, v181, v88
	ds_bpermute_b32 v206, v181, v89
	v_pk_fma_f32 v[86:87], v[86:87], v[150:151], v[90:91]
	v_pk_fma_f32 v[88:89], v[88:89], v[152:153], v[94:95]
	v_pk_mul_f32 v[90:91], v[140:141], v[104:105]
	v_pk_mul_f32 v[94:95], v[138:139], v[102:103]
	v_cndmask_b32_e64 v109, v196, v187, s[2:3]
	v_cndmask_b32_e64 v108, v129, v121, s[2:3]
	v_cndmask_b32_e64 v111, v204, v208, s[2:3]
	v_cndmask_b32_e64 v110, v200, v195, s[2:3]
	v_pk_fma_f32 v[82:83], v[82:83], v[142:143], v[94:95]
	v_pk_fma_f32 v[84:85], v[84:85], v[144:145], v[90:91]
	v_pk_fma_f32 v[82:83], v[130:131], v[108:109], v[82:83]
	v_pk_fma_f32 v[84:85], v[132:133], v[110:111], v[84:85]
	v_mul_f32_e32 v90, 0xbfb8aa3b, v82
	v_mul_f32_e32 v91, 0xbfb8aa3b, v83
	v_mul_f32_e32 v94, 0xbfb8aa3b, v84
	v_mul_f32_e32 v95, 0xbfb8aa3b, v85
	v_exp_f32_e32 v90, v90
	v_exp_f32_e32 v91, v91
	v_exp_f32_e32 v94, v94
	v_exp_f32_e32 v95, v95
	v_add_f32_e32 v90, 1.0, v90
	v_add_f32_e32 v91, 1.0, v91
	v_add_f32_e32 v94, 1.0, v94
	v_add_f32_e32 v95, 1.0, v95
	v_rcp_f32_e32 v90, v90
	v_rcp_f32_e32 v91, v91
	v_rcp_f32_e32 v94, v94
	v_rcp_f32_e32 v95, v95
	s_waitcnt lgkmcnt(0)
	v_cndmask_b32_e64 v97, v179, v125, s[2:3]
	v_cndmask_b32_e64 v96, v127, v113, s[2:3]
	v_cndmask_b32_e64 v101, v202, v206, s[2:3]
	v_cndmask_b32_e64 v100, v198, v193, s[2:3]
	v_pk_fma_f32 v[88:89], v[136:137], v[100:101], v[88:89]
	v_pk_fma_f32 v[86:87], v[134:135], v[96:97], v[86:87]
	v_pk_mul_f32 v[82:83], v[82:83], v[90:91]
	v_pk_mul_f32 v[84:85], v[84:85], v[94:95]
	ds_bpermute_b32 v104, v180, v78
	ds_bpermute_b32 v110, v180, v79
	ds_bpermute_b32 v128, v180, v80
	ds_bpermute_b32 v185, v180, v81
	v_pk_mul_f32 v[82:83], v[86:87], v[82:83]
	v_pk_mul_f32 v[84:85], v[88:89], v[84:85]
	ds_bpermute_b32 v108, v180, v74
	ds_bpermute_b32 v126, v180, v75
	ds_bpermute_b32 v178, v180, v76
	ds_bpermute_b32 v197, v180, v77
	v_cvt_pk_bf16_f32 v82, v82, v83
	v_cvt_pk_bf16_f32 v83, v84, v85
	v_or_b32_e32 v84, 0x50, v184
	v_mad_i64_i32 v[84:85], s[46:47], v84, s33, v[116:117]
	ds_bpermute_b32 v109, v181, v74
	ds_bpermute_b32 v127, v181, v75
	ds_bpermute_b32 v179, v181, v76
	ds_bpermute_b32 v198, v181, v77
	v_lshl_add_u64 v[94:95], v[84:85], 0, v[118:119]
	global_store_dwordx2 v[94:95], v[82:83], off
	s_waitcnt lgkmcnt(0)
	v_cndmask_b32_e64 v83, v110, v124, s[0:1]
	v_cndmask_b32_e64 v82, v104, v112, s[0:1]
	v_cndmask_b32_e64 v85, v185, v205, s[0:1]
	v_cndmask_b32_e64 v84, v128, v192, s[0:1]
	v_cndmask_b32_e64 v91, v126, v186, s[0:1]
	v_cndmask_b32_e64 v90, v108, v120, s[0:1]
	v_cndmask_b32_e64 v97, v197, v207, s[0:1]
	v_cndmask_b32_e64 v96, v178, v194, s[0:1]
	v_pk_mul_f32 v[84:85], v[148:149], v[84:85]
	v_pk_mul_f32 v[82:83], v[146:147], v[82:83]
	ds_bpermute_b32 v105, v181, v78
	ds_bpermute_b32 v111, v181, v79
	ds_bpermute_b32 v129, v181, v80
	ds_bpermute_b32 v196, v181, v81
	v_pk_fma_f32 v[78:79], v[78:79], v[150:151], v[82:83]
	v_pk_fma_f32 v[80:81], v[80:81], v[152:153], v[84:85]
	v_pk_mul_f32 v[82:83], v[140:141], v[96:97]
	v_pk_mul_f32 v[84:85], v[138:139], v[90:91]
	v_cndmask_b32_e64 v101, v187, v127, s[2:3]
	v_cndmask_b32_e64 v100, v121, v109, s[2:3]
	v_cndmask_b32_e64 v103, v208, v198, s[2:3]
	v_cndmask_b32_e64 v102, v195, v179, s[2:3]
	v_pk_fma_f32 v[74:75], v[74:75], v[142:143], v[84:85]
	v_pk_fma_f32 v[76:77], v[76:77], v[144:145], v[82:83]
	v_pk_fma_f32 v[74:75], v[130:131], v[100:101], v[74:75]
	v_pk_fma_f32 v[76:77], v[132:133], v[102:103], v[76:77]
	v_mul_f32_e32 v82, 0xbfb8aa3b, v74
	v_mul_f32_e32 v83, 0xbfb8aa3b, v75
	v_mul_f32_e32 v84, 0xbfb8aa3b, v76
	v_mul_f32_e32 v85, 0xbfb8aa3b, v77
	v_exp_f32_e32 v82, v82
	v_exp_f32_e32 v83, v83
	v_exp_f32_e32 v84, v84
	v_exp_f32_e32 v85, v85
	v_add_f32_e32 v82, 1.0, v82
	v_add_f32_e32 v83, 1.0, v83
	v_add_f32_e32 v84, 1.0, v84
	v_add_f32_e32 v85, 1.0, v85
	v_rcp_f32_e32 v82, v82
	v_rcp_f32_e32 v83, v83
	v_rcp_f32_e32 v84, v84
	v_rcp_f32_e32 v85, v85
	s_waitcnt lgkmcnt(0)
; __device__ __forceinline__ unsigned cvt_pk_bf16(float lo, float hi) { f32x2_t f = {lo, hi}; bf16x2_t v = __builtin_convertvector(f, bf16x2_t); return __builtin_bit_cast(unsigned, v); }
; __device__ __forceinline__ float sigmoidf_(float x) { return __builtin_amdgcn_rcpf(1.0f + __expf(-x)); }
; #define SHI(lane, v, src) shfl_idx(lane, (v), (src))
;     __device__ __forceinline__ void operator()(const f32x4 (&acc)[2][2][4][2], const Unit& u, int wr, int wc, int fr, int fq) const {
;     ...
;         for (int n = 0; n < 2; ++n) {
;             const int ch = ch0 + 4 * n;
;             f32x4 wv[3], wg[3];
; #pragma unroll
;             for (int k = 0; k < 3; ++k) { wv[k] = *(const f32x4*)(cw + k * NUP + ch); wg[k] = *(const f32x4*)(cw + k * NUP + DFF + ch); }
;             f32x4 pv1 = {0.f, 0.f, 0.f, 0.f}, pv2 = pv1, pg1 = pv1, pg2 = pv1;
; #pragma unroll
;             for (int q = 0; q < 8; ++q) {
;                 const int ai = q >> 2, m = q & 3;
;                 const f32x4 av = acc[ai][0][m][n], ag = acc[ai][1][m][n];
;                 f32x4 rv1, rv2, rg1, rg2;
; #pragma unroll
;                 for (int j = 0; j < 4; ++j) { rv1[j] = SHI(lane, av[j], src1); rv2[j] = SHI(lane, av[j], src2); rg1[j] = SHI(lane, ag[j], src1); rg2[j] = SHI(lane, ag[j], src2); }
;                 const f32x4 sv1 = fr >= 1 ? rv1 : pv1, sv2 = fr >= 2 ? rv2 : pv2, sg1 = fr >= 1 ? rg1 : pg1, sg2 = fr >= 2 ? rg2 : pg2;
;                 const f32x4 ov = wv[2] * av + wv[1] * sv1 + wv[0] * sv2;
;                 const f32x4 og = wg[2] * ag + wg[1] * sg1 + wg[0] * sg2;
;                 u32x2 w;
;                 w.x = cvt_pk_bf16(og[0] * sigmoidf_(og[0]) * ov[0], og[1] * sigmoidf_(og[1]) * ov[1]);
;                 w.y = cvt_pk_bf16(og[2] * sigmoidf_(og[2]) * ov[2], og[3] * sigmoidf_(og[3]) * ov[3]);
;                 *(u32x2*)(act + (size_t)(tok0 + q * 16) * DFF + ch) = w;
;                 if (q == 0 && fr < 2) { float* hp = halo + ((size_t)seg * 4 + fr) * NUP + ch; *(f32x4*)hp = av; *(f32x4*)(hp + DFF) = ag; }
;                 if (q == 7 && fr >= 14) { float* hp = halo + ((size_t)seg * 4 + (fr - 12)) * NUP + ch; *(f32x4*)hp = av; *(f32x4*)(hp + DFF) = ag; }
;                 pv1 = rv1; pv2 = rv2; pg1 = rg1; pg2 = rg2;
	v_cndmask_b32_e64 v87, v125, v111, s[2:3]
	v_cndmask_b32_e64 v86, v113, v105, s[2:3]
	v_cndmask_b32_e64 v89, v206, v196, s[2:3]
	v_cndmask_b32_e64 v88, v193, v129, s[2:3]
	v_pk_fma_f32 v[80:81], v[136:137], v[88:89], v[80:81]
	v_pk_fma_f32 v[78:79], v[134:135], v[86:87], v[78:79]
	v_pk_mul_f32 v[74:75], v[74:75], v[82:83]
	v_pk_mul_f32 v[76:77], v[76:77], v[84:85]
	v_pk_mul_f32 v[74:75], v[78:79], v[74:75]
	v_pk_mul_f32 v[76:77], v[80:81], v[76:77]
	v_cvt_pk_bf16_f32 v74, v74, v75
	v_cvt_pk_bf16_f32 v75, v76, v77
	v_or_b32_e32 v76, 0x60, v184
	v_mad_i64_i32 v[76:77], s[46:47], v76, s33, v[116:117]
	v_lshl_add_u64 v[96:97], v[76:77], 0, v[118:119]
	global_store_dwordx2 v[96:97], v[74:75], off
	ds_bpermute_b32 v74, v180, v70
	ds_bpermute_b32 v75, v180, v71
	ds_bpermute_b32 v76, v180, v72
	ds_bpermute_b32 v77, v180, v73
	ds_bpermute_b32 v78, v181, v70
	ds_bpermute_b32 v82, v180, v66
	ds_bpermute_b32 v79, v181, v71
	ds_bpermute_b32 v83, v180, v67
	ds_bpermute_b32 v80, v181, v72
	ds_bpermute_b32 v84, v180, v68
	ds_bpermute_b32 v81, v181, v73
	ds_bpermute_b32 v85, v180, v69
	ds_bpermute_b32 v86, v181, v66
	ds_bpermute_b32 v87, v181, v67
	ds_bpermute_b32 v88, v181, v68
	ds_bpermute_b32 v89, v181, v69
	s_waitcnt lgkmcnt(0)
	v_cndmask_b32_e64 v75, v75, v110, s[0:1]
	v_cndmask_b32_e64 v74, v74, v104, s[0:1]
	v_cndmask_b32_e64 v77, v77, v185, s[0:1]
	v_cndmask_b32_e64 v76, v76, v128, s[0:1]
	v_pk_mul_f32 v[76:77], v[148:149], v[76:77]
	v_pk_mul_f32 v[74:75], v[146:147], v[74:75]
	v_cndmask_b32_e64 v79, v111, v79, s[2:3]
	v_cndmask_b32_e64 v78, v105, v78, s[2:3]
	v_cndmask_b32_e64 v81, v196, v81, s[2:3]
	v_cndmask_b32_e64 v80, v129, v80, s[2:3]
	v_cndmask_b32_e64 v83, v83, v126, s[0:1]
	v_cndmask_b32_e64 v82, v82, v108, s[0:1]
	v_cndmask_b32_e64 v85, v85, v197, s[0:1]
	v_cndmask_b32_e64 v84, v84, v178, s[0:1]
	v_pk_fma_f32 v[74:75], v[70:71], v[150:151], v[74:75]
	v_pk_fma_f32 v[76:77], v[72:73], v[152:153], v[76:77]
	v_pk_fma_f32 v[74:75], v[134:135], v[78:79], v[74:75]
	v_pk_fma_f32 v[76:77], v[136:137], v[80:81], v[76:77]
	v_pk_mul_f32 v[78:79], v[140:141], v[84:85]
	v_pk_mul_f32 v[80:81], v[138:139], v[82:83]
	v_cndmask_b32_e64 v87, v127, v87, s[2:3]
	v_cndmask_b32_e64 v86, v109, v86, s[2:3]
	v_cndmask_b32_e64 v89, v198, v89, s[2:3]
	v_cndmask_b32_e64 v88, v179, v88, s[2:3]
	v_pk_fma_f32 v[80:81], v[66:67], v[142:143], v[80:81]
	v_pk_fma_f32 v[78:79], v[68:69], v[144:145], v[78:79]
	v_pk_fma_f32 v[80:81], v[130:131], v[86:87], v[80:81]
	v_pk_fma_f32 v[78:79], v[132:133], v[88:89], v[78:79]
	v_mul_f32_e32 v82, 0xbfb8aa3b, v80
	v_mul_f32_e32 v83, 0xbfb8aa3b, v81
	v_mul_f32_e32 v84, 0xbfb8aa3b, v78
	v_mul_f32_e32 v85, 0xbfb8aa3b, v79
	v_exp_f32_e32 v82, v82
	v_exp_f32_e32 v83, v83
	v_exp_f32_e32 v84, v84
	v_exp_f32_e32 v85, v85
	v_add_f32_e32 v82, 1.0, v82
	v_add_f32_e32 v83, 1.0, v83
	v_add_f32_e32 v84, 1.0, v84
	v_add_f32_e32 v85, 1.0, v85
	v_rcp_f32_e32 v82, v82
	v_rcp_f32_e32 v83, v83
	v_rcp_f32_e32 v84, v84
	v_rcp_f32_e32 v85, v85
	v_pk_mul_f32 v[80:81], v[80:81], v[82:83]
	s_nop 0
	v_pk_mul_f32 v[74:75], v[74:75], v[80:81]
	v_pk_mul_f32 v[78:79], v[78:79], v[84:85]
	v_cvt_pk_bf16_f32 v74, v74, v75
	v_pk_mul_f32 v[76:77], v[76:77], v[78:79]
	s_nop 0
	v_cvt_pk_bf16_f32 v75, v76, v77
	v_or_b32_e32 v76, 0x70, v184
	v_mad_i64_i32 v[76:77], s[46:47], v76, s33, v[116:117]
	v_lshl_add_u64 v[100:101], v[76:77], 0, v[118:119]
	global_store_dwordx2 v[100:101], v[74:75], off
	v_lshl_add_u64 v[74:75], s[22:23], 0, v[122:123]
	v_lshl_add_u64 v[90:91], v[170:171], 2, v[74:75]
	s_and_saveexec_b64 s[76:77], s[6:7]
	s_cbranch_execz .LBB0_624
	global_store_dwordx4 v[90:91], v[70:73], off
	s_nop 1
	v_add_co_u32_e32 v70, vcc, 0x5000, v90
	s_nop 1
	v_addc_co_u32_e32 v71, vcc, 0, v91, vcc
	global_store_dwordx4 v[70:71], v[66:69], off offset:2048
.LBB0_624:
	s_or_b64 exec, exec, s[76:77]
	s_nop 0
	v_or_b32_e32 v66, 4, v170
	v_ashrrev_i32_e32 v67, 31, v66
	v_lshlrev_b64 v[66:67], 2, v[66:67]
	v_lshl_add_u64 v[68:69], s[26:27], 0, v[66:67]
	global_load_dwordx4 v[82:85], v[68:69], off
	v_lshl_add_u64 v[68:69], s[28:29], 0, v[66:67]
	global_load_dwordx4 v[70:73], v[68:69], off
	v_lshl_add_u64 v[68:69], s[30:31], 0, v[66:67]
	global_load_dwordx4 v[86:89], v[68:69], off
	v_lshl_add_u64 v[68:69], s[34:35], 0, v[66:67]
	global_load_dwordx4 v[74:77], v[68:69], off
	v_lshl_add_u64 v[66:67], s[24:25], 0, v[66:67]
	global_load_dwordx4 v[66:69], v[66:67], off
	s_nop 0
	global_load_dwordx4 v[78:81], v[172:173], off offset:16
	ds_bpermute_b32 v103, v180, v58
	ds_bpermute_b32 v108, v180, v59
	ds_bpermute_b32 v111, v180, v60
	ds_bpermute_b32 v119, v180, v61
	ds_bpermute_b32 v102, v181, v58
	ds_bpermute_b32 v104, v181, v59
	ds_bpermute_b32 v109, v181, v60
	ds_bpermute_b32 v116, v181, v61
	s_waitcnt lgkmcnt(0)
	v_cndmask_b32_e64 v131, v119, 0, s[0:1]
	v_cndmask_b32_e64 v130, v111, 0, s[0:1]
	v_cndmask_b32_e64 v133, v108, 0, s[0:1]
	v_cndmask_b32_e64 v132, v103, 0, s[0:1]
	v_cndmask_b32_e64 v135, 0, v104, s[2:3]
	v_cndmask_b32_e64 v134, 0, v102, s[2:3]
	v_cndmask_b32_e64 v137, 0, v116, s[2:3]
	v_cndmask_b32_e64 v136, 0, v109, s[2:3]
	ds_bpermute_b32 v110, v180, v62
	ds_bpermute_b32 v117, v180, v63
	ds_bpermute_b32 v118, v180, v64
	ds_bpermute_b32 v121, v180, v65
	ds_bpermute_b32 v105, v181, v62
	ds_bpermute_b32 v112, v181, v63
	ds_bpermute_b32 v113, v181, v64
	ds_bpermute_b32 v120, v181, v65
	s_waitcnt lgkmcnt(0)
	v_cndmask_b32_e64 v123, v121, 0, s[0:1]
	v_cndmask_b32_e64 v122, v118, 0, s[0:1]
	v_cndmask_b32_e64 v125, v117, 0, s[0:1]
	v_cndmask_b32_e64 v124, v110, 0, s[0:1]
	v_cndmask_b32_e64 v127, 0, v112, s[2:3]
	v_cndmask_b32_e64 v126, 0, v105, s[2:3]
	v_cndmask_b32_e64 v129, 0, v120, s[2:3]
	v_cndmask_b32_e64 v128, 0, v113, s[2:3]
	s_waitcnt vmcnt(0)
; __device__ __forceinline__ unsigned cvt_pk_bf16(float lo, float hi) { f32x2_t f = {lo, hi}; bf16x2_t v = __builtin_convertvector(f, bf16x2_t); return __builtin_bit_cast(unsigned, v); }
; __device__ __forceinline__ float sigmoidf_(float x) { return __builtin_amdgcn_rcpf(1.0f + __expf(-x)); }
; #define SHI(lane, v, src) shfl_idx(lane, (v), (src))
;     __device__ __forceinline__ void operator()(const f32x4 (&acc)[2][2][4][2], const Unit& u, int wr, int wc, int fr, int fq) const {
;     ...
;             for (int q = 0; q < 8; ++q) {
;                 const int ai = q >> 2, m = q & 3;
;                 const f32x4 av = acc[ai][0][m][n], ag = acc[ai][1][m][n];
;                 f32x4 rv1, rv2, rg1, rg2;
; #pragma unroll
;                 for (int j = 0; j < 4; ++j) { rv1[j] = SHI(lane, av[j], src1); rv2[j] = SHI(lane, av[j], src2); rg1[j] = SHI(lane, ag[j], src1); rg2[j] = SHI(lane, ag[j], src2); }
;                 const f32x4 sv1 = fr >= 1 ? rv1 : pv1, sv2 = fr >= 2 ? rv2 : pv2, sg1 = fr >= 1 ? rg1 : pg1, sg2 = fr >= 2 ? rg2 : pg2;
;                 const f32x4 ov = wv[2] * av + wv[1] * sv1 + wv[0] * sv2;
;                 const f32x4 og = wg[2] * ag + wg[1] * sg1 + wg[0] * sg2;
;                 u32x2 w;
;                 w.x = cvt_pk_bf16(og[0] * sigmoidf_(og[0]) * ov[0], og[1] * sigmoidf_(og[1]) * ov[1]);
;                 w.y = cvt_pk_bf16(og[2] * sigmoidf_(og[2]) * ov[2], og[3] * sigmoidf_(og[3]) * ov[3]);
;                 *(u32x2*)(act + (size_t)(tok0 + q * 16) * DFF + ch) = w;
;                 if (q == 0 && fr < 2) { float* hp = halo + ((size_t)seg * 4 + fr) * NUP + ch; *(f32x4*)hp = av; *(f32x4*)(hp + DFF) = ag; }
;                 if (q == 7 && fr >= 14) { float* hp = halo + ((size_t)seg * 4 + (fr - 12)) * NUP + ch; *(f32x4*)hp = av; *(f32x4*)(hp + DFF) = ag; }
;                 pv1 = rv1; pv2 = rv2; pg1 = rg1; pg2 = rg2;
	v_pk_mul_f32 v[124:125], v[82:83], v[124:125]
	v_pk_mul_f32 v[122:123], v[84:85], v[122:123]
	v_pk_mul_f32 v[132:133], v[70:71], v[132:133]
	v_pk_mul_f32 v[130:131], v[72:73], v[130:131]
	v_pk_fma_f32 v[122:123], v[64:65], v[88:89], v[122:123]
	v_pk_fma_f32 v[124:125], v[62:63], v[86:87], v[124:125]
	v_pk_fma_f32 v[130:131], v[60:61], v[76:77], v[130:131]
	v_pk_fma_f32 v[132:133], v[58:59], v[74:75], v[132:133]
	v_pk_fma_f32 v[130:131], v[68:69], v[136:137], v[130:131]
	v_pk_fma_f32 v[132:133], v[66:67], v[134:135], v[132:133]
	v_mul_f32_e32 v136, 0xbfb8aa3b, v130
	v_mul_f32_e32 v134, 0xbfb8aa3b, v132
	v_mul_f32_e32 v135, 0xbfb8aa3b, v133
	v_mul_f32_e32 v137, 0xbfb8aa3b, v131
	v_exp_f32_e32 v134, v134
	v_exp_f32_e32 v135, v135
	v_exp_f32_e32 v136, v136
	v_exp_f32_e32 v137, v137
	v_add_f32_e32 v134, 1.0, v134
	v_add_f32_e32 v135, 1.0, v135
	v_add_f32_e32 v136, 1.0, v136
	v_add_f32_e32 v137, 1.0, v137
	v_rcp_f32_e32 v134, v134
	v_rcp_f32_e32 v135, v135
	v_rcp_f32_e32 v136, v136
	v_rcp_f32_e32 v137, v137
	v_pk_fma_f32 v[122:123], v[80:81], v[128:129], v[122:123]
	v_pk_fma_f32 v[124:125], v[78:79], v[126:127], v[124:125]
	v_pk_mul_f32 v[126:127], v[132:133], v[134:135]
	v_pk_mul_f32 v[128:129], v[130:131], v[136:137]
	v_pk_mul_f32 v[124:125], v[124:125], v[126:127]
	v_pk_mul_f32 v[122:123], v[122:123], v[128:129]
	v_cvt_pk_bf16_f32 v124, v124, v125
	v_cvt_pk_bf16_f32 v125, v122, v123
	global_store_dwordx2 v[174:175], v[124:125], off offset:8
	s_and_saveexec_b64 s[76:77], s[4:5]
	v_readlane_b32 s58, v254, 16
	s_mov_b32 s39, 0xb2a5705f
	s_mov_b32 s38, 0x42ce8ed0
	s_cbranch_execz .LBB0_626
	global_store_dwordx4 v[176:177], v[62:65], off offset:16
	s_nop 1
	v_add_co_u32_e32 v62, vcc, 0x5000, v176
	s_nop 1
	v_addc_co_u32_e32 v63, vcc, 0, v177, vcc
	global_store_dwordx4 v[62:63], v[58:61], off offset:2064
.LBB0_626:
	s_or_b64 exec, exec, s[76:77]
	ds_bpermute_b32 v122, v180, v54
	ds_bpermute_b32 v126, v180, v55
	ds_bpermute_b32 v130, v180, v56
	ds_bpermute_b32 v134, v180, v57
	ds_bpermute_b32 v124, v180, v50
	ds_bpermute_b32 v127, v181, v55
	ds_bpermute_b32 v128, v180, v51
	ds_bpermute_b32 v131, v181, v56
	ds_bpermute_b32 v132, v180, v52
	ds_bpermute_b32 v136, v180, v53
	ds_bpermute_b32 v123, v181, v54
	ds_bpermute_b32 v125, v181, v50
	ds_bpermute_b32 v129, v181, v51
	ds_bpermute_b32 v133, v181, v52
	ds_bpermute_b32 v137, v181, v53
	s_waitcnt lgkmcnt(0)
	v_cndmask_b32_e64 v59, v126, v117, s[0:1]
	v_cndmask_b32_e64 v58, v122, v110, s[0:1]
	v_cndmask_b32_e64 v61, v134, v121, s[0:1]
	v_cndmask_b32_e64 v60, v130, v118, s[0:1]
	v_cndmask_b32_e64 v63, v112, v127, s[2:3]
	v_cndmask_b32_e64 v64, v113, v131, s[2:3]
	v_cndmask_b32_e64 v113, v128, v108, s[0:1]
	v_cndmask_b32_e64 v112, v124, v103, s[0:1]
	v_cndmask_b32_e64 v119, v136, v119, s[0:1]
	v_cndmask_b32_e64 v118, v132, v111, s[0:1]
	v_pk_mul_f32 v[60:61], v[84:85], v[60:61]
	v_pk_mul_f32 v[58:59], v[82:83], v[58:59]
	ds_bpermute_b32 v135, v181, v57
	v_pk_fma_f32 v[54:55], v[54:55], v[86:87], v[58:59]
	v_pk_fma_f32 v[56:57], v[56:57], v[88:89], v[60:61]
	v_pk_mul_f32 v[58:59], v[72:73], v[118:119]
	v_pk_mul_f32 v[60:61], v[70:71], v[112:113]
	v_cndmask_b32_e64 v62, v105, v123, s[2:3]
	v_cndmask_b32_e64 v103, v104, v129, s[2:3]
	v_cndmask_b32_e64 v102, v102, v125, s[2:3]
	v_cndmask_b32_e64 v105, v116, v137, s[2:3]
	v_cndmask_b32_e64 v104, v109, v133, s[2:3]
	v_pk_fma_f32 v[50:51], v[50:51], v[74:75], v[60:61]
	v_pk_fma_f32 v[52:53], v[52:53], v[76:77], v[58:59]
	v_pk_fma_f32 v[50:51], v[66:67], v[102:103], v[50:51]
	v_pk_fma_f32 v[52:53], v[68:69], v[104:105], v[52:53]
	v_mul_f32_e32 v58, 0xbfb8aa3b, v50
	v_mul_f32_e32 v59, 0xbfb8aa3b, v51
	v_mul_f32_e32 v60, 0xbfb8aa3b, v52
	v_mul_f32_e32 v61, 0xbfb8aa3b, v53
	v_exp_f32_e32 v58, v58
	v_exp_f32_e32 v59, v59
	v_exp_f32_e32 v60, v60
	v_exp_f32_e32 v61, v61
	v_add_f32_e32 v58, 1.0, v58
	v_add_f32_e32 v59, 1.0, v59
	v_add_f32_e32 v60, 1.0, v60
	v_add_f32_e32 v61, 1.0, v61
	v_rcp_f32_e32 v58, v58
	v_rcp_f32_e32 v59, v59
	v_rcp_f32_e32 v60, v60
	v_rcp_f32_e32 v61, v61
	s_waitcnt lgkmcnt(0)
	v_cndmask_b32_e64 v65, v120, v135, s[2:3]
	v_pk_fma_f32 v[56:57], v[80:81], v[64:65], v[56:57]
	v_pk_fma_f32 v[54:55], v[78:79], v[62:63], v[54:55]
	v_pk_mul_f32 v[50:51], v[50:51], v[58:59]
	v_pk_mul_f32 v[52:53], v[52:53], v[60:61]
	v_pk_mul_f32 v[50:51], v[54:55], v[50:51]
	v_pk_mul_f32 v[52:53], v[56:57], v[52:53]
	v_cvt_pk_bf16_f32 v50, v50, v51
	v_cvt_pk_bf16_f32 v51, v52, v53
	ds_bpermute_b32 v102, v180, v46
	ds_bpermute_b32 v108, v180, v47
	ds_bpermute_b32 v112, v180, v48
	ds_bpermute_b32 v116, v180, v49
	global_store_dwordx2 v[114:115], v[50:51], off offset:8
	ds_bpermute_b32 v104, v180, v42
	ds_bpermute_b32 v110, v180, v43
	ds_bpermute_b32 v114, v180, v44
	ds_bpermute_b32 v118, v180, v45
	ds_bpermute_b32 v105, v181, v42
	ds_bpermute_b32 v111, v181, v43
	ds_bpermute_b32 v115, v181, v44
	ds_bpermute_b32 v119, v181, v45
	s_waitcnt lgkmcnt(0)
; __device__ __forceinline__ unsigned cvt_pk_bf16(float lo, float hi) { f32x2_t f = {lo, hi}; bf16x2_t v = __builtin_convertvector(f, bf16x2_t); return __builtin_bit_cast(unsigned, v); }
; __device__ __forceinline__ float sigmoidf_(float x) { return __builtin_amdgcn_rcpf(1.0f + __expf(-x)); }
; #define SHI(lane, v, src) shfl_idx(lane, (v), (src))
;     __device__ __forceinline__ void operator()(const f32x4 (&acc)[2][2][4][2], const Unit& u, int wr, int wc, int fr, int fq) const {
;     ...
;             for (int q = 0; q < 8; ++q) {
;                 const int ai = q >> 2, m = q & 3;
;                 const f32x4 av = acc[ai][0][m][n], ag = acc[ai][1][m][n];
;                 f32x4 rv1, rv2, rg1, rg2;
; #pragma unroll
;                 for (int j = 0; j < 4; ++j) { rv1[j] = SHI(lane, av[j], src1); rv2[j] = SHI(lane, av[j], src2); rg1[j] = SHI(lane, ag[j], src1); rg2[j] = SHI(lane, ag[j], src2); }
;                 const f32x4 sv1 = fr >= 1 ? rv1 : pv1, sv2 = fr >= 2 ? rv2 : pv2, sg1 = fr >= 1 ? rg1 : pg1, sg2 = fr >= 2 ? rg2 : pg2;
;                 const f32x4 ov = wv[2] * av + wv[1] * sv1 + wv[0] * sv2;
;                 const f32x4 og = wg[2] * ag + wg[1] * sg1 + wg[0] * sg2;
;                 u32x2 w;
;                 w.x = cvt_pk_bf16(og[0] * sigmoidf_(og[0]) * ov[0], og[1] * sigmoidf_(og[1]) * ov[1]);
;                 w.y = cvt_pk_bf16(og[2] * sigmoidf_(og[2]) * ov[2], og[3] * sigmoidf_(og[3]) * ov[3]);
;                 *(u32x2*)(act + (size_t)(tok0 + q * 16) * DFF + ch) = w;
;                 if (q == 0 && fr < 2) { float* hp = halo + ((size_t)seg * 4 + fr) * NUP + ch; *(f32x4*)hp = av; *(f32x4*)(hp + DFF) = ag; }
;                 if (q == 7 && fr >= 14) { float* hp = halo + ((size_t)seg * 4 + (fr - 12)) * NUP + ch; *(f32x4*)hp = av; *(f32x4*)(hp + DFF) = ag; }
;                 pv1 = rv1; pv2 = rv2; pg1 = rg1; pg2 = rg2;
	v_cndmask_b32_e64 v51, v108, v126, s[0:1]
	v_cndmask_b32_e64 v50, v102, v122, s[0:1]
	v_cndmask_b32_e64 v53, v116, v134, s[0:1]
	v_cndmask_b32_e64 v52, v112, v130, s[0:1]
	v_cndmask_b32_e64 v59, v110, v128, s[0:1]
	v_cndmask_b32_e64 v58, v104, v124, s[0:1]
	v_cndmask_b32_e64 v61, v118, v136, s[0:1]
	v_cndmask_b32_e64 v60, v114, v132, s[0:1]
	v_pk_mul_f32 v[52:53], v[84:85], v[52:53]
	v_pk_mul_f32 v[50:51], v[82:83], v[50:51]
	ds_bpermute_b32 v103, v181, v46
	ds_bpermute_b32 v109, v181, v47
	ds_bpermute_b32 v113, v181, v48
	ds_bpermute_b32 v117, v181, v49
	v_pk_fma_f32 v[46:47], v[46:47], v[86:87], v[50:51]
	v_pk_fma_f32 v[48:49], v[48:49], v[88:89], v[52:53]
	v_pk_mul_f32 v[50:51], v[72:73], v[60:61]
	v_pk_mul_f32 v[52:53], v[70:71], v[58:59]
	v_cndmask_b32_e64 v63, v129, v111, s[2:3]
	v_cndmask_b32_e64 v62, v125, v105, s[2:3]
	v_cndmask_b32_e64 v65, v137, v119, s[2:3]
	v_cndmask_b32_e64 v64, v133, v115, s[2:3]
	v_pk_fma_f32 v[42:43], v[42:43], v[74:75], v[52:53]
	v_pk_fma_f32 v[44:45], v[44:45], v[76:77], v[50:51]
	v_pk_fma_f32 v[42:43], v[66:67], v[62:63], v[42:43]
	v_pk_fma_f32 v[44:45], v[68:69], v[64:65], v[44:45]
	v_mul_f32_e32 v50, 0xbfb8aa3b, v42
	v_mul_f32_e32 v51, 0xbfb8aa3b, v43
	v_mul_f32_e32 v52, 0xbfb8aa3b, v44
	v_mul_f32_e32 v53, 0xbfb8aa3b, v45
	v_exp_f32_e32 v50, v50
	v_exp_f32_e32 v51, v51
	v_exp_f32_e32 v52, v52
	v_exp_f32_e32 v53, v53
	v_add_f32_e32 v50, 1.0, v50
	v_add_f32_e32 v51, 1.0, v51
	v_add_f32_e32 v52, 1.0, v52
	v_add_f32_e32 v53, 1.0, v53
	v_rcp_f32_e32 v50, v50
	v_rcp_f32_e32 v51, v51
	v_rcp_f32_e32 v52, v52
	v_rcp_f32_e32 v53, v53
	s_waitcnt lgkmcnt(0)
	v_cndmask_b32_e64 v55, v127, v109, s[2:3]
	v_cndmask_b32_e64 v54, v123, v103, s[2:3]
	v_cndmask_b32_e64 v57, v135, v117, s[2:3]
	v_cndmask_b32_e64 v56, v131, v113, s[2:3]
	v_pk_fma_f32 v[48:49], v[80:81], v[56:57], v[48:49]
	v_pk_fma_f32 v[46:47], v[78:79], v[54:55], v[46:47]
	v_pk_mul_f32 v[42:43], v[42:43], v[50:51]
	v_pk_mul_f32 v[44:45], v[44:45], v[52:53]
	v_pk_mul_f32 v[42:43], v[46:47], v[42:43]
	v_pk_mul_f32 v[44:45], v[48:49], v[44:45]
	v_cvt_pk_bf16_f32 v42, v42, v43
	v_cvt_pk_bf16_f32 v43, v44, v45
	global_store_dwordx2 v[106:107], v[42:43], off offset:8
	ds_bpermute_b32 v58, v180, v38
	ds_bpermute_b32 v62, v180, v39
	ds_bpermute_b32 v106, v180, v40
	ds_bpermute_b32 v122, v180, v41
	ds_bpermute_b32 v60, v180, v34
	ds_bpermute_b32 v64, v180, v35
	ds_bpermute_b32 v120, v180, v36
	ds_bpermute_b32 v124, v180, v37
	ds_bpermute_b32 v61, v181, v34
	ds_bpermute_b32 v65, v181, v35
	ds_bpermute_b32 v121, v181, v36
	ds_bpermute_b32 v125, v181, v37
	s_waitcnt lgkmcnt(0)
	v_cndmask_b32_e64 v43, v62, v108, s[0:1]
	v_cndmask_b32_e64 v42, v58, v102, s[0:1]
	v_cndmask_b32_e64 v45, v122, v116, s[0:1]
	v_cndmask_b32_e64 v44, v106, v112, s[0:1]
	v_cndmask_b32_e64 v51, v64, v110, s[0:1]
	v_cndmask_b32_e64 v50, v60, v104, s[0:1]
	v_cndmask_b32_e64 v53, v124, v118, s[0:1]
	v_cndmask_b32_e64 v52, v120, v114, s[0:1]
	v_pk_mul_f32 v[44:45], v[84:85], v[44:45]
	v_pk_mul_f32 v[42:43], v[82:83], v[42:43]
	ds_bpermute_b32 v59, v181, v38
	ds_bpermute_b32 v63, v181, v39
	ds_bpermute_b32 v107, v181, v40
	ds_bpermute_b32 v123, v181, v41
	v_pk_fma_f32 v[38:39], v[38:39], v[86:87], v[42:43]
	v_pk_fma_f32 v[40:41], v[40:41], v[88:89], v[44:45]
	v_pk_mul_f32 v[42:43], v[72:73], v[52:53]
	v_pk_mul_f32 v[44:45], v[70:71], v[50:51]
	v_cndmask_b32_e64 v55, v111, v65, s[2:3]
	v_cndmask_b32_e64 v54, v105, v61, s[2:3]
	v_cndmask_b32_e64 v57, v119, v125, s[2:3]
	v_cndmask_b32_e64 v56, v115, v121, s[2:3]
	v_pk_fma_f32 v[34:35], v[34:35], v[74:75], v[44:45]
	v_pk_fma_f32 v[36:37], v[36:37], v[76:77], v[42:43]
	v_pk_fma_f32 v[34:35], v[66:67], v[54:55], v[34:35]
	v_pk_fma_f32 v[36:37], v[68:69], v[56:57], v[36:37]
	v_mul_f32_e32 v42, 0xbfb8aa3b, v34
	v_mul_f32_e32 v43, 0xbfb8aa3b, v35
	v_mul_f32_e32 v44, 0xbfb8aa3b, v36
	v_mul_f32_e32 v45, 0xbfb8aa3b, v37
	v_exp_f32_e32 v42, v42
	v_exp_f32_e32 v43, v43
	v_exp_f32_e32 v44, v44
	v_exp_f32_e32 v45, v45
	v_add_f32_e32 v42, 1.0, v42
	v_add_f32_e32 v43, 1.0, v43
	v_add_f32_e32 v44, 1.0, v44
	v_add_f32_e32 v45, 1.0, v45
	v_rcp_f32_e32 v42, v42
	v_rcp_f32_e32 v43, v43
	v_rcp_f32_e32 v44, v44
	v_rcp_f32_e32 v45, v45
	s_waitcnt lgkmcnt(0)
	v_cndmask_b32_e64 v47, v109, v63, s[2:3]
	v_cndmask_b32_e64 v46, v103, v59, s[2:3]
	v_cndmask_b32_e64 v49, v117, v123, s[2:3]
	v_cndmask_b32_e64 v48, v113, v107, s[2:3]
	v_pk_fma_f32 v[40:41], v[80:81], v[48:49], v[40:41]
	v_pk_fma_f32 v[38:39], v[78:79], v[46:47], v[38:39]
	v_pk_mul_f32 v[34:35], v[34:35], v[42:43]
	v_pk_mul_f32 v[36:37], v[36:37], v[44:45]
	v_pk_mul_f32 v[34:35], v[38:39], v[34:35]
	v_pk_mul_f32 v[36:37], v[40:41], v[36:37]
	v_cvt_pk_bf16_f32 v34, v34, v35
	v_cvt_pk_bf16_f32 v35, v36, v37
	global_store_dwordx2 v[98:99], v[34:35], off offset:8
	ds_bpermute_b32 v50, v180, v30
	ds_bpermute_b32 v54, v180, v31
	ds_bpermute_b32 v98, v180, v32
	ds_bpermute_b32 v104, v180, v33
	ds_bpermute_b32 v52, v180, v26
	ds_bpermute_b32 v56, v180, v27
	ds_bpermute_b32 v102, v180, v28
	ds_bpermute_b32 v108, v180, v29
	ds_bpermute_b32 v53, v181, v26
	ds_bpermute_b32 v57, v181, v27
	ds_bpermute_b32 v103, v181, v28
	ds_bpermute_b32 v109, v181, v29
	s_waitcnt lgkmcnt(0)
; __device__ __forceinline__ unsigned cvt_pk_bf16(float lo, float hi) { f32x2_t f = {lo, hi}; bf16x2_t v = __builtin_convertvector(f, bf16x2_t); return __builtin_bit_cast(unsigned, v); }
; __device__ __forceinline__ float sigmoidf_(float x) { return __builtin_amdgcn_rcpf(1.0f + __expf(-x)); }
; #define SHI(lane, v, src) shfl_idx(lane, (v), (src))
;     __device__ __forceinline__ void operator()(const f32x4 (&acc)[2][2][4][2], const Unit& u, int wr, int wc, int fr, int fq) const {
;     ...
;             for (int q = 0; q < 8; ++q) {
;                 const int ai = q >> 2, m = q & 3;
;                 const f32x4 av = acc[ai][0][m][n], ag = acc[ai][1][m][n];
;                 f32x4 rv1, rv2, rg1, rg2;
; #pragma unroll
;                 for (int j = 0; j < 4; ++j) { rv1[j] = SHI(lane, av[j], src1); rv2[j] = SHI(lane, av[j], src2); rg1[j] = SHI(lane, ag[j], src1); rg2[j] = SHI(lane, ag[j], src2); }
;                 const f32x4 sv1 = fr >= 1 ? rv1 : pv1, sv2 = fr >= 2 ? rv2 : pv2, sg1 = fr >= 1 ? rg1 : pg1, sg2 = fr >= 2 ? rg2 : pg2;
;                 const f32x4 ov = wv[2] * av + wv[1] * sv1 + wv[0] * sv2;
;                 const f32x4 og = wg[2] * ag + wg[1] * sg1 + wg[0] * sg2;
;                 u32x2 w;
;                 w.x = cvt_pk_bf16(og[0] * sigmoidf_(og[0]) * ov[0], og[1] * sigmoidf_(og[1]) * ov[1]);
;                 w.y = cvt_pk_bf16(og[2] * sigmoidf_(og[2]) * ov[2], og[3] * sigmoidf_(og[3]) * ov[3]);
;                 *(u32x2*)(act + (size_t)(tok0 + q * 16) * DFF + ch) = w;
;                 if (q == 0 && fr < 2) { float* hp = halo + ((size_t)seg * 4 + fr) * NUP + ch; *(f32x4*)hp = av; *(f32x4*)(hp + DFF) = ag; }
;                 if (q == 7 && fr >= 14) { float* hp = halo + ((size_t)seg * 4 + (fr - 12)) * NUP + ch; *(f32x4*)hp = av; *(f32x4*)(hp + DFF) = ag; }
;                 pv1 = rv1; pv2 = rv2; pg1 = rg1; pg2 = rg2;
	v_cndmask_b32_e64 v35, v54, v62, s[0:1]
	v_cndmask_b32_e64 v34, v50, v58, s[0:1]
	v_cndmask_b32_e64 v37, v104, v122, s[0:1]
	v_cndmask_b32_e64 v36, v98, v106, s[0:1]
	v_cndmask_b32_e64 v43, v56, v64, s[0:1]
	v_cndmask_b32_e64 v42, v52, v60, s[0:1]
	v_cndmask_b32_e64 v45, v108, v124, s[0:1]
	v_cndmask_b32_e64 v44, v102, v120, s[0:1]
	v_pk_mul_f32 v[36:37], v[84:85], v[36:37]
	v_pk_mul_f32 v[34:35], v[82:83], v[34:35]
	ds_bpermute_b32 v51, v181, v30
	ds_bpermute_b32 v55, v181, v31
	ds_bpermute_b32 v99, v181, v32
	ds_bpermute_b32 v105, v181, v33
	v_pk_fma_f32 v[30:31], v[30:31], v[86:87], v[34:35]
	v_pk_fma_f32 v[32:33], v[32:33], v[88:89], v[36:37]
	v_pk_mul_f32 v[34:35], v[72:73], v[44:45]
	v_pk_mul_f32 v[36:37], v[70:71], v[42:43]
	v_cndmask_b32_e64 v47, v65, v57, s[2:3]
	v_cndmask_b32_e64 v46, v61, v53, s[2:3]
	v_cndmask_b32_e64 v49, v125, v109, s[2:3]
	v_cndmask_b32_e64 v48, v121, v103, s[2:3]
	v_pk_fma_f32 v[26:27], v[26:27], v[74:75], v[36:37]
	v_pk_fma_f32 v[28:29], v[28:29], v[76:77], v[34:35]
	v_pk_fma_f32 v[26:27], v[66:67], v[46:47], v[26:27]
	v_pk_fma_f32 v[28:29], v[68:69], v[48:49], v[28:29]
	v_mul_f32_e32 v34, 0xbfb8aa3b, v26
	v_mul_f32_e32 v35, 0xbfb8aa3b, v27
	v_mul_f32_e32 v36, 0xbfb8aa3b, v28
	v_mul_f32_e32 v37, 0xbfb8aa3b, v29
	v_exp_f32_e32 v34, v34
	v_exp_f32_e32 v35, v35
	v_exp_f32_e32 v36, v36
	v_exp_f32_e32 v37, v37
	v_add_f32_e32 v34, 1.0, v34
	v_add_f32_e32 v35, 1.0, v35
	v_add_f32_e32 v36, 1.0, v36
	v_add_f32_e32 v37, 1.0, v37
	v_rcp_f32_e32 v34, v34
	v_rcp_f32_e32 v35, v35
	v_rcp_f32_e32 v36, v36
	v_rcp_f32_e32 v37, v37
	ds_bpermute_b32 v42, v180, v22
	ds_bpermute_b32 v46, v180, v23
	ds_bpermute_b32 v58, v180, v24
	ds_bpermute_b32 v62, v180, v25
	s_waitcnt lgkmcnt(0)
	v_cndmask_b32_e64 v39, v63, v55, s[2:3]
	v_cndmask_b32_e64 v38, v59, v51, s[2:3]
	v_cndmask_b32_e64 v41, v123, v105, s[2:3]
	v_cndmask_b32_e64 v40, v107, v99, s[2:3]
	ds_bpermute_b32 v44, v180, v18
	ds_bpermute_b32 v48, v180, v19
	ds_bpermute_b32 v60, v180, v20
	ds_bpermute_b32 v64, v180, v21
	v_pk_fma_f32 v[32:33], v[80:81], v[40:41], v[32:33]
	v_pk_fma_f32 v[30:31], v[78:79], v[38:39], v[30:31]
	v_pk_mul_f32 v[26:27], v[26:27], v[34:35]
	v_pk_mul_f32 v[28:29], v[28:29], v[36:37]
	v_pk_mul_f32 v[26:27], v[30:31], v[26:27]
	v_pk_mul_f32 v[28:29], v[32:33], v[28:29]
	ds_bpermute_b32 v45, v181, v18
	ds_bpermute_b32 v49, v181, v19
	ds_bpermute_b32 v61, v181, v20
	ds_bpermute_b32 v65, v181, v21
	v_cvt_pk_bf16_f32 v26, v26, v27
	v_cvt_pk_bf16_f32 v27, v28, v29
	global_store_dwordx2 v[92:93], v[26:27], off offset:8
	v_cndmask_b32_e64 v27, v46, v54, s[0:1]
	v_cndmask_b32_e64 v26, v42, v50, s[0:1]
	v_cndmask_b32_e64 v29, v62, v104, s[0:1]
	v_cndmask_b32_e64 v28, v58, v98, s[0:1]
	s_waitcnt lgkmcnt(0)
	v_cndmask_b32_e64 v35, v48, v56, s[0:1]
	v_cndmask_b32_e64 v34, v44, v52, s[0:1]
	v_cndmask_b32_e64 v37, v64, v108, s[0:1]
	v_cndmask_b32_e64 v36, v60, v102, s[0:1]
	v_pk_mul_f32 v[28:29], v[84:85], v[28:29]
	v_pk_mul_f32 v[26:27], v[82:83], v[26:27]
	ds_bpermute_b32 v43, v181, v22
	ds_bpermute_b32 v47, v181, v23
	ds_bpermute_b32 v59, v181, v24
	ds_bpermute_b32 v63, v181, v25
	v_pk_fma_f32 v[22:23], v[22:23], v[86:87], v[26:27]
	v_pk_fma_f32 v[24:25], v[24:25], v[88:89], v[28:29]
	v_pk_mul_f32 v[26:27], v[72:73], v[36:37]
	v_pk_mul_f32 v[28:29], v[70:71], v[34:35]
	v_cndmask_b32_e64 v39, v57, v49, s[2:3]
	v_cndmask_b32_e64 v38, v53, v45, s[2:3]
	v_cndmask_b32_e64 v41, v109, v65, s[2:3]
	v_cndmask_b32_e64 v40, v103, v61, s[2:3]
	v_pk_fma_f32 v[18:19], v[18:19], v[74:75], v[28:29]
	v_pk_fma_f32 v[20:21], v[20:21], v[76:77], v[26:27]
	v_pk_fma_f32 v[18:19], v[66:67], v[38:39], v[18:19]
	v_pk_fma_f32 v[20:21], v[68:69], v[40:41], v[20:21]
	v_mul_f32_e32 v26, 0xbfb8aa3b, v18
	v_mul_f32_e32 v27, 0xbfb8aa3b, v19
	v_mul_f32_e32 v28, 0xbfb8aa3b, v20
	v_mul_f32_e32 v29, 0xbfb8aa3b, v21
	v_exp_f32_e32 v26, v26
	v_exp_f32_e32 v27, v27
	v_exp_f32_e32 v28, v28
	v_exp_f32_e32 v29, v29
	v_add_f32_e32 v26, 1.0, v26
	v_add_f32_e32 v27, 1.0, v27
	v_add_f32_e32 v28, 1.0, v28
	v_add_f32_e32 v29, 1.0, v29
	v_rcp_f32_e32 v26, v26
	v_rcp_f32_e32 v27, v27
	v_rcp_f32_e32 v28, v28
	v_rcp_f32_e32 v29, v29
	ds_bpermute_b32 v34, v180, v14
	ds_bpermute_b32 v38, v180, v15
	ds_bpermute_b32 v50, v180, v16
	ds_bpermute_b32 v54, v180, v17
	s_waitcnt lgkmcnt(0)
	v_cndmask_b32_e64 v31, v55, v47, s[2:3]
	v_cndmask_b32_e64 v30, v51, v43, s[2:3]
	v_cndmask_b32_e64 v33, v105, v63, s[2:3]
	v_cndmask_b32_e64 v32, v99, v59, s[2:3]
	ds_bpermute_b32 v36, v180, v10
	ds_bpermute_b32 v40, v180, v11
	ds_bpermute_b32 v52, v180, v12
	ds_bpermute_b32 v56, v180, v13
	v_pk_fma_f32 v[24:25], v[80:81], v[32:33], v[24:25]
	v_pk_fma_f32 v[22:23], v[78:79], v[30:31], v[22:23]
	v_pk_mul_f32 v[18:19], v[18:19], v[26:27]
	v_pk_mul_f32 v[20:21], v[20:21], v[28:29]
	v_pk_mul_f32 v[18:19], v[22:23], v[18:19]
	v_pk_mul_f32 v[20:21], v[24:25], v[20:21]
	ds_bpermute_b32 v37, v181, v10
	ds_bpermute_b32 v41, v181, v11
	ds_bpermute_b32 v53, v181, v12
	ds_bpermute_b32 v57, v181, v13
	v_cvt_pk_bf16_f32 v18, v18, v19
	v_cvt_pk_bf16_f32 v19, v20, v21
	global_store_dwordx2 v[94:95], v[18:19], off offset:8
	v_cndmask_b32_e64 v19, v38, v46, s[0:1]
	v_cndmask_b32_e64 v18, v34, v42, s[0:1]
	v_cndmask_b32_e64 v21, v54, v62, s[0:1]
	v_cndmask_b32_e64 v20, v50, v58, s[0:1]
	s_waitcnt lgkmcnt(0)
; __device__ __forceinline__ unsigned cvt_pk_bf16(float lo, float hi) { f32x2_t f = {lo, hi}; bf16x2_t v = __builtin_convertvector(f, bf16x2_t); return __builtin_bit_cast(unsigned, v); }
; __device__ __forceinline__ float sigmoidf_(float x) { return __builtin_amdgcn_rcpf(1.0f + __expf(-x)); }
; #define SHI(lane, v, src) shfl_idx(lane, (v), (src))
;     __device__ __forceinline__ void operator()(const f32x4 (&acc)[2][2][4][2], const Unit& u, int wr, int wc, int fr, int fq) const {
;     ...
;             for (int q = 0; q < 8; ++q) {
;                 const int ai = q >> 2, m = q & 3;
;                 const f32x4 av = acc[ai][0][m][n], ag = acc[ai][1][m][n];
;                 f32x4 rv1, rv2, rg1, rg2;
; #pragma unroll
;                 for (int j = 0; j < 4; ++j) { rv1[j] = SHI(lane, av[j], src1); rv2[j] = SHI(lane, av[j], src2); rg1[j] = SHI(lane, ag[j], src1); rg2[j] = SHI(lane, ag[j], src2); }
;                 const f32x4 sv1 = fr >= 1 ? rv1 : pv1, sv2 = fr >= 2 ? rv2 : pv2, sg1 = fr >= 1 ? rg1 : pg1, sg2 = fr >= 2 ? rg2 : pg2;
;                 const f32x4 ov = wv[2] * av + wv[1] * sv1 + wv[0] * sv2;
;                 const f32x4 og = wg[2] * ag + wg[1] * sg1 + wg[0] * sg2;
;                 u32x2 w;
;                 w.x = cvt_pk_bf16(og[0] * sigmoidf_(og[0]) * ov[0], og[1] * sigmoidf_(og[1]) * ov[1]);
;                 w.y = cvt_pk_bf16(og[2] * sigmoidf_(og[2]) * ov[2], og[3] * sigmoidf_(og[3]) * ov[3]);
;                 *(u32x2*)(act + (size_t)(tok0 + q * 16) * DFF + ch) = w;
;                 if (q == 0 && fr < 2) { float* hp = halo + ((size_t)seg * 4 + fr) * NUP + ch; *(f32x4*)hp = av; *(f32x4*)(hp + DFF) = ag; }
;                 if (q == 7 && fr >= 14) { float* hp = halo + ((size_t)seg * 4 + (fr - 12)) * NUP + ch; *(f32x4*)hp = av; *(f32x4*)(hp + DFF) = ag; }
;                 pv1 = rv1; pv2 = rv2; pg1 = rg1; pg2 = rg2;
;             }
	v_cndmask_b32_e64 v27, v40, v48, s[0:1]
	v_cndmask_b32_e64 v26, v36, v44, s[0:1]
	v_cndmask_b32_e64 v29, v56, v64, s[0:1]
	v_cndmask_b32_e64 v28, v52, v60, s[0:1]
	v_pk_mul_f32 v[20:21], v[84:85], v[20:21]
	v_pk_mul_f32 v[18:19], v[82:83], v[18:19]
	ds_bpermute_b32 v35, v181, v14
	ds_bpermute_b32 v39, v181, v15
	ds_bpermute_b32 v51, v181, v16
	ds_bpermute_b32 v55, v181, v17
	v_pk_fma_f32 v[14:15], v[14:15], v[86:87], v[18:19]
	v_pk_fma_f32 v[16:17], v[16:17], v[88:89], v[20:21]
	v_pk_mul_f32 v[18:19], v[72:73], v[28:29]
	v_pk_mul_f32 v[20:21], v[70:71], v[26:27]
	v_cndmask_b32_e64 v31, v49, v41, s[2:3]
	v_cndmask_b32_e64 v30, v45, v37, s[2:3]
	v_cndmask_b32_e64 v33, v65, v57, s[2:3]
	v_cndmask_b32_e64 v32, v61, v53, s[2:3]
	v_pk_fma_f32 v[10:11], v[10:11], v[74:75], v[20:21]
	v_pk_fma_f32 v[12:13], v[12:13], v[76:77], v[18:19]
	v_pk_fma_f32 v[10:11], v[66:67], v[30:31], v[10:11]
	v_pk_fma_f32 v[12:13], v[68:69], v[32:33], v[12:13]
	v_mul_f32_e32 v18, 0xbfb8aa3b, v10
	v_mul_f32_e32 v19, 0xbfb8aa3b, v11
	v_mul_f32_e32 v20, 0xbfb8aa3b, v12
	v_mul_f32_e32 v21, 0xbfb8aa3b, v13
	v_exp_f32_e32 v18, v18
	v_exp_f32_e32 v19, v19
	v_exp_f32_e32 v20, v20
	v_exp_f32_e32 v21, v21
	v_add_f32_e32 v18, 1.0, v18
	v_add_f32_e32 v19, 1.0, v19
	v_add_f32_e32 v20, 1.0, v20
	v_add_f32_e32 v21, 1.0, v21
	v_rcp_f32_e32 v18, v18
	v_rcp_f32_e32 v19, v19
	v_rcp_f32_e32 v20, v20
	v_rcp_f32_e32 v21, v21
	s_waitcnt lgkmcnt(0)
	v_cndmask_b32_e64 v23, v47, v39, s[2:3]
	v_cndmask_b32_e64 v22, v43, v35, s[2:3]
	v_cndmask_b32_e64 v25, v63, v55, s[2:3]
	v_cndmask_b32_e64 v24, v59, v51, s[2:3]
	v_pk_fma_f32 v[16:17], v[80:81], v[24:25], v[16:17]
	v_pk_fma_f32 v[14:15], v[78:79], v[22:23], v[14:15]
	v_pk_mul_f32 v[10:11], v[10:11], v[18:19]
	v_pk_mul_f32 v[12:13], v[12:13], v[20:21]
	v_pk_mul_f32 v[10:11], v[14:15], v[10:11]
	v_pk_mul_f32 v[12:13], v[16:17], v[12:13]
	v_cvt_pk_bf16_f32 v10, v10, v11
	v_cvt_pk_bf16_f32 v11, v12, v13
	global_store_dwordx2 v[96:97], v[10:11], off offset:8
	ds_bpermute_b32 v10, v180, v6
	ds_bpermute_b32 v11, v180, v7
	ds_bpermute_b32 v12, v180, v8
	ds_bpermute_b32 v13, v180, v9
	ds_bpermute_b32 v14, v181, v6
	ds_bpermute_b32 v18, v180, v2
	ds_bpermute_b32 v15, v181, v7
	ds_bpermute_b32 v19, v180, v3
	ds_bpermute_b32 v16, v181, v8
	ds_bpermute_b32 v20, v180, v4
	ds_bpermute_b32 v17, v181, v9
	ds_bpermute_b32 v21, v180, v5
	ds_bpermute_b32 v22, v181, v2
	ds_bpermute_b32 v23, v181, v3
	ds_bpermute_b32 v24, v181, v4
	ds_bpermute_b32 v25, v181, v5
	s_waitcnt lgkmcnt(0)
	v_cndmask_b32_e64 v11, v11, v38, s[0:1]
	v_cndmask_b32_e64 v10, v10, v34, s[0:1]
	v_cndmask_b32_e64 v13, v13, v54, s[0:1]
	v_cndmask_b32_e64 v12, v12, v50, s[0:1]
	v_pk_mul_f32 v[12:13], v[84:85], v[12:13]
	v_pk_mul_f32 v[10:11], v[82:83], v[10:11]
	v_cndmask_b32_e64 v15, v39, v15, s[2:3]
	v_cndmask_b32_e64 v14, v35, v14, s[2:3]
	v_cndmask_b32_e64 v17, v55, v17, s[2:3]
	v_cndmask_b32_e64 v16, v51, v16, s[2:3]
	v_cndmask_b32_e64 v19, v19, v40, s[0:1]
	v_cndmask_b32_e64 v18, v18, v36, s[0:1]
	v_cndmask_b32_e64 v21, v21, v56, s[0:1]
	v_cndmask_b32_e64 v20, v20, v52, s[0:1]
	v_pk_fma_f32 v[10:11], v[6:7], v[86:87], v[10:11]
	v_pk_fma_f32 v[12:13], v[8:9], v[88:89], v[12:13]
	v_pk_fma_f32 v[10:11], v[78:79], v[14:15], v[10:11]
	v_pk_fma_f32 v[12:13], v[80:81], v[16:17], v[12:13]
	v_pk_mul_f32 v[14:15], v[72:73], v[20:21]
	v_pk_mul_f32 v[16:17], v[70:71], v[18:19]
	v_cndmask_b32_e64 v23, v41, v23, s[2:3]
	v_cndmask_b32_e64 v22, v37, v22, s[2:3]
	v_cndmask_b32_e64 v25, v57, v25, s[2:3]
	v_cndmask_b32_e64 v24, v53, v24, s[2:3]
	v_pk_fma_f32 v[16:17], v[2:3], v[74:75], v[16:17]
	v_pk_fma_f32 v[14:15], v[4:5], v[76:77], v[14:15]
	v_pk_fma_f32 v[16:17], v[66:67], v[22:23], v[16:17]
	v_pk_fma_f32 v[14:15], v[68:69], v[24:25], v[14:15]
	v_mul_f32_e32 v18, 0xbfb8aa3b, v16
	v_mul_f32_e32 v19, 0xbfb8aa3b, v17
	v_mul_f32_e32 v20, 0xbfb8aa3b, v14
	v_mul_f32_e32 v21, 0xbfb8aa3b, v15
	v_exp_f32_e32 v18, v18
	v_exp_f32_e32 v19, v19
	v_exp_f32_e32 v20, v20
	v_exp_f32_e32 v21, v21
	v_add_f32_e32 v18, 1.0, v18
	v_add_f32_e32 v19, 1.0, v19
	v_add_f32_e32 v20, 1.0, v20
	v_add_f32_e32 v21, 1.0, v21
	v_rcp_f32_e32 v18, v18
	v_rcp_f32_e32 v19, v19
	v_rcp_f32_e32 v20, v20
	v_rcp_f32_e32 v21, v21
	v_pk_mul_f32 v[16:17], v[16:17], v[18:19]
	s_nop 0
	v_pk_mul_f32 v[10:11], v[10:11], v[16:17]
	v_pk_mul_f32 v[14:15], v[14:15], v[20:21]
	v_cvt_pk_bf16_f32 v10, v10, v11
	v_pk_mul_f32 v[12:13], v[12:13], v[14:15]
	s_nop 0
	v_cvt_pk_bf16_f32 v11, v12, v13
	global_store_dwordx2 v[100:101], v[10:11], off offset:8
	s_and_saveexec_b64 s[76:77], s[6:7]
	s_cbranch_execz .LBB0_615
	global_store_dwordx4 v[90:91], v[6:9], off offset:16
	s_nop 1
	v_add_co_u32_e32 v6, vcc, 0x5000, v90
	s_nop 1
	v_addc_co_u32_e32 v7, vcc, 0, v91, vcc
	global_store_dwordx4 v[6:7], v[2:5], off offset:2064
	s_branch .LBB0_615

; __device__ __forceinline__ bf16_t f2bf(float f) { return (bf16_t)(cvt_pk_bf16(f, 0.f) & 0xffffu); }
; __device__ __forceinline__ float sigmoidf_(float x) { return __builtin_amdgcn_rcpf(1.0f + __expf(-x)); }
; __device__ NOINL void halo_fix(unsigned char* ws, const float* cw, int wv) {
;     ...
;         const float* h0 = halo + (size_t)seg * 4 * NUP; const float* hm = halo + (size_t)(seg - 1) * 4 * NUP;
;         float v0, v1, v2, g0, g1, g2;
;         if (r == 0) { v2 = h0[c]; g2 = h0[DFF + c]; v1 = hm[3 * NUP + c]; g1 = hm[3 * NUP + DFF + c]; v0 = hm[2 * NUP + c]; g0 = hm[2 * NUP + DFF + c]; }
;         else { v2 = h0[NUP + c]; g2 = h0[NUP + DFF + c]; v1 = h0[c]; g1 = h0[DFF + c]; v0 = hm[3 * NUP + c]; g0 = hm[3 * NUP + DFF + c]; }
;         const float ov = cw[2 * NUP + c] * v2 + cw[NUP + c] * v1 + cw[c] * v0;
;         const float og = cw[2 * NUP + DFF + c] * g2 + cw[NUP + DFF + c] * g1 + cw[DFF + c] * g0;
;         act[(size_t)(seg * 128 + r) * DFF + c] = f2bf(og * sigmoidf_(og) * ov);
.LBB0_639:
	s_or_b64 exec, exec, s[18:19]
	global_load_dword v5, v[4:5], off
	s_nop 0
	global_load_dword v7, v[6:7], off
	s_nop 0
	global_load_dword v9, v[14:15], off
	global_load_dword v4, v[12:13], off
	global_load_dword v6, v[20:21], off
	global_load_dword v8, v[10:11], off
	v_lshl_add_u64 v[10:11], v[2:3], 2, s[16:17]
	v_add_co_u32_e32 v12, vcc, s22, v10
	s_mov_b32 s11, 0xb000
	s_nop 0
	v_addc_co_u32_e32 v13, vcc, 0, v11, vcc
	v_add_co_u32_e32 v14, vcc, s11, v10
	s_mov_b32 s11, 0x1b000
	s_nop 0
	v_addc_co_u32_e32 v15, vcc, 0, v11, vcc
	v_add_co_u32_e32 v18, vcc, s11, v10
	s_mov_b32 s11, 0x10000
	s_nop 0
	v_addc_co_u32_e32 v19, vcc, 0, v11, vcc
	global_load_dword v12, v[12:13], off
	s_nop 0
	global_load_dword v14, v[14:15], off
	s_nop 0
	global_load_dword v16, v[10:11], off
	global_load_dword v13, v[18:19], off offset:2048
	v_add_co_u32_e32 v18, vcc, s11, v10
	s_movk_i32 s11, 0x5000
	s_nop 0
	v_addc_co_u32_e32 v19, vcc, 0, v11, vcc
	global_load_dword v15, v[18:19], off offset:2048
	v_add_co_u32_e32 v10, vcc, s11, v10
	s_movk_i32 s11, 0x2c00
	s_nop 0
	v_addc_co_u32_e32 v11, vcc, 0, v11, vcc
	global_load_dword v17, v[10:11], off offset:2048
	s_waitcnt vmcnt(0) lgkmcnt(0)
	v_pk_mul_f32 v[6:7], v[6:7], v[14:15]
	s_nop 0
	v_pk_fma_f32 v[4:5], v[4:5], v[12:13], v[6:7]
	v_lshl_or_b32 v7, v22, 7, v23
	v_pk_fma_f32 v[4:5], v[8:9], v[16:17], v[4:5]
	s_nop 0
	v_mul_f32_e32 v6, 0xbfb8aa3b, v5
	v_exp_f32_e32 v6, v6
	s_nop 0
	v_add_f32_e32 v6, 1.0, v6
	v_rcp_f32_e32 v6, v6
	s_nop 0
	v_mul_f32_e32 v5, v5, v6
	v_mul_f32_e32 v4, v4, v5
	v_cvt_pk_bf16_f32 v6, v4, s0
	v_mov_b64_e32 v[4:5], s[4:5]
	v_mad_i64_i32 v[4:5], s[12:13], v7, s11, v[4:5]
	v_lshl_add_u64 v[2:3], v[2:3], 1, v[4:5]
	global_store_short v[2:3], v6, off

;     __device__ __forceinline__ void operator()(const f32x4 (&acc)[2][2][4][2], const Unit& u, int wr, int wc, int fr, int fq) const {
;     ...
;                     for (int m = 0; m < 4; ++m) xv[n][m] = *(const f32x4*)(xin + (size_t)(row0 + ai * HALF + m * 16) * DM + col0 + bj * HALF + n * 16);
; #pragma unroll
;                 for (int n = 0; n < 2; ++n) {
;                     const int cofs = bj * HALF + n * 16;
;                     const f32x4 g4 = *(const f32x4*)(gv + cofs) + 1.0f;
;                     f32x4 lg = {1.f, 1.f, 1.f, 1.f}, lb = {0.f, 0.f, 0.f, 0.f};
;                     if (stats) { lg = *(const f32x4*)(lng + col0 + cofs); lb = *(const f32x4*)(lnb + col0 + cofs); }
; #pragma unroll
;                     for (int m = 0; m < 4; ++m) { const f32x4 x = (xv[n][m] - mu[m]) * rs[m] * lg + lb;
;                         *(f32x4*)(out + (size_t)(row0 + ai * HALF + m * 16) * DM + col0 + cofs) = x * ALPHA + g4 * acc[ai][bj][m][n]; }
.LBB0_662:
	v_sub_f32_e32 v23, v57, v124
	v_sub_f32_e32 v22, v56, v124
	v_sub_f32_e32 v25, v55, v124
	v_sub_f32_e32 v24, v54, v124
	v_mov_b32_e32 v26, v120
	v_mov_b32_e32 v27, v120
	v_pk_mul_f32 v[24:25], v[100:101], v[24:25]
	v_pk_mul_f32 v[22:23], v[26:27], v[22:23]
	s_waitcnt vmcnt(0) lgkmcnt(0)
	v_pk_fma_f32 v[24:25], v[24:25], v[34:35], v[38:39]
	v_pk_fma_f32 v[22:23], v[22:23], v[36:37], v[40:41]
	v_pk_add_f32 v[20:21], v[20:21], 1.0 op_sel_hi:[1,0]
	v_pk_add_f32 v[18:19], v[18:19], 1.0 op_sel_hi:[1,0]
	v_pk_mul_f32 v[24:25], v[24:25], s[64:65] op_sel_hi:[1,0]
	v_pk_mul_f32 v[22:23], v[22:23], s[64:65] op_sel_hi:[1,0]
	v_pk_fma_f32 v[14:15], v[14:15], v[18:19], v[24:25]
	v_pk_fma_f32 v[16:17], v[16:17], v[20:21], v[22:23]
	global_store_dwordx4 v[112:113], v[14:17], off offset:576
	v_mov_b32_e32 v120, v121
	s_and_b64 vcc, exec, s[0:1]
	v_sub_f32_e32 v15, v53, v1
	v_sub_f32_e32 v14, v52, v1
	v_sub_f32_e32 v17, v51, v1
	v_sub_f32_e32 v16, v50, v1
	v_pk_mul_f32 v[16:17], v[98:99], v[16:17]
	v_pk_mul_f32 v[14:15], v[120:121], v[14:15]
	v_pk_fma_f32 v[16:17], v[16:17], v[34:35], v[38:39]
	v_pk_fma_f32 v[14:15], v[14:15], v[36:37], v[40:41]
	v_pk_mul_f32 v[16:17], v[16:17], s[64:65] op_sel_hi:[1,0]
	v_pk_mul_f32 v[14:15], v[14:15], s[64:65] op_sel_hi:[1,0]
	v_pk_fma_f32 v[10:11], v[10:11], v[18:19], v[16:17]
	v_pk_fma_f32 v[12:13], v[12:13], v[20:21], v[14:15]
	global_store_dwordx4 v[108:109], v[10:13], off offset:576
	v_mov_b32_e32 v14, v122
	v_mov_b32_e32 v15, v122
	v_sub_f32_e32 v11, v49, v66
	v_sub_f32_e32 v10, v48, v66
	v_sub_f32_e32 v13, v47, v66
	v_sub_f32_e32 v12, v46, v66
	v_pk_mul_f32 v[12:13], v[96:97], v[12:13]
	v_pk_mul_f32 v[10:11], v[14:15], v[10:11]
	v_pk_fma_f32 v[12:13], v[12:13], v[34:35], v[38:39]
	v_pk_fma_f32 v[10:11], v[10:11], v[36:37], v[40:41]
	v_pk_mul_f32 v[12:13], v[12:13], s[64:65] op_sel_hi:[1,0]
	v_pk_mul_f32 v[10:11], v[10:11], s[64:65] op_sel_hi:[1,0]
	v_pk_fma_f32 v[6:7], v[6:7], v[18:19], v[12:13]
	v_pk_fma_f32 v[8:9], v[8:9], v[20:21], v[10:11]
	global_store_dwordx4 v[104:105], v[6:9], off offset:576
	v_mov_b32_e32 v122, v123
	s_mov_b32 s63, s56
	v_sub_f32_e32 v7, v45, v67
	v_sub_f32_e32 v6, v44, v67
	v_sub_f32_e32 v9, v43, v67
	v_sub_f32_e32 v8, v42, v67
	v_pk_mul_f32 v[8:9], v[94:95], v[8:9]
	v_pk_mul_f32 v[6:7], v[122:123], v[6:7]
	v_pk_fma_f32 v[8:9], v[8:9], v[34:35], v[38:39]
	v_pk_fma_f32 v[6:7], v[6:7], v[36:37], v[40:41]
	v_pk_mul_f32 v[8:9], v[8:9], s[64:65] op_sel_hi:[1,0]
	v_pk_mul_f32 v[6:7], v[6:7], s[64:65] op_sel_hi:[1,0]
	v_pk_fma_f32 v[2:3], v[2:3], v[18:19], v[8:9]
	v_pk_fma_f32 v[4:5], v[4:5], v[20:21], v[6:7]
	global_store_dwordx4 v[92:93], v[2:5], off offset:576
	s_mov_b32 s62, s57
	s_mov_b64 s[26:27], s[4:5]
	s_mov_b64 s[24:25], s[22:23]
	s_cbranch_vccnz .LBB0_710

; #define PG8_STAGE(bufoff, gbase, voff) do { _Pragma("unroll") for (int _i = 0; _i < 2; ++_i) \
;         __builtin_amdgcn_global_load_lds((const unsigned*)((const char*)(gbase) + (voff)[_i]), (LAS unsigned*)(lds + (bufoff) + ldsw + _i * 8192), 16, 0, 0); } while (0)
; #define PG8_LDA(dst, b, h) do { _Pragma("unroll") for (int m = 0; m < 4; ++m) _Pragma("unroll") for (int k = 0; k < 2; ++k) dst[m][k] = *(const LAS bf16x8*)(lds + PG8_SA(b, h) + aoff + m * 2048 + k * 1024); } while (0)
; #define PG8_LDB(dst, b, h) do { _Pragma("unroll") for (int n = 0; n < 2; ++n) _Pragma("unroll") for (int k = 0; k < 2; ++k) dst[n][k] = *(const LAS bf16x8*)(lds + PG8_SB(b, h) + boff + n * 2048 + k * 1024); } while (0)
; #define PG8_WAIT_V(n) asm volatile("s_waitcnt vmcnt(" #n ")" ::: "memory")
; #define PG8_WAIT_L(n) asm volatile("s_waitcnt lgkmcnt(" #n ")" ::: "memory")
; template <class Epi, class Sched, bool AREMAP>
; __device__ __forceinline__ void gemm_phase(LAS unsigned char* lds, const Gemm g, const Sched& S, const Epi& E, int wv) {
;     ...
;         for (int t = 0; t < nt; t += 2) {
;             const bool last = (t == nt - 2);
;             const char* a1 = cA + (size_t)(t + 1) * kstep;
;             const char* a2 = last ? nA : cA + (size_t)(t + 2) * kstep; const char* b2 = last ? nB : cB + (size_t)(t + 2) * kstep;
;             const char* a3 = a2 + kstep; const char* b3 = b2 + kstep;
;             PG8_LDB(B0, 0, 0); PG8_SCHED; PG8_LDA(At, 0, 0); PG8_STAGE(PG8_SA(1, 1), a1 + hstepA, voffA);
;             PG8_WAIT_L(8); PG8_BAR; PG8_WAIT_L(0); PG8_MMA(0, 0, At, B0); PG8_BAR; PG8_SCHED;
;             PG8_LDB(B1, 0, 1); PG8_STAGE(PG8_SB(0, 0), b2, voffB);
;             PG8_BAR; PG8_WAIT_L(0); PG8_MMA(0, 1, At, B1); PG8_BAR;
;             PG8_LDA(At, 0, 1); PG8_STAGE(PG8_SA(0, 0), a2, voffA);
;             PG8_BAR; PG8_WAIT_L(0); PG8_MMA(1, 0, At, B0); PG8_BAR; PG8_SCHED;
;             PG8_STAGE(PG8_SB(0, 1), b2 + hstepB, voffB);
;             PG8_WAIT_V(6); PG8_BAR; PG8_MMA(1, 1, At, B1); PG8_BAR;
;             PG8_LDB(B0, 1, 0); PG8_SCHED; PG8_LDA(At, 1, 0); PG8_STAGE(PG8_SA(0, 1), a2 + hstepA, voffA);
;             PG8_WAIT_L(8); PG8_BAR; PG8_WAIT_L(0); PG8_MMA(0, 0, At, B0); PG8_BAR; PG8_SCHED;
;             PG8_LDB(B1, 1, 1); PG8_STAGE(PG8_SB(1, 0), b3, voffB);
;             PG8_BAR; PG8_WAIT_L(0); PG8_MMA(0, 1, At, B1); PG8_BAR;
.LBB0_674:
	s_add_u32 s2, s24, 0x100
	s_addc_u32 s3, s25, 0
	s_add_i32 s33, 0, 0x10000
	v_add_u32_e32 v1, s33, v250
	ds_read_b128 v[130:133], v1
	ds_read_b128 v[134:137], v1 offset:1024
	ds_read_b128 v[138:141], v1 offset:2048
	ds_read_b128 v[142:145], v1 offset:3072
	s_cmpk_eq_i32 s67, 0x54
	s_cselect_b32 s29, s23, s3
	s_cselect_b32 s28, s22, s2
	s_cselect_b32 s27, s5, s66
	s_cselect_b32 s26, s4, s65
	v_lshl_add_u64 v[178:179], s[24:25], 0, v[202:203]
	s_add_i32 m0, s35, 0xc000
	ds_read_b128 v[146:149], v252
	ds_read_b128 v[150:153], v252 offset:1024
	ds_read_b128 v[154:157], v252 offset:2048
	ds_read_b128 v[158:161], v252 offset:3072
	ds_read_b128 v[162:165], v252 offset:4096
	ds_read_b128 v[166:169], v252 offset:5120
	ds_read_b128 v[170:173], v252 offset:6144
	ds_read_b128 v[174:177], v252 offset:7168
	global_load_lds_dwordx4 v[178:179], off
	v_lshl_add_u64 v[178:179], s[24:25], 0, v[200:201]
	s_add_i32 m0, s35, 0xe000
	s_nop 0
	global_load_lds_dwordx4 v[178:179], off
	s_waitcnt lgkmcnt(8)
	s_barrier
	s_waitcnt lgkmcnt(0)
	s_setprio 1
	s_waitcnt lgkmcnt(0)
	v_mfma_f32_16x16x32_bf16 v[126:129], v[130:133], v[146:149], v[126:129]
	v_mfma_f32_16x16x32_bf16 v[110:113], v[138:141], v[146:149], v[110:113]
	v_mfma_f32_16x16x32_bf16 v[122:125], v[130:133], v[154:157], v[122:125]
	v_mfma_f32_16x16x32_bf16 v[106:109], v[138:141], v[154:157], v[106:109]
	v_mfma_f32_16x16x32_bf16 v[118:121], v[130:133], v[162:165], v[118:121]
	v_mfma_f32_16x16x32_bf16 v[102:105], v[138:141], v[162:165], v[102:105]
	v_mfma_f32_16x16x32_bf16 v[114:117], v[130:133], v[170:173], v[114:117]
	v_mfma_f32_16x16x32_bf16 v[98:101], v[138:141], v[170:173], v[98:101]
	v_mfma_f32_16x16x32_bf16 v[126:129], v[134:137], v[150:153], v[126:129]
	v_mfma_f32_16x16x32_bf16 v[110:113], v[142:145], v[150:153], v[110:113]
	v_mfma_f32_16x16x32_bf16 v[122:125], v[134:137], v[158:161], v[122:125]
	v_mfma_f32_16x16x32_bf16 v[106:109], v[142:145], v[158:161], v[106:109]
	v_mfma_f32_16x16x32_bf16 v[118:121], v[134:137], v[166:169], v[118:121]
	v_mfma_f32_16x16x32_bf16 v[102:105], v[142:145], v[166:169], v[102:105]
	v_mfma_f32_16x16x32_bf16 v[114:117], v[134:137], v[174:177], v[114:117]
	v_mfma_f32_16x16x32_bf16 v[98:101], v[142:145], v[174:177], v[98:101]
	s_setprio 0
	s_barrier
	s_add_i32 s38, 0, 0x14000
	s_add_i32 s24, s33, s34
	v_add_u32_e32 v1, s38, v250
	v_lshl_add_u64 v[186:187], s[26:27], 0, v[196:197]
	s_mov_b32 m0, s24
	ds_read_b128 v[178:181], v1
	ds_read_b128 v[182:185], v1 offset:1024
	ds_read_b128 v[192:195], v1 offset:2048
	ds_read_b128 v[204:207], v1 offset:3072
	global_load_lds_dwordx4 v[186:187], off
	v_lshl_add_u64 v[208:209], s[26:27], 0, v[198:199]
	s_add_i32 m0, s24, 0x2000
	s_nop 0
	global_load_lds_dwordx4 v[208:209], off
	s_barrier
	s_waitcnt lgkmcnt(0)
	s_setprio 1
	s_waitcnt lgkmcnt(0)
	v_mfma_f32_16x16x32_bf16 v[94:97], v[178:181], v[146:149], v[94:97]
	v_mfma_f32_16x16x32_bf16 v[78:81], v[192:195], v[146:149], v[78:81]
	v_mfma_f32_16x16x32_bf16 v[90:93], v[178:181], v[154:157], v[90:93]
	v_mfma_f32_16x16x32_bf16 v[74:77], v[192:195], v[154:157], v[74:77]
	v_mfma_f32_16x16x32_bf16 v[86:89], v[178:181], v[162:165], v[86:89]
	v_mfma_f32_16x16x32_bf16 v[70:73], v[192:195], v[162:165], v[70:73]
	v_mfma_f32_16x16x32_bf16 v[82:85], v[178:181], v[170:173], v[82:85]
	v_mfma_f32_16x16x32_bf16 v[66:69], v[192:195], v[170:173], v[66:69]
	v_mfma_f32_16x16x32_bf16 v[94:97], v[182:185], v[150:153], v[94:97]
	v_mfma_f32_16x16x32_bf16 v[78:81], v[204:207], v[150:153], v[78:81]
	v_mfma_f32_16x16x32_bf16 v[90:93], v[182:185], v[158:161], v[90:93]
	v_mfma_f32_16x16x32_bf16 v[74:77], v[204:207], v[158:161], v[74:77]
	v_mfma_f32_16x16x32_bf16 v[86:89], v[182:185], v[166:169], v[86:89]
	v_mfma_f32_16x16x32_bf16 v[70:73], v[204:207], v[166:169], v[70:73]
	v_mfma_f32_16x16x32_bf16 v[82:85], v[182:185], v[174:177], v[82:85]
	v_mfma_f32_16x16x32_bf16 v[66:69], v[204:207], v[174:177], v[66:69]
	s_setprio 0
	s_mov_b32 m0, s35
	v_lshl_add_u64 v[210:211], s[28:29], 0, v[196:197]
	s_barrier
	ds_read_b128 v[146:149], v252 offset:16384
	ds_read_b128 v[150:153], v252 offset:17408
	ds_read_b128 v[154:157], v252 offset:18432
	ds_read_b128 v[158:161], v252 offset:19456
	ds_read_b128 v[162:165], v252 offset:20480
	ds_read_b128 v[166:169], v252 offset:21504
	ds_read_b128 v[170:173], v252 offset:22528
	ds_read_b128 v[174:177], v252 offset:23552
	global_load_lds_dwordx4 v[210:211], off
	v_lshl_add_u64 v[212:213], s[28:29], 0, v[198:199]
	s_mov_b32 m0, s36
	s_nop 0
	global_load_lds_dwordx4 v[212:213], off
	s_barrier
	s_waitcnt lgkmcnt(0)
	s_setprio 1
	s_waitcnt lgkmcnt(0)
	v_mfma_f32_16x16x32_bf16 v[62:65], v[130:133], v[146:149], v[62:65]
	v_mfma_f32_16x16x32_bf16 v[46:49], v[138:141], v[146:149], v[46:49]
	v_mfma_f32_16x16x32_bf16 v[58:61], v[130:133], v[154:157], v[58:61]
	v_mfma_f32_16x16x32_bf16 v[42:45], v[138:141], v[154:157], v[42:45]
	v_mfma_f32_16x16x32_bf16 v[54:57], v[130:133], v[162:165], v[54:57]
	v_mfma_f32_16x16x32_bf16 v[38:41], v[138:141], v[162:165], v[38:41]
	v_mfma_f32_16x16x32_bf16 v[50:53], v[130:133], v[170:173], v[50:53]
	v_mfma_f32_16x16x32_bf16 v[34:37], v[138:141], v[170:173], v[34:37]
	v_mfma_f32_16x16x32_bf16 v[62:65], v[134:137], v[150:153], v[62:65]
	v_mfma_f32_16x16x32_bf16 v[46:49], v[142:145], v[150:153], v[46:49]
	v_mfma_f32_16x16x32_bf16 v[58:61], v[134:137], v[158:161], v[58:61]
	v_mfma_f32_16x16x32_bf16 v[42:45], v[142:145], v[158:161], v[42:45]
	v_mfma_f32_16x16x32_bf16 v[54:57], v[134:137], v[166:169], v[54:57]
	v_mfma_f32_16x16x32_bf16 v[38:41], v[142:145], v[166:169], v[38:41]
	v_mfma_f32_16x16x32_bf16 v[50:53], v[134:137], v[174:177], v[50:53]
	v_mfma_f32_16x16x32_bf16 v[34:37], v[142:145], v[174:177], v[34:37]
	s_setprio 0
	s_barrier
; #define PG8_STAGE(bufoff, gbase, voff) do { _Pragma("unroll") for (int _i = 0; _i < 2; ++_i) \
;         __builtin_amdgcn_global_load_lds((const unsigned*)((const char*)(gbase) + (voff)[_i]), (LAS unsigned*)(lds + (bufoff) + ldsw + _i * 8192), 16, 0, 0); } while (0)
; #define PG8_LDA(dst, b, h) do { _Pragma("unroll") for (int m = 0; m < 4; ++m) _Pragma("unroll") for (int k = 0; k < 2; ++k) dst[m][k] = *(const LAS bf16x8*)(lds + PG8_SA(b, h) + aoff + m * 2048 + k * 1024); } while (0)
; #define PG8_LDB(dst, b, h) do { _Pragma("unroll") for (int n = 0; n < 2; ++n) _Pragma("unroll") for (int k = 0; k < 2; ++k) dst[n][k] = *(const LAS bf16x8*)(lds + PG8_SB(b, h) + boff + n * 2048 + k * 1024); } while (0)
; #define PG8_MMA(ai, bj, At, Bt) do { __builtin_amdgcn_s_setprio(1); _Pragma("unroll") for (int m = 0; m < 4; ++m) _Pragma("unroll") for (int n = 0; n < 2; ++n) _Pragma("unroll") for (int k = 0; k < 2; ++k) \
;         acc[ai][bj][m][n] = __builtin_amdgcn_mfma_f32_16x16x32_bf16(Bt[n][k], At[m][k], acc[ai][bj][m][n], 0, 0, 0); __builtin_amdgcn_s_setprio(0); } while (0)
; #define PG8_WAIT_V(n) asm volatile("s_waitcnt vmcnt(" #n ")" ::: "memory")
; #define PG8_WAIT_L(n) asm volatile("s_waitcnt lgkmcnt(" #n ")" ::: "memory")
; #define PG8_BAR __builtin_amdgcn_s_barrier()
; #define PG8_SCHED __builtin_amdgcn_sched_barrier(0)
; template <class Epi, class Sched, bool AREMAP>
; __device__ __forceinline__ void gemm_phase(LAS unsigned char* lds, const Gemm g, const Sched& S, const Epi& E, int wv) {
;     ...
;             PG8_STAGE(PG8_SB(0, 1), b2 + hstepB, voffB);
;             PG8_WAIT_V(6); PG8_BAR; PG8_MMA(1, 1, At, B1); PG8_BAR;
;             PG8_LDB(B0, 1, 0); PG8_SCHED; PG8_LDA(At, 1, 0); PG8_STAGE(PG8_SA(0, 1), a2 + hstepA, voffA);
;             PG8_WAIT_L(8); PG8_BAR; PG8_WAIT_L(0); PG8_MMA(0, 0, At, B0); PG8_BAR; PG8_SCHED;
;             PG8_LDB(B1, 1, 1); PG8_STAGE(PG8_SB(1, 0), b3, voffB);
;             PG8_BAR; PG8_WAIT_L(0); PG8_MMA(0, 1, At, B1); PG8_BAR;
	s_add_u32 s24, s26, 0x160000
	s_addc_u32 s25, s27, 0
	s_add_i32 s33, s38, s34
	v_lshl_add_u64 v[130:131], s[24:25], 0, v[196:197]
	s_mov_b32 m0, s33
	s_nop 0
	global_load_lds_dwordx4 v[130:131], off
	v_lshl_add_u64 v[130:131], s[24:25], 0, v[198:199]
	s_add_i32 m0, s33, 0x2000
	s_nop 0
	global_load_lds_dwordx4 v[130:131], off
	s_waitcnt vmcnt(6)
	s_barrier
	s_setprio 1
	v_mfma_f32_16x16x32_bf16 v[30:33], v[178:181], v[146:149], v[30:33]
	v_mfma_f32_16x16x32_bf16 v[14:17], v[192:195], v[146:149], v[14:17]
	v_mfma_f32_16x16x32_bf16 v[26:29], v[178:181], v[154:157], v[26:29]
	v_mfma_f32_16x16x32_bf16 v[10:13], v[192:195], v[154:157], v[10:13]
	v_mfma_f32_16x16x32_bf16 v[22:25], v[178:181], v[162:165], v[22:25]
	v_mfma_f32_16x16x32_bf16 v[6:9], v[192:195], v[162:165], v[6:9]
	v_mfma_f32_16x16x32_bf16 v[18:21], v[178:181], v[170:173], v[18:21]
	v_mfma_f32_16x16x32_bf16 v[2:5], v[192:195], v[170:173], v[2:5]
	v_mfma_f32_16x16x32_bf16 v[30:33], v[182:185], v[150:153], v[30:33]
	v_mfma_f32_16x16x32_bf16 v[14:17], v[204:207], v[150:153], v[14:17]
	v_mfma_f32_16x16x32_bf16 v[26:29], v[182:185], v[158:161], v[26:29]
	v_mfma_f32_16x16x32_bf16 v[10:13], v[204:207], v[158:161], v[10:13]
	v_mfma_f32_16x16x32_bf16 v[22:25], v[182:185], v[166:169], v[22:25]
	v_mfma_f32_16x16x32_bf16 v[6:9], v[204:207], v[166:169], v[6:9]
	v_mfma_f32_16x16x32_bf16 v[18:21], v[182:185], v[174:177], v[18:21]
	v_mfma_f32_16x16x32_bf16 v[2:5], v[204:207], v[174:177], v[2:5]
	s_setprio 0
	s_add_i32 s33, 0, 0x18000
	v_add_u32_e32 v1, s33, v250
	s_barrier
	ds_read_b128 v[130:133], v1
	ds_read_b128 v[134:137], v1 offset:1024
	ds_read_b128 v[138:141], v1 offset:2048
	ds_read_b128 v[142:145], v1 offset:3072
	s_add_u32 s24, s28, 0x160000
	s_addc_u32 s25, s29, 0
	s_mov_b32 m0, s37
	v_lshl_add_u64 v[178:179], s[24:25], 0, v[196:197]
	ds_read_b128 v[146:149], v252 offset:32768
	ds_read_b128 v[150:153], v252 offset:33792
	ds_read_b128 v[154:157], v252 offset:34816
	ds_read_b128 v[158:161], v252 offset:35840
	ds_read_b128 v[162:165], v252 offset:36864
	ds_read_b128 v[166:169], v252 offset:37888
	ds_read_b128 v[170:173], v252 offset:38912
	ds_read_b128 v[174:177], v252 offset:39936
	global_load_lds_dwordx4 v[178:179], off
	v_lshl_add_u64 v[178:179], s[24:25], 0, v[198:199]
	s_mov_b32 m0, s41
	s_nop 0
	global_load_lds_dwordx4 v[178:179], off
	s_waitcnt lgkmcnt(8)
	s_barrier
	s_waitcnt lgkmcnt(0)
	s_setprio 1
	s_waitcnt lgkmcnt(0)
	v_mfma_f32_16x16x32_bf16 v[126:129], v[130:133], v[146:149], v[126:129]
	v_mfma_f32_16x16x32_bf16 v[110:113], v[138:141], v[146:149], v[110:113]
	v_mfma_f32_16x16x32_bf16 v[122:125], v[130:133], v[154:157], v[122:125]
	v_mfma_f32_16x16x32_bf16 v[106:109], v[138:141], v[154:157], v[106:109]
	v_mfma_f32_16x16x32_bf16 v[118:121], v[130:133], v[162:165], v[118:121]
	v_mfma_f32_16x16x32_bf16 v[102:105], v[138:141], v[162:165], v[102:105]
	v_mfma_f32_16x16x32_bf16 v[114:117], v[130:133], v[170:173], v[114:117]
	v_mfma_f32_16x16x32_bf16 v[98:101], v[138:141], v[170:173], v[98:101]
	v_mfma_f32_16x16x32_bf16 v[126:129], v[134:137], v[150:153], v[126:129]
	v_mfma_f32_16x16x32_bf16 v[110:113], v[142:145], v[150:153], v[110:113]
	v_mfma_f32_16x16x32_bf16 v[122:125], v[134:137], v[158:161], v[122:125]
	v_mfma_f32_16x16x32_bf16 v[106:109], v[142:145], v[158:161], v[106:109]
	v_mfma_f32_16x16x32_bf16 v[118:121], v[134:137], v[166:169], v[118:121]
	v_mfma_f32_16x16x32_bf16 v[102:105], v[142:145], v[166:169], v[102:105]
	v_mfma_f32_16x16x32_bf16 v[114:117], v[134:137], v[174:177], v[114:117]
	v_mfma_f32_16x16x32_bf16 v[98:101], v[142:145], v[174:177], v[98:101]
	s_setprio 0
	s_barrier
	s_add_i32 s28, 0, 0x1c000
	s_add_i32 s24, s33, s34
	v_add_u32_e32 v1, s28, v250
	v_lshl_add_u64 v[186:187], v[186:187], 0, s[86:87]
	s_mov_b32 m0, s24
	ds_read_b128 v[178:181], v1
	ds_read_b128 v[182:185], v1 offset:1024
	ds_read_b128 v[192:195], v1 offset:2048
	ds_read_b128 v[204:207], v1 offset:3072
	global_load_lds_dwordx4 v[186:187], off
	v_lshl_add_u64 v[186:187], v[208:209], 0, s[86:87]
	s_add_i32 m0, s24, 0x2000
	s_nop 0
	global_load_lds_dwordx4 v[186:187], off
	s_barrier
; #define PG8_STAGE(bufoff, gbase, voff) do { _Pragma("unroll") for (int _i = 0; _i < 2; ++_i) \
;         __builtin_amdgcn_global_load_lds((const unsigned*)((const char*)(gbase) + (voff)[_i]), (LAS unsigned*)(lds + (bufoff) + ldsw + _i * 8192), 16, 0, 0); } while (0)
; #define PG8_LDA(dst, b, h) do { _Pragma("unroll") for (int m = 0; m < 4; ++m) _Pragma("unroll") for (int k = 0; k < 2; ++k) dst[m][k] = *(const LAS bf16x8*)(lds + PG8_SA(b, h) + aoff + m * 2048 + k * 1024); } while (0)
; #define PG8_LDB(dst, b, h) do { _Pragma("unroll") for (int n = 0; n < 2; ++n) _Pragma("unroll") for (int k = 0; k < 2; ++k) dst[n][k] = *(const LAS bf16x8*)(lds + PG8_SB(b, h) + boff + n * 2048 + k * 1024); } while (0)
; #define PG8_MMA(ai, bj, At, Bt) do { __builtin_amdgcn_s_setprio(1); _Pragma("unroll") for (int m = 0; m < 4; ++m) _Pragma("unroll") for (int n = 0; n < 2; ++n) _Pragma("unroll") for (int k = 0; k < 2; ++k) \
;         acc[ai][bj][m][n] = __builtin_amdgcn_mfma_f32_16x16x32_bf16(Bt[n][k], At[m][k], acc[ai][bj][m][n], 0, 0, 0); __builtin_amdgcn_s_setprio(0); } while (0)
; #define PG8_WAIT_V(n) asm volatile("s_waitcnt vmcnt(" #n ")" ::: "memory")
; template <class Epi, class Sched, bool AREMAP>
; __device__ __forceinline__ void gemm_phase(LAS unsigned char* lds, const Gemm g, const Sched& S, const Epi& E, int wv) {
;     ...
;             PG8_WAIT_V(6); PG8_BAR; PG8_MMA(1, 1, At, B1); PG8_BAR;
;             PG8_LDB(B0, 1, 0); PG8_SCHED; PG8_LDA(At, 1, 0); PG8_STAGE(PG8_SA(0, 1), a2 + hstepA, voffA);
;             PG8_WAIT_L(8); PG8_BAR; PG8_WAIT_L(0); PG8_MMA(0, 0, At, B0); PG8_BAR; PG8_SCHED;
;             PG8_LDB(B1, 1, 1); PG8_STAGE(PG8_SB(1, 0), b3, voffB);
;             PG8_BAR; PG8_WAIT_L(0); PG8_MMA(0, 1, At, B1); PG8_BAR;
;             PG8_LDA(At, 1, 1); PG8_STAGE(PG8_SA(1, 0), a3, voffA);
;             PG8_BAR; PG8_WAIT_L(0); PG8_MMA(1, 0, At, B0); PG8_BAR; PG8_SCHED;
;             PG8_STAGE(PG8_SB(1, 1), b3 + hstepB, voffB);
;             PG8_WAIT_V(6); PG8_BAR; PG8_MMA(1, 1, At, B1); PG8_BAR;
;     __device__ __forceinline__ void operator()(const f32x4 (&acc)[2][2][4][2], const Unit& u, int wr, int wc, int fr, int fq) const {
;     ...
;             for (int m = 0; m < 4; ++m) { mu[m] = 0.f; rs[m] = 1.f;
;                 if (stats) { const float* sp = stats + (size_t)(row0 + ai * HALF + m * 16) * 2; mu[m] = sp[0]; rs[m] = sp[1]; } }
	s_waitcnt lgkmcnt(0)
	s_setprio 1
	s_waitcnt lgkmcnt(0)
	v_mfma_f32_16x16x32_bf16 v[94:97], v[178:181], v[146:149], v[94:97]
	v_mfma_f32_16x16x32_bf16 v[78:81], v[192:195], v[146:149], v[78:81]
	v_mfma_f32_16x16x32_bf16 v[90:93], v[178:181], v[154:157], v[90:93]
	v_mfma_f32_16x16x32_bf16 v[74:77], v[192:195], v[154:157], v[74:77]
	v_mfma_f32_16x16x32_bf16 v[86:89], v[178:181], v[162:165], v[86:89]
	v_mfma_f32_16x16x32_bf16 v[70:73], v[192:195], v[162:165], v[70:73]
	v_mfma_f32_16x16x32_bf16 v[82:85], v[178:181], v[170:173], v[82:85]
	v_mfma_f32_16x16x32_bf16 v[66:69], v[192:195], v[170:173], v[66:69]
	v_mfma_f32_16x16x32_bf16 v[94:97], v[182:185], v[150:153], v[94:97]
	v_mfma_f32_16x16x32_bf16 v[78:81], v[204:207], v[150:153], v[78:81]
	v_mfma_f32_16x16x32_bf16 v[90:93], v[182:185], v[158:161], v[90:93]
	v_mfma_f32_16x16x32_bf16 v[74:77], v[204:207], v[158:161], v[74:77]
	v_mfma_f32_16x16x32_bf16 v[86:89], v[182:185], v[166:169], v[86:89]
	v_mfma_f32_16x16x32_bf16 v[70:73], v[204:207], v[166:169], v[70:73]
	v_mfma_f32_16x16x32_bf16 v[82:85], v[182:185], v[174:177], v[82:85]
	v_mfma_f32_16x16x32_bf16 v[66:69], v[204:207], v[174:177], v[66:69]
	s_setprio 0
	s_mov_b32 m0, s46
	v_lshl_add_u64 v[186:187], v[210:211], 0, s[86:87]
	s_barrier
	ds_read_b128 v[146:149], v252 offset:49152
	ds_read_b128 v[150:153], v252 offset:50176
	ds_read_b128 v[154:157], v252 offset:51200
	ds_read_b128 v[158:161], v252 offset:52224
	ds_read_b128 v[162:165], v252 offset:53248
	ds_read_b128 v[166:169], v252 offset:54272
	ds_read_b128 v[170:173], v252 offset:55296
	ds_read_b128 v[174:177], v252 offset:56320
	global_load_lds_dwordx4 v[186:187], off
	v_lshl_add_u64 v[186:187], v[212:213], 0, s[86:87]
	s_mov_b32 m0, s47
	s_nop 0
	global_load_lds_dwordx4 v[186:187], off
	s_barrier
	s_waitcnt lgkmcnt(0)
	s_setprio 1
	s_waitcnt lgkmcnt(0)
	v_mfma_f32_16x16x32_bf16 v[62:65], v[130:133], v[146:149], v[62:65]
	v_mfma_f32_16x16x32_bf16 v[46:49], v[138:141], v[146:149], v[46:49]
	v_mfma_f32_16x16x32_bf16 v[58:61], v[130:133], v[154:157], v[58:61]
	v_mfma_f32_16x16x32_bf16 v[42:45], v[138:141], v[154:157], v[42:45]
	v_mfma_f32_16x16x32_bf16 v[54:57], v[130:133], v[162:165], v[54:57]
	v_mfma_f32_16x16x32_bf16 v[38:41], v[138:141], v[162:165], v[38:41]
	v_mfma_f32_16x16x32_bf16 v[50:53], v[130:133], v[170:173], v[50:53]
	v_mfma_f32_16x16x32_bf16 v[34:37], v[138:141], v[170:173], v[34:37]
	v_mfma_f32_16x16x32_bf16 v[62:65], v[134:137], v[150:153], v[62:65]
	v_mfma_f32_16x16x32_bf16 v[46:49], v[142:145], v[150:153], v[46:49]
	v_mfma_f32_16x16x32_bf16 v[58:61], v[134:137], v[158:161], v[58:61]
	v_mfma_f32_16x16x32_bf16 v[42:45], v[142:145], v[158:161], v[42:45]
	v_mfma_f32_16x16x32_bf16 v[54:57], v[134:137], v[166:169], v[54:57]
	v_mfma_f32_16x16x32_bf16 v[38:41], v[142:145], v[166:169], v[38:41]
	v_mfma_f32_16x16x32_bf16 v[50:53], v[134:137], v[174:177], v[50:53]
	v_mfma_f32_16x16x32_bf16 v[34:37], v[142:145], v[174:177], v[34:37]
	s_setprio 0
	s_barrier
	s_add_u32 s24, s26, 0x160080
	s_addc_u32 s25, s27, 0
	s_add_i32 s26, s28, s34
	v_lshl_add_u64 v[130:131], s[24:25], 0, v[196:197]
	s_mov_b32 m0, s26
	s_nop 0
	global_load_lds_dwordx4 v[130:131], off
	v_lshl_add_u64 v[130:131], s[24:25], 0, v[198:199]
	s_add_i32 m0, s26, 0x2000
	s_nop 0
	global_load_lds_dwordx4 v[130:131], off
	s_waitcnt vmcnt(6)
	s_barrier
	s_setprio 1
	v_mfma_f32_16x16x32_bf16 v[30:33], v[178:181], v[146:149], v[30:33]
	v_mfma_f32_16x16x32_bf16 v[14:17], v[192:195], v[146:149], v[14:17]
	v_mfma_f32_16x16x32_bf16 v[26:29], v[178:181], v[154:157], v[26:29]
	v_mfma_f32_16x16x32_bf16 v[10:13], v[192:195], v[154:157], v[10:13]
	v_mfma_f32_16x16x32_bf16 v[22:25], v[178:181], v[162:165], v[22:25]
	v_mfma_f32_16x16x32_bf16 v[6:9], v[192:195], v[162:165], v[6:9]
	v_mfma_f32_16x16x32_bf16 v[18:21], v[178:181], v[170:173], v[18:21]
	v_mfma_f32_16x16x32_bf16 v[2:5], v[192:195], v[170:173], v[2:5]
	v_mfma_f32_16x16x32_bf16 v[30:33], v[182:185], v[150:153], v[30:33]
	v_mfma_f32_16x16x32_bf16 v[14:17], v[204:207], v[150:153], v[14:17]
	v_mfma_f32_16x16x32_bf16 v[26:29], v[182:185], v[158:161], v[26:29]
	v_mfma_f32_16x16x32_bf16 v[10:13], v[204:207], v[158:161], v[10:13]
	v_mfma_f32_16x16x32_bf16 v[22:25], v[182:185], v[166:169], v[22:25]
	v_mfma_f32_16x16x32_bf16 v[6:9], v[204:207], v[166:169], v[6:9]
	v_mfma_f32_16x16x32_bf16 v[18:21], v[182:185], v[174:177], v[18:21]
	v_mfma_f32_16x16x32_bf16 v[2:5], v[204:207], v[174:177], v[2:5]
	s_setprio 0
	s_add_i32 s67, s67, 2
	s_add_u32 s65, s65, 0x100
	s_addc_u32 s66, s66, 0
	s_cmpk_gt_u32 s67, 0x55
	s_mov_b64 s[24:25], s[2:3]
	s_barrier
	s_cbranch_scc0 .LBB0_674
	v_lshl_add_u32 v212, s62, 8, v249
	v_cndmask_b32_e64 v1, 0, 1, s[20:21]
	v_mov_b32_e32 v216, 1.0
	v_cmp_ne_u32_e64 s[2:3], 1, v1
	s_andn2_b64 vcc, exec, s[20:21]
	v_ashrrev_i32_e32 v213, 31, v212
	s_cbranch_vccnz .LBB0_677
	v_lshl_add_u64 v[130:131], v[212:213], 3, s[18:19]
	global_load_dwordx2 v[134:135], v[130:131], off
	s_branch .LBB0_678

;     __device__ __forceinline__ void operator()(const f32x4 (&acc)[2][2][4][2], const Unit& u, int wr, int wc, int fr, int fq) const {
;     ...
;             for (int m = 0; m < 4; ++m) { mu[m] = 0.f; rs[m] = 1.f;
;                 if (stats) { const float* sp = stats + (size_t)(row0 + ai * HALF + m * 16) * 2; mu[m] = sp[0]; rs[m] = sp[1]; } }
.LBB0_678:
	v_or_b32_e32 v140, 16, v212
	s_mov_b32 s26, 1.0
	s_and_b64 vcc, exec, s[2:3]
	v_ashrrev_i32_e32 v141, 31, v140
	s_cbranch_vccnz .LBB0_680
	v_lshl_add_u64 v[130:131], v[140:141], 3, s[18:19]
	global_load_dwordx2 v[142:143], v[130:131], off
	s_waitcnt vmcnt(0) lgkmcnt(0)
	v_mov_b64_e32 v[138:139], v[136:137]
	v_mov_b64_e32 v[136:137], v[134:135]
	v_mov_b32_e32 v138, s71
	v_mov_b32_e32 v137, v142
	v_mov_b64_e32 v[130:131], v[136:137]
	v_mov_b64_e32 v[132:133], v[138:139]
	v_mov_b32_e32 v133, s71
	v_mov_b32_e32 v216, v143
	s_branch .LBB0_681

;     __device__ __forceinline__ void operator()(const f32x4 (&acc)[2][2][4][2], const Unit& u, int wr, int wc, int fr, int fq) const {
;     ...
;             for (int m = 0; m < 4; ++m) { mu[m] = 0.f; rs[m] = 1.f;
;                 if (stats) { const float* sp = stats + (size_t)(row0 + ai * HALF + m * 16) * 2; mu[m] = sp[0]; rs[m] = sp[1]; } }
; #pragma unroll
;             for (int bj = 0; bj < 2; ++bj) {
;                 f32x4 xv[2][4];
; #pragma unroll
;                 for (int n = 0; n < 2; ++n)
; #pragma unroll
;                     for (int m = 0; m < 4; ++m) xv[n][m] = *(const f32x4*)(xin + (size_t)(row0 + ai * HALF + m * 16) * DM + col0 + bj * HALF + n * 16);
; #pragma unroll
;                 for (int n = 0; n < 2; ++n) {
;                     const int cofs = bj * HALF + n * 16;
;                     const f32x4 g4 = *(const f32x4*)(gv + cofs) + 1.0f;
;                     f32x4 lg = {1.f, 1.f, 1.f, 1.f}, lb = {0.f, 0.f, 0.f, 0.f};
;                     if (stats) { lg = *(const f32x4*)(lng + col0 + cofs); lb = *(const f32x4*)(lnb + col0 + cofs); }
; #pragma unroll
;                     for (int m = 0; m < 4; ++m) { const f32x4 x = (xv[n][m] - mu[m]) * rs[m] * lg + lb;
;                         *(f32x4*)(out + (size_t)(row0 + ai * HALF + m * 16) * DM + col0 + cofs) = x * ALPHA + g4 * acc[ai][bj][m][n]; }
.LBB0_681:
	v_or_b32_e32 v142, 32, v212
	s_mov_b32 s38, 0x42ce8ed0
	v_mov_b32_e32 v218, 1.0
	s_and_b64 vcc, exec, s[2:3]
	v_ashrrev_i32_e32 v143, 31, v142
	v_mov_b32_e32 v220, 1.0
	s_cbranch_vccnz .LBB0_683
	v_lshl_add_u64 v[130:131], v[142:143], 3, s[18:19]
	global_load_dwordx2 v[144:145], v[130:131], off
	s_waitcnt vmcnt(0) lgkmcnt(0)
	v_mov_b32_e32 v138, v144
	v_mov_b64_e32 v[130:131], v[136:137]
	v_mov_b64_e32 v[132:133], v[138:139]
	v_mov_b32_e32 v133, s71
	v_mov_b32_e32 v220, v145
.LBB0_683:
	v_or_b32_e32 v144, 48, v212
	s_and_b64 vcc, exec, s[2:3]
	v_ashrrev_i32_e32 v145, 31, v144
	s_cbranch_vccnz .LBB0_685
	v_lshl_add_u64 v[130:131], v[144:145], 3, s[18:19]
	global_load_dwordx2 v[146:147], v[130:131], off
	s_waitcnt vmcnt(0) lgkmcnt(0)
	v_mov_b32_e32 v139, v146
	v_mov_b64_e32 v[130:131], v[136:137]
	v_mov_b64_e32 v[132:133], v[138:139]
	v_mov_b32_e32 v218, v147
.LBB0_685:
	v_lshl_or_b32 v136, s63, 8, v251
	s_ashr_i32 s24, s62, 3
	v_ashrrev_i32_e32 v137, 31, v136
	s_mul_hi_i32 s25, s24, 0xc000
	s_mul_i32 s24, s24, 0xc000
	v_lshlrev_b64 v[210:211], 2, v[136:137]
	s_add_u32 s24, s6, s24
	v_lshl_add_u64 v[214:215], s[8:9], 0, v[210:211]
	v_lshlrev_b64 v[234:235], 13, v[212:213]
	s_addc_u32 s25, s7, s25
	v_lshl_add_u64 v[224:225], v[214:215], 0, v[234:235]
	v_lshlrev_b64 v[232:233], 13, v[140:141]
	v_lshlrev_b64 v[142:143], 13, v[142:143]
	v_lshlrev_b64 v[138:139], 13, v[144:145]
	v_lshl_add_u64 v[204:205], s[24:25], 0, v[210:211]
	v_lshl_add_u64 v[226:227], v[214:215], 0, v[232:233]
	v_lshl_add_u64 v[228:229], v[214:215], 0, v[142:143]
	v_lshl_add_u64 v[230:231], v[214:215], 0, v[138:139]
	global_load_dwordx4 v[180:183], v[224:225], off
	global_load_dwordx4 v[156:159], v[224:225], off offset:64
	global_load_dwordx4 v[176:179], v[226:227], off
	global_load_dwordx4 v[152:155], v[226:227], off offset:64
	global_load_dwordx4 v[172:175], v[228:229], off
	global_load_dwordx4 v[148:151], v[228:229], off offset:64
	global_load_dwordx4 v[160:163], v[230:231], off
	global_load_dwordx4 v[144:147], v[230:231], off offset:64
	global_load_dwordx4 v[184:187], v[204:205], off
	v_mov_b32_e32 v140, 0
	v_mov_b32_e32 v136, 1.0
	s_and_b64 vcc, exec, s[2:3]
	v_lshl_add_u64 v[206:207], s[68:69], 0, v[210:211]
	v_lshl_add_u64 v[208:209], s[72:73], 0, v[210:211]
	v_mov_b32_e32 v164, 1.0
	v_mov_b32_e32 v165, 1.0
	v_mov_b32_e32 v166, 1.0
	v_mov_b32_e32 v167, 1.0
	v_mov_b32_e32 v168, 0
	v_mov_b32_e32 v169, 0
	v_mov_b32_e32 v170, 0
	v_mov_b32_e32 v171, 0
	s_cbranch_vccnz .LBB0_687
	global_load_dwordx4 v[164:167], v[206:207], off
	global_load_dwordx4 v[168:171], v[208:209], off
.LBB0_687:
	v_mov_b32_e32 v222, v135
	v_mov_b32_e32 v223, v216
	s_waitcnt vmcnt(0) lgkmcnt(0)
	v_sub_f32_e32 v181, v181, v130
	v_sub_f32_e32 v180, v180, v130
	v_sub_f32_e32 v183, v183, v130
	v_sub_f32_e32 v182, v182, v130
	v_pk_mul_f32 v[180:181], v[222:223], v[180:181] op_sel_hi:[0,1]
	v_pk_mul_f32 v[182:183], v[222:223], v[182:183] op_sel_hi:[0,1]
	v_pk_fma_f32 v[180:181], v[180:181], v[164:165], v[168:169]
	v_pk_add_f32 v[184:185], v[184:185], 1.0 op_sel_hi:[1,0]
	v_pk_fma_f32 v[182:183], v[182:183], v[166:167], v[170:171]
	v_pk_mul_f32 v[180:181], v[180:181], s[64:65] op_sel_hi:[1,0]
	v_pk_add_f32 v[186:187], v[186:187], 1.0 op_sel_hi:[1,0]
	v_pk_mul_f32 v[182:183], v[182:183], s[64:65] op_sel_hi:[1,0]
	v_pk_fma_f32 v[126:127], v[126:127], v[184:185], v[180:181]
	v_lshl_add_u64 v[180:181], s[16:17], 0, v[234:235]
	v_pk_fma_f32 v[128:129], v[128:129], v[186:187], v[182:183]
	v_lshl_add_u64 v[180:181], v[180:181], 0, v[210:211]
	global_store_dwordx4 v[180:181], v[126:129], off
	s_and_b64 vcc, exec, s[2:3]
	v_mov_b32_e32 v137, 1.0
	v_sub_f32_e32 v127, v179, v131
	v_sub_f32_e32 v126, v178, v131
	v_sub_f32_e32 v129, v177, v131
	v_sub_f32_e32 v128, v176, v131
	v_pk_mul_f32 v[126:127], v[222:223], v[126:127] op_sel:[1,0]
	v_pk_mul_f32 v[128:129], v[222:223], v[128:129] op_sel:[1,0]
	v_pk_fma_f32 v[126:127], v[126:127], v[166:167], v[170:171]
	v_pk_fma_f32 v[128:129], v[128:129], v[164:165], v[168:169]
	v_pk_mul_f32 v[126:127], v[126:127], s[64:65] op_sel_hi:[1,0]
	v_pk_mul_f32 v[128:129], v[128:129], s[64:65] op_sel_hi:[1,0]
	v_pk_fma_f32 v[124:125], v[124:125], v[186:187], v[126:127]
	v_lshl_add_u64 v[126:127], s[16:17], 0, v[232:233]
	v_pk_fma_f32 v[122:123], v[122:123], v[184:185], v[128:129]
	v_lshl_add_u64 v[176:177], v[126:127], 0, v[210:211]
	global_store_dwordx4 v[176:177], v[122:125], off
	v_mov_b32_e32 v141, 0
	s_nop 0
	v_sub_f32_e32 v123, v175, v132
	v_sub_f32_e32 v122, v174, v132
	v_sub_f32_e32 v125, v173, v132
	v_sub_f32_e32 v124, v172, v132
	v_pk_mul_f32 v[122:123], v[220:221], v[122:123] op_sel_hi:[0,1]
	v_pk_mul_f32 v[124:125], v[220:221], v[124:125] op_sel_hi:[0,1]
	v_pk_fma_f32 v[122:123], v[122:123], v[166:167], v[170:171]
	v_pk_fma_f32 v[124:125], v[124:125], v[164:165], v[168:169]
	v_pk_mul_f32 v[122:123], v[122:123], s[64:65] op_sel_hi:[1,0]
	v_pk_mul_f32 v[124:125], v[124:125], s[64:65] op_sel_hi:[1,0]
	v_pk_fma_f32 v[120:121], v[120:121], v[186:187], v[122:123]
	v_lshl_add_u64 v[122:123], s[16:17], 0, v[142:143]
	v_pk_fma_f32 v[118:119], v[118:119], v[184:185], v[124:125]
	v_lshl_add_u64 v[172:173], v[122:123], 0, v[210:211]
	global_store_dwordx4 v[172:173], v[118:121], off
	v_mov_b32_e32 v142, 0
	v_mov_b32_e32 v143, 0
	v_sub_f32_e32 v119, v163, v133
	v_sub_f32_e32 v118, v162, v133
	v_sub_f32_e32 v121, v161, v133
	v_sub_f32_e32 v120, v160, v133
	v_pk_mul_f32 v[118:119], v[218:219], v[118:119] op_sel_hi:[0,1]
	v_pk_mul_f32 v[120:121], v[218:219], v[120:121] op_sel_hi:[0,1]
	v_pk_fma_f32 v[118:119], v[118:119], v[166:167], v[170:171]
	v_pk_fma_f32 v[120:121], v[120:121], v[164:165], v[168:169]
	v_pk_mul_f32 v[118:119], v[118:119], s[64:65] op_sel_hi:[1,0]
	v_pk_mul_f32 v[120:121], v[120:121], s[64:65] op_sel_hi:[1,0]
	v_pk_fma_f32 v[116:117], v[116:117], v[186:187], v[118:119]
	v_lshl_add_u64 v[118:119], s[16:17], 0, v[138:139]
	v_pk_fma_f32 v[114:115], v[114:115], v[184:185], v[120:121]
	v_lshl_add_u64 v[160:161], v[118:119], 0, v[210:211]
	global_store_dwordx4 v[160:161], v[114:117], off
	global_load_dwordx4 v[114:117], v[204:205], off offset:64
	v_mov_b32_e32 v138, 1.0
	v_mov_b32_e32 v139, 1.0
	s_cbranch_vccnz .LBB0_689
	global_load_dwordx4 v[136:139], v[206:207], off offset:64
	global_load_dwordx4 v[140:143], v[208:209], off offset:64

;     __device__ __forceinline__ void operator()(const f32x4 (&acc)[2][2][4][2], const Unit& u, int wr, int wc, int fr, int fq) const {
;     ...
;             for (int m = 0; m < 4; ++m) { mu[m] = 0.f; rs[m] = 1.f;
;                 if (stats) { const float* sp = stats + (size_t)(row0 + ai * HALF + m * 16) * 2; mu[m] = sp[0]; rs[m] = sp[1]; } }
;     ...
;                     for (int m = 0; m < 4; ++m) xv[n][m] = *(const f32x4*)(xin + (size_t)(row0 + ai * HALF + m * 16) * DM + col0 + bj * HALF + n * 16);
; #pragma unroll
;                 for (int n = 0; n < 2; ++n) {
;                     const int cofs = bj * HALF + n * 16;
;                     const f32x4 g4 = *(const f32x4*)(gv + cofs) + 1.0f;
;                     f32x4 lg = {1.f, 1.f, 1.f, 1.f}, lb = {0.f, 0.f, 0.f, 0.f};
;                     if (stats) { lg = *(const f32x4*)(lng + col0 + cofs); lb = *(const f32x4*)(lnb + col0 + cofs); }
; #pragma unroll
;                     for (int m = 0; m < 4; ++m) { const f32x4 x = (xv[n][m] - mu[m]) * rs[m] * lg + lb;
;                         *(f32x4*)(out + (size_t)(row0 + ai * HALF + m * 16) * DM + col0 + cofs) = x * ALPHA + g4 * acc[ai][bj][m][n]; }
.LBB0_693:
	v_sub_f32_e32 v89, v119, v130
	v_sub_f32_e32 v88, v118, v130
	v_sub_f32_e32 v87, v121, v130
	v_sub_f32_e32 v86, v120, v130
	v_pk_mul_f32 v[88:89], v[134:135], v[88:89]
	v_mov_b32_e32 v134, v222
	v_pk_mul_f32 v[86:87], v[134:135], v[86:87]
	s_waitcnt vmcnt(0) lgkmcnt(0)
	v_pk_fma_f32 v[88:89], v[88:89], v[98:99], v[102:103]
	v_pk_fma_f32 v[86:87], v[86:87], v[100:101], v[104:105]
	v_pk_add_f32 v[84:85], v[84:85], 1.0 op_sel_hi:[1,0]
	v_pk_add_f32 v[82:83], v[82:83], 1.0 op_sel_hi:[1,0]
	v_pk_mul_f32 v[88:89], v[88:89], s[64:65] op_sel_hi:[1,0]
	v_pk_mul_f32 v[86:87], v[86:87], s[64:65] op_sel_hi:[1,0]
	v_pk_fma_f32 v[78:79], v[78:79], v[82:83], v[88:89]
	v_pk_fma_f32 v[80:81], v[80:81], v[84:85], v[86:87]
	global_store_dwordx4 v[180:181], v[78:81], off offset:576
	v_mov_b32_e32 v124, s71
	v_mov_b32_e32 v120, s26
	v_sub_f32_e32 v81, v115, v131
	v_sub_f32_e32 v80, v114, v131
	v_sub_f32_e32 v79, v117, v131
	v_sub_f32_e32 v78, v116, v131
	v_pk_mul_f32 v[80:81], v[216:217], v[80:81]
	v_mov_b32_e32 v217, v223
	v_pk_mul_f32 v[78:79], v[216:217], v[78:79]
	v_pk_fma_f32 v[80:81], v[80:81], v[98:99], v[102:103]
	v_pk_fma_f32 v[78:79], v[78:79], v[100:101], v[104:105]
	v_pk_mul_f32 v[80:81], v[80:81], s[64:65] op_sel_hi:[1,0]
	v_pk_mul_f32 v[78:79], v[78:79], s[64:65] op_sel_hi:[1,0]
	v_pk_fma_f32 v[74:75], v[74:75], v[82:83], v[80:81]
	v_pk_fma_f32 v[76:77], v[76:77], v[84:85], v[78:79]
	global_store_dwordx4 v[176:177], v[74:77], off offset:576
	s_and_b64 vcc, exec, s[2:3]
	s_nop 0
	v_sub_f32_e32 v77, v111, v132
	v_sub_f32_e32 v76, v110, v132
	v_sub_f32_e32 v75, v113, v132
	v_sub_f32_e32 v74, v112, v132
	v_pk_mul_f32 v[76:77], v[220:221], v[76:77]
	v_mov_b32_e32 v221, v220
	v_pk_mul_f32 v[74:75], v[220:221], v[74:75]
	v_pk_fma_f32 v[76:77], v[76:77], v[98:99], v[102:103]
	v_pk_fma_f32 v[74:75], v[74:75], v[100:101], v[104:105]
	v_pk_mul_f32 v[76:77], v[76:77], s[64:65] op_sel_hi:[1,0]
	v_pk_mul_f32 v[74:75], v[74:75], s[64:65] op_sel_hi:[1,0]
	v_pk_fma_f32 v[70:71], v[70:71], v[82:83], v[76:77]
	v_pk_fma_f32 v[72:73], v[72:73], v[84:85], v[74:75]
	global_store_dwordx4 v[172:173], v[70:73], off offset:576
	s_nop 1
	v_sub_f32_e32 v73, v107, v133
	v_sub_f32_e32 v72, v106, v133
	v_sub_f32_e32 v71, v109, v133
	v_sub_f32_e32 v70, v108, v133
	v_pk_mul_f32 v[72:73], v[218:219], v[72:73]
	v_mov_b32_e32 v219, v218
	v_pk_mul_f32 v[70:71], v[218:219], v[70:71]
	v_pk_fma_f32 v[72:73], v[72:73], v[98:99], v[102:103]
	v_pk_fma_f32 v[70:71], v[70:71], v[100:101], v[104:105]
	v_pk_mul_f32 v[72:73], v[72:73], s[64:65] op_sel_hi:[1,0]
	v_pk_mul_f32 v[70:71], v[70:71], s[64:65] op_sel_hi:[1,0]
	v_pk_fma_f32 v[66:67], v[66:67], v[82:83], v[72:73]
	v_pk_fma_f32 v[68:69], v[68:69], v[84:85], v[70:71]
	global_store_dwordx4 v[160:161], v[66:69], off offset:576
	s_nop 1
	v_add_u32_e32 v68, 0x80, v212
	v_ashrrev_i32_e32 v69, 31, v68
	s_cbranch_vccnz .LBB0_695
	v_lshl_add_u64 v[66:67], v[68:69], 3, s[18:19]
	global_load_dwordx2 v[124:125], v[66:67], off
	s_waitcnt vmcnt(0) lgkmcnt(0)
	v_mov_b32_e32 v120, v125
.LBB0_695:
	s_and_b64 vcc, exec, s[2:3]
	s_cbranch_vccnz .LBB0_699
	v_lshl_add_u64 v[66:67], v[212:213], 3, s[18:19]
	global_load_dwordx2 v[66:67], v[66:67], off offset:1152
	s_waitcnt vmcnt(0) lgkmcnt(0)
	v_mov_b32_e32 v1, v66
	v_mov_b32_e32 v121, v67
	s_and_b64 vcc, exec, s[2:3]
	s_cbranch_vccnz .LBB0_700
.LBB0_697:
	v_lshl_add_u64 v[66:67], v[212:213], 3, s[18:19]
	global_load_dwordx2 v[66:67], v[66:67], off offset:1280
	s_waitcnt vmcnt(0) lgkmcnt(0)
	v_mov_b32_e32 v122, v67
	v_add_u32_e32 v70, 0xb0, v212
	s_and_b64 vcc, exec, s[2:3]
	v_ashrrev_i32_e32 v71, 31, v70
	s_cbranch_vccnz .LBB0_701
.LBB0_698:
	v_lshl_add_u64 v[72:73], v[70:71], 3, s[18:19]
	global_load_dwordx2 v[72:73], v[72:73], off
	s_waitcnt vmcnt(0) lgkmcnt(0)
	v_mov_b32_e32 v67, v72
	v_mov_b32_e32 v123, v73
	s_branch .LBB0_702

;     __device__ __forceinline__ void operator()(const f32x4 (&acc)[2][2][4][2], const Unit& u, int wr, int wc, int fr, int fq) const {
;     ...
;             for (int bj = 0; bj < 2; ++bj) {
;                 f32x4 xv[2][4];
; #pragma unroll
;                 for (int n = 0; n < 2; ++n)
; #pragma unroll
;                     for (int m = 0; m < 4; ++m) xv[n][m] = *(const f32x4*)(xin + (size_t)(row0 + ai * HALF + m * 16) * DM + col0 + bj * HALF + n * 16);
; #pragma unroll
;                 for (int n = 0; n < 2; ++n) {
;                     const int cofs = bj * HALF + n * 16;
;                     const f32x4 g4 = *(const f32x4*)(gv + cofs) + 1.0f;
;                     f32x4 lg = {1.f, 1.f, 1.f, 1.f}, lb = {0.f, 0.f, 0.f, 0.f};
;                     if (stats) { lg = *(const f32x4*)(lng + col0 + cofs); lb = *(const f32x4*)(lnb + col0 + cofs); }
; #pragma unroll
;                     for (int m = 0; m < 4; ++m) { const f32x4 x = (xv[n][m] - mu[m]) * rs[m] * lg + lb;
;                         *(f32x4*)(out + (size_t)(row0 + ai * HALF + m * 16) * DM + col0 + cofs) = x * ALPHA + g4 * acc[ai][bj][m][n]; }
.LBB0_702:
	v_lshlrev_b64 v[136:137], 13, v[68:69]
	v_lshlrev_b64 v[68:69], 13, v[212:213]
	s_mov_b64 s[24:25], 0x120000
	v_lshl_add_u64 v[134:135], v[68:69], 0, s[24:25]
	s_mov_b64 s[24:25], 0x140000
	v_lshl_add_u64 v[126:127], v[214:215], 0, v[136:137]
	v_lshl_add_u64 v[74:75], v[68:69], 0, s[24:25]
	v_lshlrev_b64 v[70:71], 13, v[70:71]
	v_lshl_add_u64 v[128:129], v[214:215], 0, v[134:135]
	v_lshl_add_u64 v[130:131], v[214:215], 0, v[74:75]
	v_lshl_add_u64 v[132:133], v[214:215], 0, v[70:71]
	global_load_dwordx4 v[112:115], v[126:127], off
	global_load_dwordx4 v[88:91], v[126:127], off offset:64
	global_load_dwordx4 v[108:111], v[128:129], off
	global_load_dwordx4 v[84:87], v[128:129], off offset:64
	global_load_dwordx4 v[104:107], v[130:131], off
	global_load_dwordx4 v[80:83], v[130:131], off offset:64
	global_load_dwordx4 v[96:99], v[132:133], off
	global_load_dwordx4 v[76:79], v[132:133], off offset:64
	global_load_dwordx4 v[116:119], v[204:205], off
	v_mov_b32_e32 v72, 0
	v_mov_b32_e32 v68, 1.0
	s_and_b64 vcc, exec, s[2:3]
	v_mov_b32_e32 v92, 1.0
	v_mov_b32_e32 v93, 1.0
	v_mov_b32_e32 v94, 1.0
	v_mov_b32_e32 v95, 1.0
	v_mov_b32_e32 v100, 0
	v_mov_b32_e32 v101, 0
	v_mov_b32_e32 v102, 0
	v_mov_b32_e32 v103, 0
	s_cbranch_vccnz .LBB0_704
	global_load_dwordx4 v[92:95], v[206:207], off
	global_load_dwordx4 v[100:103], v[208:209], off
.LBB0_704:
	s_waitcnt vmcnt(0) lgkmcnt(0)
	v_sub_f32_e32 v113, v113, v124
	v_sub_f32_e32 v112, v112, v124
	v_sub_f32_e32 v115, v115, v124
	v_sub_f32_e32 v114, v114, v124
	v_pk_mul_f32 v[112:113], v[120:121], v[112:113] op_sel_hi:[0,1]
	v_pk_mul_f32 v[114:115], v[120:121], v[114:115] op_sel_hi:[0,1]
	v_pk_fma_f32 v[112:113], v[112:113], v[92:93], v[100:101]
	v_pk_add_f32 v[116:117], v[116:117], 1.0 op_sel_hi:[1,0]
	v_pk_fma_f32 v[114:115], v[114:115], v[94:95], v[102:103]
	v_pk_mul_f32 v[112:113], v[112:113], s[64:65] op_sel_hi:[1,0]
	v_pk_add_f32 v[118:119], v[118:119], 1.0 op_sel_hi:[1,0]
	v_pk_mul_f32 v[114:115], v[114:115], s[64:65] op_sel_hi:[1,0]
	v_pk_fma_f32 v[62:63], v[62:63], v[116:117], v[112:113]
	v_lshl_add_u64 v[112:113], s[16:17], 0, v[136:137]
	v_pk_fma_f32 v[64:65], v[64:65], v[118:119], v[114:115]
	v_lshl_add_u64 v[112:113], v[112:113], 0, v[210:211]
	global_store_dwordx4 v[112:113], v[62:65], off
	s_and_b64 vcc, exec, s[2:3]
	v_mov_b32_e32 v69, 1.0
	v_sub_f32_e32 v63, v111, v1
	v_sub_f32_e32 v62, v110, v1
	v_sub_f32_e32 v65, v109, v1
	v_sub_f32_e32 v64, v108, v1
	v_pk_mul_f32 v[62:63], v[120:121], v[62:63] op_sel:[1,0]
	v_pk_mul_f32 v[64:65], v[120:121], v[64:65] op_sel:[1,0]
	v_pk_fma_f32 v[62:63], v[62:63], v[94:95], v[102:103]
	v_pk_fma_f32 v[64:65], v[64:65], v[92:93], v[100:101]
	v_pk_mul_f32 v[62:63], v[62:63], s[64:65] op_sel_hi:[1,0]
	v_pk_mul_f32 v[64:65], v[64:65], s[64:65] op_sel_hi:[1,0]
	v_pk_fma_f32 v[60:61], v[60:61], v[118:119], v[62:63]
	v_lshl_add_u64 v[62:63], s[16:17], 0, v[134:135]
	v_pk_fma_f32 v[58:59], v[58:59], v[116:117], v[64:65]
	v_lshl_add_u64 v[108:109], v[62:63], 0, v[210:211]
	global_store_dwordx4 v[108:109], v[58:61], off
	v_mov_b32_e32 v73, 0
	s_nop 0
	v_sub_f32_e32 v59, v107, v66
	v_sub_f32_e32 v58, v106, v66
	v_sub_f32_e32 v61, v105, v66
	v_sub_f32_e32 v60, v104, v66
	v_pk_mul_f32 v[58:59], v[122:123], v[58:59] op_sel_hi:[0,1]
	v_pk_mul_f32 v[60:61], v[122:123], v[60:61] op_sel_hi:[0,1]
	v_pk_fma_f32 v[58:59], v[58:59], v[94:95], v[102:103]
	v_pk_fma_f32 v[60:61], v[60:61], v[92:93], v[100:101]
	v_pk_mul_f32 v[58:59], v[58:59], s[64:65] op_sel_hi:[1,0]
	v_pk_mul_f32 v[60:61], v[60:61], s[64:65] op_sel_hi:[1,0]
	v_pk_fma_f32 v[56:57], v[56:57], v[118:119], v[58:59]
	v_lshl_add_u64 v[58:59], s[16:17], 0, v[74:75]
	v_pk_fma_f32 v[54:55], v[54:55], v[116:117], v[60:61]
	v_lshl_add_u64 v[104:105], v[58:59], 0, v[210:211]
	global_store_dwordx4 v[104:105], v[54:57], off
	v_mov_b32_e32 v58, v123
	v_mov_b32_e32 v74, 0
	v_sub_f32_e32 v55, v99, v67
	v_sub_f32_e32 v54, v98, v67
	v_sub_f32_e32 v57, v97, v67
	v_sub_f32_e32 v56, v96, v67
	v_pk_mul_f32 v[54:55], v[58:59], v[54:55] op_sel_hi:[0,1]
	v_pk_mul_f32 v[56:57], v[58:59], v[56:57] op_sel_hi:[0,1]
	v_pk_fma_f32 v[54:55], v[54:55], v[94:95], v[102:103]
	v_pk_fma_f32 v[56:57], v[56:57], v[92:93], v[100:101]
	v_pk_mul_f32 v[54:55], v[54:55], s[64:65] op_sel_hi:[1,0]
	v_pk_mul_f32 v[56:57], v[56:57], s[64:65] op_sel_hi:[1,0]
	v_pk_fma_f32 v[52:53], v[52:53], v[118:119], v[54:55]
	v_lshl_add_u64 v[54:55], s[16:17], 0, v[70:71]
	v_pk_fma_f32 v[50:51], v[50:51], v[116:117], v[56:57]
	v_lshl_add_u64 v[92:93], v[54:55], 0, v[210:211]
	global_store_dwordx4 v[92:93], v[50:53], off
	global_load_dwordx4 v[50:53], v[204:205], off offset:64
	v_mov_b32_e32 v70, 1.0
	v_mov_b32_e32 v71, 1.0
	v_mov_b32_e32 v75, 0
	s_cbranch_vccnz .LBB0_706
	global_load_dwordx4 v[68:71], v[206:207], off offset:64
	global_load_dwordx4 v[72:75], v[208:209], off offset:64

; template <bool DO_LN, bool DO_H, bool DO_GATES, bool WRITE_X> ...
;     ...
;         for (int i = 0; i < 8; ++i) {
;             f32x4 g4 = {1.f, 1.f, 1.f, 1.f}, b4 = {0.f, 0.f, 0.f, 0.f};
;             if (DO_LN) { g4 = *(const f32x4*)(lng + lane * 4 + i * 256); b4 = *(const f32x4*)(lnb + lane * 4 + i * 256); }
;             if (DO_H) { const f32x4 sc = *(const f32x4*)(mb + sc_idx * 2048 + i * 256) + 1.0f, sh = *(const f32x4*)(mb + sh_idx * 2048 + i * 256);
;                 PA[i] = g4 * sc; PB[i] = b4 * sc + sh; }
;             else { PA[i] = g4; PB[i] = b4; }
;         }
;         f32x4 nv[8];
; #pragma unroll
;         for (int i = 0; i < 8; ++i) nv[i] = __builtin_nontemporal_load((const f32x4*)(src + (size_t)row0 * DM + lane * 4 + i * 256));
; #pragma unroll 1
;         for (int rr = 0; rr < 16; ++rr) {
;             const int row = row0 + rr;
;             f32x4 v[8];
; #pragma unroll
;             for (int i = 0; i < 8; ++i) v[i] = nv[i];
;             if (rr + 1 < 16) {
; #pragma unroll
;                 for (int i = 0; i < 8; ++i) nv[i] = __builtin_nontemporal_load((const f32x4*)(src + (size_t)(row + 1) * DM + lane * 4 + i * 256)); }
;             if (DO_LN) {
;                 float s = 0.f;
; #pragma unroll
;                 for (int i = 0; i < 8; ++i) s += (v[i][0] + v[i][1]) + (v[i][2] + v[i][3]);
.LBB0_723:
	global_load_dwordx4 v[2:5], v[130:131], off
	global_load_dwordx4 v[6:9], v[130:131], off offset:1024
	global_load_dwordx4 v[10:13], v[132:133], off
	global_load_dwordx4 v[14:17], v[132:133], off offset:1024
	global_load_dwordx4 v[18:21], v[130:131], off offset:2048
	global_load_dwordx4 v[22:25], v[130:131], off offset:3072
	global_load_dwordx4 v[26:29], v[132:133], off offset:2048
	global_load_dwordx4 v[30:33], v[132:133], off offset:3072
	global_load_dwordx4 v[34:37], v[136:137], off
	global_load_dwordx4 v[38:41], v[138:139], off
	global_load_dwordx4 v[42:45], v[140:141], off
	global_load_dwordx4 v[46:49], v[142:143], off
	global_load_dwordx4 v[50:53], v[144:145], off
	v_lshlrev_b32_e32 v66, 4, v1
	v_ashrrev_i32_e32 v67, 31, v66
	v_lshlrev_b64 v[68:69], 13, v[66:67]
	v_lshl_add_u64 v[54:55], v[134:135], 0, v[68:69]
	global_load_dwordx4 v[126:129], v[54:55], off nt
	global_load_dwordx4 v[118:121], v[54:55], off offset:1024 nt
	global_load_dwordx4 v[114:117], v[54:55], off offset:2048 nt
	global_load_dwordx4 v[106:109], v[54:55], off offset:3072 nt
	v_add_co_u32_e32 v54, vcc, 0x1000, v54
	v_or_b32_e32 v154, 1, v66
	s_nop 0
	v_addc_co_u32_e32 v55, vcc, 0, v55, vcc
	global_load_dwordx4 v[102:105], v[54:55], off offset:2048 nt
	global_load_dwordx4 v[98:101], v[54:55], off offset:3072 nt
	global_load_dwordx4 v[122:125], v[54:55], off nt
	global_load_dwordx4 v[110:113], v[54:55], off offset:1024 nt
	s_nop 0
	global_load_dwordx4 v[54:57], v[146:147], off
	global_load_dwordx4 v[58:61], v[148:149], off
	global_load_dwordx4 v[62:65], v[150:151], off
	v_lshl_add_u64 v[156:157], v[152:153], 0, v[68:69]
	s_mov_b64 s[6:7], 0
	s_waitcnt vmcnt(0) lgkmcnt(0)
	v_mov_b64_e32 v[78:79], v[126:127]
	v_mov_b64_e32 v[74:75], v[118:119]
	v_mov_b64_e32 v[70:71], v[114:115]
	v_mov_b64_e32 v[66:67], v[106:107]
	v_mov_b64_e32 v[82:83], v[98:99]
	v_mov_b64_e32 v[86:87], v[102:103]
	v_mov_b64_e32 v[90:91], v[110:111]
	v_mov_b64_e32 v[94:95], v[122:123]
	v_mov_b64_e32 v[68:69], v[108:109]
	v_mov_b64_e32 v[72:73], v[116:117]
	v_mov_b64_e32 v[76:77], v[120:121]
	v_mov_b64_e32 v[84:85], v[100:101]
	v_mov_b64_e32 v[88:89], v[104:105]
	v_mov_b64_e32 v[92:93], v[112:113]
	v_mov_b64_e32 v[96:97], v[124:125]
	v_mov_b64_e32 v[80:81], v[128:129]
	s_branch .LBB0_725
.LBB0_724:
	v_mov_b32_e32 v164, v118
	v_mov_b32_e32 v165, v126
	v_mov_b32_e32 v166, v119
	v_mov_b32_e32 v167, v127
	v_pk_add_f32 v[164:165], v[164:165], v[166:167]
	v_mov_b32_e32 v166, v120
	v_mov_b32_e32 v167, v128
	v_mov_b32_e32 v168, v121
	v_mov_b32_e32 v169, v129
	v_pk_add_f32 v[166:167], v[166:167], v[168:169]
	v_mov_b32_e32 v168, v114
	v_pk_add_f32 v[164:165], v[164:165], v[166:167]
	v_mov_b32_e32 v166, v115
	v_mov_b32_e32 v167, v116
	v_mov_b32_e32 v169, v117
	v_pk_add_f32 v[166:167], v[166:167], v[168:169]
	v_add_f32_e32 v155, 0, v165
	v_pk_add_f32 v[166:167], v[166:167], v[166:167] op_sel_hi:[0,1]
	v_add_f32_e32 v165, v164, v155
	v_add_f32_e32 v169, v106, v107
	v_add_f32_e32 v171, v108, v109
	v_mov_b32_e32 v168, v122
	v_mov_b32_e32 v170, v123
	v_mov_b32_e32 v166, v124
	v_mov_b32_e32 v164, v125
	v_pk_add_f32 v[168:169], v[168:169], v[170:171]
	v_pk_add_f32 v[164:165], v[166:167], v[164:165]
	v_mov_b32_e32 v166, v111
	v_pk_add_f32 v[164:165], v[168:169], v[164:165]
	v_mov_b32_e32 v167, v112
	v_mov_b32_e32 v168, v110
	v_mov_b32_e32 v169, v113
	v_pk_add_f32 v[166:167], v[166:167], v[168:169]
	v_pk_add_f32 v[164:165], v[164:165], v[164:165] op_sel_hi:[0,1]
	v_pk_add_f32 v[166:167], v[166:167], v[166:167] op_sel_hi:[0,1]
	v_add_f32_e32 v169, v102, v103
	v_add_f32_e32 v171, v104, v105
	v_mov_b32_e32 v168, v98
	v_mov_b32_e32 v170, v99
	v_mov_b32_e32 v166, v100
	v_mov_b32_e32 v164, v101
	v_pk_add_f32 v[168:169], v[168:169], v[170:171]
	v_pk_add_f32 v[164:165], v[166:167], v[164:165]
	v_add_u32_e32 v154, 1, v154
	v_pk_add_f32 v[164:165], v[168:169], v[164:165]
	s_nop 0
	v_add_f32_e32 v155, v164, v165
	ds_bpermute_b32 v164, v158, v155
	s_waitcnt lgkmcnt(0)
	v_add_f32_e32 v155, v155, v164
	ds_bpermute_b32 v164, v159, v155
	s_waitcnt lgkmcnt(0)
	v_add_f32_e32 v155, v155, v164
	ds_bpermute_b32 v164, v160, v155
	s_waitcnt lgkmcnt(0)
	v_add_f32_e32 v155, v155, v164
	ds_bpermute_b32 v164, v161, v155
	s_waitcnt lgkmcnt(0)
	v_add_f32_e32 v155, v155, v164
	ds_bpermute_b32 v164, v162, v155
	s_waitcnt lgkmcnt(0)
	v_add_f32_e32 v155, v155, v164
	ds_bpermute_b32 v164, v163, v155
	s_waitcnt lgkmcnt(0)
; template <bool DO_LN, bool DO_H, bool DO_GATES, bool WRITE_X> ...
;     ...
;                 float q = 0.f;
; #pragma unroll
;                 for (int i = 0; i < 8; ++i) { const f32x4 d = v[i] - mu; q += (d[0] * d[0] + d[1] * d[1]) + (d[2] * d[2] + d[3] * d[3]); }
;                 const float rstd = 1.0f / sqrtf(wave_sum(q, lane) * (1.0f / DM) + LN_EPS);
	v_add_f32_e32 v155, v155, v164
	v_fmamk_f32 v127, v155, 0xba000000, v127
	v_fmamk_f32 v119, v155, 0xba000000, v119
	v_fmamk_f32 v129, v155, 0xba000000, v129
	v_fmac_f32_e32 v126, 0xba000000, v155
	v_fmamk_f32 v121, v155, 0xba000000, v121
	v_fmac_f32_e32 v118, 0xba000000, v155
	v_mov_b32_e32 v166, v127
	v_mov_b32_e32 v167, v119
	v_fmamk_f32 v128, v155, 0xba000000, v128
	v_fmamk_f32 v120, v155, 0xba000000, v120
	v_mov_b32_e32 v164, v126
	v_mov_b32_e32 v165, v118
	v_pk_mul_f32 v[166:167], v[166:167], v[166:167]
	v_mov_b32_e32 v168, v129
	v_mov_b32_e32 v169, v121
	v_pk_fma_f32 v[164:165], v[164:165], v[164:165], v[166:167]
	v_mov_b32_e32 v166, v128
	v_mov_b32_e32 v167, v120
	v_pk_mul_f32 v[168:169], v[168:169], v[168:169]
	v_fmamk_f32 v115, v155, 0xba000000, v115
	v_pk_fma_f32 v[166:167], v[166:167], v[166:167], v[168:169]
	v_fmamk_f32 v114, v155, 0xba000000, v114
	v_pk_add_f32 v[164:165], v[164:165], v[166:167]
	v_fmamk_f32 v117, v155, 0xba000000, v117
	v_fmac_f32_e32 v116, 0xba000000, v155
	v_pk_add_f32 v[164:165], v[164:165], v[164:165] op_sel_hi:[0,1]
	v_pk_mul_f32 v[166:167], v[116:117], v[116:117]
	v_pk_mul_f32 v[168:169], v[114:115], v[114:115]
	v_fmamk_f32 v106, v155, 0xba000000, v106
	v_pk_mov_b32 v[170:171], v[168:169], v[166:167] op_sel:[1,0]
	v_mov_b32_e32 v169, v167
	v_fmamk_f32 v107, v155, 0xba000000, v107
	v_fmac_f32_e32 v108, 0xba000000, v155
	v_mul_f32_e32 v164, v106, v106
	v_pk_add_f32 v[166:167], v[170:171], v[168:169]
	v_fmamk_f32 v109, v155, 0xba000000, v109
	v_pk_fma_f32 v[168:169], v[106:107], v[106:107], v[164:165] op_sel_hi:[1,1,0]
	v_mul_f32_e32 v164, v108, v108
	v_pk_add_f32 v[166:167], v[166:167], v[166:167] op_sel_hi:[0,1]
	v_pk_fma_f32 v[170:171], v[108:109], v[108:109], v[164:165] op_sel_hi:[1,1,0]
	v_fmamk_f32 v125, v155, 0xba000000, v125
	v_fmamk_f32 v124, v155, 0xba000000, v124
	v_fmamk_f32 v123, v155, 0xba000000, v123
	v_fmac_f32_e32 v122, 0xba000000, v155
	v_mul_f32_e32 v168, v122, v122
	v_mul_f32_e32 v170, v123, v123
	v_mul_f32_e32 v166, v124, v124
	v_mul_f32_e32 v164, v125, v125
	v_pk_add_f32 v[168:169], v[168:169], v[170:171]
	v_pk_add_f32 v[164:165], v[166:167], v[164:165]
	v_fmamk_f32 v111, v155, 0xba000000, v111
	v_pk_add_f32 v[164:165], v[168:169], v[164:165]
	v_fmamk_f32 v110, v155, 0xba000000, v110
	v_fmamk_f32 v113, v155, 0xba000000, v113
	v_fmac_f32_e32 v112, 0xba000000, v155
	v_pk_add_f32 v[164:165], v[164:165], v[164:165] op_sel_hi:[0,1]
	v_pk_mul_f32 v[166:167], v[112:113], v[112:113]
	v_pk_mul_f32 v[168:169], v[110:111], v[110:111]
	v_fmamk_f32 v102, v155, 0xba000000, v102
	v_pk_mov_b32 v[170:171], v[168:169], v[166:167] op_sel:[1,0]
	v_mov_b32_e32 v169, v167
	v_fmamk_f32 v103, v155, 0xba000000, v103
	v_fmac_f32_e32 v104, 0xba000000, v155
	v_mul_f32_e32 v164, v102, v102
	v_pk_add_f32 v[166:167], v[170:171], v[168:169]
	v_fmamk_f32 v105, v155, 0xba000000, v105
	v_pk_fma_f32 v[168:169], v[102:103], v[102:103], v[164:165] op_sel_hi:[1,1,0]
	v_mul_f32_e32 v164, v104, v104
	v_pk_add_f32 v[166:167], v[166:167], v[166:167] op_sel_hi:[0,1]
	v_pk_fma_f32 v[170:171], v[104:105], v[104:105], v[164:165] op_sel_hi:[1,1,0]
	v_fmamk_f32 v101, v155, 0xba000000, v101
	v_fmamk_f32 v100, v155, 0xba000000, v100
	v_fmamk_f32 v99, v155, 0xba000000, v99
	v_fmac_f32_e32 v98, 0xba000000, v155
	v_mul_f32_e32 v168, v98, v98
	v_mul_f32_e32 v170, v99, v99
	v_mul_f32_e32 v166, v100, v100
	v_mul_f32_e32 v164, v101, v101
	v_pk_add_f32 v[168:169], v[168:169], v[170:171]
	v_pk_add_f32 v[164:165], v[166:167], v[164:165]
	s_nop 0
	v_pk_add_f32 v[164:165], v[168:169], v[164:165]
	s_nop 0
	v_add_f32_e32 v155, v164, v165
	ds_bpermute_b32 v164, v158, v155
	s_waitcnt lgkmcnt(0)
	v_add_f32_e32 v155, v155, v164
	ds_bpermute_b32 v164, v159, v155
	s_waitcnt lgkmcnt(0)
	v_add_f32_e32 v155, v155, v164
	ds_bpermute_b32 v164, v160, v155
	s_waitcnt lgkmcnt(0)
	v_add_f32_e32 v155, v155, v164
	ds_bpermute_b32 v164, v161, v155
	s_waitcnt lgkmcnt(0)
	v_add_f32_e32 v155, v155, v164
	ds_bpermute_b32 v164, v162, v155
	s_waitcnt lgkmcnt(0)
	v_add_f32_e32 v155, v155, v164
	ds_bpermute_b32 v164, v163, v155
	s_waitcnt lgkmcnt(0)
; template <bool DO_LN, bool DO_H, bool DO_GATES, bool WRITE_X> ...
;     ...
;             if (rr + 1 < 16) {
; #pragma unroll
;                 for (int i = 0; i < 8; ++i) nv[i] = __builtin_nontemporal_load((const f32x4*)(src + (size_t)(row + 1) * DM + lane * 4 + i * 256)); }
;     ...
;                 const float rstd = 1.0f / sqrtf(wave_sum(q, lane) * (1.0f / DM) + LN_EPS);
; #pragma unroll
;                 for (int i = 0; i < 8; ++i) v[i] = (v[i] - mu) * rstd;
;                 if (!WRITE_X && lane == 0) { float* st = (float*)(ws + WS_STATS) + (size_t)row * 2; st[0] = mu; st[1] = rstd; }
;             }
;             if (WRITE_X && !DO_H) {
; #pragma unroll
;                 for (int i = 0; i < 8; ++i) __builtin_nontemporal_store(v[i] * PA[i] + PB[i], (f32x4*)(xout + (size_t)row * DM + lane * 4 + i * 256));
	v_add_f32_e32 v155, v155, v164
	v_fmamk_f32 v155, v155, 0x3a000000, v238
	v_mul_f32_e32 v164, 0x4f800000, v155
	v_cmp_gt_f32_e32 vcc, s84, v155
	s_nop 1
	v_cndmask_b32_e32 v155, v155, v164, vcc
	v_sqrt_f32_e32 v164, v155
	s_nop 0
	v_add_u32_e32 v165, -1, v164
	v_fma_f32 v166, -v165, v164, v155
	v_cmp_ge_f32_e64 s[0:1], 0, v166
	v_add_u32_e32 v166, 1, v164
	s_nop 0
	v_cndmask_b32_e64 v165, v164, v165, s[0:1]
	v_fma_f32 v164, -v166, v164, v155
	v_cmp_lt_f32_e64 s[0:1], 0, v164
	s_nop 1
	v_cndmask_b32_e64 v164, v165, v166, s[0:1]
	v_mul_f32_e32 v165, 0x37800000, v164
	v_cndmask_b32_e32 v164, v164, v165, vcc
	v_cmp_class_f32_e32 vcc, v155, v239
	s_nop 1
	v_cndmask_b32_e32 v155, v164, v155, vcc
	v_div_scale_f32 v164, s[0:1], v155, v155, 1.0
	v_rcp_f32_e32 v165, v164
	s_nop 0
	v_fma_f32 v166, -v164, v165, 1.0
	v_fmac_f32_e32 v165, v166, v165
	v_div_scale_f32 v166, vcc, 1.0, v155, 1.0
	v_mul_f32_e32 v167, v166, v165
	v_fma_f32 v168, -v164, v167, v166
	v_fmac_f32_e32 v167, v168, v165
	v_fma_f32 v164, -v164, v167, v166
	v_div_fmas_f32 v164, v164, v165, v167
	v_div_fixup_f32 v164, v164, v155, 1.0
	v_pk_mul_f32 v[126:127], v[126:127], v[164:165] op_sel_hi:[1,0]
	v_pk_mul_f32 v[128:129], v[128:129], v[164:165] op_sel_hi:[1,0]
	v_pk_mul_f32 v[118:119], v[118:119], v[164:165] op_sel_hi:[1,0]
	v_pk_mul_f32 v[120:121], v[120:121], v[164:165] op_sel_hi:[1,0]
	v_pk_mul_f32 v[114:115], v[114:115], v[164:165] op_sel_hi:[1,0]
	v_pk_mul_f32 v[116:117], v[116:117], v[164:165] op_sel_hi:[1,0]
	v_pk_mul_f32 v[106:107], v[106:107], v[164:165] op_sel_hi:[1,0]
	v_pk_mul_f32 v[108:109], v[108:109], v[164:165] op_sel_hi:[1,0]
	v_pk_mul_f32 v[122:123], v[122:123], v[164:165] op_sel_hi:[1,0]
	v_pk_mul_f32 v[124:125], v[124:125], v[164:165] op_sel_hi:[1,0]
	v_pk_mul_f32 v[110:111], v[110:111], v[164:165] op_sel_hi:[1,0]
	v_pk_mul_f32 v[112:113], v[112:113], v[164:165] op_sel_hi:[1,0]
	v_pk_mul_f32 v[102:103], v[102:103], v[164:165] op_sel_hi:[1,0]
	v_pk_mul_f32 v[104:105], v[104:105], v[164:165] op_sel_hi:[1,0]
	v_pk_mul_f32 v[166:167], v[98:99], v[164:165] op_sel_hi:[1,0]
	v_pk_mul_f32 v[164:165], v[100:101], v[164:165] op_sel_hi:[1,0]
	v_lshl_add_u64 v[168:169], v[156:157], 0, s[6:7]
	v_pk_fma_f32 v[100:101], v[4:5], v[128:129], v[12:13]
	v_pk_fma_f32 v[98:99], v[2:3], v[126:127], v[10:11]
	global_store_dwordx4 v[168:169], v[98:101], off nt
	s_add_u32 s6, s6, 0x2000
	s_addc_u32 s7, s7, 0
	v_pk_fma_f32 v[100:101], v[8:9], v[120:121], v[16:17]
	v_pk_fma_f32 v[98:99], v[6:7], v[118:119], v[14:15]
	global_store_dwordx4 v[168:169], v[98:101], off offset:1024 nt
	s_waitcnt vmcnt(0)
	v_mov_b64_e32 v[120:121], v[76:77]
	v_mov_b64_e32 v[128:129], v[80:81]
	v_pk_fma_f32 v[100:101], v[20:21], v[116:117], v[28:29]
	v_pk_fma_f32 v[98:99], v[18:19], v[114:115], v[26:27]
	global_store_dwordx4 v[168:169], v[98:101], off offset:2048 nt
	v_mov_b64_e32 v[116:117], v[72:73]
	s_cmp_eq_u32 s6, 0x20000
	v_pk_fma_f32 v[100:101], v[24:25], v[108:109], v[32:33]
	v_pk_fma_f32 v[98:99], v[22:23], v[106:107], v[30:31]
	v_add_co_u32_e32 v106, vcc, s43, v168
	global_store_dwordx4 v[168:169], v[98:101], off offset:3072 nt
	s_nop 0
	v_addc_co_u32_e32 v107, vcc, 0, v169, vcc
	v_pk_fma_f32 v[100:101], v[36:37], v[124:125], v[40:41]
	v_pk_fma_f32 v[98:99], v[34:35], v[122:123], v[38:39]
	global_store_dwordx4 v[106:107], v[98:101], off nt
	v_mov_b64_e32 v[124:125], v[96:97]
	v_mov_b64_e32 v[122:123], v[94:95]
	v_pk_fma_f32 v[100:101], v[44:45], v[112:113], v[48:49]
	v_pk_fma_f32 v[98:99], v[42:43], v[110:111], v[46:47]
	global_store_dwordx4 v[106:107], v[98:101], off offset:1024 nt
	v_mov_b64_e32 v[112:113], v[92:93]
	v_mov_b64_e32 v[110:111], v[90:91]
	v_pk_fma_f32 v[100:101], v[52:53], v[104:105], v[56:57]
	v_pk_fma_f32 v[98:99], v[50:51], v[102:103], v[54:55]
	global_store_dwordx4 v[106:107], v[98:101], off offset:2048 nt
	v_mov_b64_e32 v[104:105], v[88:89]
	v_mov_b64_e32 v[102:103], v[86:87]
	v_pk_fma_f32 v[100:101], v[60:61], v[164:165], v[64:65]
	v_pk_fma_f32 v[98:99], v[58:59], v[166:167], v[62:63]
	global_store_dwordx4 v[106:107], v[98:101], off offset:3072 nt
	v_mov_b64_e32 v[108:109], v[68:69]
	v_mov_b64_e32 v[106:107], v[66:67]
	v_mov_b64_e32 v[100:101], v[84:85]
	v_mov_b64_e32 v[98:99], v[82:83]
	v_mov_b64_e32 v[114:115], v[70:71]
	v_mov_b64_e32 v[118:119], v[74:75]
	v_mov_b64_e32 v[126:127], v[78:79]
	s_cbranch_scc1 .LBB0_722
.LBB0_725:
	s_cmp_eq_u32 s6, 0x1e000
	s_cbranch_scc1 .LBB0_724
	v_ashrrev_i32_e32 v155, 31, v154
	v_lshlrev_b64 v[66:67], 13, v[154:155]
	v_lshl_add_u64 v[82:83], v[134:135], 0, v[66:67]
	global_load_dwordx4 v[78:81], v[82:83], off nt
	global_load_dwordx4 v[74:77], v[82:83], off offset:1024 nt
	global_load_dwordx4 v[70:73], v[82:83], off offset:2048 nt
	global_load_dwordx4 v[66:69], v[82:83], off offset:3072 nt
	v_add_co_u32_e32 v82, vcc, 0x1000, v82
	s_nop 1
	v_addc_co_u32_e32 v83, vcc, 0, v83, vcc
	global_load_dwordx4 v[94:97], v[82:83], off nt
	global_load_dwordx4 v[90:93], v[82:83], off offset:1024 nt
	global_load_dwordx4 v[86:89], v[82:83], off offset:2048 nt
	s_nop 0
	global_load_dwordx4 v[82:85], v[82:83], off offset:3072 nt
	s_branch .LBB0_724

; template <bool DO_LN, bool DO_H, bool DO_GATES, bool WRITE_X> ...
;     ...
;         const float* mb = modl + (size_t)(row0 >> 11) * 12288 + lane * 4;
;         f32x4 PA[8], PB[8];
; #pragma unroll
;         for (int i = 0; i < 8; ++i) {
;             f32x4 g4 = {1.f, 1.f, 1.f, 1.f}, b4 = {0.f, 0.f, 0.f, 0.f};
;             if (DO_LN) { g4 = *(const f32x4*)(lng + lane * 4 + i * 256); b4 = *(const f32x4*)(lnb + lane * 4 + i * 256); }
;             if (DO_H) { const f32x4 sc = *(const f32x4*)(mb + sc_idx * 2048 + i * 256) + 1.0f, sh = *(const f32x4*)(mb + sh_idx * 2048 + i * 256);
;                 PA[i] = g4 * sc; PB[i] = b4 * sc + sh; }
;             else { PA[i] = g4; PB[i] = b4; }
;         }
;         f32x4 nv[8];
; #pragma unroll
;         for (int i = 0; i < 8; ++i) nv[i] = __builtin_nontemporal_load((const f32x4*)(src + (size_t)row0 * DM + lane * 4 + i * 256));
.LBB0_734:
	v_ashrrev_i32_e32 v2, 7, v1
	s_mov_b32 s2, 0xc000
	v_mad_i64_i32 v[34:35], s[2:3], v2, s2, v[66:67]
	v_add_co_u32_e32 v22, vcc, 0x2000, v34
	s_movk_i32 s2, 0x3000
	s_nop 0
	v_addc_co_u32_e32 v23, vcc, 0, v35, vcc
	v_add_co_u32_e32 v36, vcc, s2, v34
	global_load_dwordx4 v[2:5], v[22:23], off
	global_load_dwordx4 v[6:9], v[22:23], off offset:1024
	global_load_dwordx4 v[10:13], v[22:23], off offset:2048
	global_load_dwordx4 v[14:17], v[68:69], off
	global_load_dwordx4 v[18:21], v[68:69], off offset:1024
	s_nop 0
	global_load_dwordx4 v[22:25], v[22:23], off offset:3072
	s_nop 0
	global_load_dwordx4 v[26:29], v[70:71], off
	global_load_dwordx4 v[30:33], v[70:71], off offset:1024
	global_load_dwordx4 v[98:101], v[34:35], off
	global_load_dwordx4 v[106:109], v[34:35], off offset:1024
	global_load_dwordx4 v[110:113], v[68:69], off offset:2048
	global_load_dwordx4 v[118:121], v[68:69], off offset:3072
	global_load_dwordx4 v[114:117], v[70:71], off offset:2048
	global_load_dwordx4 v[122:125], v[70:71], off offset:3072
	global_load_dwordx4 v[126:129], v[34:35], off offset:2048
	global_load_dwordx4 v[130:133], v[34:35], off offset:3072
	global_load_dwordx4 v[134:137], v[74:75], off
	global_load_dwordx4 v[138:141], v[76:77], off
	v_addc_co_u32_e32 v37, vcc, 0, v35, vcc
	v_add_co_u32_e32 v34, vcc, s43, v34
	v_lshlrev_b32_e32 v186, 4, v1
	global_load_dwordx4 v[142:145], v[36:37], off
	v_addc_co_u32_e32 v35, vcc, 0, v35, vcc
	v_ashrrev_i32_e32 v187, 31, v186
	global_load_dwordx4 v[146:149], v[34:35], off
	global_load_dwordx4 v[150:153], v[36:37], off offset:1024
	global_load_dwordx4 v[154:157], v[78:79], off
	global_load_dwordx4 v[158:161], v[80:81], off
	global_load_dwordx4 v[162:165], v[34:35], off offset:1024
	global_load_dwordx4 v[174:177], v[36:37], off offset:2048
	global_load_dwordx4 v[178:181], v[82:83], off
	global_load_dwordx4 v[182:185], v[84:85], off
	global_load_dwordx4 v[192:195], v[86:87], off
	global_load_dwordx4 v[196:199], v[34:35], off offset:2048
	global_load_dwordx4 v[200:203], v[88:89], off
	global_load_dwordx4 v[204:207], v[36:37], off offset:3072
	v_lshlrev_b64 v[36:37], 13, v[186:187]
	v_lshl_add_u64 v[62:63], v[72:73], 0, v[36:37]
	v_add_co_u32_e32 v46, vcc, s43, v62
	global_load_dwordx4 v[208:211], v[34:35], off offset:3072
	s_nop 0
	v_addc_co_u32_e32 v47, vcc, 0, v63, vcc
	global_load_dwordx4 v[34:37], v[46:47], off offset:3072 nt
	global_load_dwordx4 v[38:41], v[46:47], off offset:2048 nt
	global_load_dwordx4 v[42:45], v[46:47], off offset:1024 nt
	s_nop 0
	global_load_dwordx4 v[46:49], v[46:47], off nt
	s_nop 0
	global_load_dwordx4 v[50:53], v[62:63], off offset:3072 nt
	global_load_dwordx4 v[54:57], v[62:63], off offset:2048 nt
	global_load_dwordx4 v[58:61], v[62:63], off offset:1024 nt
	s_nop 0
	global_load_dwordx4 v[62:65], v[62:63], off nt
	s_mov_b32 s14, 0
	v_or_b32_e32 v173, 1, v186
	s_waitcnt vmcnt(0) lgkmcnt(0)
	v_pk_add_f32 v[2:3], v[2:3], 1.0 op_sel_hi:[1,0]
	v_pk_add_f32 v[4:5], v[4:5], 1.0 op_sel_hi:[1,0]
	v_pk_add_f32 v[8:9], v[8:9], 1.0 op_sel_hi:[1,0]
	v_pk_add_f32 v[12:13], v[12:13], 1.0 op_sel_hi:[1,0]
	v_pk_mul_f32 v[94:95], v[14:15], v[2:3]
	v_pk_add_f32 v[24:25], v[24:25], 1.0 op_sel_hi:[1,0]
	v_pk_add_f32 v[10:11], v[10:11], 1.0 op_sel_hi:[1,0]
	v_pk_add_f32 v[22:23], v[22:23], 1.0 op_sel_hi:[1,0]
	v_pk_fma_f32 v[98:99], v[26:27], v[2:3], v[98:99]
	v_pk_mul_f32 v[92:93], v[16:17], v[4:5]
	v_pk_fma_f32 v[96:97], v[28:29], v[4:5], v[100:101]
	v_pk_fma_f32 v[104:105], v[32:33], v[8:9], v[108:109]
	v_pk_mul_f32 v[108:109], v[112:113], v[12:13]
	v_pk_add_f32 v[6:7], v[6:7], 1.0 op_sel_hi:[1,0]
	v_pk_fma_f32 v[112:113], v[116:117], v[12:13], v[128:129]
	v_pk_mul_f32 v[116:117], v[120:121], v[24:25]
	v_pk_fma_f32 v[120:121], v[124:125], v[24:25], v[132:133]
	v_pk_fma_f32 v[114:115], v[114:115], v[10:11], v[126:127]
	v_pk_fma_f32 v[122:123], v[122:123], v[22:23], v[130:131]
	v_pk_mul_f32 v[100:101], v[20:21], v[8:9]
	v_pk_mul_f32 v[102:103], v[18:19], v[6:7]
	v_pk_fma_f32 v[106:107], v[30:31], v[6:7], v[106:107]
	v_pk_mul_f32 v[110:111], v[110:111], v[10:11]
	v_pk_add_f32 v[2:3], v[144:145], 1.0 op_sel_hi:[1,0]
	v_pk_add_f32 v[4:5], v[142:143], 1.0 op_sel_hi:[1,0]
	v_pk_mul_f32 v[124:125], v[136:137], v[2:3]
	v_pk_fma_f32 v[128:129], v[140:141], v[2:3], v[148:149]
	v_pk_add_f32 v[2:3], v[152:153], 1.0 op_sel_hi:[1,0]
	v_pk_mul_f32 v[126:127], v[134:135], v[4:5]
	v_pk_fma_f32 v[130:131], v[138:139], v[4:5], v[146:147]
	v_pk_add_f32 v[4:5], v[150:151], 1.0 op_sel_hi:[1,0]
	v_pk_mul_f32 v[132:133], v[156:157], v[2:3]
	v_pk_fma_f32 v[136:137], v[160:161], v[2:3], v[164:165]
	v_pk_add_f32 v[2:3], v[176:177], 1.0 op_sel_hi:[1,0]
	v_pk_mul_f32 v[134:135], v[154:155], v[4:5]
	v_pk_fma_f32 v[138:139], v[158:159], v[4:5], v[162:163]
	v_pk_add_f32 v[4:5], v[174:175], 1.0 op_sel_hi:[1,0]
	v_pk_mul_f32 v[140:141], v[180:181], v[2:3]
	v_pk_fma_f32 v[144:145], v[184:185], v[2:3], v[198:199]
	v_pk_add_f32 v[2:3], v[206:207], 1.0 op_sel_hi:[1,0]
	v_pk_mul_f32 v[142:143], v[178:179], v[4:5]
	v_pk_fma_f32 v[146:147], v[182:183], v[4:5], v[196:197]
	v_pk_add_f32 v[4:5], v[204:205], 1.0 op_sel_hi:[1,0]
	v_pk_mul_f32 v[148:149], v[194:195], v[2:3]
	v_pk_fma_f32 v[152:153], v[202:203], v[2:3], v[210:211]
	v_mov_b64_e32 v[2:3], 0x3d101000
	v_pk_mul_f32 v[118:119], v[118:119], v[22:23]
	v_pk_mul_f32 v[150:151], v[192:193], v[4:5]
	v_pk_fma_f32 v[154:155], v[200:201], v[4:5], v[208:209]
	v_lshl_add_u64 v[156:157], v[186:187], 3, v[2:3]
	v_lshlrev_b64 v[160:161], 12, v[186:187]
	v_mov_b64_e32 v[18:19], v[34:35]
	v_mov_b64_e32 v[22:23], v[38:39]
	v_mov_b64_e32 v[26:27], v[42:43]
	v_mov_b64_e32 v[30:31], v[46:47]
	v_mov_b64_e32 v[2:3], v[50:51]
	v_mov_b64_e32 v[6:7], v[54:55]
	v_mov_b64_e32 v[10:11], v[58:59]
	v_mov_b64_e32 v[14:15], v[62:63]
	v_lshlrev_b64 v[158:159], 5, v[186:187]
	v_or_b32_e32 v160, v90, v160
	v_mov_b64_e32 v[20:21], v[36:37]
	v_mov_b64_e32 v[24:25], v[40:41]
	v_mov_b64_e32 v[28:29], v[44:45]
	v_mov_b64_e32 v[32:33], v[48:49]
	v_mov_b64_e32 v[4:5], v[52:53]
	v_mov_b64_e32 v[8:9], v[56:57]
	v_mov_b64_e32 v[12:13], v[60:61]
	v_mov_b64_e32 v[16:17], v[64:65]
	s_branch .LBB0_736

; template <bool DO_LN, bool DO_H, bool DO_GATES, bool WRITE_X> ...
;     ...
;         for (int rr = 0; rr < 16; ++rr) {
;             const int row = row0 + rr;
;             f32x4 v[8];
; #pragma unroll
;             for (int i = 0; i < 8; ++i) v[i] = nv[i];
;             if (rr + 1 < 16) {
; #pragma unroll
;                 for (int i = 0; i < 8; ++i) nv[i] = __builtin_nontemporal_load((const f32x4*)(src + (size_t)(row + 1) * DM + lane * 4 + i * 256)); }
;             if (DO_LN) {
;                 float s = 0.f;
; #pragma unroll
;                 for (int i = 0; i < 8; ++i) s += (v[i][0] + v[i][1]) + (v[i][2] + v[i][3]);
;                 const float mu = wave_sum(s, lane) * (1.0f / DM);
;                 float q = 0.f;
; #pragma unroll
;                 for (int i = 0; i < 8; ++i) { const f32x4 d = v[i] - mu; q += (d[0] * d[0] + d[1] * d[1]) + (d[2] * d[2] + d[3] * d[3]); }
;                 const float rstd = 1.0f / sqrtf(wave_sum(q, lane) * (1.0f / DM) + LN_EPS);
.LBB0_736:
	s_cmp_eq_u32 s14, 15
	s_cbranch_scc1 .LBB0_738
	v_add_u32_e32 v2, s14, v173
	v_ashrrev_i32_e32 v3, 31, v2
	v_lshlrev_b64 v[2:3], 13, v[2:3]
	v_lshl_add_u64 v[18:19], v[72:73], 0, v[2:3]
	global_load_dwordx4 v[14:17], v[18:19], off nt
	global_load_dwordx4 v[10:13], v[18:19], off offset:1024 nt
	global_load_dwordx4 v[6:9], v[18:19], off offset:2048 nt
	global_load_dwordx4 v[2:5], v[18:19], off offset:3072 nt
	v_add_co_u32_e32 v18, vcc, 0x1000, v18
	s_nop 1
	v_addc_co_u32_e32 v19, vcc, 0, v19, vcc
	global_load_dwordx4 v[30:33], v[18:19], off nt
	global_load_dwordx4 v[26:29], v[18:19], off offset:1024 nt
	global_load_dwordx4 v[22:25], v[18:19], off offset:2048 nt
	s_nop 0
	global_load_dwordx4 v[18:21], v[18:19], off offset:3072 nt
.LBB0_738:
	v_mov_b32_e32 v162, v58
	v_mov_b32_e32 v163, v62
	v_mov_b32_e32 v164, v59
	v_mov_b32_e32 v165, v63
	v_pk_add_f32 v[162:163], v[162:163], v[164:165]
	v_mov_b32_e32 v164, v60
	v_mov_b32_e32 v165, v64
	v_mov_b32_e32 v174, v61
	v_mov_b32_e32 v175, v65
	v_pk_add_f32 v[164:165], v[164:165], v[174:175]
	v_mov_b32_e32 v174, v54
	v_pk_add_f32 v[162:163], v[162:163], v[164:165]
	v_mov_b32_e32 v164, v55
	v_mov_b32_e32 v165, v56
	v_mov_b32_e32 v175, v57
	v_pk_add_f32 v[164:165], v[164:165], v[174:175]
	v_add_f32_e32 v163, 0, v163
	v_pk_add_f32 v[164:165], v[164:165], v[164:165] op_sel_hi:[0,1]
	v_add_f32_e32 v163, v162, v163
	v_add_f32_e32 v175, v50, v51
	v_add_f32_e32 v177, v52, v53
	v_mov_b32_e32 v174, v46
	v_mov_b32_e32 v176, v47
	v_mov_b32_e32 v164, v48
	v_mov_b32_e32 v162, v49
	v_pk_add_f32 v[174:175], v[174:175], v[176:177]
	v_pk_add_f32 v[162:163], v[164:165], v[162:163]
	v_mov_b32_e32 v164, v43
	v_pk_add_f32 v[162:163], v[174:175], v[162:163]
	v_mov_b32_e32 v165, v44
	v_mov_b32_e32 v174, v42
	v_mov_b32_e32 v175, v45
	v_pk_add_f32 v[164:165], v[164:165], v[174:175]
	v_pk_add_f32 v[162:163], v[162:163], v[162:163] op_sel_hi:[0,1]
	v_pk_add_f32 v[164:165], v[164:165], v[164:165] op_sel_hi:[0,1]
	v_add_f32_e32 v175, v38, v39
	v_add_f32_e32 v177, v40, v41
	v_mov_b32_e32 v174, v34
	v_mov_b32_e32 v176, v35
	v_mov_b32_e32 v164, v36
	v_mov_b32_e32 v162, v37
	v_pk_add_f32 v[174:175], v[174:175], v[176:177]
	v_pk_add_f32 v[162:163], v[164:165], v[162:163]
	s_nop 0
	v_pk_add_f32 v[162:163], v[174:175], v[162:163]
	s_nop 0
	v_add_f32_e32 v162, v162, v163
	ds_bpermute_b32 v163, v91, v162
	s_waitcnt lgkmcnt(0)
	v_add_f32_e32 v162, v162, v163
	ds_bpermute_b32 v163, v167, v162
	s_waitcnt lgkmcnt(0)
	v_add_f32_e32 v162, v162, v163
	ds_bpermute_b32 v163, v168, v162
	s_waitcnt lgkmcnt(0)
	v_add_f32_e32 v162, v162, v163
	ds_bpermute_b32 v163, v169, v162
	s_waitcnt lgkmcnt(0)
	v_add_f32_e32 v162, v162, v163
	ds_bpermute_b32 v163, v170, v162
	s_waitcnt lgkmcnt(0)
	v_add_f32_e32 v162, v162, v163
	ds_bpermute_b32 v163, v171, v162
	s_waitcnt lgkmcnt(0)
	v_add_f32_e32 v174, v162, v163
	v_fmamk_f32 v162, v174, 0xba000000, v65
	v_fmamk_f32 v164, v174, 0xba000000, v63
	v_fmamk_f32 v163, v174, 0xba000000, v61
	v_fmamk_f32 v165, v174, 0xba000000, v59
	v_fmac_f32_e32 v58, 0xba000000, v174
	v_fmamk_f32 v64, v174, 0xba000000, v64
	v_fmac_f32_e32 v62, 0xba000000, v174
	v_fmamk_f32 v65, v174, 0xba000000, v60
	v_mov_b32_e32 v63, v58
	v_pk_mul_f32 v[60:61], v[164:165], v[164:165]
	v_pk_mul_f32 v[176:177], v[162:163], v[162:163]
	v_pk_fma_f32 v[60:61], v[62:63], v[62:63], v[60:61]
	v_pk_fma_f32 v[176:177], v[64:65], v[64:65], v[176:177]
	v_fmamk_f32 v57, v174, 0xba000000, v57
	v_pk_add_f32 v[60:61], v[60:61], v[176:177]
	v_fmamk_f32 v56, v174, 0xba000000, v56
	v_fmamk_f32 v55, v174, 0xba000000, v55
	v_fmac_f32_e32 v54, 0xba000000, v174
	v_pk_add_f32 v[60:61], v[60:61], v[60:61] op_sel_hi:[0,1]
	v_pk_mul_f32 v[176:177], v[56:57], v[56:57]
	v_pk_mul_f32 v[178:179], v[54:55], v[54:55]
	v_fmac_f32_e32 v50, 0xba000000, v174
	v_pk_mov_b32 v[180:181], v[178:179], v[176:177] op_sel:[1,0]
	v_mov_b32_e32 v179, v177
	v_fmamk_f32 v52, v174, 0xba000000, v52
	v_fmamk_f32 v51, v174, 0xba000000, v51
	v_mul_f32_e32 v60, v50, v50
	v_pk_add_f32 v[176:177], v[180:181], v[178:179]
	v_fmamk_f32 v53, v174, 0xba000000, v53
	v_pk_fma_f32 v[178:179], v[50:51], v[50:51], v[60:61] op_sel_hi:[1,1,0]
	v_mul_f32_e32 v60, v52, v52
	v_pk_add_f32 v[176:177], v[176:177], v[176:177] op_sel_hi:[0,1]
	v_pk_fma_f32 v[180:181], v[52:53], v[52:53], v[60:61] op_sel_hi:[1,1,0]
	v_fmamk_f32 v49, v174, 0xba000000, v49
	v_fmamk_f32 v48, v174, 0xba000000, v48
	v_fmamk_f32 v47, v174, 0xba000000, v47
	v_fmac_f32_e32 v46, 0xba000000, v174
	v_mul_f32_e32 v178, v46, v46
	v_mul_f32_e32 v180, v47, v47
	v_mul_f32_e32 v176, v48, v48
	v_mul_f32_e32 v60, v49, v49
	v_pk_add_f32 v[178:179], v[178:179], v[180:181]
	v_pk_add_f32 v[60:61], v[176:177], v[60:61]
	v_fmamk_f32 v45, v174, 0xba000000, v45
	v_pk_add_f32 v[60:61], v[178:179], v[60:61]
	v_fmamk_f32 v44, v174, 0xba000000, v44
	v_fmamk_f32 v43, v174, 0xba000000, v43
	v_fmac_f32_e32 v42, 0xba000000, v174
	v_pk_add_f32 v[60:61], v[60:61], v[60:61] op_sel_hi:[0,1]
	v_pk_mul_f32 v[176:177], v[44:45], v[44:45]
	v_pk_mul_f32 v[178:179], v[42:43], v[42:43]
	v_fmac_f32_e32 v38, 0xba000000, v174
	v_pk_mov_b32 v[180:181], v[178:179], v[176:177] op_sel:[1,0]
	v_mov_b32_e32 v179, v177
	v_fmamk_f32 v40, v174, 0xba000000, v40
	v_fmamk_f32 v39, v174, 0xba000000, v39
	v_mul_f32_e32 v60, v38, v38
	v_pk_add_f32 v[176:177], v[180:181], v[178:179]
	v_fmamk_f32 v41, v174, 0xba000000, v41
	v_pk_fma_f32 v[178:179], v[38:39], v[38:39], v[60:61] op_sel_hi:[1,1,0]
	v_mul_f32_e32 v60, v40, v40
	v_pk_add_f32 v[176:177], v[176:177], v[176:177] op_sel_hi:[0,1]
	v_pk_fma_f32 v[180:181], v[40:41], v[40:41], v[60:61] op_sel_hi:[1,1,0]
	v_fmamk_f32 v37, v174, 0xba000000, v37
	v_fmamk_f32 v36, v174, 0xba000000, v36
	v_fmamk_f32 v35, v174, 0xba000000, v35
	v_fmac_f32_e32 v34, 0xba000000, v174
	v_mul_f32_e32 v178, v34, v34
	v_mul_f32_e32 v180, v35, v35
	v_mul_f32_e32 v176, v36, v36
	v_mul_f32_e32 v60, v37, v37
	v_pk_add_f32 v[178:179], v[178:179], v[180:181]
	v_pk_add_f32 v[60:61], v[176:177], v[60:61]
	s_nop 0
	v_pk_add_f32 v[60:61], v[178:179], v[60:61]
	s_nop 0
	v_add_f32_e32 v59, v60, v61
	ds_bpermute_b32 v60, v91, v59
	s_waitcnt lgkmcnt(0)
; #define LAS __attribute__((address_space(3)))
; __device__ __forceinline__ unsigned cvt_pk_bf16(float lo, float hi) { f32x2_t f = {lo, hi}; bf16x2_t v = __builtin_convertvector(f, bf16x2_t); return __builtin_bit_cast(unsigned, v); }
; template <bool DO_LN, bool DO_H, bool DO_GATES, bool WRITE_X> ...
;     ...
;                 const float rstd = 1.0f / sqrtf(wave_sum(q, lane) * (1.0f / DM) + LN_EPS);
; #pragma unroll
;                 for (int i = 0; i < 8; ++i) v[i] = (v[i] - mu) * rstd;
;                 if (!WRITE_X && lane == 0) { float* st = (float*)(ws + WS_STATS) + (size_t)row * 2; st[0] = mu; st[1] = rstd; }
;             }
;             if (WRITE_X && !DO_H) {
; #pragma unroll
;                 for (int i = 0; i < 8; ++i) __builtin_nontemporal_store(v[i] * PA[i] + PB[i], (f32x4*)(xout + (size_t)row * DM + lane * 4 + i * 256));
;             }
;             if (DO_H) {
;                 float ga[8];
; #pragma unroll
;                 for (int gg = 0; gg < 8; ++gg) ga[gg] = 0.f;
; #pragma unroll
;                 for (int i = 0; i < 8; ++i) { const f32x4 h = v[i] * PA[i] + PB[i];
;                     u32x2 w; w.x = cvt_pk_bf16(h[0], h[1]); w.y = cvt_pk_bf16(h[2], h[3]);
;                     *(u32x2*)(H + (size_t)row * DM + lane * 4 + i * 256) = w;
;                     if (DO_GATES) {
; #pragma unroll
;                         for (int gg = 0; gg < 8; ++gg) { const f32x4 w4 = *(const LAS f32x4*)(wif + gg * 2048 + lane * 4 + i * 256); ga[gg] += (h[0] * w4[0] + h[1] * w4[1]) + (h[2] * w4[2] + h[3] * w4[3]); }
	v_add_f32_e32 v59, v59, v60
	ds_bpermute_b32 v60, v167, v59
	s_waitcnt lgkmcnt(0)
	v_add_f32_e32 v59, v59, v60
	ds_bpermute_b32 v60, v168, v59
	s_waitcnt lgkmcnt(0)
	v_add_f32_e32 v59, v59, v60
	ds_bpermute_b32 v60, v169, v59
	s_waitcnt lgkmcnt(0)
	v_add_f32_e32 v59, v59, v60
	ds_bpermute_b32 v60, v170, v59
	s_waitcnt lgkmcnt(0)
	v_add_f32_e32 v59, v59, v60
	ds_bpermute_b32 v60, v171, v59
	s_waitcnt lgkmcnt(0)
	v_add_f32_e32 v59, v59, v60
	v_fmamk_f32 v59, v59, 0x3a000000, v238
	v_mul_f32_e32 v60, 0x4f800000, v59
	v_cmp_gt_f32_e32 vcc, s84, v59
	s_nop 1
	v_cndmask_b32_e32 v59, v59, v60, vcc
	v_sqrt_f32_e32 v60, v59
	s_nop 0
	v_add_u32_e32 v61, -1, v60
	v_fma_f32 v63, -v61, v60, v59
	v_cmp_ge_f32_e64 s[2:3], 0, v63
	v_add_u32_e32 v63, 1, v60
	s_nop 0
	v_cndmask_b32_e64 v61, v60, v61, s[2:3]
	v_fma_f32 v60, -v63, v60, v59
	v_cmp_lt_f32_e64 s[2:3], 0, v60
	s_nop 1
	v_cndmask_b32_e64 v60, v61, v63, s[2:3]
	v_mul_f32_e32 v61, 0x37800000, v60
	v_cndmask_b32_e32 v60, v60, v61, vcc
	v_cmp_class_f32_e32 vcc, v59, v239
	s_nop 1
	v_cndmask_b32_e32 v59, v60, v59, vcc
	v_div_scale_f32 v60, s[2:3], v59, v59, 1.0
	v_rcp_f32_e32 v61, v60
	s_nop 0
	v_fma_f32 v63, -v60, v61, 1.0
	v_fmac_f32_e32 v61, v63, v61
	v_div_scale_f32 v63, vcc, 1.0, v59, 1.0
	v_mul_f32_e32 v166, v63, v61
	v_fma_f32 v175, -v60, v166, v63
	v_fmac_f32_e32 v166, v175, v61
	v_fma_f32 v60, -v60, v166, v63
	v_div_fmas_f32 v60, v60, v61, v166
	v_div_fixup_f32 v166, v60, v59, 1.0
	s_and_saveexec_b64 s[2:3], s[0:1]
	s_cbranch_execz .LBB0_740
	v_mul_f32_e32 v60, 0x3a000000, v174
	v_lshl_add_u64 v[174:175], s[4:5], 0, v[156:157]
	v_mov_b32_e32 v61, v166
	global_store_dwordx2 v[174:175], v[60:61], off
.LBB0_740:
	s_or_b64 exec, exec, s[2:3]
	v_mov_b32_e32 v63, v164
	v_mov_b32_e32 v59, v165
	v_mov_b32_e32 v60, v64
	v_mov_b32_e32 v61, v162
	v_pk_mul_f32 v[164:165], v[60:61], v[166:167] op_sel_hi:[1,0]
	v_pk_mul_f32 v[174:175], v[62:63], v[166:167] op_sel_hi:[1,0]
	v_mov_b32_e32 v162, v65
	v_pk_mul_f32 v[62:63], v[58:59], v[166:167] op_sel_hi:[1,0]
	v_pk_mul_f32 v[58:59], v[54:55], v[166:167] op_sel_hi:[1,0]
	v_pk_mul_f32 v[54:55], v[50:51], v[166:167] op_sel_hi:[1,0]
	v_pk_mul_f32 v[50:51], v[46:47], v[166:167] op_sel_hi:[1,0]
	v_pk_mul_f32 v[46:47], v[42:43], v[166:167] op_sel_hi:[1,0]
	v_pk_mul_f32 v[42:43], v[38:39], v[166:167] op_sel_hi:[1,0]
	v_lshl_add_u64 v[38:39], s[4:5], 0, v[160:161]
	v_pk_mul_f32 v[60:61], v[162:163], v[166:167] op_sel_hi:[1,0]
	v_pk_fma_f32 v[64:65], v[92:93], v[164:165], v[96:97]
	v_pk_fma_f32 v[162:163], v[94:95], v[174:175], v[98:99]
	v_add_co_u32_e32 v38, vcc, s85, v38
	v_cvt_pk_bf16_f32 v164, v162, v163
	v_cvt_pk_bf16_f32 v165, v64, v65
	v_addc_co_u32_e32 v39, vcc, 0, v39, vcc
	global_store_dwordx2 v[38:39], v[164:165], off
	ds_read_b128 v[174:177], v172
	v_pk_mul_f32 v[56:57], v[56:57], v[166:167] op_sel_hi:[1,0]
	v_pk_mul_f32 v[52:53], v[52:53], v[166:167] op_sel_hi:[1,0]
	v_pk_mul_f32 v[48:49], v[48:49], v[166:167] op_sel_hi:[1,0]
	v_pk_mul_f32 v[44:45], v[44:45], v[166:167] op_sel_hi:[1,0]
	s_waitcnt lgkmcnt(0)
	v_mul_f32_e32 v164, v163, v175
	v_mul_f32_e32 v165, v65, v177
	v_fmac_f32_e32 v164, v162, v174
	v_fmac_f32_e32 v165, v64, v176
	ds_read_b128 v[174:177], v172 offset:8192
	v_add_f32_e32 v164, v164, v165
	v_pk_mul_f32 v[40:41], v[40:41], v[166:167] op_sel_hi:[1,0]
	v_pk_mul_f32 v[36:37], v[36:37], v[166:167] op_sel_hi:[1,0]
	v_pk_mul_f32 v[34:35], v[34:35], v[166:167] op_sel_hi:[1,0]
	v_add_f32_e32 v166, 0, v164
	s_waitcnt lgkmcnt(0)
	v_mul_f32_e32 v164, v163, v175
	v_mul_f32_e32 v165, v65, v177
	v_fmac_f32_e32 v164, v162, v174
	v_fmac_f32_e32 v165, v64, v176
	ds_read_b128 v[174:177], v172 offset:16384
	v_add_f32_e32 v164, v164, v165
	v_add_f32_e32 v178, 0, v164
	v_pk_fma_f32 v[60:61], v[100:101], v[60:61], v[104:105]
	v_pk_fma_f32 v[62:63], v[102:103], v[62:63], v[106:107]
	s_waitcnt lgkmcnt(0)
	v_mul_f32_e32 v164, v163, v175
	v_mul_f32_e32 v165, v65, v177
	v_fmac_f32_e32 v164, v162, v174
	v_fmac_f32_e32 v165, v64, v176
	ds_read_b128 v[174:177], v172 offset:24576
	v_add_f32_e32 v164, v164, v165
	v_add_f32_e32 v179, 0, v164
	v_pk_fma_f32 v[56:57], v[108:109], v[56:57], v[112:113]
	v_pk_fma_f32 v[58:59], v[110:111], v[58:59], v[114:115]
	s_waitcnt lgkmcnt(0)
	v_mul_f32_e32 v164, v163, v175
	v_mul_f32_e32 v165, v65, v177
	v_fmac_f32_e32 v164, v162, v174
	v_fmac_f32_e32 v165, v64, v176
	ds_read_b128 v[174:177], v172 offset:32768
	v_add_f32_e32 v164, v164, v165
	v_add_f32_e32 v180, 0, v164
	v_pk_fma_f32 v[52:53], v[116:117], v[52:53], v[120:121]
	v_pk_fma_f32 v[54:55], v[118:119], v[54:55], v[122:123]
	s_waitcnt lgkmcnt(0)
	v_mul_f32_e32 v164, v163, v175
	v_mul_f32_e32 v165, v65, v177
	v_fmac_f32_e32 v164, v162, v174
	v_fmac_f32_e32 v165, v64, v176
	ds_read_b128 v[174:177], v172 offset:40960
	v_add_f32_e32 v164, v164, v165
	v_add_f32_e32 v181, 0, v164
	v_pk_fma_f32 v[48:49], v[124:125], v[48:49], v[128:129]
	v_pk_fma_f32 v[50:51], v[126:127], v[50:51], v[130:131]
	s_waitcnt lgkmcnt(0)
	v_mul_f32_e32 v164, v163, v175
	v_mul_f32_e32 v165, v65, v177
	v_fmac_f32_e32 v164, v162, v174
	v_fmac_f32_e32 v165, v64, v176
	ds_read_b128 v[174:177], v172 offset:49152
	v_add_f32_e32 v164, v164, v165
	v_add_f32_e32 v182, 0, v164
	v_pk_fma_f32 v[44:45], v[132:133], v[44:45], v[136:137]
	v_pk_fma_f32 v[46:47], v[134:135], v[46:47], v[138:139]
	s_waitcnt lgkmcnt(0)
	v_mul_f32_e32 v164, v163, v175
	v_mul_f32_e32 v165, v65, v177
	v_fmac_f32_e32 v164, v162, v174
	v_fmac_f32_e32 v165, v64, v176
	ds_read_b128 v[174:177], v172 offset:57344
	v_add_f32_e32 v164, v164, v165
	v_add_f32_e32 v183, 0, v164
	v_pk_fma_f32 v[40:41], v[140:141], v[40:41], v[144:145]
	v_pk_fma_f32 v[42:43], v[142:143], v[42:43], v[146:147]
	s_waitcnt lgkmcnt(0)
; #define LAS __attribute__((address_space(3)))
; __device__ __forceinline__ unsigned cvt_pk_bf16(float lo, float hi) { f32x2_t f = {lo, hi}; bf16x2_t v = __builtin_convertvector(f, bf16x2_t); return __builtin_bit_cast(unsigned, v); }
; template <bool DO_LN, bool DO_H, bool DO_GATES, bool WRITE_X> ...
;     ...
;                 for (int i = 0; i < 8; ++i) { const f32x4 h = v[i] * PA[i] + PB[i];
;                     u32x2 w; w.x = cvt_pk_bf16(h[0], h[1]); w.y = cvt_pk_bf16(h[2], h[3]);
;                     *(u32x2*)(H + (size_t)row * DM + lane * 4 + i * 256) = w;
;                     if (DO_GATES) {
; #pragma unroll
;                         for (int gg = 0; gg < 8; ++gg) { const f32x4 w4 = *(const LAS f32x4*)(wif + gg * 2048 + lane * 4 + i * 256); ga[gg] += (h[0] * w4[0] + h[1] * w4[1]) + (h[2] * w4[2] + h[3] * w4[3]); }
	v_mul_f32_e32 v163, v163, v175
	v_mul_f32_e32 v65, v65, v177
	v_fmac_f32_e32 v163, v162, v174
	v_fmac_f32_e32 v65, v64, v176
	v_add_f32_e32 v64, v163, v65
	v_add_f32_e32 v174, 0, v64
	v_cvt_pk_bf16_f32 v64, v62, v63
	v_cvt_pk_bf16_f32 v65, v60, v61
	global_store_dwordx2 v[38:39], v[64:65], off offset:512
	ds_read_b128 v[162:165], v172 offset:1024
	v_pk_fma_f32 v[36:37], v[148:149], v[36:37], v[152:153]
	v_pk_fma_f32 v[34:35], v[150:151], v[34:35], v[154:155]
	s_waitcnt lgkmcnt(0)
	v_mul_f32_e32 v64, v63, v163
	v_mul_f32_e32 v65, v61, v165
	v_fmac_f32_e32 v64, v62, v162
	v_fmac_f32_e32 v65, v60, v164
	ds_read_b128 v[162:165], v172 offset:9216
	v_add_f32_e32 v64, v64, v65
	v_add_f32_e32 v64, v166, v64
	s_waitcnt lgkmcnt(0)
	v_mul_f32_e32 v65, v63, v163
	v_fmac_f32_e32 v65, v62, v162
	v_mul_f32_e32 v162, v61, v165
	v_fmac_f32_e32 v162, v60, v164
	v_add_f32_e32 v65, v65, v162
	ds_read_b128 v[162:165], v172 offset:17408
	v_add_f32_e32 v65, v178, v65
	s_waitcnt lgkmcnt(0)
	v_mul_f32_e32 v163, v63, v163
	v_fmac_f32_e32 v163, v62, v162
	v_mul_f32_e32 v162, v61, v165
	v_fmac_f32_e32 v162, v60, v164
	v_add_f32_e32 v162, v163, v162
	v_add_f32_e32 v166, v179, v162
	ds_read_b128 v[162:165], v172 offset:25600
	s_waitcnt lgkmcnt(0)
	v_mul_f32_e32 v163, v63, v163
	v_fmac_f32_e32 v163, v62, v162
	v_mul_f32_e32 v162, v61, v165
	v_fmac_f32_e32 v162, v60, v164
	v_add_f32_e32 v162, v163, v162
	v_add_f32_e32 v175, v180, v162
	ds_read_b128 v[162:165], v172 offset:33792
	s_waitcnt lgkmcnt(0)
	v_mul_f32_e32 v163, v63, v163
	v_fmac_f32_e32 v163, v62, v162
	v_mul_f32_e32 v162, v61, v165
	v_fmac_f32_e32 v162, v60, v164
	v_add_f32_e32 v162, v163, v162
	v_add_f32_e32 v176, v181, v162
	ds_read_b128 v[162:165], v172 offset:41984
	s_waitcnt lgkmcnt(0)
	v_mul_f32_e32 v163, v63, v163
	v_fmac_f32_e32 v163, v62, v162
	v_mul_f32_e32 v162, v61, v165
	v_fmac_f32_e32 v162, v60, v164
	v_add_f32_e32 v162, v163, v162
	v_add_f32_e32 v177, v182, v162
	ds_read_b128 v[162:165], v172 offset:50176
	s_waitcnt lgkmcnt(0)
	v_mul_f32_e32 v163, v63, v163
	v_fmac_f32_e32 v163, v62, v162
	v_mul_f32_e32 v162, v61, v165
	v_fmac_f32_e32 v162, v60, v164
	v_add_f32_e32 v162, v163, v162
	v_add_f32_e32 v178, v183, v162
	ds_read_b128 v[162:165], v172 offset:58368
	s_waitcnt lgkmcnt(0)
	v_mul_f32_e32 v63, v63, v163
	v_mul_f32_e32 v61, v61, v165
	v_fmac_f32_e32 v63, v62, v162
	v_fmac_f32_e32 v61, v60, v164
	v_add_f32_e32 v60, v63, v61
	v_add_f32_e32 v162, v174, v60
	v_cvt_pk_bf16_f32 v60, v58, v59
	v_cvt_pk_bf16_f32 v61, v56, v57
	global_store_dwordx2 v[38:39], v[60:61], off offset:1024
	ds_read_b128 v[60:63], v172 offset:2048
	s_waitcnt lgkmcnt(0)
	v_mul_f32_e32 v61, v59, v61
	v_fmac_f32_e32 v61, v58, v60
	v_mul_f32_e32 v60, v57, v63
	v_fmac_f32_e32 v60, v56, v62
	v_add_f32_e32 v60, v61, v60
	v_add_f32_e32 v64, v64, v60
	ds_read_b128 v[60:63], v172 offset:10240
	s_waitcnt lgkmcnt(0)
	v_mul_f32_e32 v61, v59, v61
	v_fmac_f32_e32 v61, v58, v60
	v_mul_f32_e32 v60, v57, v63
	v_fmac_f32_e32 v60, v56, v62
	v_add_f32_e32 v60, v61, v60
	v_add_f32_e32 v65, v65, v60
	ds_read_b128 v[60:63], v172 offset:18432
	s_waitcnt lgkmcnt(0)
	v_mul_f32_e32 v61, v59, v61
	v_fmac_f32_e32 v61, v58, v60
	v_mul_f32_e32 v60, v57, v63
	v_fmac_f32_e32 v60, v56, v62
	v_add_f32_e32 v60, v61, v60
	v_add_f32_e32 v163, v166, v60
	ds_read_b128 v[60:63], v172 offset:26624
	s_waitcnt lgkmcnt(0)
	v_mul_f32_e32 v61, v59, v61
	v_fmac_f32_e32 v61, v58, v60
	v_mul_f32_e32 v60, v57, v63
	v_fmac_f32_e32 v60, v56, v62
	v_add_f32_e32 v60, v61, v60
	v_add_f32_e32 v164, v175, v60
	ds_read_b128 v[60:63], v172 offset:34816
	s_waitcnt lgkmcnt(0)
	v_mul_f32_e32 v61, v59, v61
	v_fmac_f32_e32 v61, v58, v60
	v_mul_f32_e32 v60, v57, v63
	v_fmac_f32_e32 v60, v56, v62
	v_add_f32_e32 v60, v61, v60
	v_add_f32_e32 v165, v176, v60
	ds_read_b128 v[60:63], v172 offset:43008
	s_waitcnt lgkmcnt(0)
	v_mul_f32_e32 v61, v59, v61
	v_fmac_f32_e32 v61, v58, v60
	v_mul_f32_e32 v60, v57, v63
	v_fmac_f32_e32 v60, v56, v62
	v_add_f32_e32 v60, v61, v60
	v_add_f32_e32 v166, v177, v60
	ds_read_b128 v[60:63], v172 offset:51200
	s_waitcnt lgkmcnt(0)
	v_mul_f32_e32 v61, v59, v61
	v_fmac_f32_e32 v61, v58, v60
	v_mul_f32_e32 v60, v57, v63
	v_fmac_f32_e32 v60, v56, v62
	v_add_f32_e32 v60, v61, v60
	v_add_f32_e32 v174, v178, v60
	ds_read_b128 v[60:63], v172 offset:59392
	s_waitcnt lgkmcnt(0)
	v_mul_f32_e32 v59, v59, v61
	v_mul_f32_e32 v57, v57, v63
	v_fmac_f32_e32 v59, v58, v60
	v_fmac_f32_e32 v57, v56, v62
	v_add_f32_e32 v56, v59, v57
	v_add_f32_e32 v60, v162, v56
	v_cvt_pk_bf16_f32 v56, v54, v55
	v_cvt_pk_bf16_f32 v57, v52, v53
	global_store_dwordx2 v[38:39], v[56:57], off offset:1536
	ds_read_b128 v[56:59], v172 offset:3072
	s_waitcnt lgkmcnt(0)
	v_mul_f32_e32 v57, v55, v57
	v_fmac_f32_e32 v57, v54, v56
	v_mul_f32_e32 v56, v53, v59
	v_fmac_f32_e32 v56, v52, v58
	v_add_f32_e32 v56, v57, v56
	v_add_f32_e32 v61, v64, v56
	ds_read_b128 v[56:59], v172 offset:11264
	s_waitcnt lgkmcnt(0)
	v_mul_f32_e32 v57, v55, v57
	v_fmac_f32_e32 v57, v54, v56
	v_mul_f32_e32 v56, v53, v59
	v_fmac_f32_e32 v56, v52, v58
	v_add_f32_e32 v56, v57, v56
	v_add_f32_e32 v62, v65, v56
	ds_read_b128 v[56:59], v172 offset:19456
	s_waitcnt lgkmcnt(0)
	v_mul_f32_e32 v57, v55, v57
	v_fmac_f32_e32 v57, v54, v56
	v_mul_f32_e32 v56, v53, v59
	v_fmac_f32_e32 v56, v52, v58
	v_add_f32_e32 v56, v57, v56
	v_add_f32_e32 v63, v163, v56
	ds_read_b128 v[56:59], v172 offset:27648
	s_waitcnt lgkmcnt(0)
	v_mul_f32_e32 v57, v55, v57
	v_fmac_f32_e32 v57, v54, v56
	v_mul_f32_e32 v56, v53, v59
	v_fmac_f32_e32 v56, v52, v58
	v_add_f32_e32 v56, v57, v56
	v_add_f32_e32 v64, v164, v56
	ds_read_b128 v[56:59], v172 offset:35840
	s_waitcnt lgkmcnt(0)
; #define LAS __attribute__((address_space(3)))
; __device__ __forceinline__ unsigned cvt_pk_bf16(float lo, float hi) { f32x2_t f = {lo, hi}; bf16x2_t v = __builtin_convertvector(f, bf16x2_t); return __builtin_bit_cast(unsigned, v); }
; template <bool DO_LN, bool DO_H, bool DO_GATES, bool WRITE_X> ...
;     ...
;                 for (int i = 0; i < 8; ++i) { const f32x4 h = v[i] * PA[i] + PB[i];
;                     u32x2 w; w.x = cvt_pk_bf16(h[0], h[1]); w.y = cvt_pk_bf16(h[2], h[3]);
;                     *(u32x2*)(H + (size_t)row * DM + lane * 4 + i * 256) = w;
;                     if (DO_GATES) {
; #pragma unroll
;                         for (int gg = 0; gg < 8; ++gg) { const f32x4 w4 = *(const LAS f32x4*)(wif + gg * 2048 + lane * 4 + i * 256); ga[gg] += (h[0] * w4[0] + h[1] * w4[1]) + (h[2] * w4[2] + h[3] * w4[3]); }
	v_mul_f32_e32 v57, v55, v57
	v_fmac_f32_e32 v57, v54, v56
	v_mul_f32_e32 v56, v53, v59
	v_fmac_f32_e32 v56, v52, v58
	v_add_f32_e32 v56, v57, v56
	v_add_f32_e32 v65, v165, v56
	ds_read_b128 v[56:59], v172 offset:44032
	s_waitcnt lgkmcnt(0)
	v_mul_f32_e32 v57, v55, v57
	v_fmac_f32_e32 v57, v54, v56
	v_mul_f32_e32 v56, v53, v59
	v_fmac_f32_e32 v56, v52, v58
	v_add_f32_e32 v56, v57, v56
	v_add_f32_e32 v162, v166, v56
	ds_read_b128 v[56:59], v172 offset:52224
	s_waitcnt lgkmcnt(0)
	v_mul_f32_e32 v57, v55, v57
	v_fmac_f32_e32 v57, v54, v56
	v_mul_f32_e32 v56, v53, v59
	v_fmac_f32_e32 v56, v52, v58
	v_add_f32_e32 v56, v57, v56
	v_add_f32_e32 v163, v174, v56
	ds_read_b128 v[56:59], v172 offset:60416
	s_waitcnt lgkmcnt(0)
	v_mul_f32_e32 v55, v55, v57
	v_mul_f32_e32 v53, v53, v59
	v_fmac_f32_e32 v55, v54, v56
	v_fmac_f32_e32 v53, v52, v58
	v_add_f32_e32 v52, v55, v53
	v_add_f32_e32 v56, v60, v52
	v_cvt_pk_bf16_f32 v52, v50, v51
	v_cvt_pk_bf16_f32 v53, v48, v49
	global_store_dwordx2 v[38:39], v[52:53], off offset:2048
	ds_read_b128 v[52:55], v172 offset:4096
	s_waitcnt lgkmcnt(0)
	v_mul_f32_e32 v53, v51, v53
	v_fmac_f32_e32 v53, v50, v52
	v_mul_f32_e32 v52, v49, v55
	v_fmac_f32_e32 v52, v48, v54
	v_add_f32_e32 v52, v53, v52
	v_add_f32_e32 v57, v61, v52
	ds_read_b128 v[52:55], v172 offset:12288
	s_waitcnt lgkmcnt(0)
	v_mul_f32_e32 v53, v51, v53
	v_fmac_f32_e32 v53, v50, v52
	v_mul_f32_e32 v52, v49, v55
	v_fmac_f32_e32 v52, v48, v54
	v_add_f32_e32 v52, v53, v52
	v_add_f32_e32 v58, v62, v52
	ds_read_b128 v[52:55], v172 offset:20480
	s_waitcnt lgkmcnt(0)
	v_mul_f32_e32 v53, v51, v53
	v_fmac_f32_e32 v53, v50, v52
	v_mul_f32_e32 v52, v49, v55
	v_fmac_f32_e32 v52, v48, v54
	v_add_f32_e32 v52, v53, v52
	v_add_f32_e32 v59, v63, v52
	ds_read_b128 v[52:55], v172 offset:28672
	s_waitcnt lgkmcnt(0)
	v_mul_f32_e32 v53, v51, v53
	v_fmac_f32_e32 v53, v50, v52
	v_mul_f32_e32 v52, v49, v55
	v_fmac_f32_e32 v52, v48, v54
	v_add_f32_e32 v52, v53, v52
	v_add_f32_e32 v60, v64, v52
	ds_read_b128 v[52:55], v172 offset:36864
	s_waitcnt lgkmcnt(0)
	v_mul_f32_e32 v53, v51, v53
	v_fmac_f32_e32 v53, v50, v52
	v_mul_f32_e32 v52, v49, v55
	v_fmac_f32_e32 v52, v48, v54
	v_add_f32_e32 v52, v53, v52
	v_add_f32_e32 v61, v65, v52
	ds_read_b128 v[52:55], v172 offset:45056
	s_waitcnt lgkmcnt(0)
	v_mul_f32_e32 v53, v51, v53
	v_fmac_f32_e32 v53, v50, v52
	v_mul_f32_e32 v52, v49, v55
	v_fmac_f32_e32 v52, v48, v54
	v_add_f32_e32 v52, v53, v52
	v_add_f32_e32 v62, v162, v52
	ds_read_b128 v[52:55], v172 offset:53248
	s_waitcnt lgkmcnt(0)
	v_mul_f32_e32 v53, v51, v53
	v_fmac_f32_e32 v53, v50, v52
	v_mul_f32_e32 v52, v49, v55
	v_fmac_f32_e32 v52, v48, v54
	v_add_f32_e32 v52, v53, v52
	v_add_f32_e32 v63, v163, v52
	ds_read_b128 v[52:55], v172 offset:61440
	s_waitcnt lgkmcnt(0)
	v_mul_f32_e32 v51, v51, v53
	v_mul_f32_e32 v49, v49, v55
	v_fmac_f32_e32 v51, v50, v52
	v_fmac_f32_e32 v49, v48, v54
	v_add_f32_e32 v48, v51, v49
	v_add_f32_e32 v52, v56, v48
	v_cvt_pk_bf16_f32 v48, v46, v47
	v_cvt_pk_bf16_f32 v49, v44, v45
	global_store_dwordx2 v[38:39], v[48:49], off offset:2560
	ds_read_b128 v[48:51], v172 offset:5120
	s_waitcnt lgkmcnt(0)
	v_mul_f32_e32 v49, v47, v49
	v_fmac_f32_e32 v49, v46, v48
	v_mul_f32_e32 v48, v45, v51
	v_fmac_f32_e32 v48, v44, v50
	v_add_f32_e32 v48, v49, v48
	v_add_f32_e32 v53, v57, v48
	ds_read_b128 v[48:51], v172 offset:13312
	s_waitcnt lgkmcnt(0)
	v_mul_f32_e32 v49, v47, v49
	v_fmac_f32_e32 v49, v46, v48
	v_mul_f32_e32 v48, v45, v51
	v_fmac_f32_e32 v48, v44, v50
	v_add_f32_e32 v48, v49, v48
	v_add_f32_e32 v54, v58, v48
	ds_read_b128 v[48:51], v172 offset:21504
	s_waitcnt lgkmcnt(0)
	v_mul_f32_e32 v49, v47, v49
	v_fmac_f32_e32 v49, v46, v48
	v_mul_f32_e32 v48, v45, v51
	v_fmac_f32_e32 v48, v44, v50
	v_add_f32_e32 v48, v49, v48
	v_add_f32_e32 v55, v59, v48
	ds_read_b128 v[48:51], v172 offset:29696
	s_waitcnt lgkmcnt(0)
	v_mul_f32_e32 v49, v47, v49
	v_fmac_f32_e32 v49, v46, v48
	v_mul_f32_e32 v48, v45, v51
	v_fmac_f32_e32 v48, v44, v50
	v_add_f32_e32 v48, v49, v48
	v_add_f32_e32 v56, v60, v48
	ds_read_b128 v[48:51], v172 offset:37888
	s_waitcnt lgkmcnt(0)
	v_mul_f32_e32 v49, v47, v49
	v_fmac_f32_e32 v49, v46, v48
	v_mul_f32_e32 v48, v45, v51
	v_fmac_f32_e32 v48, v44, v50
	v_add_f32_e32 v48, v49, v48
	v_add_f32_e32 v57, v61, v48
	ds_read_b128 v[48:51], v172 offset:46080
	s_waitcnt lgkmcnt(0)
	v_mul_f32_e32 v49, v47, v49
	v_fmac_f32_e32 v49, v46, v48
	v_mul_f32_e32 v48, v45, v51
	v_fmac_f32_e32 v48, v44, v50
	v_add_f32_e32 v48, v49, v48
	v_add_f32_e32 v58, v62, v48
	ds_read_b128 v[48:51], v172 offset:54272
	s_waitcnt lgkmcnt(0)
	v_mul_f32_e32 v49, v47, v49
	v_fmac_f32_e32 v49, v46, v48
	v_mul_f32_e32 v48, v45, v51
	v_fmac_f32_e32 v48, v44, v50
	v_add_f32_e32 v48, v49, v48
	v_add_f32_e32 v59, v63, v48
	ds_read_b128 v[48:51], v172 offset:62464
	s_waitcnt lgkmcnt(0)
	v_mul_f32_e32 v47, v47, v49
	v_mul_f32_e32 v45, v45, v51
	v_fmac_f32_e32 v47, v46, v48
	v_fmac_f32_e32 v45, v44, v50
	v_add_f32_e32 v44, v47, v45
	v_add_f32_e32 v48, v52, v44
	v_cvt_pk_bf16_f32 v44, v42, v43
	v_cvt_pk_bf16_f32 v45, v40, v41
	global_store_dwordx2 v[38:39], v[44:45], off offset:3072
	ds_read_b128 v[44:47], v172 offset:6144
	s_waitcnt lgkmcnt(0)
	v_mul_f32_e32 v45, v43, v45
	v_fmac_f32_e32 v45, v42, v44
	v_mul_f32_e32 v44, v41, v47
	v_fmac_f32_e32 v44, v40, v46
	v_add_f32_e32 v44, v45, v44
	v_add_f32_e32 v49, v53, v44
	ds_read_b128 v[44:47], v172 offset:14336
	s_waitcnt lgkmcnt(0)
	v_mul_f32_e32 v45, v43, v45
	v_fmac_f32_e32 v45, v42, v44
	v_mul_f32_e32 v44, v41, v47
	v_fmac_f32_e32 v44, v40, v46
	v_add_f32_e32 v44, v45, v44
	v_add_f32_e32 v50, v54, v44
	ds_read_b128 v[44:47], v172 offset:22528
	s_waitcnt lgkmcnt(0)
; #define LAS __attribute__((address_space(3)))
; __device__ __forceinline__ unsigned cvt_pk_bf16(float lo, float hi) { f32x2_t f = {lo, hi}; bf16x2_t v = __builtin_convertvector(f, bf16x2_t); return __builtin_bit_cast(unsigned, v); }
; template <bool DO_LN, bool DO_H, bool DO_GATES, bool WRITE_X> ...
;     ...
;                 for (int i = 0; i < 8; ++i) { const f32x4 h = v[i] * PA[i] + PB[i];
;                     u32x2 w; w.x = cvt_pk_bf16(h[0], h[1]); w.y = cvt_pk_bf16(h[2], h[3]);
;                     *(u32x2*)(H + (size_t)row * DM + lane * 4 + i * 256) = w;
;                     if (DO_GATES) {
; #pragma unroll
;                         for (int gg = 0; gg < 8; ++gg) { const f32x4 w4 = *(const LAS f32x4*)(wif + gg * 2048 + lane * 4 + i * 256); ga[gg] += (h[0] * w4[0] + h[1] * w4[1]) + (h[2] * w4[2] + h[3] * w4[3]); }
;                     } }
;                 if (DO_GATES) {
; #pragma unroll
;                     for (int gg = 0; gg < 8; ++gg) ga[gg] = wave_sum(ga[gg], lane);
	v_mul_f32_e32 v45, v43, v45
	v_fmac_f32_e32 v45, v42, v44
	v_mul_f32_e32 v44, v41, v47
	v_fmac_f32_e32 v44, v40, v46
	v_add_f32_e32 v44, v45, v44
	v_add_f32_e32 v51, v55, v44
	ds_read_b128 v[44:47], v172 offset:30720
	s_waitcnt lgkmcnt(0)
	v_mul_f32_e32 v45, v43, v45
	v_fmac_f32_e32 v45, v42, v44
	v_mul_f32_e32 v44, v41, v47
	v_fmac_f32_e32 v44, v40, v46
	v_add_f32_e32 v44, v45, v44
	v_add_f32_e32 v52, v56, v44
	ds_read_b128 v[44:47], v172 offset:38912
	s_waitcnt lgkmcnt(0)
	v_mul_f32_e32 v45, v43, v45
	v_fmac_f32_e32 v45, v42, v44
	v_mul_f32_e32 v44, v41, v47
	v_fmac_f32_e32 v44, v40, v46
	v_add_f32_e32 v44, v45, v44
	v_add_f32_e32 v53, v57, v44
	ds_read_b128 v[44:47], v172 offset:47104
	s_waitcnt lgkmcnt(0)
	v_mul_f32_e32 v45, v43, v45
	v_fmac_f32_e32 v45, v42, v44
	v_mul_f32_e32 v44, v41, v47
	v_fmac_f32_e32 v44, v40, v46
	v_add_f32_e32 v44, v45, v44
	v_add_f32_e32 v54, v58, v44
	ds_read_b128 v[44:47], v172 offset:55296
	s_waitcnt lgkmcnt(0)
	v_mul_f32_e32 v45, v43, v45
	v_fmac_f32_e32 v45, v42, v44
	v_mul_f32_e32 v44, v41, v47
	v_fmac_f32_e32 v44, v40, v46
	v_add_f32_e32 v44, v45, v44
	v_add_f32_e32 v55, v59, v44
	ds_read_b128 v[44:47], v172 offset:63488
	s_waitcnt lgkmcnt(0)
	v_mul_f32_e32 v43, v43, v45
	v_mul_f32_e32 v41, v41, v47
	v_fmac_f32_e32 v43, v42, v44
	v_fmac_f32_e32 v41, v40, v46
	v_add_f32_e32 v40, v43, v41
	v_add_f32_e32 v42, v48, v40
	v_cvt_pk_bf16_f32 v40, v34, v35
	v_cvt_pk_bf16_f32 v41, v36, v37
	global_store_dwordx2 v[38:39], v[40:41], off offset:3584
	ds_read_b128 v[38:41], v172 offset:7168
	s_waitcnt lgkmcnt(0)
	v_mul_f32_e32 v39, v35, v39
	v_fmac_f32_e32 v39, v34, v38
	v_mul_f32_e32 v38, v37, v41
	v_fmac_f32_e32 v38, v36, v40
	v_add_f32_e32 v38, v39, v38
	v_add_f32_e32 v43, v49, v38
	ds_read_b128 v[38:41], v172 offset:15360
	s_waitcnt lgkmcnt(0)
	v_mul_f32_e32 v39, v35, v39
	v_fmac_f32_e32 v39, v34, v38
	v_mul_f32_e32 v38, v37, v41
	v_fmac_f32_e32 v38, v36, v40
	v_add_f32_e32 v38, v39, v38
	v_add_f32_e32 v44, v50, v38
	ds_read_b128 v[38:41], v172 offset:23552
	s_waitcnt lgkmcnt(0)
	v_mul_f32_e32 v39, v35, v39
	v_fmac_f32_e32 v39, v34, v38
	v_mul_f32_e32 v38, v37, v41
	v_fmac_f32_e32 v38, v36, v40
	v_add_f32_e32 v38, v39, v38
	v_add_f32_e32 v45, v51, v38
	ds_read_b128 v[38:41], v172 offset:31744
	s_waitcnt lgkmcnt(0)
	v_mul_f32_e32 v39, v35, v39
	v_fmac_f32_e32 v39, v34, v38
	v_mul_f32_e32 v38, v37, v41
	v_fmac_f32_e32 v38, v36, v40
	v_add_f32_e32 v38, v39, v38
	v_add_f32_e32 v46, v52, v38
	ds_read_b128 v[38:41], v172 offset:39936
	s_waitcnt lgkmcnt(0)
	v_mul_f32_e32 v39, v35, v39
	v_fmac_f32_e32 v39, v34, v38
	v_mul_f32_e32 v38, v37, v41
	v_fmac_f32_e32 v38, v36, v40
	v_add_f32_e32 v38, v39, v38
	v_add_f32_e32 v47, v53, v38
	ds_read_b128 v[38:41], v172 offset:48128
	s_waitcnt lgkmcnt(0)
	v_mul_f32_e32 v39, v35, v39
	v_fmac_f32_e32 v39, v34, v38
	v_mul_f32_e32 v38, v37, v41
	v_fmac_f32_e32 v38, v36, v40
	v_add_f32_e32 v38, v39, v38
	v_add_f32_e32 v48, v54, v38
	ds_read_b128 v[38:41], v172 offset:56320
	s_waitcnt lgkmcnt(0)
	v_mul_f32_e32 v39, v35, v39
	v_fmac_f32_e32 v39, v34, v38
	v_mul_f32_e32 v38, v37, v41
	v_fmac_f32_e32 v38, v36, v40
	v_add_f32_e32 v38, v39, v38
	v_add_f32_e32 v49, v55, v38
	ds_read_b128 v[38:41], v172 offset:64512
	s_waitcnt lgkmcnt(0)
	v_mul_f32_e32 v35, v35, v39
	v_fmac_f32_e32 v35, v34, v38
	v_mul_f32_e32 v34, v37, v41
	v_fmac_f32_e32 v34, v36, v40
	v_add_f32_e32 v34, v35, v34
	v_add_f32_e32 v36, v42, v34
	ds_bpermute_b32 v34, v91, v43
	ds_bpermute_b32 v39, v91, v45
	ds_bpermute_b32 v37, v91, v44
	ds_bpermute_b32 v41, v91, v46
	s_waitcnt lgkmcnt(0)
	v_add_f32_e32 v34, v43, v34
	ds_bpermute_b32 v43, v91, v47
	v_add_f32_e32 v39, v45, v39
	ds_bpermute_b32 v45, v91, v48
	v_add_f32_e32 v37, v44, v37
	v_add_f32_e32 v41, v46, v41
	s_waitcnt lgkmcnt(0)
	v_add_f32_e32 v43, v47, v43
	ds_bpermute_b32 v47, v91, v49
	v_add_f32_e32 v45, v48, v45
	ds_bpermute_b32 v35, v167, v34
	ds_bpermute_b32 v38, v167, v37
	ds_bpermute_b32 v40, v167, v39
	s_waitcnt lgkmcnt(0)
	v_add_f32_e32 v47, v49, v47
	ds_bpermute_b32 v49, v91, v36
	ds_bpermute_b32 v42, v167, v41
	ds_bpermute_b32 v44, v167, v43
	ds_bpermute_b32 v46, v167, v45
	ds_bpermute_b32 v48, v167, v47
	s_waitcnt lgkmcnt(0)
	v_add_f32_e32 v36, v36, v49
	ds_bpermute_b32 v49, v167, v36
	v_add_f32_e32 v34, v34, v35
	v_add_f32_e32 v37, v37, v38
	v_add_f32_e32 v39, v39, v40
	v_add_f32_e32 v41, v41, v42
	v_add_f32_e32 v43, v43, v44
	v_add_f32_e32 v45, v45, v46
	v_add_f32_e32 v47, v47, v48
	s_waitcnt lgkmcnt(0)
	v_add_f32_e32 v36, v36, v49
	ds_bpermute_b32 v35, v168, v34
	ds_bpermute_b32 v38, v168, v37
	ds_bpermute_b32 v40, v168, v39
	ds_bpermute_b32 v42, v168, v41
	ds_bpermute_b32 v44, v168, v43
	ds_bpermute_b32 v46, v168, v45
	ds_bpermute_b32 v48, v168, v47
	ds_bpermute_b32 v49, v168, v36
	s_waitcnt lgkmcnt(0)
	v_add_f32_e32 v34, v34, v35
	v_add_f32_e32 v37, v37, v38
	v_add_f32_e32 v39, v39, v40
	v_add_f32_e32 v41, v41, v42
	v_add_f32_e32 v43, v43, v44
	v_add_f32_e32 v45, v45, v46
	v_add_f32_e32 v47, v47, v48
	v_add_f32_e32 v36, v36, v49
	ds_bpermute_b32 v35, v169, v34
	ds_bpermute_b32 v38, v169, v37
	ds_bpermute_b32 v40, v169, v39
	ds_bpermute_b32 v42, v169, v41
	ds_bpermute_b32 v44, v169, v43
	ds_bpermute_b32 v46, v169, v45
	ds_bpermute_b32 v48, v169, v47
	ds_bpermute_b32 v49, v169, v36
	s_waitcnt lgkmcnt(0)
	v_add_f32_e32 v34, v34, v35
	v_add_f32_e32 v37, v37, v38
	v_add_f32_e32 v39, v39, v40
	v_add_f32_e32 v41, v41, v42
	v_add_f32_e32 v43, v43, v44
	v_add_f32_e32 v45, v45, v46
	v_add_f32_e32 v47, v47, v48
	v_add_f32_e32 v36, v36, v49
	ds_bpermute_b32 v35, v170, v34
	ds_bpermute_b32 v38, v170, v37
	ds_bpermute_b32 v40, v170, v39
	ds_bpermute_b32 v42, v170, v41
	ds_bpermute_b32 v44, v170, v43
	ds_bpermute_b32 v46, v170, v45
	ds_bpermute_b32 v48, v170, v47
	ds_bpermute_b32 v49, v170, v36
	s_waitcnt lgkmcnt(0)
	v_add_f32_e32 v34, v34, v35
	v_add_f32_e32 v37, v37, v38
	v_add_f32_e32 v39, v39, v40
	v_add_f32_e32 v41, v41, v42
	v_add_f32_e32 v43, v43, v44
	v_add_f32_e32 v45, v45, v46
	v_add_f32_e32 v47, v47, v48
	v_add_f32_e32 v36, v36, v49
	ds_bpermute_b32 v35, v171, v34
	ds_bpermute_b32 v38, v171, v37
	ds_bpermute_b32 v40, v171, v39
	ds_bpermute_b32 v42, v171, v41
	ds_bpermute_b32 v44, v171, v43
	ds_bpermute_b32 v46, v171, v45
	ds_bpermute_b32 v48, v171, v47
	ds_bpermute_b32 v49, v171, v36
	s_and_saveexec_b64 s[2:3], s[0:1]
	s_cbranch_execz .LBB0_735
; template <bool DO_LN, bool DO_H, bool DO_GATES, bool WRITE_X> ...
;     ...
;                     if (lane == 0) {
; #pragma unroll
;                         for (int gg = 0; gg < 8; ++gg) GIF[(size_t)row * 8 + gg] = ga[gg] + (gg < 4 ? igb[gg] : fgb[gg - 4]); }
	s_waitcnt lgkmcnt(0)
	v_add_f32_e32 v49, v36, v49
	v_add_f32_e32 v38, v37, v38
	v_mov_b64_e32 v[36:37], s[6:7]
	v_add_f32_e32 v41, v41, v42
	global_load_dword v42, v[36:37], off
	v_add_f32_e32 v39, v39, v40
	v_add_f32_e32 v40, v34, v35
	v_lshl_add_u64 v[34:35], s[4:5], 0, v[158:159]
	v_add_co_u32_e32 v34, vcc, 0x3d000000, v34
	v_add_f32_e32 v43, v43, v44
	s_nop 0
	v_addc_co_u32_e32 v35, vcc, 0, v35, vcc
	v_add_f32_e32 v45, v45, v46
	v_add_f32_e32 v47, v47, v48
	s_waitcnt vmcnt(0) lgkmcnt(0)
	v_add_f32_e32 v40, v40, v42
	global_store_dword v[34:35], v40, off
	global_load_dword v40, v[36:37], off offset:4
	s_waitcnt vmcnt(0) lgkmcnt(0)
	v_add_f32_e32 v38, v38, v40
	global_store_dword v[34:35], v38, off offset:4
	global_load_dword v38, v[36:37], off offset:8
	s_waitcnt vmcnt(0) lgkmcnt(0)
	v_add_f32_e32 v38, v39, v38
	global_store_dword v[34:35], v38, off offset:8
	global_load_dword v36, v[36:37], off offset:12
	s_waitcnt vmcnt(0) lgkmcnt(0)
	v_add_f32_e32 v36, v41, v36
	global_store_dword v[34:35], v36, off offset:12
	v_mov_b64_e32 v[36:37], s[8:9]
	global_load_dword v38, v[36:37], off
	s_waitcnt vmcnt(0) lgkmcnt(0)
	v_add_f32_e32 v38, v43, v38
	global_store_dword v[34:35], v38, off offset:16
	global_load_dword v38, v[36:37], off offset:4
	s_waitcnt vmcnt(0) lgkmcnt(0)
	v_add_f32_e32 v38, v45, v38
	global_store_dword v[34:35], v38, off offset:20
	global_load_dword v38, v[36:37], off offset:8
	s_waitcnt vmcnt(0) lgkmcnt(0)
	v_add_f32_e32 v38, v47, v38
	global_store_dword v[34:35], v38, off offset:24
	global_load_dword v36, v[36:37], off offset:12
	s_waitcnt vmcnt(0) lgkmcnt(0)
	v_add_f32_e32 v36, v49, v36
	global_store_dword v[34:35], v36, off offset:28
	s_branch .LBB0_735

; #define LAS __attribute__((address_space(3)))
; __device__ __forceinline__ unsigned cvt_pk_bf16(float lo, float hi) { f32x2_t f = {lo, hi}; bf16x2_t v = __builtin_convertvector(f, bf16x2_t); return __builtin_bit_cast(unsigned, v); }
; __device__ __forceinline__ int otid(int wv) { int t = (wv << 6) | (int)__builtin_amdgcn_mbcnt_hi(~0u, __builtin_amdgcn_mbcnt_lo(~0u, 0u)); asm volatile("" : "+v"(t)); return t; }
; __device__ __forceinline__ void conv_tile(LAS float* tl, const float* src, int ldsrc, int k0, int n0, int N, bf16_t* dst, int lddst, int mode, int wv) {
;     const int tid = otid(wv);
;     constexpr int S = 261;
;     f32x4 v[8];
; #pragma unroll
;     for (int i = 0; i < 8; ++i) { const int e = i * 512 + tid, kk = e >> 6, n = n0 + (e & 63) * 4;
;         v[i] = (f32x4){0.f, 0.f, 0.f, 0.f};
;         if (n + 3 < N) v[i] = *(const f32x4*)(src + (size_t)(k0 + kk) * ldsrc + n);
;         else { for (int j = 0; j < 4; ++j) if (n + j < N) v[i][j] = src[(size_t)(k0 + kk) * ldsrc + n + j]; } }
;     __syncthreads();
; #pragma unroll
;     for (int i = 0; i < 8; ++i) { const int e = i * 512 + tid, kk = e >> 6, n4 = (e & 63) * 4;
; #pragma unroll
;         for (int j = 0; j < 4; ++j) tl[kk * S + n4 + j] = v[i][j]; }
;     __syncthreads();
; #pragma unroll
;     for (int i = 0; i < 4; ++i) { const int item = i * 512 + tid, nl = item >> 3, k8 = (item & 7) * 8, n = n0 + nl;
;         int row = n;
;         if (mode == 0) row = n < 8192 ? n : (n < 8200 ? -1 : n - 8);
;         else if (mode == 2) { const int c = n % DFF, gt = n / DFF; row = (c >> 7) * 256 + gt * 128 + (c & 127); }
;         if (n < N && row >= 0) {
;             float x[8];
; #pragma unroll
;             for (int j = 0; j < 8; ++j) x[j] = tl[(k8 + j) * S + nl];
;             u32x4 w; w.x = cvt_pk_bf16(x[0], x[1]); w.y = cvt_pk_bf16(x[2], x[3]); w.z = cvt_pk_bf16(x[4], x[5]); w.w = cvt_pk_bf16(x[6], x[7]);
;             *(u32x4*)(dst + (size_t)row * lddst + k0 + k8) = w;
;         } }
; __device__ NOINL void convert_weights(const float* win, const float* wbr, const float* wout, const float* wup, const float* wdown, unsigned char* ws, LAS unsigned char* lds, int wv) {
;     ...
;         else { const int q = t - T3, tk = q / 8, tn = q % 8;
;             conv_tile(tl, wdown, 2048, tk * 64, tn * 256, 2048, (bf16_t*)(ws + WS_WDOWN), DFF, 1, wv); }
.LBB0_746:
	s_cmpk_gt_i32 s20, 0x71f
	s_mov_b64 s[0:1], -1
	s_cbranch_scc0 .LBB0_791
	s_cmpk_gt_u32 s20, 0x81f
	s_cbranch_scc0 .LBB0_780
	s_cmpk_gt_u32 s20, 0x91f
	s_cbranch_scc0 .LBB0_769
	s_cmpk_gt_u32 s20, 0xe9f
	s_cbranch_scc0 .LBB0_759
	s_lshl_b32 s0, s20, 3
	s_and_b32 s0, s0, 0x7fffffc0
	v_mov_b32_e32 v40, v236
	s_add_i32 s70, s0, 0xffff8b00
	s_lshl_b32 s0, s20, 8
	s_and_b32 s14, s0, 0x700
	v_lshlrev_b32_e32 v1, 2, v40
	v_and_b32_e32 v38, 0xfc, v1
	v_or_b32_e32 v1, s14, v38
	v_lshlrev_b32_e32 v2, 2, v1
	v_add_u32_e32 v1, 0x600, v40
	v_ashrrev_i32_e32 v39, 6, v40
	v_ashrrev_i32_e32 v43, 6, v1
	v_add_u32_e32 v4, s70, v39
	v_add_u32_e32 v18, s70, v43
	v_mov_b32_e32 v3, v0
	v_ashrrev_i32_e32 v5, 31, v4
	v_ashrrev_i32_e32 v19, 31, v18
	v_lshl_add_u64 v[2:3], s[10:11], 0, v[2:3]
	v_lshlrev_b64 v[4:5], 13, v[4:5]
	v_lshlrev_b64 v[18:19], 13, v[18:19]
	v_lshl_add_u64 v[4:5], v[2:3], 0, v[4:5]
	v_lshl_add_u64 v[18:19], v[2:3], 0, v[18:19]
	global_load_dwordx4 v[6:9], v[4:5], off
	v_add_u32_e32 v22, 0x800, v40
	global_load_dwordx4 v[18:21], v[18:19], off
	v_add_u32_e32 v5, 0x200, v40
	v_ashrrev_i32_e32 v41, 6, v5
	v_add_u32_e32 v4, 0x400, v40
	v_add_u32_e32 v10, s70, v41
	v_ashrrev_i32_e32 v42, 6, v4
	v_ashrrev_i32_e32 v11, 31, v10
	v_add_u32_e32 v14, s70, v42
	v_lshlrev_b64 v[10:11], 13, v[10:11]
	v_ashrrev_i32_e32 v15, 31, v14
	v_ashrrev_i32_e32 v44, 6, v22
	v_add_u32_e32 v26, 0xa00, v40
	v_lshl_add_u64 v[10:11], v[2:3], 0, v[10:11]
	v_lshlrev_b64 v[14:15], 13, v[14:15]
	v_add_u32_e32 v22, s70, v44
	v_ashrrev_i32_e32 v45, 6, v26
	v_add_u32_e32 v30, 0xc00, v40
	v_add_u32_e32 v34, 0xe00, v40
	global_load_dwordx4 v[10:13], v[10:11], off
	v_lshl_add_u64 v[14:15], v[2:3], 0, v[14:15]
	v_ashrrev_i32_e32 v23, 31, v22
	v_add_u32_e32 v26, s70, v45
	v_ashrrev_i32_e32 v46, 6, v30
	v_ashrrev_i32_e32 v47, 6, v34
	global_load_dwordx4 v[14:17], v[14:15], off
	v_lshlrev_b64 v[22:23], 13, v[22:23]
	v_ashrrev_i32_e32 v27, 31, v26
	v_add_u32_e32 v30, s70, v46
	v_add_u32_e32 v34, s70, v47
	v_lshl_add_u64 v[22:23], v[2:3], 0, v[22:23]
	v_lshlrev_b64 v[26:27], 13, v[26:27]
	v_ashrrev_i32_e32 v31, 31, v30
	v_ashrrev_i32_e32 v35, 31, v34
	global_load_dwordx4 v[22:25], v[22:23], off
	v_lshl_add_u64 v[26:27], v[2:3], 0, v[26:27]
	v_lshlrev_b64 v[30:31], 13, v[30:31]
	v_lshlrev_b64 v[34:35], 13, v[34:35]
	global_load_dwordx4 v[26:29], v[26:27], off
	v_lshl_add_u64 v[30:31], v[2:3], 0, v[30:31]
	v_lshl_add_u64 v[2:3], v[2:3], 0, v[34:35]
	global_load_dwordx4 v[30:33], v[30:31], off
	s_movk_i32 s15, 0x414
	global_load_dwordx4 v[34:37], v[2:3], off
	v_lshl_add_u32 v2, v38, 2, 0
	v_mad_u64_u32 v[38:39], s[0:1], v39, s15, v[2:3]
	s_waitcnt lgkmcnt(0)
	s_barrier
	s_waitcnt vmcnt(0)
	ds_write2_b32 v38, v6, v7 offset1:1
	ds_write2_b32 v38, v8, v9 offset0:2 offset1:3
	v_mad_u64_u32 v[6:7], s[0:1], v41, s15, v[2:3]
	ds_write2_b32 v6, v10, v11 offset1:1
	ds_write2_b32 v6, v12, v13 offset0:2 offset1:3
	v_mad_u64_u32 v[6:7], s[0:1], v42, s15, v[2:3]
	ds_write2_b32 v6, v14, v15 offset1:1
	ds_write2_b32 v6, v16, v17 offset0:2 offset1:3
	v_mad_u64_u32 v[6:7], s[0:1], v43, s15, v[2:3]
	ds_write2_b32 v6, v18, v19 offset1:1
	ds_write2_b32 v6, v20, v21 offset0:2 offset1:3
	v_mad_u64_u32 v[6:7], s[0:1], v44, s15, v[2:3]
	ds_write2_b32 v6, v22, v23 offset1:1
	ds_write2_b32 v6, v24, v25 offset0:2 offset1:3
	v_mad_u64_u32 v[6:7], s[0:1], v45, s15, v[2:3]
	ds_write2_b32 v6, v26, v27 offset1:1
	ds_write2_b32 v6, v28, v29 offset0:2 offset1:3
	v_mad_u64_u32 v[6:7], s[0:1], v46, s15, v[2:3]
	v_mad_u64_u32 v[2:3], s[0:1], v47, s15, v[2:3]
	ds_write2_b32 v6, v30, v31 offset1:1
	ds_write2_b32 v6, v32, v33 offset0:2 offset1:3
	ds_write2_b32 v2, v34, v35 offset1:1
	ds_write2_b32 v2, v36, v37 offset0:2 offset1:3
	v_lshlrev_b32_e32 v2, 3, v40
	s_lshl_b64 s[0:1], s[70:71], 1
	v_and_b32_e32 v6, 56, v2
	s_add_u32 s0, s21, s0
	s_addc_u32 s1, s23, s1
	v_lshlrev_b32_e32 v2, 1, v6
	v_mov_b32_e32 v3, v0
	v_ashrrev_i32_e32 v8, 3, v40
	v_lshl_add_u64 v[2:3], s[0:1], 0, v[2:3]
	v_add_u32_e32 v7, s14, v8
	s_movk_i32 s0, 0x800
	v_cmp_gt_u32_e32 vcc, s0, v7
	v_mul_u32_u24_e32 v6, 0x414, v6
	s_waitcnt lgkmcnt(0)
	s_barrier
	s_and_saveexec_b64 s[0:1], vcc
	s_cbranch_execz .LBB0_752
	v_lshlrev_b32_e32 v8, 2, v8
	v_add3_u32 v8, 0, v8, v6
	ds_read_b32 v9, v8
	ds_read_b32 v10, v8 offset:1044
	ds_read_b32 v11, v8 offset:2088
	ds_read_b32 v12, v8 offset:3132
	ds_read_b32 v13, v8 offset:4176
	ds_read_b32 v14, v8 offset:5220
	ds_read_b32 v15, v8 offset:6264
	ds_read_b32 v16, v8 offset:7308
	s_movk_i32 s15, 0x1600
	s_waitcnt lgkmcnt(6)
	v_cvt_pk_bf16_f32 v8, v9, v10
	s_waitcnt lgkmcnt(4)
	v_cvt_pk_bf16_f32 v9, v11, v12
	s_waitcnt lgkmcnt(2)
	v_cvt_pk_bf16_f32 v10, v13, v14
	v_mul_lo_u32 v12, v7, s15
	v_mov_b32_e32 v13, v0
	s_waitcnt lgkmcnt(0)
	v_cvt_pk_bf16_f32 v11, v15, v16
	v_lshl_add_u64 v[12:13], v[12:13], 1, v[2:3]
	global_store_dwordx4 v[12:13], v[8:11], off
; __device__ __forceinline__ unsigned cvt_pk_bf16(float lo, float hi) { f32x2_t f = {lo, hi}; bf16x2_t v = __builtin_convertvector(f, bf16x2_t); return __builtin_bit_cast(unsigned, v); }
; __device__ __forceinline__ void conv_tile(LAS float* tl, const float* src, int ldsrc, int k0, int n0, int N, bf16_t* dst, int lddst, int mode, int wv) {
;     ...
;     for (int i = 0; i < 4; ++i) { const int item = i * 512 + tid, nl = item >> 3, k8 = (item & 7) * 8, n = n0 + nl;
;         int row = n;
;         if (mode == 0) row = n < 8192 ? n : (n < 8200 ? -1 : n - 8);
;         else if (mode == 2) { const int c = n % DFF, gt = n / DFF; row = (c >> 7) * 256 + gt * 128 + (c & 127); }
;         if (n < N && row >= 0) {
;             float x[8];
; #pragma unroll
;             for (int j = 0; j < 8; ++j) x[j] = tl[(k8 + j) * S + nl];
;             u32x4 w; w.x = cvt_pk_bf16(x[0], x[1]); w.y = cvt_pk_bf16(x[2], x[3]); w.z = cvt_pk_bf16(x[4], x[5]); w.w = cvt_pk_bf16(x[6], x[7]);
;             *(u32x4*)(dst + (size_t)row * lddst + k0 + k8) = w;
;         } }
.LBB0_752:
	s_or_b64 exec, exec, s[0:1]
	v_ashrrev_i32_e32 v7, 3, v5
	v_add_u32_e32 v5, s14, v7
	s_movk_i32 s0, 0x800
	v_cmp_gt_u32_e32 vcc, s0, v5
	s_and_saveexec_b64 s[0:1], vcc
	s_cbranch_execz .LBB0_754
	v_lshlrev_b32_e32 v7, 2, v7
	v_add3_u32 v7, 0, v7, v6
	ds_read_b32 v8, v7
	ds_read_b32 v9, v7 offset:1044
	ds_read_b32 v10, v7 offset:2088
	ds_read_b32 v11, v7 offset:3132
	ds_read_b32 v12, v7 offset:4176
	ds_read_b32 v13, v7 offset:5220
	ds_read_b32 v14, v7 offset:6264
	ds_read_b32 v7, v7 offset:7308
	s_movk_i32 s15, 0x1600
	s_waitcnt lgkmcnt(0)
	v_cvt_pk_bf16_f32 v8, v8, v9
	v_cvt_pk_bf16_f32 v9, v10, v11
	v_cvt_pk_bf16_f32 v10, v12, v13
	v_mul_lo_u32 v12, v5, s15
	v_mov_b32_e32 v13, v0
	v_cvt_pk_bf16_f32 v11, v14, v7
	v_lshl_add_u64 v[12:13], v[12:13], 1, v[2:3]
	global_store_dwordx4 v[12:13], v[8:11], off
.LBB0_754:
	s_or_b64 exec, exec, s[0:1]
	v_ashrrev_i32_e32 v5, 3, v4
	v_add_u32_e32 v4, s14, v5
	s_movk_i32 s0, 0x800
	v_cmp_gt_u32_e32 vcc, s0, v4
	s_and_saveexec_b64 s[0:1], vcc
	s_cbranch_execz .LBB0_756
	v_lshlrev_b32_e32 v5, 2, v5
	v_add3_u32 v5, 0, v5, v6
	ds_read_b32 v7, v5
	ds_read_b32 v8, v5 offset:1044
	ds_read_b32 v9, v5 offset:2088
	ds_read_b32 v10, v5 offset:3132
	ds_read_b32 v11, v5 offset:4176
	ds_read_b32 v12, v5 offset:5220
	ds_read_b32 v13, v5 offset:6264
	ds_read_b32 v5, v5 offset:7308
	s_movk_i32 s15, 0x1600
	s_waitcnt lgkmcnt(0)
	v_cvt_pk_bf16_f32 v9, v9, v10
	v_cvt_pk_bf16_f32 v10, v11, v12
	v_mul_lo_u32 v4, v4, s15
	v_cvt_pk_bf16_f32 v11, v13, v5
	v_mov_b32_e32 v5, v0
	v_cvt_pk_bf16_f32 v8, v7, v8
	v_lshl_add_u64 v[4:5], v[4:5], 1, v[2:3]
	global_store_dwordx4 v[4:5], v[8:11], off
.LBB0_756:
	s_or_b64 exec, exec, s[0:1]
	v_ashrrev_i32_e32 v4, 3, v1
	v_add_u32_e32 v1, s14, v4
	s_movk_i32 s0, 0x800
	v_cmp_gt_u32_e32 vcc, s0, v1
	s_and_saveexec_b64 s[0:1], vcc
	s_cbranch_execz .LBB0_758
	v_lshlrev_b32_e32 v4, 2, v4
	v_add3_u32 v4, 0, v4, v6
	ds_read_b32 v5, v4
	ds_read_b32 v6, v4 offset:1044
	ds_read_b32 v7, v4 offset:2088
	ds_read_b32 v8, v4 offset:3132
	ds_read_b32 v9, v4 offset:4176
	ds_read_b32 v10, v4 offset:5220
	ds_read_b32 v11, v4 offset:6264
	ds_read_b32 v12, v4 offset:7308
	s_movk_i32 s14, 0x1600
	s_waitcnt lgkmcnt(0)
	v_cvt_pk_bf16_f32 v4, v5, v6
	v_cvt_pk_bf16_f32 v5, v7, v8
	v_cvt_pk_bf16_f32 v6, v9, v10
	v_mul_lo_u32 v8, v1, s14
	v_mov_b32_e32 v9, v0
	v_cvt_pk_bf16_f32 v7, v11, v12
	v_lshl_add_u64 v[2:3], v[8:9], 1, v[2:3]
	global_store_dwordx4 v[2:3], v[4:7], off

; #define LAS __attribute__((address_space(3)))
; __device__ __forceinline__ unsigned cvt_pk_bf16(float lo, float hi) { f32x2_t f = {lo, hi}; bf16x2_t v = __builtin_convertvector(f, bf16x2_t); return __builtin_bit_cast(unsigned, v); }
; __device__ __forceinline__ int otid(int wv) { int t = (wv << 6) | (int)__builtin_amdgcn_mbcnt_hi(~0u, __builtin_amdgcn_mbcnt_lo(~0u, 0u)); asm volatile("" : "+v"(t)); return t; }
; __device__ __forceinline__ void conv_tile(LAS float* tl, const float* src, int ldsrc, int k0, int n0, int N, bf16_t* dst, int lddst, int mode, int wv) {
;     const int tid = otid(wv);
;     constexpr int S = 261;
;     f32x4 v[8];
; #pragma unroll
;     for (int i = 0; i < 8; ++i) { const int e = i * 512 + tid, kk = e >> 6, n = n0 + (e & 63) * 4;
;         v[i] = (f32x4){0.f, 0.f, 0.f, 0.f};
;         if (n + 3 < N) v[i] = *(const f32x4*)(src + (size_t)(k0 + kk) * ldsrc + n);
;         else { for (int j = 0; j < 4; ++j) if (n + j < N) v[i][j] = src[(size_t)(k0 + kk) * ldsrc + n + j]; } }
;     __syncthreads();
; #pragma unroll
;     for (int i = 0; i < 8; ++i) { const int e = i * 512 + tid, kk = e >> 6, n4 = (e & 63) * 4;
; #pragma unroll
;         for (int j = 0; j < 4; ++j) tl[kk * S + n4 + j] = v[i][j]; }
;     __syncthreads();
; #pragma unroll
;     for (int i = 0; i < 4; ++i) { const int item = i * 512 + tid, nl = item >> 3, k8 = (item & 7) * 8, n = n0 + nl;
;         int row = n;
;         if (mode == 0) row = n < 8192 ? n : (n < 8200 ? -1 : n - 8);
;         else if (mode == 2) { const int c = n % DFF, gt = n / DFF; row = (c >> 7) * 256 + gt * 128 + (c & 127); }
;         if (n < N && row >= 0) {
;             float x[8];
; #pragma unroll
;             for (int j = 0; j < 8; ++j) x[j] = tl[(k8 + j) * S + nl];
;             u32x4 w; w.x = cvt_pk_bf16(x[0], x[1]); w.y = cvt_pk_bf16(x[2], x[3]); w.z = cvt_pk_bf16(x[4], x[5]); w.w = cvt_pk_bf16(x[6], x[7]);
;             *(u32x4*)(dst + (size_t)row * lddst + k0 + k8) = w;
;         } }
; __device__ NOINL void convert_weights(const float* win, const float* wbr, const float* wout, const float* wup, const float* wdown, unsigned char* ws, LAS unsigned char* lds, int wv) {
;     ...
;         else if (t < T3) { const int q = t - T2, tk = q / 44, tn = q % 44;
;             conv_tile(tl, wup, NUP, tk * 64, tn * 256, NUP, (bf16_t*)(ws + WS_WUP), 2048, 2, wv); }
.LBB0_759:
	s_and_b64 vcc, exec, s[0:1]
	s_cbranch_vccz .LBB0_880
	s_add_i32 s1, s20, 0xf6e0
	s_and_b32 s0, s1, 0xffff
	s_mul_i32 s0, s0, 0xba2f
	s_lshr_b32 s0, s0, 21
	s_mul_i32 s14, s0, 44
	s_sub_i32 s1, s1, s14
	v_mov_b32_e32 v40, v236
	s_lshl_b32 s1, s1, 8
	s_and_b32 s14, s1, 0xff00
	v_lshlrev_b32_e32 v1, 2, v40
	v_and_b32_e32 v38, 0xfc, v1
	v_or_b32_e32 v1, s14, v38
	v_add_u32_e32 v22, 0x800, v40
	s_lshl_b32 s15, s0, 6
	v_lshlrev_b32_e32 v2, 2, v1
	v_mov_b32_e32 v3, v0
	v_ashrrev_i32_e32 v39, 6, v40
	v_ashrrev_i32_e32 v44, 6, v22
	v_lshl_add_u64 v[2:3], s[8:9], 0, v[2:3]
	v_add_u32_e32 v1, s15, v39
	s_mov_b32 s1, 0xb000
	v_add_u32_e32 v22, s15, v44
	v_mad_i64_i32 v[4:5], s[16:17], v1, s1, v[2:3]
	v_mad_i64_i32 v[22:23], s[16:17], v22, s1, v[2:3]
	global_load_dwordx4 v[6:9], v[4:5], off
	v_add_u32_e32 v26, 0xa00, v40
	global_load_dwordx4 v[22:25], v[22:23], off
	v_add_u32_e32 v5, 0x200, v40
	v_ashrrev_i32_e32 v41, 6, v5
	v_add_u32_e32 v4, 0x400, v40
	v_add_u32_e32 v1, s15, v41
	v_ashrrev_i32_e32 v42, 6, v4
	v_mad_i64_i32 v[10:11], s[16:17], v1, s1, v[2:3]
	v_add_u32_e32 v1, s15, v42
	v_mad_i64_i32 v[14:15], s[16:17], v1, s1, v[2:3]
	v_add_u32_e32 v1, 0x600, v40
	v_ashrrev_i32_e32 v43, 6, v1
	global_load_dwordx4 v[10:13], v[10:11], off
	v_add_u32_e32 v18, s15, v43
	global_load_dwordx4 v[14:17], v[14:15], off
	v_mad_i64_i32 v[18:19], s[16:17], v18, s1, v[2:3]
	v_ashrrev_i32_e32 v45, 6, v26
	v_add_u32_e32 v30, 0xc00, v40
	v_add_u32_e32 v34, 0xe00, v40
	global_load_dwordx4 v[18:21], v[18:19], off
	v_add_u32_e32 v26, s15, v45
	v_ashrrev_i32_e32 v46, 6, v30
	v_ashrrev_i32_e32 v47, 6, v34
	v_mad_i64_i32 v[26:27], s[16:17], v26, s1, v[2:3]
	v_add_u32_e32 v30, s15, v46
	v_add_u32_e32 v34, s15, v47
	global_load_dwordx4 v[26:29], v[26:27], off
	v_mad_i64_i32 v[30:31], s[16:17], v30, s1, v[2:3]
	v_mad_i64_i32 v[2:3], s[16:17], v34, s1, v[2:3]
	global_load_dwordx4 v[30:33], v[30:31], off
	s_movk_i32 s1, 0x414
	global_load_dwordx4 v[34:37], v[2:3], off
	v_lshl_add_u32 v2, v38, 2, 0
	v_mad_u64_u32 v[38:39], s[16:17], v39, s1, v[2:3]
	s_waitcnt lgkmcnt(0)
	s_barrier
	s_lshl_b32 s0, s0, 7
	s_add_u32 s0, s24, s0
	s_waitcnt vmcnt(0)
	ds_write2_b32 v38, v6, v7 offset1:1
	ds_write2_b32 v38, v8, v9 offset0:2 offset1:3
	v_mad_u64_u32 v[6:7], s[16:17], v41, s1, v[2:3]
	ds_write2_b32 v6, v10, v11 offset1:1
	ds_write2_b32 v6, v12, v13 offset0:2 offset1:3
	v_mad_u64_u32 v[6:7], s[16:17], v42, s1, v[2:3]
	ds_write2_b32 v6, v14, v15 offset1:1
	ds_write2_b32 v6, v16, v17 offset0:2 offset1:3
	v_mad_u64_u32 v[6:7], s[16:17], v43, s1, v[2:3]
	ds_write2_b32 v6, v18, v19 offset1:1
	ds_write2_b32 v6, v20, v21 offset0:2 offset1:3
	v_mad_u64_u32 v[6:7], s[16:17], v44, s1, v[2:3]
	ds_write2_b32 v6, v22, v23 offset1:1
	ds_write2_b32 v6, v24, v25 offset0:2 offset1:3
	v_mad_u64_u32 v[6:7], s[16:17], v45, s1, v[2:3]
	ds_write2_b32 v6, v26, v27 offset1:1
	ds_write2_b32 v6, v28, v29 offset0:2 offset1:3
	v_mad_u64_u32 v[6:7], s[16:17], v46, s1, v[2:3]
	v_mad_u64_u32 v[2:3], s[16:17], v47, s1, v[2:3]
	ds_write2_b32 v6, v30, v31 offset1:1
	ds_write2_b32 v6, v32, v33 offset0:2 offset1:3
	ds_write2_b32 v2, v34, v35 offset1:1
	ds_write2_b32 v2, v36, v37 offset0:2 offset1:3
	v_lshlrev_b32_e32 v2, 3, v40
	v_and_b32_e32 v6, 56, v2
	s_addc_u32 s1, s25, 0
	v_lshlrev_b32_e32 v2, 1, v6
	v_mov_b32_e32 v3, v0
	v_ashrrev_i32_e32 v7, 3, v40
	v_lshl_add_u64 v[2:3], s[0:1], 0, v[2:3]
	v_add_u32_e32 v10, s14, v7
	s_mov_b32 s0, 0x2e8ba2e9
	v_mul_hi_i32 v8, v10, s0
	v_lshrrev_b32_e32 v9, 31, v8
	v_ashrrev_i32_e32 v8, 10, v8
	v_add_u32_e32 v9, v8, v9
	v_mul_i32_i24_e32 v8, 0x1600, v9
	v_sub_u32_e32 v8, v10, v8
	v_lshlrev_b32_e32 v11, 1, v8
	v_and_b32_e32 v11, 0xffffff00, v11
	v_lshl_add_u32 v9, v9, 7, v11
	s_movk_i32 s0, 0x2c00
	v_cmp_gt_i32_e32 vcc, s0, v10
	v_cmp_lt_i32_e64 s[0:1], -1, v9
	s_and_b64 s[16:17], vcc, s[0:1]
	v_mul_u32_u24_e32 v6, 0x414, v6
	s_waitcnt lgkmcnt(0)
	s_barrier
	s_and_saveexec_b64 s[0:1], s[16:17]
	s_cbranch_execz .LBB0_762
	v_lshlrev_b32_e32 v7, 2, v7
	s_movk_i32 s15, 0x7f
	v_add3_u32 v7, 0, v7, v6
	v_and_or_b32 v12, v8, s15, v9
	ds_read_b32 v8, v7
	ds_read_b32 v9, v7 offset:1044
	ds_read_b32 v10, v7 offset:2088
	ds_read_b32 v11, v7 offset:3132
	ds_read_b32 v13, v7 offset:4176
	ds_read_b32 v14, v7 offset:5220
	ds_read_b32 v15, v7 offset:6264
	ds_read_b32 v7, v7 offset:7308
	s_waitcnt lgkmcnt(6)
	v_cvt_pk_bf16_f32 v8, v8, v9
	s_waitcnt lgkmcnt(4)
	v_cvt_pk_bf16_f32 v9, v10, v11
	s_waitcnt lgkmcnt(2)
	v_cvt_pk_bf16_f32 v10, v13, v14
	v_mov_b32_e32 v13, v0
	v_lshlrev_b64 v[12:13], 12, v[12:13]
	s_waitcnt lgkmcnt(0)
	v_cvt_pk_bf16_f32 v11, v15, v7
	v_lshl_add_u64 v[12:13], v[2:3], 0, v[12:13]
	global_store_dwordx4 v[12:13], v[8:11], off
; __device__ __forceinline__ unsigned cvt_pk_bf16(float lo, float hi) { f32x2_t f = {lo, hi}; bf16x2_t v = __builtin_convertvector(f, bf16x2_t); return __builtin_bit_cast(unsigned, v); }
; __device__ __forceinline__ void conv_tile(LAS float* tl, const float* src, int ldsrc, int k0, int n0, int N, bf16_t* dst, int lddst, int mode, int wv) {
;     ...
;     for (int i = 0; i < 4; ++i) { const int item = i * 512 + tid, nl = item >> 3, k8 = (item & 7) * 8, n = n0 + nl;
;         int row = n;
;         if (mode == 0) row = n < 8192 ? n : (n < 8200 ? -1 : n - 8);
;         else if (mode == 2) { const int c = n % DFF, gt = n / DFF; row = (c >> 7) * 256 + gt * 128 + (c & 127); }
;         if (n < N && row >= 0) {
;             float x[8];
; #pragma unroll
;             for (int j = 0; j < 8; ++j) x[j] = tl[(k8 + j) * S + nl];
;             u32x4 w; w.x = cvt_pk_bf16(x[0], x[1]); w.y = cvt_pk_bf16(x[2], x[3]); w.z = cvt_pk_bf16(x[4], x[5]); w.w = cvt_pk_bf16(x[6], x[7]);
;             *(u32x4*)(dst + (size_t)row * lddst + k0 + k8) = w;
;         } }
.LBB0_762:
	s_or_b64 exec, exec, s[0:1]
	v_ashrrev_i32_e32 v5, 3, v5
	v_add_u32_e32 v9, s14, v5
	s_mov_b32 s0, 0x2e8ba2e9
	v_mul_hi_i32 v7, v9, s0
	v_lshrrev_b32_e32 v8, 31, v7
	v_ashrrev_i32_e32 v7, 10, v7
	v_add_u32_e32 v8, v7, v8
	v_mul_i32_i24_e32 v7, 0x1600, v8
	v_sub_u32_e32 v7, v9, v7
	v_lshlrev_b32_e32 v10, 1, v7
	v_and_b32_e32 v10, 0xffffff00, v10
	v_lshl_add_u32 v8, v8, 7, v10
	s_movk_i32 s0, 0x2c00
	v_cmp_gt_i32_e32 vcc, s0, v9
	v_cmp_lt_i32_e64 s[0:1], -1, v8
	s_and_b64 s[16:17], vcc, s[0:1]
	s_and_saveexec_b64 s[0:1], s[16:17]
	s_cbranch_execz .LBB0_764
	v_lshlrev_b32_e32 v5, 2, v5
	s_movk_i32 s15, 0x7f
	v_add3_u32 v5, 0, v5, v6
	v_and_or_b32 v12, v7, s15, v8
	ds_read_b32 v7, v5
	ds_read_b32 v8, v5 offset:1044
	ds_read_b32 v9, v5 offset:2088
	ds_read_b32 v10, v5 offset:3132
	ds_read_b32 v11, v5 offset:4176
	ds_read_b32 v13, v5 offset:5220
	ds_read_b32 v14, v5 offset:6264
	ds_read_b32 v5, v5 offset:7308
	s_waitcnt lgkmcnt(0)
	v_cvt_pk_bf16_f32 v9, v9, v10
	v_cvt_pk_bf16_f32 v8, v7, v8
	v_cvt_pk_bf16_f32 v10, v11, v13
	v_mov_b32_e32 v13, v0
	v_lshlrev_b64 v[12:13], 12, v[12:13]
	v_cvt_pk_bf16_f32 v11, v14, v5
	v_lshl_add_u64 v[12:13], v[2:3], 0, v[12:13]
	global_store_dwordx4 v[12:13], v[8:11], off
.LBB0_764:
	s_or_b64 exec, exec, s[0:1]
	v_ashrrev_i32_e32 v4, 3, v4
	v_add_u32_e32 v8, s14, v4
	s_mov_b32 s0, 0x2e8ba2e9
	v_mul_hi_i32 v5, v8, s0
	v_lshrrev_b32_e32 v7, 31, v5
	v_ashrrev_i32_e32 v5, 10, v5
	v_add_u32_e32 v7, v5, v7
	v_mul_i32_i24_e32 v5, 0x1600, v7
	v_sub_u32_e32 v5, v8, v5
	v_lshlrev_b32_e32 v9, 1, v5
	v_and_b32_e32 v9, 0xffffff00, v9
	v_lshl_add_u32 v7, v7, 7, v9
	s_movk_i32 s0, 0x2c00
	v_cmp_gt_i32_e32 vcc, s0, v8
	v_cmp_lt_i32_e64 s[0:1], -1, v7
	s_and_b64 s[16:17], vcc, s[0:1]
	s_and_saveexec_b64 s[0:1], s[16:17]
	s_cbranch_execz .LBB0_766
	v_lshlrev_b32_e32 v4, 2, v4
	s_movk_i32 s15, 0x7f
	v_add3_u32 v4, 0, v4, v6
	v_and_or_b32 v12, v5, s15, v7
	ds_read_b32 v5, v4
	ds_read_b32 v7, v4 offset:1044
	ds_read_b32 v9, v4 offset:2088
	ds_read_b32 v10, v4 offset:3132
	ds_read_b32 v11, v4 offset:4176
	ds_read_b32 v13, v4 offset:5220
	ds_read_b32 v14, v4 offset:6264
	ds_read_b32 v4, v4 offset:7308
	s_waitcnt lgkmcnt(0)
	v_cvt_pk_bf16_f32 v9, v9, v10
	v_cvt_pk_bf16_f32 v8, v5, v7
	v_cvt_pk_bf16_f32 v10, v11, v13
	v_mov_b32_e32 v13, v0
	v_cvt_pk_bf16_f32 v11, v14, v4
	v_lshlrev_b64 v[4:5], 12, v[12:13]
	v_lshl_add_u64 v[4:5], v[2:3], 0, v[4:5]
	global_store_dwordx4 v[4:5], v[8:11], off
.LBB0_766:
	s_or_b64 exec, exec, s[0:1]
	v_ashrrev_i32_e32 v1, 3, v1
	v_add_u32_e32 v7, s14, v1
	s_mov_b32 s0, 0x2e8ba2e9
	v_mul_hi_i32 v4, v7, s0
	v_lshrrev_b32_e32 v5, 31, v4
	v_ashrrev_i32_e32 v4, 10, v4
	v_add_u32_e32 v5, v4, v5
	v_mul_i32_i24_e32 v4, 0x1600, v5
	v_sub_u32_e32 v4, v7, v4
	v_lshlrev_b32_e32 v8, 1, v4
	v_and_b32_e32 v8, 0xffffff00, v8
	v_lshl_add_u32 v5, v5, 7, v8
	s_movk_i32 s0, 0x2c00
	v_cmp_gt_i32_e32 vcc, s0, v7
	v_cmp_lt_i32_e64 s[0:1], -1, v5
	s_and_b64 s[14:15], vcc, s[0:1]
	s_and_saveexec_b64 s[0:1], s[14:15]
	s_cbranch_execz .LBB0_768
	v_lshlrev_b32_e32 v1, 2, v1
	s_movk_i32 s14, 0x7f
	v_add3_u32 v1, 0, v1, v6
	v_and_or_b32 v8, v4, s14, v5
	ds_read_b32 v4, v1
	ds_read_b32 v5, v1 offset:1044
	ds_read_b32 v6, v1 offset:2088
	ds_read_b32 v7, v1 offset:3132
	ds_read_b32 v9, v1 offset:4176
	ds_read_b32 v10, v1 offset:5220
	ds_read_b32 v11, v1 offset:6264
	ds_read_b32 v1, v1 offset:7308
	s_waitcnt lgkmcnt(0)
	v_cvt_pk_bf16_f32 v4, v4, v5
	v_cvt_pk_bf16_f32 v5, v6, v7
	v_cvt_pk_bf16_f32 v6, v9, v10
	v_mov_b32_e32 v9, v0
	v_lshlrev_b64 v[8:9], 12, v[8:9]
	v_cvt_pk_bf16_f32 v7, v11, v1
	v_lshl_add_u64 v[2:3], v[2:3], 0, v[8:9]
	global_store_dwordx4 v[2:3], v[4:7], off

; #define LAS __attribute__((address_space(3)))
; __device__ __forceinline__ unsigned cvt_pk_bf16(float lo, float hi) { f32x2_t f = {lo, hi}; bf16x2_t v = __builtin_convertvector(f, bf16x2_t); return __builtin_bit_cast(unsigned, v); }
; __device__ __forceinline__ int otid(int wv) { int t = (wv << 6) | (int)__builtin_amdgcn_mbcnt_hi(~0u, __builtin_amdgcn_mbcnt_lo(~0u, 0u)); asm volatile("" : "+v"(t)); return t; }
; __device__ __forceinline__ void conv_tile(LAS float* tl, const float* src, int ldsrc, int k0, int n0, int N, bf16_t* dst, int lddst, int mode, int wv) {
;     const int tid = otid(wv);
;     constexpr int S = 261;
;     f32x4 v[8];
; #pragma unroll
;     for (int i = 0; i < 8; ++i) { const int e = i * 512 + tid, kk = e >> 6, n = n0 + (e & 63) * 4;
;         v[i] = (f32x4){0.f, 0.f, 0.f, 0.f};
;         if (n + 3 < N) v[i] = *(const f32x4*)(src + (size_t)(k0 + kk) * ldsrc + n);
;         else { for (int j = 0; j < 4; ++j) if (n + j < N) v[i][j] = src[(size_t)(k0 + kk) * ldsrc + n + j]; } }
;     __syncthreads();
; #pragma unroll
;     for (int i = 0; i < 8; ++i) { const int e = i * 512 + tid, kk = e >> 6, n4 = (e & 63) * 4;
; #pragma unroll
;         for (int j = 0; j < 4; ++j) tl[kk * S + n4 + j] = v[i][j]; }
;     __syncthreads();
; #pragma unroll
;     for (int i = 0; i < 4; ++i) { const int item = i * 512 + tid, nl = item >> 3, k8 = (item & 7) * 8, n = n0 + nl;
;         int row = n;
;         if (mode == 0) row = n < 8192 ? n : (n < 8200 ? -1 : n - 8);
;         else if (mode == 2) { const int c = n % DFF, gt = n / DFF; row = (c >> 7) * 256 + gt * 128 + (c & 127); }
;         if (n < N && row >= 0) {
;             float x[8];
; #pragma unroll
;             for (int j = 0; j < 8; ++j) x[j] = tl[(k8 + j) * S + nl];
;             u32x4 w; w.x = cvt_pk_bf16(x[0], x[1]); w.y = cvt_pk_bf16(x[2], x[3]); w.z = cvt_pk_bf16(x[4], x[5]); w.w = cvt_pk_bf16(x[6], x[7]);
;             *(u32x4*)(dst + (size_t)row * lddst + k0 + k8) = w;
;         } }
; __device__ NOINL void convert_weights(const float* win, const float* wbr, const float* wout, const float* wup, const float* wdown, unsigned char* ws, LAS unsigned char* lds, int wv) {
;     ...
;         else if (t < T2) { const int q = t - T1, tk = q / 8, tn = q % 8;
;             conv_tile(tl, wout, 2048, tk * 64, tn * 256, 2048, (bf16_t*)(ws + WS_WOUT), 2048, 1, wv); }
.LBB0_770:
	s_lshl_b32 s0, s20, 3
	s_and_b32 s0, s0, 0x7fc0
	v_mov_b32_e32 v40, v236
	s_add_i32 s70, s0, 0xffffbf00
	s_lshl_b32 s0, s20, 8
	s_and_b32 s14, s0, 0x700
	v_lshlrev_b32_e32 v1, 2, v40
	v_and_b32_e32 v38, 0xfc, v1
	v_or_b32_e32 v1, s14, v38
	v_lshlrev_b32_e32 v2, 2, v1
	v_add_u32_e32 v1, 0x600, v40
	v_ashrrev_i32_e32 v39, 6, v40
	v_ashrrev_i32_e32 v43, 6, v1
	v_add_u32_e32 v4, s70, v39
	v_add_u32_e32 v18, s70, v43
	v_mov_b32_e32 v3, v0
	v_ashrrev_i32_e32 v5, 31, v4
	v_ashrrev_i32_e32 v19, 31, v18
	v_lshl_add_u64 v[2:3], s[6:7], 0, v[2:3]
	v_lshlrev_b64 v[4:5], 13, v[4:5]
	v_lshlrev_b64 v[18:19], 13, v[18:19]
	v_lshl_add_u64 v[4:5], v[2:3], 0, v[4:5]
	v_lshl_add_u64 v[18:19], v[2:3], 0, v[18:19]
	global_load_dwordx4 v[6:9], v[4:5], off
	v_add_u32_e32 v22, 0x800, v40
	global_load_dwordx4 v[18:21], v[18:19], off
	v_add_u32_e32 v5, 0x200, v40
	v_ashrrev_i32_e32 v41, 6, v5
	v_add_u32_e32 v4, 0x400, v40
	v_add_u32_e32 v10, s70, v41
	v_ashrrev_i32_e32 v42, 6, v4
	v_ashrrev_i32_e32 v11, 31, v10
	v_add_u32_e32 v14, s70, v42
	v_lshlrev_b64 v[10:11], 13, v[10:11]
	v_ashrrev_i32_e32 v15, 31, v14
	v_ashrrev_i32_e32 v44, 6, v22
	v_add_u32_e32 v26, 0xa00, v40
	v_lshl_add_u64 v[10:11], v[2:3], 0, v[10:11]
	v_lshlrev_b64 v[14:15], 13, v[14:15]
	v_add_u32_e32 v22, s70, v44
	v_ashrrev_i32_e32 v45, 6, v26
	v_add_u32_e32 v30, 0xc00, v40
	v_add_u32_e32 v34, 0xe00, v40
	global_load_dwordx4 v[10:13], v[10:11], off
	v_lshl_add_u64 v[14:15], v[2:3], 0, v[14:15]
	v_ashrrev_i32_e32 v23, 31, v22
	v_add_u32_e32 v26, s70, v45
	v_ashrrev_i32_e32 v46, 6, v30
	v_ashrrev_i32_e32 v47, 6, v34
	global_load_dwordx4 v[14:17], v[14:15], off
	v_lshlrev_b64 v[22:23], 13, v[22:23]
	v_ashrrev_i32_e32 v27, 31, v26
	v_add_u32_e32 v30, s70, v46
	v_add_u32_e32 v34, s70, v47
	v_lshl_add_u64 v[22:23], v[2:3], 0, v[22:23]
	v_lshlrev_b64 v[26:27], 13, v[26:27]
	v_ashrrev_i32_e32 v31, 31, v30
	v_ashrrev_i32_e32 v35, 31, v34
	global_load_dwordx4 v[22:25], v[22:23], off
	v_lshl_add_u64 v[26:27], v[2:3], 0, v[26:27]
	v_lshlrev_b64 v[30:31], 13, v[30:31]
	v_lshlrev_b64 v[34:35], 13, v[34:35]
	global_load_dwordx4 v[26:29], v[26:27], off
	v_lshl_add_u64 v[30:31], v[2:3], 0, v[30:31]
	v_lshl_add_u64 v[2:3], v[2:3], 0, v[34:35]
	global_load_dwordx4 v[30:33], v[30:31], off
	s_movk_i32 s15, 0x414
	global_load_dwordx4 v[34:37], v[2:3], off
	v_lshl_add_u32 v2, v38, 2, 0
	v_mad_u64_u32 v[38:39], s[0:1], v39, s15, v[2:3]
	s_waitcnt lgkmcnt(0)
	s_barrier
	s_waitcnt vmcnt(0)
	ds_write2_b32 v38, v6, v7 offset1:1
	ds_write2_b32 v38, v8, v9 offset0:2 offset1:3
	v_mad_u64_u32 v[6:7], s[0:1], v41, s15, v[2:3]
	ds_write2_b32 v6, v10, v11 offset1:1
	ds_write2_b32 v6, v12, v13 offset0:2 offset1:3
	v_mad_u64_u32 v[6:7], s[0:1], v42, s15, v[2:3]
	ds_write2_b32 v6, v14, v15 offset1:1
	ds_write2_b32 v6, v16, v17 offset0:2 offset1:3
	v_mad_u64_u32 v[6:7], s[0:1], v43, s15, v[2:3]
	ds_write2_b32 v6, v18, v19 offset1:1
	ds_write2_b32 v6, v20, v21 offset0:2 offset1:3
	v_mad_u64_u32 v[6:7], s[0:1], v44, s15, v[2:3]
	ds_write2_b32 v6, v22, v23 offset1:1
	ds_write2_b32 v6, v24, v25 offset0:2 offset1:3
	v_mad_u64_u32 v[6:7], s[0:1], v45, s15, v[2:3]
	ds_write2_b32 v6, v26, v27 offset1:1
	ds_write2_b32 v6, v28, v29 offset0:2 offset1:3
	v_mad_u64_u32 v[6:7], s[0:1], v46, s15, v[2:3]
	v_mad_u64_u32 v[2:3], s[0:1], v47, s15, v[2:3]
	ds_write2_b32 v6, v30, v31 offset1:1
	ds_write2_b32 v6, v32, v33 offset0:2 offset1:3
	ds_write2_b32 v2, v34, v35 offset1:1
	ds_write2_b32 v2, v36, v37 offset0:2 offset1:3
	v_lshlrev_b32_e32 v2, 3, v40
	s_lshl_b64 s[0:1], s[70:71], 1
	v_and_b32_e32 v6, 56, v2
	s_add_u32 s0, s26, s0
	s_addc_u32 s1, s27, s1
	v_lshlrev_b32_e32 v2, 1, v6
	v_mov_b32_e32 v3, v0
	v_ashrrev_i32_e32 v8, 3, v40
	v_lshl_add_u64 v[2:3], s[0:1], 0, v[2:3]
	v_add_u32_e32 v7, s14, v8
	s_movk_i32 s0, 0x800
	v_cmp_gt_u32_e32 vcc, s0, v7
	v_mul_u32_u24_e32 v6, 0x414, v6
	s_waitcnt lgkmcnt(0)
	s_barrier
	s_and_saveexec_b64 s[0:1], vcc
	s_cbranch_execz .LBB0_772
	v_lshlrev_b32_e32 v8, 2, v8
	v_add3_u32 v8, 0, v8, v6
	ds_read_b32 v9, v8
	ds_read_b32 v10, v8 offset:1044
	ds_read_b32 v11, v8 offset:2088
	ds_read_b32 v12, v8 offset:3132
	ds_read_b32 v13, v8 offset:4176
	ds_read_b32 v14, v8 offset:5220
	ds_read_b32 v15, v8 offset:6264
	ds_read_b32 v16, v8 offset:7308
	s_waitcnt lgkmcnt(6)
	v_cvt_pk_bf16_f32 v8, v9, v10
	s_waitcnt lgkmcnt(4)
	v_cvt_pk_bf16_f32 v9, v11, v12
	s_waitcnt lgkmcnt(2)
	v_cvt_pk_bf16_f32 v10, v13, v14
	v_lshlrev_b32_e32 v12, 12, v7
	v_mov_b32_e32 v13, v0
	s_waitcnt lgkmcnt(0)
	v_cvt_pk_bf16_f32 v11, v15, v16
	v_lshl_add_u64 v[12:13], v[2:3], 0, v[12:13]
	global_store_dwordx4 v[12:13], v[8:11], off
.LBB0_772:
	s_or_b64 exec, exec, s[0:1]
	v_ashrrev_i32_e32 v7, 3, v5
	v_add_u32_e32 v5, s14, v7
	s_movk_i32 s0, 0x800
	v_cmp_gt_u32_e32 vcc, s0, v5
	s_and_saveexec_b64 s[0:1], vcc
	s_cbranch_execz .LBB0_774
	v_lshlrev_b32_e32 v7, 2, v7
	v_add3_u32 v7, 0, v7, v6
	ds_read_b32 v8, v7
	ds_read_b32 v9, v7 offset:1044
	ds_read_b32 v10, v7 offset:2088
	ds_read_b32 v11, v7 offset:3132
	ds_read_b32 v12, v7 offset:4176
	ds_read_b32 v13, v7 offset:5220
	ds_read_b32 v14, v7 offset:6264
	ds_read_b32 v7, v7 offset:7308
	s_waitcnt lgkmcnt(0)
	v_cvt_pk_bf16_f32 v8, v8, v9
	v_cvt_pk_bf16_f32 v9, v10, v11
	v_cvt_pk_bf16_f32 v10, v12, v13
	v_lshlrev_b32_e32 v12, 12, v5
	v_mov_b32_e32 v13, v0
	v_cvt_pk_bf16_f32 v11, v14, v7
	v_lshl_add_u64 v[12:13], v[2:3], 0, v[12:13]
	global_store_dwordx4 v[12:13], v[8:11], off
.LBB0_774:
	s_or_b64 exec, exec, s[0:1]
	v_ashrrev_i32_e32 v5, 3, v4
	v_add_u32_e32 v4, s14, v5
	s_movk_i32 s0, 0x800
	v_cmp_gt_u32_e32 vcc, s0, v4
	s_and_saveexec_b64 s[0:1], vcc
	s_cbranch_execz .LBB0_776
	v_lshlrev_b32_e32 v5, 2, v5
	v_add3_u32 v5, 0, v5, v6
	ds_read_b32 v7, v5
	ds_read_b32 v8, v5 offset:1044
	ds_read_b32 v9, v5 offset:2088
	ds_read_b32 v10, v5 offset:3132
	ds_read_b32 v11, v5 offset:4176
	ds_read_b32 v12, v5 offset:5220
	ds_read_b32 v13, v5 offset:6264
	ds_read_b32 v5, v5 offset:7308
	s_waitcnt lgkmcnt(0)
	v_cvt_pk_bf16_f32 v9, v9, v10
	v_lshlrev_b32_e32 v4, 12, v4
	v_cvt_pk_bf16_f32 v10, v11, v12
	v_cvt_pk_bf16_f32 v8, v7, v8
	v_cvt_pk_bf16_f32 v11, v13, v5
	v_mov_b32_e32 v5, v0
	v_lshl_add_u64 v[4:5], v[2:3], 0, v[4:5]
	global_store_dwordx4 v[4:5], v[8:11], off
.LBB0_776:
	s_or_b64 exec, exec, s[0:1]
	v_ashrrev_i32_e32 v4, 3, v1
	v_add_u32_e32 v1, s14, v4
	s_movk_i32 s0, 0x800
	v_cmp_gt_u32_e32 vcc, s0, v1
	s_and_saveexec_b64 s[0:1], vcc
	s_cbranch_execz .LBB0_778
	v_lshlrev_b32_e32 v4, 2, v4
	v_add3_u32 v4, 0, v4, v6
	ds_read_b32 v5, v4
	ds_read_b32 v6, v4 offset:1044
	ds_read_b32 v7, v4 offset:2088
	ds_read_b32 v8, v4 offset:3132
	ds_read_b32 v9, v4 offset:4176
	ds_read_b32 v10, v4 offset:5220
	ds_read_b32 v11, v4 offset:6264
	ds_read_b32 v12, v4 offset:7308
	s_waitcnt lgkmcnt(0)
	v_cvt_pk_bf16_f32 v4, v5, v6
	v_cvt_pk_bf16_f32 v5, v7, v8
	v_cvt_pk_bf16_f32 v6, v9, v10
	v_lshlrev_b32_e32 v8, 12, v1
	v_mov_b32_e32 v9, v0
	v_cvt_pk_bf16_f32 v7, v11, v12
	v_lshl_add_u64 v[2:3], v[2:3], 0, v[8:9]
	global_store_dwordx4 v[2:3], v[4:7], off

; #define LAS __attribute__((address_space(3)))
; __device__ __forceinline__ unsigned cvt_pk_bf16(float lo, float hi) { f32x2_t f = {lo, hi}; bf16x2_t v = __builtin_convertvector(f, bf16x2_t); return __builtin_bit_cast(unsigned, v); }
; __device__ __forceinline__ void conv_tile(LAS float* tl, const float* src, int ldsrc, int k0, int n0, int N, bf16_t* dst, int lddst, int mode, int wv) {
;     const int tid = otid(wv);
;     constexpr int S = 261;
;     f32x4 v[8];
; #pragma unroll
;     for (int i = 0; i < 8; ++i) { const int e = i * 512 + tid, kk = e >> 6, n = n0 + (e & 63) * 4;
;         v[i] = (f32x4){0.f, 0.f, 0.f, 0.f};
;         if (n + 3 < N) v[i] = *(const f32x4*)(src + (size_t)(k0 + kk) * ldsrc + n);
;         else { for (int j = 0; j < 4; ++j) if (n + j < N) v[i][j] = src[(size_t)(k0 + kk) * ldsrc + n + j]; } }
;     __syncthreads();
; #pragma unroll
;     for (int i = 0; i < 8; ++i) { const int e = i * 512 + tid, kk = e >> 6, n4 = (e & 63) * 4;
; #pragma unroll
;         for (int j = 0; j < 4; ++j) tl[kk * S + n4 + j] = v[i][j]; }
;     __syncthreads();
; #pragma unroll
;     for (int i = 0; i < 4; ++i) { const int item = i * 512 + tid, nl = item >> 3, k8 = (item & 7) * 8, n = n0 + nl;
;         int row = n;
;         if (mode == 0) row = n < 8192 ? n : (n < 8200 ? -1 : n - 8);
;         else if (mode == 2) { const int c = n % DFF, gt = n / DFF; row = (c >> 7) * 256 + gt * 128 + (c & 127); }
;         if (n < N && row >= 0) {
;             float x[8];
; #pragma unroll
;             for (int j = 0; j < 8; ++j) x[j] = tl[(k8 + j) * S + nl];
;             u32x4 w; w.x = cvt_pk_bf16(x[0], x[1]); w.y = cvt_pk_bf16(x[2], x[3]); w.z = cvt_pk_bf16(x[4], x[5]); w.w = cvt_pk_bf16(x[6], x[7]);
;             *(u32x4*)(dst + (size_t)row * lddst + k0 + k8) = w;
;         } }
; __device__ NOINL void convert_weights(const float* win, const float* wbr, const float* wout, const float* wup, const float* wdown, unsigned char* ws, LAS unsigned char* lds, int wv) {
;     ...
;         else if (t < T1) { const int r = t - T0, br = 1 + r / 128, q = r % 128, tk = q / 8, tn = q % 8;
;             conv_tile(tl, wbr + (size_t)br * 1024 * 2048, 2048, tk * 64, tn * 256, 2048, (bf16_t*)(ws + WS_WBR) + (size_t)br * 2048 * 1024, 1024, 1, wv); }
.LBB0_780:
	s_andn2_b64 vcc, exec, s[0:1]
	s_cbranch_vccnz .LBB0_790
	s_add_i32 s14, s20, 0xfffff8e0
	s_lshr_b32 s0, s14, 7
	s_add_i32 s70, s0, 1
	s_lshl_b64 s[0:1], s[70:71], 23
	s_add_u32 s0, s4, s0
	s_addc_u32 s1, s5, s1
	s_lshl_b32 s14, s14, 3
	v_mov_b32_e32 v44, v236
	s_and_b32 s15, s14, 0x3c0
	s_lshl_b32 s14, s20, 8
	s_and_b32 s14, s14, 0x700
	v_lshlrev_b32_e32 v1, 2, v44
	v_and_b32_e32 v38, 0xfc, v1
	v_ashrrev_i32_e32 v39, 6, v44
	v_or_b32_e32 v1, s14, v38
	v_add_u32_e32 v4, s15, v39
	v_lshlrev_b32_e32 v2, 2, v1
	v_mov_b32_e32 v3, v0
	v_ashrrev_i32_e32 v5, 31, v4
	v_lshl_add_u64 v[2:3], s[0:1], 0, v[2:3]
	v_lshlrev_b64 v[4:5], 13, v[4:5]
	v_lshl_add_u64 v[6:7], v[2:3], 0, v[4:5]
	v_add_u32_e32 v5, 0x200, v44
	v_ashrrev_i32_e32 v40, 6, v5
	v_add_u32_e32 v4, 0x400, v44
	v_add_u32_e32 v1, 0x600, v44
	v_add_u32_e32 v8, s15, v40
	v_ashrrev_i32_e32 v42, 6, v4
	v_ashrrev_i32_e32 v45, 6, v1
	v_ashrrev_i32_e32 v9, 31, v8
	v_add_u32_e32 v14, s15, v42
	v_add_u32_e32 v16, s15, v45
	v_add_u32_e32 v22, 0x800, v44
	v_add_u32_e32 v24, 0xa00, v44
	v_lshlrev_b64 v[8:9], 13, v[8:9]
	v_ashrrev_i32_e32 v15, 31, v14
	v_ashrrev_i32_e32 v17, 31, v16
	v_ashrrev_i32_e32 v46, 6, v22
	v_ashrrev_i32_e32 v47, 6, v24
	v_add_u32_e32 v30, 0xc00, v44
	v_add_u32_e32 v34, 0xe00, v44
	v_lshl_add_u64 v[10:11], v[2:3], 0, v[8:9]
	v_lshlrev_b64 v[14:15], 13, v[14:15]
	v_lshlrev_b64 v[16:17], 13, v[16:17]
	v_add_u32_e32 v22, s15, v46
	v_add_u32_e32 v24, s15, v47
	v_ashrrev_i32_e32 v48, 6, v30
	v_ashrrev_i32_e32 v49, 6, v34
	global_load_dwordx4 v[6:9], v[6:7], off
	s_nop 0
	global_load_dwordx4 v[10:13], v[10:11], off
	v_lshl_add_u64 v[14:15], v[2:3], 0, v[14:15]
	v_lshl_add_u64 v[18:19], v[2:3], 0, v[16:17]
	v_ashrrev_i32_e32 v23, 31, v22
	v_ashrrev_i32_e32 v25, 31, v24
	v_add_u32_e32 v30, s15, v48
	v_add_u32_e32 v34, s15, v49
	global_load_dwordx4 v[14:17], v[14:15], off
	s_nop 0
	global_load_dwordx4 v[18:21], v[18:19], off
	v_lshlrev_b64 v[22:23], 13, v[22:23]
	v_lshlrev_b64 v[24:25], 13, v[24:25]
	v_ashrrev_i32_e32 v31, 31, v30
	v_ashrrev_i32_e32 v35, 31, v34
	v_lshl_add_u64 v[22:23], v[2:3], 0, v[22:23]
	v_lshl_add_u64 v[26:27], v[2:3], 0, v[24:25]
	v_lshlrev_b64 v[30:31], 13, v[30:31]
	v_lshlrev_b64 v[34:35], 13, v[34:35]
	global_load_dwordx4 v[22:25], v[22:23], off
	s_nop 0
	global_load_dwordx4 v[26:29], v[26:27], off
	v_lshl_add_u64 v[30:31], v[2:3], 0, v[30:31]
	v_lshl_add_u64 v[2:3], v[2:3], 0, v[34:35]
	global_load_dwordx4 v[30:33], v[30:31], off
	s_movk_i32 s18, 0x414
	global_load_dwordx4 v[34:37], v[2:3], off
	v_lshl_add_u32 v2, v38, 2, 0
	s_lshl_b64 s[0:1], s[70:71], 22
	v_mad_u64_u32 v[38:39], s[16:17], v39, s18, v[2:3]
	v_mad_u64_u32 v[40:41], s[16:17], v40, s18, v[2:3]
	v_mad_u64_u32 v[42:43], s[16:17], v42, s18, v[2:3]
	s_add_u32 s16, s28, s0
	s_addc_u32 s17, s29, s1
	s_waitcnt lgkmcnt(0)
	s_barrier
	s_waitcnt vmcnt(0)
	ds_write2_b32 v38, v6, v7 offset1:1
	ds_write2_b32 v38, v8, v9 offset0:2 offset1:3
	ds_write2_b32 v40, v10, v11 offset1:1
	ds_write2_b32 v40, v12, v13 offset0:2 offset1:3
	ds_write2_b32 v42, v14, v15 offset1:1
	ds_write2_b32 v42, v16, v17 offset0:2 offset1:3
	v_mad_u64_u32 v[6:7], s[0:1], v45, s18, v[2:3]
	ds_write2_b32 v6, v18, v19 offset1:1
	ds_write2_b32 v6, v20, v21 offset0:2 offset1:3
	v_mad_u64_u32 v[6:7], s[0:1], v46, s18, v[2:3]
	ds_write2_b32 v6, v22, v23 offset1:1
	ds_write2_b32 v6, v24, v25 offset0:2 offset1:3
	v_mad_u64_u32 v[6:7], s[0:1], v47, s18, v[2:3]
	ds_write2_b32 v6, v26, v27 offset1:1
	ds_write2_b32 v6, v28, v29 offset0:2 offset1:3
	v_mad_u64_u32 v[6:7], s[0:1], v48, s18, v[2:3]
	v_mad_u64_u32 v[2:3], s[0:1], v49, s18, v[2:3]
	ds_write2_b32 v6, v30, v31 offset1:1
	ds_write2_b32 v6, v32, v33 offset0:2 offset1:3
	ds_write2_b32 v2, v34, v35 offset1:1
	ds_write2_b32 v2, v36, v37 offset0:2 offset1:3
	v_lshlrev_b32_e32 v2, 3, v44
	s_lshl_b32 s0, s15, 1
	v_and_b32_e32 v6, 56, v2
	s_add_u32 s0, s16, s0
	s_addc_u32 s1, s17, 0
	v_lshlrev_b32_e32 v2, 1, v6
	v_mov_b32_e32 v3, v0
	v_ashrrev_i32_e32 v8, 3, v44
	v_lshl_add_u64 v[2:3], s[0:1], 0, v[2:3]
	v_add_u32_e32 v7, s14, v8
	s_movk_i32 s0, 0x800
	v_cmp_gt_u32_e32 vcc, s0, v7
	v_mul_u32_u24_e32 v6, 0x414, v6
	s_waitcnt lgkmcnt(0)
	s_barrier
	s_and_saveexec_b64 s[0:1], vcc
	s_cbranch_execz .LBB0_783
	v_lshlrev_b32_e32 v8, 2, v8
	v_add3_u32 v8, 0, v8, v6
	ds_read_b32 v9, v8
	ds_read_b32 v10, v8 offset:1044
	ds_read_b32 v11, v8 offset:2088
	ds_read_b32 v12, v8 offset:3132
	ds_read_b32 v13, v8 offset:4176
	ds_read_b32 v14, v8 offset:5220
	ds_read_b32 v15, v8 offset:6264
	ds_read_b32 v16, v8 offset:7308
	s_waitcnt lgkmcnt(6)
	v_cvt_pk_bf16_f32 v8, v9, v10
	s_waitcnt lgkmcnt(4)
	v_cvt_pk_bf16_f32 v9, v11, v12
	s_waitcnt lgkmcnt(2)
	v_cvt_pk_bf16_f32 v10, v13, v14
	v_lshlrev_b32_e32 v12, 11, v7
	v_mov_b32_e32 v13, v0
	s_waitcnt lgkmcnt(0)
	v_cvt_pk_bf16_f32 v11, v15, v16
	v_lshl_add_u64 v[12:13], v[2:3], 0, v[12:13]
	global_store_dwordx4 v[12:13], v[8:11], off
; __device__ __forceinline__ unsigned cvt_pk_bf16(float lo, float hi) { f32x2_t f = {lo, hi}; bf16x2_t v = __builtin_convertvector(f, bf16x2_t); return __builtin_bit_cast(unsigned, v); }
; __device__ __forceinline__ void conv_tile(LAS float* tl, const float* src, int ldsrc, int k0, int n0, int N, bf16_t* dst, int lddst, int mode, int wv) {
;     ...
;     for (int i = 0; i < 4; ++i) { const int item = i * 512 + tid, nl = item >> 3, k8 = (item & 7) * 8, n = n0 + nl;
;         int row = n;
;         if (mode == 0) row = n < 8192 ? n : (n < 8200 ? -1 : n - 8);
;         else if (mode == 2) { const int c = n % DFF, gt = n / DFF; row = (c >> 7) * 256 + gt * 128 + (c & 127); }
;         if (n < N && row >= 0) {
;             float x[8];
; #pragma unroll
;             for (int j = 0; j < 8; ++j) x[j] = tl[(k8 + j) * S + nl];
;             u32x4 w; w.x = cvt_pk_bf16(x[0], x[1]); w.y = cvt_pk_bf16(x[2], x[3]); w.z = cvt_pk_bf16(x[4], x[5]); w.w = cvt_pk_bf16(x[6], x[7]);
;             *(u32x4*)(dst + (size_t)row * lddst + k0 + k8) = w;
;         } }
.LBB0_783:
	s_or_b64 exec, exec, s[0:1]
	v_ashrrev_i32_e32 v7, 3, v5
	v_add_u32_e32 v5, s14, v7
	s_movk_i32 s0, 0x800
	v_cmp_gt_u32_e32 vcc, s0, v5
	s_and_saveexec_b64 s[0:1], vcc
	s_cbranch_execz .LBB0_785
	v_lshlrev_b32_e32 v7, 2, v7
	v_add3_u32 v7, 0, v7, v6
	ds_read_b32 v8, v7
	ds_read_b32 v9, v7 offset:1044
	ds_read_b32 v10, v7 offset:2088
	ds_read_b32 v11, v7 offset:3132
	ds_read_b32 v12, v7 offset:4176
	ds_read_b32 v13, v7 offset:5220
	ds_read_b32 v14, v7 offset:6264
	ds_read_b32 v7, v7 offset:7308
	s_waitcnt lgkmcnt(0)
	v_cvt_pk_bf16_f32 v8, v8, v9
	v_cvt_pk_bf16_f32 v9, v10, v11
	v_cvt_pk_bf16_f32 v10, v12, v13
	v_lshlrev_b32_e32 v12, 11, v5
	v_mov_b32_e32 v13, v0
	v_cvt_pk_bf16_f32 v11, v14, v7
	v_lshl_add_u64 v[12:13], v[2:3], 0, v[12:13]
	global_store_dwordx4 v[12:13], v[8:11], off
.LBB0_785:
	s_or_b64 exec, exec, s[0:1]
	v_ashrrev_i32_e32 v5, 3, v4
	v_add_u32_e32 v4, s14, v5
	s_movk_i32 s0, 0x800
	v_cmp_gt_u32_e32 vcc, s0, v4
	s_and_saveexec_b64 s[0:1], vcc
	s_cbranch_execz .LBB0_787
	v_lshlrev_b32_e32 v5, 2, v5
	v_add3_u32 v5, 0, v5, v6
	ds_read_b32 v7, v5
	ds_read_b32 v8, v5 offset:1044
	ds_read_b32 v9, v5 offset:2088
	ds_read_b32 v10, v5 offset:3132
	ds_read_b32 v11, v5 offset:4176
	ds_read_b32 v12, v5 offset:5220
	ds_read_b32 v13, v5 offset:6264
	ds_read_b32 v5, v5 offset:7308
	s_waitcnt lgkmcnt(0)
	v_cvt_pk_bf16_f32 v9, v9, v10
	v_lshlrev_b32_e32 v4, 11, v4
	v_cvt_pk_bf16_f32 v10, v11, v12
	v_cvt_pk_bf16_f32 v8, v7, v8
	v_cvt_pk_bf16_f32 v11, v13, v5
	v_mov_b32_e32 v5, v0
	v_lshl_add_u64 v[4:5], v[2:3], 0, v[4:5]
	global_store_dwordx4 v[4:5], v[8:11], off
.LBB0_787:
	s_or_b64 exec, exec, s[0:1]
	v_ashrrev_i32_e32 v4, 3, v1
	v_add_u32_e32 v1, s14, v4
	s_movk_i32 s0, 0x800
	v_cmp_gt_u32_e32 vcc, s0, v1
	s_and_saveexec_b64 s[0:1], vcc
	s_cbranch_execz .LBB0_789
	v_lshlrev_b32_e32 v4, 2, v4
	v_add3_u32 v4, 0, v4, v6
	ds_read_b32 v5, v4
	ds_read_b32 v6, v4 offset:1044
	ds_read_b32 v7, v4 offset:2088
	ds_read_b32 v8, v4 offset:3132
	ds_read_b32 v9, v4 offset:4176
	ds_read_b32 v10, v4 offset:5220
	ds_read_b32 v11, v4 offset:6264
	ds_read_b32 v12, v4 offset:7308
	s_waitcnt lgkmcnt(0)
	v_cvt_pk_bf16_f32 v4, v5, v6
	v_cvt_pk_bf16_f32 v5, v7, v8
	v_cvt_pk_bf16_f32 v6, v9, v10
	v_lshlrev_b32_e32 v8, 11, v1
	v_mov_b32_e32 v9, v0
	v_cvt_pk_bf16_f32 v7, v11, v12
	v_lshl_add_u64 v[2:3], v[2:3], 0, v[8:9]
	global_store_dwordx4 v[2:3], v[4:7], off

; __device__ __forceinline__ void conv_tile(LAS float* tl, const float* src, int ldsrc, int k0, int n0, int N, bf16_t* dst, int lddst, int mode, int wv) {
;     ...
;     for (int i = 0; i < 8; ++i) { const int e = i * 512 + tid, kk = e >> 6, n = n0 + (e & 63) * 4;
;         v[i] = (f32x4){0.f, 0.f, 0.f, 0.f};
;         if (n + 3 < N) v[i] = *(const f32x4*)(src + (size_t)(k0 + kk) * ldsrc + n);
;         else { for (int j = 0; j < 4; ++j) if (n + j < N) v[i][j] = src[(size_t)(k0 + kk) * ldsrc + n + j]; } }
; __device__ NOINL void convert_weights(const float* win, const float* wbr, const float* wout, const float* wup, const float* wdown, unsigned char* ws, LAS unsigned char* lds, int wv) {
;     ...
;         if (t < T0) { const int tk = t / 57, tn = t % 57;
;             conv_tile(tl, win, DIN, tk * 64, tn * 256, DIN, (bf16_t*)(ws + WS_WIN), 2048, 0, wv); }
.LBB0_791:
	s_andn2_b64 vcc, exec, s[0:1]
	s_cbranch_vccnz .LBB0_745
	s_mul_hi_i32 s0, s20, 0x8fb823ef
	s_add_i32 s0, s0, s20
	s_lshr_b32 s1, s0, 31
	s_ashr_i32 s0, s0, 5
	s_add_i32 s0, s0, s1
	s_mul_i32 s1, s0, 57
	v_mov_b32_e32 v40, v236
	s_sub_i32 s1, s20, s1
	s_lshl_b32 s30, s1, 8
	v_lshlrev_b32_e32 v1, 2, v40
	v_and_b32_e32 v41, 0xfc, v1
	v_or_b32_e32 v36, s30, v41
	s_lshl_b32 s14, s0, 6
	v_or_b32_e32 v1, 3, v36
	s_movk_i32 s0, 0x3807
	v_ashrrev_i32_e32 v37, 31, v36
	v_ashrrev_i32_e32 v42, 6, v40
	v_cmp_lt_i32_e32 vcc, s0, v1
	v_lshl_add_u64 v[32:33], v[36:37], 2, s[2:3]
	v_add_u32_e32 v1, s14, v42
	v_mad_i64_i32 v[8:9], s[0:1], v1, s41, v[32:33]
	s_and_saveexec_b64 s[0:1], vcc
	s_xor_b64 s[16:17], exec, s[0:1]
	s_cbranch_execz .LBB0_798
	v_mov_b32_e32 v2, v0
	v_mov_b32_e32 v3, v0
	s_movk_i32 s0, 0x3808
	v_mov_b32_e32 v1, v0
	v_mov_b64_e32 v[6:7], v[2:3]
	v_cmp_gt_u32_e64 s[0:1], s0, v36
	v_mov_b64_e32 v[4:5], v[0:1]
	s_and_saveexec_b64 s[18:19], s[0:1]
	s_cbranch_execz .LBB0_864
	global_load_dword v4, v[8:9], off
	v_mov_b32_e32 v5, v0
	v_mov_b32_e32 v6, v0
	v_mov_b32_e32 v7, v0
	s_or_b64 exec, exec, s[18:19]
	s_and_saveexec_b64 s[18:19], s[0:1]
	s_cbranch_execnz .LBB0_865

; __device__ __forceinline__ void conv_tile(LAS float* tl, const float* src, int ldsrc, int k0, int n0, int N, bf16_t* dst, int lddst, int mode, int wv) {
;     ...
;         else { for (int j = 0; j < 4; ++j) if (n + j < N) v[i][j] = src[(size_t)(k0 + kk) * ldsrc + n + j]; } }
.LBB0_796:
	global_load_dword v6, v[8:9], off offset:8

; __device__ __forceinline__ void conv_tile(LAS float* tl, const float* src, int ldsrc, int k0, int n0, int N, bf16_t* dst, int lddst, int mode, int wv) {
;     ...
;     for (int i = 0; i < 8; ++i) { const int e = i * 512 + tid, kk = e >> 6, n = n0 + (e & 63) * 4;
;         v[i] = (f32x4){0.f, 0.f, 0.f, 0.f};
;         if (n + 3 < N) v[i] = *(const f32x4*)(src + (size_t)(k0 + kk) * ldsrc + n);
;         else { for (int j = 0; j < 4; ++j) if (n + j < N) v[i][j] = src[(size_t)(k0 + kk) * ldsrc + n + j]; } }
.LBB0_798:
	s_andn2_saveexec_b64 s[0:1], s[16:17]
	s_cbranch_execz .LBB0_800
	s_waitcnt vmcnt(0) lgkmcnt(0)
	global_load_dwordx4 v[4:7], v[8:9], off
.LBB0_800:
	s_or_b64 exec, exec, s[0:1]
	v_add_u32_e32 v37, 0x200, v40
	v_ashrrev_i32_e32 v45, 6, v37
	v_add_u32_e32 v1, s14, v45
	v_mad_i64_i32 v[12:13], s[0:1], v1, s41, v[32:33]
	s_and_saveexec_b64 s[0:1], vcc
	s_xor_b64 s[16:17], exec, s[0:1]
	s_cbranch_execz .LBB0_806
	v_mov_b32_e32 v2, v0
	v_mov_b32_e32 v3, v0
	s_movk_i32 s0, 0x3808
	v_mov_b32_e32 v1, v0
	v_mov_b64_e32 v[10:11], v[2:3]
	v_cmp_gt_u32_e64 s[0:1], s0, v36
	v_mov_b64_e32 v[8:9], v[0:1]
	s_and_saveexec_b64 s[18:19], s[0:1]
	s_cbranch_execz .LBB0_866
	global_load_dword v8, v[12:13], off
	v_mov_b32_e32 v9, v0
	v_mov_b32_e32 v10, v0
	v_mov_b32_e32 v11, v0
	s_or_b64 exec, exec, s[18:19]
	s_and_saveexec_b64 s[18:19], s[0:1]
	s_cbranch_execnz .LBB0_867

; __device__ __forceinline__ void conv_tile(LAS float* tl, const float* src, int ldsrc, int k0, int n0, int N, bf16_t* dst, int lddst, int mode, int wv) {
;     ...
;         else { for (int j = 0; j < 4; ++j) if (n + j < N) v[i][j] = src[(size_t)(k0 + kk) * ldsrc + n + j]; } }
.LBB0_804:
	global_load_dword v10, v[12:13], off offset:8

; __device__ __forceinline__ void conv_tile(LAS float* tl, const float* src, int ldsrc, int k0, int n0, int N, bf16_t* dst, int lddst, int mode, int wv) {
;     ...
;     for (int i = 0; i < 8; ++i) { const int e = i * 512 + tid, kk = e >> 6, n = n0 + (e & 63) * 4;
;         v[i] = (f32x4){0.f, 0.f, 0.f, 0.f};
;         if (n + 3 < N) v[i] = *(const f32x4*)(src + (size_t)(k0 + kk) * ldsrc + n);
;         else { for (int j = 0; j < 4; ++j) if (n + j < N) v[i][j] = src[(size_t)(k0 + kk) * ldsrc + n + j]; } }
.LBB0_806:
	s_andn2_saveexec_b64 s[0:1], s[16:17]
	s_cbranch_execz .LBB0_808
	s_waitcnt vmcnt(0) lgkmcnt(0)
	global_load_dwordx4 v[8:11], v[12:13], off
.LBB0_808:
	s_or_b64 exec, exec, s[0:1]
	v_add_u32_e32 v43, 0x400, v40
	v_ashrrev_i32_e32 v46, 6, v43
	v_add_u32_e32 v1, s14, v46
	v_mad_i64_i32 v[16:17], s[0:1], v1, s41, v[32:33]
	s_and_saveexec_b64 s[0:1], vcc
	s_xor_b64 s[16:17], exec, s[0:1]
	s_cbranch_execz .LBB0_814
	v_mov_b32_e32 v2, v0
	v_mov_b32_e32 v3, v0
	s_movk_i32 s0, 0x3808
	v_mov_b32_e32 v1, v0
	v_mov_b64_e32 v[14:15], v[2:3]
	v_cmp_gt_u32_e64 s[0:1], s0, v36
	v_mov_b64_e32 v[12:13], v[0:1]
	s_and_saveexec_b64 s[18:19], s[0:1]
	s_cbranch_execz .LBB0_868
	global_load_dword v12, v[16:17], off
	v_mov_b32_e32 v13, v0
	v_mov_b32_e32 v14, v0
	v_mov_b32_e32 v15, v0
	s_or_b64 exec, exec, s[18:19]
	s_and_saveexec_b64 s[18:19], s[0:1]
	s_cbranch_execnz .LBB0_869

; __device__ __forceinline__ void conv_tile(LAS float* tl, const float* src, int ldsrc, int k0, int n0, int N, bf16_t* dst, int lddst, int mode, int wv) {
;     ...
;         else { for (int j = 0; j < 4; ++j) if (n + j < N) v[i][j] = src[(size_t)(k0 + kk) * ldsrc + n + j]; } }
.LBB0_812:
	global_load_dword v14, v[16:17], off offset:8

; __device__ __forceinline__ void conv_tile(LAS float* tl, const float* src, int ldsrc, int k0, int n0, int N, bf16_t* dst, int lddst, int mode, int wv) {
;     ...
;     for (int i = 0; i < 8; ++i) { const int e = i * 512 + tid, kk = e >> 6, n = n0 + (e & 63) * 4;
;         v[i] = (f32x4){0.f, 0.f, 0.f, 0.f};
;         if (n + 3 < N) v[i] = *(const f32x4*)(src + (size_t)(k0 + kk) * ldsrc + n);
;         else { for (int j = 0; j < 4; ++j) if (n + j < N) v[i][j] = src[(size_t)(k0 + kk) * ldsrc + n + j]; } }
.LBB0_814:
	s_andn2_saveexec_b64 s[0:1], s[16:17]
	s_cbranch_execz .LBB0_816
	s_waitcnt vmcnt(0) lgkmcnt(0)
	global_load_dwordx4 v[12:15], v[16:17], off
.LBB0_816:
	s_or_b64 exec, exec, s[0:1]
	v_add_u32_e32 v44, 0x600, v40
	v_ashrrev_i32_e32 v47, 6, v44
	v_add_u32_e32 v1, s14, v47
	v_mad_i64_i32 v[20:21], s[0:1], v1, s41, v[32:33]
	s_and_saveexec_b64 s[0:1], vcc
	s_xor_b64 s[16:17], exec, s[0:1]
	s_cbranch_execz .LBB0_822
	v_mov_b32_e32 v2, v0
	v_mov_b32_e32 v3, v0
	s_movk_i32 s0, 0x3808
	v_mov_b32_e32 v1, v0
	v_mov_b64_e32 v[18:19], v[2:3]
	v_cmp_gt_u32_e64 s[0:1], s0, v36
	v_mov_b64_e32 v[16:17], v[0:1]
	s_and_saveexec_b64 s[18:19], s[0:1]
	s_cbranch_execz .LBB0_870
	global_load_dword v16, v[20:21], off
	v_mov_b32_e32 v17, v0
	v_mov_b32_e32 v18, v0
	v_mov_b32_e32 v19, v0
	s_or_b64 exec, exec, s[18:19]
	s_and_saveexec_b64 s[18:19], s[0:1]
	s_cbranch_execnz .LBB0_871

; __device__ __forceinline__ void conv_tile(LAS float* tl, const float* src, int ldsrc, int k0, int n0, int N, bf16_t* dst, int lddst, int mode, int wv) {
;     ...
;         else { for (int j = 0; j < 4; ++j) if (n + j < N) v[i][j] = src[(size_t)(k0 + kk) * ldsrc + n + j]; } }
.LBB0_820:
	global_load_dword v18, v[20:21], off offset:8

; __device__ __forceinline__ void conv_tile(LAS float* tl, const float* src, int ldsrc, int k0, int n0, int N, bf16_t* dst, int lddst, int mode, int wv) {
;     ...
;     for (int i = 0; i < 8; ++i) { const int e = i * 512 + tid, kk = e >> 6, n = n0 + (e & 63) * 4;
;         v[i] = (f32x4){0.f, 0.f, 0.f, 0.f};
;         if (n + 3 < N) v[i] = *(const f32x4*)(src + (size_t)(k0 + kk) * ldsrc + n);
;         else { for (int j = 0; j < 4; ++j) if (n + j < N) v[i][j] = src[(size_t)(k0 + kk) * ldsrc + n + j]; } }
.LBB0_822:
	s_andn2_saveexec_b64 s[0:1], s[16:17]
	s_cbranch_execz .LBB0_824
	s_waitcnt vmcnt(0) lgkmcnt(0)
	global_load_dwordx4 v[16:19], v[20:21], off
.LBB0_824:
	s_or_b64 exec, exec, s[0:1]
	v_add_u32_e32 v1, 0x800, v40
	v_ashrrev_i32_e32 v48, 6, v1
	v_add_u32_e32 v1, s14, v48
	v_mad_i64_i32 v[24:25], s[0:1], v1, s41, v[32:33]
	s_and_saveexec_b64 s[0:1], vcc
	s_xor_b64 s[16:17], exec, s[0:1]
	s_cbranch_execz .LBB0_830
	v_mov_b32_e32 v2, v0
	v_mov_b32_e32 v3, v0
	s_movk_i32 s0, 0x3808
	v_mov_b32_e32 v1, v0
	v_mov_b64_e32 v[22:23], v[2:3]
	v_cmp_gt_u32_e64 s[0:1], s0, v36
	v_mov_b64_e32 v[20:21], v[0:1]
	s_and_saveexec_b64 s[18:19], s[0:1]
	s_cbranch_execz .LBB0_872
	global_load_dword v20, v[24:25], off
	v_mov_b32_e32 v21, v0
	v_mov_b32_e32 v22, v0
	v_mov_b32_e32 v23, v0
	s_or_b64 exec, exec, s[18:19]
	s_and_saveexec_b64 s[18:19], s[0:1]
	s_cbranch_execnz .LBB0_873

; __device__ __forceinline__ void conv_tile(LAS float* tl, const float* src, int ldsrc, int k0, int n0, int N, bf16_t* dst, int lddst, int mode, int wv) {
;     ...
;         else { for (int j = 0; j < 4; ++j) if (n + j < N) v[i][j] = src[(size_t)(k0 + kk) * ldsrc + n + j]; } }
.LBB0_828:
	global_load_dword v22, v[24:25], off offset:8

; __device__ __forceinline__ void conv_tile(LAS float* tl, const float* src, int ldsrc, int k0, int n0, int N, bf16_t* dst, int lddst, int mode, int wv) {
;     ...
;     for (int i = 0; i < 8; ++i) { const int e = i * 512 + tid, kk = e >> 6, n = n0 + (e & 63) * 4;
;         v[i] = (f32x4){0.f, 0.f, 0.f, 0.f};
;         if (n + 3 < N) v[i] = *(const f32x4*)(src + (size_t)(k0 + kk) * ldsrc + n);
;         else { for (int j = 0; j < 4; ++j) if (n + j < N) v[i][j] = src[(size_t)(k0 + kk) * ldsrc + n + j]; } }
.LBB0_830:
	s_andn2_saveexec_b64 s[0:1], s[16:17]
	s_cbranch_execz .LBB0_832
	s_waitcnt vmcnt(0) lgkmcnt(0)
	global_load_dwordx4 v[20:23], v[24:25], off
.LBB0_832:
	s_or_b64 exec, exec, s[0:1]
	v_add_u32_e32 v1, 0xa00, v40
	v_ashrrev_i32_e32 v49, 6, v1
	v_add_u32_e32 v1, s14, v49
	v_mad_i64_i32 v[28:29], s[0:1], v1, s41, v[32:33]
	s_and_saveexec_b64 s[0:1], vcc
	s_xor_b64 s[16:17], exec, s[0:1]
	s_cbranch_execz .LBB0_838
	v_mov_b32_e32 v2, v0
	v_mov_b32_e32 v3, v0
	s_movk_i32 s0, 0x3808
	v_mov_b32_e32 v1, v0
	v_mov_b64_e32 v[26:27], v[2:3]
	v_cmp_gt_u32_e64 s[0:1], s0, v36
	v_mov_b64_e32 v[24:25], v[0:1]
	s_and_saveexec_b64 s[18:19], s[0:1]
	s_cbranch_execz .LBB0_874
	global_load_dword v24, v[28:29], off
	v_mov_b32_e32 v25, v0
	v_mov_b32_e32 v26, v0
	v_mov_b32_e32 v27, v0
	s_or_b64 exec, exec, s[18:19]
	s_and_saveexec_b64 s[18:19], s[0:1]
	s_cbranch_execnz .LBB0_875

; __device__ __forceinline__ void conv_tile(LAS float* tl, const float* src, int ldsrc, int k0, int n0, int N, bf16_t* dst, int lddst, int mode, int wv) {
;     ...
;         else { for (int j = 0; j < 4; ++j) if (n + j < N) v[i][j] = src[(size_t)(k0 + kk) * ldsrc + n + j]; } }
.LBB0_836:
	global_load_dword v26, v[28:29], off offset:8

; __device__ __forceinline__ void conv_tile(LAS float* tl, const float* src, int ldsrc, int k0, int n0, int N, bf16_t* dst, int lddst, int mode, int wv) {
;     ...
;     for (int i = 0; i < 8; ++i) { const int e = i * 512 + tid, kk = e >> 6, n = n0 + (e & 63) * 4;
;         v[i] = (f32x4){0.f, 0.f, 0.f, 0.f};
;         if (n + 3 < N) v[i] = *(const f32x4*)(src + (size_t)(k0 + kk) * ldsrc + n);
;         else { for (int j = 0; j < 4; ++j) if (n + j < N) v[i][j] = src[(size_t)(k0 + kk) * ldsrc + n + j]; } }
.LBB0_838:
	s_andn2_saveexec_b64 s[0:1], s[16:17]
	s_cbranch_execz .LBB0_840
	s_waitcnt vmcnt(0) lgkmcnt(0)
	global_load_dwordx4 v[24:27], v[28:29], off
.LBB0_840:
	s_or_b64 exec, exec, s[0:1]
	v_add_u32_e32 v1, 0xc00, v40
	v_ashrrev_i32_e32 v50, 6, v1
	v_add_u32_e32 v1, s14, v50
	v_mad_i64_i32 v[34:35], s[0:1], v1, s41, v[32:33]
	s_and_saveexec_b64 s[0:1], vcc
	s_xor_b64 s[16:17], exec, s[0:1]
	s_cbranch_execz .LBB0_846
	v_mov_b32_e32 v2, v0
	v_mov_b32_e32 v3, v0
	s_movk_i32 s0, 0x3808
	v_mov_b32_e32 v1, v0
	v_mov_b64_e32 v[30:31], v[2:3]
	v_cmp_gt_u32_e64 s[0:1], s0, v36
	v_mov_b64_e32 v[28:29], v[0:1]
	s_and_saveexec_b64 s[18:19], s[0:1]
	s_cbranch_execz .LBB0_876
	global_load_dword v28, v[34:35], off
	v_mov_b32_e32 v29, v0
	v_mov_b32_e32 v30, v0
	v_mov_b32_e32 v31, v0
	s_or_b64 exec, exec, s[18:19]
	s_and_saveexec_b64 s[18:19], s[0:1]
	s_cbranch_execnz .LBB0_877

; __device__ __forceinline__ void conv_tile(LAS float* tl, const float* src, int ldsrc, int k0, int n0, int N, bf16_t* dst, int lddst, int mode, int wv) {
;     ...
;         else { for (int j = 0; j < 4; ++j) if (n + j < N) v[i][j] = src[(size_t)(k0 + kk) * ldsrc + n + j]; } }
.LBB0_844:
	global_load_dword v30, v[34:35], off offset:8

; __device__ __forceinline__ void conv_tile(LAS float* tl, const float* src, int ldsrc, int k0, int n0, int N, bf16_t* dst, int lddst, int mode, int wv) {
;     ...
;     for (int i = 0; i < 8; ++i) { const int e = i * 512 + tid, kk = e >> 6, n = n0 + (e & 63) * 4;
;         v[i] = (f32x4){0.f, 0.f, 0.f, 0.f};
;         if (n + 3 < N) v[i] = *(const f32x4*)(src + (size_t)(k0 + kk) * ldsrc + n);
;         else { for (int j = 0; j < 4; ++j) if (n + j < N) v[i][j] = src[(size_t)(k0 + kk) * ldsrc + n + j]; } }
.LBB0_846:
	s_andn2_saveexec_b64 s[0:1], s[16:17]
	s_cbranch_execz .LBB0_848
	s_waitcnt vmcnt(0) lgkmcnt(0)
	global_load_dwordx4 v[28:31], v[34:35], off
.LBB0_848:
	s_or_b64 exec, exec, s[0:1]
	v_add_u32_e32 v1, 0xe00, v40
	v_ashrrev_i32_e32 v51, 6, v1
	v_add_u32_e32 v1, s14, v51
	v_mad_i64_i32 v[38:39], s[0:1], v1, s41, v[32:33]
	s_and_saveexec_b64 s[0:1], vcc
	s_xor_b64 s[0:1], exec, s[0:1]
	s_cbranch_execz .LBB0_854
	v_mov_b32_e32 v2, v0
	v_mov_b32_e32 v3, v0
	s_movk_i32 s15, 0x3808
	v_mov_b32_e32 v1, v0
	v_mov_b64_e32 v[34:35], v[2:3]
	v_cmp_gt_u32_e32 vcc, s15, v36
	v_mov_b64_e32 v[32:33], v[0:1]
	s_and_saveexec_b64 s[16:17], vcc
	s_cbranch_execz .LBB0_878
	global_load_dword v32, v[38:39], off
	v_mov_b32_e32 v33, v0
	v_mov_b32_e32 v34, v0
	v_mov_b32_e32 v35, v0
	s_or_b64 exec, exec, s[16:17]
	s_and_saveexec_b64 s[16:17], vcc
	s_cbranch_execnz .LBB0_879

; __device__ __forceinline__ void conv_tile(LAS float* tl, const float* src, int ldsrc, int k0, int n0, int N, bf16_t* dst, int lddst, int mode, int wv) {
;     ...
;         else { for (int j = 0; j < 4; ++j) if (n + j < N) v[i][j] = src[(size_t)(k0 + kk) * ldsrc + n + j]; } }
.LBB0_852:
	global_load_dword v34, v[38:39], off offset:8

; __device__ __forceinline__ unsigned cvt_pk_bf16(float lo, float hi) { f32x2_t f = {lo, hi}; bf16x2_t v = __builtin_convertvector(f, bf16x2_t); return __builtin_bit_cast(unsigned, v); }
; __device__ __forceinline__ void conv_tile(LAS float* tl, const float* src, int ldsrc, int k0, int n0, int N, bf16_t* dst, int lddst, int mode, int wv) {
;     ...
;     for (int i = 0; i < 8; ++i) { const int e = i * 512 + tid, kk = e >> 6, n4 = (e & 63) * 4;
; #pragma unroll
;         for (int j = 0; j < 4; ++j) tl[kk * S + n4 + j] = v[i][j]; }
;     __syncthreads();
; #pragma unroll
;     for (int i = 0; i < 4; ++i) { const int item = i * 512 + tid, nl = item >> 3, k8 = (item & 7) * 8, n = n0 + nl;
;         int row = n;
;         if (mode == 0) row = n < 8192 ? n : (n < 8200 ? -1 : n - 8);
;         else if (mode == 2) { const int c = n % DFF, gt = n / DFF; row = (c >> 7) * 256 + gt * 128 + (c & 127); }
;         if (n < N && row >= 0) {
;             float x[8];
; #pragma unroll
;             for (int j = 0; j < 8; ++j) x[j] = tl[(k8 + j) * S + nl];
;             u32x4 w; w.x = cvt_pk_bf16(x[0], x[1]); w.y = cvt_pk_bf16(x[2], x[3]); w.z = cvt_pk_bf16(x[4], x[5]); w.w = cvt_pk_bf16(x[6], x[7]);
;             *(u32x4*)(dst + (size_t)row * lddst + k0 + k8) = w;
;         } }
.LBB0_854:
	s_andn2_saveexec_b64 s[0:1], s[0:1]
	s_cbranch_execz .LBB0_856
	s_waitcnt vmcnt(0) lgkmcnt(0)
	global_load_dwordx4 v[32:35], v[38:39], off
.LBB0_856:
	s_or_b64 exec, exec, s[0:1]
	v_lshl_add_u32 v2, v41, 2, 0
	s_movk_i32 s15, 0x414
	v_mad_u64_u32 v[38:39], s[0:1], v42, s15, v[2:3]
	s_waitcnt lgkmcnt(0)
	s_barrier
	s_waitcnt vmcnt(0)
	ds_write2_b32 v38, v4, v5 offset1:1
	ds_write2_b32 v38, v6, v7 offset0:2 offset1:3
	v_mad_u64_u32 v[4:5], s[0:1], v45, s15, v[2:3]
	ds_write2_b32 v4, v8, v9 offset1:1
	ds_write2_b32 v4, v10, v11 offset0:2 offset1:3
	v_mad_u64_u32 v[4:5], s[0:1], v46, s15, v[2:3]
	ds_write2_b32 v4, v12, v13 offset1:1
	ds_write2_b32 v4, v14, v15 offset0:2 offset1:3
	v_mad_u64_u32 v[4:5], s[0:1], v47, s15, v[2:3]
	ds_write2_b32 v4, v16, v17 offset1:1
	ds_write2_b32 v4, v18, v19 offset0:2 offset1:3
	v_mad_u64_u32 v[4:5], s[0:1], v48, s15, v[2:3]
	ds_write2_b32 v4, v20, v21 offset1:1
	ds_write2_b32 v4, v22, v23 offset0:2 offset1:3
	v_mad_u64_u32 v[4:5], s[0:1], v49, s15, v[2:3]
	ds_write2_b32 v4, v24, v25 offset1:1
	ds_write2_b32 v4, v26, v27 offset0:2 offset1:3
	v_mad_u64_u32 v[4:5], s[0:1], v50, s15, v[2:3]
	v_mad_u64_u32 v[2:3], s[0:1], v51, s15, v[2:3]
	s_ashr_i32 s15, s14, 31
	v_lshlrev_b32_e32 v1, 3, v40
	s_lshl_b64 s[0:1], s[14:15], 1
	v_and_b32_e32 v1, 56, v1
	s_add_u32 s0, s12, s0
	ds_write2_b32 v4, v28, v29 offset1:1
	ds_write2_b32 v4, v30, v31 offset0:2 offset1:3
	ds_write2_b32 v2, v32, v33 offset1:1
	ds_write2_b32 v2, v34, v35 offset0:2 offset1:3
	s_addc_u32 s1, s13, s1
	v_lshlrev_b32_e32 v2, 1, v1
	v_mov_b32_e32 v3, v0
	v_ashrrev_i32_e32 v5, 3, v40
	v_lshl_add_u64 v[2:3], s[0:1], 0, v[2:3]
	v_add_u32_e32 v6, s30, v5
	s_movk_i32 s0, 0x2007
	v_add_u32_e32 v4, -8, v6
	v_cmp_lt_u32_e32 vcc, s0, v6
	s_movk_i32 s0, 0x3808
	v_mul_u32_u24_e32 v1, 0x414, v1
	v_cndmask_b32_e32 v4, -1, v4, vcc
	v_cmp_gt_i32_e32 vcc, s40, v6
	s_waitcnt lgkmcnt(0)
	s_barrier
	v_cndmask_b32_e32 v4, v4, v6, vcc
	v_cmp_gt_i32_e32 vcc, s0, v6
	v_cmp_lt_i32_e64 s[0:1], -1, v4
	s_and_b64 s[14:15], vcc, s[0:1]
	s_and_saveexec_b64 s[0:1], s[14:15]
	s_cbranch_execz .LBB0_858
	v_lshlrev_b32_e32 v5, 2, v5
	v_add3_u32 v5, 0, v5, v1
	ds_read_b32 v6, v5
	ds_read_b32 v7, v5 offset:1044
	ds_read_b32 v8, v5 offset:2088
	ds_read_b32 v9, v5 offset:3132
	ds_read_b32 v10, v5 offset:4176
	ds_read_b32 v11, v5 offset:5220
	ds_read_b32 v12, v5 offset:6264
	ds_read_b32 v5, v5 offset:7308
	s_waitcnt lgkmcnt(6)
	v_cvt_pk_bf16_f32 v6, v6, v7
	s_waitcnt lgkmcnt(4)
	v_cvt_pk_bf16_f32 v7, v8, v9
	s_waitcnt lgkmcnt(2)
	v_cvt_pk_bf16_f32 v8, v10, v11
	s_waitcnt lgkmcnt(0)
	v_cvt_pk_bf16_f32 v9, v12, v5
	v_mov_b32_e32 v5, v0
	v_lshlrev_b64 v[4:5], 12, v[4:5]
	v_lshl_add_u64 v[4:5], v[2:3], 0, v[4:5]
	global_store_dwordx4 v[4:5], v[6:9], off
.LBB0_858:
	s_or_b64 exec, exec, s[0:1]
	v_ashrrev_i32_e32 v5, 3, v37
	v_add_u32_e32 v6, s30, v5
	s_movk_i32 s0, 0x2007
	v_add_u32_e32 v4, -8, v6
	v_cmp_lt_u32_e32 vcc, s0, v6
	s_movk_i32 s0, 0x3808
	s_nop 0
	v_cndmask_b32_e32 v4, -1, v4, vcc
	v_cmp_gt_i32_e32 vcc, s40, v6
	s_nop 1
	v_cndmask_b32_e32 v4, v4, v6, vcc
	v_cmp_gt_i32_e32 vcc, s0, v6
	v_cmp_lt_i32_e64 s[0:1], -1, v4
	s_and_b64 s[14:15], vcc, s[0:1]
	s_and_saveexec_b64 s[0:1], s[14:15]
	s_cbranch_execz .LBB0_860
	v_lshlrev_b32_e32 v5, 2, v5
	v_add3_u32 v5, 0, v5, v1
	ds_read_b32 v6, v5
	ds_read_b32 v7, v5 offset:1044
	ds_read_b32 v8, v5 offset:2088
	ds_read_b32 v9, v5 offset:3132
	ds_read_b32 v10, v5 offset:4176
	ds_read_b32 v11, v5 offset:5220
	ds_read_b32 v12, v5 offset:6264
	ds_read_b32 v5, v5 offset:7308
	s_waitcnt lgkmcnt(0)
	v_cvt_pk_bf16_f32 v6, v6, v7
	v_cvt_pk_bf16_f32 v7, v8, v9
	v_cvt_pk_bf16_f32 v8, v10, v11
	v_cvt_pk_bf16_f32 v9, v12, v5
	v_mov_b32_e32 v5, v0
	v_lshlrev_b64 v[4:5], 12, v[4:5]
	v_lshl_add_u64 v[4:5], v[2:3], 0, v[4:5]
	global_store_dwordx4 v[4:5], v[6:9], off
.LBB0_860:
	s_or_b64 exec, exec, s[0:1]
	v_ashrrev_i32_e32 v5, 3, v43
	v_add_u32_e32 v6, s30, v5
	s_movk_i32 s0, 0x2007
	v_add_u32_e32 v4, -8, v6
	v_cmp_lt_u32_e32 vcc, s0, v6
	s_movk_i32 s0, 0x3808
	s_nop 0
	v_cndmask_b32_e32 v4, -1, v4, vcc
	v_cmp_gt_i32_e32 vcc, s40, v6
	s_nop 1
	v_cndmask_b32_e32 v4, v4, v6, vcc
	v_cmp_gt_i32_e32 vcc, s0, v6
	v_cmp_lt_i32_e64 s[0:1], -1, v4
	s_and_b64 s[14:15], vcc, s[0:1]
	s_and_saveexec_b64 s[0:1], s[14:15]
	s_cbranch_execz .LBB0_862
	v_lshlrev_b32_e32 v5, 2, v5
	v_add3_u32 v5, 0, v5, v1
	ds_read_b32 v6, v5
	ds_read_b32 v7, v5 offset:1044
	ds_read_b32 v8, v5 offset:2088
	ds_read_b32 v9, v5 offset:3132
	ds_read_b32 v10, v5 offset:4176
	ds_read_b32 v11, v5 offset:5220
	ds_read_b32 v12, v5 offset:6264
	ds_read_b32 v5, v5 offset:7308
	s_waitcnt lgkmcnt(0)
	v_cvt_pk_bf16_f32 v6, v6, v7
	v_cvt_pk_bf16_f32 v7, v8, v9
	v_cvt_pk_bf16_f32 v8, v10, v11
	v_cvt_pk_bf16_f32 v9, v12, v5
	v_mov_b32_e32 v5, v0
	v_lshlrev_b64 v[4:5], 12, v[4:5]
	v_lshl_add_u64 v[4:5], v[2:3], 0, v[4:5]
	global_store_dwordx4 v[4:5], v[6:9], off
.LBB0_862:
	s_or_b64 exec, exec, s[0:1]
	v_ashrrev_i32_e32 v5, 3, v44
	v_add_u32_e32 v6, s30, v5
	s_movk_i32 s0, 0x2007
	v_add_u32_e32 v4, -8, v6
	v_cmp_lt_u32_e32 vcc, s0, v6
	s_movk_i32 s0, 0x3808
	s_nop 0
	v_cndmask_b32_e32 v4, -1, v4, vcc
	v_cmp_gt_i32_e32 vcc, s40, v6
	s_nop 1
	v_cndmask_b32_e32 v4, v4, v6, vcc
	v_cmp_gt_i32_e32 vcc, s0, v6
	v_cmp_lt_i32_e64 s[0:1], -1, v4
	s_and_b64 s[14:15], vcc, s[0:1]
	s_and_saveexec_b64 s[0:1], s[14:15]
	s_cbranch_execz .LBB0_744
	v_lshlrev_b32_e32 v5, 2, v5
	v_add3_u32 v1, 0, v5, v1
	ds_read_b32 v5, v1
	ds_read_b32 v6, v1 offset:1044
	ds_read_b32 v7, v1 offset:2088
	ds_read_b32 v8, v1 offset:3132
	ds_read_b32 v9, v1 offset:4176
	ds_read_b32 v10, v1 offset:5220
	ds_read_b32 v11, v1 offset:6264
	ds_read_b32 v1, v1 offset:7308
	s_waitcnt lgkmcnt(0)
	v_cvt_pk_bf16_f32 v6, v5, v6
	v_mov_b32_e32 v5, v0
	v_lshlrev_b64 v[4:5], 12, v[4:5]
	v_cvt_pk_bf16_f32 v7, v7, v8
	v_cvt_pk_bf16_f32 v8, v9, v10
	v_cvt_pk_bf16_f32 v9, v11, v1
	v_lshl_add_u64 v[2:3], v[2:3], 0, v[4:5]
	global_store_dwordx4 v[2:3], v[6:9], off
	s_branch .LBB0_744

; __device__ __forceinline__ void conv_tile(LAS float* tl, const float* src, int ldsrc, int k0, int n0, int N, bf16_t* dst, int lddst, int mode, int wv) {
;     ...
;         else { for (int j = 0; j < 4; ++j) if (n + j < N) v[i][j] = src[(size_t)(k0 + kk) * ldsrc + n + j]; } }
.LBB0_865:
	global_load_dword v5, v[8:9], off offset:4
	s_or_b64 exec, exec, s[18:19]
	s_and_saveexec_b64 s[18:19], s[0:1]
	s_cbranch_execnz .LBB0_796
	s_branch .LBB0_797

; __device__ __forceinline__ void conv_tile(LAS float* tl, const float* src, int ldsrc, int k0, int n0, int N, bf16_t* dst, int lddst, int mode, int wv) {
;     ...
;         else { for (int j = 0; j < 4; ++j) if (n + j < N) v[i][j] = src[(size_t)(k0 + kk) * ldsrc + n + j]; } }
.LBB0_867:
	global_load_dword v9, v[12:13], off offset:4
	s_or_b64 exec, exec, s[18:19]
	s_and_saveexec_b64 s[18:19], s[0:1]
	s_cbranch_execnz .LBB0_804
	s_branch .LBB0_805

; __device__ __forceinline__ void conv_tile(LAS float* tl, const float* src, int ldsrc, int k0, int n0, int N, bf16_t* dst, int lddst, int mode, int wv) {
;     ...
;         else { for (int j = 0; j < 4; ++j) if (n + j < N) v[i][j] = src[(size_t)(k0 + kk) * ldsrc + n + j]; } }
.LBB0_869:
	global_load_dword v13, v[16:17], off offset:4
	s_or_b64 exec, exec, s[18:19]
	s_and_saveexec_b64 s[18:19], s[0:1]
	s_cbranch_execnz .LBB0_812
	s_branch .LBB0_813

; __device__ __forceinline__ void conv_tile(LAS float* tl, const float* src, int ldsrc, int k0, int n0, int N, bf16_t* dst, int lddst, int mode, int wv) {
;     ...
;         else { for (int j = 0; j < 4; ++j) if (n + j < N) v[i][j] = src[(size_t)(k0 + kk) * ldsrc + n + j]; } }
.LBB0_871:
	global_load_dword v17, v[20:21], off offset:4
	s_or_b64 exec, exec, s[18:19]
	s_and_saveexec_b64 s[18:19], s[0:1]
	s_cbranch_execnz .LBB0_820
	s_branch .LBB0_821

; __device__ __forceinline__ void conv_tile(LAS float* tl, const float* src, int ldsrc, int k0, int n0, int N, bf16_t* dst, int lddst, int mode, int wv) {
;     ...
;         else { for (int j = 0; j < 4; ++j) if (n + j < N) v[i][j] = src[(size_t)(k0 + kk) * ldsrc + n + j]; } }
.LBB0_873:
	global_load_dword v21, v[24:25], off offset:4
	s_or_b64 exec, exec, s[18:19]
	s_and_saveexec_b64 s[18:19], s[0:1]
	s_cbranch_execnz .LBB0_828
	s_branch .LBB0_829

; __device__ __forceinline__ void conv_tile(LAS float* tl, const float* src, int ldsrc, int k0, int n0, int N, bf16_t* dst, int lddst, int mode, int wv) {
;     ...
;         else { for (int j = 0; j < 4; ++j) if (n + j < N) v[i][j] = src[(size_t)(k0 + kk) * ldsrc + n + j]; } }
.LBB0_875:
	global_load_dword v25, v[28:29], off offset:4
	s_or_b64 exec, exec, s[18:19]
	s_and_saveexec_b64 s[18:19], s[0:1]
	s_cbranch_execnz .LBB0_836
	s_branch .LBB0_837

; __device__ __forceinline__ void conv_tile(LAS float* tl, const float* src, int ldsrc, int k0, int n0, int N, bf16_t* dst, int lddst, int mode, int wv) {
;     ...
;         else { for (int j = 0; j < 4; ++j) if (n + j < N) v[i][j] = src[(size_t)(k0 + kk) * ldsrc + n + j]; } }
.LBB0_877:
	global_load_dword v29, v[34:35], off offset:4
	s_or_b64 exec, exec, s[18:19]
	s_and_saveexec_b64 s[18:19], s[0:1]
	s_cbranch_execnz .LBB0_844
	s_branch .LBB0_845

; __device__ __forceinline__ void conv_tile(LAS float* tl, const float* src, int ldsrc, int k0, int n0, int N, bf16_t* dst, int lddst, int mode, int wv) {
;     ...
;         else { for (int j = 0; j < 4; ++j) if (n + j < N) v[i][j] = src[(size_t)(k0 + kk) * ldsrc + n + j]; } }
.LBB0_879:
	global_load_dword v33, v[38:39], off offset:4
	s_or_b64 exec, exec, s[16:17]
	s_and_saveexec_b64 s[16:17], vcc
	s_cbranch_execnz .LBB0_852
	s_branch .LBB0_853

; __device__ NOINL void prep_weff(const float* pw, const float* ps, const float* wb, bf16_t* dst, LAS unsigned char* lds, int wv) {
;     ...
;         const float* wp = wb + (size_t)(g * 256) * 2048 + n;
; #pragma unroll 4
;         for (int d = 0; d < 256; ++d) { const float w = wp[(size_t)d * 2048];
; #pragma unroll
;             for (int cc = 0; cc < 8; ++cc) acc[cc] += wl[cc * 256 + d] * w; }
.Lweff2_loop:
	global_load_dword v124, v184, s[8:9]
	s_add_u32 s8, s8, 0x2000
	s_addc_u32 s9, s9, 0
	global_load_dword v125, v184, s[8:9]
	s_add_u32 s8, s8, 0x2000
	s_addc_u32 s9, s9, 0
	global_load_dword v126, v184, s[8:9]
	s_add_u32 s8, s8, 0x2000
	s_addc_u32 s9, s9, 0
	global_load_dword v127, v184, s[8:9]
	s_add_u32 s8, s8, 0x2000
	s_addc_u32 s9, s9, 0
	global_load_dword v128, v184, s[8:9]
	s_add_u32 s8, s8, 0x2000
	s_addc_u32 s9, s9, 0
	global_load_dword v129, v184, s[8:9]
	s_add_u32 s8, s8, 0x2000
	s_addc_u32 s9, s9, 0
	global_load_dword v130, v184, s[8:9]
	s_add_u32 s8, s8, 0x2000
	s_addc_u32 s9, s9, 0
	global_load_dword v131, v184, s[8:9]
	s_add_u32 s8, s8, 0x2000
	s_addc_u32 s9, s9, 0
	ds_read_b128 v[64:67], v185 offset:0
	ds_read_b128 v[72:75], v185 offset:1024
	ds_read_b128 v[80:83], v185 offset:2048
	ds_read_b128 v[88:91], v185 offset:3072
	ds_read_b128 v[96:99], v185 offset:4096
	ds_read_b128 v[136:139], v185 offset:5120
	ds_read_b128 v[144:147], v185 offset:6144
	ds_read_b128 v[152:155], v185 offset:7168
	ds_read_b128 v[68:71], v185 offset:16
	ds_read_b128 v[76:79], v185 offset:1040
	ds_read_b128 v[84:87], v185 offset:2064
	ds_read_b128 v[92:95], v185 offset:3088
	ds_read_b128 v[132:135], v185 offset:4112
	ds_read_b128 v[140:143], v185 offset:5136
	ds_read_b128 v[148:151], v185 offset:6160
	ds_read_b128 v[156:159], v185 offset:7184
	s_waitcnt vmcnt(24)
	s_waitcnt lgkmcnt(8)
	v_pk_fma_f32 v[168:169], v[64:65], v[100:101], v[168:169]
	v_pk_fma_f32 v[170:171], v[72:73], v[100:101], v[170:171]
	v_pk_fma_f32 v[172:173], v[80:81], v[100:101], v[172:173]
	v_pk_fma_f32 v[174:175], v[88:89], v[100:101], v[174:175]
	v_pk_fma_f32 v[176:177], v[96:97], v[100:101], v[176:177]
	v_pk_fma_f32 v[178:179], v[136:137], v[100:101], v[178:179]
	v_pk_fma_f32 v[180:181], v[144:145], v[100:101], v[180:181]
	v_pk_fma_f32 v[182:183], v[152:153], v[100:101], v[182:183]
	v_pk_fma_f32 v[168:169], v[66:67], v[102:103], v[168:169]
	v_pk_fma_f32 v[170:171], v[74:75], v[102:103], v[170:171]
	v_pk_fma_f32 v[172:173], v[82:83], v[102:103], v[172:173]
	v_pk_fma_f32 v[174:175], v[90:91], v[102:103], v[174:175]
	v_pk_fma_f32 v[176:177], v[98:99], v[102:103], v[176:177]
	v_pk_fma_f32 v[178:179], v[138:139], v[102:103], v[178:179]
	v_pk_fma_f32 v[180:181], v[146:147], v[102:103], v[180:181]
	v_pk_fma_f32 v[182:183], v[154:155], v[102:103], v[182:183]
	s_waitcnt lgkmcnt(0)
	v_pk_fma_f32 v[168:169], v[68:69], v[104:105], v[168:169]
	v_pk_fma_f32 v[170:171], v[76:77], v[104:105], v[170:171]
	v_pk_fma_f32 v[172:173], v[84:85], v[104:105], v[172:173]
	v_pk_fma_f32 v[174:175], v[92:93], v[104:105], v[174:175]
	v_pk_fma_f32 v[176:177], v[132:133], v[104:105], v[176:177]
	v_pk_fma_f32 v[178:179], v[140:141], v[104:105], v[178:179]
	v_pk_fma_f32 v[180:181], v[148:149], v[104:105], v[180:181]
	v_pk_fma_f32 v[182:183], v[156:157], v[104:105], v[182:183]
	v_pk_fma_f32 v[168:169], v[70:71], v[106:107], v[168:169]
	v_pk_fma_f32 v[170:171], v[78:79], v[106:107], v[170:171]
	v_pk_fma_f32 v[172:173], v[86:87], v[106:107], v[172:173]
	v_pk_fma_f32 v[174:175], v[94:95], v[106:107], v[174:175]
	v_pk_fma_f32 v[176:177], v[134:135], v[106:107], v[176:177]
	v_pk_fma_f32 v[178:179], v[142:143], v[106:107], v[178:179]
	v_pk_fma_f32 v[180:181], v[150:151], v[106:107], v[180:181]
	v_pk_fma_f32 v[182:183], v[158:159], v[106:107], v[182:183]
	global_load_dword v100, v184, s[8:9]
	s_add_u32 s8, s8, 0x2000
	s_addc_u32 s9, s9, 0
	global_load_dword v101, v184, s[8:9]
	s_add_u32 s8, s8, 0x2000
	s_addc_u32 s9, s9, 0
	global_load_dword v102, v184, s[8:9]
	s_add_u32 s8, s8, 0x2000
	s_addc_u32 s9, s9, 0
	global_load_dword v103, v184, s[8:9]
	s_add_u32 s8, s8, 0x2000
	s_addc_u32 s9, s9, 0
	global_load_dword v104, v184, s[8:9]
	s_add_u32 s8, s8, 0x2000
	s_addc_u32 s9, s9, 0
	global_load_dword v105, v184, s[8:9]
	s_add_u32 s8, s8, 0x2000
	s_addc_u32 s9, s9, 0
	global_load_dword v106, v184, s[8:9]
	s_add_u32 s8, s8, 0x2000
	s_addc_u32 s9, s9, 0
	global_load_dword v107, v184, s[8:9]
	s_add_u32 s8, s8, 0x2000
	s_addc_u32 s9, s9, 0
	ds_read_b128 v[64:67], v185 offset:32
	ds_read_b128 v[72:75], v185 offset:1056
	ds_read_b128 v[80:83], v185 offset:2080
	ds_read_b128 v[88:91], v185 offset:3104
	ds_read_b128 v[96:99], v185 offset:4128
	ds_read_b128 v[136:139], v185 offset:5152
	ds_read_b128 v[144:147], v185 offset:6176
	ds_read_b128 v[152:155], v185 offset:7200
	ds_read_b128 v[68:71], v185 offset:48
	ds_read_b128 v[76:79], v185 offset:1072
	ds_read_b128 v[84:87], v185 offset:2096
	ds_read_b128 v[92:95], v185 offset:3120
	ds_read_b128 v[132:135], v185 offset:4144
	ds_read_b128 v[140:143], v185 offset:5168
	ds_read_b128 v[148:151], v185 offset:6192
	ds_read_b128 v[156:159], v185 offset:7216
	s_waitcnt vmcnt(24)
	s_waitcnt lgkmcnt(8)
	v_pk_fma_f32 v[168:169], v[64:65], v[108:109], v[168:169]
	v_pk_fma_f32 v[170:171], v[72:73], v[108:109], v[170:171]
	v_pk_fma_f32 v[172:173], v[80:81], v[108:109], v[172:173]
	v_pk_fma_f32 v[174:175], v[88:89], v[108:109], v[174:175]
	v_pk_fma_f32 v[176:177], v[96:97], v[108:109], v[176:177]
	v_pk_fma_f32 v[178:179], v[136:137], v[108:109], v[178:179]
	v_pk_fma_f32 v[180:181], v[144:145], v[108:109], v[180:181]
	v_pk_fma_f32 v[182:183], v[152:153], v[108:109], v[182:183]
	v_pk_fma_f32 v[168:169], v[66:67], v[110:111], v[168:169]
	v_pk_fma_f32 v[170:171], v[74:75], v[110:111], v[170:171]
	v_pk_fma_f32 v[172:173], v[82:83], v[110:111], v[172:173]
	v_pk_fma_f32 v[174:175], v[90:91], v[110:111], v[174:175]
	v_pk_fma_f32 v[176:177], v[98:99], v[110:111], v[176:177]
	v_pk_fma_f32 v[178:179], v[138:139], v[110:111], v[178:179]
	v_pk_fma_f32 v[180:181], v[146:147], v[110:111], v[180:181]
	v_pk_fma_f32 v[182:183], v[154:155], v[110:111], v[182:183]
	s_waitcnt lgkmcnt(0)
; __device__ NOINL void prep_weff(const float* pw, const float* ps, const float* wb, bf16_t* dst, LAS unsigned char* lds, int wv) {
;     ...
;         for (int d = 0; d < 256; ++d) { const float w = wp[(size_t)d * 2048];
; #pragma unroll
;             for (int cc = 0; cc < 8; ++cc) acc[cc] += wl[cc * 256 + d] * w; }
	v_pk_fma_f32 v[168:169], v[68:69], v[112:113], v[168:169]
	v_pk_fma_f32 v[170:171], v[76:77], v[112:113], v[170:171]
	v_pk_fma_f32 v[172:173], v[84:85], v[112:113], v[172:173]
	v_pk_fma_f32 v[174:175], v[92:93], v[112:113], v[174:175]
	v_pk_fma_f32 v[176:177], v[132:133], v[112:113], v[176:177]
	v_pk_fma_f32 v[178:179], v[140:141], v[112:113], v[178:179]
	v_pk_fma_f32 v[180:181], v[148:149], v[112:113], v[180:181]
	v_pk_fma_f32 v[182:183], v[156:157], v[112:113], v[182:183]
	v_pk_fma_f32 v[168:169], v[70:71], v[114:115], v[168:169]
	v_pk_fma_f32 v[170:171], v[78:79], v[114:115], v[170:171]
	v_pk_fma_f32 v[172:173], v[86:87], v[114:115], v[172:173]
	v_pk_fma_f32 v[174:175], v[94:95], v[114:115], v[174:175]
	v_pk_fma_f32 v[176:177], v[134:135], v[114:115], v[176:177]
	v_pk_fma_f32 v[178:179], v[142:143], v[114:115], v[178:179]
	v_pk_fma_f32 v[180:181], v[150:151], v[114:115], v[180:181]
	v_pk_fma_f32 v[182:183], v[158:159], v[114:115], v[182:183]
	global_load_dword v108, v184, s[8:9]
	s_add_u32 s8, s8, 0x2000
	s_addc_u32 s9, s9, 0
	global_load_dword v109, v184, s[8:9]
	s_add_u32 s8, s8, 0x2000
	s_addc_u32 s9, s9, 0
	global_load_dword v110, v184, s[8:9]
	s_add_u32 s8, s8, 0x2000
	s_addc_u32 s9, s9, 0
	global_load_dword v111, v184, s[8:9]
	s_add_u32 s8, s8, 0x2000
	s_addc_u32 s9, s9, 0
	global_load_dword v112, v184, s[8:9]
	s_add_u32 s8, s8, 0x2000
	s_addc_u32 s9, s9, 0
	global_load_dword v113, v184, s[8:9]
	s_add_u32 s8, s8, 0x2000
	s_addc_u32 s9, s9, 0
	global_load_dword v114, v184, s[8:9]
	s_add_u32 s8, s8, 0x2000
	s_addc_u32 s9, s9, 0
	global_load_dword v115, v184, s[8:9]
	s_add_u32 s8, s8, 0x2000
	s_addc_u32 s9, s9, 0
	ds_read_b128 v[64:67], v185 offset:64
	ds_read_b128 v[72:75], v185 offset:1088
	ds_read_b128 v[80:83], v185 offset:2112
	ds_read_b128 v[88:91], v185 offset:3136
	ds_read_b128 v[96:99], v185 offset:4160
	ds_read_b128 v[136:139], v185 offset:5184
	ds_read_b128 v[144:147], v185 offset:6208
	ds_read_b128 v[152:155], v185 offset:7232
	ds_read_b128 v[68:71], v185 offset:80
	ds_read_b128 v[76:79], v185 offset:1104
	ds_read_b128 v[84:87], v185 offset:2128
	ds_read_b128 v[92:95], v185 offset:3152
	ds_read_b128 v[132:135], v185 offset:4176
	ds_read_b128 v[140:143], v185 offset:5200
	ds_read_b128 v[148:151], v185 offset:6224
	ds_read_b128 v[156:159], v185 offset:7248
	s_waitcnt vmcnt(24)
	s_waitcnt lgkmcnt(8)
	v_pk_fma_f32 v[168:169], v[64:65], v[116:117], v[168:169]
	v_pk_fma_f32 v[170:171], v[72:73], v[116:117], v[170:171]
	v_pk_fma_f32 v[172:173], v[80:81], v[116:117], v[172:173]
	v_pk_fma_f32 v[174:175], v[88:89], v[116:117], v[174:175]
	v_pk_fma_f32 v[176:177], v[96:97], v[116:117], v[176:177]
	v_pk_fma_f32 v[178:179], v[136:137], v[116:117], v[178:179]
	v_pk_fma_f32 v[180:181], v[144:145], v[116:117], v[180:181]
	v_pk_fma_f32 v[182:183], v[152:153], v[116:117], v[182:183]
	v_pk_fma_f32 v[168:169], v[66:67], v[118:119], v[168:169]
	v_pk_fma_f32 v[170:171], v[74:75], v[118:119], v[170:171]
	v_pk_fma_f32 v[172:173], v[82:83], v[118:119], v[172:173]
	v_pk_fma_f32 v[174:175], v[90:91], v[118:119], v[174:175]
	v_pk_fma_f32 v[176:177], v[98:99], v[118:119], v[176:177]
	v_pk_fma_f32 v[178:179], v[138:139], v[118:119], v[178:179]
	v_pk_fma_f32 v[180:181], v[146:147], v[118:119], v[180:181]
	v_pk_fma_f32 v[182:183], v[154:155], v[118:119], v[182:183]
	s_waitcnt lgkmcnt(0)
; __device__ __forceinline__ unsigned cvt_pk_bf16(float lo, float hi) { f32x2_t f = {lo, hi}; bf16x2_t v = __builtin_convertvector(f, bf16x2_t); return __builtin_bit_cast(unsigned, v); }
; __device__ NOINL void prep_weff(const float* pw, const float* ps, const float* wb, bf16_t* dst, LAS unsigned char* lds, int wv) {
;     ...
;         for (int d = 0; d < 256; ++d) { const float w = wp[(size_t)d * 2048];
; #pragma unroll
;             for (int cc = 0; cc < 8; ++cc) acc[cc] += wl[cc * 256 + d] * w; }
;         u32x4 w; w.x = cvt_pk_bf16(acc[0], acc[1]); w.y = cvt_pk_bf16(acc[2], acc[3]); w.z = cvt_pk_bf16(acc[4], acc[5]); w.w = cvt_pk_bf16(acc[6], acc[7]);
;         *(u32x4*)(dst + (size_t)n * 1024 + g * 256 + c8 * 8) = w;
	v_pk_fma_f32 v[168:169], v[68:69], v[120:121], v[168:169]
	v_pk_fma_f32 v[170:171], v[76:77], v[120:121], v[170:171]
	v_pk_fma_f32 v[172:173], v[84:85], v[120:121], v[172:173]
	v_pk_fma_f32 v[174:175], v[92:93], v[120:121], v[174:175]
	v_pk_fma_f32 v[176:177], v[132:133], v[120:121], v[176:177]
	v_pk_fma_f32 v[178:179], v[140:141], v[120:121], v[178:179]
	v_pk_fma_f32 v[180:181], v[148:149], v[120:121], v[180:181]
	v_pk_fma_f32 v[182:183], v[156:157], v[120:121], v[182:183]
	v_pk_fma_f32 v[168:169], v[70:71], v[122:123], v[168:169]
	v_pk_fma_f32 v[170:171], v[78:79], v[122:123], v[170:171]
	v_pk_fma_f32 v[172:173], v[86:87], v[122:123], v[172:173]
	v_pk_fma_f32 v[174:175], v[94:95], v[122:123], v[174:175]
	v_pk_fma_f32 v[176:177], v[134:135], v[122:123], v[176:177]
	v_pk_fma_f32 v[178:179], v[142:143], v[122:123], v[178:179]
	v_pk_fma_f32 v[180:181], v[150:151], v[122:123], v[180:181]
	v_pk_fma_f32 v[182:183], v[158:159], v[122:123], v[182:183]
	global_load_dword v116, v184, s[8:9]
	s_add_u32 s8, s8, 0x2000
	s_addc_u32 s9, s9, 0
	global_load_dword v117, v184, s[8:9]
	s_add_u32 s8, s8, 0x2000
	s_addc_u32 s9, s9, 0
	global_load_dword v118, v184, s[8:9]
	s_add_u32 s8, s8, 0x2000
	s_addc_u32 s9, s9, 0
	global_load_dword v119, v184, s[8:9]
	s_add_u32 s8, s8, 0x2000
	s_addc_u32 s9, s9, 0
	global_load_dword v120, v184, s[8:9]
	s_add_u32 s8, s8, 0x2000
	s_addc_u32 s9, s9, 0
	global_load_dword v121, v184, s[8:9]
	s_add_u32 s8, s8, 0x2000
	s_addc_u32 s9, s9, 0
	global_load_dword v122, v184, s[8:9]
	s_add_u32 s8, s8, 0x2000
	s_addc_u32 s9, s9, 0
	global_load_dword v123, v184, s[8:9]
	s_add_u32 s8, s8, 0x2000
	s_addc_u32 s9, s9, 0
	ds_read_b128 v[64:67], v185 offset:96
	ds_read_b128 v[72:75], v185 offset:1120
	ds_read_b128 v[80:83], v185 offset:2144
	ds_read_b128 v[88:91], v185 offset:3168
	ds_read_b128 v[96:99], v185 offset:4192
	ds_read_b128 v[136:139], v185 offset:5216
	ds_read_b128 v[144:147], v185 offset:6240
	ds_read_b128 v[152:155], v185 offset:7264
	ds_read_b128 v[68:71], v185 offset:112
	ds_read_b128 v[76:79], v185 offset:1136
	ds_read_b128 v[84:87], v185 offset:2160
	ds_read_b128 v[92:95], v185 offset:3184
	ds_read_b128 v[132:135], v185 offset:4208
	ds_read_b128 v[140:143], v185 offset:5232
	ds_read_b128 v[148:151], v185 offset:6256
	ds_read_b128 v[156:159], v185 offset:7280
	s_waitcnt vmcnt(24)
	s_waitcnt lgkmcnt(8)
	v_pk_fma_f32 v[168:169], v[64:65], v[124:125], v[168:169]
	v_pk_fma_f32 v[170:171], v[72:73], v[124:125], v[170:171]
	v_pk_fma_f32 v[172:173], v[80:81], v[124:125], v[172:173]
	v_pk_fma_f32 v[174:175], v[88:89], v[124:125], v[174:175]
	v_pk_fma_f32 v[176:177], v[96:97], v[124:125], v[176:177]
	v_pk_fma_f32 v[178:179], v[136:137], v[124:125], v[178:179]
	v_pk_fma_f32 v[180:181], v[144:145], v[124:125], v[180:181]
	v_pk_fma_f32 v[182:183], v[152:153], v[124:125], v[182:183]
	v_pk_fma_f32 v[168:169], v[66:67], v[126:127], v[168:169]
	v_pk_fma_f32 v[170:171], v[74:75], v[126:127], v[170:171]
	v_pk_fma_f32 v[172:173], v[82:83], v[126:127], v[172:173]
	v_pk_fma_f32 v[174:175], v[90:91], v[126:127], v[174:175]
	v_pk_fma_f32 v[176:177], v[98:99], v[126:127], v[176:177]
	v_pk_fma_f32 v[178:179], v[138:139], v[126:127], v[178:179]
	v_pk_fma_f32 v[180:181], v[146:147], v[126:127], v[180:181]
	v_pk_fma_f32 v[182:183], v[154:155], v[126:127], v[182:183]
	s_waitcnt lgkmcnt(0)
	v_pk_fma_f32 v[168:169], v[68:69], v[128:129], v[168:169]
	v_pk_fma_f32 v[170:171], v[76:77], v[128:129], v[170:171]
	v_pk_fma_f32 v[172:173], v[84:85], v[128:129], v[172:173]
	v_pk_fma_f32 v[174:175], v[92:93], v[128:129], v[174:175]
	v_pk_fma_f32 v[176:177], v[132:133], v[128:129], v[176:177]
	v_pk_fma_f32 v[178:179], v[140:141], v[128:129], v[178:179]
	v_pk_fma_f32 v[180:181], v[148:149], v[128:129], v[180:181]
	v_pk_fma_f32 v[182:183], v[156:157], v[128:129], v[182:183]
	v_pk_fma_f32 v[168:169], v[70:71], v[130:131], v[168:169]
	v_pk_fma_f32 v[170:171], v[78:79], v[130:131], v[170:171]
	v_pk_fma_f32 v[172:173], v[86:87], v[130:131], v[172:173]
	v_pk_fma_f32 v[174:175], v[94:95], v[130:131], v[174:175]
	v_pk_fma_f32 v[176:177], v[134:135], v[130:131], v[176:177]
	v_pk_fma_f32 v[178:179], v[142:143], v[130:131], v[178:179]
	v_pk_fma_f32 v[180:181], v[150:151], v[130:131], v[180:181]
	v_pk_fma_f32 v[182:183], v[158:159], v[130:131], v[182:183]
	v_add_u32_e32 v185, 0x80, v185
	s_add_i32 s12, s12, 1
	s_cmp_eq_u32 s12, 8
	s_cbranch_scc0 .Lweff2_loop
	s_waitcnt vmcnt(0)
	s_mov_b32 s8, 0x200000
	s_mov_b32 s9, 0
	v_add_f32_e32 v10, v168, v169
	v_add_f32_e32 v11, v170, v171
	v_add_f32_e32 v18, v172, v173
	v_add_f32_e32 v19, v174, v175
	v_add_f32_e32 v26, v176, v177
	v_add_f32_e32 v27, v178, v179
	v_add_f32_e32 v48, v180, v181
	v_add_f32_e32 v49, v182, v183
	v_lshlrev_b64 v[6:7], 11, v[44:45]
	v_lshl_add_u64 v[6:7], s[4:5], 0, v[6:7]
	v_lshl_add_u64 v[6:7], s[6:7], 1, v[6:7]
	s_lshl_b32 s70, s11, 1
	v_cvt_pk_bf16_f32 v2, v10, v11
	v_cvt_pk_bf16_f32 v3, v18, v19
	v_cvt_pk_bf16_f32 v4, v26, v27
	v_cvt_pk_bf16_f32 v5, v48, v49
	v_lshl_add_u64 v[6:7], v[6:7], 0, s[70:71]
	s_mov_b32 s6, s58
	global_store_dwordx4 v[6:7], v[2:5], off
	s_add_i32 s10, s6, s10
	s_cmpk_gt_i32 s10, 0x1ff
	s_cbranch_scc0 .LBB0_883
